# dil loop: padded dil-4 table + conflict-free K readback swizzle (second write address for rows 16..31) + early table reads, all together
# baseline (speedup 1.0000x reference)
; #define LAS __attribute__((address_space(3)))
; #define GAS __attribute__((address_space(1)))
; __device__ __forceinline__ void dil_unit(LAS unsigned char* lds, bf16_t* proj, int seq, int hd, int T0, int rho) {
;     int tid_ = threadIdx.x; asm volatile("" : "+v"(tid_));
;     const int tid = tid_, lane = tid & 63, r32 = lane & 31, hi = lane >> 5, wid = __builtin_amdgcn_readfirstlane(tid >> 6);
;     bf16_t* base = proj + (size_t)seq * SEQ * NIN;
;     LAS unsigned char* wbuf = lds + wid * 4096;
;     const LAS unsigned char* vp = wbuf + ((lane >> 4) & 1) * 32 + (lane & 3) * 8 + (4 * hi + ((lane & 15) >> 2)) * 64;
;     const int P0 = T0 + rho;
;     bf16x8 qr[4];
; #pragma unroll
;     for (int ks = 0; ks < 4; ++ks) qr[ks] = *(const GAS bf16x8*)(base + (size_t)(P0 + 16 * r32) * NIN + PC_LQ + hd * 64 + 16 * ks + 8 * hi);
;     f32x16 o0 = {}, o1 = {}; float l = 0.f;
;     const bool bound = (T0 < 1024) || (T0 >= 15360);
; __device__ __forceinline__ void attn_phase(unsigned char* ws, int l, LAS unsigned char* lds, int G) {
;     ...
;     for (int bu = vb; bu < 1152; bu += G) {
;         const int sh = bu >> 6, rem = bu & 63, T0 = (rem >> 1) * 512, rho = (rem & 1) * 8 + wid;
;         dil_unit(lds, proj, sh / 6, sh % 6, T0, rho);
.LBB0_554:
	s_lshr_b32 s82, s33, 8
	s_mul_i32 s82, s82, 13
	s_add_i32 s82, s82, s33
	s_ashr_i32 s2, s33, 6
	s_mul_hi_i32 s7, s2, 0x2aaaaaab
	s_lshl_b32 s3, s82, 8
	s_lshr_b32 s8, s7, 31
	s_and_b32 s6, s3, 0x3e00
	s_lshl_b32 s3, s82, 3
	s_add_i32 s7, s7, s8
	s_and_b32 s3, s3, 8
	s_mul_i32 s8, s7, 6
	s_add_i32 s3, s3, s64
	s_sub_i32 s8, s2, s8
	s_mul_hi_i32 s2, s7, 0x6000000
	s_mul_i32 s7, s7, 0x6000000
	v_mov_b32_e32 v2, v154
	s_add_u32 s56, s48, s7
	s_addc_u32 s57, s49, s2
	v_and_b32_e32 v105, 31, v2
	s_add_i32 s76, s3, s6
	v_lshl_add_u32 v3, v105, 4, s76
	v_mov_b64_e32 v[0:1], s[56:57]
	s_lshl_b32 s58, s8, 6
	v_bfe_u32 v106, v2, 5, 1
	v_mad_u64_u32 v[0:1], s[2:3], v3, s65, v[0:1]
	s_ashr_i32 s59, s58, 31
	v_lshl_add_u64 v[0:1], s[58:59], 1, v[0:1]
	v_lshlrev_b32_e32 v80, 4, v106
	v_lshl_add_u64 v[0:1], v[0:1], 0, v[80:81]
	global_load_dwordx4 v[48:51], v[0:1], off offset:1280
	global_load_dwordx4 v[52:55], v[0:1], off offset:1312
	global_load_dwordx4 v[56:59], v[0:1], off offset:1344
	global_load_dwordx4 v[60:63], v[0:1], off offset:1376
	v_readfirstlane_b32 s2, v2
	s_lshl_b32 s2, s2, 6
	s_and_b32 s2, s2, 0xfffff000
	v_lshlrev_b32_e32 v0, 1, v2
	v_lshlrev_b32_e32 v104, 3, v2
	v_lshlrev_b32_e32 v107, 2, v106
	v_lshrrev_b32_e32 v1, 2, v2
	v_and_b32_e32 v103, 63, v2
	v_and_b32_e32 v0, 32, v0
	v_and_b32_e32 v98, 24, v104
	v_and_or_b32 v1, v1, 3, v107
	s_add_i32 s77, s2, 0
	v_lshlrev_b32_e32 v108, 6, v1
	v_lshlrev_b32_e32 v1, 3, v106
	v_add3_u32 v109, s77, v0, v98
	s_addk_i32 s6, 0xc400
	v_lshrrev_b32_e32 v110, 2, v103
	v_lshlrev_b32_e32 v0, 4, v103
	s_mov_b64 s[2:3], -1
	s_cmp_gt_u32 s6, 0xffffc7ff
	v_lshlrev_b32_e32 v100, 1, v98
	s_mul_i32 s6, s8, 0x1c00
	v_lshlrev_b32_e32 v82, 1, v1
	v_or_b32_e32 v111, 16, v110
	v_add_u32_e32 v112, s77, v0
	s_cbranch_scc0 .LBB0_558
	s_movk_i32 s100, 0x1800
	s_add_i32 s101, s6, 0x15c00
	s_lshl_b32 s90, s58, 1
	s_add_u32 s82, s56, s90
	s_addc_u32 s83, s57, 0
	s_add_u32 s82, s82, 0x1200
	s_addc_u32 s83, s83, 0
	s_sub_i32 s90, s76, 64
	s_mul_i32 s90, s90, 0x1800
	s_add_u32 s84, s82, s90
	s_addc_u32 s85, s83, 0
	s_sub_i32 s90, s76, 256
	s_mul_i32 s90, s90, 0x1800
	s_add_u32 s86, s82, s90
	s_addc_u32 s87, s83, 0
	s_sub_i32 s90, s76, 1024
	s_mul_i32 s90, s90, 0x1800
	s_add_u32 s88, s82, s90
	s_addc_u32 s89, s83, 0
	v_lshlrev_b32_e32 v153, 1, v98
	v_mad_u32_u24 v80, v105, s100, v82
	v_mad_u32_u24 v100, v110, s100, v153
	v_add_u32_e32 v149, 0x18000, v100
	v_lshlrev_b32_e32 v83, 2, v105
	v_mad_u32_u24 v83, v83, s100, v82
	v_lshlrev_b32_e32 v101, 2, v110
	v_mad_u32_u24 v101, v101, s100, v153
	v_add_u32_e32 v150, 0x60000, v101
	v_lshlrev_b32_e32 v99, 4, v105
	v_mad_u32_u24 v99, v99, s100, v82
	v_lshlrev_b32_e32 v148, 4, v110
	v_mad_u32_u24 v148, v148, s100, v153
	v_add_u32_e32 v151, 0x180000, v148
	v_lshrrev_b32_e32 v249, 3, v103
	v_and_b32_e32 v250, 7, v103
	v_lshlrev_b32_e32 v250, 4, v250
	v_add_u32_e32 v235, 0, v249
	v_mad_u32_u24 v235, v235, s100, v250
	v_add_u32_e32 v236, 8, v249
	v_mad_u32_u24 v236, v236, s100, v250
	v_add_u32_e32 v237, 16, v249
	v_mad_u32_u24 v237, v237, s100, v250
	v_add_u32_e32 v238, 24, v249
	v_mad_u32_u24 v238, v238, s100, v250
	v_add_u32_e32 v239, 0, v249
	v_lshlrev_b32_e32 v239, 2, v239
	v_mad_u32_u24 v239, v239, s100, v250
	v_add_u32_e32 v240, 8, v249
	v_lshlrev_b32_e32 v240, 2, v240
	v_mad_u32_u24 v240, v240, s100, v250
	v_add_u32_e32 v241, 16, v249
	v_lshlrev_b32_e32 v241, 2, v241
	v_mad_u32_u24 v241, v241, s100, v250
	v_add_u32_e32 v242, 24, v249
	v_lshlrev_b32_e32 v242, 2, v242
	v_mad_u32_u24 v242, v242, s100, v250
	v_add_u32_e32 v243, 0, v249
	v_lshlrev_b32_e32 v243, 4, v243
	v_mad_u32_u24 v243, v243, s100, v250
	v_add_u32_e32 v244, 8, v249
	v_lshlrev_b32_e32 v244, 4, v244
	v_mad_u32_u24 v244, v244, s100, v250
	v_add_u32_e32 v245, 16, v249
	v_lshlrev_b32_e32 v245, 4, v245
	v_mad_u32_u24 v245, v245, s100, v250
	v_add_u32_e32 v246, 24, v249
	v_lshlrev_b32_e32 v246, 4, v246
	v_mad_u32_u24 v246, v246, s100, v250
	v_and_b32_e32 v247, 7, v249
	v_lshlrev_b32_e32 v247, 4, v247
	v_xor_b32_e32 v247, v247, v112
	v_xor_b32_e32 v111, 16, v247
	v_and_b32_e32 v153, 7, v105
	v_lshrrev_b32_e32 v248, 4, v105
	v_xor_b32_e32 v153, v153, v248
	v_or_b32_e32 v248, 0, v106
	v_xor_b32_e32 v248, v248, v153
	v_lshlrev_b32_e32 v248, 4, v248
	v_lshl_add_u32 v248, v105, 7, v248
	v_add_u32_e32 v248, s77, v248
	v_or_b32_e32 v249, 2, v106
	v_xor_b32_e32 v249, v249, v153
	v_lshlrev_b32_e32 v249, 4, v249
	v_lshl_add_u32 v249, v105, 7, v249
	v_add_u32_e32 v249, s77, v249
	v_or_b32_e32 v250, 4, v106
	v_xor_b32_e32 v250, v250, v153
	v_lshlrev_b32_e32 v250, 4, v250
	v_lshl_add_u32 v250, v105, 7, v250
	v_add_u32_e32 v250, s77, v250
	v_or_b32_e32 v251, 6, v106
	v_xor_b32_e32 v251, v251, v153
	v_lshlrev_b32_e32 v251, 4, v251
	v_lshl_add_u32 v251, v105, 7, v251
	v_add_u32_e32 v251, s77, v251
	v_lshlrev_b32_e32 v153, 1, v98
	v_mul_u32_u24_e32 v228, 17, v105
	v_sub_u32_e32 v228, v107, v228
	s_mul_i32 s90, s58, 153
	s_lshr_b32 s90, s90, 1
	s_add_i32 s90, s90, 34876
	v_lshl_add_u32 v228, v228, 2, s90
	v_mul_u32_u24_e32 v229, 5, v105
	v_sub_u32_e32 v229, v107, v229
	v_add_u32_e32 v229, v229, v106
	s_mul_i32 s90, s58, 30
	s_add_i32 s90, s90, 66156
	v_lshl_add_u32 v229, v229, 2, s90
	v_sub_u32_e32 v230, v107, v105
	s_add_i32 s90, s101, 6364
	v_lshl_add_u32 v230, v230, 2, s90
	v_add_u32_e32 v231, v109, v108
	v_mov_b64_e32 v[232:233], 0
	v_mov_b64_e32 v[0:1], 0
	v_mov_b64_e32 v[2:3], 0
	v_mov_b64_e32 v[4:5], 0
	v_mov_b64_e32 v[6:7], 0
	v_mov_b64_e32 v[8:9], 0
	v_mov_b64_e32 v[10:11], 0
	v_mov_b64_e32 v[12:13], 0
	v_mov_b64_e32 v[14:15], 0
	v_mov_b64_e32 v[16:17], 0
	v_mov_b64_e32 v[18:19], 0
	v_mov_b64_e32 v[20:21], 0
	v_mov_b64_e32 v[22:23], 0
	v_mov_b64_e32 v[24:25], 0
	v_mov_b64_e32 v[26:27], 0
	v_mov_b64_e32 v[28:29], 0
	v_mov_b64_e32 v[30:31], 0
	global_load_dwordx4 v[116:119], v235, s[84:85]
	global_load_dwordx4 v[120:123], v236, s[84:85]
	global_load_dwordx4 v[124:127], v237, s[84:85]
	global_load_dwordx4 v[128:131], v238, s[84:85]
	global_load_dwordx4 v[132:135], v100, s[84:85] offset:768
	global_load_dwordx4 v[136:139], v149, s[84:85] offset:768
	global_load_dwordx4 v[140:143], v100, s[84:85] offset:832
	global_load_dwordx4 v[144:147], v149, s[84:85] offset:832
	s_add_u32 s84, s84, 0x30000
	s_addc_u32 s85, s85, 0
	global_load_dwordx4 v[156:159], v235, s[84:85]
	global_load_dwordx4 v[160:163], v236, s[84:85]
	global_load_dwordx4 v[164:167], v237, s[84:85]
	global_load_dwordx4 v[168:171], v238, s[84:85]
	global_load_dwordx4 v[172:175], v100, s[84:85] offset:768
	global_load_dwordx4 v[176:179], v149, s[84:85] offset:768
	global_load_dwordx4 v[180:183], v100, s[84:85] offset:832
	global_load_dwordx4 v[184:187], v149, s[84:85] offset:832
	s_add_u32 s84, s84, 0x30000
	s_addc_u32 s85, s85, 0
	global_load_dwordx4 v[188:191], v235, s[84:85]
	global_load_dwordx4 v[192:195], v236, s[84:85]
	global_load_dwordx4 v[196:199], v237, s[84:85]
	global_load_dwordx4 v[200:203], v238, s[84:85]
	global_load_dwordx4 v[204:207], v100, s[84:85] offset:768
	global_load_dwordx4 v[208:211], v149, s[84:85] offset:768
	global_load_dwordx4 v[212:215], v100, s[84:85] offset:832
	global_load_dwordx4 v[216:219], v149, s[84:85] offset:832
	s_add_u32 s84, s84, 0x30000
	s_addc_u32 s85, s85, 0
	s_waitcnt vmcnt(16)
	ds_write_b128 v247, v[116:119]
	ds_write_b128 v247, v[120:123] offset:1024
	ds_write_b128 v111, v[124:127] offset:2048
	ds_write_b128 v111, v[128:131] offset:3072
	ds_read_b128 v[116:119], v248
	ds_read_b128 v[120:123], v249
	ds_read_b128 v[124:127], v250
	ds_read_b128 v[128:131], v251
	ds_write_b128 v112, v[132:135]
	ds_write_b128 v112, v[136:139] offset:1024
	ds_write_b128 v112, v[140:143] offset:2048
	ds_write_b128 v112, v[144:147] offset:3072
	v_mov_b32_e32 v115, v228
	ds_read2_b32 v[32:33], v115 offset0:0 offset1:1
	ds_read2_b32 v[34:35], v115 offset0:2 offset1:3
	ds_read2_b32 v[36:37], v115 offset0:8 offset1:9
	ds_read2_b32 v[38:39], v115 offset0:10 offset1:11
	ds_read2_b32 v[40:41], v115 offset0:17 offset1:18
	ds_read2_b32 v[42:43], v115 offset0:19 offset1:20
	ds_read2_b32 v[44:45], v115 offset0:25 offset1:26
	ds_read2_b32 v[46:47], v115 offset0:27 offset1:28
	s_waitcnt lgkmcnt(0)
	v_mfma_f32_32x32x16_bf16 v[32:47], v[116:119], v[48:51], v[32:47]
	ds_read_b64_tr_b16 v[72:73], v231
	ds_read_b64_tr_b16 v[74:75], v231 offset:512
	ds_read_b64_tr_b16 v[76:77], v231 offset:2048
	ds_read_b64_tr_b16 v[78:79], v231 offset:2560
	ds_read_b64_tr_b16 v[220:221], v231 offset:1024
	ds_read_b64_tr_b16 v[222:223], v231 offset:1536
	ds_read_b64_tr_b16 v[224:225], v231 offset:3072
	ds_read_b64_tr_b16 v[226:227], v231 offset:3584
	s_waitcnt vmcnt(8)
	ds_write_b128 v247, v[156:159]
	ds_write_b128 v247, v[160:163] offset:1024
	ds_write_b128 v111, v[164:167] offset:2048
	ds_write_b128 v111, v[168:171] offset:3072
	ds_read_b128 v[156:159], v248
	ds_read_b128 v[160:163], v249
	ds_read_b128 v[164:167], v250
	ds_read_b128 v[168:171], v251
	ds_write_b128 v112, v[172:175]
	ds_write_b128 v112, v[176:179] offset:1024
	ds_write_b128 v112, v[180:183] offset:2048
	ds_write_b128 v112, v[184:187] offset:3072
	v_mfma_f32_32x32x16_bf16 v[32:47], v[120:123], v[52:55], v[32:47]
	v_mfma_f32_32x32x16_bf16 v[32:47], v[124:127], v[56:59], v[32:47]
	v_mfma_f32_32x32x16_bf16 v[32:47], v[128:131], v[60:63], v[32:47]
	s_nop 11
	v_exp_f32_e32 v32, v32
	v_exp_f32_e32 v33, v33
	v_exp_f32_e32 v34, v34
	v_exp_f32_e32 v35, v35
	v_exp_f32_e32 v36, v36
	v_exp_f32_e32 v37, v37
	v_exp_f32_e32 v38, v38
	v_exp_f32_e32 v39, v39
	v_exp_f32_e32 v40, v40
	v_exp_f32_e32 v41, v41
	v_exp_f32_e32 v42, v42
	v_exp_f32_e32 v43, v43
	v_exp_f32_e32 v44, v44
	v_exp_f32_e32 v45, v45
	v_exp_f32_e32 v46, v46
	v_exp_f32_e32 v47, v47
	v_cvt_pk_bf16_f32 v64, v32, v33
	v_cvt_pk_bf16_f32 v65, v34, v35
	v_cvt_pk_bf16_f32 v66, v36, v37
	v_cvt_pk_bf16_f32 v67, v38, v39
	v_cvt_pk_bf16_f32 v68, v40, v41
	v_cvt_pk_bf16_f32 v69, v42, v43
	v_cvt_pk_bf16_f32 v70, v44, v45
	v_cvt_pk_bf16_f32 v71, v46, v47
	v_pk_add_f32 v[232:233], v[232:233], v[32:33]
	v_pk_add_f32 v[232:233], v[232:233], v[34:35]
	v_pk_add_f32 v[232:233], v[232:233], v[36:37]
	v_pk_add_f32 v[232:233], v[232:233], v[38:39]
	v_pk_add_f32 v[232:233], v[232:233], v[40:41]
	v_pk_add_f32 v[232:233], v[232:233], v[42:43]
	v_pk_add_f32 v[232:233], v[232:233], v[44:45]
	v_pk_add_f32 v[232:233], v[232:233], v[46:47]
	ds_read2_b32 v[32:33], v115 offset0:34 offset1:35
	ds_read2_b32 v[34:35], v115 offset0:36 offset1:37
	ds_read2_b32 v[36:37], v115 offset0:42 offset1:43
	ds_read2_b32 v[38:39], v115 offset0:44 offset1:45
	ds_read2_b32 v[40:41], v115 offset0:51 offset1:52
	ds_read2_b32 v[42:43], v115 offset0:53 offset1:54
	ds_read2_b32 v[44:45], v115 offset0:59 offset1:60
	ds_read2_b32 v[46:47], v115 offset0:61 offset1:62
	s_waitcnt lgkmcnt(15)
	v_mfma_f32_32x32x16_bf16 v[0:15], v[64:67], v[72:75], v[0:15]
	v_mfma_f32_32x32x16_bf16 v[16:31], v[64:67], v[76:79], v[16:31]
	v_mfma_f32_32x32x16_bf16 v[0:15], v[68:71], v[220:223], v[0:15]
	v_mfma_f32_32x32x16_bf16 v[16:31], v[68:71], v[224:227], v[16:31]
	global_load_dwordx4 v[116:119], v235, s[84:85]
	global_load_dwordx4 v[120:123], v236, s[84:85]
	global_load_dwordx4 v[124:127], v237, s[84:85]
	global_load_dwordx4 v[128:131], v238, s[84:85]
	global_load_dwordx4 v[132:135], v100, s[84:85] offset:768
	global_load_dwordx4 v[136:139], v149, s[84:85] offset:768
	global_load_dwordx4 v[140:143], v100, s[84:85] offset:832
	global_load_dwordx4 v[144:147], v149, s[84:85] offset:832
	s_add_u32 s84, s84, 0x30000
	s_addc_u32 s85, s85, 0
	s_waitcnt lgkmcnt(0)
	v_mfma_f32_32x32x16_bf16 v[32:47], v[156:159], v[48:51], v[32:47]
	ds_read_b64_tr_b16 v[72:73], v231
	ds_read_b64_tr_b16 v[74:75], v231 offset:512
	ds_read_b64_tr_b16 v[76:77], v231 offset:2048
	ds_read_b64_tr_b16 v[78:79], v231 offset:2560
	ds_read_b64_tr_b16 v[220:221], v231 offset:1024
	ds_read_b64_tr_b16 v[222:223], v231 offset:1536
	ds_read_b64_tr_b16 v[224:225], v231 offset:3072
	ds_read_b64_tr_b16 v[226:227], v231 offset:3584
	s_waitcnt vmcnt(8)
	ds_write_b128 v247, v[188:191]
	ds_write_b128 v247, v[192:195] offset:1024
	ds_write_b128 v111, v[196:199] offset:2048
	ds_write_b128 v111, v[200:203] offset:3072
	ds_read_b128 v[188:191], v248
	ds_read_b128 v[192:195], v249
	ds_read_b128 v[196:199], v250
	ds_read_b128 v[200:203], v251
	ds_write_b128 v112, v[204:207]
	ds_write_b128 v112, v[208:211] offset:1024
	ds_write_b128 v112, v[212:215] offset:2048
	ds_write_b128 v112, v[216:219] offset:3072
	v_mfma_f32_32x32x16_bf16 v[32:47], v[160:163], v[52:55], v[32:47]
	v_mfma_f32_32x32x16_bf16 v[32:47], v[164:167], v[56:59], v[32:47]
	v_mfma_f32_32x32x16_bf16 v[32:47], v[168:171], v[60:63], v[32:47]
	s_nop 11
	v_exp_f32_e32 v32, v32
	v_exp_f32_e32 v33, v33
	v_exp_f32_e32 v34, v34
	v_exp_f32_e32 v35, v35
	v_exp_f32_e32 v36, v36
	v_exp_f32_e32 v37, v37
	v_exp_f32_e32 v38, v38
	v_exp_f32_e32 v39, v39
	v_exp_f32_e32 v40, v40
	v_exp_f32_e32 v41, v41
	v_exp_f32_e32 v42, v42
	v_exp_f32_e32 v43, v43
	v_exp_f32_e32 v44, v44
	v_exp_f32_e32 v45, v45
	v_exp_f32_e32 v46, v46
	v_exp_f32_e32 v47, v47
	v_cvt_pk_bf16_f32 v64, v32, v33
	v_cvt_pk_bf16_f32 v65, v34, v35
	v_cvt_pk_bf16_f32 v66, v36, v37
	v_cvt_pk_bf16_f32 v67, v38, v39
	v_cvt_pk_bf16_f32 v68, v40, v41
	v_cvt_pk_bf16_f32 v69, v42, v43
	v_cvt_pk_bf16_f32 v70, v44, v45
	v_cvt_pk_bf16_f32 v71, v46, v47
	v_pk_add_f32 v[232:233], v[232:233], v[32:33]
	v_pk_add_f32 v[232:233], v[232:233], v[34:35]
	v_pk_add_f32 v[232:233], v[232:233], v[36:37]
	v_pk_add_f32 v[232:233], v[232:233], v[38:39]
	v_pk_add_f32 v[232:233], v[232:233], v[40:41]
	v_pk_add_f32 v[232:233], v[232:233], v[42:43]
	v_pk_add_f32 v[232:233], v[232:233], v[44:45]
	v_pk_add_f32 v[232:233], v[232:233], v[46:47]
	ds_read2_b32 v[32:33], v115 offset0:68 offset1:69
	ds_read2_b32 v[34:35], v115 offset0:70 offset1:71
	ds_read2_b32 v[36:37], v115 offset0:76 offset1:77
	ds_read2_b32 v[38:39], v115 offset0:78 offset1:79
	ds_read2_b32 v[40:41], v115 offset0:85 offset1:86
	ds_read2_b32 v[42:43], v115 offset0:87 offset1:88
	ds_read2_b32 v[44:45], v115 offset0:93 offset1:94
	ds_read2_b32 v[46:47], v115 offset0:95 offset1:96
	s_waitcnt lgkmcnt(15)
	v_mfma_f32_32x32x16_bf16 v[0:15], v[64:67], v[72:75], v[0:15]
	v_mfma_f32_32x32x16_bf16 v[16:31], v[64:67], v[76:79], v[16:31]
	v_mfma_f32_32x32x16_bf16 v[0:15], v[68:71], v[220:223], v[0:15]
	v_mfma_f32_32x32x16_bf16 v[16:31], v[68:71], v[224:227], v[16:31]
	global_load_dwordx4 v[156:159], v235, s[84:85]
	global_load_dwordx4 v[160:163], v236, s[84:85]
	global_load_dwordx4 v[164:167], v237, s[84:85]
	global_load_dwordx4 v[168:171], v238, s[84:85]
	global_load_dwordx4 v[172:175], v100, s[84:85] offset:768
	global_load_dwordx4 v[176:179], v149, s[84:85] offset:768
	global_load_dwordx4 v[180:183], v100, s[84:85] offset:832
	global_load_dwordx4 v[184:187], v149, s[84:85] offset:832
	s_add_u32 s84, s84, 0x30000
	s_addc_u32 s85, s85, 0
	s_waitcnt lgkmcnt(0)
	v_mfma_f32_32x32x16_bf16 v[32:47], v[188:191], v[48:51], v[32:47]
	ds_read_b64_tr_b16 v[72:73], v231
	ds_read_b64_tr_b16 v[74:75], v231 offset:512
	ds_read_b64_tr_b16 v[76:77], v231 offset:2048
	ds_read_b64_tr_b16 v[78:79], v231 offset:2560
	ds_read_b64_tr_b16 v[220:221], v231 offset:1024
	ds_read_b64_tr_b16 v[222:223], v231 offset:1536
	ds_read_b64_tr_b16 v[224:225], v231 offset:3072
	ds_read_b64_tr_b16 v[226:227], v231 offset:3584
	s_waitcnt vmcnt(8)
	ds_write_b128 v247, v[116:119]
	ds_write_b128 v247, v[120:123] offset:1024
	ds_write_b128 v111, v[124:127] offset:2048
	ds_write_b128 v111, v[128:131] offset:3072
	ds_read_b128 v[116:119], v248
	ds_read_b128 v[120:123], v249
	ds_read_b128 v[124:127], v250
	ds_read_b128 v[128:131], v251
	ds_write_b128 v112, v[132:135]
	ds_write_b128 v112, v[136:139] offset:1024
	ds_write_b128 v112, v[140:143] offset:2048
	ds_write_b128 v112, v[144:147] offset:3072
	v_mfma_f32_32x32x16_bf16 v[32:47], v[192:195], v[52:55], v[32:47]
	v_mfma_f32_32x32x16_bf16 v[32:47], v[196:199], v[56:59], v[32:47]
	v_mfma_f32_32x32x16_bf16 v[32:47], v[200:203], v[60:63], v[32:47]
	s_nop 11
	v_exp_f32_e32 v32, v32
	v_exp_f32_e32 v33, v33
	v_exp_f32_e32 v34, v34
	v_exp_f32_e32 v35, v35
	v_exp_f32_e32 v36, v36
	v_exp_f32_e32 v37, v37
	v_exp_f32_e32 v38, v38
	v_exp_f32_e32 v39, v39
	v_exp_f32_e32 v40, v40
	v_exp_f32_e32 v41, v41
	v_exp_f32_e32 v42, v42
	v_exp_f32_e32 v43, v43
	v_exp_f32_e32 v44, v44
	v_exp_f32_e32 v45, v45
	v_exp_f32_e32 v46, v46
	v_exp_f32_e32 v47, v47
	v_cvt_pk_bf16_f32 v64, v32, v33
	v_cvt_pk_bf16_f32 v65, v34, v35
	v_cvt_pk_bf16_f32 v66, v36, v37
	v_cvt_pk_bf16_f32 v67, v38, v39
	v_cvt_pk_bf16_f32 v68, v40, v41
	v_cvt_pk_bf16_f32 v69, v42, v43
	v_cvt_pk_bf16_f32 v70, v44, v45
	v_cvt_pk_bf16_f32 v71, v46, v47
	v_pk_add_f32 v[232:233], v[232:233], v[32:33]
	v_pk_add_f32 v[232:233], v[232:233], v[34:35]
	v_pk_add_f32 v[232:233], v[232:233], v[36:37]
	v_pk_add_f32 v[232:233], v[232:233], v[38:39]
	v_pk_add_f32 v[232:233], v[232:233], v[40:41]
	v_pk_add_f32 v[232:233], v[232:233], v[42:43]
	v_pk_add_f32 v[232:233], v[232:233], v[44:45]
	v_pk_add_f32 v[232:233], v[232:233], v[46:47]
	ds_read2_b32 v[32:33], v115 offset0:102 offset1:103
	ds_read2_b32 v[34:35], v115 offset0:104 offset1:105
	ds_read2_b32 v[36:37], v115 offset0:110 offset1:111
	ds_read2_b32 v[38:39], v115 offset0:112 offset1:113
	ds_read2_b32 v[40:41], v115 offset0:119 offset1:120
	ds_read2_b32 v[42:43], v115 offset0:121 offset1:122
	ds_read2_b32 v[44:45], v115 offset0:127 offset1:128
	ds_read2_b32 v[46:47], v115 offset0:129 offset1:130
	s_waitcnt lgkmcnt(15)
	v_mfma_f32_32x32x16_bf16 v[0:15], v[64:67], v[72:75], v[0:15]
	v_mfma_f32_32x32x16_bf16 v[16:31], v[64:67], v[76:79], v[16:31]
	v_mfma_f32_32x32x16_bf16 v[0:15], v[68:71], v[220:223], v[0:15]
	v_mfma_f32_32x32x16_bf16 v[16:31], v[68:71], v[224:227], v[16:31]
	global_load_dwordx4 v[188:191], v235, s[84:85]
	global_load_dwordx4 v[192:195], v236, s[84:85]
	global_load_dwordx4 v[196:199], v237, s[84:85]
	global_load_dwordx4 v[200:203], v238, s[84:85]
	global_load_dwordx4 v[204:207], v100, s[84:85] offset:768
	global_load_dwordx4 v[208:211], v149, s[84:85] offset:768
	global_load_dwordx4 v[212:215], v100, s[84:85] offset:832
	global_load_dwordx4 v[216:219], v149, s[84:85] offset:832
	s_add_u32 s84, s84, 0x30000
	s_addc_u32 s85, s85, 0
	s_waitcnt lgkmcnt(0)
	v_mfma_f32_32x32x16_bf16 v[32:47], v[116:119], v[48:51], v[32:47]
	ds_read_b64_tr_b16 v[72:73], v231
	ds_read_b64_tr_b16 v[74:75], v231 offset:512
	ds_read_b64_tr_b16 v[76:77], v231 offset:2048
	ds_read_b64_tr_b16 v[78:79], v231 offset:2560
	ds_read_b64_tr_b16 v[220:221], v231 offset:1024
	ds_read_b64_tr_b16 v[222:223], v231 offset:1536
	ds_read_b64_tr_b16 v[224:225], v231 offset:3072
	ds_read_b64_tr_b16 v[226:227], v231 offset:3584
	s_waitcnt vmcnt(8)
	ds_write_b128 v247, v[156:159]
	ds_write_b128 v247, v[160:163] offset:1024
	ds_write_b128 v111, v[164:167] offset:2048
	ds_write_b128 v111, v[168:171] offset:3072
	ds_read_b128 v[156:159], v248
	ds_read_b128 v[160:163], v249
	ds_read_b128 v[164:167], v250
	ds_read_b128 v[168:171], v251
	ds_write_b128 v112, v[172:175]
	ds_write_b128 v112, v[176:179] offset:1024
	ds_write_b128 v112, v[180:183] offset:2048
	ds_write_b128 v112, v[184:187] offset:3072
	v_mfma_f32_32x32x16_bf16 v[32:47], v[120:123], v[52:55], v[32:47]
	v_mfma_f32_32x32x16_bf16 v[32:47], v[124:127], v[56:59], v[32:47]
	v_mfma_f32_32x32x16_bf16 v[32:47], v[128:131], v[60:63], v[32:47]
	s_nop 11
	v_exp_f32_e32 v32, v32
	v_exp_f32_e32 v33, v33
	v_exp_f32_e32 v34, v34
	v_exp_f32_e32 v35, v35
	v_exp_f32_e32 v36, v36
	v_exp_f32_e32 v37, v37
	v_exp_f32_e32 v38, v38
	v_exp_f32_e32 v39, v39
	v_exp_f32_e32 v40, v40
	v_exp_f32_e32 v41, v41
	v_exp_f32_e32 v42, v42
	v_exp_f32_e32 v43, v43
	v_exp_f32_e32 v44, v44
	v_exp_f32_e32 v45, v45
	v_exp_f32_e32 v46, v46
	v_exp_f32_e32 v47, v47
	v_cvt_pk_bf16_f32 v64, v32, v33
	v_cvt_pk_bf16_f32 v65, v34, v35
	v_cvt_pk_bf16_f32 v66, v36, v37
	v_cvt_pk_bf16_f32 v67, v38, v39
	v_cvt_pk_bf16_f32 v68, v40, v41
	v_cvt_pk_bf16_f32 v69, v42, v43
	v_cvt_pk_bf16_f32 v70, v44, v45
	v_cvt_pk_bf16_f32 v71, v46, v47
	v_pk_add_f32 v[232:233], v[232:233], v[32:33]
	v_pk_add_f32 v[232:233], v[232:233], v[34:35]
	v_pk_add_f32 v[232:233], v[232:233], v[36:37]
	v_pk_add_f32 v[232:233], v[232:233], v[38:39]
	v_pk_add_f32 v[232:233], v[232:233], v[40:41]
	v_pk_add_f32 v[232:233], v[232:233], v[42:43]
	v_pk_add_f32 v[232:233], v[232:233], v[44:45]
	v_pk_add_f32 v[232:233], v[232:233], v[46:47]
	ds_read2_b32 v[32:33], v115 offset0:136 offset1:137
	ds_read2_b32 v[34:35], v115 offset0:138 offset1:139
	ds_read2_b32 v[36:37], v115 offset0:144 offset1:145
	ds_read2_b32 v[38:39], v115 offset0:146 offset1:147
	ds_read2_b32 v[40:41], v115 offset0:153 offset1:154
	ds_read2_b32 v[42:43], v115 offset0:155 offset1:156
	ds_read2_b32 v[44:45], v115 offset0:161 offset1:162
	ds_read2_b32 v[46:47], v115 offset0:163 offset1:164
	s_waitcnt lgkmcnt(15)
	v_mfma_f32_32x32x16_bf16 v[0:15], v[64:67], v[72:75], v[0:15]
	v_mfma_f32_32x32x16_bf16 v[16:31], v[64:67], v[76:79], v[16:31]
	v_mfma_f32_32x32x16_bf16 v[0:15], v[68:71], v[220:223], v[0:15]
	v_mfma_f32_32x32x16_bf16 v[16:31], v[68:71], v[224:227], v[16:31]
	global_load_dwordx4 v[116:119], v235, s[84:85]
	global_load_dwordx4 v[120:123], v236, s[84:85]
	global_load_dwordx4 v[124:127], v237, s[84:85]
	global_load_dwordx4 v[128:131], v238, s[84:85]
	global_load_dwordx4 v[132:135], v100, s[84:85] offset:768
	global_load_dwordx4 v[136:139], v149, s[84:85] offset:768
	global_load_dwordx4 v[140:143], v100, s[84:85] offset:832
	global_load_dwordx4 v[144:147], v149, s[84:85] offset:832
	s_add_u32 s84, s84, 0x30000
	s_addc_u32 s85, s85, 0
	s_waitcnt lgkmcnt(0)
	v_mfma_f32_32x32x16_bf16 v[32:47], v[156:159], v[48:51], v[32:47]
	ds_read_b64_tr_b16 v[72:73], v231
	ds_read_b64_tr_b16 v[74:75], v231 offset:512
	ds_read_b64_tr_b16 v[76:77], v231 offset:2048
	ds_read_b64_tr_b16 v[78:79], v231 offset:2560
	ds_read_b64_tr_b16 v[220:221], v231 offset:1024
	ds_read_b64_tr_b16 v[222:223], v231 offset:1536
	ds_read_b64_tr_b16 v[224:225], v231 offset:3072
	ds_read_b64_tr_b16 v[226:227], v231 offset:3584
	s_waitcnt vmcnt(8)
	ds_write_b128 v247, v[188:191]
	ds_write_b128 v247, v[192:195] offset:1024
	ds_write_b128 v111, v[196:199] offset:2048
	ds_write_b128 v111, v[200:203] offset:3072
	ds_read_b128 v[188:191], v248
	ds_read_b128 v[192:195], v249
	ds_read_b128 v[196:199], v250
	ds_read_b128 v[200:203], v251
	ds_write_b128 v112, v[204:207]
	ds_write_b128 v112, v[208:211] offset:1024
	ds_write_b128 v112, v[212:215] offset:2048
	ds_write_b128 v112, v[216:219] offset:3072
	v_mfma_f32_32x32x16_bf16 v[32:47], v[160:163], v[52:55], v[32:47]
	v_mfma_f32_32x32x16_bf16 v[32:47], v[164:167], v[56:59], v[32:47]
	v_mfma_f32_32x32x16_bf16 v[32:47], v[168:171], v[60:63], v[32:47]
	s_nop 11
	v_exp_f32_e32 v32, v32
	v_exp_f32_e32 v33, v33
	v_exp_f32_e32 v34, v34
	v_exp_f32_e32 v35, v35
	v_exp_f32_e32 v36, v36
	v_exp_f32_e32 v37, v37
	v_exp_f32_e32 v38, v38
	v_exp_f32_e32 v39, v39
	v_exp_f32_e32 v40, v40
	v_exp_f32_e32 v41, v41
	v_exp_f32_e32 v42, v42
	v_exp_f32_e32 v43, v43
	v_exp_f32_e32 v44, v44
	v_exp_f32_e32 v45, v45
	v_exp_f32_e32 v46, v46
	v_exp_f32_e32 v47, v47
	v_cvt_pk_bf16_f32 v64, v32, v33
	v_cvt_pk_bf16_f32 v65, v34, v35
	v_cvt_pk_bf16_f32 v66, v36, v37
	v_cvt_pk_bf16_f32 v67, v38, v39
	v_cvt_pk_bf16_f32 v68, v40, v41
	v_cvt_pk_bf16_f32 v69, v42, v43
	v_cvt_pk_bf16_f32 v70, v44, v45
	v_cvt_pk_bf16_f32 v71, v46, v47
	v_pk_add_f32 v[232:233], v[232:233], v[32:33]
	v_pk_add_f32 v[232:233], v[232:233], v[34:35]
	v_pk_add_f32 v[232:233], v[232:233], v[36:37]
	v_pk_add_f32 v[232:233], v[232:233], v[38:39]
	v_pk_add_f32 v[232:233], v[232:233], v[40:41]
	v_pk_add_f32 v[232:233], v[232:233], v[42:43]
	v_pk_add_f32 v[232:233], v[232:233], v[44:45]
	v_pk_add_f32 v[232:233], v[232:233], v[46:47]
	ds_read2_b32 v[32:33], v115 offset0:170 offset1:171
	ds_read2_b32 v[34:35], v115 offset0:172 offset1:173
	ds_read2_b32 v[36:37], v115 offset0:178 offset1:179
	ds_read2_b32 v[38:39], v115 offset0:180 offset1:181
	ds_read2_b32 v[40:41], v115 offset0:187 offset1:188
	ds_read2_b32 v[42:43], v115 offset0:189 offset1:190
	ds_read2_b32 v[44:45], v115 offset0:195 offset1:196
	ds_read2_b32 v[46:47], v115 offset0:197 offset1:198
	s_waitcnt lgkmcnt(15)
	v_mfma_f32_32x32x16_bf16 v[0:15], v[64:67], v[72:75], v[0:15]
	v_mfma_f32_32x32x16_bf16 v[16:31], v[64:67], v[76:79], v[16:31]
	v_mfma_f32_32x32x16_bf16 v[0:15], v[68:71], v[220:223], v[0:15]
	v_mfma_f32_32x32x16_bf16 v[16:31], v[68:71], v[224:227], v[16:31]
	global_load_dwordx4 v[156:159], v235, s[84:85]
	global_load_dwordx4 v[160:163], v236, s[84:85]
	global_load_dwordx4 v[164:167], v237, s[84:85]
	global_load_dwordx4 v[168:171], v238, s[84:85]
	global_load_dwordx4 v[172:175], v100, s[84:85] offset:768
	global_load_dwordx4 v[176:179], v149, s[84:85] offset:768
	global_load_dwordx4 v[180:183], v100, s[84:85] offset:832
	global_load_dwordx4 v[184:187], v149, s[84:85] offset:832
	s_add_u32 s84, s84, 0x30000
	s_addc_u32 s85, s85, 0
	s_waitcnt lgkmcnt(0)
	v_mfma_f32_32x32x16_bf16 v[32:47], v[188:191], v[48:51], v[32:47]
	ds_read_b64_tr_b16 v[72:73], v231
	ds_read_b64_tr_b16 v[74:75], v231 offset:512
	ds_read_b64_tr_b16 v[76:77], v231 offset:2048
	ds_read_b64_tr_b16 v[78:79], v231 offset:2560
	ds_read_b64_tr_b16 v[220:221], v231 offset:1024
	ds_read_b64_tr_b16 v[222:223], v231 offset:1536
	ds_read_b64_tr_b16 v[224:225], v231 offset:3072
	ds_read_b64_tr_b16 v[226:227], v231 offset:3584
	s_waitcnt vmcnt(8)
	ds_write_b128 v247, v[116:119]
	ds_write_b128 v247, v[120:123] offset:1024
	ds_write_b128 v111, v[124:127] offset:2048
	ds_write_b128 v111, v[128:131] offset:3072
	ds_read_b128 v[116:119], v248
	ds_read_b128 v[120:123], v249
	ds_read_b128 v[124:127], v250
	ds_read_b128 v[128:131], v251
	ds_write_b128 v112, v[132:135]
	ds_write_b128 v112, v[136:139] offset:1024
	ds_write_b128 v112, v[140:143] offset:2048
	ds_write_b128 v112, v[144:147] offset:3072
	v_mfma_f32_32x32x16_bf16 v[32:47], v[192:195], v[52:55], v[32:47]
	v_mfma_f32_32x32x16_bf16 v[32:47], v[196:199], v[56:59], v[32:47]
	v_mfma_f32_32x32x16_bf16 v[32:47], v[200:203], v[60:63], v[32:47]
	s_nop 11
	v_exp_f32_e32 v32, v32
	v_exp_f32_e32 v33, v33
	v_exp_f32_e32 v34, v34
	v_exp_f32_e32 v35, v35
	v_exp_f32_e32 v36, v36
	v_exp_f32_e32 v37, v37
	v_exp_f32_e32 v38, v38
	v_exp_f32_e32 v39, v39
	v_exp_f32_e32 v40, v40
	v_exp_f32_e32 v41, v41
	v_exp_f32_e32 v42, v42
	v_exp_f32_e32 v43, v43
	v_exp_f32_e32 v44, v44
	v_exp_f32_e32 v45, v45
	v_exp_f32_e32 v46, v46
	v_exp_f32_e32 v47, v47
	v_cvt_pk_bf16_f32 v64, v32, v33
	v_cvt_pk_bf16_f32 v65, v34, v35
	v_cvt_pk_bf16_f32 v66, v36, v37
	v_cvt_pk_bf16_f32 v67, v38, v39
	v_cvt_pk_bf16_f32 v68, v40, v41
	v_cvt_pk_bf16_f32 v69, v42, v43
	v_cvt_pk_bf16_f32 v70, v44, v45
	v_cvt_pk_bf16_f32 v71, v46, v47
	v_pk_add_f32 v[232:233], v[232:233], v[32:33]
	v_pk_add_f32 v[232:233], v[232:233], v[34:35]
	v_pk_add_f32 v[232:233], v[232:233], v[36:37]
	v_pk_add_f32 v[232:233], v[232:233], v[38:39]
	v_pk_add_f32 v[232:233], v[232:233], v[40:41]
	v_pk_add_f32 v[232:233], v[232:233], v[42:43]
	v_pk_add_f32 v[232:233], v[232:233], v[44:45]
	v_pk_add_f32 v[232:233], v[232:233], v[46:47]
	ds_read2_b32 v[32:33], v115 offset0:204 offset1:205
	ds_read2_b32 v[34:35], v115 offset0:206 offset1:207
	ds_read2_b32 v[36:37], v115 offset0:212 offset1:213
	ds_read2_b32 v[38:39], v115 offset0:214 offset1:215
	ds_read2_b32 v[40:41], v115 offset0:221 offset1:222
	ds_read2_b32 v[42:43], v115 offset0:223 offset1:224
	ds_read2_b32 v[44:45], v115 offset0:229 offset1:230
	ds_read2_b32 v[46:47], v115 offset0:231 offset1:232
	s_waitcnt lgkmcnt(15)
	v_mfma_f32_32x32x16_bf16 v[0:15], v[64:67], v[72:75], v[0:15]
	v_mfma_f32_32x32x16_bf16 v[16:31], v[64:67], v[76:79], v[16:31]
	v_mfma_f32_32x32x16_bf16 v[0:15], v[68:71], v[220:223], v[0:15]
	v_mfma_f32_32x32x16_bf16 v[16:31], v[68:71], v[224:227], v[16:31]
	global_load_dwordx4 v[188:191], v235, s[84:85]
	global_load_dwordx4 v[192:195], v236, s[84:85]
	global_load_dwordx4 v[196:199], v237, s[84:85]
	global_load_dwordx4 v[200:203], v238, s[84:85]
	global_load_dwordx4 v[204:207], v100, s[84:85] offset:768
	global_load_dwordx4 v[208:211], v149, s[84:85] offset:768
	global_load_dwordx4 v[212:215], v100, s[84:85] offset:832
	global_load_dwordx4 v[216:219], v149, s[84:85] offset:832
	s_add_u32 s84, s84, 0x30000
	s_addc_u32 s85, s85, 0
	s_waitcnt lgkmcnt(0)
	v_mfma_f32_32x32x16_bf16 v[32:47], v[116:119], v[48:51], v[32:47]
	ds_read_b64_tr_b16 v[72:73], v231
	ds_read_b64_tr_b16 v[74:75], v231 offset:512
	ds_read_b64_tr_b16 v[76:77], v231 offset:2048
	ds_read_b64_tr_b16 v[78:79], v231 offset:2560
	ds_read_b64_tr_b16 v[220:221], v231 offset:1024
	ds_read_b64_tr_b16 v[222:223], v231 offset:1536
	ds_read_b64_tr_b16 v[224:225], v231 offset:3072
	ds_read_b64_tr_b16 v[226:227], v231 offset:3584
	s_waitcnt vmcnt(8)
	ds_write_b128 v247, v[156:159]
	ds_write_b128 v247, v[160:163] offset:1024
	ds_write_b128 v111, v[164:167] offset:2048
	ds_write_b128 v111, v[168:171] offset:3072
	ds_read_b128 v[156:159], v248
	ds_read_b128 v[160:163], v249
	ds_read_b128 v[164:167], v250
	ds_read_b128 v[168:171], v251
	ds_write_b128 v112, v[172:175]
	ds_write_b128 v112, v[176:179] offset:1024
	ds_write_b128 v112, v[180:183] offset:2048
	ds_write_b128 v112, v[184:187] offset:3072
	v_mfma_f32_32x32x16_bf16 v[32:47], v[120:123], v[52:55], v[32:47]
	v_mfma_f32_32x32x16_bf16 v[32:47], v[124:127], v[56:59], v[32:47]
	v_mfma_f32_32x32x16_bf16 v[32:47], v[128:131], v[60:63], v[32:47]
	s_nop 11
	v_exp_f32_e32 v32, v32
	v_exp_f32_e32 v33, v33
	v_exp_f32_e32 v34, v34
	v_exp_f32_e32 v35, v35
	v_exp_f32_e32 v36, v36
	v_exp_f32_e32 v37, v37
	v_exp_f32_e32 v38, v38
	v_exp_f32_e32 v39, v39
	v_exp_f32_e32 v40, v40
	v_exp_f32_e32 v41, v41
	v_exp_f32_e32 v42, v42
	v_exp_f32_e32 v43, v43
	v_exp_f32_e32 v44, v44
	v_exp_f32_e32 v45, v45
	v_exp_f32_e32 v46, v46
	v_exp_f32_e32 v47, v47
	v_cvt_pk_bf16_f32 v64, v32, v33
	v_cvt_pk_bf16_f32 v65, v34, v35
	v_cvt_pk_bf16_f32 v66, v36, v37
	v_cvt_pk_bf16_f32 v67, v38, v39
	v_cvt_pk_bf16_f32 v68, v40, v41
	v_cvt_pk_bf16_f32 v69, v42, v43
	v_cvt_pk_bf16_f32 v70, v44, v45
	v_cvt_pk_bf16_f32 v71, v46, v47
	v_pk_add_f32 v[232:233], v[232:233], v[32:33]
	v_pk_add_f32 v[232:233], v[232:233], v[34:35]
	v_pk_add_f32 v[232:233], v[232:233], v[36:37]
	v_pk_add_f32 v[232:233], v[232:233], v[38:39]
	v_pk_add_f32 v[232:233], v[232:233], v[40:41]
	v_pk_add_f32 v[232:233], v[232:233], v[42:43]
	v_pk_add_f32 v[232:233], v[232:233], v[44:45]
	v_pk_add_f32 v[232:233], v[232:233], v[46:47]
	v_add_u32_e32 v115, 952, v115
	ds_read2_b32 v[32:33], v115 offset0:0 offset1:1
	ds_read2_b32 v[34:35], v115 offset0:2 offset1:3
	ds_read2_b32 v[36:37], v115 offset0:8 offset1:9
	ds_read2_b32 v[38:39], v115 offset0:10 offset1:11
	ds_read2_b32 v[40:41], v115 offset0:17 offset1:18
	ds_read2_b32 v[42:43], v115 offset0:19 offset1:20
	ds_read2_b32 v[44:45], v115 offset0:25 offset1:26
	ds_read2_b32 v[46:47], v115 offset0:27 offset1:28
	s_waitcnt lgkmcnt(15)
	v_mfma_f32_32x32x16_bf16 v[0:15], v[64:67], v[72:75], v[0:15]
	v_mfma_f32_32x32x16_bf16 v[16:31], v[64:67], v[76:79], v[16:31]
	v_mfma_f32_32x32x16_bf16 v[0:15], v[68:71], v[220:223], v[0:15]
	v_mfma_f32_32x32x16_bf16 v[16:31], v[68:71], v[224:227], v[16:31]
	global_load_dwordx4 v[116:119], v235, s[84:85]
	global_load_dwordx4 v[120:123], v236, s[84:85]
	global_load_dwordx4 v[124:127], v237, s[84:85]
	global_load_dwordx4 v[128:131], v238, s[84:85]
	global_load_dwordx4 v[132:135], v100, s[84:85] offset:768
	global_load_dwordx4 v[136:139], v149, s[84:85] offset:768
	global_load_dwordx4 v[140:143], v100, s[84:85] offset:832
	global_load_dwordx4 v[144:147], v149, s[84:85] offset:832
	s_add_u32 s84, s84, 0x30000
	s_addc_u32 s85, s85, 0
	s_waitcnt lgkmcnt(0)
	v_mfma_f32_32x32x16_bf16 v[32:47], v[156:159], v[48:51], v[32:47]
	ds_read_b64_tr_b16 v[72:73], v231
	ds_read_b64_tr_b16 v[74:75], v231 offset:512
	ds_read_b64_tr_b16 v[76:77], v231 offset:2048
	ds_read_b64_tr_b16 v[78:79], v231 offset:2560
	ds_read_b64_tr_b16 v[220:221], v231 offset:1024
	ds_read_b64_tr_b16 v[222:223], v231 offset:1536
	ds_read_b64_tr_b16 v[224:225], v231 offset:3072
	ds_read_b64_tr_b16 v[226:227], v231 offset:3584
	s_waitcnt vmcnt(8)
	ds_write_b128 v247, v[188:191]
	ds_write_b128 v247, v[192:195] offset:1024
	ds_write_b128 v111, v[196:199] offset:2048
	ds_write_b128 v111, v[200:203] offset:3072
	ds_read_b128 v[188:191], v248
	ds_read_b128 v[192:195], v249
	ds_read_b128 v[196:199], v250
	ds_read_b128 v[200:203], v251
	ds_write_b128 v112, v[204:207]
	ds_write_b128 v112, v[208:211] offset:1024
	ds_write_b128 v112, v[212:215] offset:2048
	ds_write_b128 v112, v[216:219] offset:3072
	v_mfma_f32_32x32x16_bf16 v[32:47], v[160:163], v[52:55], v[32:47]
	v_mfma_f32_32x32x16_bf16 v[32:47], v[164:167], v[56:59], v[32:47]
	v_mfma_f32_32x32x16_bf16 v[32:47], v[168:171], v[60:63], v[32:47]
	s_nop 11
	v_exp_f32_e32 v32, v32
	v_exp_f32_e32 v33, v33
	v_exp_f32_e32 v34, v34
	v_exp_f32_e32 v35, v35
	v_exp_f32_e32 v36, v36
	v_exp_f32_e32 v37, v37
	v_exp_f32_e32 v38, v38
	v_exp_f32_e32 v39, v39
	v_exp_f32_e32 v40, v40
	v_exp_f32_e32 v41, v41
	v_exp_f32_e32 v42, v42
	v_exp_f32_e32 v43, v43
	v_exp_f32_e32 v44, v44
	v_exp_f32_e32 v45, v45
	v_exp_f32_e32 v46, v46
	v_exp_f32_e32 v47, v47
	v_cvt_pk_bf16_f32 v64, v32, v33
	v_cvt_pk_bf16_f32 v65, v34, v35
	v_cvt_pk_bf16_f32 v66, v36, v37
	v_cvt_pk_bf16_f32 v67, v38, v39
	v_cvt_pk_bf16_f32 v68, v40, v41
	v_cvt_pk_bf16_f32 v69, v42, v43
	v_cvt_pk_bf16_f32 v70, v44, v45
	v_cvt_pk_bf16_f32 v71, v46, v47
	v_pk_add_f32 v[232:233], v[232:233], v[32:33]
	v_pk_add_f32 v[232:233], v[232:233], v[34:35]
	v_pk_add_f32 v[232:233], v[232:233], v[36:37]
	v_pk_add_f32 v[232:233], v[232:233], v[38:39]
	v_pk_add_f32 v[232:233], v[232:233], v[40:41]
	v_pk_add_f32 v[232:233], v[232:233], v[42:43]
	v_pk_add_f32 v[232:233], v[232:233], v[44:45]
	v_pk_add_f32 v[232:233], v[232:233], v[46:47]
	ds_read2_b32 v[32:33], v115 offset0:34 offset1:35
	ds_read2_b32 v[34:35], v115 offset0:36 offset1:37
	ds_read2_b32 v[36:37], v115 offset0:42 offset1:43
	ds_read2_b32 v[38:39], v115 offset0:44 offset1:45
	ds_read2_b32 v[40:41], v115 offset0:51 offset1:52
	ds_read2_b32 v[42:43], v115 offset0:53 offset1:54
	ds_read2_b32 v[44:45], v115 offset0:59 offset1:60
	ds_read2_b32 v[46:47], v115 offset0:61 offset1:62
	s_waitcnt lgkmcnt(15)
	v_mfma_f32_32x32x16_bf16 v[0:15], v[64:67], v[72:75], v[0:15]
	v_mfma_f32_32x32x16_bf16 v[16:31], v[64:67], v[76:79], v[16:31]
	v_mfma_f32_32x32x16_bf16 v[0:15], v[68:71], v[220:223], v[0:15]
	v_mfma_f32_32x32x16_bf16 v[16:31], v[68:71], v[224:227], v[16:31]
	global_load_dwordx4 v[156:159], v235, s[84:85]
	global_load_dwordx4 v[160:163], v236, s[84:85]
	global_load_dwordx4 v[164:167], v237, s[84:85]
	global_load_dwordx4 v[168:171], v238, s[84:85]
	global_load_dwordx4 v[172:175], v100, s[84:85] offset:768
	global_load_dwordx4 v[176:179], v149, s[84:85] offset:768
	global_load_dwordx4 v[180:183], v100, s[84:85] offset:832
	global_load_dwordx4 v[184:187], v149, s[84:85] offset:832
	s_add_u32 s84, s84, 0x30000
	s_addc_u32 s85, s85, 0
	s_waitcnt lgkmcnt(0)
	v_mfma_f32_32x32x16_bf16 v[32:47], v[188:191], v[48:51], v[32:47]
	ds_read_b64_tr_b16 v[72:73], v231
	ds_read_b64_tr_b16 v[74:75], v231 offset:512
	ds_read_b64_tr_b16 v[76:77], v231 offset:2048
	ds_read_b64_tr_b16 v[78:79], v231 offset:2560
	ds_read_b64_tr_b16 v[220:221], v231 offset:1024
	ds_read_b64_tr_b16 v[222:223], v231 offset:1536
	ds_read_b64_tr_b16 v[224:225], v231 offset:3072
	ds_read_b64_tr_b16 v[226:227], v231 offset:3584
	s_waitcnt vmcnt(8)
	ds_write_b128 v247, v[116:119]
	ds_write_b128 v247, v[120:123] offset:1024
	ds_write_b128 v111, v[124:127] offset:2048
	ds_write_b128 v111, v[128:131] offset:3072
	ds_read_b128 v[116:119], v248
	ds_read_b128 v[120:123], v249
	ds_read_b128 v[124:127], v250
	ds_read_b128 v[128:131], v251
	ds_write_b128 v112, v[132:135]
	ds_write_b128 v112, v[136:139] offset:1024
	ds_write_b128 v112, v[140:143] offset:2048
	ds_write_b128 v112, v[144:147] offset:3072
	v_mfma_f32_32x32x16_bf16 v[32:47], v[192:195], v[52:55], v[32:47]
	v_mfma_f32_32x32x16_bf16 v[32:47], v[196:199], v[56:59], v[32:47]
	v_mfma_f32_32x32x16_bf16 v[32:47], v[200:203], v[60:63], v[32:47]
	s_nop 11
	v_exp_f32_e32 v32, v32
	v_exp_f32_e32 v33, v33
	v_exp_f32_e32 v34, v34
	v_exp_f32_e32 v35, v35
	v_exp_f32_e32 v36, v36
	v_exp_f32_e32 v37, v37
	v_exp_f32_e32 v38, v38
	v_exp_f32_e32 v39, v39
	v_exp_f32_e32 v40, v40
	v_exp_f32_e32 v41, v41
	v_exp_f32_e32 v42, v42
	v_exp_f32_e32 v43, v43
	v_exp_f32_e32 v44, v44
	v_exp_f32_e32 v45, v45
	v_exp_f32_e32 v46, v46
	v_exp_f32_e32 v47, v47
	v_cvt_pk_bf16_f32 v64, v32, v33
	v_cvt_pk_bf16_f32 v65, v34, v35
	v_cvt_pk_bf16_f32 v66, v36, v37
	v_cvt_pk_bf16_f32 v67, v38, v39
	v_cvt_pk_bf16_f32 v68, v40, v41
	v_cvt_pk_bf16_f32 v69, v42, v43
	v_cvt_pk_bf16_f32 v70, v44, v45
	v_cvt_pk_bf16_f32 v71, v46, v47
	v_pk_add_f32 v[232:233], v[232:233], v[32:33]
	v_pk_add_f32 v[232:233], v[232:233], v[34:35]
	v_pk_add_f32 v[232:233], v[232:233], v[36:37]
	v_pk_add_f32 v[232:233], v[232:233], v[38:39]
	v_pk_add_f32 v[232:233], v[232:233], v[40:41]
	v_pk_add_f32 v[232:233], v[232:233], v[42:43]
	v_pk_add_f32 v[232:233], v[232:233], v[44:45]
	v_pk_add_f32 v[232:233], v[232:233], v[46:47]
	ds_read2_b32 v[32:33], v115 offset0:68 offset1:69
	ds_read2_b32 v[34:35], v115 offset0:70 offset1:71
	ds_read2_b32 v[36:37], v115 offset0:76 offset1:77
	ds_read2_b32 v[38:39], v115 offset0:78 offset1:79
	ds_read2_b32 v[40:41], v115 offset0:85 offset1:86
	ds_read2_b32 v[42:43], v115 offset0:87 offset1:88
	ds_read2_b32 v[44:45], v115 offset0:93 offset1:94
	ds_read2_b32 v[46:47], v115 offset0:95 offset1:96
	s_waitcnt lgkmcnt(15)
	v_mfma_f32_32x32x16_bf16 v[0:15], v[64:67], v[72:75], v[0:15]
	v_mfma_f32_32x32x16_bf16 v[16:31], v[64:67], v[76:79], v[16:31]
	v_mfma_f32_32x32x16_bf16 v[0:15], v[68:71], v[220:223], v[0:15]
	v_mfma_f32_32x32x16_bf16 v[16:31], v[68:71], v[224:227], v[16:31]
	global_load_dwordx4 v[188:191], v235, s[84:85]
	global_load_dwordx4 v[192:195], v236, s[84:85]
	global_load_dwordx4 v[196:199], v237, s[84:85]
	global_load_dwordx4 v[200:203], v238, s[84:85]
	global_load_dwordx4 v[204:207], v100, s[84:85] offset:768
	global_load_dwordx4 v[208:211], v149, s[84:85] offset:768
	global_load_dwordx4 v[212:215], v100, s[84:85] offset:832
	global_load_dwordx4 v[216:219], v149, s[84:85] offset:832
	s_add_u32 s84, s84, 0x30000
	s_addc_u32 s85, s85, 0
	s_waitcnt lgkmcnt(0)
	v_mfma_f32_32x32x16_bf16 v[32:47], v[116:119], v[48:51], v[32:47]
	ds_read_b64_tr_b16 v[72:73], v231
	ds_read_b64_tr_b16 v[74:75], v231 offset:512
	ds_read_b64_tr_b16 v[76:77], v231 offset:2048
	ds_read_b64_tr_b16 v[78:79], v231 offset:2560
	ds_read_b64_tr_b16 v[220:221], v231 offset:1024
	ds_read_b64_tr_b16 v[222:223], v231 offset:1536
	ds_read_b64_tr_b16 v[224:225], v231 offset:3072
	ds_read_b64_tr_b16 v[226:227], v231 offset:3584
	s_waitcnt vmcnt(8)
	ds_write_b128 v247, v[156:159]
	ds_write_b128 v247, v[160:163] offset:1024
	ds_write_b128 v111, v[164:167] offset:2048
	ds_write_b128 v111, v[168:171] offset:3072
	ds_read_b128 v[156:159], v248
	ds_read_b128 v[160:163], v249
	ds_read_b128 v[164:167], v250
	ds_read_b128 v[168:171], v251
	ds_write_b128 v112, v[172:175]
	ds_write_b128 v112, v[176:179] offset:1024
	ds_write_b128 v112, v[180:183] offset:2048
	ds_write_b128 v112, v[184:187] offset:3072
	v_mfma_f32_32x32x16_bf16 v[32:47], v[120:123], v[52:55], v[32:47]
	v_mfma_f32_32x32x16_bf16 v[32:47], v[124:127], v[56:59], v[32:47]
	v_mfma_f32_32x32x16_bf16 v[32:47], v[128:131], v[60:63], v[32:47]
	s_nop 11
	v_exp_f32_e32 v32, v32
	v_exp_f32_e32 v33, v33
	v_exp_f32_e32 v34, v34
	v_exp_f32_e32 v35, v35
	v_exp_f32_e32 v36, v36
	v_exp_f32_e32 v37, v37
	v_exp_f32_e32 v38, v38
	v_exp_f32_e32 v39, v39
	v_exp_f32_e32 v40, v40
	v_exp_f32_e32 v41, v41
	v_exp_f32_e32 v42, v42
	v_exp_f32_e32 v43, v43
	v_exp_f32_e32 v44, v44
	v_exp_f32_e32 v45, v45
	v_exp_f32_e32 v46, v46
	v_exp_f32_e32 v47, v47
	v_cvt_pk_bf16_f32 v64, v32, v33
	v_cvt_pk_bf16_f32 v65, v34, v35
	v_cvt_pk_bf16_f32 v66, v36, v37
	v_cvt_pk_bf16_f32 v67, v38, v39
	v_cvt_pk_bf16_f32 v68, v40, v41
	v_cvt_pk_bf16_f32 v69, v42, v43
	v_cvt_pk_bf16_f32 v70, v44, v45
	v_cvt_pk_bf16_f32 v71, v46, v47
	v_pk_add_f32 v[232:233], v[232:233], v[32:33]
	v_pk_add_f32 v[232:233], v[232:233], v[34:35]
	v_pk_add_f32 v[232:233], v[232:233], v[36:37]
	v_pk_add_f32 v[232:233], v[232:233], v[38:39]
	v_pk_add_f32 v[232:233], v[232:233], v[40:41]
	v_pk_add_f32 v[232:233], v[232:233], v[42:43]
	v_pk_add_f32 v[232:233], v[232:233], v[44:45]
	v_pk_add_f32 v[232:233], v[232:233], v[46:47]
	ds_read2_b32 v[32:33], v115 offset0:102 offset1:103
	ds_read2_b32 v[34:35], v115 offset0:104 offset1:105
	ds_read2_b32 v[36:37], v115 offset0:110 offset1:111
	ds_read2_b32 v[38:39], v115 offset0:112 offset1:113
	ds_read2_b32 v[40:41], v115 offset0:119 offset1:120
	ds_read2_b32 v[42:43], v115 offset0:121 offset1:122
	ds_read2_b32 v[44:45], v115 offset0:127 offset1:128
	ds_read2_b32 v[46:47], v115 offset0:129 offset1:130
	s_waitcnt lgkmcnt(15)
	v_mfma_f32_32x32x16_bf16 v[0:15], v[64:67], v[72:75], v[0:15]
	v_mfma_f32_32x32x16_bf16 v[16:31], v[64:67], v[76:79], v[16:31]
	v_mfma_f32_32x32x16_bf16 v[0:15], v[68:71], v[220:223], v[0:15]
	v_mfma_f32_32x32x16_bf16 v[16:31], v[68:71], v[224:227], v[16:31]
	global_load_dwordx4 v[116:119], v235, s[84:85]
	global_load_dwordx4 v[120:123], v236, s[84:85]
	global_load_dwordx4 v[124:127], v237, s[84:85]
	global_load_dwordx4 v[128:131], v238, s[84:85]
	global_load_dwordx4 v[132:135], v100, s[84:85] offset:768
	global_load_dwordx4 v[136:139], v149, s[84:85] offset:768
	global_load_dwordx4 v[140:143], v100, s[84:85] offset:832
	global_load_dwordx4 v[144:147], v149, s[84:85] offset:832
	s_add_u32 s84, s84, 0x30000
	s_addc_u32 s85, s85, 0
	s_waitcnt lgkmcnt(0)
	v_mfma_f32_32x32x16_bf16 v[32:47], v[156:159], v[48:51], v[32:47]
	ds_read_b64_tr_b16 v[72:73], v231
	ds_read_b64_tr_b16 v[74:75], v231 offset:512
	ds_read_b64_tr_b16 v[76:77], v231 offset:2048
	ds_read_b64_tr_b16 v[78:79], v231 offset:2560
	ds_read_b64_tr_b16 v[220:221], v231 offset:1024
	ds_read_b64_tr_b16 v[222:223], v231 offset:1536
	ds_read_b64_tr_b16 v[224:225], v231 offset:3072
	ds_read_b64_tr_b16 v[226:227], v231 offset:3584
	s_waitcnt vmcnt(8)
	ds_write_b128 v247, v[188:191]
	ds_write_b128 v247, v[192:195] offset:1024
	ds_write_b128 v111, v[196:199] offset:2048
	ds_write_b128 v111, v[200:203] offset:3072
	ds_read_b128 v[188:191], v248
	ds_read_b128 v[192:195], v249
	ds_read_b128 v[196:199], v250
	ds_read_b128 v[200:203], v251
	ds_write_b128 v112, v[204:207]
	ds_write_b128 v112, v[208:211] offset:1024
	ds_write_b128 v112, v[212:215] offset:2048
	ds_write_b128 v112, v[216:219] offset:3072
	v_mfma_f32_32x32x16_bf16 v[32:47], v[160:163], v[52:55], v[32:47]
	v_mfma_f32_32x32x16_bf16 v[32:47], v[164:167], v[56:59], v[32:47]
	v_mfma_f32_32x32x16_bf16 v[32:47], v[168:171], v[60:63], v[32:47]
	s_nop 11
	v_exp_f32_e32 v32, v32
	v_exp_f32_e32 v33, v33
	v_exp_f32_e32 v34, v34
	v_exp_f32_e32 v35, v35
	v_exp_f32_e32 v36, v36
	v_exp_f32_e32 v37, v37
	v_exp_f32_e32 v38, v38
	v_exp_f32_e32 v39, v39
	v_exp_f32_e32 v40, v40
	v_exp_f32_e32 v41, v41
	v_exp_f32_e32 v42, v42
	v_exp_f32_e32 v43, v43
	v_exp_f32_e32 v44, v44
	v_exp_f32_e32 v45, v45
	v_exp_f32_e32 v46, v46
	v_exp_f32_e32 v47, v47
	v_cvt_pk_bf16_f32 v64, v32, v33
	v_cvt_pk_bf16_f32 v65, v34, v35
	v_cvt_pk_bf16_f32 v66, v36, v37
	v_cvt_pk_bf16_f32 v67, v38, v39
	v_cvt_pk_bf16_f32 v68, v40, v41
	v_cvt_pk_bf16_f32 v69, v42, v43
	v_cvt_pk_bf16_f32 v70, v44, v45
	v_cvt_pk_bf16_f32 v71, v46, v47
	v_pk_add_f32 v[232:233], v[232:233], v[32:33]
	v_pk_add_f32 v[232:233], v[232:233], v[34:35]
	v_pk_add_f32 v[232:233], v[232:233], v[36:37]
	v_pk_add_f32 v[232:233], v[232:233], v[38:39]
	v_pk_add_f32 v[232:233], v[232:233], v[40:41]
	v_pk_add_f32 v[232:233], v[232:233], v[42:43]
	v_pk_add_f32 v[232:233], v[232:233], v[44:45]
	v_pk_add_f32 v[232:233], v[232:233], v[46:47]
	ds_read2_b32 v[32:33], v115 offset0:136 offset1:137
	ds_read2_b32 v[34:35], v115 offset0:138 offset1:139
	ds_read2_b32 v[36:37], v115 offset0:144 offset1:145
	ds_read2_b32 v[38:39], v115 offset0:146 offset1:147
	ds_read2_b32 v[40:41], v115 offset0:153 offset1:154
	ds_read2_b32 v[42:43], v115 offset0:155 offset1:156
	ds_read2_b32 v[44:45], v115 offset0:161 offset1:162
	ds_read2_b32 v[46:47], v115 offset0:163 offset1:164
	s_waitcnt lgkmcnt(15)
	v_mfma_f32_32x32x16_bf16 v[0:15], v[64:67], v[72:75], v[0:15]
	v_mfma_f32_32x32x16_bf16 v[16:31], v[64:67], v[76:79], v[16:31]
	v_mfma_f32_32x32x16_bf16 v[0:15], v[68:71], v[220:223], v[0:15]
	v_mfma_f32_32x32x16_bf16 v[16:31], v[68:71], v[224:227], v[16:31]
	global_load_dwordx4 v[156:159], v235, s[84:85]
	global_load_dwordx4 v[160:163], v236, s[84:85]
	global_load_dwordx4 v[164:167], v237, s[84:85]
	global_load_dwordx4 v[168:171], v238, s[84:85]
	global_load_dwordx4 v[172:175], v100, s[84:85] offset:768
	global_load_dwordx4 v[176:179], v149, s[84:85] offset:768
	global_load_dwordx4 v[180:183], v100, s[84:85] offset:832
	global_load_dwordx4 v[184:187], v149, s[84:85] offset:832
	s_add_u32 s84, s84, 0x30000
	s_addc_u32 s85, s85, 0
	s_waitcnt lgkmcnt(0)
	v_mfma_f32_32x32x16_bf16 v[32:47], v[188:191], v[48:51], v[32:47]
	ds_read_b64_tr_b16 v[72:73], v231
	ds_read_b64_tr_b16 v[74:75], v231 offset:512
	ds_read_b64_tr_b16 v[76:77], v231 offset:2048
	ds_read_b64_tr_b16 v[78:79], v231 offset:2560
	ds_read_b64_tr_b16 v[220:221], v231 offset:1024
	ds_read_b64_tr_b16 v[222:223], v231 offset:1536
	ds_read_b64_tr_b16 v[224:225], v231 offset:3072
	ds_read_b64_tr_b16 v[226:227], v231 offset:3584
	s_waitcnt vmcnt(8)
	ds_write_b128 v247, v[116:119]
	ds_write_b128 v247, v[120:123] offset:1024
	ds_write_b128 v111, v[124:127] offset:2048
	ds_write_b128 v111, v[128:131] offset:3072
	ds_read_b128 v[116:119], v248
	ds_read_b128 v[120:123], v249
	ds_read_b128 v[124:127], v250
	ds_read_b128 v[128:131], v251
	ds_write_b128 v112, v[132:135]
	ds_write_b128 v112, v[136:139] offset:1024
	ds_write_b128 v112, v[140:143] offset:2048
	ds_write_b128 v112, v[144:147] offset:3072
	v_mfma_f32_32x32x16_bf16 v[32:47], v[192:195], v[52:55], v[32:47]
	v_mfma_f32_32x32x16_bf16 v[32:47], v[196:199], v[56:59], v[32:47]
	v_mfma_f32_32x32x16_bf16 v[32:47], v[200:203], v[60:63], v[32:47]
	s_nop 11
	v_exp_f32_e32 v32, v32
	v_exp_f32_e32 v33, v33
	v_exp_f32_e32 v34, v34
	v_exp_f32_e32 v35, v35
	v_exp_f32_e32 v36, v36
	v_exp_f32_e32 v37, v37
	v_exp_f32_e32 v38, v38
	v_exp_f32_e32 v39, v39
	v_exp_f32_e32 v40, v40
	v_exp_f32_e32 v41, v41
	v_exp_f32_e32 v42, v42
	v_exp_f32_e32 v43, v43
	v_exp_f32_e32 v44, v44
	v_exp_f32_e32 v45, v45
	v_exp_f32_e32 v46, v46
	v_exp_f32_e32 v47, v47
	v_cvt_pk_bf16_f32 v64, v32, v33
	v_cvt_pk_bf16_f32 v65, v34, v35
	v_cvt_pk_bf16_f32 v66, v36, v37
	v_cvt_pk_bf16_f32 v67, v38, v39
	v_cvt_pk_bf16_f32 v68, v40, v41
	v_cvt_pk_bf16_f32 v69, v42, v43
	v_cvt_pk_bf16_f32 v70, v44, v45
	v_cvt_pk_bf16_f32 v71, v46, v47
	v_pk_add_f32 v[232:233], v[232:233], v[32:33]
	v_pk_add_f32 v[232:233], v[232:233], v[34:35]
	v_pk_add_f32 v[232:233], v[232:233], v[36:37]
	v_pk_add_f32 v[232:233], v[232:233], v[38:39]
	v_pk_add_f32 v[232:233], v[232:233], v[40:41]
	v_pk_add_f32 v[232:233], v[232:233], v[42:43]
	v_pk_add_f32 v[232:233], v[232:233], v[44:45]
	v_pk_add_f32 v[232:233], v[232:233], v[46:47]
	ds_read2_b32 v[32:33], v115 offset0:170 offset1:171
	ds_read2_b32 v[34:35], v115 offset0:172 offset1:173
	ds_read2_b32 v[36:37], v115 offset0:178 offset1:179
	ds_read2_b32 v[38:39], v115 offset0:180 offset1:181
	ds_read2_b32 v[40:41], v115 offset0:187 offset1:188
	ds_read2_b32 v[42:43], v115 offset0:189 offset1:190
	ds_read2_b32 v[44:45], v115 offset0:195 offset1:196
	ds_read2_b32 v[46:47], v115 offset0:197 offset1:198
	s_waitcnt lgkmcnt(15)
	v_mfma_f32_32x32x16_bf16 v[0:15], v[64:67], v[72:75], v[0:15]
	v_mfma_f32_32x32x16_bf16 v[16:31], v[64:67], v[76:79], v[16:31]
	v_mfma_f32_32x32x16_bf16 v[0:15], v[68:71], v[220:223], v[0:15]
	v_mfma_f32_32x32x16_bf16 v[16:31], v[68:71], v[224:227], v[16:31]
	global_load_dwordx4 v[188:191], v235, s[84:85]
	global_load_dwordx4 v[192:195], v236, s[84:85]
	global_load_dwordx4 v[196:199], v237, s[84:85]
	global_load_dwordx4 v[200:203], v238, s[84:85]
	global_load_dwordx4 v[204:207], v100, s[84:85] offset:768
	global_load_dwordx4 v[208:211], v149, s[84:85] offset:768
	global_load_dwordx4 v[212:215], v100, s[84:85] offset:832
	global_load_dwordx4 v[216:219], v149, s[84:85] offset:832
	s_add_u32 s84, s84, 0x30000
	s_addc_u32 s85, s85, 0
	s_waitcnt lgkmcnt(0)
	v_mfma_f32_32x32x16_bf16 v[32:47], v[116:119], v[48:51], v[32:47]
	ds_read_b64_tr_b16 v[72:73], v231
	ds_read_b64_tr_b16 v[74:75], v231 offset:512
	ds_read_b64_tr_b16 v[76:77], v231 offset:2048
	ds_read_b64_tr_b16 v[78:79], v231 offset:2560
	ds_read_b64_tr_b16 v[220:221], v231 offset:1024
	ds_read_b64_tr_b16 v[222:223], v231 offset:1536
	ds_read_b64_tr_b16 v[224:225], v231 offset:3072
	ds_read_b64_tr_b16 v[226:227], v231 offset:3584
	s_waitcnt vmcnt(8)
	ds_write_b128 v247, v[156:159]
	ds_write_b128 v247, v[160:163] offset:1024
	ds_write_b128 v111, v[164:167] offset:2048
	ds_write_b128 v111, v[168:171] offset:3072
	ds_read_b128 v[156:159], v248
	ds_read_b128 v[160:163], v249
	ds_read_b128 v[164:167], v250
	ds_read_b128 v[168:171], v251
	ds_write_b128 v112, v[172:175]
	ds_write_b128 v112, v[176:179] offset:1024
	ds_write_b128 v112, v[180:183] offset:2048
	ds_write_b128 v112, v[184:187] offset:3072
	v_mfma_f32_32x32x16_bf16 v[32:47], v[120:123], v[52:55], v[32:47]
	v_mfma_f32_32x32x16_bf16 v[32:47], v[124:127], v[56:59], v[32:47]
	v_mfma_f32_32x32x16_bf16 v[32:47], v[128:131], v[60:63], v[32:47]
	s_nop 11
	v_exp_f32_e32 v32, v32
	v_exp_f32_e32 v33, v33
	v_exp_f32_e32 v34, v34
	v_exp_f32_e32 v35, v35
	v_exp_f32_e32 v36, v36
	v_exp_f32_e32 v37, v37
	v_exp_f32_e32 v38, v38
	v_exp_f32_e32 v39, v39
	v_exp_f32_e32 v40, v40
	v_exp_f32_e32 v41, v41
	v_exp_f32_e32 v42, v42
	v_exp_f32_e32 v43, v43
	v_exp_f32_e32 v44, v44
	v_exp_f32_e32 v45, v45
	v_exp_f32_e32 v46, v46
	v_exp_f32_e32 v47, v47
	v_cvt_pk_bf16_f32 v64, v32, v33
	v_cvt_pk_bf16_f32 v65, v34, v35
	v_cvt_pk_bf16_f32 v66, v36, v37
	v_cvt_pk_bf16_f32 v67, v38, v39
	v_cvt_pk_bf16_f32 v68, v40, v41
	v_cvt_pk_bf16_f32 v69, v42, v43
	v_cvt_pk_bf16_f32 v70, v44, v45
	v_cvt_pk_bf16_f32 v71, v46, v47
	v_pk_add_f32 v[232:233], v[232:233], v[32:33]
	v_pk_add_f32 v[232:233], v[232:233], v[34:35]
	v_pk_add_f32 v[232:233], v[232:233], v[36:37]
	v_pk_add_f32 v[232:233], v[232:233], v[38:39]
	v_pk_add_f32 v[232:233], v[232:233], v[40:41]
	v_pk_add_f32 v[232:233], v[232:233], v[42:43]
	v_pk_add_f32 v[232:233], v[232:233], v[44:45]
	v_pk_add_f32 v[232:233], v[232:233], v[46:47]
	ds_read2_b32 v[32:33], v115 offset0:204 offset1:205
	ds_read2_b32 v[34:35], v115 offset0:206 offset1:207
	ds_read2_b32 v[36:37], v115 offset0:212 offset1:213
	ds_read2_b32 v[38:39], v115 offset0:214 offset1:215
	ds_read2_b32 v[40:41], v115 offset0:221 offset1:222
	ds_read2_b32 v[42:43], v115 offset0:223 offset1:224
	ds_read2_b32 v[44:45], v115 offset0:229 offset1:230
	ds_read2_b32 v[46:47], v115 offset0:231 offset1:232
	s_waitcnt lgkmcnt(15)
	v_mfma_f32_32x32x16_bf16 v[0:15], v[64:67], v[72:75], v[0:15]
	v_mfma_f32_32x32x16_bf16 v[16:31], v[64:67], v[76:79], v[16:31]
	v_mfma_f32_32x32x16_bf16 v[0:15], v[68:71], v[220:223], v[0:15]
	v_mfma_f32_32x32x16_bf16 v[16:31], v[68:71], v[224:227], v[16:31]
	global_load_dwordx4 v[116:119], v235, s[84:85]
	global_load_dwordx4 v[120:123], v236, s[84:85]
	global_load_dwordx4 v[124:127], v237, s[84:85]
	global_load_dwordx4 v[128:131], v238, s[84:85]
	global_load_dwordx4 v[132:135], v100, s[84:85] offset:768
	global_load_dwordx4 v[136:139], v149, s[84:85] offset:768
	global_load_dwordx4 v[140:143], v100, s[84:85] offset:832
	global_load_dwordx4 v[144:147], v149, s[84:85] offset:832
	s_add_u32 s84, s84, 0x30000
	s_addc_u32 s85, s85, 0
	s_waitcnt lgkmcnt(0)
	v_mfma_f32_32x32x16_bf16 v[32:47], v[156:159], v[48:51], v[32:47]
	ds_read_b64_tr_b16 v[72:73], v231
	ds_read_b64_tr_b16 v[74:75], v231 offset:512
	ds_read_b64_tr_b16 v[76:77], v231 offset:2048
	ds_read_b64_tr_b16 v[78:79], v231 offset:2560
	ds_read_b64_tr_b16 v[220:221], v231 offset:1024
	ds_read_b64_tr_b16 v[222:223], v231 offset:1536
	ds_read_b64_tr_b16 v[224:225], v231 offset:3072
	ds_read_b64_tr_b16 v[226:227], v231 offset:3584
	s_waitcnt vmcnt(8)
	ds_write_b128 v247, v[188:191]
	ds_write_b128 v247, v[192:195] offset:1024
	ds_write_b128 v111, v[196:199] offset:2048
	ds_write_b128 v111, v[200:203] offset:3072
	ds_read_b128 v[188:191], v248
	ds_read_b128 v[192:195], v249
	ds_read_b128 v[196:199], v250
	ds_read_b128 v[200:203], v251
	ds_write_b128 v112, v[204:207]
	ds_write_b128 v112, v[208:211] offset:1024
	ds_write_b128 v112, v[212:215] offset:2048
	ds_write_b128 v112, v[216:219] offset:3072
	v_mfma_f32_32x32x16_bf16 v[32:47], v[160:163], v[52:55], v[32:47]
	v_mfma_f32_32x32x16_bf16 v[32:47], v[164:167], v[56:59], v[32:47]
	v_mfma_f32_32x32x16_bf16 v[32:47], v[168:171], v[60:63], v[32:47]
	s_nop 11
	v_exp_f32_e32 v32, v32
	v_exp_f32_e32 v33, v33
	v_exp_f32_e32 v34, v34
	v_exp_f32_e32 v35, v35
	v_exp_f32_e32 v36, v36
	v_exp_f32_e32 v37, v37
	v_exp_f32_e32 v38, v38
	v_exp_f32_e32 v39, v39
	v_exp_f32_e32 v40, v40
	v_exp_f32_e32 v41, v41
	v_exp_f32_e32 v42, v42
	v_exp_f32_e32 v43, v43
	v_exp_f32_e32 v44, v44
	v_exp_f32_e32 v45, v45
	v_exp_f32_e32 v46, v46
	v_exp_f32_e32 v47, v47
	v_cvt_pk_bf16_f32 v64, v32, v33
	v_cvt_pk_bf16_f32 v65, v34, v35
	v_cvt_pk_bf16_f32 v66, v36, v37
	v_cvt_pk_bf16_f32 v67, v38, v39
	v_cvt_pk_bf16_f32 v68, v40, v41
	v_cvt_pk_bf16_f32 v69, v42, v43
	v_cvt_pk_bf16_f32 v70, v44, v45
	v_cvt_pk_bf16_f32 v71, v46, v47
	v_pk_add_f32 v[232:233], v[232:233], v[32:33]
	v_pk_add_f32 v[232:233], v[232:233], v[34:35]
	v_pk_add_f32 v[232:233], v[232:233], v[36:37]
	v_pk_add_f32 v[232:233], v[232:233], v[38:39]
	v_pk_add_f32 v[232:233], v[232:233], v[40:41]
	v_pk_add_f32 v[232:233], v[232:233], v[42:43]
	v_pk_add_f32 v[232:233], v[232:233], v[44:45]
	v_pk_add_f32 v[232:233], v[232:233], v[46:47]
	v_add_u32_e32 v115, 952, v115
	ds_read2_b32 v[32:33], v115 offset0:0 offset1:1
	ds_read2_b32 v[34:35], v115 offset0:2 offset1:3
	ds_read2_b32 v[36:37], v115 offset0:8 offset1:9
	ds_read2_b32 v[38:39], v115 offset0:10 offset1:11
	ds_read2_b32 v[40:41], v115 offset0:17 offset1:18
	ds_read2_b32 v[42:43], v115 offset0:19 offset1:20
	ds_read2_b32 v[44:45], v115 offset0:25 offset1:26
	ds_read2_b32 v[46:47], v115 offset0:27 offset1:28
	s_waitcnt lgkmcnt(15)
	v_mfma_f32_32x32x16_bf16 v[0:15], v[64:67], v[72:75], v[0:15]
	v_mfma_f32_32x32x16_bf16 v[16:31], v[64:67], v[76:79], v[16:31]
	v_mfma_f32_32x32x16_bf16 v[0:15], v[68:71], v[220:223], v[0:15]
	v_mfma_f32_32x32x16_bf16 v[16:31], v[68:71], v[224:227], v[16:31]
	global_load_dwordx4 v[156:159], v235, s[84:85]
	global_load_dwordx4 v[160:163], v236, s[84:85]
	global_load_dwordx4 v[164:167], v237, s[84:85]
	global_load_dwordx4 v[168:171], v238, s[84:85]
	global_load_dwordx4 v[172:175], v100, s[84:85] offset:768
	global_load_dwordx4 v[176:179], v149, s[84:85] offset:768
	global_load_dwordx4 v[180:183], v100, s[84:85] offset:832
	global_load_dwordx4 v[184:187], v149, s[84:85] offset:832
	s_add_u32 s84, s84, 0x30000
	s_addc_u32 s85, s85, 0
	s_waitcnt lgkmcnt(0)
	v_mfma_f32_32x32x16_bf16 v[32:47], v[188:191], v[48:51], v[32:47]
	ds_read_b64_tr_b16 v[72:73], v231
	ds_read_b64_tr_b16 v[74:75], v231 offset:512
	ds_read_b64_tr_b16 v[76:77], v231 offset:2048
	ds_read_b64_tr_b16 v[78:79], v231 offset:2560
	ds_read_b64_tr_b16 v[220:221], v231 offset:1024
	ds_read_b64_tr_b16 v[222:223], v231 offset:1536
	ds_read_b64_tr_b16 v[224:225], v231 offset:3072
	ds_read_b64_tr_b16 v[226:227], v231 offset:3584
	s_waitcnt vmcnt(8)
	ds_write_b128 v247, v[116:119]
	ds_write_b128 v247, v[120:123] offset:1024
	ds_write_b128 v111, v[124:127] offset:2048
	ds_write_b128 v111, v[128:131] offset:3072
	ds_read_b128 v[116:119], v248
	ds_read_b128 v[120:123], v249
	ds_read_b128 v[124:127], v250
	ds_read_b128 v[128:131], v251
	ds_write_b128 v112, v[132:135]
	ds_write_b128 v112, v[136:139] offset:1024
	ds_write_b128 v112, v[140:143] offset:2048
	ds_write_b128 v112, v[144:147] offset:3072
	v_mfma_f32_32x32x16_bf16 v[32:47], v[192:195], v[52:55], v[32:47]
	v_mfma_f32_32x32x16_bf16 v[32:47], v[196:199], v[56:59], v[32:47]
	v_mfma_f32_32x32x16_bf16 v[32:47], v[200:203], v[60:63], v[32:47]
	s_nop 11
	v_exp_f32_e32 v32, v32
	v_exp_f32_e32 v33, v33
	v_exp_f32_e32 v34, v34
	v_exp_f32_e32 v35, v35
	v_exp_f32_e32 v36, v36
	v_exp_f32_e32 v37, v37
	v_exp_f32_e32 v38, v38
	v_exp_f32_e32 v39, v39
	v_exp_f32_e32 v40, v40
	v_exp_f32_e32 v41, v41
	v_exp_f32_e32 v42, v42
	v_exp_f32_e32 v43, v43
	v_exp_f32_e32 v44, v44
	v_exp_f32_e32 v45, v45
	v_exp_f32_e32 v46, v46
	v_exp_f32_e32 v47, v47
	v_cvt_pk_bf16_f32 v64, v32, v33
	v_cvt_pk_bf16_f32 v65, v34, v35
	v_cvt_pk_bf16_f32 v66, v36, v37
	v_cvt_pk_bf16_f32 v67, v38, v39
	v_cvt_pk_bf16_f32 v68, v40, v41
	v_cvt_pk_bf16_f32 v69, v42, v43
	v_cvt_pk_bf16_f32 v70, v44, v45
	v_cvt_pk_bf16_f32 v71, v46, v47
	v_pk_add_f32 v[232:233], v[232:233], v[32:33]
	v_pk_add_f32 v[232:233], v[232:233], v[34:35]
	v_pk_add_f32 v[232:233], v[232:233], v[36:37]
	v_pk_add_f32 v[232:233], v[232:233], v[38:39]
	v_pk_add_f32 v[232:233], v[232:233], v[40:41]
	v_pk_add_f32 v[232:233], v[232:233], v[42:43]
	v_pk_add_f32 v[232:233], v[232:233], v[44:45]
	v_pk_add_f32 v[232:233], v[232:233], v[46:47]
	ds_read2_b32 v[32:33], v115 offset0:34 offset1:35
	ds_read2_b32 v[34:35], v115 offset0:36 offset1:37
	ds_read2_b32 v[36:37], v115 offset0:42 offset1:43
	ds_read2_b32 v[38:39], v115 offset0:44 offset1:45
	ds_read2_b32 v[40:41], v115 offset0:51 offset1:52
	ds_read2_b32 v[42:43], v115 offset0:53 offset1:54
	ds_read2_b32 v[44:45], v115 offset0:59 offset1:60
	ds_read2_b32 v[46:47], v115 offset0:61 offset1:62
	s_waitcnt lgkmcnt(15)
	v_mfma_f32_32x32x16_bf16 v[0:15], v[64:67], v[72:75], v[0:15]
	v_mfma_f32_32x32x16_bf16 v[16:31], v[64:67], v[76:79], v[16:31]
	v_mfma_f32_32x32x16_bf16 v[0:15], v[68:71], v[220:223], v[0:15]
	v_mfma_f32_32x32x16_bf16 v[16:31], v[68:71], v[224:227], v[16:31]
	global_load_dwordx4 v[188:191], v235, s[84:85]
	global_load_dwordx4 v[192:195], v236, s[84:85]
	global_load_dwordx4 v[196:199], v237, s[84:85]
	global_load_dwordx4 v[200:203], v238, s[84:85]
	global_load_dwordx4 v[204:207], v100, s[84:85] offset:768
	global_load_dwordx4 v[208:211], v149, s[84:85] offset:768
	global_load_dwordx4 v[212:215], v100, s[84:85] offset:832
	global_load_dwordx4 v[216:219], v149, s[84:85] offset:832
	s_add_u32 s84, s84, 0x30000
	s_addc_u32 s85, s85, 0
	s_waitcnt lgkmcnt(0)
	v_mfma_f32_32x32x16_bf16 v[32:47], v[116:119], v[48:51], v[32:47]
	ds_read_b64_tr_b16 v[72:73], v231
	ds_read_b64_tr_b16 v[74:75], v231 offset:512
	ds_read_b64_tr_b16 v[76:77], v231 offset:2048
	ds_read_b64_tr_b16 v[78:79], v231 offset:2560
	ds_read_b64_tr_b16 v[220:221], v231 offset:1024
	ds_read_b64_tr_b16 v[222:223], v231 offset:1536
	ds_read_b64_tr_b16 v[224:225], v231 offset:3072
	ds_read_b64_tr_b16 v[226:227], v231 offset:3584
	s_waitcnt vmcnt(8)
	ds_write_b128 v247, v[156:159]
	ds_write_b128 v247, v[160:163] offset:1024
	ds_write_b128 v111, v[164:167] offset:2048
	ds_write_b128 v111, v[168:171] offset:3072
	ds_read_b128 v[156:159], v248
	ds_read_b128 v[160:163], v249
	ds_read_b128 v[164:167], v250
	ds_read_b128 v[168:171], v251
	ds_write_b128 v112, v[172:175]
	ds_write_b128 v112, v[176:179] offset:1024
	ds_write_b128 v112, v[180:183] offset:2048
	ds_write_b128 v112, v[184:187] offset:3072
	v_mfma_f32_32x32x16_bf16 v[32:47], v[120:123], v[52:55], v[32:47]
	v_mfma_f32_32x32x16_bf16 v[32:47], v[124:127], v[56:59], v[32:47]
	v_mfma_f32_32x32x16_bf16 v[32:47], v[128:131], v[60:63], v[32:47]
	s_nop 11
	v_exp_f32_e32 v32, v32
	v_exp_f32_e32 v33, v33
	v_exp_f32_e32 v34, v34
	v_exp_f32_e32 v35, v35
	v_exp_f32_e32 v36, v36
	v_exp_f32_e32 v37, v37
	v_exp_f32_e32 v38, v38
	v_exp_f32_e32 v39, v39
	v_exp_f32_e32 v40, v40
	v_exp_f32_e32 v41, v41
	v_exp_f32_e32 v42, v42
	v_exp_f32_e32 v43, v43
	v_exp_f32_e32 v44, v44
	v_exp_f32_e32 v45, v45
	v_exp_f32_e32 v46, v46
	v_exp_f32_e32 v47, v47
	v_cvt_pk_bf16_f32 v64, v32, v33
	v_cvt_pk_bf16_f32 v65, v34, v35
	v_cvt_pk_bf16_f32 v66, v36, v37
	v_cvt_pk_bf16_f32 v67, v38, v39
	v_cvt_pk_bf16_f32 v68, v40, v41
	v_cvt_pk_bf16_f32 v69, v42, v43
	v_cvt_pk_bf16_f32 v70, v44, v45
	v_cvt_pk_bf16_f32 v71, v46, v47
	v_pk_add_f32 v[232:233], v[232:233], v[32:33]
	v_pk_add_f32 v[232:233], v[232:233], v[34:35]
	v_pk_add_f32 v[232:233], v[232:233], v[36:37]
	v_pk_add_f32 v[232:233], v[232:233], v[38:39]
	v_pk_add_f32 v[232:233], v[232:233], v[40:41]
	v_pk_add_f32 v[232:233], v[232:233], v[42:43]
	v_pk_add_f32 v[232:233], v[232:233], v[44:45]
	v_pk_add_f32 v[232:233], v[232:233], v[46:47]
	ds_read2_b32 v[32:33], v115 offset0:68 offset1:69
	ds_read2_b32 v[34:35], v115 offset0:70 offset1:71
	ds_read2_b32 v[36:37], v115 offset0:76 offset1:77
	ds_read2_b32 v[38:39], v115 offset0:78 offset1:79
	ds_read2_b32 v[40:41], v115 offset0:85 offset1:86
	ds_read2_b32 v[42:43], v115 offset0:87 offset1:88
	ds_read2_b32 v[44:45], v115 offset0:93 offset1:94
	ds_read2_b32 v[46:47], v115 offset0:95 offset1:96
	s_waitcnt lgkmcnt(15)
	v_mfma_f32_32x32x16_bf16 v[0:15], v[64:67], v[72:75], v[0:15]
	v_mfma_f32_32x32x16_bf16 v[16:31], v[64:67], v[76:79], v[16:31]
	v_mfma_f32_32x32x16_bf16 v[0:15], v[68:71], v[220:223], v[0:15]
	v_mfma_f32_32x32x16_bf16 v[16:31], v[68:71], v[224:227], v[16:31]
	global_load_dwordx4 v[116:119], v235, s[84:85]
	global_load_dwordx4 v[120:123], v236, s[84:85]
	global_load_dwordx4 v[124:127], v237, s[84:85]
	global_load_dwordx4 v[128:131], v238, s[84:85]
	global_load_dwordx4 v[132:135], v100, s[84:85] offset:768
	global_load_dwordx4 v[136:139], v149, s[84:85] offset:768
	global_load_dwordx4 v[140:143], v100, s[84:85] offset:832
	global_load_dwordx4 v[144:147], v149, s[84:85] offset:832
	s_add_u32 s84, s84, 0x30000
	s_addc_u32 s85, s85, 0
	s_waitcnt lgkmcnt(0)
	v_mfma_f32_32x32x16_bf16 v[32:47], v[156:159], v[48:51], v[32:47]
	ds_read_b64_tr_b16 v[72:73], v231
	ds_read_b64_tr_b16 v[74:75], v231 offset:512
	ds_read_b64_tr_b16 v[76:77], v231 offset:2048
	ds_read_b64_tr_b16 v[78:79], v231 offset:2560
	ds_read_b64_tr_b16 v[220:221], v231 offset:1024
	ds_read_b64_tr_b16 v[222:223], v231 offset:1536
	ds_read_b64_tr_b16 v[224:225], v231 offset:3072
	ds_read_b64_tr_b16 v[226:227], v231 offset:3584
	s_waitcnt vmcnt(8)
	ds_write_b128 v247, v[188:191]
	ds_write_b128 v247, v[192:195] offset:1024
	ds_write_b128 v111, v[196:199] offset:2048
	ds_write_b128 v111, v[200:203] offset:3072
	ds_read_b128 v[188:191], v248
	ds_read_b128 v[192:195], v249
	ds_read_b128 v[196:199], v250
	ds_read_b128 v[200:203], v251
	ds_write_b128 v112, v[204:207]
	ds_write_b128 v112, v[208:211] offset:1024
	ds_write_b128 v112, v[212:215] offset:2048
	ds_write_b128 v112, v[216:219] offset:3072
	v_mfma_f32_32x32x16_bf16 v[32:47], v[160:163], v[52:55], v[32:47]
	v_mfma_f32_32x32x16_bf16 v[32:47], v[164:167], v[56:59], v[32:47]
	v_mfma_f32_32x32x16_bf16 v[32:47], v[168:171], v[60:63], v[32:47]
	s_nop 11
	v_exp_f32_e32 v32, v32
	v_exp_f32_e32 v33, v33
	v_exp_f32_e32 v34, v34
	v_exp_f32_e32 v35, v35
	v_exp_f32_e32 v36, v36
	v_exp_f32_e32 v37, v37
	v_exp_f32_e32 v38, v38
	v_exp_f32_e32 v39, v39
	v_exp_f32_e32 v40, v40
	v_exp_f32_e32 v41, v41
	v_exp_f32_e32 v42, v42
	v_exp_f32_e32 v43, v43
	v_exp_f32_e32 v44, v44
	v_exp_f32_e32 v45, v45
	v_exp_f32_e32 v46, v46
	v_exp_f32_e32 v47, v47
	v_cvt_pk_bf16_f32 v64, v32, v33
	v_cvt_pk_bf16_f32 v65, v34, v35
	v_cvt_pk_bf16_f32 v66, v36, v37
	v_cvt_pk_bf16_f32 v67, v38, v39
	v_cvt_pk_bf16_f32 v68, v40, v41
	v_cvt_pk_bf16_f32 v69, v42, v43
	v_cvt_pk_bf16_f32 v70, v44, v45
	v_cvt_pk_bf16_f32 v71, v46, v47
	v_pk_add_f32 v[232:233], v[232:233], v[32:33]
	v_pk_add_f32 v[232:233], v[232:233], v[34:35]
	v_pk_add_f32 v[232:233], v[232:233], v[36:37]
	v_pk_add_f32 v[232:233], v[232:233], v[38:39]
	v_pk_add_f32 v[232:233], v[232:233], v[40:41]
	v_pk_add_f32 v[232:233], v[232:233], v[42:43]
	v_pk_add_f32 v[232:233], v[232:233], v[44:45]
	v_pk_add_f32 v[232:233], v[232:233], v[46:47]
	ds_read2_b32 v[32:33], v115 offset0:102 offset1:103
	ds_read2_b32 v[34:35], v115 offset0:104 offset1:105
	ds_read2_b32 v[36:37], v115 offset0:110 offset1:111
	ds_read2_b32 v[38:39], v115 offset0:112 offset1:113
	ds_read2_b32 v[40:41], v115 offset0:119 offset1:120
	ds_read2_b32 v[42:43], v115 offset0:121 offset1:122
	ds_read2_b32 v[44:45], v115 offset0:127 offset1:128
	ds_read2_b32 v[46:47], v115 offset0:129 offset1:130
	s_waitcnt lgkmcnt(15)
	v_mfma_f32_32x32x16_bf16 v[0:15], v[64:67], v[72:75], v[0:15]
	v_mfma_f32_32x32x16_bf16 v[16:31], v[64:67], v[76:79], v[16:31]
	v_mfma_f32_32x32x16_bf16 v[0:15], v[68:71], v[220:223], v[0:15]
	v_mfma_f32_32x32x16_bf16 v[16:31], v[68:71], v[224:227], v[16:31]
	global_load_dwordx4 v[156:159], v235, s[84:85]
	global_load_dwordx4 v[160:163], v236, s[84:85]
	global_load_dwordx4 v[164:167], v237, s[84:85]
	global_load_dwordx4 v[168:171], v238, s[84:85]
	global_load_dwordx4 v[172:175], v100, s[84:85] offset:768
	global_load_dwordx4 v[176:179], v149, s[84:85] offset:768
	global_load_dwordx4 v[180:183], v100, s[84:85] offset:832
	global_load_dwordx4 v[184:187], v149, s[84:85] offset:832
	s_waitcnt lgkmcnt(0)
	v_mfma_f32_32x32x16_bf16 v[32:47], v[188:191], v[48:51], v[32:47]
	ds_read_b64_tr_b16 v[72:73], v231
	ds_read_b64_tr_b16 v[74:75], v231 offset:512
	ds_read_b64_tr_b16 v[76:77], v231 offset:2048
	ds_read_b64_tr_b16 v[78:79], v231 offset:2560
	ds_read_b64_tr_b16 v[220:221], v231 offset:1024
	ds_read_b64_tr_b16 v[222:223], v231 offset:1536
	ds_read_b64_tr_b16 v[224:225], v231 offset:3072
	ds_read_b64_tr_b16 v[226:227], v231 offset:3584
	s_waitcnt vmcnt(8)
	ds_write_b128 v247, v[116:119]
	ds_write_b128 v247, v[120:123] offset:1024
	ds_write_b128 v111, v[124:127] offset:2048
	ds_write_b128 v111, v[128:131] offset:3072
	ds_read_b128 v[116:119], v248
	ds_read_b128 v[120:123], v249
	ds_read_b128 v[124:127], v250
	ds_read_b128 v[128:131], v251
	ds_write_b128 v112, v[132:135]
	ds_write_b128 v112, v[136:139] offset:1024
	ds_write_b128 v112, v[140:143] offset:2048
	ds_write_b128 v112, v[144:147] offset:3072
	v_mfma_f32_32x32x16_bf16 v[32:47], v[192:195], v[52:55], v[32:47]
	v_mfma_f32_32x32x16_bf16 v[32:47], v[196:199], v[56:59], v[32:47]
	v_mfma_f32_32x32x16_bf16 v[32:47], v[200:203], v[60:63], v[32:47]
	s_nop 11
	v_exp_f32_e32 v32, v32
	v_exp_f32_e32 v33, v33
	v_exp_f32_e32 v34, v34
	v_exp_f32_e32 v35, v35
	v_exp_f32_e32 v36, v36
	v_exp_f32_e32 v37, v37
	v_exp_f32_e32 v38, v38
	v_exp_f32_e32 v39, v39
	v_exp_f32_e32 v40, v40
	v_exp_f32_e32 v41, v41
	v_exp_f32_e32 v42, v42
	v_exp_f32_e32 v43, v43
	v_exp_f32_e32 v44, v44
	v_exp_f32_e32 v45, v45
	v_exp_f32_e32 v46, v46
	v_exp_f32_e32 v47, v47
	v_cvt_pk_bf16_f32 v64, v32, v33
	v_cvt_pk_bf16_f32 v65, v34, v35
	v_cvt_pk_bf16_f32 v66, v36, v37
	v_cvt_pk_bf16_f32 v67, v38, v39
	v_cvt_pk_bf16_f32 v68, v40, v41
	v_cvt_pk_bf16_f32 v69, v42, v43
	v_cvt_pk_bf16_f32 v70, v44, v45
	v_cvt_pk_bf16_f32 v71, v46, v47
	v_pk_add_f32 v[232:233], v[232:233], v[32:33]
	v_pk_add_f32 v[232:233], v[232:233], v[34:35]
	v_pk_add_f32 v[232:233], v[232:233], v[36:37]
	v_pk_add_f32 v[232:233], v[232:233], v[38:39]
	v_pk_add_f32 v[232:233], v[232:233], v[40:41]
	v_pk_add_f32 v[232:233], v[232:233], v[42:43]
	v_pk_add_f32 v[232:233], v[232:233], v[44:45]
	v_pk_add_f32 v[232:233], v[232:233], v[46:47]
	ds_read2_b32 v[32:33], v115 offset0:136 offset1:137
	ds_read2_b32 v[34:35], v115 offset0:138 offset1:139
	ds_read2_b32 v[36:37], v115 offset0:144 offset1:145
	ds_read2_b32 v[38:39], v115 offset0:146 offset1:147
	ds_read2_b32 v[40:41], v115 offset0:153 offset1:154
	ds_read2_b32 v[42:43], v115 offset0:155 offset1:156
	ds_read2_b32 v[44:45], v115 offset0:161 offset1:162
	ds_read2_b32 v[46:47], v115 offset0:163 offset1:164
	s_waitcnt lgkmcnt(15)
	v_mfma_f32_32x32x16_bf16 v[0:15], v[64:67], v[72:75], v[0:15]
	v_mfma_f32_32x32x16_bf16 v[16:31], v[64:67], v[76:79], v[16:31]
	v_mfma_f32_32x32x16_bf16 v[0:15], v[68:71], v[220:223], v[0:15]
	v_mfma_f32_32x32x16_bf16 v[16:31], v[68:71], v[224:227], v[16:31]
	global_load_dwordx4 v[188:191], v239, s[86:87]
	global_load_dwordx4 v[192:195], v240, s[86:87]
	global_load_dwordx4 v[196:199], v241, s[86:87]
	global_load_dwordx4 v[200:203], v242, s[86:87]
	global_load_dwordx4 v[204:207], v101, s[86:87] offset:768
	global_load_dwordx4 v[208:211], v150, s[86:87] offset:768
	global_load_dwordx4 v[212:215], v101, s[86:87] offset:832
	global_load_dwordx4 v[216:219], v150, s[86:87] offset:832
	s_add_u32 s86, s86, 0xc0000
	s_addc_u32 s87, s87, 0
	s_waitcnt lgkmcnt(0)
	v_mfma_f32_32x32x16_bf16 v[32:47], v[116:119], v[48:51], v[32:47]
	ds_read_b64_tr_b16 v[72:73], v231
	ds_read_b64_tr_b16 v[74:75], v231 offset:512
	ds_read_b64_tr_b16 v[76:77], v231 offset:2048
	ds_read_b64_tr_b16 v[78:79], v231 offset:2560
	ds_read_b64_tr_b16 v[220:221], v231 offset:1024
	ds_read_b64_tr_b16 v[222:223], v231 offset:1536
	ds_read_b64_tr_b16 v[224:225], v231 offset:3072
	ds_read_b64_tr_b16 v[226:227], v231 offset:3584
	s_waitcnt vmcnt(8)
	ds_write_b128 v247, v[156:159]
	ds_write_b128 v247, v[160:163] offset:1024
	ds_write_b128 v111, v[164:167] offset:2048
	ds_write_b128 v111, v[168:171] offset:3072
	ds_read_b128 v[156:159], v248
	ds_read_b128 v[160:163], v249
	ds_read_b128 v[164:167], v250
	ds_read_b128 v[168:171], v251
	ds_write_b128 v112, v[172:175]
	ds_write_b128 v112, v[176:179] offset:1024
	ds_write_b128 v112, v[180:183] offset:2048
	ds_write_b128 v112, v[184:187] offset:3072
	v_mfma_f32_32x32x16_bf16 v[32:47], v[120:123], v[52:55], v[32:47]
	v_mfma_f32_32x32x16_bf16 v[32:47], v[124:127], v[56:59], v[32:47]
	v_mfma_f32_32x32x16_bf16 v[32:47], v[128:131], v[60:63], v[32:47]
	s_nop 11
	v_exp_f32_e32 v32, v32
	v_exp_f32_e32 v33, v33
	v_exp_f32_e32 v34, v34
	v_exp_f32_e32 v35, v35
	v_exp_f32_e32 v36, v36
	v_exp_f32_e32 v37, v37
	v_exp_f32_e32 v38, v38
	v_exp_f32_e32 v39, v39
	v_exp_f32_e32 v40, v40
	v_exp_f32_e32 v41, v41
	v_exp_f32_e32 v42, v42
	v_exp_f32_e32 v43, v43
	v_exp_f32_e32 v44, v44
	v_exp_f32_e32 v45, v45
	v_exp_f32_e32 v46, v46
	v_exp_f32_e32 v47, v47
	v_cvt_pk_bf16_f32 v64, v32, v33
	v_cvt_pk_bf16_f32 v65, v34, v35
	v_cvt_pk_bf16_f32 v66, v36, v37
	v_cvt_pk_bf16_f32 v67, v38, v39
	v_cvt_pk_bf16_f32 v68, v40, v41
	v_cvt_pk_bf16_f32 v69, v42, v43
	v_cvt_pk_bf16_f32 v70, v44, v45
	v_cvt_pk_bf16_f32 v71, v46, v47
	v_pk_add_f32 v[232:233], v[232:233], v[32:33]
	v_pk_add_f32 v[232:233], v[232:233], v[34:35]
	v_pk_add_f32 v[232:233], v[232:233], v[36:37]
	v_pk_add_f32 v[232:233], v[232:233], v[38:39]
	v_pk_add_f32 v[232:233], v[232:233], v[40:41]
	v_pk_add_f32 v[232:233], v[232:233], v[42:43]
	v_pk_add_f32 v[232:233], v[232:233], v[44:45]
	v_pk_add_f32 v[232:233], v[232:233], v[46:47]
	ds_read2_b32 v[32:33], v115 offset0:170 offset1:171
	ds_read2_b32 v[34:35], v115 offset0:172 offset1:173
	ds_read2_b32 v[36:37], v115 offset0:178 offset1:179
	ds_read2_b32 v[38:39], v115 offset0:180 offset1:181
	ds_read2_b32 v[40:41], v115 offset0:187 offset1:188
	ds_read2_b32 v[42:43], v115 offset0:189 offset1:190
	ds_read2_b32 v[44:45], v115 offset0:195 offset1:196
	ds_read2_b32 v[46:47], v115 offset0:197 offset1:198
	s_waitcnt lgkmcnt(15)
	v_mfma_f32_32x32x16_bf16 v[0:15], v[64:67], v[72:75], v[0:15]
	v_mfma_f32_32x32x16_bf16 v[16:31], v[64:67], v[76:79], v[16:31]
	v_mfma_f32_32x32x16_bf16 v[0:15], v[68:71], v[220:223], v[0:15]
	v_mfma_f32_32x32x16_bf16 v[16:31], v[68:71], v[224:227], v[16:31]
	global_load_dwordx4 v[116:119], v239, s[86:87]
	global_load_dwordx4 v[120:123], v240, s[86:87]
	global_load_dwordx4 v[124:127], v241, s[86:87]
	global_load_dwordx4 v[128:131], v242, s[86:87]
	global_load_dwordx4 v[132:135], v101, s[86:87] offset:768
	global_load_dwordx4 v[136:139], v150, s[86:87] offset:768
	global_load_dwordx4 v[140:143], v101, s[86:87] offset:832
	global_load_dwordx4 v[144:147], v150, s[86:87] offset:832
	s_add_u32 s86, s86, 0xc0000
	s_addc_u32 s87, s87, 0
	s_waitcnt lgkmcnt(0)
	v_mfma_f32_32x32x16_bf16 v[32:47], v[156:159], v[48:51], v[32:47]
	ds_read_b64_tr_b16 v[72:73], v231
	ds_read_b64_tr_b16 v[74:75], v231 offset:512
	ds_read_b64_tr_b16 v[76:77], v231 offset:2048
	ds_read_b64_tr_b16 v[78:79], v231 offset:2560
	ds_read_b64_tr_b16 v[220:221], v231 offset:1024
	ds_read_b64_tr_b16 v[222:223], v231 offset:1536
	ds_read_b64_tr_b16 v[224:225], v231 offset:3072
	ds_read_b64_tr_b16 v[226:227], v231 offset:3584
	s_waitcnt vmcnt(8)
	ds_write_b128 v247, v[188:191]
	ds_write_b128 v247, v[192:195] offset:1024
	ds_write_b128 v111, v[196:199] offset:2048
	ds_write_b128 v111, v[200:203] offset:3072
	ds_read_b128 v[188:191], v248
	ds_read_b128 v[192:195], v249
	ds_read_b128 v[196:199], v250
	ds_read_b128 v[200:203], v251
	ds_write_b128 v112, v[204:207]
	ds_write_b128 v112, v[208:211] offset:1024
	ds_write_b128 v112, v[212:215] offset:2048
	ds_write_b128 v112, v[216:219] offset:3072
	v_mfma_f32_32x32x16_bf16 v[32:47], v[160:163], v[52:55], v[32:47]
	v_mfma_f32_32x32x16_bf16 v[32:47], v[164:167], v[56:59], v[32:47]
	v_mfma_f32_32x32x16_bf16 v[32:47], v[168:171], v[60:63], v[32:47]
	s_nop 11
	v_exp_f32_e32 v32, v32
	v_exp_f32_e32 v33, v33
	v_exp_f32_e32 v34, v34
	v_exp_f32_e32 v35, v35
	v_exp_f32_e32 v36, v36
	v_exp_f32_e32 v37, v37
	v_exp_f32_e32 v38, v38
	v_exp_f32_e32 v39, v39
	v_exp_f32_e32 v40, v40
	v_exp_f32_e32 v41, v41
	v_exp_f32_e32 v42, v42
	v_exp_f32_e32 v43, v43
	v_exp_f32_e32 v44, v44
	v_exp_f32_e32 v45, v45
	v_exp_f32_e32 v46, v46
	v_exp_f32_e32 v47, v47
	v_cvt_pk_bf16_f32 v64, v32, v33
	v_cvt_pk_bf16_f32 v65, v34, v35
	v_cvt_pk_bf16_f32 v66, v36, v37
	v_cvt_pk_bf16_f32 v67, v38, v39
	v_cvt_pk_bf16_f32 v68, v40, v41
	v_cvt_pk_bf16_f32 v69, v42, v43
	v_cvt_pk_bf16_f32 v70, v44, v45
	v_cvt_pk_bf16_f32 v71, v46, v47
	v_pk_add_f32 v[232:233], v[232:233], v[32:33]
	v_pk_add_f32 v[232:233], v[232:233], v[34:35]
	v_pk_add_f32 v[232:233], v[232:233], v[36:37]
	v_pk_add_f32 v[232:233], v[232:233], v[38:39]
	v_pk_add_f32 v[232:233], v[232:233], v[40:41]
	v_pk_add_f32 v[232:233], v[232:233], v[42:43]
	v_pk_add_f32 v[232:233], v[232:233], v[44:45]
	v_pk_add_f32 v[232:233], v[232:233], v[46:47]
	v_mov_b32_e32 v115, v229
	ds_read2_b32 v[32:33], v115 offset0:0 offset1:1
	ds_read2_b32 v[34:35], v115 offset0:2 offset1:3
	ds_read2_b32 v[36:37], v115 offset0:10 offset1:11
	ds_read2_b32 v[38:39], v115 offset0:12 offset1:13
	ds_read2_b32 v[40:41], v115 offset0:20 offset1:21
	ds_read2_b32 v[42:43], v115 offset0:22 offset1:23
	ds_read2_b32 v[44:45], v115 offset0:30 offset1:31
	ds_read2_b32 v[46:47], v115 offset0:32 offset1:33
	s_waitcnt lgkmcnt(15)
	v_mfma_f32_32x32x16_bf16 v[0:15], v[64:67], v[72:75], v[0:15]
	v_mfma_f32_32x32x16_bf16 v[16:31], v[64:67], v[76:79], v[16:31]
	v_mfma_f32_32x32x16_bf16 v[0:15], v[68:71], v[220:223], v[0:15]
	v_mfma_f32_32x32x16_bf16 v[16:31], v[68:71], v[224:227], v[16:31]
	global_load_dwordx4 v[156:159], v239, s[86:87]
	global_load_dwordx4 v[160:163], v240, s[86:87]
	global_load_dwordx4 v[164:167], v241, s[86:87]
	global_load_dwordx4 v[168:171], v242, s[86:87]
	global_load_dwordx4 v[172:175], v101, s[86:87] offset:768
	global_load_dwordx4 v[176:179], v150, s[86:87] offset:768
	global_load_dwordx4 v[180:183], v101, s[86:87] offset:832
	global_load_dwordx4 v[184:187], v150, s[86:87] offset:832
	s_add_u32 s86, s86, 0xc0000
	s_addc_u32 s87, s87, 0
	s_waitcnt lgkmcnt(0)
	v_mfma_f32_32x32x16_bf16 v[32:47], v[188:191], v[48:51], v[32:47]
	ds_read_b64_tr_b16 v[72:73], v231
	ds_read_b64_tr_b16 v[74:75], v231 offset:512
	ds_read_b64_tr_b16 v[76:77], v231 offset:2048
	ds_read_b64_tr_b16 v[78:79], v231 offset:2560
	ds_read_b64_tr_b16 v[220:221], v231 offset:1024
	ds_read_b64_tr_b16 v[222:223], v231 offset:1536
	ds_read_b64_tr_b16 v[224:225], v231 offset:3072
	ds_read_b64_tr_b16 v[226:227], v231 offset:3584
	s_waitcnt vmcnt(8)
	ds_write_b128 v247, v[116:119]
	ds_write_b128 v247, v[120:123] offset:1024
	ds_write_b128 v111, v[124:127] offset:2048
	ds_write_b128 v111, v[128:131] offset:3072
	ds_read_b128 v[116:119], v248
	ds_read_b128 v[120:123], v249
	ds_read_b128 v[124:127], v250
	ds_read_b128 v[128:131], v251
	ds_write_b128 v112, v[132:135]
	ds_write_b128 v112, v[136:139] offset:1024
	ds_write_b128 v112, v[140:143] offset:2048
	ds_write_b128 v112, v[144:147] offset:3072
	v_mfma_f32_32x32x16_bf16 v[32:47], v[192:195], v[52:55], v[32:47]
	v_mfma_f32_32x32x16_bf16 v[32:47], v[196:199], v[56:59], v[32:47]
	v_mfma_f32_32x32x16_bf16 v[32:47], v[200:203], v[60:63], v[32:47]
	s_nop 11
	v_exp_f32_e32 v32, v32
	v_exp_f32_e32 v33, v33
	v_exp_f32_e32 v34, v34
	v_exp_f32_e32 v35, v35
	v_exp_f32_e32 v36, v36
	v_exp_f32_e32 v37, v37
	v_exp_f32_e32 v38, v38
	v_exp_f32_e32 v39, v39
	v_exp_f32_e32 v40, v40
	v_exp_f32_e32 v41, v41
	v_exp_f32_e32 v42, v42
	v_exp_f32_e32 v43, v43
	v_exp_f32_e32 v44, v44
	v_exp_f32_e32 v45, v45
	v_exp_f32_e32 v46, v46
	v_exp_f32_e32 v47, v47
	v_cvt_pk_bf16_f32 v64, v32, v33
	v_cvt_pk_bf16_f32 v65, v34, v35
	v_cvt_pk_bf16_f32 v66, v36, v37
	v_cvt_pk_bf16_f32 v67, v38, v39
	v_cvt_pk_bf16_f32 v68, v40, v41
	v_cvt_pk_bf16_f32 v69, v42, v43
	v_cvt_pk_bf16_f32 v70, v44, v45
	v_cvt_pk_bf16_f32 v71, v46, v47
	v_pk_add_f32 v[232:233], v[232:233], v[32:33]
	v_pk_add_f32 v[232:233], v[232:233], v[34:35]
	v_pk_add_f32 v[232:233], v[232:233], v[36:37]
	v_pk_add_f32 v[232:233], v[232:233], v[38:39]
	v_pk_add_f32 v[232:233], v[232:233], v[40:41]
	v_pk_add_f32 v[232:233], v[232:233], v[42:43]
	v_pk_add_f32 v[232:233], v[232:233], v[44:45]
	v_pk_add_f32 v[232:233], v[232:233], v[46:47]
	ds_read2_b32 v[32:33], v115 offset0:40 offset1:41
	ds_read2_b32 v[34:35], v115 offset0:42 offset1:43
	ds_read2_b32 v[36:37], v115 offset0:50 offset1:51
	ds_read2_b32 v[38:39], v115 offset0:52 offset1:53
	ds_read2_b32 v[40:41], v115 offset0:60 offset1:61
	ds_read2_b32 v[42:43], v115 offset0:62 offset1:63
	ds_read2_b32 v[44:45], v115 offset0:70 offset1:71
	ds_read2_b32 v[46:47], v115 offset0:72 offset1:73
	s_waitcnt lgkmcnt(15)
	v_mfma_f32_32x32x16_bf16 v[0:15], v[64:67], v[72:75], v[0:15]
	v_mfma_f32_32x32x16_bf16 v[16:31], v[64:67], v[76:79], v[16:31]
	v_mfma_f32_32x32x16_bf16 v[0:15], v[68:71], v[220:223], v[0:15]
	v_mfma_f32_32x32x16_bf16 v[16:31], v[68:71], v[224:227], v[16:31]
	global_load_dwordx4 v[188:191], v239, s[86:87]
	global_load_dwordx4 v[192:195], v240, s[86:87]
	global_load_dwordx4 v[196:199], v241, s[86:87]
	global_load_dwordx4 v[200:203], v242, s[86:87]
	global_load_dwordx4 v[204:207], v101, s[86:87] offset:768
	global_load_dwordx4 v[208:211], v150, s[86:87] offset:768
	global_load_dwordx4 v[212:215], v101, s[86:87] offset:832
	global_load_dwordx4 v[216:219], v150, s[86:87] offset:832
	s_add_u32 s86, s86, 0xc0000
	s_addc_u32 s87, s87, 0
	s_waitcnt lgkmcnt(0)
	v_mfma_f32_32x32x16_bf16 v[32:47], v[116:119], v[48:51], v[32:47]
	ds_read_b64_tr_b16 v[72:73], v231
	ds_read_b64_tr_b16 v[74:75], v231 offset:512
	ds_read_b64_tr_b16 v[76:77], v231 offset:2048
	ds_read_b64_tr_b16 v[78:79], v231 offset:2560
	ds_read_b64_tr_b16 v[220:221], v231 offset:1024
	ds_read_b64_tr_b16 v[222:223], v231 offset:1536
	ds_read_b64_tr_b16 v[224:225], v231 offset:3072
	ds_read_b64_tr_b16 v[226:227], v231 offset:3584
	s_waitcnt vmcnt(8)
	ds_write_b128 v247, v[156:159]
	ds_write_b128 v247, v[160:163] offset:1024
	ds_write_b128 v111, v[164:167] offset:2048
	ds_write_b128 v111, v[168:171] offset:3072
	ds_read_b128 v[156:159], v248
	ds_read_b128 v[160:163], v249
	ds_read_b128 v[164:167], v250
	ds_read_b128 v[168:171], v251
	ds_write_b128 v112, v[172:175]
	ds_write_b128 v112, v[176:179] offset:1024
	ds_write_b128 v112, v[180:183] offset:2048
	ds_write_b128 v112, v[184:187] offset:3072
	v_mfma_f32_32x32x16_bf16 v[32:47], v[120:123], v[52:55], v[32:47]
	v_mfma_f32_32x32x16_bf16 v[32:47], v[124:127], v[56:59], v[32:47]
	v_mfma_f32_32x32x16_bf16 v[32:47], v[128:131], v[60:63], v[32:47]
	s_nop 11
	v_exp_f32_e32 v32, v32
	v_exp_f32_e32 v33, v33
	v_exp_f32_e32 v34, v34
	v_exp_f32_e32 v35, v35
	v_exp_f32_e32 v36, v36
	v_exp_f32_e32 v37, v37
	v_exp_f32_e32 v38, v38
	v_exp_f32_e32 v39, v39
	v_exp_f32_e32 v40, v40
	v_exp_f32_e32 v41, v41
	v_exp_f32_e32 v42, v42
	v_exp_f32_e32 v43, v43
	v_exp_f32_e32 v44, v44
	v_exp_f32_e32 v45, v45
	v_exp_f32_e32 v46, v46
	v_exp_f32_e32 v47, v47
	v_cvt_pk_bf16_f32 v64, v32, v33
	v_cvt_pk_bf16_f32 v65, v34, v35
	v_cvt_pk_bf16_f32 v66, v36, v37
	v_cvt_pk_bf16_f32 v67, v38, v39
	v_cvt_pk_bf16_f32 v68, v40, v41
	v_cvt_pk_bf16_f32 v69, v42, v43
	v_cvt_pk_bf16_f32 v70, v44, v45
	v_cvt_pk_bf16_f32 v71, v46, v47
	v_pk_add_f32 v[232:233], v[232:233], v[32:33]
	v_pk_add_f32 v[232:233], v[232:233], v[34:35]
	v_pk_add_f32 v[232:233], v[232:233], v[36:37]
	v_pk_add_f32 v[232:233], v[232:233], v[38:39]
	v_pk_add_f32 v[232:233], v[232:233], v[40:41]
	v_pk_add_f32 v[232:233], v[232:233], v[42:43]
	v_pk_add_f32 v[232:233], v[232:233], v[44:45]
	v_pk_add_f32 v[232:233], v[232:233], v[46:47]
	ds_read2_b32 v[32:33], v115 offset0:80 offset1:81
	ds_read2_b32 v[34:35], v115 offset0:82 offset1:83
	ds_read2_b32 v[36:37], v115 offset0:90 offset1:91
	ds_read2_b32 v[38:39], v115 offset0:92 offset1:93
	ds_read2_b32 v[40:41], v115 offset0:100 offset1:101
	ds_read2_b32 v[42:43], v115 offset0:102 offset1:103
	ds_read2_b32 v[44:45], v115 offset0:110 offset1:111
	ds_read2_b32 v[46:47], v115 offset0:112 offset1:113
	s_waitcnt lgkmcnt(15)
	v_mfma_f32_32x32x16_bf16 v[0:15], v[64:67], v[72:75], v[0:15]
	v_mfma_f32_32x32x16_bf16 v[16:31], v[64:67], v[76:79], v[16:31]
	v_mfma_f32_32x32x16_bf16 v[0:15], v[68:71], v[220:223], v[0:15]
	v_mfma_f32_32x32x16_bf16 v[16:31], v[68:71], v[224:227], v[16:31]
	global_load_dwordx4 v[116:119], v239, s[86:87]
	global_load_dwordx4 v[120:123], v240, s[86:87]
	global_load_dwordx4 v[124:127], v241, s[86:87]
	global_load_dwordx4 v[128:131], v242, s[86:87]
	global_load_dwordx4 v[132:135], v101, s[86:87] offset:768
	global_load_dwordx4 v[136:139], v150, s[86:87] offset:768
	global_load_dwordx4 v[140:143], v101, s[86:87] offset:832
	global_load_dwordx4 v[144:147], v150, s[86:87] offset:832
	s_add_u32 s86, s86, 0xc0000
	s_addc_u32 s87, s87, 0
	s_waitcnt lgkmcnt(0)
	v_mfma_f32_32x32x16_bf16 v[32:47], v[156:159], v[48:51], v[32:47]
	ds_read_b64_tr_b16 v[72:73], v231
	ds_read_b64_tr_b16 v[74:75], v231 offset:512
	ds_read_b64_tr_b16 v[76:77], v231 offset:2048
	ds_read_b64_tr_b16 v[78:79], v231 offset:2560
	ds_read_b64_tr_b16 v[220:221], v231 offset:1024
	ds_read_b64_tr_b16 v[222:223], v231 offset:1536
	ds_read_b64_tr_b16 v[224:225], v231 offset:3072
	ds_read_b64_tr_b16 v[226:227], v231 offset:3584
	s_waitcnt vmcnt(8)
	ds_write_b128 v247, v[188:191]
	ds_write_b128 v247, v[192:195] offset:1024
	ds_write_b128 v111, v[196:199] offset:2048
	ds_write_b128 v111, v[200:203] offset:3072
	ds_read_b128 v[188:191], v248
	ds_read_b128 v[192:195], v249
	ds_read_b128 v[196:199], v250
	ds_read_b128 v[200:203], v251
	ds_write_b128 v112, v[204:207]
	ds_write_b128 v112, v[208:211] offset:1024
	ds_write_b128 v112, v[212:215] offset:2048
	ds_write_b128 v112, v[216:219] offset:3072
	v_mfma_f32_32x32x16_bf16 v[32:47], v[160:163], v[52:55], v[32:47]
	v_mfma_f32_32x32x16_bf16 v[32:47], v[164:167], v[56:59], v[32:47]
	v_mfma_f32_32x32x16_bf16 v[32:47], v[168:171], v[60:63], v[32:47]
	s_nop 11
	v_exp_f32_e32 v32, v32
	v_exp_f32_e32 v33, v33
	v_exp_f32_e32 v34, v34
	v_exp_f32_e32 v35, v35
	v_exp_f32_e32 v36, v36
	v_exp_f32_e32 v37, v37
	v_exp_f32_e32 v38, v38
	v_exp_f32_e32 v39, v39
	v_exp_f32_e32 v40, v40
	v_exp_f32_e32 v41, v41
	v_exp_f32_e32 v42, v42
	v_exp_f32_e32 v43, v43
	v_exp_f32_e32 v44, v44
	v_exp_f32_e32 v45, v45
	v_exp_f32_e32 v46, v46
	v_exp_f32_e32 v47, v47
	v_cvt_pk_bf16_f32 v64, v32, v33
	v_cvt_pk_bf16_f32 v65, v34, v35
	v_cvt_pk_bf16_f32 v66, v36, v37
	v_cvt_pk_bf16_f32 v67, v38, v39
	v_cvt_pk_bf16_f32 v68, v40, v41
	v_cvt_pk_bf16_f32 v69, v42, v43
	v_cvt_pk_bf16_f32 v70, v44, v45
	v_cvt_pk_bf16_f32 v71, v46, v47
	v_pk_add_f32 v[232:233], v[232:233], v[32:33]
	v_pk_add_f32 v[232:233], v[232:233], v[34:35]
	v_pk_add_f32 v[232:233], v[232:233], v[36:37]
	v_pk_add_f32 v[232:233], v[232:233], v[38:39]
	v_pk_add_f32 v[232:233], v[232:233], v[40:41]
	v_pk_add_f32 v[232:233], v[232:233], v[42:43]
	v_pk_add_f32 v[232:233], v[232:233], v[44:45]
	v_pk_add_f32 v[232:233], v[232:233], v[46:47]
	ds_read2_b32 v[32:33], v115 offset0:120 offset1:121
	ds_read2_b32 v[34:35], v115 offset0:122 offset1:123
	ds_read2_b32 v[36:37], v115 offset0:130 offset1:131
	ds_read2_b32 v[38:39], v115 offset0:132 offset1:133
	ds_read2_b32 v[40:41], v115 offset0:140 offset1:141
	ds_read2_b32 v[42:43], v115 offset0:142 offset1:143
	ds_read2_b32 v[44:45], v115 offset0:150 offset1:151
	ds_read2_b32 v[46:47], v115 offset0:152 offset1:153
	s_waitcnt lgkmcnt(15)
	v_mfma_f32_32x32x16_bf16 v[0:15], v[64:67], v[72:75], v[0:15]
	v_mfma_f32_32x32x16_bf16 v[16:31], v[64:67], v[76:79], v[16:31]
	v_mfma_f32_32x32x16_bf16 v[0:15], v[68:71], v[220:223], v[0:15]
	v_mfma_f32_32x32x16_bf16 v[16:31], v[68:71], v[224:227], v[16:31]
	global_load_dwordx4 v[156:159], v239, s[86:87]
	global_load_dwordx4 v[160:163], v240, s[86:87]
	global_load_dwordx4 v[164:167], v241, s[86:87]
	global_load_dwordx4 v[168:171], v242, s[86:87]
	global_load_dwordx4 v[172:175], v101, s[86:87] offset:768
	global_load_dwordx4 v[176:179], v150, s[86:87] offset:768
	global_load_dwordx4 v[180:183], v101, s[86:87] offset:832
	global_load_dwordx4 v[184:187], v150, s[86:87] offset:832
	s_add_u32 s86, s86, 0xc0000
	s_addc_u32 s87, s87, 0
	s_waitcnt lgkmcnt(0)
	v_mfma_f32_32x32x16_bf16 v[32:47], v[188:191], v[48:51], v[32:47]
	ds_read_b64_tr_b16 v[72:73], v231
	ds_read_b64_tr_b16 v[74:75], v231 offset:512
	ds_read_b64_tr_b16 v[76:77], v231 offset:2048
	ds_read_b64_tr_b16 v[78:79], v231 offset:2560
	ds_read_b64_tr_b16 v[220:221], v231 offset:1024
	ds_read_b64_tr_b16 v[222:223], v231 offset:1536
	ds_read_b64_tr_b16 v[224:225], v231 offset:3072
	ds_read_b64_tr_b16 v[226:227], v231 offset:3584
	s_waitcnt vmcnt(8)
	ds_write_b128 v247, v[116:119]
	ds_write_b128 v247, v[120:123] offset:1024
	ds_write_b128 v111, v[124:127] offset:2048
	ds_write_b128 v111, v[128:131] offset:3072
	ds_read_b128 v[116:119], v248
	ds_read_b128 v[120:123], v249
	ds_read_b128 v[124:127], v250
	ds_read_b128 v[128:131], v251
	ds_write_b128 v112, v[132:135]
	ds_write_b128 v112, v[136:139] offset:1024
	ds_write_b128 v112, v[140:143] offset:2048
	ds_write_b128 v112, v[144:147] offset:3072
	v_mfma_f32_32x32x16_bf16 v[32:47], v[192:195], v[52:55], v[32:47]
	v_mfma_f32_32x32x16_bf16 v[32:47], v[196:199], v[56:59], v[32:47]
	v_mfma_f32_32x32x16_bf16 v[32:47], v[200:203], v[60:63], v[32:47]
	s_nop 11
	v_exp_f32_e32 v32, v32
	v_exp_f32_e32 v33, v33
	v_exp_f32_e32 v34, v34
	v_exp_f32_e32 v35, v35
	v_exp_f32_e32 v36, v36
	v_exp_f32_e32 v37, v37
	v_exp_f32_e32 v38, v38
	v_exp_f32_e32 v39, v39
	v_exp_f32_e32 v40, v40
	v_exp_f32_e32 v41, v41
	v_exp_f32_e32 v42, v42
	v_exp_f32_e32 v43, v43
	v_exp_f32_e32 v44, v44
	v_exp_f32_e32 v45, v45
	v_exp_f32_e32 v46, v46
	v_exp_f32_e32 v47, v47
	v_cvt_pk_bf16_f32 v64, v32, v33
	v_cvt_pk_bf16_f32 v65, v34, v35
	v_cvt_pk_bf16_f32 v66, v36, v37
	v_cvt_pk_bf16_f32 v67, v38, v39
	v_cvt_pk_bf16_f32 v68, v40, v41
	v_cvt_pk_bf16_f32 v69, v42, v43
	v_cvt_pk_bf16_f32 v70, v44, v45
	v_cvt_pk_bf16_f32 v71, v46, v47
	v_pk_add_f32 v[232:233], v[232:233], v[32:33]
	v_pk_add_f32 v[232:233], v[232:233], v[34:35]
	v_pk_add_f32 v[232:233], v[232:233], v[36:37]
	v_pk_add_f32 v[232:233], v[232:233], v[38:39]
	v_pk_add_f32 v[232:233], v[232:233], v[40:41]
	v_pk_add_f32 v[232:233], v[232:233], v[42:43]
	v_pk_add_f32 v[232:233], v[232:233], v[44:45]
	v_pk_add_f32 v[232:233], v[232:233], v[46:47]
	v_add_u32_e32 v115, 640, v115
	ds_read2_b32 v[32:33], v115 offset0:0 offset1:1
	ds_read2_b32 v[34:35], v115 offset0:2 offset1:3
	ds_read2_b32 v[36:37], v115 offset0:10 offset1:11
	ds_read2_b32 v[38:39], v115 offset0:12 offset1:13
	ds_read2_b32 v[40:41], v115 offset0:20 offset1:21
	ds_read2_b32 v[42:43], v115 offset0:22 offset1:23
	ds_read2_b32 v[44:45], v115 offset0:30 offset1:31
	ds_read2_b32 v[46:47], v115 offset0:32 offset1:33
	s_waitcnt lgkmcnt(15)
	v_mfma_f32_32x32x16_bf16 v[0:15], v[64:67], v[72:75], v[0:15]
	v_mfma_f32_32x32x16_bf16 v[16:31], v[64:67], v[76:79], v[16:31]
	v_mfma_f32_32x32x16_bf16 v[0:15], v[68:71], v[220:223], v[0:15]
	v_mfma_f32_32x32x16_bf16 v[16:31], v[68:71], v[224:227], v[16:31]
	global_load_dwordx4 v[188:191], v239, s[86:87]
	global_load_dwordx4 v[192:195], v240, s[86:87]
	global_load_dwordx4 v[196:199], v241, s[86:87]
	global_load_dwordx4 v[200:203], v242, s[86:87]
	global_load_dwordx4 v[204:207], v101, s[86:87] offset:768
	global_load_dwordx4 v[208:211], v150, s[86:87] offset:768
	global_load_dwordx4 v[212:215], v101, s[86:87] offset:832
	global_load_dwordx4 v[216:219], v150, s[86:87] offset:832
	s_add_u32 s86, s86, 0xc0000
	s_addc_u32 s87, s87, 0
	s_waitcnt lgkmcnt(0)
	v_mfma_f32_32x32x16_bf16 v[32:47], v[116:119], v[48:51], v[32:47]
	ds_read_b64_tr_b16 v[72:73], v231
	ds_read_b64_tr_b16 v[74:75], v231 offset:512
	ds_read_b64_tr_b16 v[76:77], v231 offset:2048
	ds_read_b64_tr_b16 v[78:79], v231 offset:2560
	ds_read_b64_tr_b16 v[220:221], v231 offset:1024
	ds_read_b64_tr_b16 v[222:223], v231 offset:1536
	ds_read_b64_tr_b16 v[224:225], v231 offset:3072
	ds_read_b64_tr_b16 v[226:227], v231 offset:3584
	s_waitcnt vmcnt(8)
	ds_write_b128 v247, v[156:159]
	ds_write_b128 v247, v[160:163] offset:1024
	ds_write_b128 v111, v[164:167] offset:2048
	ds_write_b128 v111, v[168:171] offset:3072
	ds_read_b128 v[156:159], v248
	ds_read_b128 v[160:163], v249
	ds_read_b128 v[164:167], v250
	ds_read_b128 v[168:171], v251
	ds_write_b128 v112, v[172:175]
	ds_write_b128 v112, v[176:179] offset:1024
	ds_write_b128 v112, v[180:183] offset:2048
	ds_write_b128 v112, v[184:187] offset:3072
	v_mfma_f32_32x32x16_bf16 v[32:47], v[120:123], v[52:55], v[32:47]
	v_mfma_f32_32x32x16_bf16 v[32:47], v[124:127], v[56:59], v[32:47]
	v_mfma_f32_32x32x16_bf16 v[32:47], v[128:131], v[60:63], v[32:47]
	s_nop 11
	v_exp_f32_e32 v32, v32
	v_exp_f32_e32 v33, v33
	v_exp_f32_e32 v34, v34
	v_exp_f32_e32 v35, v35
	v_exp_f32_e32 v36, v36
	v_exp_f32_e32 v37, v37
	v_exp_f32_e32 v38, v38
	v_exp_f32_e32 v39, v39
	v_exp_f32_e32 v40, v40
	v_exp_f32_e32 v41, v41
	v_exp_f32_e32 v42, v42
	v_exp_f32_e32 v43, v43
	v_exp_f32_e32 v44, v44
	v_exp_f32_e32 v45, v45
	v_exp_f32_e32 v46, v46
	v_exp_f32_e32 v47, v47
	v_cvt_pk_bf16_f32 v64, v32, v33
	v_cvt_pk_bf16_f32 v65, v34, v35
	v_cvt_pk_bf16_f32 v66, v36, v37
	v_cvt_pk_bf16_f32 v67, v38, v39
	v_cvt_pk_bf16_f32 v68, v40, v41
	v_cvt_pk_bf16_f32 v69, v42, v43
	v_cvt_pk_bf16_f32 v70, v44, v45
	v_cvt_pk_bf16_f32 v71, v46, v47
	v_pk_add_f32 v[232:233], v[232:233], v[32:33]
	v_pk_add_f32 v[232:233], v[232:233], v[34:35]
	v_pk_add_f32 v[232:233], v[232:233], v[36:37]
	v_pk_add_f32 v[232:233], v[232:233], v[38:39]
	v_pk_add_f32 v[232:233], v[232:233], v[40:41]
	v_pk_add_f32 v[232:233], v[232:233], v[42:43]
	v_pk_add_f32 v[232:233], v[232:233], v[44:45]
	v_pk_add_f32 v[232:233], v[232:233], v[46:47]
	ds_read2_b32 v[32:33], v115 offset0:40 offset1:41
	ds_read2_b32 v[34:35], v115 offset0:42 offset1:43
	ds_read2_b32 v[36:37], v115 offset0:50 offset1:51
	ds_read2_b32 v[38:39], v115 offset0:52 offset1:53
	ds_read2_b32 v[40:41], v115 offset0:60 offset1:61
	ds_read2_b32 v[42:43], v115 offset0:62 offset1:63
	ds_read2_b32 v[44:45], v115 offset0:70 offset1:71
	ds_read2_b32 v[46:47], v115 offset0:72 offset1:73
	s_waitcnt lgkmcnt(15)
	v_mfma_f32_32x32x16_bf16 v[0:15], v[64:67], v[72:75], v[0:15]
	v_mfma_f32_32x32x16_bf16 v[16:31], v[64:67], v[76:79], v[16:31]
	v_mfma_f32_32x32x16_bf16 v[0:15], v[68:71], v[220:223], v[0:15]
	v_mfma_f32_32x32x16_bf16 v[16:31], v[68:71], v[224:227], v[16:31]
	global_load_dwordx4 v[116:119], v239, s[86:87]
	global_load_dwordx4 v[120:123], v240, s[86:87]
	global_load_dwordx4 v[124:127], v241, s[86:87]
	global_load_dwordx4 v[128:131], v242, s[86:87]
	global_load_dwordx4 v[132:135], v101, s[86:87] offset:768
	global_load_dwordx4 v[136:139], v150, s[86:87] offset:768
	global_load_dwordx4 v[140:143], v101, s[86:87] offset:832
	global_load_dwordx4 v[144:147], v150, s[86:87] offset:832
	s_waitcnt lgkmcnt(0)
	v_mfma_f32_32x32x16_bf16 v[32:47], v[156:159], v[48:51], v[32:47]
	ds_read_b64_tr_b16 v[72:73], v231
	ds_read_b64_tr_b16 v[74:75], v231 offset:512
	ds_read_b64_tr_b16 v[76:77], v231 offset:2048
	ds_read_b64_tr_b16 v[78:79], v231 offset:2560
	ds_read_b64_tr_b16 v[220:221], v231 offset:1024
	ds_read_b64_tr_b16 v[222:223], v231 offset:1536
	ds_read_b64_tr_b16 v[224:225], v231 offset:3072
	ds_read_b64_tr_b16 v[226:227], v231 offset:3584
	s_waitcnt vmcnt(8)
	ds_write_b128 v247, v[188:191]
	ds_write_b128 v247, v[192:195] offset:1024
	ds_write_b128 v111, v[196:199] offset:2048
	ds_write_b128 v111, v[200:203] offset:3072
	ds_read_b128 v[188:191], v248
	ds_read_b128 v[192:195], v249
	ds_read_b128 v[196:199], v250
	ds_read_b128 v[200:203], v251
	ds_write_b128 v112, v[204:207]
	ds_write_b128 v112, v[208:211] offset:1024
	ds_write_b128 v112, v[212:215] offset:2048
	ds_write_b128 v112, v[216:219] offset:3072
	v_mfma_f32_32x32x16_bf16 v[32:47], v[160:163], v[52:55], v[32:47]
	v_mfma_f32_32x32x16_bf16 v[32:47], v[164:167], v[56:59], v[32:47]
	v_mfma_f32_32x32x16_bf16 v[32:47], v[168:171], v[60:63], v[32:47]
	s_nop 11
	v_exp_f32_e32 v32, v32
	v_exp_f32_e32 v33, v33
	v_exp_f32_e32 v34, v34
	v_exp_f32_e32 v35, v35
	v_exp_f32_e32 v36, v36
	v_exp_f32_e32 v37, v37
	v_exp_f32_e32 v38, v38
	v_exp_f32_e32 v39, v39
	v_exp_f32_e32 v40, v40
	v_exp_f32_e32 v41, v41
	v_exp_f32_e32 v42, v42
	v_exp_f32_e32 v43, v43
	v_exp_f32_e32 v44, v44
	v_exp_f32_e32 v45, v45
	v_exp_f32_e32 v46, v46
	v_exp_f32_e32 v47, v47
	v_cvt_pk_bf16_f32 v64, v32, v33
	v_cvt_pk_bf16_f32 v65, v34, v35
	v_cvt_pk_bf16_f32 v66, v36, v37
	v_cvt_pk_bf16_f32 v67, v38, v39
	v_cvt_pk_bf16_f32 v68, v40, v41
	v_cvt_pk_bf16_f32 v69, v42, v43
	v_cvt_pk_bf16_f32 v70, v44, v45
	v_cvt_pk_bf16_f32 v71, v46, v47
	v_pk_add_f32 v[232:233], v[232:233], v[32:33]
	v_pk_add_f32 v[232:233], v[232:233], v[34:35]
	v_pk_add_f32 v[232:233], v[232:233], v[36:37]
	v_pk_add_f32 v[232:233], v[232:233], v[38:39]
	v_pk_add_f32 v[232:233], v[232:233], v[40:41]
	v_pk_add_f32 v[232:233], v[232:233], v[42:43]
	v_pk_add_f32 v[232:233], v[232:233], v[44:45]
	v_pk_add_f32 v[232:233], v[232:233], v[46:47]
	ds_read2_b32 v[32:33], v115 offset0:80 offset1:81
	ds_read2_b32 v[34:35], v115 offset0:82 offset1:83
	ds_read2_b32 v[36:37], v115 offset0:90 offset1:91
	ds_read2_b32 v[38:39], v115 offset0:92 offset1:93
	ds_read2_b32 v[40:41], v115 offset0:100 offset1:101
	ds_read2_b32 v[42:43], v115 offset0:102 offset1:103
	ds_read2_b32 v[44:45], v115 offset0:110 offset1:111
	ds_read2_b32 v[46:47], v115 offset0:112 offset1:113
	s_waitcnt lgkmcnt(15)
	v_mfma_f32_32x32x16_bf16 v[0:15], v[64:67], v[72:75], v[0:15]
	v_mfma_f32_32x32x16_bf16 v[16:31], v[64:67], v[76:79], v[16:31]
	v_mfma_f32_32x32x16_bf16 v[0:15], v[68:71], v[220:223], v[0:15]
	v_mfma_f32_32x32x16_bf16 v[16:31], v[68:71], v[224:227], v[16:31]
	global_load_dwordx4 v[156:159], v243, s[88:89]
	global_load_dwordx4 v[160:163], v244, s[88:89]
	global_load_dwordx4 v[164:167], v245, s[88:89]
	global_load_dwordx4 v[168:171], v246, s[88:89]
	global_load_dwordx4 v[172:175], v148, s[88:89] offset:768
	global_load_dwordx4 v[176:179], v151, s[88:89] offset:768
	global_load_dwordx4 v[180:183], v148, s[88:89] offset:832
	global_load_dwordx4 v[184:187], v151, s[88:89] offset:832
	s_add_u32 s88, s88, 0x300000
	s_addc_u32 s89, s89, 0
	s_waitcnt lgkmcnt(0)
	v_mfma_f32_32x32x16_bf16 v[32:47], v[188:191], v[48:51], v[32:47]
	ds_read_b64_tr_b16 v[72:73], v231
	ds_read_b64_tr_b16 v[74:75], v231 offset:512
	ds_read_b64_tr_b16 v[76:77], v231 offset:2048
	ds_read_b64_tr_b16 v[78:79], v231 offset:2560
	ds_read_b64_tr_b16 v[220:221], v231 offset:1024
	ds_read_b64_tr_b16 v[222:223], v231 offset:1536
	ds_read_b64_tr_b16 v[224:225], v231 offset:3072
	ds_read_b64_tr_b16 v[226:227], v231 offset:3584
	s_waitcnt vmcnt(8)
	ds_write_b128 v247, v[116:119]
	ds_write_b128 v247, v[120:123] offset:1024
	ds_write_b128 v111, v[124:127] offset:2048
	ds_write_b128 v111, v[128:131] offset:3072
	ds_read_b128 v[116:119], v248
	ds_read_b128 v[120:123], v249
	ds_read_b128 v[124:127], v250
	ds_read_b128 v[128:131], v251
	ds_write_b128 v112, v[132:135]
	ds_write_b128 v112, v[136:139] offset:1024
	ds_write_b128 v112, v[140:143] offset:2048
	ds_write_b128 v112, v[144:147] offset:3072
	v_mfma_f32_32x32x16_bf16 v[32:47], v[192:195], v[52:55], v[32:47]
	v_mfma_f32_32x32x16_bf16 v[32:47], v[196:199], v[56:59], v[32:47]
	v_mfma_f32_32x32x16_bf16 v[32:47], v[200:203], v[60:63], v[32:47]
	s_nop 11
	v_exp_f32_e32 v32, v32
	v_exp_f32_e32 v33, v33
	v_exp_f32_e32 v34, v34
	v_exp_f32_e32 v35, v35
	v_exp_f32_e32 v36, v36
	v_exp_f32_e32 v37, v37
	v_exp_f32_e32 v38, v38
	v_exp_f32_e32 v39, v39
	v_exp_f32_e32 v40, v40
	v_exp_f32_e32 v41, v41
	v_exp_f32_e32 v42, v42
	v_exp_f32_e32 v43, v43
	v_exp_f32_e32 v44, v44
	v_exp_f32_e32 v45, v45
	v_exp_f32_e32 v46, v46
	v_exp_f32_e32 v47, v47
	v_cvt_pk_bf16_f32 v64, v32, v33
	v_cvt_pk_bf16_f32 v65, v34, v35
	v_cvt_pk_bf16_f32 v66, v36, v37
	v_cvt_pk_bf16_f32 v67, v38, v39
	v_cvt_pk_bf16_f32 v68, v40, v41
	v_cvt_pk_bf16_f32 v69, v42, v43
	v_cvt_pk_bf16_f32 v70, v44, v45
	v_cvt_pk_bf16_f32 v71, v46, v47
	v_pk_add_f32 v[232:233], v[232:233], v[32:33]
	v_pk_add_f32 v[232:233], v[232:233], v[34:35]
	v_pk_add_f32 v[232:233], v[232:233], v[36:37]
	v_pk_add_f32 v[232:233], v[232:233], v[38:39]
	v_pk_add_f32 v[232:233], v[232:233], v[40:41]
	v_pk_add_f32 v[232:233], v[232:233], v[42:43]
	v_pk_add_f32 v[232:233], v[232:233], v[44:45]
	v_pk_add_f32 v[232:233], v[232:233], v[46:47]
	ds_read2_b32 v[32:33], v115 offset0:120 offset1:121
	ds_read2_b32 v[34:35], v115 offset0:122 offset1:123
	ds_read2_b32 v[36:37], v115 offset0:130 offset1:131
	ds_read2_b32 v[38:39], v115 offset0:132 offset1:133
	ds_read2_b32 v[40:41], v115 offset0:140 offset1:141
	ds_read2_b32 v[42:43], v115 offset0:142 offset1:143
	ds_read2_b32 v[44:45], v115 offset0:150 offset1:151
	ds_read2_b32 v[46:47], v115 offset0:152 offset1:153
	s_waitcnt lgkmcnt(15)
	v_mfma_f32_32x32x16_bf16 v[0:15], v[64:67], v[72:75], v[0:15]
	v_mfma_f32_32x32x16_bf16 v[16:31], v[64:67], v[76:79], v[16:31]
	v_mfma_f32_32x32x16_bf16 v[0:15], v[68:71], v[220:223], v[0:15]
	v_mfma_f32_32x32x16_bf16 v[16:31], v[68:71], v[224:227], v[16:31]
	global_load_dwordx4 v[188:191], v243, s[88:89]
	global_load_dwordx4 v[192:195], v244, s[88:89]
	global_load_dwordx4 v[196:199], v245, s[88:89]
	global_load_dwordx4 v[200:203], v246, s[88:89]
	global_load_dwordx4 v[204:207], v148, s[88:89] offset:768
	global_load_dwordx4 v[208:211], v151, s[88:89] offset:768
	global_load_dwordx4 v[212:215], v148, s[88:89] offset:832
	global_load_dwordx4 v[216:219], v151, s[88:89] offset:832
	s_add_u32 s88, s88, 0x300000
	s_addc_u32 s89, s89, 0
	s_waitcnt lgkmcnt(0)
	v_mfma_f32_32x32x16_bf16 v[32:47], v[116:119], v[48:51], v[32:47]
	ds_read_b64_tr_b16 v[72:73], v231
	ds_read_b64_tr_b16 v[74:75], v231 offset:512
	ds_read_b64_tr_b16 v[76:77], v231 offset:2048
	ds_read_b64_tr_b16 v[78:79], v231 offset:2560
	ds_read_b64_tr_b16 v[220:221], v231 offset:1024
	ds_read_b64_tr_b16 v[222:223], v231 offset:1536
	ds_read_b64_tr_b16 v[224:225], v231 offset:3072
	ds_read_b64_tr_b16 v[226:227], v231 offset:3584
	s_waitcnt vmcnt(8)
	ds_write_b128 v247, v[156:159]
	ds_write_b128 v247, v[160:163] offset:1024
	ds_write_b128 v111, v[164:167] offset:2048
	ds_write_b128 v111, v[168:171] offset:3072
	ds_read_b128 v[156:159], v248
	ds_read_b128 v[160:163], v249
	ds_read_b128 v[164:167], v250
	ds_read_b128 v[168:171], v251
	ds_write_b128 v112, v[172:175]
	ds_write_b128 v112, v[176:179] offset:1024
	ds_write_b128 v112, v[180:183] offset:2048
	ds_write_b128 v112, v[184:187] offset:3072
	v_mfma_f32_32x32x16_bf16 v[32:47], v[120:123], v[52:55], v[32:47]
	v_mfma_f32_32x32x16_bf16 v[32:47], v[124:127], v[56:59], v[32:47]
	v_mfma_f32_32x32x16_bf16 v[32:47], v[128:131], v[60:63], v[32:47]
	s_nop 11
	v_exp_f32_e32 v32, v32
	v_exp_f32_e32 v33, v33
	v_exp_f32_e32 v34, v34
	v_exp_f32_e32 v35, v35
	v_exp_f32_e32 v36, v36
	v_exp_f32_e32 v37, v37
	v_exp_f32_e32 v38, v38
	v_exp_f32_e32 v39, v39
	v_exp_f32_e32 v40, v40
	v_exp_f32_e32 v41, v41
	v_exp_f32_e32 v42, v42
	v_exp_f32_e32 v43, v43
	v_exp_f32_e32 v44, v44
	v_exp_f32_e32 v45, v45
	v_exp_f32_e32 v46, v46
	v_exp_f32_e32 v47, v47
	v_cvt_pk_bf16_f32 v64, v32, v33
	v_cvt_pk_bf16_f32 v65, v34, v35
	v_cvt_pk_bf16_f32 v66, v36, v37
	v_cvt_pk_bf16_f32 v67, v38, v39
	v_cvt_pk_bf16_f32 v68, v40, v41
	v_cvt_pk_bf16_f32 v69, v42, v43
	v_cvt_pk_bf16_f32 v70, v44, v45
	v_cvt_pk_bf16_f32 v71, v46, v47
	v_pk_add_f32 v[232:233], v[232:233], v[32:33]
	v_pk_add_f32 v[232:233], v[232:233], v[34:35]
	v_pk_add_f32 v[232:233], v[232:233], v[36:37]
	v_pk_add_f32 v[232:233], v[232:233], v[38:39]
	v_pk_add_f32 v[232:233], v[232:233], v[40:41]
	v_pk_add_f32 v[232:233], v[232:233], v[42:43]
	v_pk_add_f32 v[232:233], v[232:233], v[44:45]
	v_pk_add_f32 v[232:233], v[232:233], v[46:47]
	v_mov_b32_e32 v115, v230
	ds_read2_b32 v[32:33], v115 offset0:0 offset1:1
	ds_read2_b32 v[34:35], v115 offset0:2 offset1:3
	ds_read2_b32 v[36:37], v115 offset0:8 offset1:9
	ds_read2_b32 v[38:39], v115 offset0:10 offset1:11
	ds_read2_b32 v[40:41], v115 offset0:16 offset1:17
	ds_read2_b32 v[42:43], v115 offset0:18 offset1:19
	ds_read2_b32 v[44:45], v115 offset0:24 offset1:25
	ds_read2_b32 v[46:47], v115 offset0:26 offset1:27
	s_waitcnt lgkmcnt(15)
	v_mfma_f32_32x32x16_bf16 v[0:15], v[64:67], v[72:75], v[0:15]
	v_mfma_f32_32x32x16_bf16 v[16:31], v[64:67], v[76:79], v[16:31]
	v_mfma_f32_32x32x16_bf16 v[0:15], v[68:71], v[220:223], v[0:15]
	v_mfma_f32_32x32x16_bf16 v[16:31], v[68:71], v[224:227], v[16:31]
	global_load_dwordx4 v[116:119], v243, s[88:89]
	global_load_dwordx4 v[120:123], v244, s[88:89]
	global_load_dwordx4 v[124:127], v245, s[88:89]
	global_load_dwordx4 v[128:131], v246, s[88:89]
	global_load_dwordx4 v[132:135], v148, s[88:89] offset:768
	global_load_dwordx4 v[136:139], v151, s[88:89] offset:768
	global_load_dwordx4 v[140:143], v148, s[88:89] offset:832
	global_load_dwordx4 v[144:147], v151, s[88:89] offset:832
	s_add_u32 s88, s88, 0x300000
	s_addc_u32 s89, s89, 0
	s_waitcnt lgkmcnt(0)
	v_mfma_f32_32x32x16_bf16 v[32:47], v[156:159], v[48:51], v[32:47]
	ds_read_b64_tr_b16 v[72:73], v231
	ds_read_b64_tr_b16 v[74:75], v231 offset:512
	ds_read_b64_tr_b16 v[76:77], v231 offset:2048
	ds_read_b64_tr_b16 v[78:79], v231 offset:2560
	ds_read_b64_tr_b16 v[220:221], v231 offset:1024
	ds_read_b64_tr_b16 v[222:223], v231 offset:1536
	ds_read_b64_tr_b16 v[224:225], v231 offset:3072
	ds_read_b64_tr_b16 v[226:227], v231 offset:3584
	s_waitcnt vmcnt(8)
	ds_write_b128 v247, v[188:191]
	ds_write_b128 v247, v[192:195] offset:1024
	ds_write_b128 v111, v[196:199] offset:2048
	ds_write_b128 v111, v[200:203] offset:3072
	ds_read_b128 v[188:191], v248
	ds_read_b128 v[192:195], v249
	ds_read_b128 v[196:199], v250
	ds_read_b128 v[200:203], v251
	ds_write_b128 v112, v[204:207]
	ds_write_b128 v112, v[208:211] offset:1024
	ds_write_b128 v112, v[212:215] offset:2048
	ds_write_b128 v112, v[216:219] offset:3072
	v_mfma_f32_32x32x16_bf16 v[32:47], v[160:163], v[52:55], v[32:47]
	v_mfma_f32_32x32x16_bf16 v[32:47], v[164:167], v[56:59], v[32:47]
	v_mfma_f32_32x32x16_bf16 v[32:47], v[168:171], v[60:63], v[32:47]
	s_nop 11
	v_exp_f32_e32 v32, v32
	v_exp_f32_e32 v33, v33
	v_exp_f32_e32 v34, v34
	v_exp_f32_e32 v35, v35
	v_exp_f32_e32 v36, v36
	v_exp_f32_e32 v37, v37
	v_exp_f32_e32 v38, v38
	v_exp_f32_e32 v39, v39
	v_exp_f32_e32 v40, v40
	v_exp_f32_e32 v41, v41
	v_exp_f32_e32 v42, v42
	v_exp_f32_e32 v43, v43
	v_exp_f32_e32 v44, v44
	v_exp_f32_e32 v45, v45
	v_exp_f32_e32 v46, v46
	v_exp_f32_e32 v47, v47
	v_cvt_pk_bf16_f32 v64, v32, v33
	v_cvt_pk_bf16_f32 v65, v34, v35
	v_cvt_pk_bf16_f32 v66, v36, v37
	v_cvt_pk_bf16_f32 v67, v38, v39
	v_cvt_pk_bf16_f32 v68, v40, v41
	v_cvt_pk_bf16_f32 v69, v42, v43
	v_cvt_pk_bf16_f32 v70, v44, v45
	v_cvt_pk_bf16_f32 v71, v46, v47
	v_pk_add_f32 v[232:233], v[232:233], v[32:33]
	v_pk_add_f32 v[232:233], v[232:233], v[34:35]
	v_pk_add_f32 v[232:233], v[232:233], v[36:37]
	v_pk_add_f32 v[232:233], v[232:233], v[38:39]
	v_pk_add_f32 v[232:233], v[232:233], v[40:41]
	v_pk_add_f32 v[232:233], v[232:233], v[42:43]
	v_pk_add_f32 v[232:233], v[232:233], v[44:45]
	v_pk_add_f32 v[232:233], v[232:233], v[46:47]
	ds_read2_b32 v[32:33], v115 offset0:32 offset1:33
	ds_read2_b32 v[34:35], v115 offset0:34 offset1:35
	ds_read2_b32 v[36:37], v115 offset0:40 offset1:41
	ds_read2_b32 v[38:39], v115 offset0:42 offset1:43
	ds_read2_b32 v[40:41], v115 offset0:48 offset1:49
	ds_read2_b32 v[42:43], v115 offset0:50 offset1:51
	ds_read2_b32 v[44:45], v115 offset0:56 offset1:57
	ds_read2_b32 v[46:47], v115 offset0:58 offset1:59
	s_waitcnt lgkmcnt(15)
	v_mfma_f32_32x32x16_bf16 v[0:15], v[64:67], v[72:75], v[0:15]
	v_mfma_f32_32x32x16_bf16 v[16:31], v[64:67], v[76:79], v[16:31]
	v_mfma_f32_32x32x16_bf16 v[0:15], v[68:71], v[220:223], v[0:15]
	v_mfma_f32_32x32x16_bf16 v[16:31], v[68:71], v[224:227], v[16:31]
	global_load_dwordx4 v[156:159], v243, s[88:89]
	global_load_dwordx4 v[160:163], v244, s[88:89]
	global_load_dwordx4 v[164:167], v245, s[88:89]
	global_load_dwordx4 v[168:171], v246, s[88:89]
	global_load_dwordx4 v[172:175], v148, s[88:89] offset:768
	global_load_dwordx4 v[176:179], v151, s[88:89] offset:768
	global_load_dwordx4 v[180:183], v148, s[88:89] offset:832
	global_load_dwordx4 v[184:187], v151, s[88:89] offset:832
	s_add_u32 s88, s88, 0x300000
	s_addc_u32 s89, s89, 0
	s_waitcnt lgkmcnt(0)
	v_mfma_f32_32x32x16_bf16 v[32:47], v[188:191], v[48:51], v[32:47]
	ds_read_b64_tr_b16 v[72:73], v231
	ds_read_b64_tr_b16 v[74:75], v231 offset:512
	ds_read_b64_tr_b16 v[76:77], v231 offset:2048
	ds_read_b64_tr_b16 v[78:79], v231 offset:2560
	ds_read_b64_tr_b16 v[220:221], v231 offset:1024
	ds_read_b64_tr_b16 v[222:223], v231 offset:1536
	ds_read_b64_tr_b16 v[224:225], v231 offset:3072
	ds_read_b64_tr_b16 v[226:227], v231 offset:3584
	s_waitcnt vmcnt(8)
	ds_write_b128 v247, v[116:119]
	ds_write_b128 v247, v[120:123] offset:1024
	ds_write_b128 v111, v[124:127] offset:2048
	ds_write_b128 v111, v[128:131] offset:3072
	ds_read_b128 v[116:119], v248
	ds_read_b128 v[120:123], v249
	ds_read_b128 v[124:127], v250
	ds_read_b128 v[128:131], v251
	ds_write_b128 v112, v[132:135]
	ds_write_b128 v112, v[136:139] offset:1024
	ds_write_b128 v112, v[140:143] offset:2048
	ds_write_b128 v112, v[144:147] offset:3072
	v_mfma_f32_32x32x16_bf16 v[32:47], v[192:195], v[52:55], v[32:47]
	v_mfma_f32_32x32x16_bf16 v[32:47], v[196:199], v[56:59], v[32:47]
	v_mfma_f32_32x32x16_bf16 v[32:47], v[200:203], v[60:63], v[32:47]
	s_nop 11
	v_exp_f32_e32 v32, v32
	v_exp_f32_e32 v33, v33
	v_exp_f32_e32 v34, v34
	v_exp_f32_e32 v35, v35
	v_exp_f32_e32 v36, v36
	v_exp_f32_e32 v37, v37
	v_exp_f32_e32 v38, v38
	v_exp_f32_e32 v39, v39
	v_exp_f32_e32 v40, v40
	v_exp_f32_e32 v41, v41
	v_exp_f32_e32 v42, v42
	v_exp_f32_e32 v43, v43
	v_exp_f32_e32 v44, v44
	v_exp_f32_e32 v45, v45
	v_exp_f32_e32 v46, v46
	v_exp_f32_e32 v47, v47
	v_cvt_pk_bf16_f32 v64, v32, v33
	v_cvt_pk_bf16_f32 v65, v34, v35
	v_cvt_pk_bf16_f32 v66, v36, v37
	v_cvt_pk_bf16_f32 v67, v38, v39
	v_cvt_pk_bf16_f32 v68, v40, v41
	v_cvt_pk_bf16_f32 v69, v42, v43
	v_cvt_pk_bf16_f32 v70, v44, v45
	v_cvt_pk_bf16_f32 v71, v46, v47
	v_pk_add_f32 v[232:233], v[232:233], v[32:33]
	v_pk_add_f32 v[232:233], v[232:233], v[34:35]
	v_pk_add_f32 v[232:233], v[232:233], v[36:37]
	v_pk_add_f32 v[232:233], v[232:233], v[38:39]
	v_pk_add_f32 v[232:233], v[232:233], v[40:41]
	v_pk_add_f32 v[232:233], v[232:233], v[42:43]
	v_pk_add_f32 v[232:233], v[232:233], v[44:45]
	v_pk_add_f32 v[232:233], v[232:233], v[46:47]
	ds_read2_b32 v[32:33], v115 offset0:64 offset1:65
	ds_read2_b32 v[34:35], v115 offset0:66 offset1:67
	ds_read2_b32 v[36:37], v115 offset0:72 offset1:73
	ds_read2_b32 v[38:39], v115 offset0:74 offset1:75
	ds_read2_b32 v[40:41], v115 offset0:80 offset1:81
	ds_read2_b32 v[42:43], v115 offset0:82 offset1:83
	ds_read2_b32 v[44:45], v115 offset0:88 offset1:89
	ds_read2_b32 v[46:47], v115 offset0:90 offset1:91
	s_waitcnt lgkmcnt(15)
	v_mfma_f32_32x32x16_bf16 v[0:15], v[64:67], v[72:75], v[0:15]
	v_mfma_f32_32x32x16_bf16 v[16:31], v[64:67], v[76:79], v[16:31]
	v_mfma_f32_32x32x16_bf16 v[0:15], v[68:71], v[220:223], v[0:15]
	v_mfma_f32_32x32x16_bf16 v[16:31], v[68:71], v[224:227], v[16:31]
	global_load_dwordx4 v[188:191], v243, s[88:89]
	global_load_dwordx4 v[192:195], v244, s[88:89]
	global_load_dwordx4 v[196:199], v245, s[88:89]
	global_load_dwordx4 v[200:203], v246, s[88:89]
	global_load_dwordx4 v[204:207], v148, s[88:89] offset:768
	global_load_dwordx4 v[208:211], v151, s[88:89] offset:768
	global_load_dwordx4 v[212:215], v148, s[88:89] offset:832
	global_load_dwordx4 v[216:219], v151, s[88:89] offset:832
	s_waitcnt lgkmcnt(0)
	v_mfma_f32_32x32x16_bf16 v[32:47], v[116:119], v[48:51], v[32:47]
	ds_read_b64_tr_b16 v[72:73], v231
	ds_read_b64_tr_b16 v[74:75], v231 offset:512
	ds_read_b64_tr_b16 v[76:77], v231 offset:2048
	ds_read_b64_tr_b16 v[78:79], v231 offset:2560
	ds_read_b64_tr_b16 v[220:221], v231 offset:1024
	ds_read_b64_tr_b16 v[222:223], v231 offset:1536
	ds_read_b64_tr_b16 v[224:225], v231 offset:3072
	ds_read_b64_tr_b16 v[226:227], v231 offset:3584
	s_waitcnt vmcnt(8)
	ds_write_b128 v247, v[156:159]
	ds_write_b128 v247, v[160:163] offset:1024
	ds_write_b128 v111, v[164:167] offset:2048
	ds_write_b128 v111, v[168:171] offset:3072
	ds_read_b128 v[156:159], v248
	ds_read_b128 v[160:163], v249
	ds_read_b128 v[164:167], v250
	ds_read_b128 v[168:171], v251
	ds_write_b128 v112, v[172:175]
	ds_write_b128 v112, v[176:179] offset:1024
	ds_write_b128 v112, v[180:183] offset:2048
	ds_write_b128 v112, v[184:187] offset:3072
	v_mfma_f32_32x32x16_bf16 v[32:47], v[120:123], v[52:55], v[32:47]
	v_mfma_f32_32x32x16_bf16 v[32:47], v[124:127], v[56:59], v[32:47]
	v_mfma_f32_32x32x16_bf16 v[32:47], v[128:131], v[60:63], v[32:47]
	s_nop 11
	v_exp_f32_e32 v32, v32
	v_exp_f32_e32 v33, v33
	v_exp_f32_e32 v34, v34
	v_exp_f32_e32 v35, v35
	v_exp_f32_e32 v36, v36
	v_exp_f32_e32 v37, v37
	v_exp_f32_e32 v38, v38
	v_exp_f32_e32 v39, v39
	v_exp_f32_e32 v40, v40
	v_exp_f32_e32 v41, v41
	v_exp_f32_e32 v42, v42
	v_exp_f32_e32 v43, v43
	v_exp_f32_e32 v44, v44
	v_exp_f32_e32 v45, v45
	v_exp_f32_e32 v46, v46
	v_exp_f32_e32 v47, v47
	v_cvt_pk_bf16_f32 v64, v32, v33
	v_cvt_pk_bf16_f32 v65, v34, v35
	v_cvt_pk_bf16_f32 v66, v36, v37
	v_cvt_pk_bf16_f32 v67, v38, v39
	v_cvt_pk_bf16_f32 v68, v40, v41
	v_cvt_pk_bf16_f32 v69, v42, v43
	v_cvt_pk_bf16_f32 v70, v44, v45
	v_cvt_pk_bf16_f32 v71, v46, v47
	v_pk_add_f32 v[232:233], v[232:233], v[32:33]
	v_pk_add_f32 v[232:233], v[232:233], v[34:35]
	v_pk_add_f32 v[232:233], v[232:233], v[36:37]
	v_pk_add_f32 v[232:233], v[232:233], v[38:39]
	v_pk_add_f32 v[232:233], v[232:233], v[40:41]
	v_pk_add_f32 v[232:233], v[232:233], v[42:43]
	v_pk_add_f32 v[232:233], v[232:233], v[44:45]
	v_pk_add_f32 v[232:233], v[232:233], v[46:47]
	ds_read2_b32 v[32:33], v115 offset0:96 offset1:97
	ds_read2_b32 v[34:35], v115 offset0:98 offset1:99
	ds_read2_b32 v[36:37], v115 offset0:104 offset1:105
	ds_read2_b32 v[38:39], v115 offset0:106 offset1:107
	ds_read2_b32 v[40:41], v115 offset0:112 offset1:113
	ds_read2_b32 v[42:43], v115 offset0:114 offset1:115
	ds_read2_b32 v[44:45], v115 offset0:120 offset1:121
	ds_read2_b32 v[46:47], v115 offset0:122 offset1:123
	s_waitcnt lgkmcnt(15)
	v_mfma_f32_32x32x16_bf16 v[0:15], v[64:67], v[72:75], v[0:15]
	v_mfma_f32_32x32x16_bf16 v[16:31], v[64:67], v[76:79], v[16:31]
	v_mfma_f32_32x32x16_bf16 v[0:15], v[68:71], v[220:223], v[0:15]
	v_mfma_f32_32x32x16_bf16 v[16:31], v[68:71], v[224:227], v[16:31]
	s_waitcnt lgkmcnt(0)
	v_mfma_f32_32x32x16_bf16 v[32:47], v[156:159], v[48:51], v[32:47]
	ds_read_b64_tr_b16 v[72:73], v231
	ds_read_b64_tr_b16 v[74:75], v231 offset:512
	ds_read_b64_tr_b16 v[76:77], v231 offset:2048
	ds_read_b64_tr_b16 v[78:79], v231 offset:2560
	ds_read_b64_tr_b16 v[220:221], v231 offset:1024
	ds_read_b64_tr_b16 v[222:223], v231 offset:1536
	ds_read_b64_tr_b16 v[224:225], v231 offset:3072
	ds_read_b64_tr_b16 v[226:227], v231 offset:3584
	s_waitcnt vmcnt(0)
	ds_write_b128 v247, v[188:191]
	ds_write_b128 v247, v[192:195] offset:1024
	ds_write_b128 v111, v[196:199] offset:2048
	ds_write_b128 v111, v[200:203] offset:3072
	ds_read_b128 v[188:191], v248
	ds_read_b128 v[192:195], v249
	ds_read_b128 v[196:199], v250
	ds_read_b128 v[200:203], v251
	ds_write_b128 v112, v[204:207]
	ds_write_b128 v112, v[208:211] offset:1024
	ds_write_b128 v112, v[212:215] offset:2048
	ds_write_b128 v112, v[216:219] offset:3072
	v_mfma_f32_32x32x16_bf16 v[32:47], v[160:163], v[52:55], v[32:47]
	v_mfma_f32_32x32x16_bf16 v[32:47], v[164:167], v[56:59], v[32:47]
	v_mfma_f32_32x32x16_bf16 v[32:47], v[168:171], v[60:63], v[32:47]
	s_nop 11
	v_exp_f32_e32 v32, v32
	v_exp_f32_e32 v33, v33
	v_exp_f32_e32 v34, v34
	v_exp_f32_e32 v35, v35
	v_exp_f32_e32 v36, v36
	v_exp_f32_e32 v37, v37
	v_exp_f32_e32 v38, v38
	v_exp_f32_e32 v39, v39
	v_exp_f32_e32 v40, v40
	v_exp_f32_e32 v41, v41
	v_exp_f32_e32 v42, v42
	v_exp_f32_e32 v43, v43
	v_exp_f32_e32 v44, v44
	v_exp_f32_e32 v45, v45
	v_exp_f32_e32 v46, v46
	v_exp_f32_e32 v47, v47
	v_cvt_pk_bf16_f32 v64, v32, v33
	v_cvt_pk_bf16_f32 v65, v34, v35
	v_cvt_pk_bf16_f32 v66, v36, v37
	v_cvt_pk_bf16_f32 v67, v38, v39
	v_cvt_pk_bf16_f32 v68, v40, v41
	v_cvt_pk_bf16_f32 v69, v42, v43
	v_cvt_pk_bf16_f32 v70, v44, v45
	v_cvt_pk_bf16_f32 v71, v46, v47
	v_pk_add_f32 v[232:233], v[232:233], v[32:33]
	v_pk_add_f32 v[232:233], v[232:233], v[34:35]
	v_pk_add_f32 v[232:233], v[232:233], v[36:37]
	v_pk_add_f32 v[232:233], v[232:233], v[38:39]
	v_pk_add_f32 v[232:233], v[232:233], v[40:41]
	v_pk_add_f32 v[232:233], v[232:233], v[42:43]
	v_pk_add_f32 v[232:233], v[232:233], v[44:45]
	v_pk_add_f32 v[232:233], v[232:233], v[46:47]
	ds_read2_b32 v[32:33], v115 offset0:128 offset1:129
	ds_read2_b32 v[34:35], v115 offset0:130 offset1:131
	ds_read2_b32 v[36:37], v115 offset0:136 offset1:137
	ds_read2_b32 v[38:39], v115 offset0:138 offset1:139
	ds_read2_b32 v[40:41], v115 offset0:144 offset1:145
	ds_read2_b32 v[42:43], v115 offset0:146 offset1:147
	ds_read2_b32 v[44:45], v115 offset0:152 offset1:153
	ds_read2_b32 v[46:47], v115 offset0:154 offset1:155
	s_waitcnt lgkmcnt(15)
; #define LAS __attribute__((address_space(3)))
; #define GAS __attribute__((address_space(1)))
; __device__ __forceinline__ void dil_unit(LAS unsigned char* lds, bf16_t* proj, int seq, int hd, int T0, int rho) {
;     ...
;     bf16_t* base = proj + (size_t)seq * SEQ * NIN;
;     LAS unsigned char* wbuf = lds + wid * 4096;
;     const LAS unsigned char* vp = wbuf + ((lane >> 4) & 1) * 32 + (lane & 3) * 8 + (4 * hi + ((lane & 15) >> 2)) * 64;
;     const int P0 = T0 + rho;
;     bf16x8 qr[4];
; #pragma unroll
;     for (int ks = 0; ks < 4; ++ks) qr[ks] = *(const GAS bf16x8*)(base + (size_t)(P0 + 16 * r32) * NIN + PC_LQ + hd * 64 + 16 * ks + 8 * hi);
;     f32x16 o0 = {}, o1 = {}; float l = 0.f;
;     const bool bound = (T0 < 1024) || (T0 >= 15360);
;     ...
;     if (bound) DIL_LOOP(true); else DIL_LOOP(false);
;     ...
;     LAS bf16_t* stg = (LAS bf16_t*)wbuf;
;     l += __shfl_xor(l, 32);
	v_mfma_f32_32x32x16_bf16 v[0:15], v[64:67], v[72:75], v[0:15]
	v_mfma_f32_32x32x16_bf16 v[16:31], v[64:67], v[76:79], v[16:31]
	v_mfma_f32_32x32x16_bf16 v[0:15], v[68:71], v[220:223], v[0:15]
	v_mfma_f32_32x32x16_bf16 v[16:31], v[68:71], v[224:227], v[16:31]
	s_waitcnt lgkmcnt(0)
	v_mfma_f32_32x32x16_bf16 v[32:47], v[188:191], v[48:51], v[32:47]
	ds_read_b64_tr_b16 v[72:73], v231
	ds_read_b64_tr_b16 v[74:75], v231 offset:512
	ds_read_b64_tr_b16 v[76:77], v231 offset:2048
	ds_read_b64_tr_b16 v[78:79], v231 offset:2560
	ds_read_b64_tr_b16 v[220:221], v231 offset:1024
	ds_read_b64_tr_b16 v[222:223], v231 offset:1536
	ds_read_b64_tr_b16 v[224:225], v231 offset:3072
	ds_read_b64_tr_b16 v[226:227], v231 offset:3584
	v_mfma_f32_32x32x16_bf16 v[32:47], v[192:195], v[52:55], v[32:47]
	v_mfma_f32_32x32x16_bf16 v[32:47], v[196:199], v[56:59], v[32:47]
	v_mfma_f32_32x32x16_bf16 v[32:47], v[200:203], v[60:63], v[32:47]
	s_nop 11
	v_exp_f32_e32 v32, v32
	v_exp_f32_e32 v33, v33
	v_exp_f32_e32 v34, v34
	v_exp_f32_e32 v35, v35
	v_exp_f32_e32 v36, v36
	v_exp_f32_e32 v37, v37
	v_exp_f32_e32 v38, v38
	v_exp_f32_e32 v39, v39
	v_exp_f32_e32 v40, v40
	v_exp_f32_e32 v41, v41
	v_exp_f32_e32 v42, v42
	v_exp_f32_e32 v43, v43
	v_exp_f32_e32 v44, v44
	v_exp_f32_e32 v45, v45
	v_exp_f32_e32 v46, v46
	v_exp_f32_e32 v47, v47
	v_cvt_pk_bf16_f32 v64, v32, v33
	v_cvt_pk_bf16_f32 v65, v34, v35
	v_cvt_pk_bf16_f32 v66, v36, v37
	v_cvt_pk_bf16_f32 v67, v38, v39
	v_cvt_pk_bf16_f32 v68, v40, v41
	v_cvt_pk_bf16_f32 v69, v42, v43
	v_cvt_pk_bf16_f32 v70, v44, v45
	v_cvt_pk_bf16_f32 v71, v46, v47
	v_pk_add_f32 v[232:233], v[232:233], v[32:33]
	v_pk_add_f32 v[232:233], v[232:233], v[34:35]
	v_pk_add_f32 v[232:233], v[232:233], v[36:37]
	v_pk_add_f32 v[232:233], v[232:233], v[38:39]
	v_pk_add_f32 v[232:233], v[232:233], v[40:41]
	v_pk_add_f32 v[232:233], v[232:233], v[42:43]
	v_pk_add_f32 v[232:233], v[232:233], v[44:45]
	v_pk_add_f32 v[232:233], v[232:233], v[46:47]
	s_waitcnt lgkmcnt(0)
	v_mfma_f32_32x32x16_bf16 v[0:15], v[64:67], v[72:75], v[0:15]
	v_mfma_f32_32x32x16_bf16 v[16:31], v[64:67], v[76:79], v[16:31]
	v_mfma_f32_32x32x16_bf16 v[0:15], v[68:71], v[220:223], v[0:15]
	v_mfma_f32_32x32x16_bf16 v[16:31], v[68:71], v[224:227], v[16:31]
	v_add_f32_e32 v113, v232, v233
	v_or_b32_e32 v114, 1, v107
	v_or_b32_e32 v97, 2, v107
	v_or_b32_e32 v96, 3, v107
	v_or_b32_e32 v95, 8, v107
	v_or_b32_e32 v94, 9, v107
	v_or_b32_e32 v93, 10, v107
	v_or_b32_e32 v92, 11, v107
	v_or_b32_e32 v91, 16, v107
	v_or_b32_e32 v90, 17, v107
	v_or_b32_e32 v89, 18, v107
	v_or_b32_e32 v88, 19, v107
	v_or_b32_e32 v87, 24, v107
	v_or_b32_e32 v86, 25, v107
	v_or_b32_e32 v85, 26, v107
	v_or_b32_e32 v84, 27, v107
	s_nop 11
	s_branch .LBB0_553
.LBB0_558:
	s_movk_i32 s100, 0x1800
	s_add_i32 s101, s6, 0x15c00
	s_lshl_b32 s90, s58, 1
	s_add_u32 s82, s56, s90
	s_addc_u32 s83, s57, 0
	s_add_u32 s82, s82, 0x1200
	s_addc_u32 s83, s83, 0
	s_sub_i32 s90, s76, 64
	s_mul_i32 s90, s90, 0x1800
	s_add_u32 s84, s82, s90
	s_addc_u32 s85, s83, 0
	s_sub_i32 s90, s76, 256
	s_mul_i32 s90, s90, 0x1800
	s_add_u32 s86, s82, s90
	s_addc_u32 s87, s83, 0
	s_sub_i32 s90, s76, 1024
	s_mul_i32 s90, s90, 0x1800
	s_add_u32 s88, s82, s90
	s_addc_u32 s89, s83, 0
	v_lshlrev_b32_e32 v153, 1, v98
	v_mad_u32_u24 v80, v105, s100, v82
	v_mad_u32_u24 v100, v110, s100, v153
	v_add_u32_e32 v149, 0x18000, v100
	v_lshlrev_b32_e32 v83, 2, v105
	v_mad_u32_u24 v83, v83, s100, v82
	v_lshlrev_b32_e32 v101, 2, v110
	v_mad_u32_u24 v101, v101, s100, v153
	v_add_u32_e32 v150, 0x60000, v101
	v_lshlrev_b32_e32 v99, 4, v105
	v_mad_u32_u24 v99, v99, s100, v82
	v_lshlrev_b32_e32 v148, 4, v110
	v_mad_u32_u24 v148, v148, s100, v153
	v_add_u32_e32 v151, 0x180000, v148
	v_lshrrev_b32_e32 v249, 3, v103
	v_and_b32_e32 v250, 7, v103
	v_lshlrev_b32_e32 v250, 4, v250
	v_add_u32_e32 v235, 0, v249
	v_add_u32_e32 v236, 8, v249
	v_add_u32_e32 v237, 16, v249
	v_add_u32_e32 v238, 24, v249
	v_add_u32_e32 v239, 0, v249
	v_lshlrev_b32_e32 v239, 2, v239
	v_add_u32_e32 v240, 8, v249
	v_lshlrev_b32_e32 v240, 2, v240
	v_add_u32_e32 v241, 16, v249
	v_lshlrev_b32_e32 v241, 2, v241
	v_add_u32_e32 v242, 24, v249
	v_lshlrev_b32_e32 v242, 2, v242
	v_add_u32_e32 v243, 0, v249
	v_lshlrev_b32_e32 v243, 4, v243
	v_add_u32_e32 v244, 8, v249
	v_lshlrev_b32_e32 v244, 4, v244
	v_add_u32_e32 v245, 16, v249
	v_lshlrev_b32_e32 v245, 4, v245
	v_add_u32_e32 v246, 24, v249
	v_lshlrev_b32_e32 v246, 4, v246
	v_mov_b32_e32 v252, v250
	v_mov_b32_e32 v100, v110
	v_add_u32_e32 v149, 16, v100
	v_lshlrev_b32_e32 v101, 2, v110
	v_add_u32_e32 v150, 64, v101
	v_lshlrev_b32_e32 v148, 4, v110
	v_add_u32_e32 v151, 256, v148
	s_mov_b32 s98, 0x4000
	s_mov_b32 s99, 0x3fff
	v_and_b32_e32 v247, 7, v249
	v_lshlrev_b32_e32 v247, 4, v247
	v_xor_b32_e32 v247, v247, v112
	v_xor_b32_e32 v111, 16, v247
	v_and_b32_e32 v153, 7, v105
	v_lshrrev_b32_e32 v248, 4, v105
	v_xor_b32_e32 v153, v153, v248
	v_or_b32_e32 v248, 0, v106
	v_xor_b32_e32 v248, v248, v153
	v_lshlrev_b32_e32 v248, 4, v248
	v_lshl_add_u32 v248, v105, 7, v248
	v_add_u32_e32 v248, s77, v248
	v_or_b32_e32 v249, 2, v106
	v_xor_b32_e32 v249, v249, v153
	v_lshlrev_b32_e32 v249, 4, v249
	v_lshl_add_u32 v249, v105, 7, v249
	v_add_u32_e32 v249, s77, v249
	v_or_b32_e32 v250, 4, v106
	v_xor_b32_e32 v250, v250, v153
	v_lshlrev_b32_e32 v250, 4, v250
	v_lshl_add_u32 v250, v105, 7, v250
	v_add_u32_e32 v250, s77, v250
	v_or_b32_e32 v251, 6, v106
	v_xor_b32_e32 v251, v251, v153
	v_lshlrev_b32_e32 v251, 4, v251
	v_lshl_add_u32 v251, v105, 7, v251
	v_add_u32_e32 v251, s77, v251
	v_lshlrev_b32_e32 v153, 1, v98
	v_mul_u32_u24_e32 v228, 17, v105
	v_sub_u32_e32 v228, v107, v228
	s_mul_i32 s90, s58, 153
; __device__ __forceinline__ void dil_unit(LAS unsigned char* lds, bf16_t* proj, int seq, int hd, int T0, int rho) {
;     ...
;     f32x16 o0 = {}, o1 = {}; float l = 0.f;
;     const bool bound = (T0 < 1024) || (T0 >= 15360);
	s_lshr_b32 s90, s90, 1
	s_add_i32 s90, s90, 34876
	v_lshl_add_u32 v228, v228, 2, s90
	v_mul_u32_u24_e32 v229, 5, v105
	v_sub_u32_e32 v229, v107, v229
	v_add_u32_e32 v229, v229, v106
	s_mul_i32 s90, s58, 30
	s_add_i32 s90, s90, 66156
	v_lshl_add_u32 v229, v229, 2, s90
	v_sub_u32_e32 v230, v107, v105
	s_add_i32 s90, s101, 6364
	v_lshl_add_u32 v230, v230, 2, s90
	v_add_u32_e32 v231, v109, v108
	v_mov_b64_e32 v[232:233], 0
	v_mov_b64_e32 v[0:1], 0
	v_mov_b64_e32 v[2:3], 0
	v_mov_b64_e32 v[4:5], 0
	v_mov_b64_e32 v[6:7], 0
	v_mov_b64_e32 v[8:9], 0
	v_mov_b64_e32 v[10:11], 0
	v_mov_b64_e32 v[12:13], 0
	v_mov_b64_e32 v[14:15], 0
	v_mov_b64_e32 v[16:17], 0
	v_mov_b64_e32 v[18:19], 0
	v_mov_b64_e32 v[20:21], 0
	v_mov_b64_e32 v[22:23], 0
	v_mov_b64_e32 v[24:25], 0
	v_mov_b64_e32 v[26:27], 0
	v_mov_b64_e32 v[28:29], 0
	v_mov_b64_e32 v[30:31], 0
	s_add_i32 s90, s76, -64
	v_add_u32_e32 v80, s90, v235
	v_add_u32_e32 v83, s90, v236
	v_add_u32_e32 v99, s90, v237
	v_add_u32_e32 v253, s90, v238
	v_add_u32_e32 v254, s90, v100
	v_add_u32_e32 v255, s90, v149
	v_med3_i32 v80, v80, 0, s99
	v_med3_i32 v83, v83, 0, s99
	v_med3_i32 v99, v99, 0, s99
	v_med3_i32 v253, v253, 0, s99
	v_med3_i32 v254, v254, 0, s99
	v_med3_i32 v255, v255, 0, s99
	v_mad_u32_u24 v80, v80, s100, v252
	v_mad_u32_u24 v83, v83, s100, v252
	v_mad_u32_u24 v99, v99, s100, v252
	v_mad_u32_u24 v253, v253, s100, v252
	v_mad_u32_u24 v254, v254, s100, v153
	v_mad_u32_u24 v255, v255, s100, v153
	global_load_dwordx4 v[116:119], v80, s[82:83]
	global_load_dwordx4 v[120:123], v83, s[82:83]
	global_load_dwordx4 v[124:127], v99, s[82:83]
	global_load_dwordx4 v[128:131], v253, s[82:83]
	global_load_dwordx4 v[132:135], v254, s[82:83] offset:768
	global_load_dwordx4 v[136:139], v255, s[82:83] offset:768
	global_load_dwordx4 v[140:143], v254, s[82:83] offset:832
	global_load_dwordx4 v[144:147], v255, s[82:83] offset:832
	s_add_i32 s90, s76, -32
	v_add_u32_e32 v80, s90, v235
	v_add_u32_e32 v83, s90, v236
	v_add_u32_e32 v99, s90, v237
	v_add_u32_e32 v253, s90, v238
	v_add_u32_e32 v254, s90, v100
	v_add_u32_e32 v255, s90, v149
	v_med3_i32 v80, v80, 0, s99
	v_med3_i32 v83, v83, 0, s99
	v_med3_i32 v99, v99, 0, s99
	v_med3_i32 v253, v253, 0, s99
	v_med3_i32 v254, v254, 0, s99
	v_med3_i32 v255, v255, 0, s99
	v_mad_u32_u24 v80, v80, s100, v252
	v_mad_u32_u24 v83, v83, s100, v252
	v_mad_u32_u24 v99, v99, s100, v252
	v_mad_u32_u24 v253, v253, s100, v252
	v_mad_u32_u24 v254, v254, s100, v153
	v_mad_u32_u24 v255, v255, s100, v153
	global_load_dwordx4 v[156:159], v80, s[82:83]
	global_load_dwordx4 v[160:163], v83, s[82:83]
	global_load_dwordx4 v[164:167], v99, s[82:83]
	global_load_dwordx4 v[168:171], v253, s[82:83]
	global_load_dwordx4 v[172:175], v254, s[82:83] offset:768
	global_load_dwordx4 v[176:179], v255, s[82:83] offset:768
	global_load_dwordx4 v[180:183], v254, s[82:83] offset:832
	global_load_dwordx4 v[184:187], v255, s[82:83] offset:832
	s_add_i32 s90, s76, 0
	v_add_u32_e32 v80, s90, v235
	v_add_u32_e32 v83, s90, v236
	v_add_u32_e32 v99, s90, v237
	v_add_u32_e32 v253, s90, v238
	v_add_u32_e32 v254, s90, v100
	v_add_u32_e32 v255, s90, v149
	v_med3_i32 v80, v80, 0, s99
	v_med3_i32 v83, v83, 0, s99
	v_med3_i32 v99, v99, 0, s99
	v_med3_i32 v253, v253, 0, s99
	v_med3_i32 v254, v254, 0, s99
	v_med3_i32 v255, v255, 0, s99
	v_mad_u32_u24 v80, v80, s100, v252
	v_mad_u32_u24 v83, v83, s100, v252
	v_mad_u32_u24 v99, v99, s100, v252
	v_mad_u32_u24 v253, v253, s100, v252
	v_mad_u32_u24 v254, v254, s100, v153
	v_mad_u32_u24 v255, v255, s100, v153
	global_load_dwordx4 v[188:191], v80, s[82:83]
	global_load_dwordx4 v[192:195], v83, s[82:83]
	global_load_dwordx4 v[196:199], v99, s[82:83]
	global_load_dwordx4 v[200:203], v253, s[82:83]
	global_load_dwordx4 v[204:207], v254, s[82:83] offset:768
	global_load_dwordx4 v[208:211], v255, s[82:83] offset:768
	global_load_dwordx4 v[212:215], v254, s[82:83] offset:832
	global_load_dwordx4 v[216:219], v255, s[82:83] offset:832
	s_waitcnt vmcnt(16)
	ds_write_b128 v247, v[116:119]
	ds_write_b128 v247, v[120:123] offset:1024
	ds_write_b128 v111, v[124:127] offset:2048
	ds_write_b128 v111, v[128:131] offset:3072
	ds_read_b128 v[116:119], v248
	ds_read_b128 v[120:123], v249
	ds_read_b128 v[124:127], v250
	ds_read_b128 v[128:131], v251
	ds_write_b128 v112, v[132:135]
	ds_write_b128 v112, v[136:139] offset:1024
	ds_write_b128 v112, v[140:143] offset:2048
	ds_write_b128 v112, v[144:147] offset:3072
	v_mov_b32_e32 v115, v228
	ds_read2_b32 v[32:33], v115 offset0:0 offset1:1
	ds_read2_b32 v[34:35], v115 offset0:2 offset1:3
	ds_read2_b32 v[36:37], v115 offset0:8 offset1:9
	ds_read2_b32 v[38:39], v115 offset0:10 offset1:11
	ds_read2_b32 v[40:41], v115 offset0:17 offset1:18
	ds_read2_b32 v[42:43], v115 offset0:19 offset1:20
	ds_read2_b32 v[44:45], v115 offset0:25 offset1:26
	ds_read2_b32 v[46:47], v115 offset0:27 offset1:28
	s_waitcnt lgkmcnt(0)
	v_mfma_f32_32x32x16_bf16 v[32:47], v[116:119], v[48:51], v[32:47]
	ds_read_b64_tr_b16 v[72:73], v231
	ds_read_b64_tr_b16 v[74:75], v231 offset:512
	ds_read_b64_tr_b16 v[76:77], v231 offset:2048
	ds_read_b64_tr_b16 v[78:79], v231 offset:2560
	ds_read_b64_tr_b16 v[220:221], v231 offset:1024
	ds_read_b64_tr_b16 v[222:223], v231 offset:1536
	ds_read_b64_tr_b16 v[224:225], v231 offset:3072
	ds_read_b64_tr_b16 v[226:227], v231 offset:3584
	s_waitcnt vmcnt(8)
	ds_write_b128 v247, v[156:159]
	ds_write_b128 v247, v[160:163] offset:1024
	ds_write_b128 v111, v[164:167] offset:2048
	ds_write_b128 v111, v[168:171] offset:3072
	ds_read_b128 v[156:159], v248
	ds_read_b128 v[160:163], v249
	ds_read_b128 v[164:167], v250
	ds_read_b128 v[168:171], v251
	ds_write_b128 v112, v[172:175]
	ds_write_b128 v112, v[176:179] offset:1024
	ds_write_b128 v112, v[180:183] offset:2048
	ds_write_b128 v112, v[184:187] offset:3072
	v_mfma_f32_32x32x16_bf16 v[32:47], v[120:123], v[52:55], v[32:47]
	v_mfma_f32_32x32x16_bf16 v[32:47], v[124:127], v[56:59], v[32:47]
	v_mfma_f32_32x32x16_bf16 v[32:47], v[128:131], v[60:63], v[32:47]
	s_nop 11
	v_exp_f32_e32 v32, v32
	v_exp_f32_e32 v33, v33
	v_exp_f32_e32 v34, v34
	v_exp_f32_e32 v35, v35
	v_exp_f32_e32 v36, v36
	v_exp_f32_e32 v37, v37
	v_exp_f32_e32 v38, v38
	v_exp_f32_e32 v39, v39
	v_exp_f32_e32 v40, v40
	v_exp_f32_e32 v41, v41
	v_exp_f32_e32 v42, v42
	v_exp_f32_e32 v43, v43
	v_exp_f32_e32 v44, v44
	v_exp_f32_e32 v45, v45
	v_exp_f32_e32 v46, v46
	v_exp_f32_e32 v47, v47
	s_add_i32 s90, s76, -64
	v_add_u32_e32 v84, s90, v107
	v_add_u32_e32 v85, 0, v84
	v_add_u32_e32 v86, 1, v84
	v_add_u32_e32 v87, 2, v84
	v_add_u32_e32 v88, 3, v84
	v_cmp_gt_u32_e64 s[30:31], s98, v85
	v_cmp_gt_u32_e64 s[36:37], s98, v86
	v_cmp_gt_u32_e64 s[78:79], s98, v87
	v_cmp_gt_u32_e64 s[50:51], s98, v88
	v_cndmask_b32_e64 v32, 0, v32, s[30:31]
	v_add_u32_e32 v85, 8, v84
	v_cmp_gt_u32_e64 s[30:31], s98, v85
	v_cndmask_b32_e64 v33, 0, v33, s[36:37]
	v_add_u32_e32 v86, 9, v84
	v_cmp_gt_u32_e64 s[36:37], s98, v86
	v_cndmask_b32_e64 v34, 0, v34, s[78:79]
	v_add_u32_e32 v87, 10, v84
	v_cmp_gt_u32_e64 s[78:79], s98, v87
	v_cndmask_b32_e64 v35, 0, v35, s[50:51]
	v_add_u32_e32 v88, 11, v84
	v_cmp_gt_u32_e64 s[50:51], s98, v88
	v_cndmask_b32_e64 v36, 0, v36, s[30:31]
	v_add_u32_e32 v85, 16, v84
	v_cmp_gt_u32_e64 s[30:31], s98, v85
	v_cndmask_b32_e64 v37, 0, v37, s[36:37]
	v_add_u32_e32 v86, 17, v84
	v_cmp_gt_u32_e64 s[36:37], s98, v86
	v_cndmask_b32_e64 v38, 0, v38, s[78:79]
	v_add_u32_e32 v87, 18, v84
	v_cmp_gt_u32_e64 s[78:79], s98, v87
	v_cndmask_b32_e64 v39, 0, v39, s[50:51]
	v_add_u32_e32 v88, 19, v84
	v_cmp_gt_u32_e64 s[50:51], s98, v88
	v_cndmask_b32_e64 v40, 0, v40, s[30:31]
	v_add_u32_e32 v85, 24, v84
	v_cmp_gt_u32_e64 s[30:31], s98, v85
	v_cndmask_b32_e64 v41, 0, v41, s[36:37]
	v_add_u32_e32 v86, 25, v84
	v_cmp_gt_u32_e64 s[36:37], s98, v86
	v_cndmask_b32_e64 v42, 0, v42, s[78:79]
	v_add_u32_e32 v87, 26, v84
	v_cmp_gt_u32_e64 s[78:79], s98, v87
	v_cndmask_b32_e64 v43, 0, v43, s[50:51]
	v_add_u32_e32 v88, 27, v84
	v_cmp_gt_u32_e64 s[50:51], s98, v88
	v_nop
	v_cndmask_b32_e64 v44, 0, v44, s[30:31]
	v_cndmask_b32_e64 v45, 0, v45, s[36:37]
	v_cndmask_b32_e64 v46, 0, v46, s[78:79]
	v_cndmask_b32_e64 v47, 0, v47, s[50:51]
	v_cvt_pk_bf16_f32 v64, v32, v33
	v_cvt_pk_bf16_f32 v65, v34, v35
	v_cvt_pk_bf16_f32 v66, v36, v37
	v_cvt_pk_bf16_f32 v67, v38, v39
	v_cvt_pk_bf16_f32 v68, v40, v41
	v_cvt_pk_bf16_f32 v69, v42, v43
	v_cvt_pk_bf16_f32 v70, v44, v45
	v_cvt_pk_bf16_f32 v71, v46, v47
	v_pk_add_f32 v[232:233], v[232:233], v[32:33]
	v_pk_add_f32 v[232:233], v[232:233], v[34:35]
	v_pk_add_f32 v[232:233], v[232:233], v[36:37]
	v_pk_add_f32 v[232:233], v[232:233], v[38:39]
	v_pk_add_f32 v[232:233], v[232:233], v[40:41]
	v_pk_add_f32 v[232:233], v[232:233], v[42:43]
	v_pk_add_f32 v[232:233], v[232:233], v[44:45]
	v_pk_add_f32 v[232:233], v[232:233], v[46:47]
	ds_read2_b32 v[32:33], v115 offset0:34 offset1:35
	ds_read2_b32 v[34:35], v115 offset0:36 offset1:37
	ds_read2_b32 v[36:37], v115 offset0:42 offset1:43
	ds_read2_b32 v[38:39], v115 offset0:44 offset1:45
	ds_read2_b32 v[40:41], v115 offset0:51 offset1:52
	ds_read2_b32 v[42:43], v115 offset0:53 offset1:54
	ds_read2_b32 v[44:45], v115 offset0:59 offset1:60
	ds_read2_b32 v[46:47], v115 offset0:61 offset1:62
	s_waitcnt lgkmcnt(15)
	v_mfma_f32_32x32x16_bf16 v[0:15], v[64:67], v[72:75], v[0:15]
	v_mfma_f32_32x32x16_bf16 v[16:31], v[64:67], v[76:79], v[16:31]
	v_mfma_f32_32x32x16_bf16 v[0:15], v[68:71], v[220:223], v[0:15]
	v_mfma_f32_32x32x16_bf16 v[16:31], v[68:71], v[224:227], v[16:31]
	s_add_i32 s90, s76, 32
	v_add_u32_e32 v80, s90, v235
	v_add_u32_e32 v83, s90, v236
	v_add_u32_e32 v99, s90, v237
	v_add_u32_e32 v253, s90, v238
	v_add_u32_e32 v254, s90, v100
	v_add_u32_e32 v255, s90, v149
	v_med3_i32 v80, v80, 0, s99
	v_med3_i32 v83, v83, 0, s99
	v_med3_i32 v99, v99, 0, s99
	v_med3_i32 v253, v253, 0, s99
	v_med3_i32 v254, v254, 0, s99
	v_med3_i32 v255, v255, 0, s99
	v_mad_u32_u24 v80, v80, s100, v252
	v_mad_u32_u24 v83, v83, s100, v252
	v_mad_u32_u24 v99, v99, s100, v252
	v_mad_u32_u24 v253, v253, s100, v252
	v_mad_u32_u24 v254, v254, s100, v153
	v_mad_u32_u24 v255, v255, s100, v153
	global_load_dwordx4 v[116:119], v80, s[82:83]
	global_load_dwordx4 v[120:123], v83, s[82:83]
	global_load_dwordx4 v[124:127], v99, s[82:83]
	global_load_dwordx4 v[128:131], v253, s[82:83]
	global_load_dwordx4 v[132:135], v254, s[82:83] offset:768
	global_load_dwordx4 v[136:139], v255, s[82:83] offset:768
	global_load_dwordx4 v[140:143], v254, s[82:83] offset:832
	global_load_dwordx4 v[144:147], v255, s[82:83] offset:832
	s_waitcnt lgkmcnt(0)
	v_mfma_f32_32x32x16_bf16 v[32:47], v[156:159], v[48:51], v[32:47]
	ds_read_b64_tr_b16 v[72:73], v231
	ds_read_b64_tr_b16 v[74:75], v231 offset:512
	ds_read_b64_tr_b16 v[76:77], v231 offset:2048
	ds_read_b64_tr_b16 v[78:79], v231 offset:2560
	ds_read_b64_tr_b16 v[220:221], v231 offset:1024
	ds_read_b64_tr_b16 v[222:223], v231 offset:1536
	ds_read_b64_tr_b16 v[224:225], v231 offset:3072
	ds_read_b64_tr_b16 v[226:227], v231 offset:3584
	s_waitcnt vmcnt(8)
	ds_write_b128 v247, v[188:191]
	ds_write_b128 v247, v[192:195] offset:1024
	ds_write_b128 v111, v[196:199] offset:2048
	ds_write_b128 v111, v[200:203] offset:3072
	ds_read_b128 v[188:191], v248
	ds_read_b128 v[192:195], v249
	ds_read_b128 v[196:199], v250
	ds_read_b128 v[200:203], v251
	ds_write_b128 v112, v[204:207]
	ds_write_b128 v112, v[208:211] offset:1024
	ds_write_b128 v112, v[212:215] offset:2048
	ds_write_b128 v112, v[216:219] offset:3072
	v_mfma_f32_32x32x16_bf16 v[32:47], v[160:163], v[52:55], v[32:47]
	v_mfma_f32_32x32x16_bf16 v[32:47], v[164:167], v[56:59], v[32:47]
	v_mfma_f32_32x32x16_bf16 v[32:47], v[168:171], v[60:63], v[32:47]
	s_nop 11
	v_exp_f32_e32 v32, v32
	v_exp_f32_e32 v33, v33
	v_exp_f32_e32 v34, v34
	v_exp_f32_e32 v35, v35
	v_exp_f32_e32 v36, v36
	v_exp_f32_e32 v37, v37
	v_exp_f32_e32 v38, v38
	v_exp_f32_e32 v39, v39
	v_exp_f32_e32 v40, v40
	v_exp_f32_e32 v41, v41
	v_exp_f32_e32 v42, v42
	v_exp_f32_e32 v43, v43
	v_exp_f32_e32 v44, v44
	v_exp_f32_e32 v45, v45
	v_exp_f32_e32 v46, v46
	v_exp_f32_e32 v47, v47
	s_add_i32 s90, s76, -32
	v_add_u32_e32 v84, s90, v107
	v_add_u32_e32 v85, 0, v84
	v_add_u32_e32 v86, 1, v84
	v_add_u32_e32 v87, 2, v84
	v_add_u32_e32 v88, 3, v84
	v_cmp_gt_u32_e64 s[30:31], s98, v85
	v_cmp_gt_u32_e64 s[36:37], s98, v86
	v_cmp_gt_u32_e64 s[78:79], s98, v87
	v_cmp_gt_u32_e64 s[50:51], s98, v88
	v_cndmask_b32_e64 v32, 0, v32, s[30:31]
	v_add_u32_e32 v85, 8, v84
	v_cmp_gt_u32_e64 s[30:31], s98, v85
	v_cndmask_b32_e64 v33, 0, v33, s[36:37]
	v_add_u32_e32 v86, 9, v84
	v_cmp_gt_u32_e64 s[36:37], s98, v86
	v_cndmask_b32_e64 v34, 0, v34, s[78:79]
	v_add_u32_e32 v87, 10, v84
	v_cmp_gt_u32_e64 s[78:79], s98, v87
	v_cndmask_b32_e64 v35, 0, v35, s[50:51]
	v_add_u32_e32 v88, 11, v84
	v_cmp_gt_u32_e64 s[50:51], s98, v88
	v_cndmask_b32_e64 v36, 0, v36, s[30:31]
	v_add_u32_e32 v85, 16, v84
	v_cmp_gt_u32_e64 s[30:31], s98, v85
	v_cndmask_b32_e64 v37, 0, v37, s[36:37]
	v_add_u32_e32 v86, 17, v84
	v_cmp_gt_u32_e64 s[36:37], s98, v86
	v_cndmask_b32_e64 v38, 0, v38, s[78:79]
	v_add_u32_e32 v87, 18, v84
	v_cmp_gt_u32_e64 s[78:79], s98, v87
	v_cndmask_b32_e64 v39, 0, v39, s[50:51]
	v_add_u32_e32 v88, 19, v84
	v_cmp_gt_u32_e64 s[50:51], s98, v88
	v_cndmask_b32_e64 v40, 0, v40, s[30:31]
	v_add_u32_e32 v85, 24, v84
	v_cmp_gt_u32_e64 s[30:31], s98, v85
	v_cndmask_b32_e64 v41, 0, v41, s[36:37]
	v_add_u32_e32 v86, 25, v84
	v_cmp_gt_u32_e64 s[36:37], s98, v86
	v_cndmask_b32_e64 v42, 0, v42, s[78:79]
	v_add_u32_e32 v87, 26, v84
	v_cmp_gt_u32_e64 s[78:79], s98, v87
	v_cndmask_b32_e64 v43, 0, v43, s[50:51]
	v_add_u32_e32 v88, 27, v84
	v_cmp_gt_u32_e64 s[50:51], s98, v88
	v_nop
	v_cndmask_b32_e64 v44, 0, v44, s[30:31]
	v_cndmask_b32_e64 v45, 0, v45, s[36:37]
	v_cndmask_b32_e64 v46, 0, v46, s[78:79]
	v_cndmask_b32_e64 v47, 0, v47, s[50:51]
	v_cvt_pk_bf16_f32 v64, v32, v33
	v_cvt_pk_bf16_f32 v65, v34, v35
	v_cvt_pk_bf16_f32 v66, v36, v37
	v_cvt_pk_bf16_f32 v67, v38, v39
	v_cvt_pk_bf16_f32 v68, v40, v41
	v_cvt_pk_bf16_f32 v69, v42, v43
	v_cvt_pk_bf16_f32 v70, v44, v45
	v_cvt_pk_bf16_f32 v71, v46, v47
	v_pk_add_f32 v[232:233], v[232:233], v[32:33]
	v_pk_add_f32 v[232:233], v[232:233], v[34:35]
	v_pk_add_f32 v[232:233], v[232:233], v[36:37]
	v_pk_add_f32 v[232:233], v[232:233], v[38:39]
	v_pk_add_f32 v[232:233], v[232:233], v[40:41]
	v_pk_add_f32 v[232:233], v[232:233], v[42:43]
	v_pk_add_f32 v[232:233], v[232:233], v[44:45]
	v_pk_add_f32 v[232:233], v[232:233], v[46:47]
	ds_read2_b32 v[32:33], v115 offset0:68 offset1:69
	ds_read2_b32 v[34:35], v115 offset0:70 offset1:71
	ds_read2_b32 v[36:37], v115 offset0:76 offset1:77
	ds_read2_b32 v[38:39], v115 offset0:78 offset1:79
	ds_read2_b32 v[40:41], v115 offset0:85 offset1:86
	ds_read2_b32 v[42:43], v115 offset0:87 offset1:88
	ds_read2_b32 v[44:45], v115 offset0:93 offset1:94
	ds_read2_b32 v[46:47], v115 offset0:95 offset1:96
	s_waitcnt lgkmcnt(15)
	v_mfma_f32_32x32x16_bf16 v[0:15], v[64:67], v[72:75], v[0:15]
	v_mfma_f32_32x32x16_bf16 v[16:31], v[64:67], v[76:79], v[16:31]
	v_mfma_f32_32x32x16_bf16 v[0:15], v[68:71], v[220:223], v[0:15]
	v_mfma_f32_32x32x16_bf16 v[16:31], v[68:71], v[224:227], v[16:31]
	s_add_i32 s90, s76, 64
	v_add_u32_e32 v80, s90, v235
	v_add_u32_e32 v83, s90, v236
	v_add_u32_e32 v99, s90, v237
	v_add_u32_e32 v253, s90, v238
	v_add_u32_e32 v254, s90, v100
	v_add_u32_e32 v255, s90, v149
	v_med3_i32 v80, v80, 0, s99
	v_med3_i32 v83, v83, 0, s99
	v_med3_i32 v99, v99, 0, s99
	v_med3_i32 v253, v253, 0, s99
	v_med3_i32 v254, v254, 0, s99
	v_med3_i32 v255, v255, 0, s99
	v_mad_u32_u24 v80, v80, s100, v252
	v_mad_u32_u24 v83, v83, s100, v252
	v_mad_u32_u24 v99, v99, s100, v252
	v_mad_u32_u24 v253, v253, s100, v252
	v_mad_u32_u24 v254, v254, s100, v153
	v_mad_u32_u24 v255, v255, s100, v153
	global_load_dwordx4 v[156:159], v80, s[82:83]
	global_load_dwordx4 v[160:163], v83, s[82:83]
	global_load_dwordx4 v[164:167], v99, s[82:83]
	global_load_dwordx4 v[168:171], v253, s[82:83]
	global_load_dwordx4 v[172:175], v254, s[82:83] offset:768
	global_load_dwordx4 v[176:179], v255, s[82:83] offset:768
	global_load_dwordx4 v[180:183], v254, s[82:83] offset:832
	global_load_dwordx4 v[184:187], v255, s[82:83] offset:832
	s_waitcnt lgkmcnt(0)
	v_mfma_f32_32x32x16_bf16 v[32:47], v[188:191], v[48:51], v[32:47]
	ds_read_b64_tr_b16 v[72:73], v231
	ds_read_b64_tr_b16 v[74:75], v231 offset:512
	ds_read_b64_tr_b16 v[76:77], v231 offset:2048
	ds_read_b64_tr_b16 v[78:79], v231 offset:2560
	ds_read_b64_tr_b16 v[220:221], v231 offset:1024
	ds_read_b64_tr_b16 v[222:223], v231 offset:1536
	ds_read_b64_tr_b16 v[224:225], v231 offset:3072
	ds_read_b64_tr_b16 v[226:227], v231 offset:3584
	s_waitcnt vmcnt(8)
	ds_write_b128 v247, v[116:119]
	ds_write_b128 v247, v[120:123] offset:1024
	ds_write_b128 v111, v[124:127] offset:2048
	ds_write_b128 v111, v[128:131] offset:3072
	ds_read_b128 v[116:119], v248
	ds_read_b128 v[120:123], v249
	ds_read_b128 v[124:127], v250
	ds_read_b128 v[128:131], v251
	ds_write_b128 v112, v[132:135]
	ds_write_b128 v112, v[136:139] offset:1024
	ds_write_b128 v112, v[140:143] offset:2048
	ds_write_b128 v112, v[144:147] offset:3072
	v_mfma_f32_32x32x16_bf16 v[32:47], v[192:195], v[52:55], v[32:47]
	v_mfma_f32_32x32x16_bf16 v[32:47], v[196:199], v[56:59], v[32:47]
	v_mfma_f32_32x32x16_bf16 v[32:47], v[200:203], v[60:63], v[32:47]
	s_nop 11
	v_exp_f32_e32 v32, v32
	v_exp_f32_e32 v33, v33
	v_exp_f32_e32 v34, v34
	v_exp_f32_e32 v35, v35
	v_exp_f32_e32 v36, v36
	v_exp_f32_e32 v37, v37
	v_exp_f32_e32 v38, v38
	v_exp_f32_e32 v39, v39
	v_exp_f32_e32 v40, v40
	v_exp_f32_e32 v41, v41
	v_exp_f32_e32 v42, v42
	v_exp_f32_e32 v43, v43
	v_exp_f32_e32 v44, v44
	v_exp_f32_e32 v45, v45
	v_exp_f32_e32 v46, v46
	v_exp_f32_e32 v47, v47
	s_add_i32 s90, s76, 0
	v_add_u32_e32 v84, s90, v107
	v_add_u32_e32 v85, 0, v84
	v_add_u32_e32 v86, 1, v84
	v_add_u32_e32 v87, 2, v84
	v_add_u32_e32 v88, 3, v84
	v_cmp_gt_u32_e64 s[30:31], s98, v85
	v_cmp_gt_u32_e64 s[36:37], s98, v86
	v_cmp_gt_u32_e64 s[78:79], s98, v87
	v_cmp_gt_u32_e64 s[50:51], s98, v88
	v_cndmask_b32_e64 v32, 0, v32, s[30:31]
	v_add_u32_e32 v85, 8, v84
	v_cmp_gt_u32_e64 s[30:31], s98, v85
	v_cndmask_b32_e64 v33, 0, v33, s[36:37]
	v_add_u32_e32 v86, 9, v84
	v_cmp_gt_u32_e64 s[36:37], s98, v86
	v_cndmask_b32_e64 v34, 0, v34, s[78:79]
	v_add_u32_e32 v87, 10, v84
	v_cmp_gt_u32_e64 s[78:79], s98, v87
	v_cndmask_b32_e64 v35, 0, v35, s[50:51]
	v_add_u32_e32 v88, 11, v84
	v_cmp_gt_u32_e64 s[50:51], s98, v88
	v_cndmask_b32_e64 v36, 0, v36, s[30:31]
	v_add_u32_e32 v85, 16, v84
	v_cmp_gt_u32_e64 s[30:31], s98, v85
	v_cndmask_b32_e64 v37, 0, v37, s[36:37]
	v_add_u32_e32 v86, 17, v84
	v_cmp_gt_u32_e64 s[36:37], s98, v86
	v_cndmask_b32_e64 v38, 0, v38, s[78:79]
	v_add_u32_e32 v87, 18, v84
	v_cmp_gt_u32_e64 s[78:79], s98, v87
	v_cndmask_b32_e64 v39, 0, v39, s[50:51]
	v_add_u32_e32 v88, 19, v84
	v_cmp_gt_u32_e64 s[50:51], s98, v88
	v_cndmask_b32_e64 v40, 0, v40, s[30:31]
	v_add_u32_e32 v85, 24, v84
	v_cmp_gt_u32_e64 s[30:31], s98, v85
	v_cndmask_b32_e64 v41, 0, v41, s[36:37]
	v_add_u32_e32 v86, 25, v84
	v_cmp_gt_u32_e64 s[36:37], s98, v86
	v_cndmask_b32_e64 v42, 0, v42, s[78:79]
	v_add_u32_e32 v87, 26, v84
	v_cmp_gt_u32_e64 s[78:79], s98, v87
	v_cndmask_b32_e64 v43, 0, v43, s[50:51]
	v_add_u32_e32 v88, 27, v84
	v_cmp_gt_u32_e64 s[50:51], s98, v88
	v_nop
	v_cndmask_b32_e64 v44, 0, v44, s[30:31]
	v_cndmask_b32_e64 v45, 0, v45, s[36:37]
	v_cndmask_b32_e64 v46, 0, v46, s[78:79]
	v_cndmask_b32_e64 v47, 0, v47, s[50:51]
	v_cvt_pk_bf16_f32 v64, v32, v33
	v_cvt_pk_bf16_f32 v65, v34, v35
	v_cvt_pk_bf16_f32 v66, v36, v37
	v_cvt_pk_bf16_f32 v67, v38, v39
	v_cvt_pk_bf16_f32 v68, v40, v41
	v_cvt_pk_bf16_f32 v69, v42, v43
	v_cvt_pk_bf16_f32 v70, v44, v45
	v_cvt_pk_bf16_f32 v71, v46, v47
	v_pk_add_f32 v[232:233], v[232:233], v[32:33]
	v_pk_add_f32 v[232:233], v[232:233], v[34:35]
	v_pk_add_f32 v[232:233], v[232:233], v[36:37]
	v_pk_add_f32 v[232:233], v[232:233], v[38:39]
	v_pk_add_f32 v[232:233], v[232:233], v[40:41]
	v_pk_add_f32 v[232:233], v[232:233], v[42:43]
	v_pk_add_f32 v[232:233], v[232:233], v[44:45]
	v_pk_add_f32 v[232:233], v[232:233], v[46:47]
	ds_read2_b32 v[32:33], v115 offset0:102 offset1:103
	ds_read2_b32 v[34:35], v115 offset0:104 offset1:105
	ds_read2_b32 v[36:37], v115 offset0:110 offset1:111
	ds_read2_b32 v[38:39], v115 offset0:112 offset1:113
	ds_read2_b32 v[40:41], v115 offset0:119 offset1:120
	ds_read2_b32 v[42:43], v115 offset0:121 offset1:122
	ds_read2_b32 v[44:45], v115 offset0:127 offset1:128
	ds_read2_b32 v[46:47], v115 offset0:129 offset1:130
	s_waitcnt lgkmcnt(15)
	v_mfma_f32_32x32x16_bf16 v[0:15], v[64:67], v[72:75], v[0:15]
	v_mfma_f32_32x32x16_bf16 v[16:31], v[64:67], v[76:79], v[16:31]
	v_mfma_f32_32x32x16_bf16 v[0:15], v[68:71], v[220:223], v[0:15]
	v_mfma_f32_32x32x16_bf16 v[16:31], v[68:71], v[224:227], v[16:31]
	s_add_i32 s90, s76, 96
	v_add_u32_e32 v80, s90, v235
	v_add_u32_e32 v83, s90, v236
	v_add_u32_e32 v99, s90, v237
	v_add_u32_e32 v253, s90, v238
	v_add_u32_e32 v254, s90, v100
	v_add_u32_e32 v255, s90, v149
	v_med3_i32 v80, v80, 0, s99
	v_med3_i32 v83, v83, 0, s99
	v_med3_i32 v99, v99, 0, s99
	v_med3_i32 v253, v253, 0, s99
	v_med3_i32 v254, v254, 0, s99
	v_med3_i32 v255, v255, 0, s99
	v_mad_u32_u24 v80, v80, s100, v252
	v_mad_u32_u24 v83, v83, s100, v252
	v_mad_u32_u24 v99, v99, s100, v252
	v_mad_u32_u24 v253, v253, s100, v252
	v_mad_u32_u24 v254, v254, s100, v153
	v_mad_u32_u24 v255, v255, s100, v153
	global_load_dwordx4 v[188:191], v80, s[82:83]
	global_load_dwordx4 v[192:195], v83, s[82:83]
	global_load_dwordx4 v[196:199], v99, s[82:83]
	global_load_dwordx4 v[200:203], v253, s[82:83]
	global_load_dwordx4 v[204:207], v254, s[82:83] offset:768
	global_load_dwordx4 v[208:211], v255, s[82:83] offset:768
	global_load_dwordx4 v[212:215], v254, s[82:83] offset:832
	global_load_dwordx4 v[216:219], v255, s[82:83] offset:832
	s_waitcnt lgkmcnt(0)
	v_mfma_f32_32x32x16_bf16 v[32:47], v[116:119], v[48:51], v[32:47]
	ds_read_b64_tr_b16 v[72:73], v231
	ds_read_b64_tr_b16 v[74:75], v231 offset:512
	ds_read_b64_tr_b16 v[76:77], v231 offset:2048
	ds_read_b64_tr_b16 v[78:79], v231 offset:2560
	ds_read_b64_tr_b16 v[220:221], v231 offset:1024
	ds_read_b64_tr_b16 v[222:223], v231 offset:1536
	ds_read_b64_tr_b16 v[224:225], v231 offset:3072
	ds_read_b64_tr_b16 v[226:227], v231 offset:3584
	s_waitcnt vmcnt(8)
	ds_write_b128 v247, v[156:159]
	ds_write_b128 v247, v[160:163] offset:1024
	ds_write_b128 v111, v[164:167] offset:2048
	ds_write_b128 v111, v[168:171] offset:3072
	ds_read_b128 v[156:159], v248
	ds_read_b128 v[160:163], v249
	ds_read_b128 v[164:167], v250
	ds_read_b128 v[168:171], v251
	ds_write_b128 v112, v[172:175]
	ds_write_b128 v112, v[176:179] offset:1024
	ds_write_b128 v112, v[180:183] offset:2048
	ds_write_b128 v112, v[184:187] offset:3072
	v_mfma_f32_32x32x16_bf16 v[32:47], v[120:123], v[52:55], v[32:47]
	v_mfma_f32_32x32x16_bf16 v[32:47], v[124:127], v[56:59], v[32:47]
	v_mfma_f32_32x32x16_bf16 v[32:47], v[128:131], v[60:63], v[32:47]
	s_nop 11
	v_exp_f32_e32 v32, v32
	v_exp_f32_e32 v33, v33
	v_exp_f32_e32 v34, v34
	v_exp_f32_e32 v35, v35
	v_exp_f32_e32 v36, v36
	v_exp_f32_e32 v37, v37
	v_exp_f32_e32 v38, v38
	v_exp_f32_e32 v39, v39
	v_exp_f32_e32 v40, v40
	v_exp_f32_e32 v41, v41
	v_exp_f32_e32 v42, v42
	v_exp_f32_e32 v43, v43
	v_exp_f32_e32 v44, v44
	v_exp_f32_e32 v45, v45
	v_exp_f32_e32 v46, v46
	v_exp_f32_e32 v47, v47
	s_add_i32 s90, s76, 32
	v_add_u32_e32 v84, s90, v107
	v_add_u32_e32 v85, 0, v84
	v_add_u32_e32 v86, 1, v84
	v_add_u32_e32 v87, 2, v84
	v_add_u32_e32 v88, 3, v84
	v_cmp_gt_u32_e64 s[30:31], s98, v85
	v_cmp_gt_u32_e64 s[36:37], s98, v86
	v_cmp_gt_u32_e64 s[78:79], s98, v87
	v_cmp_gt_u32_e64 s[50:51], s98, v88
	v_cndmask_b32_e64 v32, 0, v32, s[30:31]
	v_add_u32_e32 v85, 8, v84
	v_cmp_gt_u32_e64 s[30:31], s98, v85
	v_cndmask_b32_e64 v33, 0, v33, s[36:37]
	v_add_u32_e32 v86, 9, v84
	v_cmp_gt_u32_e64 s[36:37], s98, v86
	v_cndmask_b32_e64 v34, 0, v34, s[78:79]
	v_add_u32_e32 v87, 10, v84
	v_cmp_gt_u32_e64 s[78:79], s98, v87
	v_cndmask_b32_e64 v35, 0, v35, s[50:51]
	v_add_u32_e32 v88, 11, v84
	v_cmp_gt_u32_e64 s[50:51], s98, v88
	v_cndmask_b32_e64 v36, 0, v36, s[30:31]
	v_add_u32_e32 v85, 16, v84
	v_cmp_gt_u32_e64 s[30:31], s98, v85
	v_cndmask_b32_e64 v37, 0, v37, s[36:37]
	v_add_u32_e32 v86, 17, v84
	v_cmp_gt_u32_e64 s[36:37], s98, v86
	v_cndmask_b32_e64 v38, 0, v38, s[78:79]
	v_add_u32_e32 v87, 18, v84
	v_cmp_gt_u32_e64 s[78:79], s98, v87
	v_cndmask_b32_e64 v39, 0, v39, s[50:51]
	v_add_u32_e32 v88, 19, v84
	v_cmp_gt_u32_e64 s[50:51], s98, v88
	v_cndmask_b32_e64 v40, 0, v40, s[30:31]
	v_add_u32_e32 v85, 24, v84
	v_cmp_gt_u32_e64 s[30:31], s98, v85
	v_cndmask_b32_e64 v41, 0, v41, s[36:37]
	v_add_u32_e32 v86, 25, v84
	v_cmp_gt_u32_e64 s[36:37], s98, v86
	v_cndmask_b32_e64 v42, 0, v42, s[78:79]
	v_add_u32_e32 v87, 26, v84
	v_cmp_gt_u32_e64 s[78:79], s98, v87
	v_cndmask_b32_e64 v43, 0, v43, s[50:51]
	v_add_u32_e32 v88, 27, v84
	v_cmp_gt_u32_e64 s[50:51], s98, v88
	v_nop
	v_cndmask_b32_e64 v44, 0, v44, s[30:31]
	v_cndmask_b32_e64 v45, 0, v45, s[36:37]
	v_cndmask_b32_e64 v46, 0, v46, s[78:79]
	v_cndmask_b32_e64 v47, 0, v47, s[50:51]
	v_cvt_pk_bf16_f32 v64, v32, v33
	v_cvt_pk_bf16_f32 v65, v34, v35
	v_cvt_pk_bf16_f32 v66, v36, v37
	v_cvt_pk_bf16_f32 v67, v38, v39
	v_cvt_pk_bf16_f32 v68, v40, v41
	v_cvt_pk_bf16_f32 v69, v42, v43
	v_cvt_pk_bf16_f32 v70, v44, v45
	v_cvt_pk_bf16_f32 v71, v46, v47
	v_pk_add_f32 v[232:233], v[232:233], v[32:33]
	v_pk_add_f32 v[232:233], v[232:233], v[34:35]
	v_pk_add_f32 v[232:233], v[232:233], v[36:37]
	v_pk_add_f32 v[232:233], v[232:233], v[38:39]
	v_pk_add_f32 v[232:233], v[232:233], v[40:41]
	v_pk_add_f32 v[232:233], v[232:233], v[42:43]
	v_pk_add_f32 v[232:233], v[232:233], v[44:45]
	v_pk_add_f32 v[232:233], v[232:233], v[46:47]
	ds_read2_b32 v[32:33], v115 offset0:136 offset1:137
	ds_read2_b32 v[34:35], v115 offset0:138 offset1:139
	ds_read2_b32 v[36:37], v115 offset0:144 offset1:145
	ds_read2_b32 v[38:39], v115 offset0:146 offset1:147
	ds_read2_b32 v[40:41], v115 offset0:153 offset1:154
	ds_read2_b32 v[42:43], v115 offset0:155 offset1:156
	ds_read2_b32 v[44:45], v115 offset0:161 offset1:162
	ds_read2_b32 v[46:47], v115 offset0:163 offset1:164
	s_waitcnt lgkmcnt(15)
	v_mfma_f32_32x32x16_bf16 v[0:15], v[64:67], v[72:75], v[0:15]
	v_mfma_f32_32x32x16_bf16 v[16:31], v[64:67], v[76:79], v[16:31]
	v_mfma_f32_32x32x16_bf16 v[0:15], v[68:71], v[220:223], v[0:15]
	v_mfma_f32_32x32x16_bf16 v[16:31], v[68:71], v[224:227], v[16:31]
	s_add_i32 s90, s76, 128
	v_add_u32_e32 v80, s90, v235
	v_add_u32_e32 v83, s90, v236
	v_add_u32_e32 v99, s90, v237
	v_add_u32_e32 v253, s90, v238
	v_add_u32_e32 v254, s90, v100
	v_add_u32_e32 v255, s90, v149
	v_med3_i32 v80, v80, 0, s99
	v_med3_i32 v83, v83, 0, s99
	v_med3_i32 v99, v99, 0, s99
	v_med3_i32 v253, v253, 0, s99
	v_med3_i32 v254, v254, 0, s99
	v_med3_i32 v255, v255, 0, s99
	v_mad_u32_u24 v80, v80, s100, v252
	v_mad_u32_u24 v83, v83, s100, v252
	v_mad_u32_u24 v99, v99, s100, v252
	v_mad_u32_u24 v253, v253, s100, v252
	v_mad_u32_u24 v254, v254, s100, v153
	v_mad_u32_u24 v255, v255, s100, v153
	global_load_dwordx4 v[116:119], v80, s[82:83]
	global_load_dwordx4 v[120:123], v83, s[82:83]
	global_load_dwordx4 v[124:127], v99, s[82:83]
	global_load_dwordx4 v[128:131], v253, s[82:83]
	global_load_dwordx4 v[132:135], v254, s[82:83] offset:768
	global_load_dwordx4 v[136:139], v255, s[82:83] offset:768
	global_load_dwordx4 v[140:143], v254, s[82:83] offset:832
	global_load_dwordx4 v[144:147], v255, s[82:83] offset:832
	s_waitcnt lgkmcnt(0)
	v_mfma_f32_32x32x16_bf16 v[32:47], v[156:159], v[48:51], v[32:47]
	ds_read_b64_tr_b16 v[72:73], v231
	ds_read_b64_tr_b16 v[74:75], v231 offset:512
	ds_read_b64_tr_b16 v[76:77], v231 offset:2048
	ds_read_b64_tr_b16 v[78:79], v231 offset:2560
	ds_read_b64_tr_b16 v[220:221], v231 offset:1024
	ds_read_b64_tr_b16 v[222:223], v231 offset:1536
	ds_read_b64_tr_b16 v[224:225], v231 offset:3072
	ds_read_b64_tr_b16 v[226:227], v231 offset:3584
	s_waitcnt vmcnt(8)
	ds_write_b128 v247, v[188:191]
	ds_write_b128 v247, v[192:195] offset:1024
	ds_write_b128 v111, v[196:199] offset:2048
	ds_write_b128 v111, v[200:203] offset:3072
	ds_read_b128 v[188:191], v248
	ds_read_b128 v[192:195], v249
	ds_read_b128 v[196:199], v250
	ds_read_b128 v[200:203], v251
	ds_write_b128 v112, v[204:207]
	ds_write_b128 v112, v[208:211] offset:1024
	ds_write_b128 v112, v[212:215] offset:2048
	ds_write_b128 v112, v[216:219] offset:3072
	v_mfma_f32_32x32x16_bf16 v[32:47], v[160:163], v[52:55], v[32:47]
	v_mfma_f32_32x32x16_bf16 v[32:47], v[164:167], v[56:59], v[32:47]
	v_mfma_f32_32x32x16_bf16 v[32:47], v[168:171], v[60:63], v[32:47]
	s_nop 11
	v_exp_f32_e32 v32, v32
	v_exp_f32_e32 v33, v33
	v_exp_f32_e32 v34, v34
	v_exp_f32_e32 v35, v35
	v_exp_f32_e32 v36, v36
	v_exp_f32_e32 v37, v37
	v_exp_f32_e32 v38, v38
	v_exp_f32_e32 v39, v39
	v_exp_f32_e32 v40, v40
	v_exp_f32_e32 v41, v41
	v_exp_f32_e32 v42, v42
	v_exp_f32_e32 v43, v43
	v_exp_f32_e32 v44, v44
	v_exp_f32_e32 v45, v45
	v_exp_f32_e32 v46, v46
	v_exp_f32_e32 v47, v47
	s_add_i32 s90, s76, 64
	v_add_u32_e32 v84, s90, v107
	v_add_u32_e32 v85, 0, v84
	v_add_u32_e32 v86, 1, v84
	v_add_u32_e32 v87, 2, v84
	v_add_u32_e32 v88, 3, v84
	v_cmp_gt_u32_e64 s[30:31], s98, v85
	v_cmp_gt_u32_e64 s[36:37], s98, v86
	v_cmp_gt_u32_e64 s[78:79], s98, v87
	v_cmp_gt_u32_e64 s[50:51], s98, v88
	v_cndmask_b32_e64 v32, 0, v32, s[30:31]
	v_add_u32_e32 v85, 8, v84
	v_cmp_gt_u32_e64 s[30:31], s98, v85
	v_cndmask_b32_e64 v33, 0, v33, s[36:37]
	v_add_u32_e32 v86, 9, v84
	v_cmp_gt_u32_e64 s[36:37], s98, v86
	v_cndmask_b32_e64 v34, 0, v34, s[78:79]
	v_add_u32_e32 v87, 10, v84
	v_cmp_gt_u32_e64 s[78:79], s98, v87
	v_cndmask_b32_e64 v35, 0, v35, s[50:51]
	v_add_u32_e32 v88, 11, v84
	v_cmp_gt_u32_e64 s[50:51], s98, v88
	v_cndmask_b32_e64 v36, 0, v36, s[30:31]
	v_add_u32_e32 v85, 16, v84
	v_cmp_gt_u32_e64 s[30:31], s98, v85
	v_cndmask_b32_e64 v37, 0, v37, s[36:37]
	v_add_u32_e32 v86, 17, v84
	v_cmp_gt_u32_e64 s[36:37], s98, v86
	v_cndmask_b32_e64 v38, 0, v38, s[78:79]
	v_add_u32_e32 v87, 18, v84
	v_cmp_gt_u32_e64 s[78:79], s98, v87
	v_cndmask_b32_e64 v39, 0, v39, s[50:51]
	v_add_u32_e32 v88, 19, v84
	v_cmp_gt_u32_e64 s[50:51], s98, v88
	v_cndmask_b32_e64 v40, 0, v40, s[30:31]
	v_add_u32_e32 v85, 24, v84
	v_cmp_gt_u32_e64 s[30:31], s98, v85
	v_cndmask_b32_e64 v41, 0, v41, s[36:37]
	v_add_u32_e32 v86, 25, v84
	v_cmp_gt_u32_e64 s[36:37], s98, v86
	v_cndmask_b32_e64 v42, 0, v42, s[78:79]
	v_add_u32_e32 v87, 26, v84
	v_cmp_gt_u32_e64 s[78:79], s98, v87
	v_cndmask_b32_e64 v43, 0, v43, s[50:51]
	v_add_u32_e32 v88, 27, v84
	v_cmp_gt_u32_e64 s[50:51], s98, v88
	v_nop
	v_cndmask_b32_e64 v44, 0, v44, s[30:31]
	v_cndmask_b32_e64 v45, 0, v45, s[36:37]
	v_cndmask_b32_e64 v46, 0, v46, s[78:79]
	v_cndmask_b32_e64 v47, 0, v47, s[50:51]
	v_cvt_pk_bf16_f32 v64, v32, v33
	v_cvt_pk_bf16_f32 v65, v34, v35
	v_cvt_pk_bf16_f32 v66, v36, v37
	v_cvt_pk_bf16_f32 v67, v38, v39
	v_cvt_pk_bf16_f32 v68, v40, v41
	v_cvt_pk_bf16_f32 v69, v42, v43
	v_cvt_pk_bf16_f32 v70, v44, v45
	v_cvt_pk_bf16_f32 v71, v46, v47
	v_pk_add_f32 v[232:233], v[232:233], v[32:33]
	v_pk_add_f32 v[232:233], v[232:233], v[34:35]
	v_pk_add_f32 v[232:233], v[232:233], v[36:37]
	v_pk_add_f32 v[232:233], v[232:233], v[38:39]
	v_pk_add_f32 v[232:233], v[232:233], v[40:41]
	v_pk_add_f32 v[232:233], v[232:233], v[42:43]
	v_pk_add_f32 v[232:233], v[232:233], v[44:45]
	v_pk_add_f32 v[232:233], v[232:233], v[46:47]
	ds_read2_b32 v[32:33], v115 offset0:170 offset1:171
	ds_read2_b32 v[34:35], v115 offset0:172 offset1:173
	ds_read2_b32 v[36:37], v115 offset0:178 offset1:179
	ds_read2_b32 v[38:39], v115 offset0:180 offset1:181
	ds_read2_b32 v[40:41], v115 offset0:187 offset1:188
	ds_read2_b32 v[42:43], v115 offset0:189 offset1:190
	ds_read2_b32 v[44:45], v115 offset0:195 offset1:196
	ds_read2_b32 v[46:47], v115 offset0:197 offset1:198
	s_waitcnt lgkmcnt(15)
	v_mfma_f32_32x32x16_bf16 v[0:15], v[64:67], v[72:75], v[0:15]
	v_mfma_f32_32x32x16_bf16 v[16:31], v[64:67], v[76:79], v[16:31]
	v_mfma_f32_32x32x16_bf16 v[0:15], v[68:71], v[220:223], v[0:15]
	v_mfma_f32_32x32x16_bf16 v[16:31], v[68:71], v[224:227], v[16:31]
	s_add_i32 s90, s76, 160
	v_add_u32_e32 v80, s90, v235
	v_add_u32_e32 v83, s90, v236
	v_add_u32_e32 v99, s90, v237
	v_add_u32_e32 v253, s90, v238
	v_add_u32_e32 v254, s90, v100
	v_add_u32_e32 v255, s90, v149
	v_med3_i32 v80, v80, 0, s99
	v_med3_i32 v83, v83, 0, s99
	v_med3_i32 v99, v99, 0, s99
	v_med3_i32 v253, v253, 0, s99
	v_med3_i32 v254, v254, 0, s99
	v_med3_i32 v255, v255, 0, s99
	v_mad_u32_u24 v80, v80, s100, v252
	v_mad_u32_u24 v83, v83, s100, v252
	v_mad_u32_u24 v99, v99, s100, v252
	v_mad_u32_u24 v253, v253, s100, v252
	v_mad_u32_u24 v254, v254, s100, v153
	v_mad_u32_u24 v255, v255, s100, v153
	global_load_dwordx4 v[156:159], v80, s[82:83]
	global_load_dwordx4 v[160:163], v83, s[82:83]
	global_load_dwordx4 v[164:167], v99, s[82:83]
	global_load_dwordx4 v[168:171], v253, s[82:83]
	global_load_dwordx4 v[172:175], v254, s[82:83] offset:768
	global_load_dwordx4 v[176:179], v255, s[82:83] offset:768
	global_load_dwordx4 v[180:183], v254, s[82:83] offset:832
	global_load_dwordx4 v[184:187], v255, s[82:83] offset:832
	s_waitcnt lgkmcnt(0)
	v_mfma_f32_32x32x16_bf16 v[32:47], v[188:191], v[48:51], v[32:47]
	ds_read_b64_tr_b16 v[72:73], v231
	ds_read_b64_tr_b16 v[74:75], v231 offset:512
	ds_read_b64_tr_b16 v[76:77], v231 offset:2048
	ds_read_b64_tr_b16 v[78:79], v231 offset:2560
	ds_read_b64_tr_b16 v[220:221], v231 offset:1024
	ds_read_b64_tr_b16 v[222:223], v231 offset:1536
	ds_read_b64_tr_b16 v[224:225], v231 offset:3072
	ds_read_b64_tr_b16 v[226:227], v231 offset:3584
	s_waitcnt vmcnt(8)
	ds_write_b128 v247, v[116:119]
	ds_write_b128 v247, v[120:123] offset:1024
	ds_write_b128 v111, v[124:127] offset:2048
	ds_write_b128 v111, v[128:131] offset:3072
	ds_read_b128 v[116:119], v248
	ds_read_b128 v[120:123], v249
	ds_read_b128 v[124:127], v250
	ds_read_b128 v[128:131], v251
	ds_write_b128 v112, v[132:135]
	ds_write_b128 v112, v[136:139] offset:1024
	ds_write_b128 v112, v[140:143] offset:2048
	ds_write_b128 v112, v[144:147] offset:3072
	v_mfma_f32_32x32x16_bf16 v[32:47], v[192:195], v[52:55], v[32:47]
	v_mfma_f32_32x32x16_bf16 v[32:47], v[196:199], v[56:59], v[32:47]
	v_mfma_f32_32x32x16_bf16 v[32:47], v[200:203], v[60:63], v[32:47]
	s_nop 11
	v_exp_f32_e32 v32, v32
	v_exp_f32_e32 v33, v33
	v_exp_f32_e32 v34, v34
	v_exp_f32_e32 v35, v35
	v_exp_f32_e32 v36, v36
	v_exp_f32_e32 v37, v37
	v_exp_f32_e32 v38, v38
	v_exp_f32_e32 v39, v39
	v_exp_f32_e32 v40, v40
	v_exp_f32_e32 v41, v41
	v_exp_f32_e32 v42, v42
	v_exp_f32_e32 v43, v43
	v_exp_f32_e32 v44, v44
	v_exp_f32_e32 v45, v45
	v_exp_f32_e32 v46, v46
	v_exp_f32_e32 v47, v47
	s_add_i32 s90, s76, 96
	v_add_u32_e32 v84, s90, v107
	v_add_u32_e32 v85, 0, v84
	v_add_u32_e32 v86, 1, v84
	v_add_u32_e32 v87, 2, v84
	v_add_u32_e32 v88, 3, v84
	v_cmp_gt_u32_e64 s[30:31], s98, v85
	v_cmp_gt_u32_e64 s[36:37], s98, v86
	v_cmp_gt_u32_e64 s[78:79], s98, v87
	v_cmp_gt_u32_e64 s[50:51], s98, v88
	v_cndmask_b32_e64 v32, 0, v32, s[30:31]
	v_add_u32_e32 v85, 8, v84
	v_cmp_gt_u32_e64 s[30:31], s98, v85
	v_cndmask_b32_e64 v33, 0, v33, s[36:37]
	v_add_u32_e32 v86, 9, v84
	v_cmp_gt_u32_e64 s[36:37], s98, v86
	v_cndmask_b32_e64 v34, 0, v34, s[78:79]
	v_add_u32_e32 v87, 10, v84
	v_cmp_gt_u32_e64 s[78:79], s98, v87
	v_cndmask_b32_e64 v35, 0, v35, s[50:51]
	v_add_u32_e32 v88, 11, v84
	v_cmp_gt_u32_e64 s[50:51], s98, v88
	v_cndmask_b32_e64 v36, 0, v36, s[30:31]
	v_add_u32_e32 v85, 16, v84
	v_cmp_gt_u32_e64 s[30:31], s98, v85
	v_cndmask_b32_e64 v37, 0, v37, s[36:37]
	v_add_u32_e32 v86, 17, v84
	v_cmp_gt_u32_e64 s[36:37], s98, v86
	v_cndmask_b32_e64 v38, 0, v38, s[78:79]
	v_add_u32_e32 v87, 18, v84
	v_cmp_gt_u32_e64 s[78:79], s98, v87
	v_cndmask_b32_e64 v39, 0, v39, s[50:51]
	v_add_u32_e32 v88, 19, v84
	v_cmp_gt_u32_e64 s[50:51], s98, v88
	v_cndmask_b32_e64 v40, 0, v40, s[30:31]
	v_add_u32_e32 v85, 24, v84
	v_cmp_gt_u32_e64 s[30:31], s98, v85
	v_cndmask_b32_e64 v41, 0, v41, s[36:37]
	v_add_u32_e32 v86, 25, v84
	v_cmp_gt_u32_e64 s[36:37], s98, v86
	v_cndmask_b32_e64 v42, 0, v42, s[78:79]
	v_add_u32_e32 v87, 26, v84
	v_cmp_gt_u32_e64 s[78:79], s98, v87
	v_cndmask_b32_e64 v43, 0, v43, s[50:51]
	v_add_u32_e32 v88, 27, v84
	v_cmp_gt_u32_e64 s[50:51], s98, v88
	v_nop
	v_cndmask_b32_e64 v44, 0, v44, s[30:31]
	v_cndmask_b32_e64 v45, 0, v45, s[36:37]
	v_cndmask_b32_e64 v46, 0, v46, s[78:79]
	v_cndmask_b32_e64 v47, 0, v47, s[50:51]
	v_cvt_pk_bf16_f32 v64, v32, v33
	v_cvt_pk_bf16_f32 v65, v34, v35
	v_cvt_pk_bf16_f32 v66, v36, v37
	v_cvt_pk_bf16_f32 v67, v38, v39
	v_cvt_pk_bf16_f32 v68, v40, v41
	v_cvt_pk_bf16_f32 v69, v42, v43
	v_cvt_pk_bf16_f32 v70, v44, v45
	v_cvt_pk_bf16_f32 v71, v46, v47
	v_pk_add_f32 v[232:233], v[232:233], v[32:33]
	v_pk_add_f32 v[232:233], v[232:233], v[34:35]
	v_pk_add_f32 v[232:233], v[232:233], v[36:37]
	v_pk_add_f32 v[232:233], v[232:233], v[38:39]
	v_pk_add_f32 v[232:233], v[232:233], v[40:41]
	v_pk_add_f32 v[232:233], v[232:233], v[42:43]
	v_pk_add_f32 v[232:233], v[232:233], v[44:45]
	v_pk_add_f32 v[232:233], v[232:233], v[46:47]
	ds_read2_b32 v[32:33], v115 offset0:204 offset1:205
	ds_read2_b32 v[34:35], v115 offset0:206 offset1:207
	ds_read2_b32 v[36:37], v115 offset0:212 offset1:213
	ds_read2_b32 v[38:39], v115 offset0:214 offset1:215
	ds_read2_b32 v[40:41], v115 offset0:221 offset1:222
	ds_read2_b32 v[42:43], v115 offset0:223 offset1:224
	ds_read2_b32 v[44:45], v115 offset0:229 offset1:230
	ds_read2_b32 v[46:47], v115 offset0:231 offset1:232
	s_waitcnt lgkmcnt(15)
	v_mfma_f32_32x32x16_bf16 v[0:15], v[64:67], v[72:75], v[0:15]
	v_mfma_f32_32x32x16_bf16 v[16:31], v[64:67], v[76:79], v[16:31]
	v_mfma_f32_32x32x16_bf16 v[0:15], v[68:71], v[220:223], v[0:15]
	v_mfma_f32_32x32x16_bf16 v[16:31], v[68:71], v[224:227], v[16:31]
	s_add_i32 s90, s76, 192
	v_add_u32_e32 v80, s90, v235
	v_add_u32_e32 v83, s90, v236
	v_add_u32_e32 v99, s90, v237
	v_add_u32_e32 v253, s90, v238
	v_add_u32_e32 v254, s90, v100
	v_add_u32_e32 v255, s90, v149
	v_med3_i32 v80, v80, 0, s99
	v_med3_i32 v83, v83, 0, s99
	v_med3_i32 v99, v99, 0, s99
	v_med3_i32 v253, v253, 0, s99
	v_med3_i32 v254, v254, 0, s99
	v_med3_i32 v255, v255, 0, s99
	v_mad_u32_u24 v80, v80, s100, v252
	v_mad_u32_u24 v83, v83, s100, v252
	v_mad_u32_u24 v99, v99, s100, v252
	v_mad_u32_u24 v253, v253, s100, v252
	v_mad_u32_u24 v254, v254, s100, v153
	v_mad_u32_u24 v255, v255, s100, v153
	global_load_dwordx4 v[188:191], v80, s[82:83]
	global_load_dwordx4 v[192:195], v83, s[82:83]
	global_load_dwordx4 v[196:199], v99, s[82:83]
	global_load_dwordx4 v[200:203], v253, s[82:83]
	global_load_dwordx4 v[204:207], v254, s[82:83] offset:768
	global_load_dwordx4 v[208:211], v255, s[82:83] offset:768
	global_load_dwordx4 v[212:215], v254, s[82:83] offset:832
	global_load_dwordx4 v[216:219], v255, s[82:83] offset:832
	s_waitcnt lgkmcnt(0)
	v_mfma_f32_32x32x16_bf16 v[32:47], v[116:119], v[48:51], v[32:47]
	ds_read_b64_tr_b16 v[72:73], v231
	ds_read_b64_tr_b16 v[74:75], v231 offset:512
	ds_read_b64_tr_b16 v[76:77], v231 offset:2048
	ds_read_b64_tr_b16 v[78:79], v231 offset:2560
	ds_read_b64_tr_b16 v[220:221], v231 offset:1024
	ds_read_b64_tr_b16 v[222:223], v231 offset:1536
	ds_read_b64_tr_b16 v[224:225], v231 offset:3072
	ds_read_b64_tr_b16 v[226:227], v231 offset:3584
	s_waitcnt vmcnt(8)
	ds_write_b128 v247, v[156:159]
	ds_write_b128 v247, v[160:163] offset:1024
	ds_write_b128 v111, v[164:167] offset:2048
	ds_write_b128 v111, v[168:171] offset:3072
	ds_read_b128 v[156:159], v248
	ds_read_b128 v[160:163], v249
	ds_read_b128 v[164:167], v250
	ds_read_b128 v[168:171], v251
	ds_write_b128 v112, v[172:175]
	ds_write_b128 v112, v[176:179] offset:1024
	ds_write_b128 v112, v[180:183] offset:2048
	ds_write_b128 v112, v[184:187] offset:3072
	v_mfma_f32_32x32x16_bf16 v[32:47], v[120:123], v[52:55], v[32:47]
	v_mfma_f32_32x32x16_bf16 v[32:47], v[124:127], v[56:59], v[32:47]
	v_mfma_f32_32x32x16_bf16 v[32:47], v[128:131], v[60:63], v[32:47]
	s_nop 11
	v_exp_f32_e32 v32, v32
	v_exp_f32_e32 v33, v33
	v_exp_f32_e32 v34, v34
	v_exp_f32_e32 v35, v35
	v_exp_f32_e32 v36, v36
	v_exp_f32_e32 v37, v37
	v_exp_f32_e32 v38, v38
	v_exp_f32_e32 v39, v39
	v_exp_f32_e32 v40, v40
	v_exp_f32_e32 v41, v41
	v_exp_f32_e32 v42, v42
	v_exp_f32_e32 v43, v43
	v_exp_f32_e32 v44, v44
	v_exp_f32_e32 v45, v45
	v_exp_f32_e32 v46, v46
	v_exp_f32_e32 v47, v47
	s_add_i32 s90, s76, 128
	v_add_u32_e32 v84, s90, v107
	v_add_u32_e32 v85, 0, v84
	v_add_u32_e32 v86, 1, v84
	v_add_u32_e32 v87, 2, v84
	v_add_u32_e32 v88, 3, v84
	v_cmp_gt_u32_e64 s[30:31], s98, v85
	v_cmp_gt_u32_e64 s[36:37], s98, v86
	v_cmp_gt_u32_e64 s[78:79], s98, v87
	v_cmp_gt_u32_e64 s[50:51], s98, v88
	v_cndmask_b32_e64 v32, 0, v32, s[30:31]
	v_add_u32_e32 v85, 8, v84
	v_cmp_gt_u32_e64 s[30:31], s98, v85
	v_cndmask_b32_e64 v33, 0, v33, s[36:37]
	v_add_u32_e32 v86, 9, v84
	v_cmp_gt_u32_e64 s[36:37], s98, v86
	v_cndmask_b32_e64 v34, 0, v34, s[78:79]
	v_add_u32_e32 v87, 10, v84
	v_cmp_gt_u32_e64 s[78:79], s98, v87
	v_cndmask_b32_e64 v35, 0, v35, s[50:51]
	v_add_u32_e32 v88, 11, v84
	v_cmp_gt_u32_e64 s[50:51], s98, v88
	v_cndmask_b32_e64 v36, 0, v36, s[30:31]
	v_add_u32_e32 v85, 16, v84
	v_cmp_gt_u32_e64 s[30:31], s98, v85
	v_cndmask_b32_e64 v37, 0, v37, s[36:37]
	v_add_u32_e32 v86, 17, v84
	v_cmp_gt_u32_e64 s[36:37], s98, v86
	v_cndmask_b32_e64 v38, 0, v38, s[78:79]
	v_add_u32_e32 v87, 18, v84
	v_cmp_gt_u32_e64 s[78:79], s98, v87
	v_cndmask_b32_e64 v39, 0, v39, s[50:51]
	v_add_u32_e32 v88, 19, v84
	v_cmp_gt_u32_e64 s[50:51], s98, v88
	v_cndmask_b32_e64 v40, 0, v40, s[30:31]
	v_add_u32_e32 v85, 24, v84
	v_cmp_gt_u32_e64 s[30:31], s98, v85
	v_cndmask_b32_e64 v41, 0, v41, s[36:37]
	v_add_u32_e32 v86, 25, v84
	v_cmp_gt_u32_e64 s[36:37], s98, v86
	v_cndmask_b32_e64 v42, 0, v42, s[78:79]
	v_add_u32_e32 v87, 26, v84
	v_cmp_gt_u32_e64 s[78:79], s98, v87
	v_cndmask_b32_e64 v43, 0, v43, s[50:51]
	v_add_u32_e32 v88, 27, v84
	v_cmp_gt_u32_e64 s[50:51], s98, v88
	v_nop
	v_cndmask_b32_e64 v44, 0, v44, s[30:31]
	v_cndmask_b32_e64 v45, 0, v45, s[36:37]
	v_cndmask_b32_e64 v46, 0, v46, s[78:79]
	v_cndmask_b32_e64 v47, 0, v47, s[50:51]
	v_cvt_pk_bf16_f32 v64, v32, v33
	v_cvt_pk_bf16_f32 v65, v34, v35
	v_cvt_pk_bf16_f32 v66, v36, v37
	v_cvt_pk_bf16_f32 v67, v38, v39
	v_cvt_pk_bf16_f32 v68, v40, v41
	v_cvt_pk_bf16_f32 v69, v42, v43
	v_cvt_pk_bf16_f32 v70, v44, v45
	v_cvt_pk_bf16_f32 v71, v46, v47
	v_pk_add_f32 v[232:233], v[232:233], v[32:33]
	v_pk_add_f32 v[232:233], v[232:233], v[34:35]
	v_pk_add_f32 v[232:233], v[232:233], v[36:37]
	v_pk_add_f32 v[232:233], v[232:233], v[38:39]
	v_pk_add_f32 v[232:233], v[232:233], v[40:41]
	v_pk_add_f32 v[232:233], v[232:233], v[42:43]
	v_pk_add_f32 v[232:233], v[232:233], v[44:45]
	v_pk_add_f32 v[232:233], v[232:233], v[46:47]
	v_add_u32_e32 v115, 952, v115
	ds_read2_b32 v[32:33], v115 offset0:0 offset1:1
	ds_read2_b32 v[34:35], v115 offset0:2 offset1:3
	ds_read2_b32 v[36:37], v115 offset0:8 offset1:9
	ds_read2_b32 v[38:39], v115 offset0:10 offset1:11
	ds_read2_b32 v[40:41], v115 offset0:17 offset1:18
	ds_read2_b32 v[42:43], v115 offset0:19 offset1:20
	ds_read2_b32 v[44:45], v115 offset0:25 offset1:26
	ds_read2_b32 v[46:47], v115 offset0:27 offset1:28
	s_waitcnt lgkmcnt(15)
	v_mfma_f32_32x32x16_bf16 v[0:15], v[64:67], v[72:75], v[0:15]
	v_mfma_f32_32x32x16_bf16 v[16:31], v[64:67], v[76:79], v[16:31]
	v_mfma_f32_32x32x16_bf16 v[0:15], v[68:71], v[220:223], v[0:15]
	v_mfma_f32_32x32x16_bf16 v[16:31], v[68:71], v[224:227], v[16:31]
	s_add_i32 s90, s76, 224
	v_add_u32_e32 v80, s90, v235
	v_add_u32_e32 v83, s90, v236
	v_add_u32_e32 v99, s90, v237
	v_add_u32_e32 v253, s90, v238
	v_add_u32_e32 v254, s90, v100
	v_add_u32_e32 v255, s90, v149
	v_med3_i32 v80, v80, 0, s99
	v_med3_i32 v83, v83, 0, s99
	v_med3_i32 v99, v99, 0, s99
	v_med3_i32 v253, v253, 0, s99
	v_med3_i32 v254, v254, 0, s99
	v_med3_i32 v255, v255, 0, s99
	v_mad_u32_u24 v80, v80, s100, v252
	v_mad_u32_u24 v83, v83, s100, v252
	v_mad_u32_u24 v99, v99, s100, v252
	v_mad_u32_u24 v253, v253, s100, v252
	v_mad_u32_u24 v254, v254, s100, v153
	v_mad_u32_u24 v255, v255, s100, v153
	global_load_dwordx4 v[116:119], v80, s[82:83]
	global_load_dwordx4 v[120:123], v83, s[82:83]
	global_load_dwordx4 v[124:127], v99, s[82:83]
	global_load_dwordx4 v[128:131], v253, s[82:83]
	global_load_dwordx4 v[132:135], v254, s[82:83] offset:768
	global_load_dwordx4 v[136:139], v255, s[82:83] offset:768
	global_load_dwordx4 v[140:143], v254, s[82:83] offset:832
	global_load_dwordx4 v[144:147], v255, s[82:83] offset:832
	s_waitcnt lgkmcnt(0)
	v_mfma_f32_32x32x16_bf16 v[32:47], v[156:159], v[48:51], v[32:47]
	ds_read_b64_tr_b16 v[72:73], v231
	ds_read_b64_tr_b16 v[74:75], v231 offset:512
	ds_read_b64_tr_b16 v[76:77], v231 offset:2048
	ds_read_b64_tr_b16 v[78:79], v231 offset:2560
	ds_read_b64_tr_b16 v[220:221], v231 offset:1024
	ds_read_b64_tr_b16 v[222:223], v231 offset:1536
	ds_read_b64_tr_b16 v[224:225], v231 offset:3072
	ds_read_b64_tr_b16 v[226:227], v231 offset:3584
	s_waitcnt vmcnt(8)
	ds_write_b128 v247, v[188:191]
	ds_write_b128 v247, v[192:195] offset:1024
	ds_write_b128 v111, v[196:199] offset:2048
	ds_write_b128 v111, v[200:203] offset:3072
	ds_read_b128 v[188:191], v248
	ds_read_b128 v[192:195], v249
	ds_read_b128 v[196:199], v250
	ds_read_b128 v[200:203], v251
	ds_write_b128 v112, v[204:207]
	ds_write_b128 v112, v[208:211] offset:1024
	ds_write_b128 v112, v[212:215] offset:2048
	ds_write_b128 v112, v[216:219] offset:3072
	v_mfma_f32_32x32x16_bf16 v[32:47], v[160:163], v[52:55], v[32:47]
	v_mfma_f32_32x32x16_bf16 v[32:47], v[164:167], v[56:59], v[32:47]
	v_mfma_f32_32x32x16_bf16 v[32:47], v[168:171], v[60:63], v[32:47]
	s_nop 11
	v_exp_f32_e32 v32, v32
	v_exp_f32_e32 v33, v33
	v_exp_f32_e32 v34, v34
	v_exp_f32_e32 v35, v35
	v_exp_f32_e32 v36, v36
	v_exp_f32_e32 v37, v37
	v_exp_f32_e32 v38, v38
	v_exp_f32_e32 v39, v39
	v_exp_f32_e32 v40, v40
	v_exp_f32_e32 v41, v41
	v_exp_f32_e32 v42, v42
	v_exp_f32_e32 v43, v43
	v_exp_f32_e32 v44, v44
	v_exp_f32_e32 v45, v45
	v_exp_f32_e32 v46, v46
	v_exp_f32_e32 v47, v47
	s_add_i32 s90, s76, 160
	v_add_u32_e32 v84, s90, v107
	v_add_u32_e32 v85, 0, v84
	v_add_u32_e32 v86, 1, v84
	v_add_u32_e32 v87, 2, v84
	v_add_u32_e32 v88, 3, v84
	v_cmp_gt_u32_e64 s[30:31], s98, v85
	v_cmp_gt_u32_e64 s[36:37], s98, v86
	v_cmp_gt_u32_e64 s[78:79], s98, v87
	v_cmp_gt_u32_e64 s[50:51], s98, v88
	v_cndmask_b32_e64 v32, 0, v32, s[30:31]
	v_add_u32_e32 v85, 8, v84
	v_cmp_gt_u32_e64 s[30:31], s98, v85
	v_cndmask_b32_e64 v33, 0, v33, s[36:37]
	v_add_u32_e32 v86, 9, v84
	v_cmp_gt_u32_e64 s[36:37], s98, v86
	v_cndmask_b32_e64 v34, 0, v34, s[78:79]
	v_add_u32_e32 v87, 10, v84
	v_cmp_gt_u32_e64 s[78:79], s98, v87
	v_cndmask_b32_e64 v35, 0, v35, s[50:51]
	v_add_u32_e32 v88, 11, v84
	v_cmp_gt_u32_e64 s[50:51], s98, v88
	v_cndmask_b32_e64 v36, 0, v36, s[30:31]
	v_add_u32_e32 v85, 16, v84
	v_cmp_gt_u32_e64 s[30:31], s98, v85
	v_cndmask_b32_e64 v37, 0, v37, s[36:37]
	v_add_u32_e32 v86, 17, v84
	v_cmp_gt_u32_e64 s[36:37], s98, v86
	v_cndmask_b32_e64 v38, 0, v38, s[78:79]
	v_add_u32_e32 v87, 18, v84
	v_cmp_gt_u32_e64 s[78:79], s98, v87
	v_cndmask_b32_e64 v39, 0, v39, s[50:51]
	v_add_u32_e32 v88, 19, v84
	v_cmp_gt_u32_e64 s[50:51], s98, v88
	v_cndmask_b32_e64 v40, 0, v40, s[30:31]
	v_add_u32_e32 v85, 24, v84
	v_cmp_gt_u32_e64 s[30:31], s98, v85
	v_cndmask_b32_e64 v41, 0, v41, s[36:37]
	v_add_u32_e32 v86, 25, v84
	v_cmp_gt_u32_e64 s[36:37], s98, v86
	v_cndmask_b32_e64 v42, 0, v42, s[78:79]
	v_add_u32_e32 v87, 26, v84
	v_cmp_gt_u32_e64 s[78:79], s98, v87
	v_cndmask_b32_e64 v43, 0, v43, s[50:51]
	v_add_u32_e32 v88, 27, v84
	v_cmp_gt_u32_e64 s[50:51], s98, v88
	v_nop
	v_cndmask_b32_e64 v44, 0, v44, s[30:31]
	v_cndmask_b32_e64 v45, 0, v45, s[36:37]
	v_cndmask_b32_e64 v46, 0, v46, s[78:79]
	v_cndmask_b32_e64 v47, 0, v47, s[50:51]
	v_cvt_pk_bf16_f32 v64, v32, v33
	v_cvt_pk_bf16_f32 v65, v34, v35
	v_cvt_pk_bf16_f32 v66, v36, v37
	v_cvt_pk_bf16_f32 v67, v38, v39
	v_cvt_pk_bf16_f32 v68, v40, v41
	v_cvt_pk_bf16_f32 v69, v42, v43
	v_cvt_pk_bf16_f32 v70, v44, v45
	v_cvt_pk_bf16_f32 v71, v46, v47
	v_pk_add_f32 v[232:233], v[232:233], v[32:33]
	v_pk_add_f32 v[232:233], v[232:233], v[34:35]
	v_pk_add_f32 v[232:233], v[232:233], v[36:37]
	v_pk_add_f32 v[232:233], v[232:233], v[38:39]
	v_pk_add_f32 v[232:233], v[232:233], v[40:41]
	v_pk_add_f32 v[232:233], v[232:233], v[42:43]
	v_pk_add_f32 v[232:233], v[232:233], v[44:45]
	v_pk_add_f32 v[232:233], v[232:233], v[46:47]
	ds_read2_b32 v[32:33], v115 offset0:34 offset1:35
	ds_read2_b32 v[34:35], v115 offset0:36 offset1:37
	ds_read2_b32 v[36:37], v115 offset0:42 offset1:43
	ds_read2_b32 v[38:39], v115 offset0:44 offset1:45
	ds_read2_b32 v[40:41], v115 offset0:51 offset1:52
	ds_read2_b32 v[42:43], v115 offset0:53 offset1:54
	ds_read2_b32 v[44:45], v115 offset0:59 offset1:60
	ds_read2_b32 v[46:47], v115 offset0:61 offset1:62
	s_waitcnt lgkmcnt(15)
	v_mfma_f32_32x32x16_bf16 v[0:15], v[64:67], v[72:75], v[0:15]
	v_mfma_f32_32x32x16_bf16 v[16:31], v[64:67], v[76:79], v[16:31]
	v_mfma_f32_32x32x16_bf16 v[0:15], v[68:71], v[220:223], v[0:15]
	v_mfma_f32_32x32x16_bf16 v[16:31], v[68:71], v[224:227], v[16:31]
	s_add_i32 s90, s76, 256
	v_add_u32_e32 v80, s90, v235
	v_add_u32_e32 v83, s90, v236
	v_add_u32_e32 v99, s90, v237
	v_add_u32_e32 v253, s90, v238
	v_add_u32_e32 v254, s90, v100
	v_add_u32_e32 v255, s90, v149
	v_med3_i32 v80, v80, 0, s99
	v_med3_i32 v83, v83, 0, s99
	v_med3_i32 v99, v99, 0, s99
	v_med3_i32 v253, v253, 0, s99
	v_med3_i32 v254, v254, 0, s99
	v_med3_i32 v255, v255, 0, s99
	v_mad_u32_u24 v80, v80, s100, v252
	v_mad_u32_u24 v83, v83, s100, v252
	v_mad_u32_u24 v99, v99, s100, v252
	v_mad_u32_u24 v253, v253, s100, v252
	v_mad_u32_u24 v254, v254, s100, v153
	v_mad_u32_u24 v255, v255, s100, v153
	global_load_dwordx4 v[156:159], v80, s[82:83]
	global_load_dwordx4 v[160:163], v83, s[82:83]
	global_load_dwordx4 v[164:167], v99, s[82:83]
	global_load_dwordx4 v[168:171], v253, s[82:83]
	global_load_dwordx4 v[172:175], v254, s[82:83] offset:768
	global_load_dwordx4 v[176:179], v255, s[82:83] offset:768
	global_load_dwordx4 v[180:183], v254, s[82:83] offset:832
	global_load_dwordx4 v[184:187], v255, s[82:83] offset:832
	s_waitcnt lgkmcnt(0)
	v_mfma_f32_32x32x16_bf16 v[32:47], v[188:191], v[48:51], v[32:47]
	ds_read_b64_tr_b16 v[72:73], v231
	ds_read_b64_tr_b16 v[74:75], v231 offset:512
	ds_read_b64_tr_b16 v[76:77], v231 offset:2048
	ds_read_b64_tr_b16 v[78:79], v231 offset:2560
	ds_read_b64_tr_b16 v[220:221], v231 offset:1024
	ds_read_b64_tr_b16 v[222:223], v231 offset:1536
	ds_read_b64_tr_b16 v[224:225], v231 offset:3072
	ds_read_b64_tr_b16 v[226:227], v231 offset:3584
	s_waitcnt vmcnt(8)
	ds_write_b128 v247, v[116:119]
	ds_write_b128 v247, v[120:123] offset:1024
	ds_write_b128 v111, v[124:127] offset:2048
	ds_write_b128 v111, v[128:131] offset:3072
	ds_read_b128 v[116:119], v248
	ds_read_b128 v[120:123], v249
	ds_read_b128 v[124:127], v250
	ds_read_b128 v[128:131], v251
	ds_write_b128 v112, v[132:135]
	ds_write_b128 v112, v[136:139] offset:1024
	ds_write_b128 v112, v[140:143] offset:2048
	ds_write_b128 v112, v[144:147] offset:3072
	v_mfma_f32_32x32x16_bf16 v[32:47], v[192:195], v[52:55], v[32:47]
	v_mfma_f32_32x32x16_bf16 v[32:47], v[196:199], v[56:59], v[32:47]
	v_mfma_f32_32x32x16_bf16 v[32:47], v[200:203], v[60:63], v[32:47]
	s_nop 11
	v_exp_f32_e32 v32, v32
	v_exp_f32_e32 v33, v33
	v_exp_f32_e32 v34, v34
	v_exp_f32_e32 v35, v35
	v_exp_f32_e32 v36, v36
	v_exp_f32_e32 v37, v37
	v_exp_f32_e32 v38, v38
	v_exp_f32_e32 v39, v39
	v_exp_f32_e32 v40, v40
	v_exp_f32_e32 v41, v41
	v_exp_f32_e32 v42, v42
	v_exp_f32_e32 v43, v43
	v_exp_f32_e32 v44, v44
	v_exp_f32_e32 v45, v45
	v_exp_f32_e32 v46, v46
	v_exp_f32_e32 v47, v47
	s_add_i32 s90, s76, 192
	v_add_u32_e32 v84, s90, v107
	v_add_u32_e32 v85, 0, v84
	v_add_u32_e32 v86, 1, v84
	v_add_u32_e32 v87, 2, v84
	v_add_u32_e32 v88, 3, v84
	v_cmp_gt_u32_e64 s[30:31], s98, v85
	v_cmp_gt_u32_e64 s[36:37], s98, v86
	v_cmp_gt_u32_e64 s[78:79], s98, v87
	v_cmp_gt_u32_e64 s[50:51], s98, v88
	v_cndmask_b32_e64 v32, 0, v32, s[30:31]
	v_add_u32_e32 v85, 8, v84
	v_cmp_gt_u32_e64 s[30:31], s98, v85
	v_cndmask_b32_e64 v33, 0, v33, s[36:37]
	v_add_u32_e32 v86, 9, v84
	v_cmp_gt_u32_e64 s[36:37], s98, v86
	v_cndmask_b32_e64 v34, 0, v34, s[78:79]
	v_add_u32_e32 v87, 10, v84
	v_cmp_gt_u32_e64 s[78:79], s98, v87
	v_cndmask_b32_e64 v35, 0, v35, s[50:51]
	v_add_u32_e32 v88, 11, v84
	v_cmp_gt_u32_e64 s[50:51], s98, v88
	v_cndmask_b32_e64 v36, 0, v36, s[30:31]
	v_add_u32_e32 v85, 16, v84
	v_cmp_gt_u32_e64 s[30:31], s98, v85
	v_cndmask_b32_e64 v37, 0, v37, s[36:37]
	v_add_u32_e32 v86, 17, v84
	v_cmp_gt_u32_e64 s[36:37], s98, v86
	v_cndmask_b32_e64 v38, 0, v38, s[78:79]
	v_add_u32_e32 v87, 18, v84
	v_cmp_gt_u32_e64 s[78:79], s98, v87
	v_cndmask_b32_e64 v39, 0, v39, s[50:51]
	v_add_u32_e32 v88, 19, v84
	v_cmp_gt_u32_e64 s[50:51], s98, v88
	v_cndmask_b32_e64 v40, 0, v40, s[30:31]
	v_add_u32_e32 v85, 24, v84
	v_cmp_gt_u32_e64 s[30:31], s98, v85
	v_cndmask_b32_e64 v41, 0, v41, s[36:37]
	v_add_u32_e32 v86, 25, v84
	v_cmp_gt_u32_e64 s[36:37], s98, v86
	v_cndmask_b32_e64 v42, 0, v42, s[78:79]
	v_add_u32_e32 v87, 26, v84
	v_cmp_gt_u32_e64 s[78:79], s98, v87
	v_cndmask_b32_e64 v43, 0, v43, s[50:51]
	v_add_u32_e32 v88, 27, v84
	v_cmp_gt_u32_e64 s[50:51], s98, v88
	v_nop
	v_cndmask_b32_e64 v44, 0, v44, s[30:31]
	v_cndmask_b32_e64 v45, 0, v45, s[36:37]
	v_cndmask_b32_e64 v46, 0, v46, s[78:79]
	v_cndmask_b32_e64 v47, 0, v47, s[50:51]
	v_cvt_pk_bf16_f32 v64, v32, v33
	v_cvt_pk_bf16_f32 v65, v34, v35
	v_cvt_pk_bf16_f32 v66, v36, v37
	v_cvt_pk_bf16_f32 v67, v38, v39
	v_cvt_pk_bf16_f32 v68, v40, v41
	v_cvt_pk_bf16_f32 v69, v42, v43
	v_cvt_pk_bf16_f32 v70, v44, v45
	v_cvt_pk_bf16_f32 v71, v46, v47
	v_pk_add_f32 v[232:233], v[232:233], v[32:33]
	v_pk_add_f32 v[232:233], v[232:233], v[34:35]
	v_pk_add_f32 v[232:233], v[232:233], v[36:37]
	v_pk_add_f32 v[232:233], v[232:233], v[38:39]
	v_pk_add_f32 v[232:233], v[232:233], v[40:41]
	v_pk_add_f32 v[232:233], v[232:233], v[42:43]
	v_pk_add_f32 v[232:233], v[232:233], v[44:45]
	v_pk_add_f32 v[232:233], v[232:233], v[46:47]
	ds_read2_b32 v[32:33], v115 offset0:68 offset1:69
	ds_read2_b32 v[34:35], v115 offset0:70 offset1:71
	ds_read2_b32 v[36:37], v115 offset0:76 offset1:77
	ds_read2_b32 v[38:39], v115 offset0:78 offset1:79
	ds_read2_b32 v[40:41], v115 offset0:85 offset1:86
	ds_read2_b32 v[42:43], v115 offset0:87 offset1:88
	ds_read2_b32 v[44:45], v115 offset0:93 offset1:94
	ds_read2_b32 v[46:47], v115 offset0:95 offset1:96
	s_waitcnt lgkmcnt(15)
	v_mfma_f32_32x32x16_bf16 v[0:15], v[64:67], v[72:75], v[0:15]
	v_mfma_f32_32x32x16_bf16 v[16:31], v[64:67], v[76:79], v[16:31]
	v_mfma_f32_32x32x16_bf16 v[0:15], v[68:71], v[220:223], v[0:15]
	v_mfma_f32_32x32x16_bf16 v[16:31], v[68:71], v[224:227], v[16:31]
	s_add_i32 s90, s76, 288
	v_add_u32_e32 v80, s90, v235
	v_add_u32_e32 v83, s90, v236
	v_add_u32_e32 v99, s90, v237
	v_add_u32_e32 v253, s90, v238
	v_add_u32_e32 v254, s90, v100
	v_add_u32_e32 v255, s90, v149
	v_med3_i32 v80, v80, 0, s99
	v_med3_i32 v83, v83, 0, s99
	v_med3_i32 v99, v99, 0, s99
	v_med3_i32 v253, v253, 0, s99
	v_med3_i32 v254, v254, 0, s99
	v_med3_i32 v255, v255, 0, s99
	v_mad_u32_u24 v80, v80, s100, v252
	v_mad_u32_u24 v83, v83, s100, v252
	v_mad_u32_u24 v99, v99, s100, v252
	v_mad_u32_u24 v253, v253, s100, v252
	v_mad_u32_u24 v254, v254, s100, v153
	v_mad_u32_u24 v255, v255, s100, v153
	global_load_dwordx4 v[188:191], v80, s[82:83]
	global_load_dwordx4 v[192:195], v83, s[82:83]
	global_load_dwordx4 v[196:199], v99, s[82:83]
	global_load_dwordx4 v[200:203], v253, s[82:83]
	global_load_dwordx4 v[204:207], v254, s[82:83] offset:768
	global_load_dwordx4 v[208:211], v255, s[82:83] offset:768
	global_load_dwordx4 v[212:215], v254, s[82:83] offset:832
	global_load_dwordx4 v[216:219], v255, s[82:83] offset:832
	s_waitcnt lgkmcnt(0)
	v_mfma_f32_32x32x16_bf16 v[32:47], v[116:119], v[48:51], v[32:47]
	ds_read_b64_tr_b16 v[72:73], v231
	ds_read_b64_tr_b16 v[74:75], v231 offset:512
	ds_read_b64_tr_b16 v[76:77], v231 offset:2048
	ds_read_b64_tr_b16 v[78:79], v231 offset:2560
	ds_read_b64_tr_b16 v[220:221], v231 offset:1024
	ds_read_b64_tr_b16 v[222:223], v231 offset:1536
	ds_read_b64_tr_b16 v[224:225], v231 offset:3072
	ds_read_b64_tr_b16 v[226:227], v231 offset:3584
	s_waitcnt vmcnt(8)
	ds_write_b128 v247, v[156:159]
	ds_write_b128 v247, v[160:163] offset:1024
	ds_write_b128 v111, v[164:167] offset:2048
	ds_write_b128 v111, v[168:171] offset:3072
	ds_read_b128 v[156:159], v248
	ds_read_b128 v[160:163], v249
	ds_read_b128 v[164:167], v250
	ds_read_b128 v[168:171], v251
	ds_write_b128 v112, v[172:175]
	ds_write_b128 v112, v[176:179] offset:1024
	ds_write_b128 v112, v[180:183] offset:2048
	ds_write_b128 v112, v[184:187] offset:3072
	v_mfma_f32_32x32x16_bf16 v[32:47], v[120:123], v[52:55], v[32:47]
	v_mfma_f32_32x32x16_bf16 v[32:47], v[124:127], v[56:59], v[32:47]
	v_mfma_f32_32x32x16_bf16 v[32:47], v[128:131], v[60:63], v[32:47]
	s_nop 11
	v_exp_f32_e32 v32, v32
	v_exp_f32_e32 v33, v33
	v_exp_f32_e32 v34, v34
	v_exp_f32_e32 v35, v35
	v_exp_f32_e32 v36, v36
	v_exp_f32_e32 v37, v37
	v_exp_f32_e32 v38, v38
	v_exp_f32_e32 v39, v39
	v_exp_f32_e32 v40, v40
	v_exp_f32_e32 v41, v41
	v_exp_f32_e32 v42, v42
	v_exp_f32_e32 v43, v43
	v_exp_f32_e32 v44, v44
	v_exp_f32_e32 v45, v45
	v_exp_f32_e32 v46, v46
	v_exp_f32_e32 v47, v47
	s_add_i32 s90, s76, 224
	v_add_u32_e32 v84, s90, v107
	v_add_u32_e32 v85, 0, v84
	v_add_u32_e32 v86, 1, v84
	v_add_u32_e32 v87, 2, v84
	v_add_u32_e32 v88, 3, v84
	v_cmp_gt_u32_e64 s[30:31], s98, v85
	v_cmp_gt_u32_e64 s[36:37], s98, v86
	v_cmp_gt_u32_e64 s[78:79], s98, v87
	v_cmp_gt_u32_e64 s[50:51], s98, v88
	v_cndmask_b32_e64 v32, 0, v32, s[30:31]
	v_add_u32_e32 v85, 8, v84
	v_cmp_gt_u32_e64 s[30:31], s98, v85
	v_cndmask_b32_e64 v33, 0, v33, s[36:37]
	v_add_u32_e32 v86, 9, v84
	v_cmp_gt_u32_e64 s[36:37], s98, v86
	v_cndmask_b32_e64 v34, 0, v34, s[78:79]
	v_add_u32_e32 v87, 10, v84
	v_cmp_gt_u32_e64 s[78:79], s98, v87
	v_cndmask_b32_e64 v35, 0, v35, s[50:51]
	v_add_u32_e32 v88, 11, v84
	v_cmp_gt_u32_e64 s[50:51], s98, v88
	v_cndmask_b32_e64 v36, 0, v36, s[30:31]
	v_add_u32_e32 v85, 16, v84
	v_cmp_gt_u32_e64 s[30:31], s98, v85
	v_cndmask_b32_e64 v37, 0, v37, s[36:37]
	v_add_u32_e32 v86, 17, v84
	v_cmp_gt_u32_e64 s[36:37], s98, v86
	v_cndmask_b32_e64 v38, 0, v38, s[78:79]
	v_add_u32_e32 v87, 18, v84
	v_cmp_gt_u32_e64 s[78:79], s98, v87
	v_cndmask_b32_e64 v39, 0, v39, s[50:51]
	v_add_u32_e32 v88, 19, v84
	v_cmp_gt_u32_e64 s[50:51], s98, v88
	v_cndmask_b32_e64 v40, 0, v40, s[30:31]
	v_add_u32_e32 v85, 24, v84
	v_cmp_gt_u32_e64 s[30:31], s98, v85
	v_cndmask_b32_e64 v41, 0, v41, s[36:37]
	v_add_u32_e32 v86, 25, v84
	v_cmp_gt_u32_e64 s[36:37], s98, v86
	v_cndmask_b32_e64 v42, 0, v42, s[78:79]
	v_add_u32_e32 v87, 26, v84
	v_cmp_gt_u32_e64 s[78:79], s98, v87
	v_cndmask_b32_e64 v43, 0, v43, s[50:51]
	v_add_u32_e32 v88, 27, v84
	v_cmp_gt_u32_e64 s[50:51], s98, v88
	v_nop
	v_cndmask_b32_e64 v44, 0, v44, s[30:31]
	v_cndmask_b32_e64 v45, 0, v45, s[36:37]
	v_cndmask_b32_e64 v46, 0, v46, s[78:79]
	v_cndmask_b32_e64 v47, 0, v47, s[50:51]
	v_cvt_pk_bf16_f32 v64, v32, v33
	v_cvt_pk_bf16_f32 v65, v34, v35
	v_cvt_pk_bf16_f32 v66, v36, v37
	v_cvt_pk_bf16_f32 v67, v38, v39
	v_cvt_pk_bf16_f32 v68, v40, v41
	v_cvt_pk_bf16_f32 v69, v42, v43
	v_cvt_pk_bf16_f32 v70, v44, v45
	v_cvt_pk_bf16_f32 v71, v46, v47
	v_pk_add_f32 v[232:233], v[232:233], v[32:33]
	v_pk_add_f32 v[232:233], v[232:233], v[34:35]
	v_pk_add_f32 v[232:233], v[232:233], v[36:37]
	v_pk_add_f32 v[232:233], v[232:233], v[38:39]
	v_pk_add_f32 v[232:233], v[232:233], v[40:41]
	v_pk_add_f32 v[232:233], v[232:233], v[42:43]
	v_pk_add_f32 v[232:233], v[232:233], v[44:45]
	v_pk_add_f32 v[232:233], v[232:233], v[46:47]
	ds_read2_b32 v[32:33], v115 offset0:102 offset1:103
	ds_read2_b32 v[34:35], v115 offset0:104 offset1:105
	ds_read2_b32 v[36:37], v115 offset0:110 offset1:111
	ds_read2_b32 v[38:39], v115 offset0:112 offset1:113
	ds_read2_b32 v[40:41], v115 offset0:119 offset1:120
	ds_read2_b32 v[42:43], v115 offset0:121 offset1:122
	ds_read2_b32 v[44:45], v115 offset0:127 offset1:128
	ds_read2_b32 v[46:47], v115 offset0:129 offset1:130
	s_waitcnt lgkmcnt(15)
	v_mfma_f32_32x32x16_bf16 v[0:15], v[64:67], v[72:75], v[0:15]
	v_mfma_f32_32x32x16_bf16 v[16:31], v[64:67], v[76:79], v[16:31]
	v_mfma_f32_32x32x16_bf16 v[0:15], v[68:71], v[220:223], v[0:15]
	v_mfma_f32_32x32x16_bf16 v[16:31], v[68:71], v[224:227], v[16:31]
	s_add_i32 s90, s76, 320
	v_add_u32_e32 v80, s90, v235
	v_add_u32_e32 v83, s90, v236
	v_add_u32_e32 v99, s90, v237
	v_add_u32_e32 v253, s90, v238
	v_add_u32_e32 v254, s90, v100
	v_add_u32_e32 v255, s90, v149
	v_med3_i32 v80, v80, 0, s99
	v_med3_i32 v83, v83, 0, s99
	v_med3_i32 v99, v99, 0, s99
	v_med3_i32 v253, v253, 0, s99
	v_med3_i32 v254, v254, 0, s99
	v_med3_i32 v255, v255, 0, s99
	v_mad_u32_u24 v80, v80, s100, v252
	v_mad_u32_u24 v83, v83, s100, v252
	v_mad_u32_u24 v99, v99, s100, v252
	v_mad_u32_u24 v253, v253, s100, v252
	v_mad_u32_u24 v254, v254, s100, v153
	v_mad_u32_u24 v255, v255, s100, v153
	global_load_dwordx4 v[116:119], v80, s[82:83]
	global_load_dwordx4 v[120:123], v83, s[82:83]
	global_load_dwordx4 v[124:127], v99, s[82:83]
	global_load_dwordx4 v[128:131], v253, s[82:83]
	global_load_dwordx4 v[132:135], v254, s[82:83] offset:768
	global_load_dwordx4 v[136:139], v255, s[82:83] offset:768
	global_load_dwordx4 v[140:143], v254, s[82:83] offset:832
	global_load_dwordx4 v[144:147], v255, s[82:83] offset:832
	s_waitcnt lgkmcnt(0)
	v_mfma_f32_32x32x16_bf16 v[32:47], v[156:159], v[48:51], v[32:47]
	ds_read_b64_tr_b16 v[72:73], v231
	ds_read_b64_tr_b16 v[74:75], v231 offset:512
	ds_read_b64_tr_b16 v[76:77], v231 offset:2048
	ds_read_b64_tr_b16 v[78:79], v231 offset:2560
	ds_read_b64_tr_b16 v[220:221], v231 offset:1024
	ds_read_b64_tr_b16 v[222:223], v231 offset:1536
	ds_read_b64_tr_b16 v[224:225], v231 offset:3072
	ds_read_b64_tr_b16 v[226:227], v231 offset:3584
	s_waitcnt vmcnt(8)
	ds_write_b128 v247, v[188:191]
	ds_write_b128 v247, v[192:195] offset:1024
	ds_write_b128 v111, v[196:199] offset:2048
	ds_write_b128 v111, v[200:203] offset:3072
	ds_read_b128 v[188:191], v248
	ds_read_b128 v[192:195], v249
	ds_read_b128 v[196:199], v250
	ds_read_b128 v[200:203], v251
	ds_write_b128 v112, v[204:207]
	ds_write_b128 v112, v[208:211] offset:1024
	ds_write_b128 v112, v[212:215] offset:2048
	ds_write_b128 v112, v[216:219] offset:3072
	v_mfma_f32_32x32x16_bf16 v[32:47], v[160:163], v[52:55], v[32:47]
	v_mfma_f32_32x32x16_bf16 v[32:47], v[164:167], v[56:59], v[32:47]
	v_mfma_f32_32x32x16_bf16 v[32:47], v[168:171], v[60:63], v[32:47]
	s_nop 11
	v_exp_f32_e32 v32, v32
	v_exp_f32_e32 v33, v33
	v_exp_f32_e32 v34, v34
	v_exp_f32_e32 v35, v35
	v_exp_f32_e32 v36, v36
	v_exp_f32_e32 v37, v37
	v_exp_f32_e32 v38, v38
	v_exp_f32_e32 v39, v39
	v_exp_f32_e32 v40, v40
	v_exp_f32_e32 v41, v41
	v_exp_f32_e32 v42, v42
	v_exp_f32_e32 v43, v43
	v_exp_f32_e32 v44, v44
	v_exp_f32_e32 v45, v45
	v_exp_f32_e32 v46, v46
	v_exp_f32_e32 v47, v47
	s_add_i32 s90, s76, 256
	v_add_u32_e32 v84, s90, v107
	v_add_u32_e32 v85, 0, v84
	v_add_u32_e32 v86, 1, v84
	v_add_u32_e32 v87, 2, v84
	v_add_u32_e32 v88, 3, v84
	v_cmp_gt_u32_e64 s[30:31], s98, v85
	v_cmp_gt_u32_e64 s[36:37], s98, v86
	v_cmp_gt_u32_e64 s[78:79], s98, v87
	v_cmp_gt_u32_e64 s[50:51], s98, v88
	v_cndmask_b32_e64 v32, 0, v32, s[30:31]
	v_add_u32_e32 v85, 8, v84
	v_cmp_gt_u32_e64 s[30:31], s98, v85
	v_cndmask_b32_e64 v33, 0, v33, s[36:37]
	v_add_u32_e32 v86, 9, v84
	v_cmp_gt_u32_e64 s[36:37], s98, v86
	v_cndmask_b32_e64 v34, 0, v34, s[78:79]
	v_add_u32_e32 v87, 10, v84
	v_cmp_gt_u32_e64 s[78:79], s98, v87
	v_cndmask_b32_e64 v35, 0, v35, s[50:51]
	v_add_u32_e32 v88, 11, v84
	v_cmp_gt_u32_e64 s[50:51], s98, v88
	v_cndmask_b32_e64 v36, 0, v36, s[30:31]
	v_add_u32_e32 v85, 16, v84
	v_cmp_gt_u32_e64 s[30:31], s98, v85
	v_cndmask_b32_e64 v37, 0, v37, s[36:37]
	v_add_u32_e32 v86, 17, v84
	v_cmp_gt_u32_e64 s[36:37], s98, v86
	v_cndmask_b32_e64 v38, 0, v38, s[78:79]
	v_add_u32_e32 v87, 18, v84
	v_cmp_gt_u32_e64 s[78:79], s98, v87
	v_cndmask_b32_e64 v39, 0, v39, s[50:51]
	v_add_u32_e32 v88, 19, v84
	v_cmp_gt_u32_e64 s[50:51], s98, v88
	v_cndmask_b32_e64 v40, 0, v40, s[30:31]
	v_add_u32_e32 v85, 24, v84
	v_cmp_gt_u32_e64 s[30:31], s98, v85
	v_cndmask_b32_e64 v41, 0, v41, s[36:37]
	v_add_u32_e32 v86, 25, v84
	v_cmp_gt_u32_e64 s[36:37], s98, v86
	v_cndmask_b32_e64 v42, 0, v42, s[78:79]
	v_add_u32_e32 v87, 26, v84
	v_cmp_gt_u32_e64 s[78:79], s98, v87
	v_cndmask_b32_e64 v43, 0, v43, s[50:51]
	v_add_u32_e32 v88, 27, v84
	v_cmp_gt_u32_e64 s[50:51], s98, v88
	v_nop
	v_cndmask_b32_e64 v44, 0, v44, s[30:31]
	v_cndmask_b32_e64 v45, 0, v45, s[36:37]
	v_cndmask_b32_e64 v46, 0, v46, s[78:79]
	v_cndmask_b32_e64 v47, 0, v47, s[50:51]
	v_cvt_pk_bf16_f32 v64, v32, v33
	v_cvt_pk_bf16_f32 v65, v34, v35
	v_cvt_pk_bf16_f32 v66, v36, v37
	v_cvt_pk_bf16_f32 v67, v38, v39
	v_cvt_pk_bf16_f32 v68, v40, v41
	v_cvt_pk_bf16_f32 v69, v42, v43
	v_cvt_pk_bf16_f32 v70, v44, v45
	v_cvt_pk_bf16_f32 v71, v46, v47
	v_pk_add_f32 v[232:233], v[232:233], v[32:33]
	v_pk_add_f32 v[232:233], v[232:233], v[34:35]
	v_pk_add_f32 v[232:233], v[232:233], v[36:37]
	v_pk_add_f32 v[232:233], v[232:233], v[38:39]
	v_pk_add_f32 v[232:233], v[232:233], v[40:41]
	v_pk_add_f32 v[232:233], v[232:233], v[42:43]
	v_pk_add_f32 v[232:233], v[232:233], v[44:45]
	v_pk_add_f32 v[232:233], v[232:233], v[46:47]
	ds_read2_b32 v[32:33], v115 offset0:136 offset1:137
	ds_read2_b32 v[34:35], v115 offset0:138 offset1:139
	ds_read2_b32 v[36:37], v115 offset0:144 offset1:145
	ds_read2_b32 v[38:39], v115 offset0:146 offset1:147
	ds_read2_b32 v[40:41], v115 offset0:153 offset1:154
	ds_read2_b32 v[42:43], v115 offset0:155 offset1:156
	ds_read2_b32 v[44:45], v115 offset0:161 offset1:162
	ds_read2_b32 v[46:47], v115 offset0:163 offset1:164
	s_waitcnt lgkmcnt(15)
	v_mfma_f32_32x32x16_bf16 v[0:15], v[64:67], v[72:75], v[0:15]
	v_mfma_f32_32x32x16_bf16 v[16:31], v[64:67], v[76:79], v[16:31]
	v_mfma_f32_32x32x16_bf16 v[0:15], v[68:71], v[220:223], v[0:15]
	v_mfma_f32_32x32x16_bf16 v[16:31], v[68:71], v[224:227], v[16:31]
	s_add_i32 s90, s76, 352
	v_add_u32_e32 v80, s90, v235
	v_add_u32_e32 v83, s90, v236
	v_add_u32_e32 v99, s90, v237
	v_add_u32_e32 v253, s90, v238
	v_add_u32_e32 v254, s90, v100
	v_add_u32_e32 v255, s90, v149
	v_med3_i32 v80, v80, 0, s99
	v_med3_i32 v83, v83, 0, s99
	v_med3_i32 v99, v99, 0, s99
	v_med3_i32 v253, v253, 0, s99
	v_med3_i32 v254, v254, 0, s99
	v_med3_i32 v255, v255, 0, s99
	v_mad_u32_u24 v80, v80, s100, v252
	v_mad_u32_u24 v83, v83, s100, v252
	v_mad_u32_u24 v99, v99, s100, v252
	v_mad_u32_u24 v253, v253, s100, v252
	v_mad_u32_u24 v254, v254, s100, v153
	v_mad_u32_u24 v255, v255, s100, v153
	global_load_dwordx4 v[156:159], v80, s[82:83]
	global_load_dwordx4 v[160:163], v83, s[82:83]
	global_load_dwordx4 v[164:167], v99, s[82:83]
	global_load_dwordx4 v[168:171], v253, s[82:83]
	global_load_dwordx4 v[172:175], v254, s[82:83] offset:768
	global_load_dwordx4 v[176:179], v255, s[82:83] offset:768
	global_load_dwordx4 v[180:183], v254, s[82:83] offset:832
	global_load_dwordx4 v[184:187], v255, s[82:83] offset:832
	s_waitcnt lgkmcnt(0)
	v_mfma_f32_32x32x16_bf16 v[32:47], v[188:191], v[48:51], v[32:47]
	ds_read_b64_tr_b16 v[72:73], v231
	ds_read_b64_tr_b16 v[74:75], v231 offset:512
	ds_read_b64_tr_b16 v[76:77], v231 offset:2048
	ds_read_b64_tr_b16 v[78:79], v231 offset:2560
	ds_read_b64_tr_b16 v[220:221], v231 offset:1024
	ds_read_b64_tr_b16 v[222:223], v231 offset:1536
	ds_read_b64_tr_b16 v[224:225], v231 offset:3072
	ds_read_b64_tr_b16 v[226:227], v231 offset:3584
	s_waitcnt vmcnt(8)
	ds_write_b128 v247, v[116:119]
	ds_write_b128 v247, v[120:123] offset:1024
	ds_write_b128 v111, v[124:127] offset:2048
	ds_write_b128 v111, v[128:131] offset:3072
	ds_read_b128 v[116:119], v248
	ds_read_b128 v[120:123], v249
	ds_read_b128 v[124:127], v250
	ds_read_b128 v[128:131], v251
	ds_write_b128 v112, v[132:135]
	ds_write_b128 v112, v[136:139] offset:1024
	ds_write_b128 v112, v[140:143] offset:2048
	ds_write_b128 v112, v[144:147] offset:3072
	v_mfma_f32_32x32x16_bf16 v[32:47], v[192:195], v[52:55], v[32:47]
	v_mfma_f32_32x32x16_bf16 v[32:47], v[196:199], v[56:59], v[32:47]
	v_mfma_f32_32x32x16_bf16 v[32:47], v[200:203], v[60:63], v[32:47]
	s_nop 11
	v_exp_f32_e32 v32, v32
	v_exp_f32_e32 v33, v33
	v_exp_f32_e32 v34, v34
	v_exp_f32_e32 v35, v35
	v_exp_f32_e32 v36, v36
	v_exp_f32_e32 v37, v37
	v_exp_f32_e32 v38, v38
	v_exp_f32_e32 v39, v39
	v_exp_f32_e32 v40, v40
	v_exp_f32_e32 v41, v41
	v_exp_f32_e32 v42, v42
	v_exp_f32_e32 v43, v43
	v_exp_f32_e32 v44, v44
	v_exp_f32_e32 v45, v45
	v_exp_f32_e32 v46, v46
	v_exp_f32_e32 v47, v47
	s_add_i32 s90, s76, 288
	v_add_u32_e32 v84, s90, v107
	v_add_u32_e32 v85, 0, v84
	v_add_u32_e32 v86, 1, v84
	v_add_u32_e32 v87, 2, v84
	v_add_u32_e32 v88, 3, v84
	v_cmp_gt_u32_e64 s[30:31], s98, v85
	v_cmp_gt_u32_e64 s[36:37], s98, v86
	v_cmp_gt_u32_e64 s[78:79], s98, v87
	v_cmp_gt_u32_e64 s[50:51], s98, v88
	v_cndmask_b32_e64 v32, 0, v32, s[30:31]
	v_add_u32_e32 v85, 8, v84
	v_cmp_gt_u32_e64 s[30:31], s98, v85
	v_cndmask_b32_e64 v33, 0, v33, s[36:37]
	v_add_u32_e32 v86, 9, v84
	v_cmp_gt_u32_e64 s[36:37], s98, v86
	v_cndmask_b32_e64 v34, 0, v34, s[78:79]
	v_add_u32_e32 v87, 10, v84
	v_cmp_gt_u32_e64 s[78:79], s98, v87
	v_cndmask_b32_e64 v35, 0, v35, s[50:51]
	v_add_u32_e32 v88, 11, v84
	v_cmp_gt_u32_e64 s[50:51], s98, v88
	v_cndmask_b32_e64 v36, 0, v36, s[30:31]
	v_add_u32_e32 v85, 16, v84
	v_cmp_gt_u32_e64 s[30:31], s98, v85
	v_cndmask_b32_e64 v37, 0, v37, s[36:37]
	v_add_u32_e32 v86, 17, v84
	v_cmp_gt_u32_e64 s[36:37], s98, v86
	v_cndmask_b32_e64 v38, 0, v38, s[78:79]
	v_add_u32_e32 v87, 18, v84
	v_cmp_gt_u32_e64 s[78:79], s98, v87
	v_cndmask_b32_e64 v39, 0, v39, s[50:51]
	v_add_u32_e32 v88, 19, v84
	v_cmp_gt_u32_e64 s[50:51], s98, v88
	v_cndmask_b32_e64 v40, 0, v40, s[30:31]
	v_add_u32_e32 v85, 24, v84
	v_cmp_gt_u32_e64 s[30:31], s98, v85
	v_cndmask_b32_e64 v41, 0, v41, s[36:37]
	v_add_u32_e32 v86, 25, v84
	v_cmp_gt_u32_e64 s[36:37], s98, v86
	v_cndmask_b32_e64 v42, 0, v42, s[78:79]
	v_add_u32_e32 v87, 26, v84
	v_cmp_gt_u32_e64 s[78:79], s98, v87
	v_cndmask_b32_e64 v43, 0, v43, s[50:51]
	v_add_u32_e32 v88, 27, v84
	v_cmp_gt_u32_e64 s[50:51], s98, v88
	v_nop
	v_cndmask_b32_e64 v44, 0, v44, s[30:31]
	v_cndmask_b32_e64 v45, 0, v45, s[36:37]
	v_cndmask_b32_e64 v46, 0, v46, s[78:79]
	v_cndmask_b32_e64 v47, 0, v47, s[50:51]
	v_cvt_pk_bf16_f32 v64, v32, v33
	v_cvt_pk_bf16_f32 v65, v34, v35
	v_cvt_pk_bf16_f32 v66, v36, v37
	v_cvt_pk_bf16_f32 v67, v38, v39
	v_cvt_pk_bf16_f32 v68, v40, v41
	v_cvt_pk_bf16_f32 v69, v42, v43
	v_cvt_pk_bf16_f32 v70, v44, v45
	v_cvt_pk_bf16_f32 v71, v46, v47
	v_pk_add_f32 v[232:233], v[232:233], v[32:33]
	v_pk_add_f32 v[232:233], v[232:233], v[34:35]
	v_pk_add_f32 v[232:233], v[232:233], v[36:37]
	v_pk_add_f32 v[232:233], v[232:233], v[38:39]
	v_pk_add_f32 v[232:233], v[232:233], v[40:41]
	v_pk_add_f32 v[232:233], v[232:233], v[42:43]
	v_pk_add_f32 v[232:233], v[232:233], v[44:45]
	v_pk_add_f32 v[232:233], v[232:233], v[46:47]
	ds_read2_b32 v[32:33], v115 offset0:170 offset1:171
	ds_read2_b32 v[34:35], v115 offset0:172 offset1:173
	ds_read2_b32 v[36:37], v115 offset0:178 offset1:179
	ds_read2_b32 v[38:39], v115 offset0:180 offset1:181
	ds_read2_b32 v[40:41], v115 offset0:187 offset1:188
	ds_read2_b32 v[42:43], v115 offset0:189 offset1:190
	ds_read2_b32 v[44:45], v115 offset0:195 offset1:196
	ds_read2_b32 v[46:47], v115 offset0:197 offset1:198
	s_waitcnt lgkmcnt(15)
	v_mfma_f32_32x32x16_bf16 v[0:15], v[64:67], v[72:75], v[0:15]
	v_mfma_f32_32x32x16_bf16 v[16:31], v[64:67], v[76:79], v[16:31]
	v_mfma_f32_32x32x16_bf16 v[0:15], v[68:71], v[220:223], v[0:15]
	v_mfma_f32_32x32x16_bf16 v[16:31], v[68:71], v[224:227], v[16:31]
	s_add_i32 s90, s76, 384
	v_add_u32_e32 v80, s90, v235
	v_add_u32_e32 v83, s90, v236
	v_add_u32_e32 v99, s90, v237
	v_add_u32_e32 v253, s90, v238
	v_add_u32_e32 v254, s90, v100
	v_add_u32_e32 v255, s90, v149
	v_med3_i32 v80, v80, 0, s99
	v_med3_i32 v83, v83, 0, s99
	v_med3_i32 v99, v99, 0, s99
	v_med3_i32 v253, v253, 0, s99
	v_med3_i32 v254, v254, 0, s99
	v_med3_i32 v255, v255, 0, s99
	v_mad_u32_u24 v80, v80, s100, v252
	v_mad_u32_u24 v83, v83, s100, v252
	v_mad_u32_u24 v99, v99, s100, v252
	v_mad_u32_u24 v253, v253, s100, v252
	v_mad_u32_u24 v254, v254, s100, v153
	v_mad_u32_u24 v255, v255, s100, v153
	global_load_dwordx4 v[188:191], v80, s[82:83]
	global_load_dwordx4 v[192:195], v83, s[82:83]
	global_load_dwordx4 v[196:199], v99, s[82:83]
	global_load_dwordx4 v[200:203], v253, s[82:83]
	global_load_dwordx4 v[204:207], v254, s[82:83] offset:768
	global_load_dwordx4 v[208:211], v255, s[82:83] offset:768
	global_load_dwordx4 v[212:215], v254, s[82:83] offset:832
	global_load_dwordx4 v[216:219], v255, s[82:83] offset:832
	s_waitcnt lgkmcnt(0)
	v_mfma_f32_32x32x16_bf16 v[32:47], v[116:119], v[48:51], v[32:47]
	ds_read_b64_tr_b16 v[72:73], v231
	ds_read_b64_tr_b16 v[74:75], v231 offset:512
	ds_read_b64_tr_b16 v[76:77], v231 offset:2048
	ds_read_b64_tr_b16 v[78:79], v231 offset:2560
	ds_read_b64_tr_b16 v[220:221], v231 offset:1024
	ds_read_b64_tr_b16 v[222:223], v231 offset:1536
	ds_read_b64_tr_b16 v[224:225], v231 offset:3072
	ds_read_b64_tr_b16 v[226:227], v231 offset:3584
	s_waitcnt vmcnt(8)
	ds_write_b128 v247, v[156:159]
	ds_write_b128 v247, v[160:163] offset:1024
	ds_write_b128 v111, v[164:167] offset:2048
	ds_write_b128 v111, v[168:171] offset:3072
	ds_read_b128 v[156:159], v248
	ds_read_b128 v[160:163], v249
	ds_read_b128 v[164:167], v250
	ds_read_b128 v[168:171], v251
	ds_write_b128 v112, v[172:175]
	ds_write_b128 v112, v[176:179] offset:1024
	ds_write_b128 v112, v[180:183] offset:2048
	ds_write_b128 v112, v[184:187] offset:3072
	v_mfma_f32_32x32x16_bf16 v[32:47], v[120:123], v[52:55], v[32:47]
	v_mfma_f32_32x32x16_bf16 v[32:47], v[124:127], v[56:59], v[32:47]
	v_mfma_f32_32x32x16_bf16 v[32:47], v[128:131], v[60:63], v[32:47]
	s_nop 11
	v_exp_f32_e32 v32, v32
	v_exp_f32_e32 v33, v33
	v_exp_f32_e32 v34, v34
	v_exp_f32_e32 v35, v35
	v_exp_f32_e32 v36, v36
	v_exp_f32_e32 v37, v37
	v_exp_f32_e32 v38, v38
	v_exp_f32_e32 v39, v39
	v_exp_f32_e32 v40, v40
	v_exp_f32_e32 v41, v41
	v_exp_f32_e32 v42, v42
	v_exp_f32_e32 v43, v43
	v_exp_f32_e32 v44, v44
	v_exp_f32_e32 v45, v45
	v_exp_f32_e32 v46, v46
	v_exp_f32_e32 v47, v47
	s_add_i32 s90, s76, 320
	v_add_u32_e32 v84, s90, v107
	v_add_u32_e32 v85, 0, v84
	v_add_u32_e32 v86, 1, v84
	v_add_u32_e32 v87, 2, v84
	v_add_u32_e32 v88, 3, v84
	v_cmp_gt_u32_e64 s[30:31], s98, v85
	v_cmp_gt_u32_e64 s[36:37], s98, v86
	v_cmp_gt_u32_e64 s[78:79], s98, v87
	v_cmp_gt_u32_e64 s[50:51], s98, v88
	v_cndmask_b32_e64 v32, 0, v32, s[30:31]
	v_add_u32_e32 v85, 8, v84
	v_cmp_gt_u32_e64 s[30:31], s98, v85
	v_cndmask_b32_e64 v33, 0, v33, s[36:37]
	v_add_u32_e32 v86, 9, v84
	v_cmp_gt_u32_e64 s[36:37], s98, v86
	v_cndmask_b32_e64 v34, 0, v34, s[78:79]
	v_add_u32_e32 v87, 10, v84
	v_cmp_gt_u32_e64 s[78:79], s98, v87
	v_cndmask_b32_e64 v35, 0, v35, s[50:51]
	v_add_u32_e32 v88, 11, v84
	v_cmp_gt_u32_e64 s[50:51], s98, v88
	v_cndmask_b32_e64 v36, 0, v36, s[30:31]
	v_add_u32_e32 v85, 16, v84
	v_cmp_gt_u32_e64 s[30:31], s98, v85
	v_cndmask_b32_e64 v37, 0, v37, s[36:37]
	v_add_u32_e32 v86, 17, v84
	v_cmp_gt_u32_e64 s[36:37], s98, v86
	v_cndmask_b32_e64 v38, 0, v38, s[78:79]
	v_add_u32_e32 v87, 18, v84
	v_cmp_gt_u32_e64 s[78:79], s98, v87
	v_cndmask_b32_e64 v39, 0, v39, s[50:51]
	v_add_u32_e32 v88, 19, v84
	v_cmp_gt_u32_e64 s[50:51], s98, v88
	v_cndmask_b32_e64 v40, 0, v40, s[30:31]
	v_add_u32_e32 v85, 24, v84
	v_cmp_gt_u32_e64 s[30:31], s98, v85
	v_cndmask_b32_e64 v41, 0, v41, s[36:37]
	v_add_u32_e32 v86, 25, v84
	v_cmp_gt_u32_e64 s[36:37], s98, v86
	v_cndmask_b32_e64 v42, 0, v42, s[78:79]
	v_add_u32_e32 v87, 26, v84
	v_cmp_gt_u32_e64 s[78:79], s98, v87
	v_cndmask_b32_e64 v43, 0, v43, s[50:51]
	v_add_u32_e32 v88, 27, v84
	v_cmp_gt_u32_e64 s[50:51], s98, v88
	v_nop
	v_cndmask_b32_e64 v44, 0, v44, s[30:31]
	v_cndmask_b32_e64 v45, 0, v45, s[36:37]
	v_cndmask_b32_e64 v46, 0, v46, s[78:79]
	v_cndmask_b32_e64 v47, 0, v47, s[50:51]
	v_cvt_pk_bf16_f32 v64, v32, v33
	v_cvt_pk_bf16_f32 v65, v34, v35
	v_cvt_pk_bf16_f32 v66, v36, v37
	v_cvt_pk_bf16_f32 v67, v38, v39
	v_cvt_pk_bf16_f32 v68, v40, v41
	v_cvt_pk_bf16_f32 v69, v42, v43
	v_cvt_pk_bf16_f32 v70, v44, v45
	v_cvt_pk_bf16_f32 v71, v46, v47
	v_pk_add_f32 v[232:233], v[232:233], v[32:33]
	v_pk_add_f32 v[232:233], v[232:233], v[34:35]
	v_pk_add_f32 v[232:233], v[232:233], v[36:37]
	v_pk_add_f32 v[232:233], v[232:233], v[38:39]
	v_pk_add_f32 v[232:233], v[232:233], v[40:41]
	v_pk_add_f32 v[232:233], v[232:233], v[42:43]
	v_pk_add_f32 v[232:233], v[232:233], v[44:45]
	v_pk_add_f32 v[232:233], v[232:233], v[46:47]
	ds_read2_b32 v[32:33], v115 offset0:204 offset1:205
	ds_read2_b32 v[34:35], v115 offset0:206 offset1:207
	ds_read2_b32 v[36:37], v115 offset0:212 offset1:213
	ds_read2_b32 v[38:39], v115 offset0:214 offset1:215
	ds_read2_b32 v[40:41], v115 offset0:221 offset1:222
	ds_read2_b32 v[42:43], v115 offset0:223 offset1:224
	ds_read2_b32 v[44:45], v115 offset0:229 offset1:230
	ds_read2_b32 v[46:47], v115 offset0:231 offset1:232
	s_waitcnt lgkmcnt(15)
	v_mfma_f32_32x32x16_bf16 v[0:15], v[64:67], v[72:75], v[0:15]
	v_mfma_f32_32x32x16_bf16 v[16:31], v[64:67], v[76:79], v[16:31]
	v_mfma_f32_32x32x16_bf16 v[0:15], v[68:71], v[220:223], v[0:15]
	v_mfma_f32_32x32x16_bf16 v[16:31], v[68:71], v[224:227], v[16:31]
	s_add_i32 s90, s76, 416
	v_add_u32_e32 v80, s90, v235
	v_add_u32_e32 v83, s90, v236
	v_add_u32_e32 v99, s90, v237
	v_add_u32_e32 v253, s90, v238
	v_add_u32_e32 v254, s90, v100
	v_add_u32_e32 v255, s90, v149
	v_med3_i32 v80, v80, 0, s99
	v_med3_i32 v83, v83, 0, s99
	v_med3_i32 v99, v99, 0, s99
	v_med3_i32 v253, v253, 0, s99
	v_med3_i32 v254, v254, 0, s99
	v_med3_i32 v255, v255, 0, s99
	v_mad_u32_u24 v80, v80, s100, v252
	v_mad_u32_u24 v83, v83, s100, v252
	v_mad_u32_u24 v99, v99, s100, v252
	v_mad_u32_u24 v253, v253, s100, v252
	v_mad_u32_u24 v254, v254, s100, v153
	v_mad_u32_u24 v255, v255, s100, v153
	global_load_dwordx4 v[116:119], v80, s[82:83]
	global_load_dwordx4 v[120:123], v83, s[82:83]
	global_load_dwordx4 v[124:127], v99, s[82:83]
	global_load_dwordx4 v[128:131], v253, s[82:83]
	global_load_dwordx4 v[132:135], v254, s[82:83] offset:768
	global_load_dwordx4 v[136:139], v255, s[82:83] offset:768
	global_load_dwordx4 v[140:143], v254, s[82:83] offset:832
	global_load_dwordx4 v[144:147], v255, s[82:83] offset:832
	s_waitcnt lgkmcnt(0)
	v_mfma_f32_32x32x16_bf16 v[32:47], v[156:159], v[48:51], v[32:47]
	ds_read_b64_tr_b16 v[72:73], v231
	ds_read_b64_tr_b16 v[74:75], v231 offset:512
	ds_read_b64_tr_b16 v[76:77], v231 offset:2048
	ds_read_b64_tr_b16 v[78:79], v231 offset:2560
	ds_read_b64_tr_b16 v[220:221], v231 offset:1024
	ds_read_b64_tr_b16 v[222:223], v231 offset:1536
	ds_read_b64_tr_b16 v[224:225], v231 offset:3072
	ds_read_b64_tr_b16 v[226:227], v231 offset:3584
	s_waitcnt vmcnt(8)
	ds_write_b128 v247, v[188:191]
	ds_write_b128 v247, v[192:195] offset:1024
	ds_write_b128 v111, v[196:199] offset:2048
	ds_write_b128 v111, v[200:203] offset:3072
	ds_read_b128 v[188:191], v248
	ds_read_b128 v[192:195], v249
	ds_read_b128 v[196:199], v250
	ds_read_b128 v[200:203], v251
	ds_write_b128 v112, v[204:207]
	ds_write_b128 v112, v[208:211] offset:1024
	ds_write_b128 v112, v[212:215] offset:2048
	ds_write_b128 v112, v[216:219] offset:3072
	v_mfma_f32_32x32x16_bf16 v[32:47], v[160:163], v[52:55], v[32:47]
	v_mfma_f32_32x32x16_bf16 v[32:47], v[164:167], v[56:59], v[32:47]
	v_mfma_f32_32x32x16_bf16 v[32:47], v[168:171], v[60:63], v[32:47]
	s_nop 11
	v_exp_f32_e32 v32, v32
	v_exp_f32_e32 v33, v33
	v_exp_f32_e32 v34, v34
	v_exp_f32_e32 v35, v35
	v_exp_f32_e32 v36, v36
	v_exp_f32_e32 v37, v37
	v_exp_f32_e32 v38, v38
	v_exp_f32_e32 v39, v39
	v_exp_f32_e32 v40, v40
	v_exp_f32_e32 v41, v41
	v_exp_f32_e32 v42, v42
	v_exp_f32_e32 v43, v43
	v_exp_f32_e32 v44, v44
	v_exp_f32_e32 v45, v45
	v_exp_f32_e32 v46, v46
	v_exp_f32_e32 v47, v47
	s_add_i32 s90, s76, 352
	v_add_u32_e32 v84, s90, v107
	v_add_u32_e32 v85, 0, v84
	v_add_u32_e32 v86, 1, v84
	v_add_u32_e32 v87, 2, v84
	v_add_u32_e32 v88, 3, v84
	v_cmp_gt_u32_e64 s[30:31], s98, v85
	v_cmp_gt_u32_e64 s[36:37], s98, v86
	v_cmp_gt_u32_e64 s[78:79], s98, v87
	v_cmp_gt_u32_e64 s[50:51], s98, v88
	v_cndmask_b32_e64 v32, 0, v32, s[30:31]
	v_add_u32_e32 v85, 8, v84
	v_cmp_gt_u32_e64 s[30:31], s98, v85
	v_cndmask_b32_e64 v33, 0, v33, s[36:37]
	v_add_u32_e32 v86, 9, v84
	v_cmp_gt_u32_e64 s[36:37], s98, v86
	v_cndmask_b32_e64 v34, 0, v34, s[78:79]
	v_add_u32_e32 v87, 10, v84
	v_cmp_gt_u32_e64 s[78:79], s98, v87
	v_cndmask_b32_e64 v35, 0, v35, s[50:51]
	v_add_u32_e32 v88, 11, v84
	v_cmp_gt_u32_e64 s[50:51], s98, v88
	v_cndmask_b32_e64 v36, 0, v36, s[30:31]
	v_add_u32_e32 v85, 16, v84
	v_cmp_gt_u32_e64 s[30:31], s98, v85
	v_cndmask_b32_e64 v37, 0, v37, s[36:37]
	v_add_u32_e32 v86, 17, v84
	v_cmp_gt_u32_e64 s[36:37], s98, v86
	v_cndmask_b32_e64 v38, 0, v38, s[78:79]
	v_add_u32_e32 v87, 18, v84
	v_cmp_gt_u32_e64 s[78:79], s98, v87
	v_cndmask_b32_e64 v39, 0, v39, s[50:51]
	v_add_u32_e32 v88, 19, v84
	v_cmp_gt_u32_e64 s[50:51], s98, v88
	v_cndmask_b32_e64 v40, 0, v40, s[30:31]
	v_add_u32_e32 v85, 24, v84
	v_cmp_gt_u32_e64 s[30:31], s98, v85
	v_cndmask_b32_e64 v41, 0, v41, s[36:37]
	v_add_u32_e32 v86, 25, v84
	v_cmp_gt_u32_e64 s[36:37], s98, v86
	v_cndmask_b32_e64 v42, 0, v42, s[78:79]
	v_add_u32_e32 v87, 26, v84
	v_cmp_gt_u32_e64 s[78:79], s98, v87
	v_cndmask_b32_e64 v43, 0, v43, s[50:51]
	v_add_u32_e32 v88, 27, v84
	v_cmp_gt_u32_e64 s[50:51], s98, v88
	v_nop
	v_cndmask_b32_e64 v44, 0, v44, s[30:31]
	v_cndmask_b32_e64 v45, 0, v45, s[36:37]
	v_cndmask_b32_e64 v46, 0, v46, s[78:79]
	v_cndmask_b32_e64 v47, 0, v47, s[50:51]
	v_cvt_pk_bf16_f32 v64, v32, v33
	v_cvt_pk_bf16_f32 v65, v34, v35
	v_cvt_pk_bf16_f32 v66, v36, v37
	v_cvt_pk_bf16_f32 v67, v38, v39
	v_cvt_pk_bf16_f32 v68, v40, v41
	v_cvt_pk_bf16_f32 v69, v42, v43
	v_cvt_pk_bf16_f32 v70, v44, v45
	v_cvt_pk_bf16_f32 v71, v46, v47
	v_pk_add_f32 v[232:233], v[232:233], v[32:33]
	v_pk_add_f32 v[232:233], v[232:233], v[34:35]
	v_pk_add_f32 v[232:233], v[232:233], v[36:37]
	v_pk_add_f32 v[232:233], v[232:233], v[38:39]
	v_pk_add_f32 v[232:233], v[232:233], v[40:41]
	v_pk_add_f32 v[232:233], v[232:233], v[42:43]
	v_pk_add_f32 v[232:233], v[232:233], v[44:45]
	v_pk_add_f32 v[232:233], v[232:233], v[46:47]
	v_add_u32_e32 v115, 952, v115
	ds_read2_b32 v[32:33], v115 offset0:0 offset1:1
	ds_read2_b32 v[34:35], v115 offset0:2 offset1:3
	ds_read2_b32 v[36:37], v115 offset0:8 offset1:9
	ds_read2_b32 v[38:39], v115 offset0:10 offset1:11
	ds_read2_b32 v[40:41], v115 offset0:17 offset1:18
	ds_read2_b32 v[42:43], v115 offset0:19 offset1:20
	ds_read2_b32 v[44:45], v115 offset0:25 offset1:26
	ds_read2_b32 v[46:47], v115 offset0:27 offset1:28
	s_waitcnt lgkmcnt(15)
	v_mfma_f32_32x32x16_bf16 v[0:15], v[64:67], v[72:75], v[0:15]
	v_mfma_f32_32x32x16_bf16 v[16:31], v[64:67], v[76:79], v[16:31]
	v_mfma_f32_32x32x16_bf16 v[0:15], v[68:71], v[220:223], v[0:15]
	v_mfma_f32_32x32x16_bf16 v[16:31], v[68:71], v[224:227], v[16:31]
	s_add_i32 s90, s76, 448
	v_add_u32_e32 v80, s90, v235
	v_add_u32_e32 v83, s90, v236
	v_add_u32_e32 v99, s90, v237
	v_add_u32_e32 v253, s90, v238
	v_add_u32_e32 v254, s90, v100
	v_add_u32_e32 v255, s90, v149
	v_med3_i32 v80, v80, 0, s99
	v_med3_i32 v83, v83, 0, s99
	v_med3_i32 v99, v99, 0, s99
	v_med3_i32 v253, v253, 0, s99
	v_med3_i32 v254, v254, 0, s99
	v_med3_i32 v255, v255, 0, s99
	v_mad_u32_u24 v80, v80, s100, v252
	v_mad_u32_u24 v83, v83, s100, v252
	v_mad_u32_u24 v99, v99, s100, v252
	v_mad_u32_u24 v253, v253, s100, v252
	v_mad_u32_u24 v254, v254, s100, v153
	v_mad_u32_u24 v255, v255, s100, v153
	global_load_dwordx4 v[156:159], v80, s[82:83]
	global_load_dwordx4 v[160:163], v83, s[82:83]
	global_load_dwordx4 v[164:167], v99, s[82:83]
	global_load_dwordx4 v[168:171], v253, s[82:83]
	global_load_dwordx4 v[172:175], v254, s[82:83] offset:768
	global_load_dwordx4 v[176:179], v255, s[82:83] offset:768
	global_load_dwordx4 v[180:183], v254, s[82:83] offset:832
	global_load_dwordx4 v[184:187], v255, s[82:83] offset:832
	s_waitcnt lgkmcnt(0)
	v_mfma_f32_32x32x16_bf16 v[32:47], v[188:191], v[48:51], v[32:47]
	ds_read_b64_tr_b16 v[72:73], v231
	ds_read_b64_tr_b16 v[74:75], v231 offset:512
	ds_read_b64_tr_b16 v[76:77], v231 offset:2048
	ds_read_b64_tr_b16 v[78:79], v231 offset:2560
	ds_read_b64_tr_b16 v[220:221], v231 offset:1024
	ds_read_b64_tr_b16 v[222:223], v231 offset:1536
	ds_read_b64_tr_b16 v[224:225], v231 offset:3072
	ds_read_b64_tr_b16 v[226:227], v231 offset:3584
	s_waitcnt vmcnt(8)
	ds_write_b128 v247, v[116:119]
	ds_write_b128 v247, v[120:123] offset:1024
	ds_write_b128 v111, v[124:127] offset:2048
	ds_write_b128 v111, v[128:131] offset:3072
	ds_read_b128 v[116:119], v248
	ds_read_b128 v[120:123], v249
	ds_read_b128 v[124:127], v250
	ds_read_b128 v[128:131], v251
	ds_write_b128 v112, v[132:135]
	ds_write_b128 v112, v[136:139] offset:1024
	ds_write_b128 v112, v[140:143] offset:2048
	ds_write_b128 v112, v[144:147] offset:3072
	v_mfma_f32_32x32x16_bf16 v[32:47], v[192:195], v[52:55], v[32:47]
	v_mfma_f32_32x32x16_bf16 v[32:47], v[196:199], v[56:59], v[32:47]
	v_mfma_f32_32x32x16_bf16 v[32:47], v[200:203], v[60:63], v[32:47]
	s_nop 11
	v_exp_f32_e32 v32, v32
	v_exp_f32_e32 v33, v33
	v_exp_f32_e32 v34, v34
	v_exp_f32_e32 v35, v35
	v_exp_f32_e32 v36, v36
	v_exp_f32_e32 v37, v37
	v_exp_f32_e32 v38, v38
	v_exp_f32_e32 v39, v39
	v_exp_f32_e32 v40, v40
	v_exp_f32_e32 v41, v41
	v_exp_f32_e32 v42, v42
	v_exp_f32_e32 v43, v43
	v_exp_f32_e32 v44, v44
	v_exp_f32_e32 v45, v45
	v_exp_f32_e32 v46, v46
	v_exp_f32_e32 v47, v47
	s_add_i32 s90, s76, 384
	v_add_u32_e32 v84, s90, v107
	v_add_u32_e32 v85, 0, v84
	v_add_u32_e32 v86, 1, v84
	v_add_u32_e32 v87, 2, v84
	v_add_u32_e32 v88, 3, v84
	v_cmp_gt_u32_e64 s[30:31], s98, v85
	v_cmp_gt_u32_e64 s[36:37], s98, v86
	v_cmp_gt_u32_e64 s[78:79], s98, v87
	v_cmp_gt_u32_e64 s[50:51], s98, v88
	v_cndmask_b32_e64 v32, 0, v32, s[30:31]
	v_add_u32_e32 v85, 8, v84
	v_cmp_gt_u32_e64 s[30:31], s98, v85
	v_cndmask_b32_e64 v33, 0, v33, s[36:37]
	v_add_u32_e32 v86, 9, v84
	v_cmp_gt_u32_e64 s[36:37], s98, v86
	v_cndmask_b32_e64 v34, 0, v34, s[78:79]
	v_add_u32_e32 v87, 10, v84
	v_cmp_gt_u32_e64 s[78:79], s98, v87
	v_cndmask_b32_e64 v35, 0, v35, s[50:51]
	v_add_u32_e32 v88, 11, v84
	v_cmp_gt_u32_e64 s[50:51], s98, v88
	v_cndmask_b32_e64 v36, 0, v36, s[30:31]
	v_add_u32_e32 v85, 16, v84
	v_cmp_gt_u32_e64 s[30:31], s98, v85
	v_cndmask_b32_e64 v37, 0, v37, s[36:37]
	v_add_u32_e32 v86, 17, v84
	v_cmp_gt_u32_e64 s[36:37], s98, v86
	v_cndmask_b32_e64 v38, 0, v38, s[78:79]
	v_add_u32_e32 v87, 18, v84
	v_cmp_gt_u32_e64 s[78:79], s98, v87
	v_cndmask_b32_e64 v39, 0, v39, s[50:51]
	v_add_u32_e32 v88, 19, v84
	v_cmp_gt_u32_e64 s[50:51], s98, v88
	v_cndmask_b32_e64 v40, 0, v40, s[30:31]
	v_add_u32_e32 v85, 24, v84
	v_cmp_gt_u32_e64 s[30:31], s98, v85
	v_cndmask_b32_e64 v41, 0, v41, s[36:37]
	v_add_u32_e32 v86, 25, v84
	v_cmp_gt_u32_e64 s[36:37], s98, v86
	v_cndmask_b32_e64 v42, 0, v42, s[78:79]
	v_add_u32_e32 v87, 26, v84
	v_cmp_gt_u32_e64 s[78:79], s98, v87
	v_cndmask_b32_e64 v43, 0, v43, s[50:51]
	v_add_u32_e32 v88, 27, v84
	v_cmp_gt_u32_e64 s[50:51], s98, v88
	v_nop
	v_cndmask_b32_e64 v44, 0, v44, s[30:31]
	v_cndmask_b32_e64 v45, 0, v45, s[36:37]
	v_cndmask_b32_e64 v46, 0, v46, s[78:79]
	v_cndmask_b32_e64 v47, 0, v47, s[50:51]
	v_cvt_pk_bf16_f32 v64, v32, v33
	v_cvt_pk_bf16_f32 v65, v34, v35
	v_cvt_pk_bf16_f32 v66, v36, v37
	v_cvt_pk_bf16_f32 v67, v38, v39
	v_cvt_pk_bf16_f32 v68, v40, v41
	v_cvt_pk_bf16_f32 v69, v42, v43
	v_cvt_pk_bf16_f32 v70, v44, v45
	v_cvt_pk_bf16_f32 v71, v46, v47
	v_pk_add_f32 v[232:233], v[232:233], v[32:33]
	v_pk_add_f32 v[232:233], v[232:233], v[34:35]
	v_pk_add_f32 v[232:233], v[232:233], v[36:37]
	v_pk_add_f32 v[232:233], v[232:233], v[38:39]
	v_pk_add_f32 v[232:233], v[232:233], v[40:41]
	v_pk_add_f32 v[232:233], v[232:233], v[42:43]
	v_pk_add_f32 v[232:233], v[232:233], v[44:45]
	v_pk_add_f32 v[232:233], v[232:233], v[46:47]
	ds_read2_b32 v[32:33], v115 offset0:34 offset1:35
	ds_read2_b32 v[34:35], v115 offset0:36 offset1:37
	ds_read2_b32 v[36:37], v115 offset0:42 offset1:43
	ds_read2_b32 v[38:39], v115 offset0:44 offset1:45
	ds_read2_b32 v[40:41], v115 offset0:51 offset1:52
	ds_read2_b32 v[42:43], v115 offset0:53 offset1:54
	ds_read2_b32 v[44:45], v115 offset0:59 offset1:60
	ds_read2_b32 v[46:47], v115 offset0:61 offset1:62
	s_waitcnt lgkmcnt(15)
	v_mfma_f32_32x32x16_bf16 v[0:15], v[64:67], v[72:75], v[0:15]
	v_mfma_f32_32x32x16_bf16 v[16:31], v[64:67], v[76:79], v[16:31]
	v_mfma_f32_32x32x16_bf16 v[0:15], v[68:71], v[220:223], v[0:15]
	v_mfma_f32_32x32x16_bf16 v[16:31], v[68:71], v[224:227], v[16:31]
	s_add_i32 s90, s76, 480
	v_add_u32_e32 v80, s90, v235
	v_add_u32_e32 v83, s90, v236
	v_add_u32_e32 v99, s90, v237
	v_add_u32_e32 v253, s90, v238
	v_add_u32_e32 v254, s90, v100
	v_add_u32_e32 v255, s90, v149
	v_med3_i32 v80, v80, 0, s99
	v_med3_i32 v83, v83, 0, s99
	v_med3_i32 v99, v99, 0, s99
	v_med3_i32 v253, v253, 0, s99
	v_med3_i32 v254, v254, 0, s99
	v_med3_i32 v255, v255, 0, s99
	v_mad_u32_u24 v80, v80, s100, v252
	v_mad_u32_u24 v83, v83, s100, v252
	v_mad_u32_u24 v99, v99, s100, v252
	v_mad_u32_u24 v253, v253, s100, v252
	v_mad_u32_u24 v254, v254, s100, v153
	v_mad_u32_u24 v255, v255, s100, v153
	global_load_dwordx4 v[188:191], v80, s[82:83]
	global_load_dwordx4 v[192:195], v83, s[82:83]
	global_load_dwordx4 v[196:199], v99, s[82:83]
	global_load_dwordx4 v[200:203], v253, s[82:83]
	global_load_dwordx4 v[204:207], v254, s[82:83] offset:768
	global_load_dwordx4 v[208:211], v255, s[82:83] offset:768
	global_load_dwordx4 v[212:215], v254, s[82:83] offset:832
	global_load_dwordx4 v[216:219], v255, s[82:83] offset:832
	s_waitcnt lgkmcnt(0)
	v_mfma_f32_32x32x16_bf16 v[32:47], v[116:119], v[48:51], v[32:47]
	ds_read_b64_tr_b16 v[72:73], v231
	ds_read_b64_tr_b16 v[74:75], v231 offset:512
	ds_read_b64_tr_b16 v[76:77], v231 offset:2048
	ds_read_b64_tr_b16 v[78:79], v231 offset:2560
	ds_read_b64_tr_b16 v[220:221], v231 offset:1024
	ds_read_b64_tr_b16 v[222:223], v231 offset:1536
	ds_read_b64_tr_b16 v[224:225], v231 offset:3072
	ds_read_b64_tr_b16 v[226:227], v231 offset:3584
	s_waitcnt vmcnt(8)
	ds_write_b128 v247, v[156:159]
	ds_write_b128 v247, v[160:163] offset:1024
	ds_write_b128 v111, v[164:167] offset:2048
	ds_write_b128 v111, v[168:171] offset:3072
	ds_read_b128 v[156:159], v248
	ds_read_b128 v[160:163], v249
	ds_read_b128 v[164:167], v250
	ds_read_b128 v[168:171], v251
	ds_write_b128 v112, v[172:175]
	ds_write_b128 v112, v[176:179] offset:1024
	ds_write_b128 v112, v[180:183] offset:2048
	ds_write_b128 v112, v[184:187] offset:3072
	v_mfma_f32_32x32x16_bf16 v[32:47], v[120:123], v[52:55], v[32:47]
	v_mfma_f32_32x32x16_bf16 v[32:47], v[124:127], v[56:59], v[32:47]
	v_mfma_f32_32x32x16_bf16 v[32:47], v[128:131], v[60:63], v[32:47]
	s_nop 11
	v_exp_f32_e32 v32, v32
	v_exp_f32_e32 v33, v33
	v_exp_f32_e32 v34, v34
	v_exp_f32_e32 v35, v35
	v_exp_f32_e32 v36, v36
	v_exp_f32_e32 v37, v37
	v_exp_f32_e32 v38, v38
	v_exp_f32_e32 v39, v39
	v_exp_f32_e32 v40, v40
	v_exp_f32_e32 v41, v41
	v_exp_f32_e32 v42, v42
	v_exp_f32_e32 v43, v43
	v_exp_f32_e32 v44, v44
	v_exp_f32_e32 v45, v45
	v_exp_f32_e32 v46, v46
	v_exp_f32_e32 v47, v47
	s_add_i32 s90, s76, 416
	v_add_u32_e32 v84, s90, v107
	v_add_u32_e32 v85, 0, v84
	v_add_u32_e32 v86, 1, v84
	v_add_u32_e32 v87, 2, v84
	v_add_u32_e32 v88, 3, v84
	v_cmp_gt_u32_e64 s[30:31], s98, v85
	v_cmp_gt_u32_e64 s[36:37], s98, v86
	v_cmp_gt_u32_e64 s[78:79], s98, v87
	v_cmp_gt_u32_e64 s[50:51], s98, v88
	v_cndmask_b32_e64 v32, 0, v32, s[30:31]
	v_add_u32_e32 v85, 8, v84
	v_cmp_gt_u32_e64 s[30:31], s98, v85
	v_cndmask_b32_e64 v33, 0, v33, s[36:37]
	v_add_u32_e32 v86, 9, v84
	v_cmp_gt_u32_e64 s[36:37], s98, v86
	v_cndmask_b32_e64 v34, 0, v34, s[78:79]
	v_add_u32_e32 v87, 10, v84
	v_cmp_gt_u32_e64 s[78:79], s98, v87
	v_cndmask_b32_e64 v35, 0, v35, s[50:51]
	v_add_u32_e32 v88, 11, v84
	v_cmp_gt_u32_e64 s[50:51], s98, v88
	v_cndmask_b32_e64 v36, 0, v36, s[30:31]
	v_add_u32_e32 v85, 16, v84
	v_cmp_gt_u32_e64 s[30:31], s98, v85
	v_cndmask_b32_e64 v37, 0, v37, s[36:37]
	v_add_u32_e32 v86, 17, v84
	v_cmp_gt_u32_e64 s[36:37], s98, v86
	v_cndmask_b32_e64 v38, 0, v38, s[78:79]
	v_add_u32_e32 v87, 18, v84
	v_cmp_gt_u32_e64 s[78:79], s98, v87
	v_cndmask_b32_e64 v39, 0, v39, s[50:51]
	v_add_u32_e32 v88, 19, v84
	v_cmp_gt_u32_e64 s[50:51], s98, v88
	v_cndmask_b32_e64 v40, 0, v40, s[30:31]
	v_add_u32_e32 v85, 24, v84
	v_cmp_gt_u32_e64 s[30:31], s98, v85
	v_cndmask_b32_e64 v41, 0, v41, s[36:37]
	v_add_u32_e32 v86, 25, v84
	v_cmp_gt_u32_e64 s[36:37], s98, v86
	v_cndmask_b32_e64 v42, 0, v42, s[78:79]
	v_add_u32_e32 v87, 26, v84
	v_cmp_gt_u32_e64 s[78:79], s98, v87
	v_cndmask_b32_e64 v43, 0, v43, s[50:51]
	v_add_u32_e32 v88, 27, v84
	v_cmp_gt_u32_e64 s[50:51], s98, v88
	v_nop
	v_cndmask_b32_e64 v44, 0, v44, s[30:31]
	v_cndmask_b32_e64 v45, 0, v45, s[36:37]
	v_cndmask_b32_e64 v46, 0, v46, s[78:79]
	v_cndmask_b32_e64 v47, 0, v47, s[50:51]
	v_cvt_pk_bf16_f32 v64, v32, v33
	v_cvt_pk_bf16_f32 v65, v34, v35
	v_cvt_pk_bf16_f32 v66, v36, v37
	v_cvt_pk_bf16_f32 v67, v38, v39
	v_cvt_pk_bf16_f32 v68, v40, v41
	v_cvt_pk_bf16_f32 v69, v42, v43
	v_cvt_pk_bf16_f32 v70, v44, v45
	v_cvt_pk_bf16_f32 v71, v46, v47
	v_pk_add_f32 v[232:233], v[232:233], v[32:33]
	v_pk_add_f32 v[232:233], v[232:233], v[34:35]
	v_pk_add_f32 v[232:233], v[232:233], v[36:37]
	v_pk_add_f32 v[232:233], v[232:233], v[38:39]
	v_pk_add_f32 v[232:233], v[232:233], v[40:41]
	v_pk_add_f32 v[232:233], v[232:233], v[42:43]
	v_pk_add_f32 v[232:233], v[232:233], v[44:45]
	v_pk_add_f32 v[232:233], v[232:233], v[46:47]
	ds_read2_b32 v[32:33], v115 offset0:68 offset1:69
	ds_read2_b32 v[34:35], v115 offset0:70 offset1:71
	ds_read2_b32 v[36:37], v115 offset0:76 offset1:77
	ds_read2_b32 v[38:39], v115 offset0:78 offset1:79
	ds_read2_b32 v[40:41], v115 offset0:85 offset1:86
	ds_read2_b32 v[42:43], v115 offset0:87 offset1:88
	ds_read2_b32 v[44:45], v115 offset0:93 offset1:94
	ds_read2_b32 v[46:47], v115 offset0:95 offset1:96
	s_waitcnt lgkmcnt(15)
	v_mfma_f32_32x32x16_bf16 v[0:15], v[64:67], v[72:75], v[0:15]
	v_mfma_f32_32x32x16_bf16 v[16:31], v[64:67], v[76:79], v[16:31]
	v_mfma_f32_32x32x16_bf16 v[0:15], v[68:71], v[220:223], v[0:15]
	v_mfma_f32_32x32x16_bf16 v[16:31], v[68:71], v[224:227], v[16:31]
	s_add_i32 s90, s76, 512
	v_add_u32_e32 v80, s90, v235
	v_add_u32_e32 v83, s90, v236
	v_add_u32_e32 v99, s90, v237
	v_add_u32_e32 v253, s90, v238
	v_add_u32_e32 v254, s90, v100
	v_add_u32_e32 v255, s90, v149
	v_med3_i32 v80, v80, 0, s99
	v_med3_i32 v83, v83, 0, s99
	v_med3_i32 v99, v99, 0, s99
	v_med3_i32 v253, v253, 0, s99
	v_med3_i32 v254, v254, 0, s99
	v_med3_i32 v255, v255, 0, s99
	v_mad_u32_u24 v80, v80, s100, v252
	v_mad_u32_u24 v83, v83, s100, v252
	v_mad_u32_u24 v99, v99, s100, v252
	v_mad_u32_u24 v253, v253, s100, v252
	v_mad_u32_u24 v254, v254, s100, v153
	v_mad_u32_u24 v255, v255, s100, v153
	global_load_dwordx4 v[116:119], v80, s[82:83]
	global_load_dwordx4 v[120:123], v83, s[82:83]
	global_load_dwordx4 v[124:127], v99, s[82:83]
	global_load_dwordx4 v[128:131], v253, s[82:83]
	global_load_dwordx4 v[132:135], v254, s[82:83] offset:768
	global_load_dwordx4 v[136:139], v255, s[82:83] offset:768
	global_load_dwordx4 v[140:143], v254, s[82:83] offset:832
	global_load_dwordx4 v[144:147], v255, s[82:83] offset:832
	s_waitcnt lgkmcnt(0)
	v_mfma_f32_32x32x16_bf16 v[32:47], v[156:159], v[48:51], v[32:47]
	ds_read_b64_tr_b16 v[72:73], v231
	ds_read_b64_tr_b16 v[74:75], v231 offset:512
	ds_read_b64_tr_b16 v[76:77], v231 offset:2048
	ds_read_b64_tr_b16 v[78:79], v231 offset:2560
	ds_read_b64_tr_b16 v[220:221], v231 offset:1024
	ds_read_b64_tr_b16 v[222:223], v231 offset:1536
	ds_read_b64_tr_b16 v[224:225], v231 offset:3072
	ds_read_b64_tr_b16 v[226:227], v231 offset:3584
	s_waitcnt vmcnt(8)
	ds_write_b128 v247, v[188:191]
	ds_write_b128 v247, v[192:195] offset:1024
	ds_write_b128 v111, v[196:199] offset:2048
	ds_write_b128 v111, v[200:203] offset:3072
	ds_read_b128 v[188:191], v248
	ds_read_b128 v[192:195], v249
	ds_read_b128 v[196:199], v250
	ds_read_b128 v[200:203], v251
	ds_write_b128 v112, v[204:207]
	ds_write_b128 v112, v[208:211] offset:1024
	ds_write_b128 v112, v[212:215] offset:2048
	ds_write_b128 v112, v[216:219] offset:3072
	v_mfma_f32_32x32x16_bf16 v[32:47], v[160:163], v[52:55], v[32:47]
	v_mfma_f32_32x32x16_bf16 v[32:47], v[164:167], v[56:59], v[32:47]
	v_mfma_f32_32x32x16_bf16 v[32:47], v[168:171], v[60:63], v[32:47]
	s_nop 11
	v_exp_f32_e32 v32, v32
	v_exp_f32_e32 v33, v33
	v_exp_f32_e32 v34, v34
	v_exp_f32_e32 v35, v35
	v_exp_f32_e32 v36, v36
	v_exp_f32_e32 v37, v37
	v_exp_f32_e32 v38, v38
	v_exp_f32_e32 v39, v39
	v_exp_f32_e32 v40, v40
	v_exp_f32_e32 v41, v41
	v_exp_f32_e32 v42, v42
	v_exp_f32_e32 v43, v43
	v_exp_f32_e32 v44, v44
	v_exp_f32_e32 v45, v45
	v_exp_f32_e32 v46, v46
	v_exp_f32_e32 v47, v47
	s_add_i32 s90, s76, 448
	v_add_u32_e32 v84, s90, v107
	v_add_u32_e32 v85, 0, v84
	v_add_u32_e32 v86, 1, v84
	v_add_u32_e32 v87, 2, v84
	v_add_u32_e32 v88, 3, v84
	v_cmp_gt_u32_e64 s[30:31], s98, v85
	v_cmp_gt_u32_e64 s[36:37], s98, v86
	v_cmp_gt_u32_e64 s[78:79], s98, v87
	v_cmp_gt_u32_e64 s[50:51], s98, v88
	v_cndmask_b32_e64 v32, 0, v32, s[30:31]
	v_add_u32_e32 v85, 8, v84
	v_cmp_gt_u32_e64 s[30:31], s98, v85
	v_cndmask_b32_e64 v33, 0, v33, s[36:37]
	v_add_u32_e32 v86, 9, v84
	v_cmp_gt_u32_e64 s[36:37], s98, v86
	v_cndmask_b32_e64 v34, 0, v34, s[78:79]
	v_add_u32_e32 v87, 10, v84
	v_cmp_gt_u32_e64 s[78:79], s98, v87
	v_cndmask_b32_e64 v35, 0, v35, s[50:51]
	v_add_u32_e32 v88, 11, v84
	v_cmp_gt_u32_e64 s[50:51], s98, v88
	v_cndmask_b32_e64 v36, 0, v36, s[30:31]
	v_add_u32_e32 v85, 16, v84
	v_cmp_gt_u32_e64 s[30:31], s98, v85
	v_cndmask_b32_e64 v37, 0, v37, s[36:37]
	v_add_u32_e32 v86, 17, v84
	v_cmp_gt_u32_e64 s[36:37], s98, v86
	v_cndmask_b32_e64 v38, 0, v38, s[78:79]
	v_add_u32_e32 v87, 18, v84
	v_cmp_gt_u32_e64 s[78:79], s98, v87
	v_cndmask_b32_e64 v39, 0, v39, s[50:51]
	v_add_u32_e32 v88, 19, v84
	v_cmp_gt_u32_e64 s[50:51], s98, v88
	v_cndmask_b32_e64 v40, 0, v40, s[30:31]
	v_add_u32_e32 v85, 24, v84
	v_cmp_gt_u32_e64 s[30:31], s98, v85
	v_cndmask_b32_e64 v41, 0, v41, s[36:37]
	v_add_u32_e32 v86, 25, v84
	v_cmp_gt_u32_e64 s[36:37], s98, v86
	v_cndmask_b32_e64 v42, 0, v42, s[78:79]
	v_add_u32_e32 v87, 26, v84
	v_cmp_gt_u32_e64 s[78:79], s98, v87
	v_cndmask_b32_e64 v43, 0, v43, s[50:51]
	v_add_u32_e32 v88, 27, v84
	v_cmp_gt_u32_e64 s[50:51], s98, v88
	v_nop
	v_cndmask_b32_e64 v44, 0, v44, s[30:31]
	v_cndmask_b32_e64 v45, 0, v45, s[36:37]
	v_cndmask_b32_e64 v46, 0, v46, s[78:79]
	v_cndmask_b32_e64 v47, 0, v47, s[50:51]
	v_cvt_pk_bf16_f32 v64, v32, v33
	v_cvt_pk_bf16_f32 v65, v34, v35
	v_cvt_pk_bf16_f32 v66, v36, v37
	v_cvt_pk_bf16_f32 v67, v38, v39
	v_cvt_pk_bf16_f32 v68, v40, v41
	v_cvt_pk_bf16_f32 v69, v42, v43
	v_cvt_pk_bf16_f32 v70, v44, v45
	v_cvt_pk_bf16_f32 v71, v46, v47
	v_pk_add_f32 v[232:233], v[232:233], v[32:33]
	v_pk_add_f32 v[232:233], v[232:233], v[34:35]
	v_pk_add_f32 v[232:233], v[232:233], v[36:37]
	v_pk_add_f32 v[232:233], v[232:233], v[38:39]
	v_pk_add_f32 v[232:233], v[232:233], v[40:41]
	v_pk_add_f32 v[232:233], v[232:233], v[42:43]
	v_pk_add_f32 v[232:233], v[232:233], v[44:45]
	v_pk_add_f32 v[232:233], v[232:233], v[46:47]
	ds_read2_b32 v[32:33], v115 offset0:102 offset1:103
	ds_read2_b32 v[34:35], v115 offset0:104 offset1:105
	ds_read2_b32 v[36:37], v115 offset0:110 offset1:111
	ds_read2_b32 v[38:39], v115 offset0:112 offset1:113
	ds_read2_b32 v[40:41], v115 offset0:119 offset1:120
	ds_read2_b32 v[42:43], v115 offset0:121 offset1:122
	ds_read2_b32 v[44:45], v115 offset0:127 offset1:128
	ds_read2_b32 v[46:47], v115 offset0:129 offset1:130
	s_waitcnt lgkmcnt(15)
	v_mfma_f32_32x32x16_bf16 v[0:15], v[64:67], v[72:75], v[0:15]
	v_mfma_f32_32x32x16_bf16 v[16:31], v[64:67], v[76:79], v[16:31]
	v_mfma_f32_32x32x16_bf16 v[0:15], v[68:71], v[220:223], v[0:15]
	v_mfma_f32_32x32x16_bf16 v[16:31], v[68:71], v[224:227], v[16:31]
	s_add_i32 s90, s76, 544
	v_add_u32_e32 v80, s90, v235
	v_add_u32_e32 v83, s90, v236
	v_add_u32_e32 v99, s90, v237
	v_add_u32_e32 v253, s90, v238
	v_add_u32_e32 v254, s90, v100
	v_add_u32_e32 v255, s90, v149
	v_med3_i32 v80, v80, 0, s99
	v_med3_i32 v83, v83, 0, s99
	v_med3_i32 v99, v99, 0, s99
	v_med3_i32 v253, v253, 0, s99
	v_med3_i32 v254, v254, 0, s99
	v_med3_i32 v255, v255, 0, s99
	v_mad_u32_u24 v80, v80, s100, v252
	v_mad_u32_u24 v83, v83, s100, v252
	v_mad_u32_u24 v99, v99, s100, v252
	v_mad_u32_u24 v253, v253, s100, v252
	v_mad_u32_u24 v254, v254, s100, v153
	v_mad_u32_u24 v255, v255, s100, v153
	global_load_dwordx4 v[156:159], v80, s[82:83]
	global_load_dwordx4 v[160:163], v83, s[82:83]
	global_load_dwordx4 v[164:167], v99, s[82:83]
	global_load_dwordx4 v[168:171], v253, s[82:83]
	global_load_dwordx4 v[172:175], v254, s[82:83] offset:768
	global_load_dwordx4 v[176:179], v255, s[82:83] offset:768
	global_load_dwordx4 v[180:183], v254, s[82:83] offset:832
	global_load_dwordx4 v[184:187], v255, s[82:83] offset:832
	s_waitcnt lgkmcnt(0)
	v_mfma_f32_32x32x16_bf16 v[32:47], v[188:191], v[48:51], v[32:47]
	ds_read_b64_tr_b16 v[72:73], v231
	ds_read_b64_tr_b16 v[74:75], v231 offset:512
	ds_read_b64_tr_b16 v[76:77], v231 offset:2048
	ds_read_b64_tr_b16 v[78:79], v231 offset:2560
	ds_read_b64_tr_b16 v[220:221], v231 offset:1024
	ds_read_b64_tr_b16 v[222:223], v231 offset:1536
	ds_read_b64_tr_b16 v[224:225], v231 offset:3072
	ds_read_b64_tr_b16 v[226:227], v231 offset:3584
	s_waitcnt vmcnt(8)
	ds_write_b128 v247, v[116:119]
	ds_write_b128 v247, v[120:123] offset:1024
	ds_write_b128 v111, v[124:127] offset:2048
	ds_write_b128 v111, v[128:131] offset:3072
	ds_read_b128 v[116:119], v248
	ds_read_b128 v[120:123], v249
	ds_read_b128 v[124:127], v250
	ds_read_b128 v[128:131], v251
	ds_write_b128 v112, v[132:135]
	ds_write_b128 v112, v[136:139] offset:1024
	ds_write_b128 v112, v[140:143] offset:2048
	ds_write_b128 v112, v[144:147] offset:3072
	v_mfma_f32_32x32x16_bf16 v[32:47], v[192:195], v[52:55], v[32:47]
	v_mfma_f32_32x32x16_bf16 v[32:47], v[196:199], v[56:59], v[32:47]
	v_mfma_f32_32x32x16_bf16 v[32:47], v[200:203], v[60:63], v[32:47]
	s_nop 11
	v_exp_f32_e32 v32, v32
	v_exp_f32_e32 v33, v33
	v_exp_f32_e32 v34, v34
	v_exp_f32_e32 v35, v35
	v_exp_f32_e32 v36, v36
	v_exp_f32_e32 v37, v37
	v_exp_f32_e32 v38, v38
	v_exp_f32_e32 v39, v39
	v_exp_f32_e32 v40, v40
	v_exp_f32_e32 v41, v41
	v_exp_f32_e32 v42, v42
	v_exp_f32_e32 v43, v43
	v_exp_f32_e32 v44, v44
	v_exp_f32_e32 v45, v45
	v_exp_f32_e32 v46, v46
	v_exp_f32_e32 v47, v47
	s_add_i32 s90, s76, 480
	v_add_u32_e32 v84, s90, v107
	v_add_u32_e32 v85, 0, v84
	v_add_u32_e32 v86, 1, v84
	v_add_u32_e32 v87, 2, v84
	v_add_u32_e32 v88, 3, v84
	v_cmp_gt_u32_e64 s[30:31], s98, v85
	v_cmp_gt_u32_e64 s[36:37], s98, v86
	v_cmp_gt_u32_e64 s[78:79], s98, v87
	v_cmp_gt_u32_e64 s[50:51], s98, v88
	v_cndmask_b32_e64 v32, 0, v32, s[30:31]
	v_add_u32_e32 v85, 8, v84
	v_cmp_gt_u32_e64 s[30:31], s98, v85
	v_cndmask_b32_e64 v33, 0, v33, s[36:37]
	v_add_u32_e32 v86, 9, v84
	v_cmp_gt_u32_e64 s[36:37], s98, v86
	v_cndmask_b32_e64 v34, 0, v34, s[78:79]
	v_add_u32_e32 v87, 10, v84
	v_cmp_gt_u32_e64 s[78:79], s98, v87
	v_cndmask_b32_e64 v35, 0, v35, s[50:51]
	v_add_u32_e32 v88, 11, v84
	v_cmp_gt_u32_e64 s[50:51], s98, v88
	v_cndmask_b32_e64 v36, 0, v36, s[30:31]
	v_add_u32_e32 v85, 16, v84
	v_cmp_gt_u32_e64 s[30:31], s98, v85
	v_cndmask_b32_e64 v37, 0, v37, s[36:37]
	v_add_u32_e32 v86, 17, v84
	v_cmp_gt_u32_e64 s[36:37], s98, v86
	v_cndmask_b32_e64 v38, 0, v38, s[78:79]
	v_add_u32_e32 v87, 18, v84
	v_cmp_gt_u32_e64 s[78:79], s98, v87
	v_cndmask_b32_e64 v39, 0, v39, s[50:51]
	v_add_u32_e32 v88, 19, v84
	v_cmp_gt_u32_e64 s[50:51], s98, v88
	v_cndmask_b32_e64 v40, 0, v40, s[30:31]
	v_add_u32_e32 v85, 24, v84
	v_cmp_gt_u32_e64 s[30:31], s98, v85
	v_cndmask_b32_e64 v41, 0, v41, s[36:37]
	v_add_u32_e32 v86, 25, v84
	v_cmp_gt_u32_e64 s[36:37], s98, v86
	v_cndmask_b32_e64 v42, 0, v42, s[78:79]
	v_add_u32_e32 v87, 26, v84
	v_cmp_gt_u32_e64 s[78:79], s98, v87
	v_cndmask_b32_e64 v43, 0, v43, s[50:51]
	v_add_u32_e32 v88, 27, v84
	v_cmp_gt_u32_e64 s[50:51], s98, v88
	v_nop
	v_cndmask_b32_e64 v44, 0, v44, s[30:31]
	v_cndmask_b32_e64 v45, 0, v45, s[36:37]
	v_cndmask_b32_e64 v46, 0, v46, s[78:79]
	v_cndmask_b32_e64 v47, 0, v47, s[50:51]
	v_cvt_pk_bf16_f32 v64, v32, v33
	v_cvt_pk_bf16_f32 v65, v34, v35
	v_cvt_pk_bf16_f32 v66, v36, v37
	v_cvt_pk_bf16_f32 v67, v38, v39
	v_cvt_pk_bf16_f32 v68, v40, v41
	v_cvt_pk_bf16_f32 v69, v42, v43
	v_cvt_pk_bf16_f32 v70, v44, v45
	v_cvt_pk_bf16_f32 v71, v46, v47
	v_pk_add_f32 v[232:233], v[232:233], v[32:33]
	v_pk_add_f32 v[232:233], v[232:233], v[34:35]
	v_pk_add_f32 v[232:233], v[232:233], v[36:37]
	v_pk_add_f32 v[232:233], v[232:233], v[38:39]
	v_pk_add_f32 v[232:233], v[232:233], v[40:41]
	v_pk_add_f32 v[232:233], v[232:233], v[42:43]
	v_pk_add_f32 v[232:233], v[232:233], v[44:45]
	v_pk_add_f32 v[232:233], v[232:233], v[46:47]
	ds_read2_b32 v[32:33], v115 offset0:136 offset1:137
	ds_read2_b32 v[34:35], v115 offset0:138 offset1:139
	ds_read2_b32 v[36:37], v115 offset0:144 offset1:145
	ds_read2_b32 v[38:39], v115 offset0:146 offset1:147
	ds_read2_b32 v[40:41], v115 offset0:153 offset1:154
	ds_read2_b32 v[42:43], v115 offset0:155 offset1:156
	ds_read2_b32 v[44:45], v115 offset0:161 offset1:162
	ds_read2_b32 v[46:47], v115 offset0:163 offset1:164
	s_waitcnt lgkmcnt(15)
	v_mfma_f32_32x32x16_bf16 v[0:15], v[64:67], v[72:75], v[0:15]
	v_mfma_f32_32x32x16_bf16 v[16:31], v[64:67], v[76:79], v[16:31]
	v_mfma_f32_32x32x16_bf16 v[0:15], v[68:71], v[220:223], v[0:15]
	v_mfma_f32_32x32x16_bf16 v[16:31], v[68:71], v[224:227], v[16:31]
	s_add_i32 s90, s76, -256
	v_add_u32_e32 v80, s90, v239
	v_add_u32_e32 v83, s90, v240
	v_add_u32_e32 v99, s90, v241
	v_add_u32_e32 v253, s90, v242
	v_add_u32_e32 v254, s90, v101
	v_add_u32_e32 v255, s90, v150
	v_med3_i32 v80, v80, 0, s99
	v_med3_i32 v83, v83, 0, s99
	v_med3_i32 v99, v99, 0, s99
	v_med3_i32 v253, v253, 0, s99
	v_med3_i32 v254, v254, 0, s99
	v_med3_i32 v255, v255, 0, s99
	v_mad_u32_u24 v80, v80, s100, v252
	v_mad_u32_u24 v83, v83, s100, v252
	v_mad_u32_u24 v99, v99, s100, v252
	v_mad_u32_u24 v253, v253, s100, v252
	v_mad_u32_u24 v254, v254, s100, v153
	v_mad_u32_u24 v255, v255, s100, v153
	global_load_dwordx4 v[188:191], v80, s[82:83]
	global_load_dwordx4 v[192:195], v83, s[82:83]
	global_load_dwordx4 v[196:199], v99, s[82:83]
	global_load_dwordx4 v[200:203], v253, s[82:83]
	global_load_dwordx4 v[204:207], v254, s[82:83] offset:768
	global_load_dwordx4 v[208:211], v255, s[82:83] offset:768
	global_load_dwordx4 v[212:215], v254, s[82:83] offset:832
	global_load_dwordx4 v[216:219], v255, s[82:83] offset:832
	s_waitcnt lgkmcnt(0)
	v_mfma_f32_32x32x16_bf16 v[32:47], v[116:119], v[48:51], v[32:47]
	ds_read_b64_tr_b16 v[72:73], v231
	ds_read_b64_tr_b16 v[74:75], v231 offset:512
	ds_read_b64_tr_b16 v[76:77], v231 offset:2048
	ds_read_b64_tr_b16 v[78:79], v231 offset:2560
	ds_read_b64_tr_b16 v[220:221], v231 offset:1024
	ds_read_b64_tr_b16 v[222:223], v231 offset:1536
	ds_read_b64_tr_b16 v[224:225], v231 offset:3072
	ds_read_b64_tr_b16 v[226:227], v231 offset:3584
	s_waitcnt vmcnt(8)
	ds_write_b128 v247, v[156:159]
	ds_write_b128 v247, v[160:163] offset:1024
	ds_write_b128 v111, v[164:167] offset:2048
	ds_write_b128 v111, v[168:171] offset:3072
	ds_read_b128 v[156:159], v248
	ds_read_b128 v[160:163], v249
	ds_read_b128 v[164:167], v250
	ds_read_b128 v[168:171], v251
	ds_write_b128 v112, v[172:175]
	ds_write_b128 v112, v[176:179] offset:1024
	ds_write_b128 v112, v[180:183] offset:2048
	ds_write_b128 v112, v[184:187] offset:3072
	v_mfma_f32_32x32x16_bf16 v[32:47], v[120:123], v[52:55], v[32:47]
	v_mfma_f32_32x32x16_bf16 v[32:47], v[124:127], v[56:59], v[32:47]
	v_mfma_f32_32x32x16_bf16 v[32:47], v[128:131], v[60:63], v[32:47]
	s_nop 11
	v_exp_f32_e32 v32, v32
	v_exp_f32_e32 v33, v33
	v_exp_f32_e32 v34, v34
	v_exp_f32_e32 v35, v35
	v_exp_f32_e32 v36, v36
	v_exp_f32_e32 v37, v37
	v_exp_f32_e32 v38, v38
	v_exp_f32_e32 v39, v39
	v_exp_f32_e32 v40, v40
	v_exp_f32_e32 v41, v41
	v_exp_f32_e32 v42, v42
	v_exp_f32_e32 v43, v43
	v_exp_f32_e32 v44, v44
	v_exp_f32_e32 v45, v45
	v_exp_f32_e32 v46, v46
	v_exp_f32_e32 v47, v47
	s_add_i32 s90, s76, 512
	v_add_u32_e32 v84, s90, v107
	v_add_u32_e32 v85, 0, v84
	v_add_u32_e32 v86, 1, v84
	v_add_u32_e32 v87, 2, v84
	v_add_u32_e32 v88, 3, v84
	v_cmp_gt_u32_e64 s[30:31], s98, v85
	v_cmp_gt_u32_e64 s[36:37], s98, v86
	v_cmp_gt_u32_e64 s[78:79], s98, v87
	v_cmp_gt_u32_e64 s[50:51], s98, v88
	v_cndmask_b32_e64 v32, 0, v32, s[30:31]
	v_add_u32_e32 v85, 8, v84
	v_cmp_gt_u32_e64 s[30:31], s98, v85
	v_cndmask_b32_e64 v33, 0, v33, s[36:37]
	v_add_u32_e32 v86, 9, v84
	v_cmp_gt_u32_e64 s[36:37], s98, v86
	v_cndmask_b32_e64 v34, 0, v34, s[78:79]
	v_add_u32_e32 v87, 10, v84
	v_cmp_gt_u32_e64 s[78:79], s98, v87
	v_cndmask_b32_e64 v35, 0, v35, s[50:51]
	v_add_u32_e32 v88, 11, v84
	v_cmp_gt_u32_e64 s[50:51], s98, v88
	v_cndmask_b32_e64 v36, 0, v36, s[30:31]
	v_add_u32_e32 v85, 16, v84
	v_cmp_gt_u32_e64 s[30:31], s98, v85
	v_cndmask_b32_e64 v37, 0, v37, s[36:37]
	v_add_u32_e32 v86, 17, v84
	v_cmp_gt_u32_e64 s[36:37], s98, v86
	v_cndmask_b32_e64 v38, 0, v38, s[78:79]
	v_add_u32_e32 v87, 18, v84
	v_cmp_gt_u32_e64 s[78:79], s98, v87
	v_cndmask_b32_e64 v39, 0, v39, s[50:51]
	v_add_u32_e32 v88, 19, v84
	v_cmp_gt_u32_e64 s[50:51], s98, v88
	v_cndmask_b32_e64 v40, 0, v40, s[30:31]
	v_add_u32_e32 v85, 24, v84
	v_cmp_gt_u32_e64 s[30:31], s98, v85
	v_cndmask_b32_e64 v41, 0, v41, s[36:37]
	v_add_u32_e32 v86, 25, v84
	v_cmp_gt_u32_e64 s[36:37], s98, v86
	v_cndmask_b32_e64 v42, 0, v42, s[78:79]
	v_add_u32_e32 v87, 26, v84
	v_cmp_gt_u32_e64 s[78:79], s98, v87
	v_cndmask_b32_e64 v43, 0, v43, s[50:51]
	v_add_u32_e32 v88, 27, v84
	v_cmp_gt_u32_e64 s[50:51], s98, v88
	v_nop
	v_cndmask_b32_e64 v44, 0, v44, s[30:31]
	v_cndmask_b32_e64 v45, 0, v45, s[36:37]
	v_cndmask_b32_e64 v46, 0, v46, s[78:79]
	v_cndmask_b32_e64 v47, 0, v47, s[50:51]
	v_cvt_pk_bf16_f32 v64, v32, v33
	v_cvt_pk_bf16_f32 v65, v34, v35
	v_cvt_pk_bf16_f32 v66, v36, v37
	v_cvt_pk_bf16_f32 v67, v38, v39
	v_cvt_pk_bf16_f32 v68, v40, v41
	v_cvt_pk_bf16_f32 v69, v42, v43
	v_cvt_pk_bf16_f32 v70, v44, v45
	v_cvt_pk_bf16_f32 v71, v46, v47
	v_pk_add_f32 v[232:233], v[232:233], v[32:33]
	v_pk_add_f32 v[232:233], v[232:233], v[34:35]
	v_pk_add_f32 v[232:233], v[232:233], v[36:37]
	v_pk_add_f32 v[232:233], v[232:233], v[38:39]
	v_pk_add_f32 v[232:233], v[232:233], v[40:41]
	v_pk_add_f32 v[232:233], v[232:233], v[42:43]
	v_pk_add_f32 v[232:233], v[232:233], v[44:45]
	v_pk_add_f32 v[232:233], v[232:233], v[46:47]
	ds_read2_b32 v[32:33], v115 offset0:170 offset1:171
	ds_read2_b32 v[34:35], v115 offset0:172 offset1:173
	ds_read2_b32 v[36:37], v115 offset0:178 offset1:179
	ds_read2_b32 v[38:39], v115 offset0:180 offset1:181
	ds_read2_b32 v[40:41], v115 offset0:187 offset1:188
	ds_read2_b32 v[42:43], v115 offset0:189 offset1:190
	ds_read2_b32 v[44:45], v115 offset0:195 offset1:196
	ds_read2_b32 v[46:47], v115 offset0:197 offset1:198
	s_waitcnt lgkmcnt(15)
	v_mfma_f32_32x32x16_bf16 v[0:15], v[64:67], v[72:75], v[0:15]
	v_mfma_f32_32x32x16_bf16 v[16:31], v[64:67], v[76:79], v[16:31]
	v_mfma_f32_32x32x16_bf16 v[0:15], v[68:71], v[220:223], v[0:15]
	v_mfma_f32_32x32x16_bf16 v[16:31], v[68:71], v[224:227], v[16:31]
	s_add_i32 s90, s76, -128
	v_add_u32_e32 v80, s90, v239
	v_add_u32_e32 v83, s90, v240
	v_add_u32_e32 v99, s90, v241
	v_add_u32_e32 v253, s90, v242
	v_add_u32_e32 v254, s90, v101
	v_add_u32_e32 v255, s90, v150
	v_med3_i32 v80, v80, 0, s99
	v_med3_i32 v83, v83, 0, s99
	v_med3_i32 v99, v99, 0, s99
	v_med3_i32 v253, v253, 0, s99
	v_med3_i32 v254, v254, 0, s99
	v_med3_i32 v255, v255, 0, s99
	v_mad_u32_u24 v80, v80, s100, v252
	v_mad_u32_u24 v83, v83, s100, v252
	v_mad_u32_u24 v99, v99, s100, v252
	v_mad_u32_u24 v253, v253, s100, v252
	v_mad_u32_u24 v254, v254, s100, v153
	v_mad_u32_u24 v255, v255, s100, v153
	global_load_dwordx4 v[116:119], v80, s[82:83]
	global_load_dwordx4 v[120:123], v83, s[82:83]
	global_load_dwordx4 v[124:127], v99, s[82:83]
	global_load_dwordx4 v[128:131], v253, s[82:83]
	global_load_dwordx4 v[132:135], v254, s[82:83] offset:768
	global_load_dwordx4 v[136:139], v255, s[82:83] offset:768
	global_load_dwordx4 v[140:143], v254, s[82:83] offset:832
	global_load_dwordx4 v[144:147], v255, s[82:83] offset:832
	s_waitcnt lgkmcnt(0)
	v_mfma_f32_32x32x16_bf16 v[32:47], v[156:159], v[48:51], v[32:47]
	ds_read_b64_tr_b16 v[72:73], v231
	ds_read_b64_tr_b16 v[74:75], v231 offset:512
	ds_read_b64_tr_b16 v[76:77], v231 offset:2048
	ds_read_b64_tr_b16 v[78:79], v231 offset:2560
	ds_read_b64_tr_b16 v[220:221], v231 offset:1024
	ds_read_b64_tr_b16 v[222:223], v231 offset:1536
	ds_read_b64_tr_b16 v[224:225], v231 offset:3072
	ds_read_b64_tr_b16 v[226:227], v231 offset:3584
	s_waitcnt vmcnt(8)
	ds_write_b128 v247, v[188:191]
	ds_write_b128 v247, v[192:195] offset:1024
	ds_write_b128 v111, v[196:199] offset:2048
	ds_write_b128 v111, v[200:203] offset:3072
	ds_read_b128 v[188:191], v248
	ds_read_b128 v[192:195], v249
	ds_read_b128 v[196:199], v250
	ds_read_b128 v[200:203], v251
	ds_write_b128 v112, v[204:207]
	ds_write_b128 v112, v[208:211] offset:1024
	ds_write_b128 v112, v[212:215] offset:2048
	ds_write_b128 v112, v[216:219] offset:3072
	v_mfma_f32_32x32x16_bf16 v[32:47], v[160:163], v[52:55], v[32:47]
	v_mfma_f32_32x32x16_bf16 v[32:47], v[164:167], v[56:59], v[32:47]
	v_mfma_f32_32x32x16_bf16 v[32:47], v[168:171], v[60:63], v[32:47]
	s_nop 11
	v_exp_f32_e32 v32, v32
	v_exp_f32_e32 v33, v33
	v_exp_f32_e32 v34, v34
	v_exp_f32_e32 v35, v35
	v_exp_f32_e32 v36, v36
	v_exp_f32_e32 v37, v37
	v_exp_f32_e32 v38, v38
	v_exp_f32_e32 v39, v39
	v_exp_f32_e32 v40, v40
	v_exp_f32_e32 v41, v41
	v_exp_f32_e32 v42, v42
	v_exp_f32_e32 v43, v43
	v_exp_f32_e32 v44, v44
	v_exp_f32_e32 v45, v45
	v_exp_f32_e32 v46, v46
	v_exp_f32_e32 v47, v47
	s_add_i32 s90, s76, 544
	v_add_u32_e32 v84, s90, v107
	v_add_u32_e32 v85, 0, v84
	v_add_u32_e32 v86, 1, v84
	v_add_u32_e32 v87, 2, v84
	v_add_u32_e32 v88, 3, v84
	v_cmp_gt_u32_e64 s[30:31], s98, v85
	v_cmp_gt_u32_e64 s[36:37], s98, v86
	v_cmp_gt_u32_e64 s[78:79], s98, v87
	v_cmp_gt_u32_e64 s[50:51], s98, v88
	v_cndmask_b32_e64 v32, 0, v32, s[30:31]
	v_add_u32_e32 v85, 8, v84
	v_cmp_gt_u32_e64 s[30:31], s98, v85
	v_cndmask_b32_e64 v33, 0, v33, s[36:37]
	v_add_u32_e32 v86, 9, v84
	v_cmp_gt_u32_e64 s[36:37], s98, v86
	v_cndmask_b32_e64 v34, 0, v34, s[78:79]
	v_add_u32_e32 v87, 10, v84
	v_cmp_gt_u32_e64 s[78:79], s98, v87
	v_cndmask_b32_e64 v35, 0, v35, s[50:51]
	v_add_u32_e32 v88, 11, v84
	v_cmp_gt_u32_e64 s[50:51], s98, v88
	v_cndmask_b32_e64 v36, 0, v36, s[30:31]
	v_add_u32_e32 v85, 16, v84
	v_cmp_gt_u32_e64 s[30:31], s98, v85
	v_cndmask_b32_e64 v37, 0, v37, s[36:37]
	v_add_u32_e32 v86, 17, v84
	v_cmp_gt_u32_e64 s[36:37], s98, v86
	v_cndmask_b32_e64 v38, 0, v38, s[78:79]
	v_add_u32_e32 v87, 18, v84
	v_cmp_gt_u32_e64 s[78:79], s98, v87
	v_cndmask_b32_e64 v39, 0, v39, s[50:51]
	v_add_u32_e32 v88, 19, v84
	v_cmp_gt_u32_e64 s[50:51], s98, v88
	v_cndmask_b32_e64 v40, 0, v40, s[30:31]
	v_add_u32_e32 v85, 24, v84
	v_cmp_gt_u32_e64 s[30:31], s98, v85
	v_cndmask_b32_e64 v41, 0, v41, s[36:37]
	v_add_u32_e32 v86, 25, v84
	v_cmp_gt_u32_e64 s[36:37], s98, v86
	v_cndmask_b32_e64 v42, 0, v42, s[78:79]
	v_add_u32_e32 v87, 26, v84
	v_cmp_gt_u32_e64 s[78:79], s98, v87
	v_cndmask_b32_e64 v43, 0, v43, s[50:51]
	v_add_u32_e32 v88, 27, v84
	v_cmp_gt_u32_e64 s[50:51], s98, v88
	v_nop
	v_cndmask_b32_e64 v44, 0, v44, s[30:31]
	v_cndmask_b32_e64 v45, 0, v45, s[36:37]
	v_cndmask_b32_e64 v46, 0, v46, s[78:79]
	v_cndmask_b32_e64 v47, 0, v47, s[50:51]
	v_cvt_pk_bf16_f32 v64, v32, v33
	v_cvt_pk_bf16_f32 v65, v34, v35
	v_cvt_pk_bf16_f32 v66, v36, v37
	v_cvt_pk_bf16_f32 v67, v38, v39
	v_cvt_pk_bf16_f32 v68, v40, v41
	v_cvt_pk_bf16_f32 v69, v42, v43
	v_cvt_pk_bf16_f32 v70, v44, v45
	v_cvt_pk_bf16_f32 v71, v46, v47
	v_pk_add_f32 v[232:233], v[232:233], v[32:33]
	v_pk_add_f32 v[232:233], v[232:233], v[34:35]
	v_pk_add_f32 v[232:233], v[232:233], v[36:37]
	v_pk_add_f32 v[232:233], v[232:233], v[38:39]
	v_pk_add_f32 v[232:233], v[232:233], v[40:41]
	v_pk_add_f32 v[232:233], v[232:233], v[42:43]
	v_pk_add_f32 v[232:233], v[232:233], v[44:45]
	v_pk_add_f32 v[232:233], v[232:233], v[46:47]
	v_mov_b32_e32 v115, v229
	ds_read2_b32 v[32:33], v115 offset0:0 offset1:1
	ds_read2_b32 v[34:35], v115 offset0:2 offset1:3
	ds_read2_b32 v[36:37], v115 offset0:10 offset1:11
	ds_read2_b32 v[38:39], v115 offset0:12 offset1:13
	ds_read2_b32 v[40:41], v115 offset0:20 offset1:21
	ds_read2_b32 v[42:43], v115 offset0:22 offset1:23
	ds_read2_b32 v[44:45], v115 offset0:30 offset1:31
	ds_read2_b32 v[46:47], v115 offset0:32 offset1:33
	s_waitcnt lgkmcnt(15)
	v_mfma_f32_32x32x16_bf16 v[0:15], v[64:67], v[72:75], v[0:15]
	v_mfma_f32_32x32x16_bf16 v[16:31], v[64:67], v[76:79], v[16:31]
	v_mfma_f32_32x32x16_bf16 v[0:15], v[68:71], v[220:223], v[0:15]
	v_mfma_f32_32x32x16_bf16 v[16:31], v[68:71], v[224:227], v[16:31]
	s_add_i32 s90, s76, 0
	v_add_u32_e32 v80, s90, v239
	v_add_u32_e32 v83, s90, v240
	v_add_u32_e32 v99, s90, v241
	v_add_u32_e32 v253, s90, v242
	v_add_u32_e32 v254, s90, v101
	v_add_u32_e32 v255, s90, v150
	v_med3_i32 v80, v80, 0, s99
	v_med3_i32 v83, v83, 0, s99
	v_med3_i32 v99, v99, 0, s99
	v_med3_i32 v253, v253, 0, s99
	v_med3_i32 v254, v254, 0, s99
	v_med3_i32 v255, v255, 0, s99
	v_mad_u32_u24 v80, v80, s100, v252
	v_mad_u32_u24 v83, v83, s100, v252
	v_mad_u32_u24 v99, v99, s100, v252
	v_mad_u32_u24 v253, v253, s100, v252
	v_mad_u32_u24 v254, v254, s100, v153
	v_mad_u32_u24 v255, v255, s100, v153
	global_load_dwordx4 v[156:159], v80, s[82:83]
	global_load_dwordx4 v[160:163], v83, s[82:83]
	global_load_dwordx4 v[164:167], v99, s[82:83]
	global_load_dwordx4 v[168:171], v253, s[82:83]
	global_load_dwordx4 v[172:175], v254, s[82:83] offset:768
	global_load_dwordx4 v[176:179], v255, s[82:83] offset:768
	global_load_dwordx4 v[180:183], v254, s[82:83] offset:832
	global_load_dwordx4 v[184:187], v255, s[82:83] offset:832
	s_waitcnt lgkmcnt(0)
	v_mfma_f32_32x32x16_bf16 v[32:47], v[188:191], v[48:51], v[32:47]
	ds_read_b64_tr_b16 v[72:73], v231
	ds_read_b64_tr_b16 v[74:75], v231 offset:512
	ds_read_b64_tr_b16 v[76:77], v231 offset:2048
	ds_read_b64_tr_b16 v[78:79], v231 offset:2560
	ds_read_b64_tr_b16 v[220:221], v231 offset:1024
	ds_read_b64_tr_b16 v[222:223], v231 offset:1536
	ds_read_b64_tr_b16 v[224:225], v231 offset:3072
	ds_read_b64_tr_b16 v[226:227], v231 offset:3584
	s_waitcnt vmcnt(8)
	ds_write_b128 v247, v[116:119]
	ds_write_b128 v247, v[120:123] offset:1024
	ds_write_b128 v111, v[124:127] offset:2048
	ds_write_b128 v111, v[128:131] offset:3072
	ds_read_b128 v[116:119], v248
	ds_read_b128 v[120:123], v249
	ds_read_b128 v[124:127], v250
	ds_read_b128 v[128:131], v251
	ds_write_b128 v112, v[132:135]
	ds_write_b128 v112, v[136:139] offset:1024
	ds_write_b128 v112, v[140:143] offset:2048
	ds_write_b128 v112, v[144:147] offset:3072
	v_mfma_f32_32x32x16_bf16 v[32:47], v[192:195], v[52:55], v[32:47]
	v_mfma_f32_32x32x16_bf16 v[32:47], v[196:199], v[56:59], v[32:47]
	v_mfma_f32_32x32x16_bf16 v[32:47], v[200:203], v[60:63], v[32:47]
	s_nop 11
	v_exp_f32_e32 v32, v32
	v_exp_f32_e32 v33, v33
	v_exp_f32_e32 v34, v34
	v_exp_f32_e32 v35, v35
	v_exp_f32_e32 v36, v36
	v_exp_f32_e32 v37, v37
	v_exp_f32_e32 v38, v38
	v_exp_f32_e32 v39, v39
	v_exp_f32_e32 v40, v40
	v_exp_f32_e32 v41, v41
	v_exp_f32_e32 v42, v42
	v_exp_f32_e32 v43, v43
	v_exp_f32_e32 v44, v44
	v_exp_f32_e32 v45, v45
	v_exp_f32_e32 v46, v46
	v_exp_f32_e32 v47, v47
	s_add_i32 s90, s76, -256
	v_lshlrev_b32_e32 v84, 2, v107
	v_add_u32_e32 v84, s90, v84
	v_add_u32_e32 v85, 0, v84
	v_add_u32_e32 v86, 4, v84
	v_add_u32_e32 v87, 8, v84
	v_add_u32_e32 v88, 12, v84
	v_cmp_gt_u32_e64 s[30:31], s98, v85
	v_cmp_gt_u32_e64 s[36:37], s98, v86
	v_cmp_gt_u32_e64 s[78:79], s98, v87
	v_cmp_gt_u32_e64 s[50:51], s98, v88
	v_cndmask_b32_e64 v32, 0, v32, s[30:31]
	v_add_u32_e32 v85, 32, v84
	v_cmp_gt_u32_e64 s[30:31], s98, v85
	v_cndmask_b32_e64 v33, 0, v33, s[36:37]
	v_add_u32_e32 v86, 36, v84
	v_cmp_gt_u32_e64 s[36:37], s98, v86
	v_cndmask_b32_e64 v34, 0, v34, s[78:79]
	v_add_u32_e32 v87, 40, v84
	v_cmp_gt_u32_e64 s[78:79], s98, v87
	v_cndmask_b32_e64 v35, 0, v35, s[50:51]
	v_add_u32_e32 v88, 44, v84
	v_cmp_gt_u32_e64 s[50:51], s98, v88
	v_cndmask_b32_e64 v36, 0, v36, s[30:31]
	v_add_u32_e32 v85, 64, v84
	v_cmp_gt_u32_e64 s[30:31], s98, v85
	v_cndmask_b32_e64 v37, 0, v37, s[36:37]
	v_add_u32_e32 v86, 68, v84
	v_cmp_gt_u32_e64 s[36:37], s98, v86
	v_cndmask_b32_e64 v38, 0, v38, s[78:79]
	v_add_u32_e32 v87, 72, v84
	v_cmp_gt_u32_e64 s[78:79], s98, v87
	v_cndmask_b32_e64 v39, 0, v39, s[50:51]
	v_add_u32_e32 v88, 76, v84
	v_cmp_gt_u32_e64 s[50:51], s98, v88
	v_cndmask_b32_e64 v40, 0, v40, s[30:31]
	v_add_u32_e32 v85, 96, v84
	v_cmp_gt_u32_e64 s[30:31], s98, v85
	v_cndmask_b32_e64 v41, 0, v41, s[36:37]
	v_add_u32_e32 v86, 100, v84
	v_cmp_gt_u32_e64 s[36:37], s98, v86
	v_cndmask_b32_e64 v42, 0, v42, s[78:79]
	v_add_u32_e32 v87, 104, v84
	v_cmp_gt_u32_e64 s[78:79], s98, v87
	v_cndmask_b32_e64 v43, 0, v43, s[50:51]
	v_add_u32_e32 v88, 108, v84
	v_cmp_gt_u32_e64 s[50:51], s98, v88
	v_nop
	v_cndmask_b32_e64 v44, 0, v44, s[30:31]
	v_cndmask_b32_e64 v45, 0, v45, s[36:37]
	v_cndmask_b32_e64 v46, 0, v46, s[78:79]
	v_cndmask_b32_e64 v47, 0, v47, s[50:51]
	v_cvt_pk_bf16_f32 v64, v32, v33
	v_cvt_pk_bf16_f32 v65, v34, v35
	v_cvt_pk_bf16_f32 v66, v36, v37
	v_cvt_pk_bf16_f32 v67, v38, v39
	v_cvt_pk_bf16_f32 v68, v40, v41
	v_cvt_pk_bf16_f32 v69, v42, v43
	v_cvt_pk_bf16_f32 v70, v44, v45
	v_cvt_pk_bf16_f32 v71, v46, v47
	v_pk_add_f32 v[232:233], v[232:233], v[32:33]
	v_pk_add_f32 v[232:233], v[232:233], v[34:35]
	v_pk_add_f32 v[232:233], v[232:233], v[36:37]
	v_pk_add_f32 v[232:233], v[232:233], v[38:39]
	v_pk_add_f32 v[232:233], v[232:233], v[40:41]
	v_pk_add_f32 v[232:233], v[232:233], v[42:43]
	v_pk_add_f32 v[232:233], v[232:233], v[44:45]
	v_pk_add_f32 v[232:233], v[232:233], v[46:47]
	ds_read2_b32 v[32:33], v115 offset0:40 offset1:41
	ds_read2_b32 v[34:35], v115 offset0:42 offset1:43
	ds_read2_b32 v[36:37], v115 offset0:50 offset1:51
	ds_read2_b32 v[38:39], v115 offset0:52 offset1:53
	ds_read2_b32 v[40:41], v115 offset0:60 offset1:61
	ds_read2_b32 v[42:43], v115 offset0:62 offset1:63
	ds_read2_b32 v[44:45], v115 offset0:70 offset1:71
	ds_read2_b32 v[46:47], v115 offset0:72 offset1:73
	s_waitcnt lgkmcnt(15)
	v_mfma_f32_32x32x16_bf16 v[0:15], v[64:67], v[72:75], v[0:15]
	v_mfma_f32_32x32x16_bf16 v[16:31], v[64:67], v[76:79], v[16:31]
	v_mfma_f32_32x32x16_bf16 v[0:15], v[68:71], v[220:223], v[0:15]
	v_mfma_f32_32x32x16_bf16 v[16:31], v[68:71], v[224:227], v[16:31]
	s_add_i32 s90, s76, 128
	v_add_u32_e32 v80, s90, v239
	v_add_u32_e32 v83, s90, v240
	v_add_u32_e32 v99, s90, v241
	v_add_u32_e32 v253, s90, v242
	v_add_u32_e32 v254, s90, v101
	v_add_u32_e32 v255, s90, v150
	v_med3_i32 v80, v80, 0, s99
	v_med3_i32 v83, v83, 0, s99
	v_med3_i32 v99, v99, 0, s99
	v_med3_i32 v253, v253, 0, s99
	v_med3_i32 v254, v254, 0, s99
	v_med3_i32 v255, v255, 0, s99
	v_mad_u32_u24 v80, v80, s100, v252
	v_mad_u32_u24 v83, v83, s100, v252
	v_mad_u32_u24 v99, v99, s100, v252
	v_mad_u32_u24 v253, v253, s100, v252
	v_mad_u32_u24 v254, v254, s100, v153
	v_mad_u32_u24 v255, v255, s100, v153
	global_load_dwordx4 v[188:191], v80, s[82:83]
	global_load_dwordx4 v[192:195], v83, s[82:83]
	global_load_dwordx4 v[196:199], v99, s[82:83]
	global_load_dwordx4 v[200:203], v253, s[82:83]
	global_load_dwordx4 v[204:207], v254, s[82:83] offset:768
	global_load_dwordx4 v[208:211], v255, s[82:83] offset:768
	global_load_dwordx4 v[212:215], v254, s[82:83] offset:832
	global_load_dwordx4 v[216:219], v255, s[82:83] offset:832
	s_waitcnt lgkmcnt(0)
	v_mfma_f32_32x32x16_bf16 v[32:47], v[116:119], v[48:51], v[32:47]
	ds_read_b64_tr_b16 v[72:73], v231
	ds_read_b64_tr_b16 v[74:75], v231 offset:512
	ds_read_b64_tr_b16 v[76:77], v231 offset:2048
	ds_read_b64_tr_b16 v[78:79], v231 offset:2560
	ds_read_b64_tr_b16 v[220:221], v231 offset:1024
	ds_read_b64_tr_b16 v[222:223], v231 offset:1536
	ds_read_b64_tr_b16 v[224:225], v231 offset:3072
	ds_read_b64_tr_b16 v[226:227], v231 offset:3584
	s_waitcnt vmcnt(8)
	ds_write_b128 v247, v[156:159]
	ds_write_b128 v247, v[160:163] offset:1024
	ds_write_b128 v111, v[164:167] offset:2048
	ds_write_b128 v111, v[168:171] offset:3072
	ds_read_b128 v[156:159], v248
	ds_read_b128 v[160:163], v249
	ds_read_b128 v[164:167], v250
	ds_read_b128 v[168:171], v251
	ds_write_b128 v112, v[172:175]
	ds_write_b128 v112, v[176:179] offset:1024
	ds_write_b128 v112, v[180:183] offset:2048
	ds_write_b128 v112, v[184:187] offset:3072
	v_mfma_f32_32x32x16_bf16 v[32:47], v[120:123], v[52:55], v[32:47]
	v_mfma_f32_32x32x16_bf16 v[32:47], v[124:127], v[56:59], v[32:47]
	v_mfma_f32_32x32x16_bf16 v[32:47], v[128:131], v[60:63], v[32:47]
	s_nop 11
	v_exp_f32_e32 v32, v32
	v_exp_f32_e32 v33, v33
	v_exp_f32_e32 v34, v34
	v_exp_f32_e32 v35, v35
	v_exp_f32_e32 v36, v36
	v_exp_f32_e32 v37, v37
	v_exp_f32_e32 v38, v38
	v_exp_f32_e32 v39, v39
	v_exp_f32_e32 v40, v40
	v_exp_f32_e32 v41, v41
	v_exp_f32_e32 v42, v42
	v_exp_f32_e32 v43, v43
	v_exp_f32_e32 v44, v44
	v_exp_f32_e32 v45, v45
	v_exp_f32_e32 v46, v46
	v_exp_f32_e32 v47, v47
	s_add_i32 s90, s76, -128
	v_lshlrev_b32_e32 v84, 2, v107
	v_add_u32_e32 v84, s90, v84
	v_add_u32_e32 v85, 0, v84
	v_add_u32_e32 v86, 4, v84
	v_add_u32_e32 v87, 8, v84
	v_add_u32_e32 v88, 12, v84
	v_cmp_gt_u32_e64 s[30:31], s98, v85
	v_cmp_gt_u32_e64 s[36:37], s98, v86
	v_cmp_gt_u32_e64 s[78:79], s98, v87
	v_cmp_gt_u32_e64 s[50:51], s98, v88
	v_cndmask_b32_e64 v32, 0, v32, s[30:31]
	v_add_u32_e32 v85, 32, v84
	v_cmp_gt_u32_e64 s[30:31], s98, v85
	v_cndmask_b32_e64 v33, 0, v33, s[36:37]
	v_add_u32_e32 v86, 36, v84
	v_cmp_gt_u32_e64 s[36:37], s98, v86
	v_cndmask_b32_e64 v34, 0, v34, s[78:79]
	v_add_u32_e32 v87, 40, v84
	v_cmp_gt_u32_e64 s[78:79], s98, v87
	v_cndmask_b32_e64 v35, 0, v35, s[50:51]
	v_add_u32_e32 v88, 44, v84
	v_cmp_gt_u32_e64 s[50:51], s98, v88
	v_cndmask_b32_e64 v36, 0, v36, s[30:31]
	v_add_u32_e32 v85, 64, v84
	v_cmp_gt_u32_e64 s[30:31], s98, v85
	v_cndmask_b32_e64 v37, 0, v37, s[36:37]
	v_add_u32_e32 v86, 68, v84
	v_cmp_gt_u32_e64 s[36:37], s98, v86
	v_cndmask_b32_e64 v38, 0, v38, s[78:79]
	v_add_u32_e32 v87, 72, v84
	v_cmp_gt_u32_e64 s[78:79], s98, v87
	v_cndmask_b32_e64 v39, 0, v39, s[50:51]
	v_add_u32_e32 v88, 76, v84
	v_cmp_gt_u32_e64 s[50:51], s98, v88
	v_cndmask_b32_e64 v40, 0, v40, s[30:31]
	v_add_u32_e32 v85, 96, v84
	v_cmp_gt_u32_e64 s[30:31], s98, v85
	v_cndmask_b32_e64 v41, 0, v41, s[36:37]
	v_add_u32_e32 v86, 100, v84
	v_cmp_gt_u32_e64 s[36:37], s98, v86
	v_cndmask_b32_e64 v42, 0, v42, s[78:79]
	v_add_u32_e32 v87, 104, v84
	v_cmp_gt_u32_e64 s[78:79], s98, v87
	v_cndmask_b32_e64 v43, 0, v43, s[50:51]
	v_add_u32_e32 v88, 108, v84
	v_cmp_gt_u32_e64 s[50:51], s98, v88
	v_nop
	v_cndmask_b32_e64 v44, 0, v44, s[30:31]
	v_cndmask_b32_e64 v45, 0, v45, s[36:37]
	v_cndmask_b32_e64 v46, 0, v46, s[78:79]
	v_cndmask_b32_e64 v47, 0, v47, s[50:51]
	v_cvt_pk_bf16_f32 v64, v32, v33
	v_cvt_pk_bf16_f32 v65, v34, v35
	v_cvt_pk_bf16_f32 v66, v36, v37
	v_cvt_pk_bf16_f32 v67, v38, v39
	v_cvt_pk_bf16_f32 v68, v40, v41
	v_cvt_pk_bf16_f32 v69, v42, v43
	v_cvt_pk_bf16_f32 v70, v44, v45
	v_cvt_pk_bf16_f32 v71, v46, v47
	v_pk_add_f32 v[232:233], v[232:233], v[32:33]
	v_pk_add_f32 v[232:233], v[232:233], v[34:35]
	v_pk_add_f32 v[232:233], v[232:233], v[36:37]
	v_pk_add_f32 v[232:233], v[232:233], v[38:39]
	v_pk_add_f32 v[232:233], v[232:233], v[40:41]
	v_pk_add_f32 v[232:233], v[232:233], v[42:43]
	v_pk_add_f32 v[232:233], v[232:233], v[44:45]
	v_pk_add_f32 v[232:233], v[232:233], v[46:47]
	ds_read2_b32 v[32:33], v115 offset0:80 offset1:81
	ds_read2_b32 v[34:35], v115 offset0:82 offset1:83
	ds_read2_b32 v[36:37], v115 offset0:90 offset1:91
	ds_read2_b32 v[38:39], v115 offset0:92 offset1:93
	ds_read2_b32 v[40:41], v115 offset0:100 offset1:101
	ds_read2_b32 v[42:43], v115 offset0:102 offset1:103
	ds_read2_b32 v[44:45], v115 offset0:110 offset1:111
	ds_read2_b32 v[46:47], v115 offset0:112 offset1:113
	s_waitcnt lgkmcnt(15)
	v_mfma_f32_32x32x16_bf16 v[0:15], v[64:67], v[72:75], v[0:15]
	v_mfma_f32_32x32x16_bf16 v[16:31], v[64:67], v[76:79], v[16:31]
	v_mfma_f32_32x32x16_bf16 v[0:15], v[68:71], v[220:223], v[0:15]
	v_mfma_f32_32x32x16_bf16 v[16:31], v[68:71], v[224:227], v[16:31]
	s_add_i32 s90, s76, 256
	v_add_u32_e32 v80, s90, v239
	v_add_u32_e32 v83, s90, v240
	v_add_u32_e32 v99, s90, v241
	v_add_u32_e32 v253, s90, v242
	v_add_u32_e32 v254, s90, v101
	v_add_u32_e32 v255, s90, v150
	v_med3_i32 v80, v80, 0, s99
	v_med3_i32 v83, v83, 0, s99
	v_med3_i32 v99, v99, 0, s99
	v_med3_i32 v253, v253, 0, s99
	v_med3_i32 v254, v254, 0, s99
	v_med3_i32 v255, v255, 0, s99
	v_mad_u32_u24 v80, v80, s100, v252
	v_mad_u32_u24 v83, v83, s100, v252
	v_mad_u32_u24 v99, v99, s100, v252
	v_mad_u32_u24 v253, v253, s100, v252
	v_mad_u32_u24 v254, v254, s100, v153
	v_mad_u32_u24 v255, v255, s100, v153
	global_load_dwordx4 v[116:119], v80, s[82:83]
	global_load_dwordx4 v[120:123], v83, s[82:83]
	global_load_dwordx4 v[124:127], v99, s[82:83]
	global_load_dwordx4 v[128:131], v253, s[82:83]
	global_load_dwordx4 v[132:135], v254, s[82:83] offset:768
	global_load_dwordx4 v[136:139], v255, s[82:83] offset:768
	global_load_dwordx4 v[140:143], v254, s[82:83] offset:832
	global_load_dwordx4 v[144:147], v255, s[82:83] offset:832
	s_waitcnt lgkmcnt(0)
	v_mfma_f32_32x32x16_bf16 v[32:47], v[156:159], v[48:51], v[32:47]
	ds_read_b64_tr_b16 v[72:73], v231
	ds_read_b64_tr_b16 v[74:75], v231 offset:512
	ds_read_b64_tr_b16 v[76:77], v231 offset:2048
	ds_read_b64_tr_b16 v[78:79], v231 offset:2560
	ds_read_b64_tr_b16 v[220:221], v231 offset:1024
	ds_read_b64_tr_b16 v[222:223], v231 offset:1536
	ds_read_b64_tr_b16 v[224:225], v231 offset:3072
	ds_read_b64_tr_b16 v[226:227], v231 offset:3584
	s_waitcnt vmcnt(8)
	ds_write_b128 v247, v[188:191]
	ds_write_b128 v247, v[192:195] offset:1024
	ds_write_b128 v111, v[196:199] offset:2048
	ds_write_b128 v111, v[200:203] offset:3072
	ds_read_b128 v[188:191], v248
	ds_read_b128 v[192:195], v249
	ds_read_b128 v[196:199], v250
	ds_read_b128 v[200:203], v251
	ds_write_b128 v112, v[204:207]
	ds_write_b128 v112, v[208:211] offset:1024
	ds_write_b128 v112, v[212:215] offset:2048
	ds_write_b128 v112, v[216:219] offset:3072
	v_mfma_f32_32x32x16_bf16 v[32:47], v[160:163], v[52:55], v[32:47]
	v_mfma_f32_32x32x16_bf16 v[32:47], v[164:167], v[56:59], v[32:47]
	v_mfma_f32_32x32x16_bf16 v[32:47], v[168:171], v[60:63], v[32:47]
	s_nop 11
	v_exp_f32_e32 v32, v32
	v_exp_f32_e32 v33, v33
	v_exp_f32_e32 v34, v34
	v_exp_f32_e32 v35, v35
	v_exp_f32_e32 v36, v36
	v_exp_f32_e32 v37, v37
	v_exp_f32_e32 v38, v38
	v_exp_f32_e32 v39, v39
	v_exp_f32_e32 v40, v40
	v_exp_f32_e32 v41, v41
	v_exp_f32_e32 v42, v42
	v_exp_f32_e32 v43, v43
	v_exp_f32_e32 v44, v44
	v_exp_f32_e32 v45, v45
	v_exp_f32_e32 v46, v46
	v_exp_f32_e32 v47, v47
	s_add_i32 s90, s76, 0
	v_lshlrev_b32_e32 v84, 2, v107
	v_add_u32_e32 v84, s90, v84
	v_add_u32_e32 v85, 0, v84
	v_add_u32_e32 v86, 4, v84
	v_add_u32_e32 v87, 8, v84
	v_add_u32_e32 v88, 12, v84
	v_cmp_gt_u32_e64 s[30:31], s98, v85
	v_cmp_gt_u32_e64 s[36:37], s98, v86
	v_cmp_gt_u32_e64 s[78:79], s98, v87
	v_cmp_gt_u32_e64 s[50:51], s98, v88
	v_cndmask_b32_e64 v32, 0, v32, s[30:31]
	v_add_u32_e32 v85, 32, v84
	v_cmp_gt_u32_e64 s[30:31], s98, v85
	v_cndmask_b32_e64 v33, 0, v33, s[36:37]
	v_add_u32_e32 v86, 36, v84
	v_cmp_gt_u32_e64 s[36:37], s98, v86
	v_cndmask_b32_e64 v34, 0, v34, s[78:79]
	v_add_u32_e32 v87, 40, v84
	v_cmp_gt_u32_e64 s[78:79], s98, v87
	v_cndmask_b32_e64 v35, 0, v35, s[50:51]
	v_add_u32_e32 v88, 44, v84
	v_cmp_gt_u32_e64 s[50:51], s98, v88
	v_cndmask_b32_e64 v36, 0, v36, s[30:31]
	v_add_u32_e32 v85, 64, v84
	v_cmp_gt_u32_e64 s[30:31], s98, v85
	v_cndmask_b32_e64 v37, 0, v37, s[36:37]
	v_add_u32_e32 v86, 68, v84
	v_cmp_gt_u32_e64 s[36:37], s98, v86
	v_cndmask_b32_e64 v38, 0, v38, s[78:79]
	v_add_u32_e32 v87, 72, v84
	v_cmp_gt_u32_e64 s[78:79], s98, v87
	v_cndmask_b32_e64 v39, 0, v39, s[50:51]
	v_add_u32_e32 v88, 76, v84
	v_cmp_gt_u32_e64 s[50:51], s98, v88
	v_cndmask_b32_e64 v40, 0, v40, s[30:31]
	v_add_u32_e32 v85, 96, v84
	v_cmp_gt_u32_e64 s[30:31], s98, v85
	v_cndmask_b32_e64 v41, 0, v41, s[36:37]
	v_add_u32_e32 v86, 100, v84
	v_cmp_gt_u32_e64 s[36:37], s98, v86
	v_cndmask_b32_e64 v42, 0, v42, s[78:79]
	v_add_u32_e32 v87, 104, v84
	v_cmp_gt_u32_e64 s[78:79], s98, v87
	v_cndmask_b32_e64 v43, 0, v43, s[50:51]
	v_add_u32_e32 v88, 108, v84
	v_cmp_gt_u32_e64 s[50:51], s98, v88
	v_nop
	v_cndmask_b32_e64 v44, 0, v44, s[30:31]
	v_cndmask_b32_e64 v45, 0, v45, s[36:37]
	v_cndmask_b32_e64 v46, 0, v46, s[78:79]
	v_cndmask_b32_e64 v47, 0, v47, s[50:51]
	v_cvt_pk_bf16_f32 v64, v32, v33
	v_cvt_pk_bf16_f32 v65, v34, v35
	v_cvt_pk_bf16_f32 v66, v36, v37
	v_cvt_pk_bf16_f32 v67, v38, v39
	v_cvt_pk_bf16_f32 v68, v40, v41
	v_cvt_pk_bf16_f32 v69, v42, v43
	v_cvt_pk_bf16_f32 v70, v44, v45
	v_cvt_pk_bf16_f32 v71, v46, v47
	v_pk_add_f32 v[232:233], v[232:233], v[32:33]
	v_pk_add_f32 v[232:233], v[232:233], v[34:35]
	v_pk_add_f32 v[232:233], v[232:233], v[36:37]
	v_pk_add_f32 v[232:233], v[232:233], v[38:39]
	v_pk_add_f32 v[232:233], v[232:233], v[40:41]
	v_pk_add_f32 v[232:233], v[232:233], v[42:43]
	v_pk_add_f32 v[232:233], v[232:233], v[44:45]
	v_pk_add_f32 v[232:233], v[232:233], v[46:47]
	ds_read2_b32 v[32:33], v115 offset0:120 offset1:121
	ds_read2_b32 v[34:35], v115 offset0:122 offset1:123
	ds_read2_b32 v[36:37], v115 offset0:130 offset1:131
	ds_read2_b32 v[38:39], v115 offset0:132 offset1:133
	ds_read2_b32 v[40:41], v115 offset0:140 offset1:141
	ds_read2_b32 v[42:43], v115 offset0:142 offset1:143
	ds_read2_b32 v[44:45], v115 offset0:150 offset1:151
	ds_read2_b32 v[46:47], v115 offset0:152 offset1:153
	s_waitcnt lgkmcnt(15)
	v_mfma_f32_32x32x16_bf16 v[0:15], v[64:67], v[72:75], v[0:15]
	v_mfma_f32_32x32x16_bf16 v[16:31], v[64:67], v[76:79], v[16:31]
	v_mfma_f32_32x32x16_bf16 v[0:15], v[68:71], v[220:223], v[0:15]
	v_mfma_f32_32x32x16_bf16 v[16:31], v[68:71], v[224:227], v[16:31]
	s_add_i32 s90, s76, 384
	v_add_u32_e32 v80, s90, v239
	v_add_u32_e32 v83, s90, v240
	v_add_u32_e32 v99, s90, v241
	v_add_u32_e32 v253, s90, v242
	v_add_u32_e32 v254, s90, v101
	v_add_u32_e32 v255, s90, v150
	v_med3_i32 v80, v80, 0, s99
	v_med3_i32 v83, v83, 0, s99
	v_med3_i32 v99, v99, 0, s99
	v_med3_i32 v253, v253, 0, s99
	v_med3_i32 v254, v254, 0, s99
	v_med3_i32 v255, v255, 0, s99
	v_mad_u32_u24 v80, v80, s100, v252
	v_mad_u32_u24 v83, v83, s100, v252
	v_mad_u32_u24 v99, v99, s100, v252
	v_mad_u32_u24 v253, v253, s100, v252
	v_mad_u32_u24 v254, v254, s100, v153
	v_mad_u32_u24 v255, v255, s100, v153
	global_load_dwordx4 v[156:159], v80, s[82:83]
	global_load_dwordx4 v[160:163], v83, s[82:83]
	global_load_dwordx4 v[164:167], v99, s[82:83]
	global_load_dwordx4 v[168:171], v253, s[82:83]
	global_load_dwordx4 v[172:175], v254, s[82:83] offset:768
	global_load_dwordx4 v[176:179], v255, s[82:83] offset:768
	global_load_dwordx4 v[180:183], v254, s[82:83] offset:832
	global_load_dwordx4 v[184:187], v255, s[82:83] offset:832
	s_waitcnt lgkmcnt(0)
	v_mfma_f32_32x32x16_bf16 v[32:47], v[188:191], v[48:51], v[32:47]
	ds_read_b64_tr_b16 v[72:73], v231
	ds_read_b64_tr_b16 v[74:75], v231 offset:512
	ds_read_b64_tr_b16 v[76:77], v231 offset:2048
	ds_read_b64_tr_b16 v[78:79], v231 offset:2560
	ds_read_b64_tr_b16 v[220:221], v231 offset:1024
	ds_read_b64_tr_b16 v[222:223], v231 offset:1536
	ds_read_b64_tr_b16 v[224:225], v231 offset:3072
	ds_read_b64_tr_b16 v[226:227], v231 offset:3584
	s_waitcnt vmcnt(8)
	ds_write_b128 v247, v[116:119]
	ds_write_b128 v247, v[120:123] offset:1024
	ds_write_b128 v111, v[124:127] offset:2048
	ds_write_b128 v111, v[128:131] offset:3072
	ds_read_b128 v[116:119], v248
	ds_read_b128 v[120:123], v249
	ds_read_b128 v[124:127], v250
	ds_read_b128 v[128:131], v251
	ds_write_b128 v112, v[132:135]
	ds_write_b128 v112, v[136:139] offset:1024
	ds_write_b128 v112, v[140:143] offset:2048
	ds_write_b128 v112, v[144:147] offset:3072
	v_mfma_f32_32x32x16_bf16 v[32:47], v[192:195], v[52:55], v[32:47]
	v_mfma_f32_32x32x16_bf16 v[32:47], v[196:199], v[56:59], v[32:47]
	v_mfma_f32_32x32x16_bf16 v[32:47], v[200:203], v[60:63], v[32:47]
	s_nop 11
	v_exp_f32_e32 v32, v32
	v_exp_f32_e32 v33, v33
	v_exp_f32_e32 v34, v34
	v_exp_f32_e32 v35, v35
	v_exp_f32_e32 v36, v36
	v_exp_f32_e32 v37, v37
	v_exp_f32_e32 v38, v38
	v_exp_f32_e32 v39, v39
	v_exp_f32_e32 v40, v40
	v_exp_f32_e32 v41, v41
	v_exp_f32_e32 v42, v42
	v_exp_f32_e32 v43, v43
	v_exp_f32_e32 v44, v44
	v_exp_f32_e32 v45, v45
	v_exp_f32_e32 v46, v46
	v_exp_f32_e32 v47, v47
	s_add_i32 s90, s76, 128
	v_lshlrev_b32_e32 v84, 2, v107
	v_add_u32_e32 v84, s90, v84
	v_add_u32_e32 v85, 0, v84
	v_add_u32_e32 v86, 4, v84
	v_add_u32_e32 v87, 8, v84
	v_add_u32_e32 v88, 12, v84
	v_cmp_gt_u32_e64 s[30:31], s98, v85
	v_cmp_gt_u32_e64 s[36:37], s98, v86
	v_cmp_gt_u32_e64 s[78:79], s98, v87
	v_cmp_gt_u32_e64 s[50:51], s98, v88
	v_cndmask_b32_e64 v32, 0, v32, s[30:31]
	v_add_u32_e32 v85, 32, v84
	v_cmp_gt_u32_e64 s[30:31], s98, v85
	v_cndmask_b32_e64 v33, 0, v33, s[36:37]
	v_add_u32_e32 v86, 36, v84
	v_cmp_gt_u32_e64 s[36:37], s98, v86
	v_cndmask_b32_e64 v34, 0, v34, s[78:79]
	v_add_u32_e32 v87, 40, v84
	v_cmp_gt_u32_e64 s[78:79], s98, v87
	v_cndmask_b32_e64 v35, 0, v35, s[50:51]
	v_add_u32_e32 v88, 44, v84
	v_cmp_gt_u32_e64 s[50:51], s98, v88
	v_cndmask_b32_e64 v36, 0, v36, s[30:31]
	v_add_u32_e32 v85, 64, v84
	v_cmp_gt_u32_e64 s[30:31], s98, v85
	v_cndmask_b32_e64 v37, 0, v37, s[36:37]
	v_add_u32_e32 v86, 68, v84
	v_cmp_gt_u32_e64 s[36:37], s98, v86
	v_cndmask_b32_e64 v38, 0, v38, s[78:79]
	v_add_u32_e32 v87, 72, v84
	v_cmp_gt_u32_e64 s[78:79], s98, v87
	v_cndmask_b32_e64 v39, 0, v39, s[50:51]
	v_add_u32_e32 v88, 76, v84
	v_cmp_gt_u32_e64 s[50:51], s98, v88
	v_cndmask_b32_e64 v40, 0, v40, s[30:31]
	v_add_u32_e32 v85, 96, v84
	v_cmp_gt_u32_e64 s[30:31], s98, v85
	v_cndmask_b32_e64 v41, 0, v41, s[36:37]
	v_add_u32_e32 v86, 100, v84
	v_cmp_gt_u32_e64 s[36:37], s98, v86
	v_cndmask_b32_e64 v42, 0, v42, s[78:79]
	v_add_u32_e32 v87, 104, v84
	v_cmp_gt_u32_e64 s[78:79], s98, v87
	v_cndmask_b32_e64 v43, 0, v43, s[50:51]
	v_add_u32_e32 v88, 108, v84
	v_cmp_gt_u32_e64 s[50:51], s98, v88
	v_nop
	v_cndmask_b32_e64 v44, 0, v44, s[30:31]
	v_cndmask_b32_e64 v45, 0, v45, s[36:37]
	v_cndmask_b32_e64 v46, 0, v46, s[78:79]
	v_cndmask_b32_e64 v47, 0, v47, s[50:51]
	v_cvt_pk_bf16_f32 v64, v32, v33
	v_cvt_pk_bf16_f32 v65, v34, v35
	v_cvt_pk_bf16_f32 v66, v36, v37
	v_cvt_pk_bf16_f32 v67, v38, v39
	v_cvt_pk_bf16_f32 v68, v40, v41
	v_cvt_pk_bf16_f32 v69, v42, v43
	v_cvt_pk_bf16_f32 v70, v44, v45
	v_cvt_pk_bf16_f32 v71, v46, v47
	v_pk_add_f32 v[232:233], v[232:233], v[32:33]
	v_pk_add_f32 v[232:233], v[232:233], v[34:35]
	v_pk_add_f32 v[232:233], v[232:233], v[36:37]
	v_pk_add_f32 v[232:233], v[232:233], v[38:39]
	v_pk_add_f32 v[232:233], v[232:233], v[40:41]
	v_pk_add_f32 v[232:233], v[232:233], v[42:43]
	v_pk_add_f32 v[232:233], v[232:233], v[44:45]
	v_pk_add_f32 v[232:233], v[232:233], v[46:47]
	v_add_u32_e32 v115, 640, v115
	ds_read2_b32 v[32:33], v115 offset0:0 offset1:1
	ds_read2_b32 v[34:35], v115 offset0:2 offset1:3
	ds_read2_b32 v[36:37], v115 offset0:10 offset1:11
	ds_read2_b32 v[38:39], v115 offset0:12 offset1:13
	ds_read2_b32 v[40:41], v115 offset0:20 offset1:21
	ds_read2_b32 v[42:43], v115 offset0:22 offset1:23
	ds_read2_b32 v[44:45], v115 offset0:30 offset1:31
	ds_read2_b32 v[46:47], v115 offset0:32 offset1:33
	s_waitcnt lgkmcnt(15)
	v_mfma_f32_32x32x16_bf16 v[0:15], v[64:67], v[72:75], v[0:15]
	v_mfma_f32_32x32x16_bf16 v[16:31], v[64:67], v[76:79], v[16:31]
	v_mfma_f32_32x32x16_bf16 v[0:15], v[68:71], v[220:223], v[0:15]
	v_mfma_f32_32x32x16_bf16 v[16:31], v[68:71], v[224:227], v[16:31]
	s_add_i32 s90, s76, 512
	v_add_u32_e32 v80, s90, v239
	v_add_u32_e32 v83, s90, v240
	v_add_u32_e32 v99, s90, v241
	v_add_u32_e32 v253, s90, v242
	v_add_u32_e32 v254, s90, v101
	v_add_u32_e32 v255, s90, v150
	v_med3_i32 v80, v80, 0, s99
	v_med3_i32 v83, v83, 0, s99
	v_med3_i32 v99, v99, 0, s99
	v_med3_i32 v253, v253, 0, s99
	v_med3_i32 v254, v254, 0, s99
	v_med3_i32 v255, v255, 0, s99
	v_mad_u32_u24 v80, v80, s100, v252
	v_mad_u32_u24 v83, v83, s100, v252
	v_mad_u32_u24 v99, v99, s100, v252
	v_mad_u32_u24 v253, v253, s100, v252
	v_mad_u32_u24 v254, v254, s100, v153
	v_mad_u32_u24 v255, v255, s100, v153
	global_load_dwordx4 v[188:191], v80, s[82:83]
	global_load_dwordx4 v[192:195], v83, s[82:83]
	global_load_dwordx4 v[196:199], v99, s[82:83]
	global_load_dwordx4 v[200:203], v253, s[82:83]
	global_load_dwordx4 v[204:207], v254, s[82:83] offset:768
	global_load_dwordx4 v[208:211], v255, s[82:83] offset:768
	global_load_dwordx4 v[212:215], v254, s[82:83] offset:832
	global_load_dwordx4 v[216:219], v255, s[82:83] offset:832
	s_waitcnt lgkmcnt(0)
	v_mfma_f32_32x32x16_bf16 v[32:47], v[116:119], v[48:51], v[32:47]
	ds_read_b64_tr_b16 v[72:73], v231
	ds_read_b64_tr_b16 v[74:75], v231 offset:512
	ds_read_b64_tr_b16 v[76:77], v231 offset:2048
	ds_read_b64_tr_b16 v[78:79], v231 offset:2560
	ds_read_b64_tr_b16 v[220:221], v231 offset:1024
	ds_read_b64_tr_b16 v[222:223], v231 offset:1536
	ds_read_b64_tr_b16 v[224:225], v231 offset:3072
	ds_read_b64_tr_b16 v[226:227], v231 offset:3584
	s_waitcnt vmcnt(8)
	ds_write_b128 v247, v[156:159]
	ds_write_b128 v247, v[160:163] offset:1024
	ds_write_b128 v111, v[164:167] offset:2048
	ds_write_b128 v111, v[168:171] offset:3072
	ds_read_b128 v[156:159], v248
	ds_read_b128 v[160:163], v249
	ds_read_b128 v[164:167], v250
	ds_read_b128 v[168:171], v251
	ds_write_b128 v112, v[172:175]
	ds_write_b128 v112, v[176:179] offset:1024
	ds_write_b128 v112, v[180:183] offset:2048
	ds_write_b128 v112, v[184:187] offset:3072
	v_mfma_f32_32x32x16_bf16 v[32:47], v[120:123], v[52:55], v[32:47]
	v_mfma_f32_32x32x16_bf16 v[32:47], v[124:127], v[56:59], v[32:47]
	v_mfma_f32_32x32x16_bf16 v[32:47], v[128:131], v[60:63], v[32:47]
	s_nop 11
	v_exp_f32_e32 v32, v32
	v_exp_f32_e32 v33, v33
	v_exp_f32_e32 v34, v34
	v_exp_f32_e32 v35, v35
	v_exp_f32_e32 v36, v36
	v_exp_f32_e32 v37, v37
	v_exp_f32_e32 v38, v38
	v_exp_f32_e32 v39, v39
	v_exp_f32_e32 v40, v40
	v_exp_f32_e32 v41, v41
	v_exp_f32_e32 v42, v42
	v_exp_f32_e32 v43, v43
	v_exp_f32_e32 v44, v44
	v_exp_f32_e32 v45, v45
	v_exp_f32_e32 v46, v46
	v_exp_f32_e32 v47, v47
	s_add_i32 s90, s76, 256
	v_lshlrev_b32_e32 v84, 2, v107
	v_add_u32_e32 v84, s90, v84
	v_add_u32_e32 v85, 0, v84
	v_add_u32_e32 v86, 4, v84
	v_add_u32_e32 v87, 8, v84
	v_add_u32_e32 v88, 12, v84
	v_cmp_gt_u32_e64 s[30:31], s98, v85
	v_cmp_gt_u32_e64 s[36:37], s98, v86
	v_cmp_gt_u32_e64 s[78:79], s98, v87
	v_cmp_gt_u32_e64 s[50:51], s98, v88
	v_cndmask_b32_e64 v32, 0, v32, s[30:31]
	v_add_u32_e32 v85, 32, v84
	v_cmp_gt_u32_e64 s[30:31], s98, v85
	v_cndmask_b32_e64 v33, 0, v33, s[36:37]
	v_add_u32_e32 v86, 36, v84
	v_cmp_gt_u32_e64 s[36:37], s98, v86
	v_cndmask_b32_e64 v34, 0, v34, s[78:79]
	v_add_u32_e32 v87, 40, v84
	v_cmp_gt_u32_e64 s[78:79], s98, v87
	v_cndmask_b32_e64 v35, 0, v35, s[50:51]
	v_add_u32_e32 v88, 44, v84
	v_cmp_gt_u32_e64 s[50:51], s98, v88
	v_cndmask_b32_e64 v36, 0, v36, s[30:31]
	v_add_u32_e32 v85, 64, v84
	v_cmp_gt_u32_e64 s[30:31], s98, v85
	v_cndmask_b32_e64 v37, 0, v37, s[36:37]
	v_add_u32_e32 v86, 68, v84
	v_cmp_gt_u32_e64 s[36:37], s98, v86
	v_cndmask_b32_e64 v38, 0, v38, s[78:79]
	v_add_u32_e32 v87, 72, v84
	v_cmp_gt_u32_e64 s[78:79], s98, v87
	v_cndmask_b32_e64 v39, 0, v39, s[50:51]
	v_add_u32_e32 v88, 76, v84
	v_cmp_gt_u32_e64 s[50:51], s98, v88
	v_cndmask_b32_e64 v40, 0, v40, s[30:31]
	v_add_u32_e32 v85, 96, v84
	v_cmp_gt_u32_e64 s[30:31], s98, v85
	v_cndmask_b32_e64 v41, 0, v41, s[36:37]
	v_add_u32_e32 v86, 100, v84
	v_cmp_gt_u32_e64 s[36:37], s98, v86
	v_cndmask_b32_e64 v42, 0, v42, s[78:79]
	v_add_u32_e32 v87, 104, v84
	v_cmp_gt_u32_e64 s[78:79], s98, v87
	v_cndmask_b32_e64 v43, 0, v43, s[50:51]
	v_add_u32_e32 v88, 108, v84
	v_cmp_gt_u32_e64 s[50:51], s98, v88
	v_nop
	v_cndmask_b32_e64 v44, 0, v44, s[30:31]
	v_cndmask_b32_e64 v45, 0, v45, s[36:37]
	v_cndmask_b32_e64 v46, 0, v46, s[78:79]
	v_cndmask_b32_e64 v47, 0, v47, s[50:51]
	v_cvt_pk_bf16_f32 v64, v32, v33
	v_cvt_pk_bf16_f32 v65, v34, v35
	v_cvt_pk_bf16_f32 v66, v36, v37
	v_cvt_pk_bf16_f32 v67, v38, v39
	v_cvt_pk_bf16_f32 v68, v40, v41
	v_cvt_pk_bf16_f32 v69, v42, v43
	v_cvt_pk_bf16_f32 v70, v44, v45
	v_cvt_pk_bf16_f32 v71, v46, v47
	v_pk_add_f32 v[232:233], v[232:233], v[32:33]
	v_pk_add_f32 v[232:233], v[232:233], v[34:35]
	v_pk_add_f32 v[232:233], v[232:233], v[36:37]
	v_pk_add_f32 v[232:233], v[232:233], v[38:39]
	v_pk_add_f32 v[232:233], v[232:233], v[40:41]
	v_pk_add_f32 v[232:233], v[232:233], v[42:43]
	v_pk_add_f32 v[232:233], v[232:233], v[44:45]
	v_pk_add_f32 v[232:233], v[232:233], v[46:47]
	ds_read2_b32 v[32:33], v115 offset0:40 offset1:41
	ds_read2_b32 v[34:35], v115 offset0:42 offset1:43
	ds_read2_b32 v[36:37], v115 offset0:50 offset1:51
	ds_read2_b32 v[38:39], v115 offset0:52 offset1:53
	ds_read2_b32 v[40:41], v115 offset0:60 offset1:61
	ds_read2_b32 v[42:43], v115 offset0:62 offset1:63
	ds_read2_b32 v[44:45], v115 offset0:70 offset1:71
	ds_read2_b32 v[46:47], v115 offset0:72 offset1:73
	s_waitcnt lgkmcnt(15)
	v_mfma_f32_32x32x16_bf16 v[0:15], v[64:67], v[72:75], v[0:15]
	v_mfma_f32_32x32x16_bf16 v[16:31], v[64:67], v[76:79], v[16:31]
	v_mfma_f32_32x32x16_bf16 v[0:15], v[68:71], v[220:223], v[0:15]
	v_mfma_f32_32x32x16_bf16 v[16:31], v[68:71], v[224:227], v[16:31]
	s_add_i32 s90, s76, 640
	v_add_u32_e32 v80, s90, v239
	v_add_u32_e32 v83, s90, v240
	v_add_u32_e32 v99, s90, v241
	v_add_u32_e32 v253, s90, v242
	v_add_u32_e32 v254, s90, v101
	v_add_u32_e32 v255, s90, v150
	v_med3_i32 v80, v80, 0, s99
	v_med3_i32 v83, v83, 0, s99
	v_med3_i32 v99, v99, 0, s99
	v_med3_i32 v253, v253, 0, s99
	v_med3_i32 v254, v254, 0, s99
	v_med3_i32 v255, v255, 0, s99
	v_mad_u32_u24 v80, v80, s100, v252
	v_mad_u32_u24 v83, v83, s100, v252
	v_mad_u32_u24 v99, v99, s100, v252
	v_mad_u32_u24 v253, v253, s100, v252
	v_mad_u32_u24 v254, v254, s100, v153
	v_mad_u32_u24 v255, v255, s100, v153
	global_load_dwordx4 v[116:119], v80, s[82:83]
	global_load_dwordx4 v[120:123], v83, s[82:83]
	global_load_dwordx4 v[124:127], v99, s[82:83]
	global_load_dwordx4 v[128:131], v253, s[82:83]
	global_load_dwordx4 v[132:135], v254, s[82:83] offset:768
	global_load_dwordx4 v[136:139], v255, s[82:83] offset:768
	global_load_dwordx4 v[140:143], v254, s[82:83] offset:832
	global_load_dwordx4 v[144:147], v255, s[82:83] offset:832
	s_waitcnt lgkmcnt(0)
	v_mfma_f32_32x32x16_bf16 v[32:47], v[156:159], v[48:51], v[32:47]
	ds_read_b64_tr_b16 v[72:73], v231
	ds_read_b64_tr_b16 v[74:75], v231 offset:512
	ds_read_b64_tr_b16 v[76:77], v231 offset:2048
	ds_read_b64_tr_b16 v[78:79], v231 offset:2560
	ds_read_b64_tr_b16 v[220:221], v231 offset:1024
	ds_read_b64_tr_b16 v[222:223], v231 offset:1536
	ds_read_b64_tr_b16 v[224:225], v231 offset:3072
	ds_read_b64_tr_b16 v[226:227], v231 offset:3584
	s_waitcnt vmcnt(8)
	ds_write_b128 v247, v[188:191]
	ds_write_b128 v247, v[192:195] offset:1024
	ds_write_b128 v111, v[196:199] offset:2048
	ds_write_b128 v111, v[200:203] offset:3072
	ds_read_b128 v[188:191], v248
	ds_read_b128 v[192:195], v249
	ds_read_b128 v[196:199], v250
	ds_read_b128 v[200:203], v251
	ds_write_b128 v112, v[204:207]
	ds_write_b128 v112, v[208:211] offset:1024
	ds_write_b128 v112, v[212:215] offset:2048
	ds_write_b128 v112, v[216:219] offset:3072
	v_mfma_f32_32x32x16_bf16 v[32:47], v[160:163], v[52:55], v[32:47]
	v_mfma_f32_32x32x16_bf16 v[32:47], v[164:167], v[56:59], v[32:47]
	v_mfma_f32_32x32x16_bf16 v[32:47], v[168:171], v[60:63], v[32:47]
	s_nop 11
	v_exp_f32_e32 v32, v32
	v_exp_f32_e32 v33, v33
	v_exp_f32_e32 v34, v34
	v_exp_f32_e32 v35, v35
	v_exp_f32_e32 v36, v36
	v_exp_f32_e32 v37, v37
	v_exp_f32_e32 v38, v38
	v_exp_f32_e32 v39, v39
	v_exp_f32_e32 v40, v40
	v_exp_f32_e32 v41, v41
	v_exp_f32_e32 v42, v42
	v_exp_f32_e32 v43, v43
	v_exp_f32_e32 v44, v44
	v_exp_f32_e32 v45, v45
	v_exp_f32_e32 v46, v46
	v_exp_f32_e32 v47, v47
	s_add_i32 s90, s76, 384
	v_lshlrev_b32_e32 v84, 2, v107
	v_add_u32_e32 v84, s90, v84
	v_add_u32_e32 v85, 0, v84
	v_add_u32_e32 v86, 4, v84
	v_add_u32_e32 v87, 8, v84
	v_add_u32_e32 v88, 12, v84
	v_cmp_gt_u32_e64 s[30:31], s98, v85
	v_cmp_gt_u32_e64 s[36:37], s98, v86
	v_cmp_gt_u32_e64 s[78:79], s98, v87
	v_cmp_gt_u32_e64 s[50:51], s98, v88
	v_cndmask_b32_e64 v32, 0, v32, s[30:31]
	v_add_u32_e32 v85, 32, v84
	v_cmp_gt_u32_e64 s[30:31], s98, v85
	v_cndmask_b32_e64 v33, 0, v33, s[36:37]
	v_add_u32_e32 v86, 36, v84
	v_cmp_gt_u32_e64 s[36:37], s98, v86
	v_cndmask_b32_e64 v34, 0, v34, s[78:79]
	v_add_u32_e32 v87, 40, v84
	v_cmp_gt_u32_e64 s[78:79], s98, v87
	v_cndmask_b32_e64 v35, 0, v35, s[50:51]
	v_add_u32_e32 v88, 44, v84
	v_cmp_gt_u32_e64 s[50:51], s98, v88
	v_cndmask_b32_e64 v36, 0, v36, s[30:31]
	v_add_u32_e32 v85, 64, v84
	v_cmp_gt_u32_e64 s[30:31], s98, v85
	v_cndmask_b32_e64 v37, 0, v37, s[36:37]
	v_add_u32_e32 v86, 68, v84
	v_cmp_gt_u32_e64 s[36:37], s98, v86
	v_cndmask_b32_e64 v38, 0, v38, s[78:79]
	v_add_u32_e32 v87, 72, v84
	v_cmp_gt_u32_e64 s[78:79], s98, v87
	v_cndmask_b32_e64 v39, 0, v39, s[50:51]
	v_add_u32_e32 v88, 76, v84
	v_cmp_gt_u32_e64 s[50:51], s98, v88
	v_cndmask_b32_e64 v40, 0, v40, s[30:31]
	v_add_u32_e32 v85, 96, v84
	v_cmp_gt_u32_e64 s[30:31], s98, v85
	v_cndmask_b32_e64 v41, 0, v41, s[36:37]
	v_add_u32_e32 v86, 100, v84
	v_cmp_gt_u32_e64 s[36:37], s98, v86
	v_cndmask_b32_e64 v42, 0, v42, s[78:79]
	v_add_u32_e32 v87, 104, v84
	v_cmp_gt_u32_e64 s[78:79], s98, v87
	v_cndmask_b32_e64 v43, 0, v43, s[50:51]
	v_add_u32_e32 v88, 108, v84
	v_cmp_gt_u32_e64 s[50:51], s98, v88
	v_nop
	v_cndmask_b32_e64 v44, 0, v44, s[30:31]
	v_cndmask_b32_e64 v45, 0, v45, s[36:37]
	v_cndmask_b32_e64 v46, 0, v46, s[78:79]
	v_cndmask_b32_e64 v47, 0, v47, s[50:51]
	v_cvt_pk_bf16_f32 v64, v32, v33
	v_cvt_pk_bf16_f32 v65, v34, v35
	v_cvt_pk_bf16_f32 v66, v36, v37
	v_cvt_pk_bf16_f32 v67, v38, v39
	v_cvt_pk_bf16_f32 v68, v40, v41
	v_cvt_pk_bf16_f32 v69, v42, v43
	v_cvt_pk_bf16_f32 v70, v44, v45
	v_cvt_pk_bf16_f32 v71, v46, v47
	v_pk_add_f32 v[232:233], v[232:233], v[32:33]
	v_pk_add_f32 v[232:233], v[232:233], v[34:35]
	v_pk_add_f32 v[232:233], v[232:233], v[36:37]
	v_pk_add_f32 v[232:233], v[232:233], v[38:39]
	v_pk_add_f32 v[232:233], v[232:233], v[40:41]
	v_pk_add_f32 v[232:233], v[232:233], v[42:43]
	v_pk_add_f32 v[232:233], v[232:233], v[44:45]
	v_pk_add_f32 v[232:233], v[232:233], v[46:47]
	ds_read2_b32 v[32:33], v115 offset0:80 offset1:81
	ds_read2_b32 v[34:35], v115 offset0:82 offset1:83
	ds_read2_b32 v[36:37], v115 offset0:90 offset1:91
	ds_read2_b32 v[38:39], v115 offset0:92 offset1:93
	ds_read2_b32 v[40:41], v115 offset0:100 offset1:101
	ds_read2_b32 v[42:43], v115 offset0:102 offset1:103
	ds_read2_b32 v[44:45], v115 offset0:110 offset1:111
	ds_read2_b32 v[46:47], v115 offset0:112 offset1:113
	s_waitcnt lgkmcnt(15)
	v_mfma_f32_32x32x16_bf16 v[0:15], v[64:67], v[72:75], v[0:15]
	v_mfma_f32_32x32x16_bf16 v[16:31], v[64:67], v[76:79], v[16:31]
	v_mfma_f32_32x32x16_bf16 v[0:15], v[68:71], v[220:223], v[0:15]
	v_mfma_f32_32x32x16_bf16 v[16:31], v[68:71], v[224:227], v[16:31]
	s_add_i32 s90, s76, -1024
	v_add_u32_e32 v80, s90, v243
	v_add_u32_e32 v83, s90, v244
	v_add_u32_e32 v99, s90, v245
	v_add_u32_e32 v253, s90, v246
	v_add_u32_e32 v254, s90, v148
	v_add_u32_e32 v255, s90, v151
	v_med3_i32 v80, v80, 0, s99
	v_med3_i32 v83, v83, 0, s99
	v_med3_i32 v99, v99, 0, s99
	v_med3_i32 v253, v253, 0, s99
	v_med3_i32 v254, v254, 0, s99
	v_med3_i32 v255, v255, 0, s99
	v_mad_u32_u24 v80, v80, s100, v252
	v_mad_u32_u24 v83, v83, s100, v252
	v_mad_u32_u24 v99, v99, s100, v252
	v_mad_u32_u24 v253, v253, s100, v252
	v_mad_u32_u24 v254, v254, s100, v153
	v_mad_u32_u24 v255, v255, s100, v153
	global_load_dwordx4 v[156:159], v80, s[82:83]
	global_load_dwordx4 v[160:163], v83, s[82:83]
	global_load_dwordx4 v[164:167], v99, s[82:83]
	global_load_dwordx4 v[168:171], v253, s[82:83]
	global_load_dwordx4 v[172:175], v254, s[82:83] offset:768
	global_load_dwordx4 v[176:179], v255, s[82:83] offset:768
	global_load_dwordx4 v[180:183], v254, s[82:83] offset:832
	global_load_dwordx4 v[184:187], v255, s[82:83] offset:832
	s_waitcnt lgkmcnt(0)
	v_mfma_f32_32x32x16_bf16 v[32:47], v[188:191], v[48:51], v[32:47]
	ds_read_b64_tr_b16 v[72:73], v231
	ds_read_b64_tr_b16 v[74:75], v231 offset:512
	ds_read_b64_tr_b16 v[76:77], v231 offset:2048
	ds_read_b64_tr_b16 v[78:79], v231 offset:2560
	ds_read_b64_tr_b16 v[220:221], v231 offset:1024
	ds_read_b64_tr_b16 v[222:223], v231 offset:1536
	ds_read_b64_tr_b16 v[224:225], v231 offset:3072
	ds_read_b64_tr_b16 v[226:227], v231 offset:3584
	s_waitcnt vmcnt(8)
	ds_write_b128 v247, v[116:119]
	ds_write_b128 v247, v[120:123] offset:1024
	ds_write_b128 v111, v[124:127] offset:2048
	ds_write_b128 v111, v[128:131] offset:3072
	ds_read_b128 v[116:119], v248
	ds_read_b128 v[120:123], v249
	ds_read_b128 v[124:127], v250
	ds_read_b128 v[128:131], v251
	ds_write_b128 v112, v[132:135]
	ds_write_b128 v112, v[136:139] offset:1024
	ds_write_b128 v112, v[140:143] offset:2048
	ds_write_b128 v112, v[144:147] offset:3072
	v_mfma_f32_32x32x16_bf16 v[32:47], v[192:195], v[52:55], v[32:47]
	v_mfma_f32_32x32x16_bf16 v[32:47], v[196:199], v[56:59], v[32:47]
	v_mfma_f32_32x32x16_bf16 v[32:47], v[200:203], v[60:63], v[32:47]
	s_nop 11
	v_exp_f32_e32 v32, v32
	v_exp_f32_e32 v33, v33
	v_exp_f32_e32 v34, v34
	v_exp_f32_e32 v35, v35
	v_exp_f32_e32 v36, v36
	v_exp_f32_e32 v37, v37
	v_exp_f32_e32 v38, v38
	v_exp_f32_e32 v39, v39
	v_exp_f32_e32 v40, v40
	v_exp_f32_e32 v41, v41
	v_exp_f32_e32 v42, v42
	v_exp_f32_e32 v43, v43
	v_exp_f32_e32 v44, v44
	v_exp_f32_e32 v45, v45
	v_exp_f32_e32 v46, v46
	v_exp_f32_e32 v47, v47
	s_add_i32 s90, s76, 512
	v_lshlrev_b32_e32 v84, 2, v107
	v_add_u32_e32 v84, s90, v84
	v_add_u32_e32 v85, 0, v84
	v_add_u32_e32 v86, 4, v84
	v_add_u32_e32 v87, 8, v84
	v_add_u32_e32 v88, 12, v84
	v_cmp_gt_u32_e64 s[30:31], s98, v85
	v_cmp_gt_u32_e64 s[36:37], s98, v86
	v_cmp_gt_u32_e64 s[78:79], s98, v87
	v_cmp_gt_u32_e64 s[50:51], s98, v88
	v_cndmask_b32_e64 v32, 0, v32, s[30:31]
	v_add_u32_e32 v85, 32, v84
	v_cmp_gt_u32_e64 s[30:31], s98, v85
	v_cndmask_b32_e64 v33, 0, v33, s[36:37]
	v_add_u32_e32 v86, 36, v84
	v_cmp_gt_u32_e64 s[36:37], s98, v86
	v_cndmask_b32_e64 v34, 0, v34, s[78:79]
	v_add_u32_e32 v87, 40, v84
	v_cmp_gt_u32_e64 s[78:79], s98, v87
	v_cndmask_b32_e64 v35, 0, v35, s[50:51]
	v_add_u32_e32 v88, 44, v84
	v_cmp_gt_u32_e64 s[50:51], s98, v88
	v_cndmask_b32_e64 v36, 0, v36, s[30:31]
	v_add_u32_e32 v85, 64, v84
	v_cmp_gt_u32_e64 s[30:31], s98, v85
	v_cndmask_b32_e64 v37, 0, v37, s[36:37]
	v_add_u32_e32 v86, 68, v84
	v_cmp_gt_u32_e64 s[36:37], s98, v86
	v_cndmask_b32_e64 v38, 0, v38, s[78:79]
	v_add_u32_e32 v87, 72, v84
	v_cmp_gt_u32_e64 s[78:79], s98, v87
	v_cndmask_b32_e64 v39, 0, v39, s[50:51]
	v_add_u32_e32 v88, 76, v84
	v_cmp_gt_u32_e64 s[50:51], s98, v88
	v_cndmask_b32_e64 v40, 0, v40, s[30:31]
	v_add_u32_e32 v85, 96, v84
	v_cmp_gt_u32_e64 s[30:31], s98, v85
	v_cndmask_b32_e64 v41, 0, v41, s[36:37]
	v_add_u32_e32 v86, 100, v84
	v_cmp_gt_u32_e64 s[36:37], s98, v86
	v_cndmask_b32_e64 v42, 0, v42, s[78:79]
	v_add_u32_e32 v87, 104, v84
	v_cmp_gt_u32_e64 s[78:79], s98, v87
	v_cndmask_b32_e64 v43, 0, v43, s[50:51]
	v_add_u32_e32 v88, 108, v84
	v_cmp_gt_u32_e64 s[50:51], s98, v88
	v_nop
	v_cndmask_b32_e64 v44, 0, v44, s[30:31]
	v_cndmask_b32_e64 v45, 0, v45, s[36:37]
	v_cndmask_b32_e64 v46, 0, v46, s[78:79]
	v_cndmask_b32_e64 v47, 0, v47, s[50:51]
	v_cvt_pk_bf16_f32 v64, v32, v33
	v_cvt_pk_bf16_f32 v65, v34, v35
	v_cvt_pk_bf16_f32 v66, v36, v37
	v_cvt_pk_bf16_f32 v67, v38, v39
	v_cvt_pk_bf16_f32 v68, v40, v41
	v_cvt_pk_bf16_f32 v69, v42, v43
	v_cvt_pk_bf16_f32 v70, v44, v45
	v_cvt_pk_bf16_f32 v71, v46, v47
	v_pk_add_f32 v[232:233], v[232:233], v[32:33]
	v_pk_add_f32 v[232:233], v[232:233], v[34:35]
	v_pk_add_f32 v[232:233], v[232:233], v[36:37]
	v_pk_add_f32 v[232:233], v[232:233], v[38:39]
	v_pk_add_f32 v[232:233], v[232:233], v[40:41]
	v_pk_add_f32 v[232:233], v[232:233], v[42:43]
	v_pk_add_f32 v[232:233], v[232:233], v[44:45]
	v_pk_add_f32 v[232:233], v[232:233], v[46:47]
	ds_read2_b32 v[32:33], v115 offset0:120 offset1:121
	ds_read2_b32 v[34:35], v115 offset0:122 offset1:123
	ds_read2_b32 v[36:37], v115 offset0:130 offset1:131
	ds_read2_b32 v[38:39], v115 offset0:132 offset1:133
	ds_read2_b32 v[40:41], v115 offset0:140 offset1:141
	ds_read2_b32 v[42:43], v115 offset0:142 offset1:143
	ds_read2_b32 v[44:45], v115 offset0:150 offset1:151
	ds_read2_b32 v[46:47], v115 offset0:152 offset1:153
	s_waitcnt lgkmcnt(15)
	v_mfma_f32_32x32x16_bf16 v[0:15], v[64:67], v[72:75], v[0:15]
	v_mfma_f32_32x32x16_bf16 v[16:31], v[64:67], v[76:79], v[16:31]
	v_mfma_f32_32x32x16_bf16 v[0:15], v[68:71], v[220:223], v[0:15]
	v_mfma_f32_32x32x16_bf16 v[16:31], v[68:71], v[224:227], v[16:31]
	s_add_i32 s90, s76, -512
	v_add_u32_e32 v80, s90, v243
	v_add_u32_e32 v83, s90, v244
	v_add_u32_e32 v99, s90, v245
	v_add_u32_e32 v253, s90, v246
	v_add_u32_e32 v254, s90, v148
	v_add_u32_e32 v255, s90, v151
	v_med3_i32 v80, v80, 0, s99
	v_med3_i32 v83, v83, 0, s99
	v_med3_i32 v99, v99, 0, s99
	v_med3_i32 v253, v253, 0, s99
	v_med3_i32 v254, v254, 0, s99
	v_med3_i32 v255, v255, 0, s99
	v_mad_u32_u24 v80, v80, s100, v252
	v_mad_u32_u24 v83, v83, s100, v252
	v_mad_u32_u24 v99, v99, s100, v252
	v_mad_u32_u24 v253, v253, s100, v252
	v_mad_u32_u24 v254, v254, s100, v153
	v_mad_u32_u24 v255, v255, s100, v153
	global_load_dwordx4 v[188:191], v80, s[82:83]
	global_load_dwordx4 v[192:195], v83, s[82:83]
	global_load_dwordx4 v[196:199], v99, s[82:83]
	global_load_dwordx4 v[200:203], v253, s[82:83]
	global_load_dwordx4 v[204:207], v254, s[82:83] offset:768
	global_load_dwordx4 v[208:211], v255, s[82:83] offset:768
	global_load_dwordx4 v[212:215], v254, s[82:83] offset:832
	global_load_dwordx4 v[216:219], v255, s[82:83] offset:832
	s_waitcnt lgkmcnt(0)
	v_mfma_f32_32x32x16_bf16 v[32:47], v[116:119], v[48:51], v[32:47]
	ds_read_b64_tr_b16 v[72:73], v231
	ds_read_b64_tr_b16 v[74:75], v231 offset:512
	ds_read_b64_tr_b16 v[76:77], v231 offset:2048
	ds_read_b64_tr_b16 v[78:79], v231 offset:2560
	ds_read_b64_tr_b16 v[220:221], v231 offset:1024
	ds_read_b64_tr_b16 v[222:223], v231 offset:1536
	ds_read_b64_tr_b16 v[224:225], v231 offset:3072
	ds_read_b64_tr_b16 v[226:227], v231 offset:3584
	s_waitcnt vmcnt(8)
	ds_write_b128 v247, v[156:159]
	ds_write_b128 v247, v[160:163] offset:1024
	ds_write_b128 v111, v[164:167] offset:2048
	ds_write_b128 v111, v[168:171] offset:3072
	ds_read_b128 v[156:159], v248
	ds_read_b128 v[160:163], v249
	ds_read_b128 v[164:167], v250
	ds_read_b128 v[168:171], v251
	ds_write_b128 v112, v[172:175]
	ds_write_b128 v112, v[176:179] offset:1024
	ds_write_b128 v112, v[180:183] offset:2048
	ds_write_b128 v112, v[184:187] offset:3072
	v_mfma_f32_32x32x16_bf16 v[32:47], v[120:123], v[52:55], v[32:47]
	v_mfma_f32_32x32x16_bf16 v[32:47], v[124:127], v[56:59], v[32:47]
	v_mfma_f32_32x32x16_bf16 v[32:47], v[128:131], v[60:63], v[32:47]
	s_nop 11
	v_exp_f32_e32 v32, v32
	v_exp_f32_e32 v33, v33
	v_exp_f32_e32 v34, v34
	v_exp_f32_e32 v35, v35
	v_exp_f32_e32 v36, v36
	v_exp_f32_e32 v37, v37
	v_exp_f32_e32 v38, v38
	v_exp_f32_e32 v39, v39
	v_exp_f32_e32 v40, v40
	v_exp_f32_e32 v41, v41
	v_exp_f32_e32 v42, v42
	v_exp_f32_e32 v43, v43
	v_exp_f32_e32 v44, v44
	v_exp_f32_e32 v45, v45
	v_exp_f32_e32 v46, v46
	v_exp_f32_e32 v47, v47
	s_add_i32 s90, s76, 640
	v_lshlrev_b32_e32 v84, 2, v107
	v_add_u32_e32 v84, s90, v84
	v_add_u32_e32 v85, 0, v84
	v_add_u32_e32 v86, 4, v84
	v_add_u32_e32 v87, 8, v84
	v_add_u32_e32 v88, 12, v84
	v_cmp_gt_u32_e64 s[30:31], s98, v85
	v_cmp_gt_u32_e64 s[36:37], s98, v86
	v_cmp_gt_u32_e64 s[78:79], s98, v87
	v_cmp_gt_u32_e64 s[50:51], s98, v88
	v_cndmask_b32_e64 v32, 0, v32, s[30:31]
	v_add_u32_e32 v85, 32, v84
	v_cmp_gt_u32_e64 s[30:31], s98, v85
	v_cndmask_b32_e64 v33, 0, v33, s[36:37]
	v_add_u32_e32 v86, 36, v84
	v_cmp_gt_u32_e64 s[36:37], s98, v86
	v_cndmask_b32_e64 v34, 0, v34, s[78:79]
	v_add_u32_e32 v87, 40, v84
	v_cmp_gt_u32_e64 s[78:79], s98, v87
	v_cndmask_b32_e64 v35, 0, v35, s[50:51]
	v_add_u32_e32 v88, 44, v84
	v_cmp_gt_u32_e64 s[50:51], s98, v88
	v_cndmask_b32_e64 v36, 0, v36, s[30:31]
	v_add_u32_e32 v85, 64, v84
	v_cmp_gt_u32_e64 s[30:31], s98, v85
	v_cndmask_b32_e64 v37, 0, v37, s[36:37]
	v_add_u32_e32 v86, 68, v84
	v_cmp_gt_u32_e64 s[36:37], s98, v86
	v_cndmask_b32_e64 v38, 0, v38, s[78:79]
	v_add_u32_e32 v87, 72, v84
	v_cmp_gt_u32_e64 s[78:79], s98, v87
	v_cndmask_b32_e64 v39, 0, v39, s[50:51]
	v_add_u32_e32 v88, 76, v84
	v_cmp_gt_u32_e64 s[50:51], s98, v88
	v_cndmask_b32_e64 v40, 0, v40, s[30:31]
	v_add_u32_e32 v85, 96, v84
	v_cmp_gt_u32_e64 s[30:31], s98, v85
	v_cndmask_b32_e64 v41, 0, v41, s[36:37]
	v_add_u32_e32 v86, 100, v84
	v_cmp_gt_u32_e64 s[36:37], s98, v86
	v_cndmask_b32_e64 v42, 0, v42, s[78:79]
	v_add_u32_e32 v87, 104, v84
	v_cmp_gt_u32_e64 s[78:79], s98, v87
	v_cndmask_b32_e64 v43, 0, v43, s[50:51]
	v_add_u32_e32 v88, 108, v84
	v_cmp_gt_u32_e64 s[50:51], s98, v88
	v_nop
	v_cndmask_b32_e64 v44, 0, v44, s[30:31]
	v_cndmask_b32_e64 v45, 0, v45, s[36:37]
	v_cndmask_b32_e64 v46, 0, v46, s[78:79]
	v_cndmask_b32_e64 v47, 0, v47, s[50:51]
	v_cvt_pk_bf16_f32 v64, v32, v33
	v_cvt_pk_bf16_f32 v65, v34, v35
	v_cvt_pk_bf16_f32 v66, v36, v37
	v_cvt_pk_bf16_f32 v67, v38, v39
	v_cvt_pk_bf16_f32 v68, v40, v41
	v_cvt_pk_bf16_f32 v69, v42, v43
	v_cvt_pk_bf16_f32 v70, v44, v45
	v_cvt_pk_bf16_f32 v71, v46, v47
	v_pk_add_f32 v[232:233], v[232:233], v[32:33]
	v_pk_add_f32 v[232:233], v[232:233], v[34:35]
	v_pk_add_f32 v[232:233], v[232:233], v[36:37]
	v_pk_add_f32 v[232:233], v[232:233], v[38:39]
	v_pk_add_f32 v[232:233], v[232:233], v[40:41]
	v_pk_add_f32 v[232:233], v[232:233], v[42:43]
	v_pk_add_f32 v[232:233], v[232:233], v[44:45]
	v_pk_add_f32 v[232:233], v[232:233], v[46:47]
	v_mov_b32_e32 v115, v230
	ds_read2_b32 v[32:33], v115 offset0:0 offset1:1
	ds_read2_b32 v[34:35], v115 offset0:2 offset1:3
	ds_read2_b32 v[36:37], v115 offset0:8 offset1:9
	ds_read2_b32 v[38:39], v115 offset0:10 offset1:11
	ds_read2_b32 v[40:41], v115 offset0:16 offset1:17
	ds_read2_b32 v[42:43], v115 offset0:18 offset1:19
	ds_read2_b32 v[44:45], v115 offset0:24 offset1:25
	ds_read2_b32 v[46:47], v115 offset0:26 offset1:27
	s_waitcnt lgkmcnt(15)
	v_mfma_f32_32x32x16_bf16 v[0:15], v[64:67], v[72:75], v[0:15]
	v_mfma_f32_32x32x16_bf16 v[16:31], v[64:67], v[76:79], v[16:31]
	v_mfma_f32_32x32x16_bf16 v[0:15], v[68:71], v[220:223], v[0:15]
	v_mfma_f32_32x32x16_bf16 v[16:31], v[68:71], v[224:227], v[16:31]
	s_add_i32 s90, s76, 0
	v_add_u32_e32 v80, s90, v243
	v_add_u32_e32 v83, s90, v244
	v_add_u32_e32 v99, s90, v245
	v_add_u32_e32 v253, s90, v246
	v_add_u32_e32 v254, s90, v148
	v_add_u32_e32 v255, s90, v151
	v_med3_i32 v80, v80, 0, s99
	v_med3_i32 v83, v83, 0, s99
	v_med3_i32 v99, v99, 0, s99
	v_med3_i32 v253, v253, 0, s99
	v_med3_i32 v254, v254, 0, s99
	v_med3_i32 v255, v255, 0, s99
	v_mad_u32_u24 v80, v80, s100, v252
	v_mad_u32_u24 v83, v83, s100, v252
	v_mad_u32_u24 v99, v99, s100, v252
	v_mad_u32_u24 v253, v253, s100, v252
	v_mad_u32_u24 v254, v254, s100, v153
	v_mad_u32_u24 v255, v255, s100, v153
	global_load_dwordx4 v[116:119], v80, s[82:83]
	global_load_dwordx4 v[120:123], v83, s[82:83]
	global_load_dwordx4 v[124:127], v99, s[82:83]
	global_load_dwordx4 v[128:131], v253, s[82:83]
	global_load_dwordx4 v[132:135], v254, s[82:83] offset:768
	global_load_dwordx4 v[136:139], v255, s[82:83] offset:768
	global_load_dwordx4 v[140:143], v254, s[82:83] offset:832
	global_load_dwordx4 v[144:147], v255, s[82:83] offset:832
	s_waitcnt lgkmcnt(0)
	v_mfma_f32_32x32x16_bf16 v[32:47], v[156:159], v[48:51], v[32:47]
	ds_read_b64_tr_b16 v[72:73], v231
	ds_read_b64_tr_b16 v[74:75], v231 offset:512
	ds_read_b64_tr_b16 v[76:77], v231 offset:2048
	ds_read_b64_tr_b16 v[78:79], v231 offset:2560
	ds_read_b64_tr_b16 v[220:221], v231 offset:1024
	ds_read_b64_tr_b16 v[222:223], v231 offset:1536
	ds_read_b64_tr_b16 v[224:225], v231 offset:3072
	ds_read_b64_tr_b16 v[226:227], v231 offset:3584
	s_waitcnt vmcnt(8)
	ds_write_b128 v247, v[188:191]
	ds_write_b128 v247, v[192:195] offset:1024
	ds_write_b128 v111, v[196:199] offset:2048
	ds_write_b128 v111, v[200:203] offset:3072
	ds_read_b128 v[188:191], v248
	ds_read_b128 v[192:195], v249
	ds_read_b128 v[196:199], v250
	ds_read_b128 v[200:203], v251
	ds_write_b128 v112, v[204:207]
	ds_write_b128 v112, v[208:211] offset:1024
	ds_write_b128 v112, v[212:215] offset:2048
	ds_write_b128 v112, v[216:219] offset:3072
	v_mfma_f32_32x32x16_bf16 v[32:47], v[160:163], v[52:55], v[32:47]
	v_mfma_f32_32x32x16_bf16 v[32:47], v[164:167], v[56:59], v[32:47]
	v_mfma_f32_32x32x16_bf16 v[32:47], v[168:171], v[60:63], v[32:47]
	s_nop 11
	v_exp_f32_e32 v32, v32
	v_exp_f32_e32 v33, v33
	v_exp_f32_e32 v34, v34
	v_exp_f32_e32 v35, v35
	v_exp_f32_e32 v36, v36
	v_exp_f32_e32 v37, v37
	v_exp_f32_e32 v38, v38
	v_exp_f32_e32 v39, v39
	v_exp_f32_e32 v40, v40
	v_exp_f32_e32 v41, v41
	v_exp_f32_e32 v42, v42
	v_exp_f32_e32 v43, v43
	v_exp_f32_e32 v44, v44
	v_exp_f32_e32 v45, v45
	v_exp_f32_e32 v46, v46
	v_exp_f32_e32 v47, v47
	s_add_i32 s90, s76, -1024
	v_lshlrev_b32_e32 v84, 4, v107
	v_add_u32_e32 v84, s90, v84
	v_add_u32_e32 v85, 0, v84
	v_add_u32_e32 v86, 16, v84
	v_add_u32_e32 v87, 32, v84
	v_add_u32_e32 v88, 48, v84
	v_cmp_gt_u32_e64 s[30:31], s98, v85
	v_cmp_gt_u32_e64 s[36:37], s98, v86
	v_cmp_gt_u32_e64 s[78:79], s98, v87
	v_cmp_gt_u32_e64 s[50:51], s98, v88
	v_cndmask_b32_e64 v32, 0, v32, s[30:31]
	v_add_u32_e32 v85, 128, v84
	v_cmp_gt_u32_e64 s[30:31], s98, v85
	v_cndmask_b32_e64 v33, 0, v33, s[36:37]
	v_add_u32_e32 v86, 144, v84
	v_cmp_gt_u32_e64 s[36:37], s98, v86
	v_cndmask_b32_e64 v34, 0, v34, s[78:79]
	v_add_u32_e32 v87, 160, v84
	v_cmp_gt_u32_e64 s[78:79], s98, v87
	v_cndmask_b32_e64 v35, 0, v35, s[50:51]
	v_add_u32_e32 v88, 176, v84
	v_cmp_gt_u32_e64 s[50:51], s98, v88
	v_cndmask_b32_e64 v36, 0, v36, s[30:31]
	v_add_u32_e32 v85, 256, v84
	v_cmp_gt_u32_e64 s[30:31], s98, v85
	v_cndmask_b32_e64 v37, 0, v37, s[36:37]
	v_add_u32_e32 v86, 272, v84
	v_cmp_gt_u32_e64 s[36:37], s98, v86
	v_cndmask_b32_e64 v38, 0, v38, s[78:79]
	v_add_u32_e32 v87, 288, v84
	v_cmp_gt_u32_e64 s[78:79], s98, v87
	v_cndmask_b32_e64 v39, 0, v39, s[50:51]
	v_add_u32_e32 v88, 304, v84
	v_cmp_gt_u32_e64 s[50:51], s98, v88
	v_cndmask_b32_e64 v40, 0, v40, s[30:31]
	v_add_u32_e32 v85, 384, v84
	v_cmp_gt_u32_e64 s[30:31], s98, v85
	v_cndmask_b32_e64 v41, 0, v41, s[36:37]
	v_add_u32_e32 v86, 400, v84
	v_cmp_gt_u32_e64 s[36:37], s98, v86
	v_cndmask_b32_e64 v42, 0, v42, s[78:79]
	v_add_u32_e32 v87, 416, v84
	v_cmp_gt_u32_e64 s[78:79], s98, v87
	v_cndmask_b32_e64 v43, 0, v43, s[50:51]
	v_add_u32_e32 v88, 432, v84
	v_cmp_gt_u32_e64 s[50:51], s98, v88
	v_nop
	v_cndmask_b32_e64 v44, 0, v44, s[30:31]
	v_cndmask_b32_e64 v45, 0, v45, s[36:37]
	v_cndmask_b32_e64 v46, 0, v46, s[78:79]
	v_cndmask_b32_e64 v47, 0, v47, s[50:51]
	v_cvt_pk_bf16_f32 v64, v32, v33
	v_cvt_pk_bf16_f32 v65, v34, v35
	v_cvt_pk_bf16_f32 v66, v36, v37
	v_cvt_pk_bf16_f32 v67, v38, v39
	v_cvt_pk_bf16_f32 v68, v40, v41
	v_cvt_pk_bf16_f32 v69, v42, v43
	v_cvt_pk_bf16_f32 v70, v44, v45
	v_cvt_pk_bf16_f32 v71, v46, v47
	v_pk_add_f32 v[232:233], v[232:233], v[32:33]
	v_pk_add_f32 v[232:233], v[232:233], v[34:35]
	v_pk_add_f32 v[232:233], v[232:233], v[36:37]
	v_pk_add_f32 v[232:233], v[232:233], v[38:39]
	v_pk_add_f32 v[232:233], v[232:233], v[40:41]
	v_pk_add_f32 v[232:233], v[232:233], v[42:43]
	v_pk_add_f32 v[232:233], v[232:233], v[44:45]
	v_pk_add_f32 v[232:233], v[232:233], v[46:47]
	ds_read2_b32 v[32:33], v115 offset0:32 offset1:33
	ds_read2_b32 v[34:35], v115 offset0:34 offset1:35
	ds_read2_b32 v[36:37], v115 offset0:40 offset1:41
	ds_read2_b32 v[38:39], v115 offset0:42 offset1:43
	ds_read2_b32 v[40:41], v115 offset0:48 offset1:49
	ds_read2_b32 v[42:43], v115 offset0:50 offset1:51
	ds_read2_b32 v[44:45], v115 offset0:56 offset1:57
	ds_read2_b32 v[46:47], v115 offset0:58 offset1:59
	s_waitcnt lgkmcnt(15)
	v_mfma_f32_32x32x16_bf16 v[0:15], v[64:67], v[72:75], v[0:15]
	v_mfma_f32_32x32x16_bf16 v[16:31], v[64:67], v[76:79], v[16:31]
	v_mfma_f32_32x32x16_bf16 v[0:15], v[68:71], v[220:223], v[0:15]
	v_mfma_f32_32x32x16_bf16 v[16:31], v[68:71], v[224:227], v[16:31]
	s_add_i32 s90, s76, 512
	v_add_u32_e32 v80, s90, v243
	v_add_u32_e32 v83, s90, v244
	v_add_u32_e32 v99, s90, v245
	v_add_u32_e32 v253, s90, v246
	v_add_u32_e32 v254, s90, v148
	v_add_u32_e32 v255, s90, v151
	v_med3_i32 v80, v80, 0, s99
	v_med3_i32 v83, v83, 0, s99
	v_med3_i32 v99, v99, 0, s99
	v_med3_i32 v253, v253, 0, s99
	v_med3_i32 v254, v254, 0, s99
	v_med3_i32 v255, v255, 0, s99
	v_mad_u32_u24 v80, v80, s100, v252
	v_mad_u32_u24 v83, v83, s100, v252
	v_mad_u32_u24 v99, v99, s100, v252
	v_mad_u32_u24 v253, v253, s100, v252
	v_mad_u32_u24 v254, v254, s100, v153
	v_mad_u32_u24 v255, v255, s100, v153
	global_load_dwordx4 v[156:159], v80, s[82:83]
	global_load_dwordx4 v[160:163], v83, s[82:83]
	global_load_dwordx4 v[164:167], v99, s[82:83]
	global_load_dwordx4 v[168:171], v253, s[82:83]
	global_load_dwordx4 v[172:175], v254, s[82:83] offset:768
	global_load_dwordx4 v[176:179], v255, s[82:83] offset:768
	global_load_dwordx4 v[180:183], v254, s[82:83] offset:832
	global_load_dwordx4 v[184:187], v255, s[82:83] offset:832
	s_waitcnt lgkmcnt(0)
	v_mfma_f32_32x32x16_bf16 v[32:47], v[188:191], v[48:51], v[32:47]
	ds_read_b64_tr_b16 v[72:73], v231
	ds_read_b64_tr_b16 v[74:75], v231 offset:512
	ds_read_b64_tr_b16 v[76:77], v231 offset:2048
	ds_read_b64_tr_b16 v[78:79], v231 offset:2560
	ds_read_b64_tr_b16 v[220:221], v231 offset:1024
	ds_read_b64_tr_b16 v[222:223], v231 offset:1536
	ds_read_b64_tr_b16 v[224:225], v231 offset:3072
	ds_read_b64_tr_b16 v[226:227], v231 offset:3584
	s_waitcnt vmcnt(8)
	ds_write_b128 v247, v[116:119]
	ds_write_b128 v247, v[120:123] offset:1024
	ds_write_b128 v111, v[124:127] offset:2048
	ds_write_b128 v111, v[128:131] offset:3072
	ds_read_b128 v[116:119], v248
	ds_read_b128 v[120:123], v249
	ds_read_b128 v[124:127], v250
	ds_read_b128 v[128:131], v251
	ds_write_b128 v112, v[132:135]
	ds_write_b128 v112, v[136:139] offset:1024
	ds_write_b128 v112, v[140:143] offset:2048
	ds_write_b128 v112, v[144:147] offset:3072
	v_mfma_f32_32x32x16_bf16 v[32:47], v[192:195], v[52:55], v[32:47]
	v_mfma_f32_32x32x16_bf16 v[32:47], v[196:199], v[56:59], v[32:47]
	v_mfma_f32_32x32x16_bf16 v[32:47], v[200:203], v[60:63], v[32:47]
	s_nop 11
	v_exp_f32_e32 v32, v32
	v_exp_f32_e32 v33, v33
	v_exp_f32_e32 v34, v34
	v_exp_f32_e32 v35, v35
	v_exp_f32_e32 v36, v36
	v_exp_f32_e32 v37, v37
	v_exp_f32_e32 v38, v38
	v_exp_f32_e32 v39, v39
	v_exp_f32_e32 v40, v40
	v_exp_f32_e32 v41, v41
	v_exp_f32_e32 v42, v42
	v_exp_f32_e32 v43, v43
	v_exp_f32_e32 v44, v44
	v_exp_f32_e32 v45, v45
	v_exp_f32_e32 v46, v46
	v_exp_f32_e32 v47, v47
	s_add_i32 s90, s76, -512
	v_lshlrev_b32_e32 v84, 4, v107
	v_add_u32_e32 v84, s90, v84
	v_add_u32_e32 v85, 0, v84
	v_add_u32_e32 v86, 16, v84
	v_add_u32_e32 v87, 32, v84
	v_add_u32_e32 v88, 48, v84
	v_cmp_gt_u32_e64 s[30:31], s98, v85
	v_cmp_gt_u32_e64 s[36:37], s98, v86
	v_cmp_gt_u32_e64 s[78:79], s98, v87
	v_cmp_gt_u32_e64 s[50:51], s98, v88
	v_cndmask_b32_e64 v32, 0, v32, s[30:31]
	v_add_u32_e32 v85, 128, v84
	v_cmp_gt_u32_e64 s[30:31], s98, v85
	v_cndmask_b32_e64 v33, 0, v33, s[36:37]
	v_add_u32_e32 v86, 144, v84
	v_cmp_gt_u32_e64 s[36:37], s98, v86
	v_cndmask_b32_e64 v34, 0, v34, s[78:79]
	v_add_u32_e32 v87, 160, v84
	v_cmp_gt_u32_e64 s[78:79], s98, v87
	v_cndmask_b32_e64 v35, 0, v35, s[50:51]
	v_add_u32_e32 v88, 176, v84
	v_cmp_gt_u32_e64 s[50:51], s98, v88
	v_cndmask_b32_e64 v36, 0, v36, s[30:31]
	v_add_u32_e32 v85, 256, v84
	v_cmp_gt_u32_e64 s[30:31], s98, v85
	v_cndmask_b32_e64 v37, 0, v37, s[36:37]
	v_add_u32_e32 v86, 272, v84
	v_cmp_gt_u32_e64 s[36:37], s98, v86
	v_cndmask_b32_e64 v38, 0, v38, s[78:79]
	v_add_u32_e32 v87, 288, v84
	v_cmp_gt_u32_e64 s[78:79], s98, v87
	v_cndmask_b32_e64 v39, 0, v39, s[50:51]
	v_add_u32_e32 v88, 304, v84
	v_cmp_gt_u32_e64 s[50:51], s98, v88
	v_cndmask_b32_e64 v40, 0, v40, s[30:31]
	v_add_u32_e32 v85, 384, v84
	v_cmp_gt_u32_e64 s[30:31], s98, v85
	v_cndmask_b32_e64 v41, 0, v41, s[36:37]
	v_add_u32_e32 v86, 400, v84
	v_cmp_gt_u32_e64 s[36:37], s98, v86
	v_cndmask_b32_e64 v42, 0, v42, s[78:79]
	v_add_u32_e32 v87, 416, v84
	v_cmp_gt_u32_e64 s[78:79], s98, v87
	v_cndmask_b32_e64 v43, 0, v43, s[50:51]
	v_add_u32_e32 v88, 432, v84
	v_cmp_gt_u32_e64 s[50:51], s98, v88
	v_nop
	v_cndmask_b32_e64 v44, 0, v44, s[30:31]
	v_cndmask_b32_e64 v45, 0, v45, s[36:37]
	v_cndmask_b32_e64 v46, 0, v46, s[78:79]
	v_cndmask_b32_e64 v47, 0, v47, s[50:51]
	v_cvt_pk_bf16_f32 v64, v32, v33
	v_cvt_pk_bf16_f32 v65, v34, v35
	v_cvt_pk_bf16_f32 v66, v36, v37
	v_cvt_pk_bf16_f32 v67, v38, v39
	v_cvt_pk_bf16_f32 v68, v40, v41
	v_cvt_pk_bf16_f32 v69, v42, v43
	v_cvt_pk_bf16_f32 v70, v44, v45
	v_cvt_pk_bf16_f32 v71, v46, v47
	v_pk_add_f32 v[232:233], v[232:233], v[32:33]
	v_pk_add_f32 v[232:233], v[232:233], v[34:35]
	v_pk_add_f32 v[232:233], v[232:233], v[36:37]
	v_pk_add_f32 v[232:233], v[232:233], v[38:39]
	v_pk_add_f32 v[232:233], v[232:233], v[40:41]
	v_pk_add_f32 v[232:233], v[232:233], v[42:43]
	v_pk_add_f32 v[232:233], v[232:233], v[44:45]
	v_pk_add_f32 v[232:233], v[232:233], v[46:47]
	ds_read2_b32 v[32:33], v115 offset0:64 offset1:65
	ds_read2_b32 v[34:35], v115 offset0:66 offset1:67
	ds_read2_b32 v[36:37], v115 offset0:72 offset1:73
	ds_read2_b32 v[38:39], v115 offset0:74 offset1:75
	ds_read2_b32 v[40:41], v115 offset0:80 offset1:81
	ds_read2_b32 v[42:43], v115 offset0:82 offset1:83
	ds_read2_b32 v[44:45], v115 offset0:88 offset1:89
	ds_read2_b32 v[46:47], v115 offset0:90 offset1:91
	s_waitcnt lgkmcnt(15)
	v_mfma_f32_32x32x16_bf16 v[0:15], v[64:67], v[72:75], v[0:15]
	v_mfma_f32_32x32x16_bf16 v[16:31], v[64:67], v[76:79], v[16:31]
	v_mfma_f32_32x32x16_bf16 v[0:15], v[68:71], v[220:223], v[0:15]
	v_mfma_f32_32x32x16_bf16 v[16:31], v[68:71], v[224:227], v[16:31]
	s_add_i32 s90, s76, 1024
	v_add_u32_e32 v80, s90, v243
	v_add_u32_e32 v83, s90, v244
	v_add_u32_e32 v99, s90, v245
	v_add_u32_e32 v253, s90, v246
	v_add_u32_e32 v254, s90, v148
	v_add_u32_e32 v255, s90, v151
	v_med3_i32 v80, v80, 0, s99
	v_med3_i32 v83, v83, 0, s99
	v_med3_i32 v99, v99, 0, s99
	v_med3_i32 v253, v253, 0, s99
	v_med3_i32 v254, v254, 0, s99
	v_med3_i32 v255, v255, 0, s99
	v_mad_u32_u24 v80, v80, s100, v252
	v_mad_u32_u24 v83, v83, s100, v252
	v_mad_u32_u24 v99, v99, s100, v252
	v_mad_u32_u24 v253, v253, s100, v252
	v_mad_u32_u24 v254, v254, s100, v153
	v_mad_u32_u24 v255, v255, s100, v153
	global_load_dwordx4 v[188:191], v80, s[82:83]
	global_load_dwordx4 v[192:195], v83, s[82:83]
	global_load_dwordx4 v[196:199], v99, s[82:83]
	global_load_dwordx4 v[200:203], v253, s[82:83]
	global_load_dwordx4 v[204:207], v254, s[82:83] offset:768
	global_load_dwordx4 v[208:211], v255, s[82:83] offset:768
	global_load_dwordx4 v[212:215], v254, s[82:83] offset:832
	global_load_dwordx4 v[216:219], v255, s[82:83] offset:832
	s_waitcnt lgkmcnt(0)
	v_mfma_f32_32x32x16_bf16 v[32:47], v[116:119], v[48:51], v[32:47]
	ds_read_b64_tr_b16 v[72:73], v231
	ds_read_b64_tr_b16 v[74:75], v231 offset:512
	ds_read_b64_tr_b16 v[76:77], v231 offset:2048
	ds_read_b64_tr_b16 v[78:79], v231 offset:2560
	ds_read_b64_tr_b16 v[220:221], v231 offset:1024
	ds_read_b64_tr_b16 v[222:223], v231 offset:1536
	ds_read_b64_tr_b16 v[224:225], v231 offset:3072
	ds_read_b64_tr_b16 v[226:227], v231 offset:3584
	s_waitcnt vmcnt(8)
	ds_write_b128 v247, v[156:159]
	ds_write_b128 v247, v[160:163] offset:1024
	ds_write_b128 v111, v[164:167] offset:2048
	ds_write_b128 v111, v[168:171] offset:3072
	ds_read_b128 v[156:159], v248
	ds_read_b128 v[160:163], v249
	ds_read_b128 v[164:167], v250
	ds_read_b128 v[168:171], v251
	ds_write_b128 v112, v[172:175]
	ds_write_b128 v112, v[176:179] offset:1024
	ds_write_b128 v112, v[180:183] offset:2048
	ds_write_b128 v112, v[184:187] offset:3072
	v_mfma_f32_32x32x16_bf16 v[32:47], v[120:123], v[52:55], v[32:47]
	v_mfma_f32_32x32x16_bf16 v[32:47], v[124:127], v[56:59], v[32:47]
	v_mfma_f32_32x32x16_bf16 v[32:47], v[128:131], v[60:63], v[32:47]
	s_nop 11
	v_exp_f32_e32 v32, v32
	v_exp_f32_e32 v33, v33
	v_exp_f32_e32 v34, v34
	v_exp_f32_e32 v35, v35
	v_exp_f32_e32 v36, v36
	v_exp_f32_e32 v37, v37
	v_exp_f32_e32 v38, v38
	v_exp_f32_e32 v39, v39
	v_exp_f32_e32 v40, v40
	v_exp_f32_e32 v41, v41
	v_exp_f32_e32 v42, v42
	v_exp_f32_e32 v43, v43
	v_exp_f32_e32 v44, v44
	v_exp_f32_e32 v45, v45
	v_exp_f32_e32 v46, v46
	v_exp_f32_e32 v47, v47
	s_add_i32 s90, s76, 0
	v_lshlrev_b32_e32 v84, 4, v107
	v_add_u32_e32 v84, s90, v84
	v_add_u32_e32 v85, 0, v84
	v_add_u32_e32 v86, 16, v84
	v_add_u32_e32 v87, 32, v84
	v_add_u32_e32 v88, 48, v84
	v_cmp_gt_u32_e64 s[30:31], s98, v85
	v_cmp_gt_u32_e64 s[36:37], s98, v86
	v_cmp_gt_u32_e64 s[78:79], s98, v87
	v_cmp_gt_u32_e64 s[50:51], s98, v88
	v_cndmask_b32_e64 v32, 0, v32, s[30:31]
	v_add_u32_e32 v85, 128, v84
	v_cmp_gt_u32_e64 s[30:31], s98, v85
	v_cndmask_b32_e64 v33, 0, v33, s[36:37]
	v_add_u32_e32 v86, 144, v84
	v_cmp_gt_u32_e64 s[36:37], s98, v86
	v_cndmask_b32_e64 v34, 0, v34, s[78:79]
	v_add_u32_e32 v87, 160, v84
	v_cmp_gt_u32_e64 s[78:79], s98, v87
	v_cndmask_b32_e64 v35, 0, v35, s[50:51]
	v_add_u32_e32 v88, 176, v84
	v_cmp_gt_u32_e64 s[50:51], s98, v88
	v_cndmask_b32_e64 v36, 0, v36, s[30:31]
	v_add_u32_e32 v85, 256, v84
	v_cmp_gt_u32_e64 s[30:31], s98, v85
	v_cndmask_b32_e64 v37, 0, v37, s[36:37]
	v_add_u32_e32 v86, 272, v84
	v_cmp_gt_u32_e64 s[36:37], s98, v86
	v_cndmask_b32_e64 v38, 0, v38, s[78:79]
	v_add_u32_e32 v87, 288, v84
	v_cmp_gt_u32_e64 s[78:79], s98, v87
	v_cndmask_b32_e64 v39, 0, v39, s[50:51]
	v_add_u32_e32 v88, 304, v84
	v_cmp_gt_u32_e64 s[50:51], s98, v88
	v_cndmask_b32_e64 v40, 0, v40, s[30:31]
	v_add_u32_e32 v85, 384, v84
	v_cmp_gt_u32_e64 s[30:31], s98, v85
	v_cndmask_b32_e64 v41, 0, v41, s[36:37]
	v_add_u32_e32 v86, 400, v84
	v_cmp_gt_u32_e64 s[36:37], s98, v86
	v_cndmask_b32_e64 v42, 0, v42, s[78:79]
	v_add_u32_e32 v87, 416, v84
	v_cmp_gt_u32_e64 s[78:79], s98, v87
	v_cndmask_b32_e64 v43, 0, v43, s[50:51]
	v_add_u32_e32 v88, 432, v84
	v_cmp_gt_u32_e64 s[50:51], s98, v88
	v_nop
	v_cndmask_b32_e64 v44, 0, v44, s[30:31]
	v_cndmask_b32_e64 v45, 0, v45, s[36:37]
	v_cndmask_b32_e64 v46, 0, v46, s[78:79]
	v_cndmask_b32_e64 v47, 0, v47, s[50:51]
	v_cvt_pk_bf16_f32 v64, v32, v33
	v_cvt_pk_bf16_f32 v65, v34, v35
	v_cvt_pk_bf16_f32 v66, v36, v37
	v_cvt_pk_bf16_f32 v67, v38, v39
	v_cvt_pk_bf16_f32 v68, v40, v41
	v_cvt_pk_bf16_f32 v69, v42, v43
	v_cvt_pk_bf16_f32 v70, v44, v45
	v_cvt_pk_bf16_f32 v71, v46, v47
	v_pk_add_f32 v[232:233], v[232:233], v[32:33]
	v_pk_add_f32 v[232:233], v[232:233], v[34:35]
	v_pk_add_f32 v[232:233], v[232:233], v[36:37]
	v_pk_add_f32 v[232:233], v[232:233], v[38:39]
	v_pk_add_f32 v[232:233], v[232:233], v[40:41]
	v_pk_add_f32 v[232:233], v[232:233], v[42:43]
	v_pk_add_f32 v[232:233], v[232:233], v[44:45]
	v_pk_add_f32 v[232:233], v[232:233], v[46:47]
	ds_read2_b32 v[32:33], v115 offset0:96 offset1:97
	ds_read2_b32 v[34:35], v115 offset0:98 offset1:99
	ds_read2_b32 v[36:37], v115 offset0:104 offset1:105
	ds_read2_b32 v[38:39], v115 offset0:106 offset1:107
	ds_read2_b32 v[40:41], v115 offset0:112 offset1:113
	ds_read2_b32 v[42:43], v115 offset0:114 offset1:115
	ds_read2_b32 v[44:45], v115 offset0:120 offset1:121
	ds_read2_b32 v[46:47], v115 offset0:122 offset1:123
	s_waitcnt lgkmcnt(15)
	v_mfma_f32_32x32x16_bf16 v[0:15], v[64:67], v[72:75], v[0:15]
	v_mfma_f32_32x32x16_bf16 v[16:31], v[64:67], v[76:79], v[16:31]
	v_mfma_f32_32x32x16_bf16 v[0:15], v[68:71], v[220:223], v[0:15]
	v_mfma_f32_32x32x16_bf16 v[16:31], v[68:71], v[224:227], v[16:31]
	s_waitcnt lgkmcnt(0)
	v_mfma_f32_32x32x16_bf16 v[32:47], v[156:159], v[48:51], v[32:47]
	ds_read_b64_tr_b16 v[72:73], v231
	ds_read_b64_tr_b16 v[74:75], v231 offset:512
	ds_read_b64_tr_b16 v[76:77], v231 offset:2048
	ds_read_b64_tr_b16 v[78:79], v231 offset:2560
	ds_read_b64_tr_b16 v[220:221], v231 offset:1024
	ds_read_b64_tr_b16 v[222:223], v231 offset:1536
	ds_read_b64_tr_b16 v[224:225], v231 offset:3072
	ds_read_b64_tr_b16 v[226:227], v231 offset:3584
	s_waitcnt vmcnt(0)
	ds_write_b128 v247, v[188:191]
	ds_write_b128 v247, v[192:195] offset:1024
	ds_write_b128 v111, v[196:199] offset:2048
	ds_write_b128 v111, v[200:203] offset:3072
	ds_read_b128 v[188:191], v248
	ds_read_b128 v[192:195], v249
	ds_read_b128 v[196:199], v250
	ds_read_b128 v[200:203], v251
	ds_write_b128 v112, v[204:207]
	ds_write_b128 v112, v[208:211] offset:1024
	ds_write_b128 v112, v[212:215] offset:2048
	ds_write_b128 v112, v[216:219] offset:3072
	v_mfma_f32_32x32x16_bf16 v[32:47], v[160:163], v[52:55], v[32:47]
	v_mfma_f32_32x32x16_bf16 v[32:47], v[164:167], v[56:59], v[32:47]
	v_mfma_f32_32x32x16_bf16 v[32:47], v[168:171], v[60:63], v[32:47]
	s_nop 11
	v_exp_f32_e32 v32, v32
	v_exp_f32_e32 v33, v33
	v_exp_f32_e32 v34, v34
	v_exp_f32_e32 v35, v35
	v_exp_f32_e32 v36, v36
	v_exp_f32_e32 v37, v37
	v_exp_f32_e32 v38, v38
	v_exp_f32_e32 v39, v39
	v_exp_f32_e32 v40, v40
	v_exp_f32_e32 v41, v41
	v_exp_f32_e32 v42, v42
	v_exp_f32_e32 v43, v43
	v_exp_f32_e32 v44, v44
	v_exp_f32_e32 v45, v45
	v_exp_f32_e32 v46, v46
	v_exp_f32_e32 v47, v47
	s_add_i32 s90, s76, 512
	v_lshlrev_b32_e32 v84, 4, v107
	v_add_u32_e32 v84, s90, v84
	v_add_u32_e32 v85, 0, v84
	v_add_u32_e32 v86, 16, v84
	v_add_u32_e32 v87, 32, v84
	v_add_u32_e32 v88, 48, v84
	v_cmp_gt_u32_e64 s[30:31], s98, v85
	v_cmp_gt_u32_e64 s[36:37], s98, v86
	v_cmp_gt_u32_e64 s[78:79], s98, v87
	v_cmp_gt_u32_e64 s[50:51], s98, v88
	v_cndmask_b32_e64 v32, 0, v32, s[30:31]
	v_add_u32_e32 v85, 128, v84
	v_cmp_gt_u32_e64 s[30:31], s98, v85
	v_cndmask_b32_e64 v33, 0, v33, s[36:37]
	v_add_u32_e32 v86, 144, v84
	v_cmp_gt_u32_e64 s[36:37], s98, v86
	v_cndmask_b32_e64 v34, 0, v34, s[78:79]
	v_add_u32_e32 v87, 160, v84
	v_cmp_gt_u32_e64 s[78:79], s98, v87
	v_cndmask_b32_e64 v35, 0, v35, s[50:51]
	v_add_u32_e32 v88, 176, v84
	v_cmp_gt_u32_e64 s[50:51], s98, v88
	v_cndmask_b32_e64 v36, 0, v36, s[30:31]
	v_add_u32_e32 v85, 256, v84
	v_cmp_gt_u32_e64 s[30:31], s98, v85
	v_cndmask_b32_e64 v37, 0, v37, s[36:37]
	v_add_u32_e32 v86, 272, v84
	v_cmp_gt_u32_e64 s[36:37], s98, v86
	v_cndmask_b32_e64 v38, 0, v38, s[78:79]
	v_add_u32_e32 v87, 288, v84
	v_cmp_gt_u32_e64 s[78:79], s98, v87
	v_cndmask_b32_e64 v39, 0, v39, s[50:51]
	v_add_u32_e32 v88, 304, v84
	v_cmp_gt_u32_e64 s[50:51], s98, v88
	v_cndmask_b32_e64 v40, 0, v40, s[30:31]
	v_add_u32_e32 v85, 384, v84
	v_cmp_gt_u32_e64 s[30:31], s98, v85
	v_cndmask_b32_e64 v41, 0, v41, s[36:37]
	v_add_u32_e32 v86, 400, v84
	v_cmp_gt_u32_e64 s[36:37], s98, v86
	v_cndmask_b32_e64 v42, 0, v42, s[78:79]
	v_add_u32_e32 v87, 416, v84
	v_cmp_gt_u32_e64 s[78:79], s98, v87
	v_cndmask_b32_e64 v43, 0, v43, s[50:51]
	v_add_u32_e32 v88, 432, v84
	v_cmp_gt_u32_e64 s[50:51], s98, v88
	v_nop
	v_cndmask_b32_e64 v44, 0, v44, s[30:31]
	v_cndmask_b32_e64 v45, 0, v45, s[36:37]
	v_cndmask_b32_e64 v46, 0, v46, s[78:79]
	v_cndmask_b32_e64 v47, 0, v47, s[50:51]
	v_cvt_pk_bf16_f32 v64, v32, v33
	v_cvt_pk_bf16_f32 v65, v34, v35
	v_cvt_pk_bf16_f32 v66, v36, v37
	v_cvt_pk_bf16_f32 v67, v38, v39
	v_cvt_pk_bf16_f32 v68, v40, v41
	v_cvt_pk_bf16_f32 v69, v42, v43
	v_cvt_pk_bf16_f32 v70, v44, v45
	v_cvt_pk_bf16_f32 v71, v46, v47
	v_pk_add_f32 v[232:233], v[232:233], v[32:33]
	v_pk_add_f32 v[232:233], v[232:233], v[34:35]
	v_pk_add_f32 v[232:233], v[232:233], v[36:37]
	v_pk_add_f32 v[232:233], v[232:233], v[38:39]
	v_pk_add_f32 v[232:233], v[232:233], v[40:41]
	v_pk_add_f32 v[232:233], v[232:233], v[42:43]
	v_pk_add_f32 v[232:233], v[232:233], v[44:45]
	v_pk_add_f32 v[232:233], v[232:233], v[46:47]
	ds_read2_b32 v[32:33], v115 offset0:128 offset1:129
	ds_read2_b32 v[34:35], v115 offset0:130 offset1:131
	ds_read2_b32 v[36:37], v115 offset0:136 offset1:137
	ds_read2_b32 v[38:39], v115 offset0:138 offset1:139
	ds_read2_b32 v[40:41], v115 offset0:144 offset1:145
	ds_read2_b32 v[42:43], v115 offset0:146 offset1:147
	ds_read2_b32 v[44:45], v115 offset0:152 offset1:153
	ds_read2_b32 v[46:47], v115 offset0:154 offset1:155
	s_waitcnt lgkmcnt(15)
	v_mfma_f32_32x32x16_bf16 v[0:15], v[64:67], v[72:75], v[0:15]
	v_mfma_f32_32x32x16_bf16 v[16:31], v[64:67], v[76:79], v[16:31]
	v_mfma_f32_32x32x16_bf16 v[0:15], v[68:71], v[220:223], v[0:15]
	v_mfma_f32_32x32x16_bf16 v[16:31], v[68:71], v[224:227], v[16:31]
	s_waitcnt lgkmcnt(0)
; #define LAS __attribute__((address_space(3)))
; __device__ __forceinline__ int crow(int r, int hi) { return (r & 3) + 8 * (r >> 2) + 4 * hi; }
; __device__ __forceinline__ void dil_unit(LAS unsigned char* lds, bf16_t* proj, int seq, int hd, int T0, int rho) {
;     ...
;     LAS bf16_t* stg = (LAS bf16_t*)wbuf;
;     l += __shfl_xor(l, 32);
; #pragma unroll
;     for (int rr = 0; rr < 16; ++rr) {
;         const int j = crow(rr, hi);
	v_mfma_f32_32x32x16_bf16 v[32:47], v[188:191], v[48:51], v[32:47]
	ds_read_b64_tr_b16 v[72:73], v231
	ds_read_b64_tr_b16 v[74:75], v231 offset:512
	ds_read_b64_tr_b16 v[76:77], v231 offset:2048
	ds_read_b64_tr_b16 v[78:79], v231 offset:2560
	ds_read_b64_tr_b16 v[220:221], v231 offset:1024
	ds_read_b64_tr_b16 v[222:223], v231 offset:1536
	ds_read_b64_tr_b16 v[224:225], v231 offset:3072
	ds_read_b64_tr_b16 v[226:227], v231 offset:3584
	v_mfma_f32_32x32x16_bf16 v[32:47], v[192:195], v[52:55], v[32:47]
	v_mfma_f32_32x32x16_bf16 v[32:47], v[196:199], v[56:59], v[32:47]
	v_mfma_f32_32x32x16_bf16 v[32:47], v[200:203], v[60:63], v[32:47]
	s_nop 11
	v_exp_f32_e32 v32, v32
	v_exp_f32_e32 v33, v33
	v_exp_f32_e32 v34, v34
	v_exp_f32_e32 v35, v35
	v_exp_f32_e32 v36, v36
	v_exp_f32_e32 v37, v37
	v_exp_f32_e32 v38, v38
	v_exp_f32_e32 v39, v39
	v_exp_f32_e32 v40, v40
	v_exp_f32_e32 v41, v41
	v_exp_f32_e32 v42, v42
	v_exp_f32_e32 v43, v43
	v_exp_f32_e32 v44, v44
	v_exp_f32_e32 v45, v45
	v_exp_f32_e32 v46, v46
	v_exp_f32_e32 v47, v47
	s_add_i32 s90, s76, 1024
	v_lshlrev_b32_e32 v84, 4, v107
	v_add_u32_e32 v84, s90, v84
	v_add_u32_e32 v85, 0, v84
	v_add_u32_e32 v86, 16, v84
	v_add_u32_e32 v87, 32, v84
	v_add_u32_e32 v88, 48, v84
	v_cmp_gt_u32_e64 s[30:31], s98, v85
	v_cmp_gt_u32_e64 s[36:37], s98, v86
	v_cmp_gt_u32_e64 s[78:79], s98, v87
	v_cmp_gt_u32_e64 s[50:51], s98, v88
	v_cndmask_b32_e64 v32, 0, v32, s[30:31]
	v_add_u32_e32 v85, 128, v84
	v_cmp_gt_u32_e64 s[30:31], s98, v85
	v_cndmask_b32_e64 v33, 0, v33, s[36:37]
	v_add_u32_e32 v86, 144, v84
	v_cmp_gt_u32_e64 s[36:37], s98, v86
	v_cndmask_b32_e64 v34, 0, v34, s[78:79]
	v_add_u32_e32 v87, 160, v84
	v_cmp_gt_u32_e64 s[78:79], s98, v87
	v_cndmask_b32_e64 v35, 0, v35, s[50:51]
	v_add_u32_e32 v88, 176, v84
	v_cmp_gt_u32_e64 s[50:51], s98, v88
	v_cndmask_b32_e64 v36, 0, v36, s[30:31]
	v_add_u32_e32 v85, 256, v84
	v_cmp_gt_u32_e64 s[30:31], s98, v85
	v_cndmask_b32_e64 v37, 0, v37, s[36:37]
	v_add_u32_e32 v86, 272, v84
	v_cmp_gt_u32_e64 s[36:37], s98, v86
	v_cndmask_b32_e64 v38, 0, v38, s[78:79]
	v_add_u32_e32 v87, 288, v84
	v_cmp_gt_u32_e64 s[78:79], s98, v87
	v_cndmask_b32_e64 v39, 0, v39, s[50:51]
	v_add_u32_e32 v88, 304, v84
	v_cmp_gt_u32_e64 s[50:51], s98, v88
	v_cndmask_b32_e64 v40, 0, v40, s[30:31]
	v_add_u32_e32 v85, 384, v84
	v_cmp_gt_u32_e64 s[30:31], s98, v85
	v_cndmask_b32_e64 v41, 0, v41, s[36:37]
	v_add_u32_e32 v86, 400, v84
	v_cmp_gt_u32_e64 s[36:37], s98, v86
	v_cndmask_b32_e64 v42, 0, v42, s[78:79]
	v_add_u32_e32 v87, 416, v84
	v_cmp_gt_u32_e64 s[78:79], s98, v87
	v_cndmask_b32_e64 v43, 0, v43, s[50:51]
	v_add_u32_e32 v88, 432, v84
	v_cmp_gt_u32_e64 s[50:51], s98, v88
	v_nop
	v_cndmask_b32_e64 v44, 0, v44, s[30:31]
	v_cndmask_b32_e64 v45, 0, v45, s[36:37]
	v_cndmask_b32_e64 v46, 0, v46, s[78:79]
	v_cndmask_b32_e64 v47, 0, v47, s[50:51]
	v_cvt_pk_bf16_f32 v64, v32, v33
	v_cvt_pk_bf16_f32 v65, v34, v35
	v_cvt_pk_bf16_f32 v66, v36, v37
	v_cvt_pk_bf16_f32 v67, v38, v39
	v_cvt_pk_bf16_f32 v68, v40, v41
	v_cvt_pk_bf16_f32 v69, v42, v43
	v_cvt_pk_bf16_f32 v70, v44, v45
	v_cvt_pk_bf16_f32 v71, v46, v47
	v_pk_add_f32 v[232:233], v[232:233], v[32:33]
	v_pk_add_f32 v[232:233], v[232:233], v[34:35]
	v_pk_add_f32 v[232:233], v[232:233], v[36:37]
	v_pk_add_f32 v[232:233], v[232:233], v[38:39]
	v_pk_add_f32 v[232:233], v[232:233], v[40:41]
	v_pk_add_f32 v[232:233], v[232:233], v[42:43]
	v_pk_add_f32 v[232:233], v[232:233], v[44:45]
	v_pk_add_f32 v[232:233], v[232:233], v[46:47]
	s_waitcnt lgkmcnt(0)
	v_mfma_f32_32x32x16_bf16 v[0:15], v[64:67], v[72:75], v[0:15]
	v_mfma_f32_32x32x16_bf16 v[16:31], v[64:67], v[76:79], v[16:31]
	v_mfma_f32_32x32x16_bf16 v[0:15], v[68:71], v[220:223], v[0:15]
	v_mfma_f32_32x32x16_bf16 v[16:31], v[68:71], v[224:227], v[16:31]
	v_add_f32_e32 v113, v232, v233
	v_or_b32_e32 v114, 1, v107
	v_or_b32_e32 v97, 2, v107
	v_or_b32_e32 v96, 3, v107
	v_or_b32_e32 v95, 8, v107
	v_or_b32_e32 v94, 9, v107
	v_or_b32_e32 v93, 10, v107
	v_or_b32_e32 v92, 11, v107
	v_or_b32_e32 v91, 16, v107
	v_or_b32_e32 v90, 17, v107
	v_or_b32_e32 v89, 18, v107
	v_or_b32_e32 v88, 19, v107
	v_or_b32_e32 v87, 24, v107
	v_or_b32_e32 v86, 25, v107
	v_or_b32_e32 v85, 26, v107
	v_or_b32_e32 v84, 27, v107
	s_nop 11
	s_branch .LBB0_553

; #define LAS __attribute__((address_space(3)))
; #define GAS __attribute__((address_space(1)))
; __device__ __forceinline__ void dil_unit(LAS unsigned char* lds, bf16_t* proj, int seq, int hd, int T0, int rho) {
;     ...
;     const int tid = tid_, lane = tid & 63, r32 = lane & 31, hi = lane >> 5, wid = __builtin_amdgcn_readfirstlane(tid >> 6);
;     bf16_t* base = proj + (size_t)seq * SEQ * NIN;
;     LAS unsigned char* wbuf = lds + wid * 4096;
;     const LAS unsigned char* vp = wbuf + ((lane >> 4) & 1) * 32 + (lane & 3) * 8 + (4 * hi + ((lane & 15) >> 2)) * 64;
;     const int P0 = T0 + rho;
;     bf16x8 qr[4];
; #pragma unroll
;     for (int ks = 0; ks < 4; ++ks) qr[ks] = *(const GAS bf16x8*)(base + (size_t)(P0 + 16 * r32) * NIN + PC_LQ + hd * 64 + 16 * ks + 8 * hi);
;     f32x16 o0 = {}, o1 = {}; float l = 0.f;
;     const bool bound = (T0 < 1024) || (T0 >= 15360);
; __device__ __forceinline__ void attn_phase(unsigned char* ws, int l, LAS unsigned char* lds, int G) {
;     ...
;         const int sh = bu >> 6, rem = bu & 63, T0 = (rem >> 1) * 512, rho = (rem & 1) * 8 + wid;
;         dil_unit(lds, proj, sh / 6, sh % 6, T0, rho);
.LBB0_1266:
	s_lshr_b32 s82, s60, 8
	s_mul_i32 s82, s82, 13
	s_add_i32 s82, s82, s60
	s_ashr_i32 s4, s60, 6
	s_mul_hi_i32 s9, s4, 0x2aaaaaab
	s_lshl_b32 s5, s82, 8
	s_lshr_b32 s10, s9, 31
	s_and_b32 s8, s5, 0x3e00
	s_lshl_b32 s5, s82, 3
	s_add_i32 s9, s9, s10
	s_and_b32 s5, s5, 8
	s_mul_i32 s10, s9, 6
	s_add_i32 s5, s5, s61
	s_sub_i32 s10, s4, s10
	s_mul_hi_i32 s4, s9, 0x6000000
	s_mul_i32 s9, s9, 0x6000000
	v_mov_b32_e32 v2, v154
	s_add_u32 s52, s44, s9
	s_addc_u32 s53, s45, s4
	v_and_b32_e32 v105, 31, v2
	s_add_i32 s67, s5, s8
	v_lshl_add_u32 v3, v105, 4, s67
	v_mov_b64_e32 v[0:1], s[52:53]
	s_lshl_b32 s54, s10, 6
	v_bfe_u32 v106, v2, 5, 1
	v_mad_u64_u32 v[0:1], s[4:5], v3, s62, v[0:1]
	s_ashr_i32 s55, s54, 31
	v_lshl_add_u64 v[0:1], s[54:55], 1, v[0:1]
	v_lshlrev_b32_e32 v80, 4, v106
	v_lshl_add_u64 v[0:1], v[0:1], 0, v[80:81]
	global_load_dwordx4 v[48:51], v[0:1], off offset:1280
	global_load_dwordx4 v[52:55], v[0:1], off offset:1312
	global_load_dwordx4 v[56:59], v[0:1], off offset:1344
	global_load_dwordx4 v[60:63], v[0:1], off offset:1376
	v_readfirstlane_b32 s4, v2
	s_lshl_b32 s4, s4, 6
	s_and_b32 s4, s4, 0xfffff000
	v_lshlrev_b32_e32 v0, 1, v2
	v_lshlrev_b32_e32 v104, 3, v2
	v_lshlrev_b32_e32 v107, 2, v106
	v_lshrrev_b32_e32 v1, 2, v2
	v_and_b32_e32 v103, 63, v2
	v_and_b32_e32 v0, 32, v0
	v_and_b32_e32 v98, 24, v104
	v_and_or_b32 v1, v1, 3, v107
	s_add_i32 s69, s4, 0
	v_lshlrev_b32_e32 v108, 6, v1
	v_lshlrev_b32_e32 v1, 3, v106
	v_add3_u32 v109, s69, v0, v98
	s_addk_i32 s8, 0xc400
	v_lshrrev_b32_e32 v110, 2, v103
	v_lshlrev_b32_e32 v0, 4, v103
	s_mov_b64 s[4:5], -1
	s_cmp_gt_u32 s8, 0xffffc7ff
	v_lshlrev_b32_e32 v100, 1, v98
	s_mul_i32 s8, s10, 0x1c00
	v_lshlrev_b32_e32 v82, 1, v1
	v_or_b32_e32 v111, 16, v110
	v_add_u32_e32 v112, s69, v0
	s_cbranch_scc0 .LBB0_1270
	s_movk_i32 s100, 0x1800
	s_add_i32 s101, s8, 0x15c00
	s_lshl_b32 s90, s54, 1
	s_add_u32 s82, s52, s90
	s_addc_u32 s83, s53, 0
	s_add_u32 s82, s82, 0x1200
	s_addc_u32 s83, s83, 0
	s_sub_i32 s90, s67, 64
	s_mul_i32 s90, s90, 0x1800
	s_add_u32 s84, s82, s90
	s_addc_u32 s85, s83, 0
	s_sub_i32 s90, s67, 256
	s_mul_i32 s90, s90, 0x1800
	s_add_u32 s86, s82, s90
	s_addc_u32 s87, s83, 0
	s_sub_i32 s90, s67, 1024
	s_mul_i32 s90, s90, 0x1800
	s_add_u32 s88, s82, s90
	s_addc_u32 s89, s83, 0
	v_lshlrev_b32_e32 v153, 1, v98
	v_mad_u32_u24 v80, v105, s100, v82
	v_mad_u32_u24 v100, v110, s100, v153
	v_add_u32_e32 v149, 0x18000, v100
	v_lshlrev_b32_e32 v83, 2, v105
	v_mad_u32_u24 v83, v83, s100, v82
	v_lshlrev_b32_e32 v101, 2, v110
	v_mad_u32_u24 v101, v101, s100, v153
	v_add_u32_e32 v150, 0x60000, v101
	v_lshlrev_b32_e32 v99, 4, v105
	v_mad_u32_u24 v99, v99, s100, v82
	v_lshlrev_b32_e32 v148, 4, v110
	v_mad_u32_u24 v148, v148, s100, v153
	v_add_u32_e32 v151, 0x180000, v148
	v_lshrrev_b32_e32 v249, 3, v103
	v_and_b32_e32 v250, 7, v103
	v_lshlrev_b32_e32 v250, 4, v250
	v_add_u32_e32 v235, 0, v249
	v_mad_u32_u24 v235, v235, s100, v250
	v_add_u32_e32 v236, 8, v249
	v_mad_u32_u24 v236, v236, s100, v250
	v_add_u32_e32 v237, 16, v249
	v_mad_u32_u24 v237, v237, s100, v250
	v_add_u32_e32 v238, 24, v249
	v_mad_u32_u24 v238, v238, s100, v250
	v_add_u32_e32 v239, 0, v249
	v_lshlrev_b32_e32 v239, 2, v239
	v_mad_u32_u24 v239, v239, s100, v250
	v_add_u32_e32 v240, 8, v249
	v_lshlrev_b32_e32 v240, 2, v240
	v_mad_u32_u24 v240, v240, s100, v250
	v_add_u32_e32 v241, 16, v249
	v_lshlrev_b32_e32 v241, 2, v241
	v_mad_u32_u24 v241, v241, s100, v250
	v_add_u32_e32 v242, 24, v249
	v_lshlrev_b32_e32 v242, 2, v242
	v_mad_u32_u24 v242, v242, s100, v250
	v_add_u32_e32 v243, 0, v249
	v_lshlrev_b32_e32 v243, 4, v243
	v_mad_u32_u24 v243, v243, s100, v250
	v_add_u32_e32 v244, 8, v249
	v_lshlrev_b32_e32 v244, 4, v244
	v_mad_u32_u24 v244, v244, s100, v250
	v_add_u32_e32 v245, 16, v249
	v_lshlrev_b32_e32 v245, 4, v245
	v_mad_u32_u24 v245, v245, s100, v250
	v_add_u32_e32 v246, 24, v249
	v_lshlrev_b32_e32 v246, 4, v246
	v_mad_u32_u24 v246, v246, s100, v250
	v_and_b32_e32 v247, 7, v249
	v_lshlrev_b32_e32 v247, 4, v247
	v_xor_b32_e32 v247, v247, v112
	v_xor_b32_e32 v111, 16, v247
	v_and_b32_e32 v153, 7, v105
	v_lshrrev_b32_e32 v248, 4, v105
	v_xor_b32_e32 v153, v153, v248
	v_or_b32_e32 v248, 0, v106
	v_xor_b32_e32 v248, v248, v153
	v_lshlrev_b32_e32 v248, 4, v248
	v_lshl_add_u32 v248, v105, 7, v248
	v_add_u32_e32 v248, s69, v248
	v_or_b32_e32 v249, 2, v106
	v_xor_b32_e32 v249, v249, v153
	v_lshlrev_b32_e32 v249, 4, v249
	v_lshl_add_u32 v249, v105, 7, v249
	v_add_u32_e32 v249, s69, v249
	v_or_b32_e32 v250, 4, v106
	v_xor_b32_e32 v250, v250, v153
	v_lshlrev_b32_e32 v250, 4, v250
	v_lshl_add_u32 v250, v105, 7, v250
	v_add_u32_e32 v250, s69, v250
	v_or_b32_e32 v251, 6, v106
	v_xor_b32_e32 v251, v251, v153
	v_lshlrev_b32_e32 v251, 4, v251
	v_lshl_add_u32 v251, v105, 7, v251
	v_add_u32_e32 v251, s69, v251
	v_lshlrev_b32_e32 v153, 1, v98
	v_mul_u32_u24_e32 v228, 17, v105
	v_sub_u32_e32 v228, v107, v228
	s_mul_i32 s90, s54, 153
	s_lshr_b32 s90, s90, 1
	s_add_i32 s90, s90, 34876
	v_lshl_add_u32 v228, v228, 2, s90
	v_mul_u32_u24_e32 v229, 5, v105
	v_sub_u32_e32 v229, v107, v229
	v_add_u32_e32 v229, v229, v106
	s_mul_i32 s90, s54, 30
	s_add_i32 s90, s90, 66156
	v_lshl_add_u32 v229, v229, 2, s90
	v_sub_u32_e32 v230, v107, v105
	s_add_i32 s90, s101, 6364
	v_lshl_add_u32 v230, v230, 2, s90
	v_add_u32_e32 v231, v109, v108
	v_mov_b64_e32 v[232:233], 0
	v_mov_b64_e32 v[0:1], 0
	v_mov_b64_e32 v[2:3], 0
	v_mov_b64_e32 v[4:5], 0
	v_mov_b64_e32 v[6:7], 0
	v_mov_b64_e32 v[8:9], 0
	v_mov_b64_e32 v[10:11], 0
	v_mov_b64_e32 v[12:13], 0
	v_mov_b64_e32 v[14:15], 0
	v_mov_b64_e32 v[16:17], 0
	v_mov_b64_e32 v[18:19], 0
	v_mov_b64_e32 v[20:21], 0
	v_mov_b64_e32 v[22:23], 0
	v_mov_b64_e32 v[24:25], 0
	v_mov_b64_e32 v[26:27], 0
	v_mov_b64_e32 v[28:29], 0
	v_mov_b64_e32 v[30:31], 0
	global_load_dwordx4 v[116:119], v235, s[84:85]
	global_load_dwordx4 v[120:123], v236, s[84:85]
	global_load_dwordx4 v[124:127], v237, s[84:85]
	global_load_dwordx4 v[128:131], v238, s[84:85]
	global_load_dwordx4 v[132:135], v100, s[84:85] offset:768
	global_load_dwordx4 v[136:139], v149, s[84:85] offset:768
	global_load_dwordx4 v[140:143], v100, s[84:85] offset:832
	global_load_dwordx4 v[144:147], v149, s[84:85] offset:832
	s_add_u32 s84, s84, 0x30000
	s_addc_u32 s85, s85, 0
	global_load_dwordx4 v[156:159], v235, s[84:85]
	global_load_dwordx4 v[160:163], v236, s[84:85]
	global_load_dwordx4 v[164:167], v237, s[84:85]
	global_load_dwordx4 v[168:171], v238, s[84:85]
	global_load_dwordx4 v[172:175], v100, s[84:85] offset:768
	global_load_dwordx4 v[176:179], v149, s[84:85] offset:768
	global_load_dwordx4 v[180:183], v100, s[84:85] offset:832
	global_load_dwordx4 v[184:187], v149, s[84:85] offset:832
	s_add_u32 s84, s84, 0x30000
	s_addc_u32 s85, s85, 0
	global_load_dwordx4 v[188:191], v235, s[84:85]
	global_load_dwordx4 v[192:195], v236, s[84:85]
	global_load_dwordx4 v[196:199], v237, s[84:85]
	global_load_dwordx4 v[200:203], v238, s[84:85]
	global_load_dwordx4 v[204:207], v100, s[84:85] offset:768
	global_load_dwordx4 v[208:211], v149, s[84:85] offset:768
	global_load_dwordx4 v[212:215], v100, s[84:85] offset:832
	global_load_dwordx4 v[216:219], v149, s[84:85] offset:832
	s_add_u32 s84, s84, 0x30000
	s_addc_u32 s85, s85, 0
	s_waitcnt vmcnt(16)
	ds_write_b128 v247, v[116:119]
	ds_write_b128 v247, v[120:123] offset:1024
	ds_write_b128 v111, v[124:127] offset:2048
	ds_write_b128 v111, v[128:131] offset:3072
	ds_read_b128 v[116:119], v248
	ds_read_b128 v[120:123], v249
	ds_read_b128 v[124:127], v250
	ds_read_b128 v[128:131], v251
	ds_write_b128 v112, v[132:135]
	ds_write_b128 v112, v[136:139] offset:1024
	ds_write_b128 v112, v[140:143] offset:2048
	ds_write_b128 v112, v[144:147] offset:3072
	v_mov_b32_e32 v115, v228
	ds_read2_b32 v[32:33], v115 offset0:0 offset1:1
	ds_read2_b32 v[34:35], v115 offset0:2 offset1:3
	ds_read2_b32 v[36:37], v115 offset0:8 offset1:9
	ds_read2_b32 v[38:39], v115 offset0:10 offset1:11
	ds_read2_b32 v[40:41], v115 offset0:17 offset1:18
	ds_read2_b32 v[42:43], v115 offset0:19 offset1:20
	ds_read2_b32 v[44:45], v115 offset0:25 offset1:26
	ds_read2_b32 v[46:47], v115 offset0:27 offset1:28
	s_waitcnt lgkmcnt(0)
	v_mfma_f32_32x32x16_bf16 v[32:47], v[116:119], v[48:51], v[32:47]
	ds_read_b64_tr_b16 v[72:73], v231
	ds_read_b64_tr_b16 v[74:75], v231 offset:512
	ds_read_b64_tr_b16 v[76:77], v231 offset:2048
	ds_read_b64_tr_b16 v[78:79], v231 offset:2560
	ds_read_b64_tr_b16 v[220:221], v231 offset:1024
	ds_read_b64_tr_b16 v[222:223], v231 offset:1536
	ds_read_b64_tr_b16 v[224:225], v231 offset:3072
	ds_read_b64_tr_b16 v[226:227], v231 offset:3584
	s_waitcnt vmcnt(8)
	ds_write_b128 v247, v[156:159]
	ds_write_b128 v247, v[160:163] offset:1024
	ds_write_b128 v111, v[164:167] offset:2048
	ds_write_b128 v111, v[168:171] offset:3072
	ds_read_b128 v[156:159], v248
	ds_read_b128 v[160:163], v249
	ds_read_b128 v[164:167], v250
	ds_read_b128 v[168:171], v251
	ds_write_b128 v112, v[172:175]
	ds_write_b128 v112, v[176:179] offset:1024
	ds_write_b128 v112, v[180:183] offset:2048
	ds_write_b128 v112, v[184:187] offset:3072
	v_mfma_f32_32x32x16_bf16 v[32:47], v[120:123], v[52:55], v[32:47]
	v_mfma_f32_32x32x16_bf16 v[32:47], v[124:127], v[56:59], v[32:47]
	v_mfma_f32_32x32x16_bf16 v[32:47], v[128:131], v[60:63], v[32:47]
	s_nop 11
	v_exp_f32_e32 v32, v32
	v_exp_f32_e32 v33, v33
	v_exp_f32_e32 v34, v34
	v_exp_f32_e32 v35, v35
	v_exp_f32_e32 v36, v36
	v_exp_f32_e32 v37, v37
	v_exp_f32_e32 v38, v38
	v_exp_f32_e32 v39, v39
	v_exp_f32_e32 v40, v40
	v_exp_f32_e32 v41, v41
	v_exp_f32_e32 v42, v42
	v_exp_f32_e32 v43, v43
	v_exp_f32_e32 v44, v44
	v_exp_f32_e32 v45, v45
	v_exp_f32_e32 v46, v46
	v_exp_f32_e32 v47, v47
	v_cvt_pk_bf16_f32 v64, v32, v33
	v_cvt_pk_bf16_f32 v65, v34, v35
	v_cvt_pk_bf16_f32 v66, v36, v37
	v_cvt_pk_bf16_f32 v67, v38, v39
	v_cvt_pk_bf16_f32 v68, v40, v41
	v_cvt_pk_bf16_f32 v69, v42, v43
	v_cvt_pk_bf16_f32 v70, v44, v45
	v_cvt_pk_bf16_f32 v71, v46, v47
	v_pk_add_f32 v[232:233], v[232:233], v[32:33]
	v_pk_add_f32 v[232:233], v[232:233], v[34:35]
	v_pk_add_f32 v[232:233], v[232:233], v[36:37]
	v_pk_add_f32 v[232:233], v[232:233], v[38:39]
	v_pk_add_f32 v[232:233], v[232:233], v[40:41]
	v_pk_add_f32 v[232:233], v[232:233], v[42:43]
	v_pk_add_f32 v[232:233], v[232:233], v[44:45]
	v_pk_add_f32 v[232:233], v[232:233], v[46:47]
	ds_read2_b32 v[32:33], v115 offset0:34 offset1:35
	ds_read2_b32 v[34:35], v115 offset0:36 offset1:37
	ds_read2_b32 v[36:37], v115 offset0:42 offset1:43
	ds_read2_b32 v[38:39], v115 offset0:44 offset1:45
	ds_read2_b32 v[40:41], v115 offset0:51 offset1:52
	ds_read2_b32 v[42:43], v115 offset0:53 offset1:54
	ds_read2_b32 v[44:45], v115 offset0:59 offset1:60
	ds_read2_b32 v[46:47], v115 offset0:61 offset1:62
	s_waitcnt lgkmcnt(15)
	v_mfma_f32_32x32x16_bf16 v[0:15], v[64:67], v[72:75], v[0:15]
	v_mfma_f32_32x32x16_bf16 v[16:31], v[64:67], v[76:79], v[16:31]
	v_mfma_f32_32x32x16_bf16 v[0:15], v[68:71], v[220:223], v[0:15]
	v_mfma_f32_32x32x16_bf16 v[16:31], v[68:71], v[224:227], v[16:31]
	global_load_dwordx4 v[116:119], v235, s[84:85]
	global_load_dwordx4 v[120:123], v236, s[84:85]
	global_load_dwordx4 v[124:127], v237, s[84:85]
	global_load_dwordx4 v[128:131], v238, s[84:85]
	global_load_dwordx4 v[132:135], v100, s[84:85] offset:768
	global_load_dwordx4 v[136:139], v149, s[84:85] offset:768
	global_load_dwordx4 v[140:143], v100, s[84:85] offset:832
	global_load_dwordx4 v[144:147], v149, s[84:85] offset:832
	s_add_u32 s84, s84, 0x30000
	s_addc_u32 s85, s85, 0
	s_waitcnt lgkmcnt(0)
	v_mfma_f32_32x32x16_bf16 v[32:47], v[156:159], v[48:51], v[32:47]
	ds_read_b64_tr_b16 v[72:73], v231
	ds_read_b64_tr_b16 v[74:75], v231 offset:512
	ds_read_b64_tr_b16 v[76:77], v231 offset:2048
	ds_read_b64_tr_b16 v[78:79], v231 offset:2560
	ds_read_b64_tr_b16 v[220:221], v231 offset:1024
	ds_read_b64_tr_b16 v[222:223], v231 offset:1536
	ds_read_b64_tr_b16 v[224:225], v231 offset:3072
	ds_read_b64_tr_b16 v[226:227], v231 offset:3584
	s_waitcnt vmcnt(8)
	ds_write_b128 v247, v[188:191]
	ds_write_b128 v247, v[192:195] offset:1024
	ds_write_b128 v111, v[196:199] offset:2048
	ds_write_b128 v111, v[200:203] offset:3072
	ds_read_b128 v[188:191], v248
	ds_read_b128 v[192:195], v249
	ds_read_b128 v[196:199], v250
	ds_read_b128 v[200:203], v251
	ds_write_b128 v112, v[204:207]
	ds_write_b128 v112, v[208:211] offset:1024
	ds_write_b128 v112, v[212:215] offset:2048
	ds_write_b128 v112, v[216:219] offset:3072
	v_mfma_f32_32x32x16_bf16 v[32:47], v[160:163], v[52:55], v[32:47]
	v_mfma_f32_32x32x16_bf16 v[32:47], v[164:167], v[56:59], v[32:47]
	v_mfma_f32_32x32x16_bf16 v[32:47], v[168:171], v[60:63], v[32:47]
	s_nop 11
	v_exp_f32_e32 v32, v32
	v_exp_f32_e32 v33, v33
	v_exp_f32_e32 v34, v34
	v_exp_f32_e32 v35, v35
	v_exp_f32_e32 v36, v36
	v_exp_f32_e32 v37, v37
	v_exp_f32_e32 v38, v38
	v_exp_f32_e32 v39, v39
	v_exp_f32_e32 v40, v40
	v_exp_f32_e32 v41, v41
	v_exp_f32_e32 v42, v42
	v_exp_f32_e32 v43, v43
	v_exp_f32_e32 v44, v44
	v_exp_f32_e32 v45, v45
	v_exp_f32_e32 v46, v46
	v_exp_f32_e32 v47, v47
	v_cvt_pk_bf16_f32 v64, v32, v33
	v_cvt_pk_bf16_f32 v65, v34, v35
	v_cvt_pk_bf16_f32 v66, v36, v37
	v_cvt_pk_bf16_f32 v67, v38, v39
	v_cvt_pk_bf16_f32 v68, v40, v41
	v_cvt_pk_bf16_f32 v69, v42, v43
	v_cvt_pk_bf16_f32 v70, v44, v45
	v_cvt_pk_bf16_f32 v71, v46, v47
	v_pk_add_f32 v[232:233], v[232:233], v[32:33]
	v_pk_add_f32 v[232:233], v[232:233], v[34:35]
	v_pk_add_f32 v[232:233], v[232:233], v[36:37]
	v_pk_add_f32 v[232:233], v[232:233], v[38:39]
	v_pk_add_f32 v[232:233], v[232:233], v[40:41]
	v_pk_add_f32 v[232:233], v[232:233], v[42:43]
	v_pk_add_f32 v[232:233], v[232:233], v[44:45]
	v_pk_add_f32 v[232:233], v[232:233], v[46:47]
	ds_read2_b32 v[32:33], v115 offset0:68 offset1:69
	ds_read2_b32 v[34:35], v115 offset0:70 offset1:71
	ds_read2_b32 v[36:37], v115 offset0:76 offset1:77
	ds_read2_b32 v[38:39], v115 offset0:78 offset1:79
	ds_read2_b32 v[40:41], v115 offset0:85 offset1:86
	ds_read2_b32 v[42:43], v115 offset0:87 offset1:88
	ds_read2_b32 v[44:45], v115 offset0:93 offset1:94
	ds_read2_b32 v[46:47], v115 offset0:95 offset1:96
	s_waitcnt lgkmcnt(15)
	v_mfma_f32_32x32x16_bf16 v[0:15], v[64:67], v[72:75], v[0:15]
	v_mfma_f32_32x32x16_bf16 v[16:31], v[64:67], v[76:79], v[16:31]
	v_mfma_f32_32x32x16_bf16 v[0:15], v[68:71], v[220:223], v[0:15]
	v_mfma_f32_32x32x16_bf16 v[16:31], v[68:71], v[224:227], v[16:31]
	global_load_dwordx4 v[156:159], v235, s[84:85]
	global_load_dwordx4 v[160:163], v236, s[84:85]
	global_load_dwordx4 v[164:167], v237, s[84:85]
	global_load_dwordx4 v[168:171], v238, s[84:85]
	global_load_dwordx4 v[172:175], v100, s[84:85] offset:768
	global_load_dwordx4 v[176:179], v149, s[84:85] offset:768
	global_load_dwordx4 v[180:183], v100, s[84:85] offset:832
	global_load_dwordx4 v[184:187], v149, s[84:85] offset:832
	s_add_u32 s84, s84, 0x30000
	s_addc_u32 s85, s85, 0
	s_waitcnt lgkmcnt(0)
	v_mfma_f32_32x32x16_bf16 v[32:47], v[188:191], v[48:51], v[32:47]
	ds_read_b64_tr_b16 v[72:73], v231
	ds_read_b64_tr_b16 v[74:75], v231 offset:512
	ds_read_b64_tr_b16 v[76:77], v231 offset:2048
	ds_read_b64_tr_b16 v[78:79], v231 offset:2560
	ds_read_b64_tr_b16 v[220:221], v231 offset:1024
	ds_read_b64_tr_b16 v[222:223], v231 offset:1536
	ds_read_b64_tr_b16 v[224:225], v231 offset:3072
	ds_read_b64_tr_b16 v[226:227], v231 offset:3584
	s_waitcnt vmcnt(8)
	ds_write_b128 v247, v[116:119]
	ds_write_b128 v247, v[120:123] offset:1024
	ds_write_b128 v111, v[124:127] offset:2048
	ds_write_b128 v111, v[128:131] offset:3072
	ds_read_b128 v[116:119], v248
	ds_read_b128 v[120:123], v249
	ds_read_b128 v[124:127], v250
	ds_read_b128 v[128:131], v251
	ds_write_b128 v112, v[132:135]
	ds_write_b128 v112, v[136:139] offset:1024
	ds_write_b128 v112, v[140:143] offset:2048
	ds_write_b128 v112, v[144:147] offset:3072
	v_mfma_f32_32x32x16_bf16 v[32:47], v[192:195], v[52:55], v[32:47]
	v_mfma_f32_32x32x16_bf16 v[32:47], v[196:199], v[56:59], v[32:47]
	v_mfma_f32_32x32x16_bf16 v[32:47], v[200:203], v[60:63], v[32:47]
	s_nop 11
	v_exp_f32_e32 v32, v32
	v_exp_f32_e32 v33, v33
	v_exp_f32_e32 v34, v34
	v_exp_f32_e32 v35, v35
	v_exp_f32_e32 v36, v36
	v_exp_f32_e32 v37, v37
	v_exp_f32_e32 v38, v38
	v_exp_f32_e32 v39, v39
	v_exp_f32_e32 v40, v40
	v_exp_f32_e32 v41, v41
	v_exp_f32_e32 v42, v42
	v_exp_f32_e32 v43, v43
	v_exp_f32_e32 v44, v44
	v_exp_f32_e32 v45, v45
	v_exp_f32_e32 v46, v46
	v_exp_f32_e32 v47, v47
	v_cvt_pk_bf16_f32 v64, v32, v33
	v_cvt_pk_bf16_f32 v65, v34, v35
	v_cvt_pk_bf16_f32 v66, v36, v37
	v_cvt_pk_bf16_f32 v67, v38, v39
	v_cvt_pk_bf16_f32 v68, v40, v41
	v_cvt_pk_bf16_f32 v69, v42, v43
	v_cvt_pk_bf16_f32 v70, v44, v45
	v_cvt_pk_bf16_f32 v71, v46, v47
	v_pk_add_f32 v[232:233], v[232:233], v[32:33]
	v_pk_add_f32 v[232:233], v[232:233], v[34:35]
	v_pk_add_f32 v[232:233], v[232:233], v[36:37]
	v_pk_add_f32 v[232:233], v[232:233], v[38:39]
	v_pk_add_f32 v[232:233], v[232:233], v[40:41]
	v_pk_add_f32 v[232:233], v[232:233], v[42:43]
	v_pk_add_f32 v[232:233], v[232:233], v[44:45]
	v_pk_add_f32 v[232:233], v[232:233], v[46:47]
	ds_read2_b32 v[32:33], v115 offset0:102 offset1:103
	ds_read2_b32 v[34:35], v115 offset0:104 offset1:105
	ds_read2_b32 v[36:37], v115 offset0:110 offset1:111
	ds_read2_b32 v[38:39], v115 offset0:112 offset1:113
	ds_read2_b32 v[40:41], v115 offset0:119 offset1:120
	ds_read2_b32 v[42:43], v115 offset0:121 offset1:122
	ds_read2_b32 v[44:45], v115 offset0:127 offset1:128
	ds_read2_b32 v[46:47], v115 offset0:129 offset1:130
	s_waitcnt lgkmcnt(15)
	v_mfma_f32_32x32x16_bf16 v[0:15], v[64:67], v[72:75], v[0:15]
	v_mfma_f32_32x32x16_bf16 v[16:31], v[64:67], v[76:79], v[16:31]
	v_mfma_f32_32x32x16_bf16 v[0:15], v[68:71], v[220:223], v[0:15]
	v_mfma_f32_32x32x16_bf16 v[16:31], v[68:71], v[224:227], v[16:31]
	global_load_dwordx4 v[188:191], v235, s[84:85]
	global_load_dwordx4 v[192:195], v236, s[84:85]
	global_load_dwordx4 v[196:199], v237, s[84:85]
	global_load_dwordx4 v[200:203], v238, s[84:85]
	global_load_dwordx4 v[204:207], v100, s[84:85] offset:768
	global_load_dwordx4 v[208:211], v149, s[84:85] offset:768
	global_load_dwordx4 v[212:215], v100, s[84:85] offset:832
	global_load_dwordx4 v[216:219], v149, s[84:85] offset:832
	s_add_u32 s84, s84, 0x30000
	s_addc_u32 s85, s85, 0
	s_waitcnt lgkmcnt(0)
	v_mfma_f32_32x32x16_bf16 v[32:47], v[116:119], v[48:51], v[32:47]
	ds_read_b64_tr_b16 v[72:73], v231
	ds_read_b64_tr_b16 v[74:75], v231 offset:512
	ds_read_b64_tr_b16 v[76:77], v231 offset:2048
	ds_read_b64_tr_b16 v[78:79], v231 offset:2560
	ds_read_b64_tr_b16 v[220:221], v231 offset:1024
	ds_read_b64_tr_b16 v[222:223], v231 offset:1536
	ds_read_b64_tr_b16 v[224:225], v231 offset:3072
	ds_read_b64_tr_b16 v[226:227], v231 offset:3584
	s_waitcnt vmcnt(8)
	ds_write_b128 v247, v[156:159]
	ds_write_b128 v247, v[160:163] offset:1024
	ds_write_b128 v111, v[164:167] offset:2048
	ds_write_b128 v111, v[168:171] offset:3072
	ds_read_b128 v[156:159], v248
	ds_read_b128 v[160:163], v249
	ds_read_b128 v[164:167], v250
	ds_read_b128 v[168:171], v251
	ds_write_b128 v112, v[172:175]
	ds_write_b128 v112, v[176:179] offset:1024
	ds_write_b128 v112, v[180:183] offset:2048
	ds_write_b128 v112, v[184:187] offset:3072
	v_mfma_f32_32x32x16_bf16 v[32:47], v[120:123], v[52:55], v[32:47]
	v_mfma_f32_32x32x16_bf16 v[32:47], v[124:127], v[56:59], v[32:47]
	v_mfma_f32_32x32x16_bf16 v[32:47], v[128:131], v[60:63], v[32:47]
	s_nop 11
	v_exp_f32_e32 v32, v32
	v_exp_f32_e32 v33, v33
	v_exp_f32_e32 v34, v34
	v_exp_f32_e32 v35, v35
	v_exp_f32_e32 v36, v36
	v_exp_f32_e32 v37, v37
	v_exp_f32_e32 v38, v38
	v_exp_f32_e32 v39, v39
	v_exp_f32_e32 v40, v40
	v_exp_f32_e32 v41, v41
	v_exp_f32_e32 v42, v42
	v_exp_f32_e32 v43, v43
	v_exp_f32_e32 v44, v44
	v_exp_f32_e32 v45, v45
	v_exp_f32_e32 v46, v46
	v_exp_f32_e32 v47, v47
	v_cvt_pk_bf16_f32 v64, v32, v33
	v_cvt_pk_bf16_f32 v65, v34, v35
	v_cvt_pk_bf16_f32 v66, v36, v37
	v_cvt_pk_bf16_f32 v67, v38, v39
	v_cvt_pk_bf16_f32 v68, v40, v41
	v_cvt_pk_bf16_f32 v69, v42, v43
	v_cvt_pk_bf16_f32 v70, v44, v45
	v_cvt_pk_bf16_f32 v71, v46, v47
	v_pk_add_f32 v[232:233], v[232:233], v[32:33]
	v_pk_add_f32 v[232:233], v[232:233], v[34:35]
	v_pk_add_f32 v[232:233], v[232:233], v[36:37]
	v_pk_add_f32 v[232:233], v[232:233], v[38:39]
	v_pk_add_f32 v[232:233], v[232:233], v[40:41]
	v_pk_add_f32 v[232:233], v[232:233], v[42:43]
	v_pk_add_f32 v[232:233], v[232:233], v[44:45]
	v_pk_add_f32 v[232:233], v[232:233], v[46:47]
	ds_read2_b32 v[32:33], v115 offset0:136 offset1:137
	ds_read2_b32 v[34:35], v115 offset0:138 offset1:139
	ds_read2_b32 v[36:37], v115 offset0:144 offset1:145
	ds_read2_b32 v[38:39], v115 offset0:146 offset1:147
	ds_read2_b32 v[40:41], v115 offset0:153 offset1:154
	ds_read2_b32 v[42:43], v115 offset0:155 offset1:156
	ds_read2_b32 v[44:45], v115 offset0:161 offset1:162
	ds_read2_b32 v[46:47], v115 offset0:163 offset1:164
	s_waitcnt lgkmcnt(15)
	v_mfma_f32_32x32x16_bf16 v[0:15], v[64:67], v[72:75], v[0:15]
	v_mfma_f32_32x32x16_bf16 v[16:31], v[64:67], v[76:79], v[16:31]
	v_mfma_f32_32x32x16_bf16 v[0:15], v[68:71], v[220:223], v[0:15]
	v_mfma_f32_32x32x16_bf16 v[16:31], v[68:71], v[224:227], v[16:31]
	global_load_dwordx4 v[116:119], v235, s[84:85]
	global_load_dwordx4 v[120:123], v236, s[84:85]
	global_load_dwordx4 v[124:127], v237, s[84:85]
	global_load_dwordx4 v[128:131], v238, s[84:85]
	global_load_dwordx4 v[132:135], v100, s[84:85] offset:768
	global_load_dwordx4 v[136:139], v149, s[84:85] offset:768
	global_load_dwordx4 v[140:143], v100, s[84:85] offset:832
	global_load_dwordx4 v[144:147], v149, s[84:85] offset:832
	s_add_u32 s84, s84, 0x30000
	s_addc_u32 s85, s85, 0
	s_waitcnt lgkmcnt(0)
	v_mfma_f32_32x32x16_bf16 v[32:47], v[156:159], v[48:51], v[32:47]
	ds_read_b64_tr_b16 v[72:73], v231
	ds_read_b64_tr_b16 v[74:75], v231 offset:512
	ds_read_b64_tr_b16 v[76:77], v231 offset:2048
	ds_read_b64_tr_b16 v[78:79], v231 offset:2560
	ds_read_b64_tr_b16 v[220:221], v231 offset:1024
	ds_read_b64_tr_b16 v[222:223], v231 offset:1536
	ds_read_b64_tr_b16 v[224:225], v231 offset:3072
	ds_read_b64_tr_b16 v[226:227], v231 offset:3584
	s_waitcnt vmcnt(8)
	ds_write_b128 v247, v[188:191]
	ds_write_b128 v247, v[192:195] offset:1024
	ds_write_b128 v111, v[196:199] offset:2048
	ds_write_b128 v111, v[200:203] offset:3072
	ds_read_b128 v[188:191], v248
	ds_read_b128 v[192:195], v249
	ds_read_b128 v[196:199], v250
	ds_read_b128 v[200:203], v251
	ds_write_b128 v112, v[204:207]
	ds_write_b128 v112, v[208:211] offset:1024
	ds_write_b128 v112, v[212:215] offset:2048
	ds_write_b128 v112, v[216:219] offset:3072
	v_mfma_f32_32x32x16_bf16 v[32:47], v[160:163], v[52:55], v[32:47]
	v_mfma_f32_32x32x16_bf16 v[32:47], v[164:167], v[56:59], v[32:47]
	v_mfma_f32_32x32x16_bf16 v[32:47], v[168:171], v[60:63], v[32:47]
	s_nop 11
	v_exp_f32_e32 v32, v32
	v_exp_f32_e32 v33, v33
	v_exp_f32_e32 v34, v34
	v_exp_f32_e32 v35, v35
	v_exp_f32_e32 v36, v36
	v_exp_f32_e32 v37, v37
	v_exp_f32_e32 v38, v38
	v_exp_f32_e32 v39, v39
	v_exp_f32_e32 v40, v40
	v_exp_f32_e32 v41, v41
	v_exp_f32_e32 v42, v42
	v_exp_f32_e32 v43, v43
	v_exp_f32_e32 v44, v44
	v_exp_f32_e32 v45, v45
	v_exp_f32_e32 v46, v46
	v_exp_f32_e32 v47, v47
	v_cvt_pk_bf16_f32 v64, v32, v33
	v_cvt_pk_bf16_f32 v65, v34, v35
	v_cvt_pk_bf16_f32 v66, v36, v37
	v_cvt_pk_bf16_f32 v67, v38, v39
	v_cvt_pk_bf16_f32 v68, v40, v41
	v_cvt_pk_bf16_f32 v69, v42, v43
	v_cvt_pk_bf16_f32 v70, v44, v45
	v_cvt_pk_bf16_f32 v71, v46, v47
	v_pk_add_f32 v[232:233], v[232:233], v[32:33]
	v_pk_add_f32 v[232:233], v[232:233], v[34:35]
	v_pk_add_f32 v[232:233], v[232:233], v[36:37]
	v_pk_add_f32 v[232:233], v[232:233], v[38:39]
	v_pk_add_f32 v[232:233], v[232:233], v[40:41]
	v_pk_add_f32 v[232:233], v[232:233], v[42:43]
	v_pk_add_f32 v[232:233], v[232:233], v[44:45]
	v_pk_add_f32 v[232:233], v[232:233], v[46:47]
	ds_read2_b32 v[32:33], v115 offset0:170 offset1:171
	ds_read2_b32 v[34:35], v115 offset0:172 offset1:173
	ds_read2_b32 v[36:37], v115 offset0:178 offset1:179
	ds_read2_b32 v[38:39], v115 offset0:180 offset1:181
	ds_read2_b32 v[40:41], v115 offset0:187 offset1:188
	ds_read2_b32 v[42:43], v115 offset0:189 offset1:190
	ds_read2_b32 v[44:45], v115 offset0:195 offset1:196
	ds_read2_b32 v[46:47], v115 offset0:197 offset1:198
	s_waitcnt lgkmcnt(15)
	v_mfma_f32_32x32x16_bf16 v[0:15], v[64:67], v[72:75], v[0:15]
	v_mfma_f32_32x32x16_bf16 v[16:31], v[64:67], v[76:79], v[16:31]
	v_mfma_f32_32x32x16_bf16 v[0:15], v[68:71], v[220:223], v[0:15]
	v_mfma_f32_32x32x16_bf16 v[16:31], v[68:71], v[224:227], v[16:31]
	global_load_dwordx4 v[156:159], v235, s[84:85]
	global_load_dwordx4 v[160:163], v236, s[84:85]
	global_load_dwordx4 v[164:167], v237, s[84:85]
	global_load_dwordx4 v[168:171], v238, s[84:85]
	global_load_dwordx4 v[172:175], v100, s[84:85] offset:768
	global_load_dwordx4 v[176:179], v149, s[84:85] offset:768
	global_load_dwordx4 v[180:183], v100, s[84:85] offset:832
	global_load_dwordx4 v[184:187], v149, s[84:85] offset:832
	s_add_u32 s84, s84, 0x30000
	s_addc_u32 s85, s85, 0
	s_waitcnt lgkmcnt(0)
	v_mfma_f32_32x32x16_bf16 v[32:47], v[188:191], v[48:51], v[32:47]
	ds_read_b64_tr_b16 v[72:73], v231
	ds_read_b64_tr_b16 v[74:75], v231 offset:512
	ds_read_b64_tr_b16 v[76:77], v231 offset:2048
	ds_read_b64_tr_b16 v[78:79], v231 offset:2560
	ds_read_b64_tr_b16 v[220:221], v231 offset:1024
	ds_read_b64_tr_b16 v[222:223], v231 offset:1536
	ds_read_b64_tr_b16 v[224:225], v231 offset:3072
	ds_read_b64_tr_b16 v[226:227], v231 offset:3584
	s_waitcnt vmcnt(8)
	ds_write_b128 v247, v[116:119]
	ds_write_b128 v247, v[120:123] offset:1024
	ds_write_b128 v111, v[124:127] offset:2048
	ds_write_b128 v111, v[128:131] offset:3072
	ds_read_b128 v[116:119], v248
	ds_read_b128 v[120:123], v249
	ds_read_b128 v[124:127], v250
	ds_read_b128 v[128:131], v251
	ds_write_b128 v112, v[132:135]
	ds_write_b128 v112, v[136:139] offset:1024
	ds_write_b128 v112, v[140:143] offset:2048
	ds_write_b128 v112, v[144:147] offset:3072
	v_mfma_f32_32x32x16_bf16 v[32:47], v[192:195], v[52:55], v[32:47]
	v_mfma_f32_32x32x16_bf16 v[32:47], v[196:199], v[56:59], v[32:47]
	v_mfma_f32_32x32x16_bf16 v[32:47], v[200:203], v[60:63], v[32:47]
	s_nop 11
	v_exp_f32_e32 v32, v32
	v_exp_f32_e32 v33, v33
	v_exp_f32_e32 v34, v34
	v_exp_f32_e32 v35, v35
	v_exp_f32_e32 v36, v36
	v_exp_f32_e32 v37, v37
	v_exp_f32_e32 v38, v38
	v_exp_f32_e32 v39, v39
	v_exp_f32_e32 v40, v40
	v_exp_f32_e32 v41, v41
	v_exp_f32_e32 v42, v42
	v_exp_f32_e32 v43, v43
	v_exp_f32_e32 v44, v44
	v_exp_f32_e32 v45, v45
	v_exp_f32_e32 v46, v46
	v_exp_f32_e32 v47, v47
	v_cvt_pk_bf16_f32 v64, v32, v33
	v_cvt_pk_bf16_f32 v65, v34, v35
	v_cvt_pk_bf16_f32 v66, v36, v37
	v_cvt_pk_bf16_f32 v67, v38, v39
	v_cvt_pk_bf16_f32 v68, v40, v41
	v_cvt_pk_bf16_f32 v69, v42, v43
	v_cvt_pk_bf16_f32 v70, v44, v45
	v_cvt_pk_bf16_f32 v71, v46, v47
	v_pk_add_f32 v[232:233], v[232:233], v[32:33]
	v_pk_add_f32 v[232:233], v[232:233], v[34:35]
	v_pk_add_f32 v[232:233], v[232:233], v[36:37]
	v_pk_add_f32 v[232:233], v[232:233], v[38:39]
	v_pk_add_f32 v[232:233], v[232:233], v[40:41]
	v_pk_add_f32 v[232:233], v[232:233], v[42:43]
	v_pk_add_f32 v[232:233], v[232:233], v[44:45]
	v_pk_add_f32 v[232:233], v[232:233], v[46:47]
	ds_read2_b32 v[32:33], v115 offset0:204 offset1:205
	ds_read2_b32 v[34:35], v115 offset0:206 offset1:207
	ds_read2_b32 v[36:37], v115 offset0:212 offset1:213
	ds_read2_b32 v[38:39], v115 offset0:214 offset1:215
	ds_read2_b32 v[40:41], v115 offset0:221 offset1:222
	ds_read2_b32 v[42:43], v115 offset0:223 offset1:224
	ds_read2_b32 v[44:45], v115 offset0:229 offset1:230
	ds_read2_b32 v[46:47], v115 offset0:231 offset1:232
	s_waitcnt lgkmcnt(15)
	v_mfma_f32_32x32x16_bf16 v[0:15], v[64:67], v[72:75], v[0:15]
	v_mfma_f32_32x32x16_bf16 v[16:31], v[64:67], v[76:79], v[16:31]
	v_mfma_f32_32x32x16_bf16 v[0:15], v[68:71], v[220:223], v[0:15]
	v_mfma_f32_32x32x16_bf16 v[16:31], v[68:71], v[224:227], v[16:31]
	global_load_dwordx4 v[188:191], v235, s[84:85]
	global_load_dwordx4 v[192:195], v236, s[84:85]
	global_load_dwordx4 v[196:199], v237, s[84:85]
	global_load_dwordx4 v[200:203], v238, s[84:85]
	global_load_dwordx4 v[204:207], v100, s[84:85] offset:768
	global_load_dwordx4 v[208:211], v149, s[84:85] offset:768
	global_load_dwordx4 v[212:215], v100, s[84:85] offset:832
	global_load_dwordx4 v[216:219], v149, s[84:85] offset:832
	s_add_u32 s84, s84, 0x30000
	s_addc_u32 s85, s85, 0
	s_waitcnt lgkmcnt(0)
	v_mfma_f32_32x32x16_bf16 v[32:47], v[116:119], v[48:51], v[32:47]
	ds_read_b64_tr_b16 v[72:73], v231
	ds_read_b64_tr_b16 v[74:75], v231 offset:512
	ds_read_b64_tr_b16 v[76:77], v231 offset:2048
	ds_read_b64_tr_b16 v[78:79], v231 offset:2560
	ds_read_b64_tr_b16 v[220:221], v231 offset:1024
	ds_read_b64_tr_b16 v[222:223], v231 offset:1536
	ds_read_b64_tr_b16 v[224:225], v231 offset:3072
	ds_read_b64_tr_b16 v[226:227], v231 offset:3584
	s_waitcnt vmcnt(8)
	ds_write_b128 v247, v[156:159]
	ds_write_b128 v247, v[160:163] offset:1024
	ds_write_b128 v111, v[164:167] offset:2048
	ds_write_b128 v111, v[168:171] offset:3072
	ds_read_b128 v[156:159], v248
	ds_read_b128 v[160:163], v249
	ds_read_b128 v[164:167], v250
	ds_read_b128 v[168:171], v251
	ds_write_b128 v112, v[172:175]
	ds_write_b128 v112, v[176:179] offset:1024
	ds_write_b128 v112, v[180:183] offset:2048
	ds_write_b128 v112, v[184:187] offset:3072
	v_mfma_f32_32x32x16_bf16 v[32:47], v[120:123], v[52:55], v[32:47]
	v_mfma_f32_32x32x16_bf16 v[32:47], v[124:127], v[56:59], v[32:47]
	v_mfma_f32_32x32x16_bf16 v[32:47], v[128:131], v[60:63], v[32:47]
	s_nop 11
	v_exp_f32_e32 v32, v32
	v_exp_f32_e32 v33, v33
	v_exp_f32_e32 v34, v34
	v_exp_f32_e32 v35, v35
	v_exp_f32_e32 v36, v36
	v_exp_f32_e32 v37, v37
	v_exp_f32_e32 v38, v38
	v_exp_f32_e32 v39, v39
	v_exp_f32_e32 v40, v40
	v_exp_f32_e32 v41, v41
	v_exp_f32_e32 v42, v42
	v_exp_f32_e32 v43, v43
	v_exp_f32_e32 v44, v44
	v_exp_f32_e32 v45, v45
	v_exp_f32_e32 v46, v46
	v_exp_f32_e32 v47, v47
	v_cvt_pk_bf16_f32 v64, v32, v33
	v_cvt_pk_bf16_f32 v65, v34, v35
	v_cvt_pk_bf16_f32 v66, v36, v37
	v_cvt_pk_bf16_f32 v67, v38, v39
	v_cvt_pk_bf16_f32 v68, v40, v41
	v_cvt_pk_bf16_f32 v69, v42, v43
	v_cvt_pk_bf16_f32 v70, v44, v45
	v_cvt_pk_bf16_f32 v71, v46, v47
	v_pk_add_f32 v[232:233], v[232:233], v[32:33]
	v_pk_add_f32 v[232:233], v[232:233], v[34:35]
	v_pk_add_f32 v[232:233], v[232:233], v[36:37]
	v_pk_add_f32 v[232:233], v[232:233], v[38:39]
	v_pk_add_f32 v[232:233], v[232:233], v[40:41]
	v_pk_add_f32 v[232:233], v[232:233], v[42:43]
	v_pk_add_f32 v[232:233], v[232:233], v[44:45]
	v_pk_add_f32 v[232:233], v[232:233], v[46:47]
	v_add_u32_e32 v115, 952, v115
	ds_read2_b32 v[32:33], v115 offset0:0 offset1:1
	ds_read2_b32 v[34:35], v115 offset0:2 offset1:3
	ds_read2_b32 v[36:37], v115 offset0:8 offset1:9
	ds_read2_b32 v[38:39], v115 offset0:10 offset1:11
	ds_read2_b32 v[40:41], v115 offset0:17 offset1:18
	ds_read2_b32 v[42:43], v115 offset0:19 offset1:20
	ds_read2_b32 v[44:45], v115 offset0:25 offset1:26
	ds_read2_b32 v[46:47], v115 offset0:27 offset1:28
	s_waitcnt lgkmcnt(15)
	v_mfma_f32_32x32x16_bf16 v[0:15], v[64:67], v[72:75], v[0:15]
	v_mfma_f32_32x32x16_bf16 v[16:31], v[64:67], v[76:79], v[16:31]
	v_mfma_f32_32x32x16_bf16 v[0:15], v[68:71], v[220:223], v[0:15]
	v_mfma_f32_32x32x16_bf16 v[16:31], v[68:71], v[224:227], v[16:31]
	global_load_dwordx4 v[116:119], v235, s[84:85]
	global_load_dwordx4 v[120:123], v236, s[84:85]
	global_load_dwordx4 v[124:127], v237, s[84:85]
	global_load_dwordx4 v[128:131], v238, s[84:85]
	global_load_dwordx4 v[132:135], v100, s[84:85] offset:768
	global_load_dwordx4 v[136:139], v149, s[84:85] offset:768
	global_load_dwordx4 v[140:143], v100, s[84:85] offset:832
	global_load_dwordx4 v[144:147], v149, s[84:85] offset:832
	s_add_u32 s84, s84, 0x30000
	s_addc_u32 s85, s85, 0
	s_waitcnt lgkmcnt(0)
	v_mfma_f32_32x32x16_bf16 v[32:47], v[156:159], v[48:51], v[32:47]
	ds_read_b64_tr_b16 v[72:73], v231
	ds_read_b64_tr_b16 v[74:75], v231 offset:512
	ds_read_b64_tr_b16 v[76:77], v231 offset:2048
	ds_read_b64_tr_b16 v[78:79], v231 offset:2560
	ds_read_b64_tr_b16 v[220:221], v231 offset:1024
	ds_read_b64_tr_b16 v[222:223], v231 offset:1536
	ds_read_b64_tr_b16 v[224:225], v231 offset:3072
	ds_read_b64_tr_b16 v[226:227], v231 offset:3584
	s_waitcnt vmcnt(8)
	ds_write_b128 v247, v[188:191]
	ds_write_b128 v247, v[192:195] offset:1024
	ds_write_b128 v111, v[196:199] offset:2048
	ds_write_b128 v111, v[200:203] offset:3072
	ds_read_b128 v[188:191], v248
	ds_read_b128 v[192:195], v249
	ds_read_b128 v[196:199], v250
	ds_read_b128 v[200:203], v251
	ds_write_b128 v112, v[204:207]
	ds_write_b128 v112, v[208:211] offset:1024
	ds_write_b128 v112, v[212:215] offset:2048
	ds_write_b128 v112, v[216:219] offset:3072
	v_mfma_f32_32x32x16_bf16 v[32:47], v[160:163], v[52:55], v[32:47]
	v_mfma_f32_32x32x16_bf16 v[32:47], v[164:167], v[56:59], v[32:47]
	v_mfma_f32_32x32x16_bf16 v[32:47], v[168:171], v[60:63], v[32:47]
	s_nop 11
	v_exp_f32_e32 v32, v32
	v_exp_f32_e32 v33, v33
	v_exp_f32_e32 v34, v34
	v_exp_f32_e32 v35, v35
	v_exp_f32_e32 v36, v36
	v_exp_f32_e32 v37, v37
	v_exp_f32_e32 v38, v38
	v_exp_f32_e32 v39, v39
	v_exp_f32_e32 v40, v40
	v_exp_f32_e32 v41, v41
	v_exp_f32_e32 v42, v42
	v_exp_f32_e32 v43, v43
	v_exp_f32_e32 v44, v44
	v_exp_f32_e32 v45, v45
	v_exp_f32_e32 v46, v46
	v_exp_f32_e32 v47, v47
	v_cvt_pk_bf16_f32 v64, v32, v33
	v_cvt_pk_bf16_f32 v65, v34, v35
	v_cvt_pk_bf16_f32 v66, v36, v37
	v_cvt_pk_bf16_f32 v67, v38, v39
	v_cvt_pk_bf16_f32 v68, v40, v41
	v_cvt_pk_bf16_f32 v69, v42, v43
	v_cvt_pk_bf16_f32 v70, v44, v45
	v_cvt_pk_bf16_f32 v71, v46, v47
	v_pk_add_f32 v[232:233], v[232:233], v[32:33]
	v_pk_add_f32 v[232:233], v[232:233], v[34:35]
	v_pk_add_f32 v[232:233], v[232:233], v[36:37]
	v_pk_add_f32 v[232:233], v[232:233], v[38:39]
	v_pk_add_f32 v[232:233], v[232:233], v[40:41]
	v_pk_add_f32 v[232:233], v[232:233], v[42:43]
	v_pk_add_f32 v[232:233], v[232:233], v[44:45]
	v_pk_add_f32 v[232:233], v[232:233], v[46:47]
	ds_read2_b32 v[32:33], v115 offset0:34 offset1:35
	ds_read2_b32 v[34:35], v115 offset0:36 offset1:37
	ds_read2_b32 v[36:37], v115 offset0:42 offset1:43
	ds_read2_b32 v[38:39], v115 offset0:44 offset1:45
	ds_read2_b32 v[40:41], v115 offset0:51 offset1:52
	ds_read2_b32 v[42:43], v115 offset0:53 offset1:54
	ds_read2_b32 v[44:45], v115 offset0:59 offset1:60
	ds_read2_b32 v[46:47], v115 offset0:61 offset1:62
	s_waitcnt lgkmcnt(15)
	v_mfma_f32_32x32x16_bf16 v[0:15], v[64:67], v[72:75], v[0:15]
	v_mfma_f32_32x32x16_bf16 v[16:31], v[64:67], v[76:79], v[16:31]
	v_mfma_f32_32x32x16_bf16 v[0:15], v[68:71], v[220:223], v[0:15]
	v_mfma_f32_32x32x16_bf16 v[16:31], v[68:71], v[224:227], v[16:31]
	global_load_dwordx4 v[156:159], v235, s[84:85]
	global_load_dwordx4 v[160:163], v236, s[84:85]
	global_load_dwordx4 v[164:167], v237, s[84:85]
	global_load_dwordx4 v[168:171], v238, s[84:85]
	global_load_dwordx4 v[172:175], v100, s[84:85] offset:768
	global_load_dwordx4 v[176:179], v149, s[84:85] offset:768
	global_load_dwordx4 v[180:183], v100, s[84:85] offset:832
	global_load_dwordx4 v[184:187], v149, s[84:85] offset:832
	s_add_u32 s84, s84, 0x30000
	s_addc_u32 s85, s85, 0
	s_waitcnt lgkmcnt(0)
	v_mfma_f32_32x32x16_bf16 v[32:47], v[188:191], v[48:51], v[32:47]
	ds_read_b64_tr_b16 v[72:73], v231
	ds_read_b64_tr_b16 v[74:75], v231 offset:512
	ds_read_b64_tr_b16 v[76:77], v231 offset:2048
	ds_read_b64_tr_b16 v[78:79], v231 offset:2560
	ds_read_b64_tr_b16 v[220:221], v231 offset:1024
	ds_read_b64_tr_b16 v[222:223], v231 offset:1536
	ds_read_b64_tr_b16 v[224:225], v231 offset:3072
	ds_read_b64_tr_b16 v[226:227], v231 offset:3584
	s_waitcnt vmcnt(8)
	ds_write_b128 v247, v[116:119]
	ds_write_b128 v247, v[120:123] offset:1024
	ds_write_b128 v111, v[124:127] offset:2048
	ds_write_b128 v111, v[128:131] offset:3072
	ds_read_b128 v[116:119], v248
	ds_read_b128 v[120:123], v249
	ds_read_b128 v[124:127], v250
	ds_read_b128 v[128:131], v251
	ds_write_b128 v112, v[132:135]
	ds_write_b128 v112, v[136:139] offset:1024
	ds_write_b128 v112, v[140:143] offset:2048
	ds_write_b128 v112, v[144:147] offset:3072
	v_mfma_f32_32x32x16_bf16 v[32:47], v[192:195], v[52:55], v[32:47]
	v_mfma_f32_32x32x16_bf16 v[32:47], v[196:199], v[56:59], v[32:47]
	v_mfma_f32_32x32x16_bf16 v[32:47], v[200:203], v[60:63], v[32:47]
	s_nop 11
	v_exp_f32_e32 v32, v32
	v_exp_f32_e32 v33, v33
	v_exp_f32_e32 v34, v34
	v_exp_f32_e32 v35, v35
	v_exp_f32_e32 v36, v36
	v_exp_f32_e32 v37, v37
	v_exp_f32_e32 v38, v38
	v_exp_f32_e32 v39, v39
	v_exp_f32_e32 v40, v40
	v_exp_f32_e32 v41, v41
	v_exp_f32_e32 v42, v42
	v_exp_f32_e32 v43, v43
	v_exp_f32_e32 v44, v44
	v_exp_f32_e32 v45, v45
	v_exp_f32_e32 v46, v46
	v_exp_f32_e32 v47, v47
	v_cvt_pk_bf16_f32 v64, v32, v33
	v_cvt_pk_bf16_f32 v65, v34, v35
	v_cvt_pk_bf16_f32 v66, v36, v37
	v_cvt_pk_bf16_f32 v67, v38, v39
	v_cvt_pk_bf16_f32 v68, v40, v41
	v_cvt_pk_bf16_f32 v69, v42, v43
	v_cvt_pk_bf16_f32 v70, v44, v45
	v_cvt_pk_bf16_f32 v71, v46, v47
	v_pk_add_f32 v[232:233], v[232:233], v[32:33]
	v_pk_add_f32 v[232:233], v[232:233], v[34:35]
	v_pk_add_f32 v[232:233], v[232:233], v[36:37]
	v_pk_add_f32 v[232:233], v[232:233], v[38:39]
	v_pk_add_f32 v[232:233], v[232:233], v[40:41]
	v_pk_add_f32 v[232:233], v[232:233], v[42:43]
	v_pk_add_f32 v[232:233], v[232:233], v[44:45]
	v_pk_add_f32 v[232:233], v[232:233], v[46:47]
	ds_read2_b32 v[32:33], v115 offset0:68 offset1:69
	ds_read2_b32 v[34:35], v115 offset0:70 offset1:71
	ds_read2_b32 v[36:37], v115 offset0:76 offset1:77
	ds_read2_b32 v[38:39], v115 offset0:78 offset1:79
	ds_read2_b32 v[40:41], v115 offset0:85 offset1:86
	ds_read2_b32 v[42:43], v115 offset0:87 offset1:88
	ds_read2_b32 v[44:45], v115 offset0:93 offset1:94
	ds_read2_b32 v[46:47], v115 offset0:95 offset1:96
	s_waitcnt lgkmcnt(15)
	v_mfma_f32_32x32x16_bf16 v[0:15], v[64:67], v[72:75], v[0:15]
	v_mfma_f32_32x32x16_bf16 v[16:31], v[64:67], v[76:79], v[16:31]
	v_mfma_f32_32x32x16_bf16 v[0:15], v[68:71], v[220:223], v[0:15]
	v_mfma_f32_32x32x16_bf16 v[16:31], v[68:71], v[224:227], v[16:31]
	global_load_dwordx4 v[188:191], v235, s[84:85]
	global_load_dwordx4 v[192:195], v236, s[84:85]
	global_load_dwordx4 v[196:199], v237, s[84:85]
	global_load_dwordx4 v[200:203], v238, s[84:85]
	global_load_dwordx4 v[204:207], v100, s[84:85] offset:768
	global_load_dwordx4 v[208:211], v149, s[84:85] offset:768
	global_load_dwordx4 v[212:215], v100, s[84:85] offset:832
	global_load_dwordx4 v[216:219], v149, s[84:85] offset:832
	s_add_u32 s84, s84, 0x30000
	s_addc_u32 s85, s85, 0
	s_waitcnt lgkmcnt(0)
	v_mfma_f32_32x32x16_bf16 v[32:47], v[116:119], v[48:51], v[32:47]
	ds_read_b64_tr_b16 v[72:73], v231
	ds_read_b64_tr_b16 v[74:75], v231 offset:512
	ds_read_b64_tr_b16 v[76:77], v231 offset:2048
	ds_read_b64_tr_b16 v[78:79], v231 offset:2560
	ds_read_b64_tr_b16 v[220:221], v231 offset:1024
	ds_read_b64_tr_b16 v[222:223], v231 offset:1536
	ds_read_b64_tr_b16 v[224:225], v231 offset:3072
	ds_read_b64_tr_b16 v[226:227], v231 offset:3584
	s_waitcnt vmcnt(8)
	ds_write_b128 v247, v[156:159]
	ds_write_b128 v247, v[160:163] offset:1024
	ds_write_b128 v111, v[164:167] offset:2048
	ds_write_b128 v111, v[168:171] offset:3072
	ds_read_b128 v[156:159], v248
	ds_read_b128 v[160:163], v249
	ds_read_b128 v[164:167], v250
	ds_read_b128 v[168:171], v251
	ds_write_b128 v112, v[172:175]
	ds_write_b128 v112, v[176:179] offset:1024
	ds_write_b128 v112, v[180:183] offset:2048
	ds_write_b128 v112, v[184:187] offset:3072
	v_mfma_f32_32x32x16_bf16 v[32:47], v[120:123], v[52:55], v[32:47]
	v_mfma_f32_32x32x16_bf16 v[32:47], v[124:127], v[56:59], v[32:47]
	v_mfma_f32_32x32x16_bf16 v[32:47], v[128:131], v[60:63], v[32:47]
	s_nop 11
	v_exp_f32_e32 v32, v32
	v_exp_f32_e32 v33, v33
	v_exp_f32_e32 v34, v34
	v_exp_f32_e32 v35, v35
	v_exp_f32_e32 v36, v36
	v_exp_f32_e32 v37, v37
	v_exp_f32_e32 v38, v38
	v_exp_f32_e32 v39, v39
	v_exp_f32_e32 v40, v40
	v_exp_f32_e32 v41, v41
	v_exp_f32_e32 v42, v42
	v_exp_f32_e32 v43, v43
	v_exp_f32_e32 v44, v44
	v_exp_f32_e32 v45, v45
	v_exp_f32_e32 v46, v46
	v_exp_f32_e32 v47, v47
	v_cvt_pk_bf16_f32 v64, v32, v33
	v_cvt_pk_bf16_f32 v65, v34, v35
	v_cvt_pk_bf16_f32 v66, v36, v37
	v_cvt_pk_bf16_f32 v67, v38, v39
	v_cvt_pk_bf16_f32 v68, v40, v41
	v_cvt_pk_bf16_f32 v69, v42, v43
	v_cvt_pk_bf16_f32 v70, v44, v45
	v_cvt_pk_bf16_f32 v71, v46, v47
	v_pk_add_f32 v[232:233], v[232:233], v[32:33]
	v_pk_add_f32 v[232:233], v[232:233], v[34:35]
	v_pk_add_f32 v[232:233], v[232:233], v[36:37]
	v_pk_add_f32 v[232:233], v[232:233], v[38:39]
	v_pk_add_f32 v[232:233], v[232:233], v[40:41]
	v_pk_add_f32 v[232:233], v[232:233], v[42:43]
	v_pk_add_f32 v[232:233], v[232:233], v[44:45]
	v_pk_add_f32 v[232:233], v[232:233], v[46:47]
	ds_read2_b32 v[32:33], v115 offset0:102 offset1:103
	ds_read2_b32 v[34:35], v115 offset0:104 offset1:105
	ds_read2_b32 v[36:37], v115 offset0:110 offset1:111
	ds_read2_b32 v[38:39], v115 offset0:112 offset1:113
	ds_read2_b32 v[40:41], v115 offset0:119 offset1:120
	ds_read2_b32 v[42:43], v115 offset0:121 offset1:122
	ds_read2_b32 v[44:45], v115 offset0:127 offset1:128
	ds_read2_b32 v[46:47], v115 offset0:129 offset1:130
	s_waitcnt lgkmcnt(15)
	v_mfma_f32_32x32x16_bf16 v[0:15], v[64:67], v[72:75], v[0:15]
	v_mfma_f32_32x32x16_bf16 v[16:31], v[64:67], v[76:79], v[16:31]
	v_mfma_f32_32x32x16_bf16 v[0:15], v[68:71], v[220:223], v[0:15]
	v_mfma_f32_32x32x16_bf16 v[16:31], v[68:71], v[224:227], v[16:31]
	global_load_dwordx4 v[116:119], v235, s[84:85]
	global_load_dwordx4 v[120:123], v236, s[84:85]
	global_load_dwordx4 v[124:127], v237, s[84:85]
	global_load_dwordx4 v[128:131], v238, s[84:85]
	global_load_dwordx4 v[132:135], v100, s[84:85] offset:768
	global_load_dwordx4 v[136:139], v149, s[84:85] offset:768
	global_load_dwordx4 v[140:143], v100, s[84:85] offset:832
	global_load_dwordx4 v[144:147], v149, s[84:85] offset:832
	s_add_u32 s84, s84, 0x30000
	s_addc_u32 s85, s85, 0
	s_waitcnt lgkmcnt(0)
	v_mfma_f32_32x32x16_bf16 v[32:47], v[156:159], v[48:51], v[32:47]
	ds_read_b64_tr_b16 v[72:73], v231
	ds_read_b64_tr_b16 v[74:75], v231 offset:512
	ds_read_b64_tr_b16 v[76:77], v231 offset:2048
	ds_read_b64_tr_b16 v[78:79], v231 offset:2560
	ds_read_b64_tr_b16 v[220:221], v231 offset:1024
	ds_read_b64_tr_b16 v[222:223], v231 offset:1536
	ds_read_b64_tr_b16 v[224:225], v231 offset:3072
	ds_read_b64_tr_b16 v[226:227], v231 offset:3584
	s_waitcnt vmcnt(8)
	ds_write_b128 v247, v[188:191]
	ds_write_b128 v247, v[192:195] offset:1024
	ds_write_b128 v111, v[196:199] offset:2048
	ds_write_b128 v111, v[200:203] offset:3072
	ds_read_b128 v[188:191], v248
	ds_read_b128 v[192:195], v249
	ds_read_b128 v[196:199], v250
	ds_read_b128 v[200:203], v251
	ds_write_b128 v112, v[204:207]
	ds_write_b128 v112, v[208:211] offset:1024
	ds_write_b128 v112, v[212:215] offset:2048
	ds_write_b128 v112, v[216:219] offset:3072
	v_mfma_f32_32x32x16_bf16 v[32:47], v[160:163], v[52:55], v[32:47]
	v_mfma_f32_32x32x16_bf16 v[32:47], v[164:167], v[56:59], v[32:47]
	v_mfma_f32_32x32x16_bf16 v[32:47], v[168:171], v[60:63], v[32:47]
	s_nop 11
	v_exp_f32_e32 v32, v32
	v_exp_f32_e32 v33, v33
	v_exp_f32_e32 v34, v34
	v_exp_f32_e32 v35, v35
	v_exp_f32_e32 v36, v36
	v_exp_f32_e32 v37, v37
	v_exp_f32_e32 v38, v38
	v_exp_f32_e32 v39, v39
	v_exp_f32_e32 v40, v40
	v_exp_f32_e32 v41, v41
	v_exp_f32_e32 v42, v42
	v_exp_f32_e32 v43, v43
	v_exp_f32_e32 v44, v44
	v_exp_f32_e32 v45, v45
	v_exp_f32_e32 v46, v46
	v_exp_f32_e32 v47, v47
	v_cvt_pk_bf16_f32 v64, v32, v33
	v_cvt_pk_bf16_f32 v65, v34, v35
	v_cvt_pk_bf16_f32 v66, v36, v37
	v_cvt_pk_bf16_f32 v67, v38, v39
	v_cvt_pk_bf16_f32 v68, v40, v41
	v_cvt_pk_bf16_f32 v69, v42, v43
	v_cvt_pk_bf16_f32 v70, v44, v45
	v_cvt_pk_bf16_f32 v71, v46, v47
	v_pk_add_f32 v[232:233], v[232:233], v[32:33]
	v_pk_add_f32 v[232:233], v[232:233], v[34:35]
	v_pk_add_f32 v[232:233], v[232:233], v[36:37]
	v_pk_add_f32 v[232:233], v[232:233], v[38:39]
	v_pk_add_f32 v[232:233], v[232:233], v[40:41]
	v_pk_add_f32 v[232:233], v[232:233], v[42:43]
	v_pk_add_f32 v[232:233], v[232:233], v[44:45]
	v_pk_add_f32 v[232:233], v[232:233], v[46:47]
	ds_read2_b32 v[32:33], v115 offset0:136 offset1:137
	ds_read2_b32 v[34:35], v115 offset0:138 offset1:139
	ds_read2_b32 v[36:37], v115 offset0:144 offset1:145
	ds_read2_b32 v[38:39], v115 offset0:146 offset1:147
	ds_read2_b32 v[40:41], v115 offset0:153 offset1:154
	ds_read2_b32 v[42:43], v115 offset0:155 offset1:156
	ds_read2_b32 v[44:45], v115 offset0:161 offset1:162
	ds_read2_b32 v[46:47], v115 offset0:163 offset1:164
	s_waitcnt lgkmcnt(15)
	v_mfma_f32_32x32x16_bf16 v[0:15], v[64:67], v[72:75], v[0:15]
	v_mfma_f32_32x32x16_bf16 v[16:31], v[64:67], v[76:79], v[16:31]
	v_mfma_f32_32x32x16_bf16 v[0:15], v[68:71], v[220:223], v[0:15]
	v_mfma_f32_32x32x16_bf16 v[16:31], v[68:71], v[224:227], v[16:31]
	global_load_dwordx4 v[156:159], v235, s[84:85]
	global_load_dwordx4 v[160:163], v236, s[84:85]
	global_load_dwordx4 v[164:167], v237, s[84:85]
	global_load_dwordx4 v[168:171], v238, s[84:85]
	global_load_dwordx4 v[172:175], v100, s[84:85] offset:768
	global_load_dwordx4 v[176:179], v149, s[84:85] offset:768
	global_load_dwordx4 v[180:183], v100, s[84:85] offset:832
	global_load_dwordx4 v[184:187], v149, s[84:85] offset:832
	s_add_u32 s84, s84, 0x30000
	s_addc_u32 s85, s85, 0
	s_waitcnt lgkmcnt(0)
	v_mfma_f32_32x32x16_bf16 v[32:47], v[188:191], v[48:51], v[32:47]
	ds_read_b64_tr_b16 v[72:73], v231
	ds_read_b64_tr_b16 v[74:75], v231 offset:512
	ds_read_b64_tr_b16 v[76:77], v231 offset:2048
	ds_read_b64_tr_b16 v[78:79], v231 offset:2560
	ds_read_b64_tr_b16 v[220:221], v231 offset:1024
	ds_read_b64_tr_b16 v[222:223], v231 offset:1536
	ds_read_b64_tr_b16 v[224:225], v231 offset:3072
	ds_read_b64_tr_b16 v[226:227], v231 offset:3584
	s_waitcnt vmcnt(8)
	ds_write_b128 v247, v[116:119]
	ds_write_b128 v247, v[120:123] offset:1024
	ds_write_b128 v111, v[124:127] offset:2048
	ds_write_b128 v111, v[128:131] offset:3072
	ds_read_b128 v[116:119], v248
	ds_read_b128 v[120:123], v249
	ds_read_b128 v[124:127], v250
	ds_read_b128 v[128:131], v251
	ds_write_b128 v112, v[132:135]
	ds_write_b128 v112, v[136:139] offset:1024
	ds_write_b128 v112, v[140:143] offset:2048
	ds_write_b128 v112, v[144:147] offset:3072
	v_mfma_f32_32x32x16_bf16 v[32:47], v[192:195], v[52:55], v[32:47]
	v_mfma_f32_32x32x16_bf16 v[32:47], v[196:199], v[56:59], v[32:47]
	v_mfma_f32_32x32x16_bf16 v[32:47], v[200:203], v[60:63], v[32:47]
	s_nop 11
	v_exp_f32_e32 v32, v32
	v_exp_f32_e32 v33, v33
	v_exp_f32_e32 v34, v34
	v_exp_f32_e32 v35, v35
	v_exp_f32_e32 v36, v36
	v_exp_f32_e32 v37, v37
	v_exp_f32_e32 v38, v38
	v_exp_f32_e32 v39, v39
	v_exp_f32_e32 v40, v40
	v_exp_f32_e32 v41, v41
	v_exp_f32_e32 v42, v42
	v_exp_f32_e32 v43, v43
	v_exp_f32_e32 v44, v44
	v_exp_f32_e32 v45, v45
	v_exp_f32_e32 v46, v46
	v_exp_f32_e32 v47, v47
	v_cvt_pk_bf16_f32 v64, v32, v33
	v_cvt_pk_bf16_f32 v65, v34, v35
	v_cvt_pk_bf16_f32 v66, v36, v37
	v_cvt_pk_bf16_f32 v67, v38, v39
	v_cvt_pk_bf16_f32 v68, v40, v41
	v_cvt_pk_bf16_f32 v69, v42, v43
	v_cvt_pk_bf16_f32 v70, v44, v45
	v_cvt_pk_bf16_f32 v71, v46, v47
	v_pk_add_f32 v[232:233], v[232:233], v[32:33]
	v_pk_add_f32 v[232:233], v[232:233], v[34:35]
	v_pk_add_f32 v[232:233], v[232:233], v[36:37]
	v_pk_add_f32 v[232:233], v[232:233], v[38:39]
	v_pk_add_f32 v[232:233], v[232:233], v[40:41]
	v_pk_add_f32 v[232:233], v[232:233], v[42:43]
	v_pk_add_f32 v[232:233], v[232:233], v[44:45]
	v_pk_add_f32 v[232:233], v[232:233], v[46:47]
	ds_read2_b32 v[32:33], v115 offset0:170 offset1:171
	ds_read2_b32 v[34:35], v115 offset0:172 offset1:173
	ds_read2_b32 v[36:37], v115 offset0:178 offset1:179
	ds_read2_b32 v[38:39], v115 offset0:180 offset1:181
	ds_read2_b32 v[40:41], v115 offset0:187 offset1:188
	ds_read2_b32 v[42:43], v115 offset0:189 offset1:190
	ds_read2_b32 v[44:45], v115 offset0:195 offset1:196
	ds_read2_b32 v[46:47], v115 offset0:197 offset1:198
	s_waitcnt lgkmcnt(15)
	v_mfma_f32_32x32x16_bf16 v[0:15], v[64:67], v[72:75], v[0:15]
	v_mfma_f32_32x32x16_bf16 v[16:31], v[64:67], v[76:79], v[16:31]
	v_mfma_f32_32x32x16_bf16 v[0:15], v[68:71], v[220:223], v[0:15]
	v_mfma_f32_32x32x16_bf16 v[16:31], v[68:71], v[224:227], v[16:31]
	global_load_dwordx4 v[188:191], v235, s[84:85]
	global_load_dwordx4 v[192:195], v236, s[84:85]
	global_load_dwordx4 v[196:199], v237, s[84:85]
	global_load_dwordx4 v[200:203], v238, s[84:85]
	global_load_dwordx4 v[204:207], v100, s[84:85] offset:768
	global_load_dwordx4 v[208:211], v149, s[84:85] offset:768
	global_load_dwordx4 v[212:215], v100, s[84:85] offset:832
	global_load_dwordx4 v[216:219], v149, s[84:85] offset:832
	s_add_u32 s84, s84, 0x30000
	s_addc_u32 s85, s85, 0
	s_waitcnt lgkmcnt(0)
	v_mfma_f32_32x32x16_bf16 v[32:47], v[116:119], v[48:51], v[32:47]
	ds_read_b64_tr_b16 v[72:73], v231
	ds_read_b64_tr_b16 v[74:75], v231 offset:512
	ds_read_b64_tr_b16 v[76:77], v231 offset:2048
	ds_read_b64_tr_b16 v[78:79], v231 offset:2560
	ds_read_b64_tr_b16 v[220:221], v231 offset:1024
	ds_read_b64_tr_b16 v[222:223], v231 offset:1536
	ds_read_b64_tr_b16 v[224:225], v231 offset:3072
	ds_read_b64_tr_b16 v[226:227], v231 offset:3584
	s_waitcnt vmcnt(8)
	ds_write_b128 v247, v[156:159]
	ds_write_b128 v247, v[160:163] offset:1024
	ds_write_b128 v111, v[164:167] offset:2048
	ds_write_b128 v111, v[168:171] offset:3072
	ds_read_b128 v[156:159], v248
	ds_read_b128 v[160:163], v249
	ds_read_b128 v[164:167], v250
	ds_read_b128 v[168:171], v251
	ds_write_b128 v112, v[172:175]
	ds_write_b128 v112, v[176:179] offset:1024
	ds_write_b128 v112, v[180:183] offset:2048
	ds_write_b128 v112, v[184:187] offset:3072
	v_mfma_f32_32x32x16_bf16 v[32:47], v[120:123], v[52:55], v[32:47]
	v_mfma_f32_32x32x16_bf16 v[32:47], v[124:127], v[56:59], v[32:47]
	v_mfma_f32_32x32x16_bf16 v[32:47], v[128:131], v[60:63], v[32:47]
	s_nop 11
	v_exp_f32_e32 v32, v32
	v_exp_f32_e32 v33, v33
	v_exp_f32_e32 v34, v34
	v_exp_f32_e32 v35, v35
	v_exp_f32_e32 v36, v36
	v_exp_f32_e32 v37, v37
	v_exp_f32_e32 v38, v38
	v_exp_f32_e32 v39, v39
	v_exp_f32_e32 v40, v40
	v_exp_f32_e32 v41, v41
	v_exp_f32_e32 v42, v42
	v_exp_f32_e32 v43, v43
	v_exp_f32_e32 v44, v44
	v_exp_f32_e32 v45, v45
	v_exp_f32_e32 v46, v46
	v_exp_f32_e32 v47, v47
	v_cvt_pk_bf16_f32 v64, v32, v33
	v_cvt_pk_bf16_f32 v65, v34, v35
	v_cvt_pk_bf16_f32 v66, v36, v37
	v_cvt_pk_bf16_f32 v67, v38, v39
	v_cvt_pk_bf16_f32 v68, v40, v41
	v_cvt_pk_bf16_f32 v69, v42, v43
	v_cvt_pk_bf16_f32 v70, v44, v45
	v_cvt_pk_bf16_f32 v71, v46, v47
	v_pk_add_f32 v[232:233], v[232:233], v[32:33]
	v_pk_add_f32 v[232:233], v[232:233], v[34:35]
	v_pk_add_f32 v[232:233], v[232:233], v[36:37]
	v_pk_add_f32 v[232:233], v[232:233], v[38:39]
	v_pk_add_f32 v[232:233], v[232:233], v[40:41]
	v_pk_add_f32 v[232:233], v[232:233], v[42:43]
	v_pk_add_f32 v[232:233], v[232:233], v[44:45]
	v_pk_add_f32 v[232:233], v[232:233], v[46:47]
	ds_read2_b32 v[32:33], v115 offset0:204 offset1:205
	ds_read2_b32 v[34:35], v115 offset0:206 offset1:207
	ds_read2_b32 v[36:37], v115 offset0:212 offset1:213
	ds_read2_b32 v[38:39], v115 offset0:214 offset1:215
	ds_read2_b32 v[40:41], v115 offset0:221 offset1:222
	ds_read2_b32 v[42:43], v115 offset0:223 offset1:224
	ds_read2_b32 v[44:45], v115 offset0:229 offset1:230
	ds_read2_b32 v[46:47], v115 offset0:231 offset1:232
	s_waitcnt lgkmcnt(15)
	v_mfma_f32_32x32x16_bf16 v[0:15], v[64:67], v[72:75], v[0:15]
	v_mfma_f32_32x32x16_bf16 v[16:31], v[64:67], v[76:79], v[16:31]
	v_mfma_f32_32x32x16_bf16 v[0:15], v[68:71], v[220:223], v[0:15]
	v_mfma_f32_32x32x16_bf16 v[16:31], v[68:71], v[224:227], v[16:31]
	global_load_dwordx4 v[116:119], v235, s[84:85]
	global_load_dwordx4 v[120:123], v236, s[84:85]
	global_load_dwordx4 v[124:127], v237, s[84:85]
	global_load_dwordx4 v[128:131], v238, s[84:85]
	global_load_dwordx4 v[132:135], v100, s[84:85] offset:768
	global_load_dwordx4 v[136:139], v149, s[84:85] offset:768
	global_load_dwordx4 v[140:143], v100, s[84:85] offset:832
	global_load_dwordx4 v[144:147], v149, s[84:85] offset:832
	s_add_u32 s84, s84, 0x30000
	s_addc_u32 s85, s85, 0
	s_waitcnt lgkmcnt(0)
	v_mfma_f32_32x32x16_bf16 v[32:47], v[156:159], v[48:51], v[32:47]
	ds_read_b64_tr_b16 v[72:73], v231
	ds_read_b64_tr_b16 v[74:75], v231 offset:512
	ds_read_b64_tr_b16 v[76:77], v231 offset:2048
	ds_read_b64_tr_b16 v[78:79], v231 offset:2560
	ds_read_b64_tr_b16 v[220:221], v231 offset:1024
	ds_read_b64_tr_b16 v[222:223], v231 offset:1536
	ds_read_b64_tr_b16 v[224:225], v231 offset:3072
	ds_read_b64_tr_b16 v[226:227], v231 offset:3584
	s_waitcnt vmcnt(8)
	ds_write_b128 v247, v[188:191]
	ds_write_b128 v247, v[192:195] offset:1024
	ds_write_b128 v111, v[196:199] offset:2048
	ds_write_b128 v111, v[200:203] offset:3072
	ds_read_b128 v[188:191], v248
	ds_read_b128 v[192:195], v249
	ds_read_b128 v[196:199], v250
	ds_read_b128 v[200:203], v251
	ds_write_b128 v112, v[204:207]
	ds_write_b128 v112, v[208:211] offset:1024
	ds_write_b128 v112, v[212:215] offset:2048
	ds_write_b128 v112, v[216:219] offset:3072
	v_mfma_f32_32x32x16_bf16 v[32:47], v[160:163], v[52:55], v[32:47]
	v_mfma_f32_32x32x16_bf16 v[32:47], v[164:167], v[56:59], v[32:47]
	v_mfma_f32_32x32x16_bf16 v[32:47], v[168:171], v[60:63], v[32:47]
	s_nop 11
	v_exp_f32_e32 v32, v32
	v_exp_f32_e32 v33, v33
	v_exp_f32_e32 v34, v34
	v_exp_f32_e32 v35, v35
	v_exp_f32_e32 v36, v36
	v_exp_f32_e32 v37, v37
	v_exp_f32_e32 v38, v38
	v_exp_f32_e32 v39, v39
	v_exp_f32_e32 v40, v40
	v_exp_f32_e32 v41, v41
	v_exp_f32_e32 v42, v42
	v_exp_f32_e32 v43, v43
	v_exp_f32_e32 v44, v44
	v_exp_f32_e32 v45, v45
	v_exp_f32_e32 v46, v46
	v_exp_f32_e32 v47, v47
	v_cvt_pk_bf16_f32 v64, v32, v33
	v_cvt_pk_bf16_f32 v65, v34, v35
	v_cvt_pk_bf16_f32 v66, v36, v37
	v_cvt_pk_bf16_f32 v67, v38, v39
	v_cvt_pk_bf16_f32 v68, v40, v41
	v_cvt_pk_bf16_f32 v69, v42, v43
	v_cvt_pk_bf16_f32 v70, v44, v45
	v_cvt_pk_bf16_f32 v71, v46, v47
	v_pk_add_f32 v[232:233], v[232:233], v[32:33]
	v_pk_add_f32 v[232:233], v[232:233], v[34:35]
	v_pk_add_f32 v[232:233], v[232:233], v[36:37]
	v_pk_add_f32 v[232:233], v[232:233], v[38:39]
	v_pk_add_f32 v[232:233], v[232:233], v[40:41]
	v_pk_add_f32 v[232:233], v[232:233], v[42:43]
	v_pk_add_f32 v[232:233], v[232:233], v[44:45]
	v_pk_add_f32 v[232:233], v[232:233], v[46:47]
	v_add_u32_e32 v115, 952, v115
	ds_read2_b32 v[32:33], v115 offset0:0 offset1:1
	ds_read2_b32 v[34:35], v115 offset0:2 offset1:3
	ds_read2_b32 v[36:37], v115 offset0:8 offset1:9
	ds_read2_b32 v[38:39], v115 offset0:10 offset1:11
	ds_read2_b32 v[40:41], v115 offset0:17 offset1:18
	ds_read2_b32 v[42:43], v115 offset0:19 offset1:20
	ds_read2_b32 v[44:45], v115 offset0:25 offset1:26
	ds_read2_b32 v[46:47], v115 offset0:27 offset1:28
	s_waitcnt lgkmcnt(15)
	v_mfma_f32_32x32x16_bf16 v[0:15], v[64:67], v[72:75], v[0:15]
	v_mfma_f32_32x32x16_bf16 v[16:31], v[64:67], v[76:79], v[16:31]
	v_mfma_f32_32x32x16_bf16 v[0:15], v[68:71], v[220:223], v[0:15]
	v_mfma_f32_32x32x16_bf16 v[16:31], v[68:71], v[224:227], v[16:31]
	global_load_dwordx4 v[156:159], v235, s[84:85]
	global_load_dwordx4 v[160:163], v236, s[84:85]
	global_load_dwordx4 v[164:167], v237, s[84:85]
	global_load_dwordx4 v[168:171], v238, s[84:85]
	global_load_dwordx4 v[172:175], v100, s[84:85] offset:768
	global_load_dwordx4 v[176:179], v149, s[84:85] offset:768
	global_load_dwordx4 v[180:183], v100, s[84:85] offset:832
	global_load_dwordx4 v[184:187], v149, s[84:85] offset:832
	s_add_u32 s84, s84, 0x30000
	s_addc_u32 s85, s85, 0
	s_waitcnt lgkmcnt(0)
	v_mfma_f32_32x32x16_bf16 v[32:47], v[188:191], v[48:51], v[32:47]
	ds_read_b64_tr_b16 v[72:73], v231
	ds_read_b64_tr_b16 v[74:75], v231 offset:512
	ds_read_b64_tr_b16 v[76:77], v231 offset:2048
	ds_read_b64_tr_b16 v[78:79], v231 offset:2560
	ds_read_b64_tr_b16 v[220:221], v231 offset:1024
	ds_read_b64_tr_b16 v[222:223], v231 offset:1536
	ds_read_b64_tr_b16 v[224:225], v231 offset:3072
	ds_read_b64_tr_b16 v[226:227], v231 offset:3584
	s_waitcnt vmcnt(8)
	ds_write_b128 v247, v[116:119]
	ds_write_b128 v247, v[120:123] offset:1024
	ds_write_b128 v111, v[124:127] offset:2048
	ds_write_b128 v111, v[128:131] offset:3072
	ds_read_b128 v[116:119], v248
	ds_read_b128 v[120:123], v249
	ds_read_b128 v[124:127], v250
	ds_read_b128 v[128:131], v251
	ds_write_b128 v112, v[132:135]
	ds_write_b128 v112, v[136:139] offset:1024
	ds_write_b128 v112, v[140:143] offset:2048
	ds_write_b128 v112, v[144:147] offset:3072
	v_mfma_f32_32x32x16_bf16 v[32:47], v[192:195], v[52:55], v[32:47]
	v_mfma_f32_32x32x16_bf16 v[32:47], v[196:199], v[56:59], v[32:47]
	v_mfma_f32_32x32x16_bf16 v[32:47], v[200:203], v[60:63], v[32:47]
	s_nop 11
	v_exp_f32_e32 v32, v32
	v_exp_f32_e32 v33, v33
	v_exp_f32_e32 v34, v34
	v_exp_f32_e32 v35, v35
	v_exp_f32_e32 v36, v36
	v_exp_f32_e32 v37, v37
	v_exp_f32_e32 v38, v38
	v_exp_f32_e32 v39, v39
	v_exp_f32_e32 v40, v40
	v_exp_f32_e32 v41, v41
	v_exp_f32_e32 v42, v42
	v_exp_f32_e32 v43, v43
	v_exp_f32_e32 v44, v44
	v_exp_f32_e32 v45, v45
	v_exp_f32_e32 v46, v46
	v_exp_f32_e32 v47, v47
	v_cvt_pk_bf16_f32 v64, v32, v33
	v_cvt_pk_bf16_f32 v65, v34, v35
	v_cvt_pk_bf16_f32 v66, v36, v37
	v_cvt_pk_bf16_f32 v67, v38, v39
	v_cvt_pk_bf16_f32 v68, v40, v41
	v_cvt_pk_bf16_f32 v69, v42, v43
	v_cvt_pk_bf16_f32 v70, v44, v45
	v_cvt_pk_bf16_f32 v71, v46, v47
	v_pk_add_f32 v[232:233], v[232:233], v[32:33]
	v_pk_add_f32 v[232:233], v[232:233], v[34:35]
	v_pk_add_f32 v[232:233], v[232:233], v[36:37]
	v_pk_add_f32 v[232:233], v[232:233], v[38:39]
	v_pk_add_f32 v[232:233], v[232:233], v[40:41]
	v_pk_add_f32 v[232:233], v[232:233], v[42:43]
	v_pk_add_f32 v[232:233], v[232:233], v[44:45]
	v_pk_add_f32 v[232:233], v[232:233], v[46:47]
	ds_read2_b32 v[32:33], v115 offset0:34 offset1:35
	ds_read2_b32 v[34:35], v115 offset0:36 offset1:37
	ds_read2_b32 v[36:37], v115 offset0:42 offset1:43
	ds_read2_b32 v[38:39], v115 offset0:44 offset1:45
	ds_read2_b32 v[40:41], v115 offset0:51 offset1:52
	ds_read2_b32 v[42:43], v115 offset0:53 offset1:54
	ds_read2_b32 v[44:45], v115 offset0:59 offset1:60
	ds_read2_b32 v[46:47], v115 offset0:61 offset1:62
	s_waitcnt lgkmcnt(15)
	v_mfma_f32_32x32x16_bf16 v[0:15], v[64:67], v[72:75], v[0:15]
	v_mfma_f32_32x32x16_bf16 v[16:31], v[64:67], v[76:79], v[16:31]
	v_mfma_f32_32x32x16_bf16 v[0:15], v[68:71], v[220:223], v[0:15]
	v_mfma_f32_32x32x16_bf16 v[16:31], v[68:71], v[224:227], v[16:31]
	global_load_dwordx4 v[188:191], v235, s[84:85]
	global_load_dwordx4 v[192:195], v236, s[84:85]
	global_load_dwordx4 v[196:199], v237, s[84:85]
	global_load_dwordx4 v[200:203], v238, s[84:85]
	global_load_dwordx4 v[204:207], v100, s[84:85] offset:768
	global_load_dwordx4 v[208:211], v149, s[84:85] offset:768
	global_load_dwordx4 v[212:215], v100, s[84:85] offset:832
	global_load_dwordx4 v[216:219], v149, s[84:85] offset:832
	s_add_u32 s84, s84, 0x30000
	s_addc_u32 s85, s85, 0
	s_waitcnt lgkmcnt(0)
	v_mfma_f32_32x32x16_bf16 v[32:47], v[116:119], v[48:51], v[32:47]
	ds_read_b64_tr_b16 v[72:73], v231
	ds_read_b64_tr_b16 v[74:75], v231 offset:512
	ds_read_b64_tr_b16 v[76:77], v231 offset:2048
	ds_read_b64_tr_b16 v[78:79], v231 offset:2560
	ds_read_b64_tr_b16 v[220:221], v231 offset:1024
	ds_read_b64_tr_b16 v[222:223], v231 offset:1536
	ds_read_b64_tr_b16 v[224:225], v231 offset:3072
	ds_read_b64_tr_b16 v[226:227], v231 offset:3584
	s_waitcnt vmcnt(8)
	ds_write_b128 v247, v[156:159]
	ds_write_b128 v247, v[160:163] offset:1024
	ds_write_b128 v111, v[164:167] offset:2048
	ds_write_b128 v111, v[168:171] offset:3072
	ds_read_b128 v[156:159], v248
	ds_read_b128 v[160:163], v249
	ds_read_b128 v[164:167], v250
	ds_read_b128 v[168:171], v251
	ds_write_b128 v112, v[172:175]
	ds_write_b128 v112, v[176:179] offset:1024
	ds_write_b128 v112, v[180:183] offset:2048
	ds_write_b128 v112, v[184:187] offset:3072
	v_mfma_f32_32x32x16_bf16 v[32:47], v[120:123], v[52:55], v[32:47]
	v_mfma_f32_32x32x16_bf16 v[32:47], v[124:127], v[56:59], v[32:47]
	v_mfma_f32_32x32x16_bf16 v[32:47], v[128:131], v[60:63], v[32:47]
	s_nop 11
	v_exp_f32_e32 v32, v32
	v_exp_f32_e32 v33, v33
	v_exp_f32_e32 v34, v34
	v_exp_f32_e32 v35, v35
	v_exp_f32_e32 v36, v36
	v_exp_f32_e32 v37, v37
	v_exp_f32_e32 v38, v38
	v_exp_f32_e32 v39, v39
	v_exp_f32_e32 v40, v40
	v_exp_f32_e32 v41, v41
	v_exp_f32_e32 v42, v42
	v_exp_f32_e32 v43, v43
	v_exp_f32_e32 v44, v44
	v_exp_f32_e32 v45, v45
	v_exp_f32_e32 v46, v46
	v_exp_f32_e32 v47, v47
	v_cvt_pk_bf16_f32 v64, v32, v33
	v_cvt_pk_bf16_f32 v65, v34, v35
	v_cvt_pk_bf16_f32 v66, v36, v37
	v_cvt_pk_bf16_f32 v67, v38, v39
	v_cvt_pk_bf16_f32 v68, v40, v41
	v_cvt_pk_bf16_f32 v69, v42, v43
	v_cvt_pk_bf16_f32 v70, v44, v45
	v_cvt_pk_bf16_f32 v71, v46, v47
	v_pk_add_f32 v[232:233], v[232:233], v[32:33]
	v_pk_add_f32 v[232:233], v[232:233], v[34:35]
	v_pk_add_f32 v[232:233], v[232:233], v[36:37]
	v_pk_add_f32 v[232:233], v[232:233], v[38:39]
	v_pk_add_f32 v[232:233], v[232:233], v[40:41]
	v_pk_add_f32 v[232:233], v[232:233], v[42:43]
	v_pk_add_f32 v[232:233], v[232:233], v[44:45]
	v_pk_add_f32 v[232:233], v[232:233], v[46:47]
	ds_read2_b32 v[32:33], v115 offset0:68 offset1:69
	ds_read2_b32 v[34:35], v115 offset0:70 offset1:71
	ds_read2_b32 v[36:37], v115 offset0:76 offset1:77
	ds_read2_b32 v[38:39], v115 offset0:78 offset1:79
	ds_read2_b32 v[40:41], v115 offset0:85 offset1:86
	ds_read2_b32 v[42:43], v115 offset0:87 offset1:88
	ds_read2_b32 v[44:45], v115 offset0:93 offset1:94
	ds_read2_b32 v[46:47], v115 offset0:95 offset1:96
	s_waitcnt lgkmcnt(15)
	v_mfma_f32_32x32x16_bf16 v[0:15], v[64:67], v[72:75], v[0:15]
	v_mfma_f32_32x32x16_bf16 v[16:31], v[64:67], v[76:79], v[16:31]
	v_mfma_f32_32x32x16_bf16 v[0:15], v[68:71], v[220:223], v[0:15]
	v_mfma_f32_32x32x16_bf16 v[16:31], v[68:71], v[224:227], v[16:31]
	global_load_dwordx4 v[116:119], v235, s[84:85]
	global_load_dwordx4 v[120:123], v236, s[84:85]
	global_load_dwordx4 v[124:127], v237, s[84:85]
	global_load_dwordx4 v[128:131], v238, s[84:85]
	global_load_dwordx4 v[132:135], v100, s[84:85] offset:768
	global_load_dwordx4 v[136:139], v149, s[84:85] offset:768
	global_load_dwordx4 v[140:143], v100, s[84:85] offset:832
	global_load_dwordx4 v[144:147], v149, s[84:85] offset:832
	s_add_u32 s84, s84, 0x30000
	s_addc_u32 s85, s85, 0
	s_waitcnt lgkmcnt(0)
	v_mfma_f32_32x32x16_bf16 v[32:47], v[156:159], v[48:51], v[32:47]
	ds_read_b64_tr_b16 v[72:73], v231
	ds_read_b64_tr_b16 v[74:75], v231 offset:512
	ds_read_b64_tr_b16 v[76:77], v231 offset:2048
	ds_read_b64_tr_b16 v[78:79], v231 offset:2560
	ds_read_b64_tr_b16 v[220:221], v231 offset:1024
	ds_read_b64_tr_b16 v[222:223], v231 offset:1536
	ds_read_b64_tr_b16 v[224:225], v231 offset:3072
	ds_read_b64_tr_b16 v[226:227], v231 offset:3584
	s_waitcnt vmcnt(8)
	ds_write_b128 v247, v[188:191]
	ds_write_b128 v247, v[192:195] offset:1024
	ds_write_b128 v111, v[196:199] offset:2048
	ds_write_b128 v111, v[200:203] offset:3072
	ds_read_b128 v[188:191], v248
	ds_read_b128 v[192:195], v249
	ds_read_b128 v[196:199], v250
	ds_read_b128 v[200:203], v251
	ds_write_b128 v112, v[204:207]
	ds_write_b128 v112, v[208:211] offset:1024
	ds_write_b128 v112, v[212:215] offset:2048
	ds_write_b128 v112, v[216:219] offset:3072
	v_mfma_f32_32x32x16_bf16 v[32:47], v[160:163], v[52:55], v[32:47]
	v_mfma_f32_32x32x16_bf16 v[32:47], v[164:167], v[56:59], v[32:47]
	v_mfma_f32_32x32x16_bf16 v[32:47], v[168:171], v[60:63], v[32:47]
	s_nop 11
	v_exp_f32_e32 v32, v32
	v_exp_f32_e32 v33, v33
	v_exp_f32_e32 v34, v34
	v_exp_f32_e32 v35, v35
	v_exp_f32_e32 v36, v36
	v_exp_f32_e32 v37, v37
	v_exp_f32_e32 v38, v38
	v_exp_f32_e32 v39, v39
	v_exp_f32_e32 v40, v40
	v_exp_f32_e32 v41, v41
	v_exp_f32_e32 v42, v42
	v_exp_f32_e32 v43, v43
	v_exp_f32_e32 v44, v44
	v_exp_f32_e32 v45, v45
	v_exp_f32_e32 v46, v46
	v_exp_f32_e32 v47, v47
	v_cvt_pk_bf16_f32 v64, v32, v33
	v_cvt_pk_bf16_f32 v65, v34, v35
	v_cvt_pk_bf16_f32 v66, v36, v37
	v_cvt_pk_bf16_f32 v67, v38, v39
	v_cvt_pk_bf16_f32 v68, v40, v41
	v_cvt_pk_bf16_f32 v69, v42, v43
	v_cvt_pk_bf16_f32 v70, v44, v45
	v_cvt_pk_bf16_f32 v71, v46, v47
	v_pk_add_f32 v[232:233], v[232:233], v[32:33]
	v_pk_add_f32 v[232:233], v[232:233], v[34:35]
	v_pk_add_f32 v[232:233], v[232:233], v[36:37]
	v_pk_add_f32 v[232:233], v[232:233], v[38:39]
	v_pk_add_f32 v[232:233], v[232:233], v[40:41]
	v_pk_add_f32 v[232:233], v[232:233], v[42:43]
	v_pk_add_f32 v[232:233], v[232:233], v[44:45]
	v_pk_add_f32 v[232:233], v[232:233], v[46:47]
	ds_read2_b32 v[32:33], v115 offset0:102 offset1:103
	ds_read2_b32 v[34:35], v115 offset0:104 offset1:105
	ds_read2_b32 v[36:37], v115 offset0:110 offset1:111
	ds_read2_b32 v[38:39], v115 offset0:112 offset1:113
	ds_read2_b32 v[40:41], v115 offset0:119 offset1:120
	ds_read2_b32 v[42:43], v115 offset0:121 offset1:122
	ds_read2_b32 v[44:45], v115 offset0:127 offset1:128
	ds_read2_b32 v[46:47], v115 offset0:129 offset1:130
	s_waitcnt lgkmcnt(15)
	v_mfma_f32_32x32x16_bf16 v[0:15], v[64:67], v[72:75], v[0:15]
	v_mfma_f32_32x32x16_bf16 v[16:31], v[64:67], v[76:79], v[16:31]
	v_mfma_f32_32x32x16_bf16 v[0:15], v[68:71], v[220:223], v[0:15]
	v_mfma_f32_32x32x16_bf16 v[16:31], v[68:71], v[224:227], v[16:31]
	global_load_dwordx4 v[156:159], v235, s[84:85]
	global_load_dwordx4 v[160:163], v236, s[84:85]
	global_load_dwordx4 v[164:167], v237, s[84:85]
	global_load_dwordx4 v[168:171], v238, s[84:85]
	global_load_dwordx4 v[172:175], v100, s[84:85] offset:768
	global_load_dwordx4 v[176:179], v149, s[84:85] offset:768
	global_load_dwordx4 v[180:183], v100, s[84:85] offset:832
	global_load_dwordx4 v[184:187], v149, s[84:85] offset:832
	s_waitcnt lgkmcnt(0)
	v_mfma_f32_32x32x16_bf16 v[32:47], v[188:191], v[48:51], v[32:47]
	ds_read_b64_tr_b16 v[72:73], v231
	ds_read_b64_tr_b16 v[74:75], v231 offset:512
	ds_read_b64_tr_b16 v[76:77], v231 offset:2048
	ds_read_b64_tr_b16 v[78:79], v231 offset:2560
	ds_read_b64_tr_b16 v[220:221], v231 offset:1024
	ds_read_b64_tr_b16 v[222:223], v231 offset:1536
	ds_read_b64_tr_b16 v[224:225], v231 offset:3072
	ds_read_b64_tr_b16 v[226:227], v231 offset:3584
	s_waitcnt vmcnt(8)
	ds_write_b128 v247, v[116:119]
	ds_write_b128 v247, v[120:123] offset:1024
	ds_write_b128 v111, v[124:127] offset:2048
	ds_write_b128 v111, v[128:131] offset:3072
	ds_read_b128 v[116:119], v248
	ds_read_b128 v[120:123], v249
	ds_read_b128 v[124:127], v250
	ds_read_b128 v[128:131], v251
	ds_write_b128 v112, v[132:135]
	ds_write_b128 v112, v[136:139] offset:1024
	ds_write_b128 v112, v[140:143] offset:2048
	ds_write_b128 v112, v[144:147] offset:3072
	v_mfma_f32_32x32x16_bf16 v[32:47], v[192:195], v[52:55], v[32:47]
	v_mfma_f32_32x32x16_bf16 v[32:47], v[196:199], v[56:59], v[32:47]
	v_mfma_f32_32x32x16_bf16 v[32:47], v[200:203], v[60:63], v[32:47]
	s_nop 11
	v_exp_f32_e32 v32, v32
	v_exp_f32_e32 v33, v33
	v_exp_f32_e32 v34, v34
	v_exp_f32_e32 v35, v35
	v_exp_f32_e32 v36, v36
	v_exp_f32_e32 v37, v37
	v_exp_f32_e32 v38, v38
	v_exp_f32_e32 v39, v39
	v_exp_f32_e32 v40, v40
	v_exp_f32_e32 v41, v41
	v_exp_f32_e32 v42, v42
	v_exp_f32_e32 v43, v43
	v_exp_f32_e32 v44, v44
	v_exp_f32_e32 v45, v45
	v_exp_f32_e32 v46, v46
	v_exp_f32_e32 v47, v47
	v_cvt_pk_bf16_f32 v64, v32, v33
	v_cvt_pk_bf16_f32 v65, v34, v35
	v_cvt_pk_bf16_f32 v66, v36, v37
	v_cvt_pk_bf16_f32 v67, v38, v39
	v_cvt_pk_bf16_f32 v68, v40, v41
	v_cvt_pk_bf16_f32 v69, v42, v43
	v_cvt_pk_bf16_f32 v70, v44, v45
	v_cvt_pk_bf16_f32 v71, v46, v47
	v_pk_add_f32 v[232:233], v[232:233], v[32:33]
	v_pk_add_f32 v[232:233], v[232:233], v[34:35]
	v_pk_add_f32 v[232:233], v[232:233], v[36:37]
	v_pk_add_f32 v[232:233], v[232:233], v[38:39]
	v_pk_add_f32 v[232:233], v[232:233], v[40:41]
	v_pk_add_f32 v[232:233], v[232:233], v[42:43]
	v_pk_add_f32 v[232:233], v[232:233], v[44:45]
	v_pk_add_f32 v[232:233], v[232:233], v[46:47]
	ds_read2_b32 v[32:33], v115 offset0:136 offset1:137
	ds_read2_b32 v[34:35], v115 offset0:138 offset1:139
	ds_read2_b32 v[36:37], v115 offset0:144 offset1:145
	ds_read2_b32 v[38:39], v115 offset0:146 offset1:147
	ds_read2_b32 v[40:41], v115 offset0:153 offset1:154
	ds_read2_b32 v[42:43], v115 offset0:155 offset1:156
	ds_read2_b32 v[44:45], v115 offset0:161 offset1:162
	ds_read2_b32 v[46:47], v115 offset0:163 offset1:164
	s_waitcnt lgkmcnt(15)
	v_mfma_f32_32x32x16_bf16 v[0:15], v[64:67], v[72:75], v[0:15]
	v_mfma_f32_32x32x16_bf16 v[16:31], v[64:67], v[76:79], v[16:31]
	v_mfma_f32_32x32x16_bf16 v[0:15], v[68:71], v[220:223], v[0:15]
	v_mfma_f32_32x32x16_bf16 v[16:31], v[68:71], v[224:227], v[16:31]
	global_load_dwordx4 v[188:191], v239, s[86:87]
	global_load_dwordx4 v[192:195], v240, s[86:87]
	global_load_dwordx4 v[196:199], v241, s[86:87]
	global_load_dwordx4 v[200:203], v242, s[86:87]
	global_load_dwordx4 v[204:207], v101, s[86:87] offset:768
	global_load_dwordx4 v[208:211], v150, s[86:87] offset:768
	global_load_dwordx4 v[212:215], v101, s[86:87] offset:832
	global_load_dwordx4 v[216:219], v150, s[86:87] offset:832
	s_add_u32 s86, s86, 0xc0000
	s_addc_u32 s87, s87, 0
	s_waitcnt lgkmcnt(0)
	v_mfma_f32_32x32x16_bf16 v[32:47], v[116:119], v[48:51], v[32:47]
	ds_read_b64_tr_b16 v[72:73], v231
	ds_read_b64_tr_b16 v[74:75], v231 offset:512
	ds_read_b64_tr_b16 v[76:77], v231 offset:2048
	ds_read_b64_tr_b16 v[78:79], v231 offset:2560
	ds_read_b64_tr_b16 v[220:221], v231 offset:1024
	ds_read_b64_tr_b16 v[222:223], v231 offset:1536
	ds_read_b64_tr_b16 v[224:225], v231 offset:3072
	ds_read_b64_tr_b16 v[226:227], v231 offset:3584
	s_waitcnt vmcnt(8)
	ds_write_b128 v247, v[156:159]
	ds_write_b128 v247, v[160:163] offset:1024
	ds_write_b128 v111, v[164:167] offset:2048
	ds_write_b128 v111, v[168:171] offset:3072
	ds_read_b128 v[156:159], v248
	ds_read_b128 v[160:163], v249
	ds_read_b128 v[164:167], v250
	ds_read_b128 v[168:171], v251
	ds_write_b128 v112, v[172:175]
	ds_write_b128 v112, v[176:179] offset:1024
	ds_write_b128 v112, v[180:183] offset:2048
	ds_write_b128 v112, v[184:187] offset:3072
	v_mfma_f32_32x32x16_bf16 v[32:47], v[120:123], v[52:55], v[32:47]
	v_mfma_f32_32x32x16_bf16 v[32:47], v[124:127], v[56:59], v[32:47]
	v_mfma_f32_32x32x16_bf16 v[32:47], v[128:131], v[60:63], v[32:47]
	s_nop 11
	v_exp_f32_e32 v32, v32
	v_exp_f32_e32 v33, v33
	v_exp_f32_e32 v34, v34
	v_exp_f32_e32 v35, v35
	v_exp_f32_e32 v36, v36
	v_exp_f32_e32 v37, v37
	v_exp_f32_e32 v38, v38
	v_exp_f32_e32 v39, v39
	v_exp_f32_e32 v40, v40
	v_exp_f32_e32 v41, v41
	v_exp_f32_e32 v42, v42
	v_exp_f32_e32 v43, v43
	v_exp_f32_e32 v44, v44
	v_exp_f32_e32 v45, v45
	v_exp_f32_e32 v46, v46
	v_exp_f32_e32 v47, v47
	v_cvt_pk_bf16_f32 v64, v32, v33
	v_cvt_pk_bf16_f32 v65, v34, v35
	v_cvt_pk_bf16_f32 v66, v36, v37
	v_cvt_pk_bf16_f32 v67, v38, v39
	v_cvt_pk_bf16_f32 v68, v40, v41
	v_cvt_pk_bf16_f32 v69, v42, v43
	v_cvt_pk_bf16_f32 v70, v44, v45
	v_cvt_pk_bf16_f32 v71, v46, v47
	v_pk_add_f32 v[232:233], v[232:233], v[32:33]
	v_pk_add_f32 v[232:233], v[232:233], v[34:35]
	v_pk_add_f32 v[232:233], v[232:233], v[36:37]
	v_pk_add_f32 v[232:233], v[232:233], v[38:39]
	v_pk_add_f32 v[232:233], v[232:233], v[40:41]
	v_pk_add_f32 v[232:233], v[232:233], v[42:43]
	v_pk_add_f32 v[232:233], v[232:233], v[44:45]
	v_pk_add_f32 v[232:233], v[232:233], v[46:47]
	ds_read2_b32 v[32:33], v115 offset0:170 offset1:171
	ds_read2_b32 v[34:35], v115 offset0:172 offset1:173
	ds_read2_b32 v[36:37], v115 offset0:178 offset1:179
	ds_read2_b32 v[38:39], v115 offset0:180 offset1:181
	ds_read2_b32 v[40:41], v115 offset0:187 offset1:188
	ds_read2_b32 v[42:43], v115 offset0:189 offset1:190
	ds_read2_b32 v[44:45], v115 offset0:195 offset1:196
	ds_read2_b32 v[46:47], v115 offset0:197 offset1:198
	s_waitcnt lgkmcnt(15)
	v_mfma_f32_32x32x16_bf16 v[0:15], v[64:67], v[72:75], v[0:15]
	v_mfma_f32_32x32x16_bf16 v[16:31], v[64:67], v[76:79], v[16:31]
	v_mfma_f32_32x32x16_bf16 v[0:15], v[68:71], v[220:223], v[0:15]
	v_mfma_f32_32x32x16_bf16 v[16:31], v[68:71], v[224:227], v[16:31]
	global_load_dwordx4 v[116:119], v239, s[86:87]
	global_load_dwordx4 v[120:123], v240, s[86:87]
	global_load_dwordx4 v[124:127], v241, s[86:87]
	global_load_dwordx4 v[128:131], v242, s[86:87]
	global_load_dwordx4 v[132:135], v101, s[86:87] offset:768
	global_load_dwordx4 v[136:139], v150, s[86:87] offset:768
	global_load_dwordx4 v[140:143], v101, s[86:87] offset:832
	global_load_dwordx4 v[144:147], v150, s[86:87] offset:832
	s_add_u32 s86, s86, 0xc0000
	s_addc_u32 s87, s87, 0
	s_waitcnt lgkmcnt(0)
	v_mfma_f32_32x32x16_bf16 v[32:47], v[156:159], v[48:51], v[32:47]
	ds_read_b64_tr_b16 v[72:73], v231
	ds_read_b64_tr_b16 v[74:75], v231 offset:512
	ds_read_b64_tr_b16 v[76:77], v231 offset:2048
	ds_read_b64_tr_b16 v[78:79], v231 offset:2560
	ds_read_b64_tr_b16 v[220:221], v231 offset:1024
	ds_read_b64_tr_b16 v[222:223], v231 offset:1536
	ds_read_b64_tr_b16 v[224:225], v231 offset:3072
	ds_read_b64_tr_b16 v[226:227], v231 offset:3584
	s_waitcnt vmcnt(8)
	ds_write_b128 v247, v[188:191]
	ds_write_b128 v247, v[192:195] offset:1024
	ds_write_b128 v111, v[196:199] offset:2048
	ds_write_b128 v111, v[200:203] offset:3072
	ds_read_b128 v[188:191], v248
	ds_read_b128 v[192:195], v249
	ds_read_b128 v[196:199], v250
	ds_read_b128 v[200:203], v251
	ds_write_b128 v112, v[204:207]
	ds_write_b128 v112, v[208:211] offset:1024
	ds_write_b128 v112, v[212:215] offset:2048
	ds_write_b128 v112, v[216:219] offset:3072
	v_mfma_f32_32x32x16_bf16 v[32:47], v[160:163], v[52:55], v[32:47]
	v_mfma_f32_32x32x16_bf16 v[32:47], v[164:167], v[56:59], v[32:47]
	v_mfma_f32_32x32x16_bf16 v[32:47], v[168:171], v[60:63], v[32:47]
	s_nop 11
	v_exp_f32_e32 v32, v32
	v_exp_f32_e32 v33, v33
	v_exp_f32_e32 v34, v34
	v_exp_f32_e32 v35, v35
	v_exp_f32_e32 v36, v36
	v_exp_f32_e32 v37, v37
	v_exp_f32_e32 v38, v38
	v_exp_f32_e32 v39, v39
	v_exp_f32_e32 v40, v40
	v_exp_f32_e32 v41, v41
	v_exp_f32_e32 v42, v42
	v_exp_f32_e32 v43, v43
	v_exp_f32_e32 v44, v44
	v_exp_f32_e32 v45, v45
	v_exp_f32_e32 v46, v46
	v_exp_f32_e32 v47, v47
	v_cvt_pk_bf16_f32 v64, v32, v33
	v_cvt_pk_bf16_f32 v65, v34, v35
	v_cvt_pk_bf16_f32 v66, v36, v37
	v_cvt_pk_bf16_f32 v67, v38, v39
	v_cvt_pk_bf16_f32 v68, v40, v41
	v_cvt_pk_bf16_f32 v69, v42, v43
	v_cvt_pk_bf16_f32 v70, v44, v45
	v_cvt_pk_bf16_f32 v71, v46, v47
	v_pk_add_f32 v[232:233], v[232:233], v[32:33]
	v_pk_add_f32 v[232:233], v[232:233], v[34:35]
	v_pk_add_f32 v[232:233], v[232:233], v[36:37]
	v_pk_add_f32 v[232:233], v[232:233], v[38:39]
	v_pk_add_f32 v[232:233], v[232:233], v[40:41]
	v_pk_add_f32 v[232:233], v[232:233], v[42:43]
	v_pk_add_f32 v[232:233], v[232:233], v[44:45]
	v_pk_add_f32 v[232:233], v[232:233], v[46:47]
	v_mov_b32_e32 v115, v229
	ds_read2_b32 v[32:33], v115 offset0:0 offset1:1
	ds_read2_b32 v[34:35], v115 offset0:2 offset1:3
	ds_read2_b32 v[36:37], v115 offset0:10 offset1:11
	ds_read2_b32 v[38:39], v115 offset0:12 offset1:13
	ds_read2_b32 v[40:41], v115 offset0:20 offset1:21
	ds_read2_b32 v[42:43], v115 offset0:22 offset1:23
	ds_read2_b32 v[44:45], v115 offset0:30 offset1:31
	ds_read2_b32 v[46:47], v115 offset0:32 offset1:33
	s_waitcnt lgkmcnt(15)
	v_mfma_f32_32x32x16_bf16 v[0:15], v[64:67], v[72:75], v[0:15]
	v_mfma_f32_32x32x16_bf16 v[16:31], v[64:67], v[76:79], v[16:31]
	v_mfma_f32_32x32x16_bf16 v[0:15], v[68:71], v[220:223], v[0:15]
	v_mfma_f32_32x32x16_bf16 v[16:31], v[68:71], v[224:227], v[16:31]
	global_load_dwordx4 v[156:159], v239, s[86:87]
	global_load_dwordx4 v[160:163], v240, s[86:87]
	global_load_dwordx4 v[164:167], v241, s[86:87]
	global_load_dwordx4 v[168:171], v242, s[86:87]
	global_load_dwordx4 v[172:175], v101, s[86:87] offset:768
	global_load_dwordx4 v[176:179], v150, s[86:87] offset:768
	global_load_dwordx4 v[180:183], v101, s[86:87] offset:832
	global_load_dwordx4 v[184:187], v150, s[86:87] offset:832
	s_add_u32 s86, s86, 0xc0000
	s_addc_u32 s87, s87, 0
	s_waitcnt lgkmcnt(0)
	v_mfma_f32_32x32x16_bf16 v[32:47], v[188:191], v[48:51], v[32:47]
	ds_read_b64_tr_b16 v[72:73], v231
	ds_read_b64_tr_b16 v[74:75], v231 offset:512
	ds_read_b64_tr_b16 v[76:77], v231 offset:2048
	ds_read_b64_tr_b16 v[78:79], v231 offset:2560
	ds_read_b64_tr_b16 v[220:221], v231 offset:1024
	ds_read_b64_tr_b16 v[222:223], v231 offset:1536
	ds_read_b64_tr_b16 v[224:225], v231 offset:3072
	ds_read_b64_tr_b16 v[226:227], v231 offset:3584
	s_waitcnt vmcnt(8)
	ds_write_b128 v247, v[116:119]
	ds_write_b128 v247, v[120:123] offset:1024
	ds_write_b128 v111, v[124:127] offset:2048
	ds_write_b128 v111, v[128:131] offset:3072
	ds_read_b128 v[116:119], v248
	ds_read_b128 v[120:123], v249
	ds_read_b128 v[124:127], v250
	ds_read_b128 v[128:131], v251
	ds_write_b128 v112, v[132:135]
	ds_write_b128 v112, v[136:139] offset:1024
	ds_write_b128 v112, v[140:143] offset:2048
	ds_write_b128 v112, v[144:147] offset:3072
	v_mfma_f32_32x32x16_bf16 v[32:47], v[192:195], v[52:55], v[32:47]
	v_mfma_f32_32x32x16_bf16 v[32:47], v[196:199], v[56:59], v[32:47]
	v_mfma_f32_32x32x16_bf16 v[32:47], v[200:203], v[60:63], v[32:47]
	s_nop 11
	v_exp_f32_e32 v32, v32
	v_exp_f32_e32 v33, v33
	v_exp_f32_e32 v34, v34
	v_exp_f32_e32 v35, v35
	v_exp_f32_e32 v36, v36
	v_exp_f32_e32 v37, v37
	v_exp_f32_e32 v38, v38
	v_exp_f32_e32 v39, v39
	v_exp_f32_e32 v40, v40
	v_exp_f32_e32 v41, v41
	v_exp_f32_e32 v42, v42
	v_exp_f32_e32 v43, v43
	v_exp_f32_e32 v44, v44
	v_exp_f32_e32 v45, v45
	v_exp_f32_e32 v46, v46
	v_exp_f32_e32 v47, v47
	v_cvt_pk_bf16_f32 v64, v32, v33
	v_cvt_pk_bf16_f32 v65, v34, v35
	v_cvt_pk_bf16_f32 v66, v36, v37
	v_cvt_pk_bf16_f32 v67, v38, v39
	v_cvt_pk_bf16_f32 v68, v40, v41
	v_cvt_pk_bf16_f32 v69, v42, v43
	v_cvt_pk_bf16_f32 v70, v44, v45
	v_cvt_pk_bf16_f32 v71, v46, v47
	v_pk_add_f32 v[232:233], v[232:233], v[32:33]
	v_pk_add_f32 v[232:233], v[232:233], v[34:35]
	v_pk_add_f32 v[232:233], v[232:233], v[36:37]
	v_pk_add_f32 v[232:233], v[232:233], v[38:39]
	v_pk_add_f32 v[232:233], v[232:233], v[40:41]
	v_pk_add_f32 v[232:233], v[232:233], v[42:43]
	v_pk_add_f32 v[232:233], v[232:233], v[44:45]
	v_pk_add_f32 v[232:233], v[232:233], v[46:47]
	ds_read2_b32 v[32:33], v115 offset0:40 offset1:41
	ds_read2_b32 v[34:35], v115 offset0:42 offset1:43
	ds_read2_b32 v[36:37], v115 offset0:50 offset1:51
	ds_read2_b32 v[38:39], v115 offset0:52 offset1:53
	ds_read2_b32 v[40:41], v115 offset0:60 offset1:61
	ds_read2_b32 v[42:43], v115 offset0:62 offset1:63
	ds_read2_b32 v[44:45], v115 offset0:70 offset1:71
	ds_read2_b32 v[46:47], v115 offset0:72 offset1:73
	s_waitcnt lgkmcnt(15)
	v_mfma_f32_32x32x16_bf16 v[0:15], v[64:67], v[72:75], v[0:15]
	v_mfma_f32_32x32x16_bf16 v[16:31], v[64:67], v[76:79], v[16:31]
	v_mfma_f32_32x32x16_bf16 v[0:15], v[68:71], v[220:223], v[0:15]
	v_mfma_f32_32x32x16_bf16 v[16:31], v[68:71], v[224:227], v[16:31]
	global_load_dwordx4 v[188:191], v239, s[86:87]
	global_load_dwordx4 v[192:195], v240, s[86:87]
	global_load_dwordx4 v[196:199], v241, s[86:87]
	global_load_dwordx4 v[200:203], v242, s[86:87]
	global_load_dwordx4 v[204:207], v101, s[86:87] offset:768
	global_load_dwordx4 v[208:211], v150, s[86:87] offset:768
	global_load_dwordx4 v[212:215], v101, s[86:87] offset:832
	global_load_dwordx4 v[216:219], v150, s[86:87] offset:832
	s_add_u32 s86, s86, 0xc0000
	s_addc_u32 s87, s87, 0
	s_waitcnt lgkmcnt(0)
	v_mfma_f32_32x32x16_bf16 v[32:47], v[116:119], v[48:51], v[32:47]
	ds_read_b64_tr_b16 v[72:73], v231
	ds_read_b64_tr_b16 v[74:75], v231 offset:512
	ds_read_b64_tr_b16 v[76:77], v231 offset:2048
	ds_read_b64_tr_b16 v[78:79], v231 offset:2560
	ds_read_b64_tr_b16 v[220:221], v231 offset:1024
	ds_read_b64_tr_b16 v[222:223], v231 offset:1536
	ds_read_b64_tr_b16 v[224:225], v231 offset:3072
	ds_read_b64_tr_b16 v[226:227], v231 offset:3584
	s_waitcnt vmcnt(8)
	ds_write_b128 v247, v[156:159]
	ds_write_b128 v247, v[160:163] offset:1024
	ds_write_b128 v111, v[164:167] offset:2048
	ds_write_b128 v111, v[168:171] offset:3072
	ds_read_b128 v[156:159], v248
	ds_read_b128 v[160:163], v249
	ds_read_b128 v[164:167], v250
	ds_read_b128 v[168:171], v251
	ds_write_b128 v112, v[172:175]
	ds_write_b128 v112, v[176:179] offset:1024
	ds_write_b128 v112, v[180:183] offset:2048
	ds_write_b128 v112, v[184:187] offset:3072
	v_mfma_f32_32x32x16_bf16 v[32:47], v[120:123], v[52:55], v[32:47]
	v_mfma_f32_32x32x16_bf16 v[32:47], v[124:127], v[56:59], v[32:47]
	v_mfma_f32_32x32x16_bf16 v[32:47], v[128:131], v[60:63], v[32:47]
	s_nop 11
	v_exp_f32_e32 v32, v32
	v_exp_f32_e32 v33, v33
	v_exp_f32_e32 v34, v34
	v_exp_f32_e32 v35, v35
	v_exp_f32_e32 v36, v36
	v_exp_f32_e32 v37, v37
	v_exp_f32_e32 v38, v38
	v_exp_f32_e32 v39, v39
	v_exp_f32_e32 v40, v40
	v_exp_f32_e32 v41, v41
	v_exp_f32_e32 v42, v42
	v_exp_f32_e32 v43, v43
	v_exp_f32_e32 v44, v44
	v_exp_f32_e32 v45, v45
	v_exp_f32_e32 v46, v46
	v_exp_f32_e32 v47, v47
	v_cvt_pk_bf16_f32 v64, v32, v33
	v_cvt_pk_bf16_f32 v65, v34, v35
	v_cvt_pk_bf16_f32 v66, v36, v37
	v_cvt_pk_bf16_f32 v67, v38, v39
	v_cvt_pk_bf16_f32 v68, v40, v41
	v_cvt_pk_bf16_f32 v69, v42, v43
	v_cvt_pk_bf16_f32 v70, v44, v45
	v_cvt_pk_bf16_f32 v71, v46, v47
	v_pk_add_f32 v[232:233], v[232:233], v[32:33]
	v_pk_add_f32 v[232:233], v[232:233], v[34:35]
	v_pk_add_f32 v[232:233], v[232:233], v[36:37]
	v_pk_add_f32 v[232:233], v[232:233], v[38:39]
	v_pk_add_f32 v[232:233], v[232:233], v[40:41]
	v_pk_add_f32 v[232:233], v[232:233], v[42:43]
	v_pk_add_f32 v[232:233], v[232:233], v[44:45]
	v_pk_add_f32 v[232:233], v[232:233], v[46:47]
	ds_read2_b32 v[32:33], v115 offset0:80 offset1:81
	ds_read2_b32 v[34:35], v115 offset0:82 offset1:83
	ds_read2_b32 v[36:37], v115 offset0:90 offset1:91
	ds_read2_b32 v[38:39], v115 offset0:92 offset1:93
	ds_read2_b32 v[40:41], v115 offset0:100 offset1:101
	ds_read2_b32 v[42:43], v115 offset0:102 offset1:103
	ds_read2_b32 v[44:45], v115 offset0:110 offset1:111
	ds_read2_b32 v[46:47], v115 offset0:112 offset1:113
	s_waitcnt lgkmcnt(15)
	v_mfma_f32_32x32x16_bf16 v[0:15], v[64:67], v[72:75], v[0:15]
	v_mfma_f32_32x32x16_bf16 v[16:31], v[64:67], v[76:79], v[16:31]
	v_mfma_f32_32x32x16_bf16 v[0:15], v[68:71], v[220:223], v[0:15]
	v_mfma_f32_32x32x16_bf16 v[16:31], v[68:71], v[224:227], v[16:31]
	global_load_dwordx4 v[116:119], v239, s[86:87]
	global_load_dwordx4 v[120:123], v240, s[86:87]
	global_load_dwordx4 v[124:127], v241, s[86:87]
	global_load_dwordx4 v[128:131], v242, s[86:87]
	global_load_dwordx4 v[132:135], v101, s[86:87] offset:768
	global_load_dwordx4 v[136:139], v150, s[86:87] offset:768
	global_load_dwordx4 v[140:143], v101, s[86:87] offset:832
	global_load_dwordx4 v[144:147], v150, s[86:87] offset:832
	s_add_u32 s86, s86, 0xc0000
	s_addc_u32 s87, s87, 0
	s_waitcnt lgkmcnt(0)
	v_mfma_f32_32x32x16_bf16 v[32:47], v[156:159], v[48:51], v[32:47]
	ds_read_b64_tr_b16 v[72:73], v231
	ds_read_b64_tr_b16 v[74:75], v231 offset:512
	ds_read_b64_tr_b16 v[76:77], v231 offset:2048
	ds_read_b64_tr_b16 v[78:79], v231 offset:2560
	ds_read_b64_tr_b16 v[220:221], v231 offset:1024
	ds_read_b64_tr_b16 v[222:223], v231 offset:1536
	ds_read_b64_tr_b16 v[224:225], v231 offset:3072
	ds_read_b64_tr_b16 v[226:227], v231 offset:3584
	s_waitcnt vmcnt(8)
	ds_write_b128 v247, v[188:191]
	ds_write_b128 v247, v[192:195] offset:1024
	ds_write_b128 v111, v[196:199] offset:2048
	ds_write_b128 v111, v[200:203] offset:3072
	ds_read_b128 v[188:191], v248
	ds_read_b128 v[192:195], v249
	ds_read_b128 v[196:199], v250
	ds_read_b128 v[200:203], v251
	ds_write_b128 v112, v[204:207]
	ds_write_b128 v112, v[208:211] offset:1024
	ds_write_b128 v112, v[212:215] offset:2048
	ds_write_b128 v112, v[216:219] offset:3072
	v_mfma_f32_32x32x16_bf16 v[32:47], v[160:163], v[52:55], v[32:47]
	v_mfma_f32_32x32x16_bf16 v[32:47], v[164:167], v[56:59], v[32:47]
	v_mfma_f32_32x32x16_bf16 v[32:47], v[168:171], v[60:63], v[32:47]
	s_nop 11
	v_exp_f32_e32 v32, v32
	v_exp_f32_e32 v33, v33
	v_exp_f32_e32 v34, v34
	v_exp_f32_e32 v35, v35
	v_exp_f32_e32 v36, v36
	v_exp_f32_e32 v37, v37
	v_exp_f32_e32 v38, v38
	v_exp_f32_e32 v39, v39
	v_exp_f32_e32 v40, v40
	v_exp_f32_e32 v41, v41
	v_exp_f32_e32 v42, v42
	v_exp_f32_e32 v43, v43
	v_exp_f32_e32 v44, v44
	v_exp_f32_e32 v45, v45
	v_exp_f32_e32 v46, v46
	v_exp_f32_e32 v47, v47
	v_cvt_pk_bf16_f32 v64, v32, v33
	v_cvt_pk_bf16_f32 v65, v34, v35
	v_cvt_pk_bf16_f32 v66, v36, v37
	v_cvt_pk_bf16_f32 v67, v38, v39
	v_cvt_pk_bf16_f32 v68, v40, v41
	v_cvt_pk_bf16_f32 v69, v42, v43
	v_cvt_pk_bf16_f32 v70, v44, v45
	v_cvt_pk_bf16_f32 v71, v46, v47
	v_pk_add_f32 v[232:233], v[232:233], v[32:33]
	v_pk_add_f32 v[232:233], v[232:233], v[34:35]
	v_pk_add_f32 v[232:233], v[232:233], v[36:37]
	v_pk_add_f32 v[232:233], v[232:233], v[38:39]
	v_pk_add_f32 v[232:233], v[232:233], v[40:41]
	v_pk_add_f32 v[232:233], v[232:233], v[42:43]
	v_pk_add_f32 v[232:233], v[232:233], v[44:45]
	v_pk_add_f32 v[232:233], v[232:233], v[46:47]
	ds_read2_b32 v[32:33], v115 offset0:120 offset1:121
	ds_read2_b32 v[34:35], v115 offset0:122 offset1:123
	ds_read2_b32 v[36:37], v115 offset0:130 offset1:131
	ds_read2_b32 v[38:39], v115 offset0:132 offset1:133
	ds_read2_b32 v[40:41], v115 offset0:140 offset1:141
	ds_read2_b32 v[42:43], v115 offset0:142 offset1:143
	ds_read2_b32 v[44:45], v115 offset0:150 offset1:151
	ds_read2_b32 v[46:47], v115 offset0:152 offset1:153
	s_waitcnt lgkmcnt(15)
	v_mfma_f32_32x32x16_bf16 v[0:15], v[64:67], v[72:75], v[0:15]
	v_mfma_f32_32x32x16_bf16 v[16:31], v[64:67], v[76:79], v[16:31]
	v_mfma_f32_32x32x16_bf16 v[0:15], v[68:71], v[220:223], v[0:15]
	v_mfma_f32_32x32x16_bf16 v[16:31], v[68:71], v[224:227], v[16:31]
	global_load_dwordx4 v[156:159], v239, s[86:87]
	global_load_dwordx4 v[160:163], v240, s[86:87]
	global_load_dwordx4 v[164:167], v241, s[86:87]
	global_load_dwordx4 v[168:171], v242, s[86:87]
	global_load_dwordx4 v[172:175], v101, s[86:87] offset:768
	global_load_dwordx4 v[176:179], v150, s[86:87] offset:768
	global_load_dwordx4 v[180:183], v101, s[86:87] offset:832
	global_load_dwordx4 v[184:187], v150, s[86:87] offset:832
	s_add_u32 s86, s86, 0xc0000
	s_addc_u32 s87, s87, 0
	s_waitcnt lgkmcnt(0)
	v_mfma_f32_32x32x16_bf16 v[32:47], v[188:191], v[48:51], v[32:47]
	ds_read_b64_tr_b16 v[72:73], v231
	ds_read_b64_tr_b16 v[74:75], v231 offset:512
	ds_read_b64_tr_b16 v[76:77], v231 offset:2048
	ds_read_b64_tr_b16 v[78:79], v231 offset:2560
	ds_read_b64_tr_b16 v[220:221], v231 offset:1024
	ds_read_b64_tr_b16 v[222:223], v231 offset:1536
	ds_read_b64_tr_b16 v[224:225], v231 offset:3072
	ds_read_b64_tr_b16 v[226:227], v231 offset:3584
	s_waitcnt vmcnt(8)
	ds_write_b128 v247, v[116:119]
	ds_write_b128 v247, v[120:123] offset:1024
	ds_write_b128 v111, v[124:127] offset:2048
	ds_write_b128 v111, v[128:131] offset:3072
	ds_read_b128 v[116:119], v248
	ds_read_b128 v[120:123], v249
	ds_read_b128 v[124:127], v250
	ds_read_b128 v[128:131], v251
	ds_write_b128 v112, v[132:135]
	ds_write_b128 v112, v[136:139] offset:1024
	ds_write_b128 v112, v[140:143] offset:2048
	ds_write_b128 v112, v[144:147] offset:3072
	v_mfma_f32_32x32x16_bf16 v[32:47], v[192:195], v[52:55], v[32:47]
	v_mfma_f32_32x32x16_bf16 v[32:47], v[196:199], v[56:59], v[32:47]
	v_mfma_f32_32x32x16_bf16 v[32:47], v[200:203], v[60:63], v[32:47]
	s_nop 11
	v_exp_f32_e32 v32, v32
	v_exp_f32_e32 v33, v33
	v_exp_f32_e32 v34, v34
	v_exp_f32_e32 v35, v35
	v_exp_f32_e32 v36, v36
	v_exp_f32_e32 v37, v37
	v_exp_f32_e32 v38, v38
	v_exp_f32_e32 v39, v39
	v_exp_f32_e32 v40, v40
	v_exp_f32_e32 v41, v41
	v_exp_f32_e32 v42, v42
	v_exp_f32_e32 v43, v43
	v_exp_f32_e32 v44, v44
	v_exp_f32_e32 v45, v45
	v_exp_f32_e32 v46, v46
	v_exp_f32_e32 v47, v47
	v_cvt_pk_bf16_f32 v64, v32, v33
	v_cvt_pk_bf16_f32 v65, v34, v35
	v_cvt_pk_bf16_f32 v66, v36, v37
	v_cvt_pk_bf16_f32 v67, v38, v39
	v_cvt_pk_bf16_f32 v68, v40, v41
	v_cvt_pk_bf16_f32 v69, v42, v43
	v_cvt_pk_bf16_f32 v70, v44, v45
	v_cvt_pk_bf16_f32 v71, v46, v47
	v_pk_add_f32 v[232:233], v[232:233], v[32:33]
	v_pk_add_f32 v[232:233], v[232:233], v[34:35]
	v_pk_add_f32 v[232:233], v[232:233], v[36:37]
	v_pk_add_f32 v[232:233], v[232:233], v[38:39]
	v_pk_add_f32 v[232:233], v[232:233], v[40:41]
	v_pk_add_f32 v[232:233], v[232:233], v[42:43]
	v_pk_add_f32 v[232:233], v[232:233], v[44:45]
	v_pk_add_f32 v[232:233], v[232:233], v[46:47]
	v_add_u32_e32 v115, 640, v115
	ds_read2_b32 v[32:33], v115 offset0:0 offset1:1
	ds_read2_b32 v[34:35], v115 offset0:2 offset1:3
	ds_read2_b32 v[36:37], v115 offset0:10 offset1:11
	ds_read2_b32 v[38:39], v115 offset0:12 offset1:13
	ds_read2_b32 v[40:41], v115 offset0:20 offset1:21
	ds_read2_b32 v[42:43], v115 offset0:22 offset1:23
	ds_read2_b32 v[44:45], v115 offset0:30 offset1:31
	ds_read2_b32 v[46:47], v115 offset0:32 offset1:33
	s_waitcnt lgkmcnt(15)
	v_mfma_f32_32x32x16_bf16 v[0:15], v[64:67], v[72:75], v[0:15]
	v_mfma_f32_32x32x16_bf16 v[16:31], v[64:67], v[76:79], v[16:31]
	v_mfma_f32_32x32x16_bf16 v[0:15], v[68:71], v[220:223], v[0:15]
	v_mfma_f32_32x32x16_bf16 v[16:31], v[68:71], v[224:227], v[16:31]
	global_load_dwordx4 v[188:191], v239, s[86:87]
	global_load_dwordx4 v[192:195], v240, s[86:87]
	global_load_dwordx4 v[196:199], v241, s[86:87]
	global_load_dwordx4 v[200:203], v242, s[86:87]
	global_load_dwordx4 v[204:207], v101, s[86:87] offset:768
	global_load_dwordx4 v[208:211], v150, s[86:87] offset:768
	global_load_dwordx4 v[212:215], v101, s[86:87] offset:832
	global_load_dwordx4 v[216:219], v150, s[86:87] offset:832
	s_add_u32 s86, s86, 0xc0000
	s_addc_u32 s87, s87, 0
	s_waitcnt lgkmcnt(0)
	v_mfma_f32_32x32x16_bf16 v[32:47], v[116:119], v[48:51], v[32:47]
	ds_read_b64_tr_b16 v[72:73], v231
	ds_read_b64_tr_b16 v[74:75], v231 offset:512
	ds_read_b64_tr_b16 v[76:77], v231 offset:2048
	ds_read_b64_tr_b16 v[78:79], v231 offset:2560
	ds_read_b64_tr_b16 v[220:221], v231 offset:1024
	ds_read_b64_tr_b16 v[222:223], v231 offset:1536
	ds_read_b64_tr_b16 v[224:225], v231 offset:3072
	ds_read_b64_tr_b16 v[226:227], v231 offset:3584
	s_waitcnt vmcnt(8)
	ds_write_b128 v247, v[156:159]
	ds_write_b128 v247, v[160:163] offset:1024
	ds_write_b128 v111, v[164:167] offset:2048
	ds_write_b128 v111, v[168:171] offset:3072
	ds_read_b128 v[156:159], v248
	ds_read_b128 v[160:163], v249
	ds_read_b128 v[164:167], v250
	ds_read_b128 v[168:171], v251
	ds_write_b128 v112, v[172:175]
	ds_write_b128 v112, v[176:179] offset:1024
	ds_write_b128 v112, v[180:183] offset:2048
	ds_write_b128 v112, v[184:187] offset:3072
	v_mfma_f32_32x32x16_bf16 v[32:47], v[120:123], v[52:55], v[32:47]
	v_mfma_f32_32x32x16_bf16 v[32:47], v[124:127], v[56:59], v[32:47]
	v_mfma_f32_32x32x16_bf16 v[32:47], v[128:131], v[60:63], v[32:47]
	s_nop 11
	v_exp_f32_e32 v32, v32
	v_exp_f32_e32 v33, v33
	v_exp_f32_e32 v34, v34
	v_exp_f32_e32 v35, v35
	v_exp_f32_e32 v36, v36
	v_exp_f32_e32 v37, v37
	v_exp_f32_e32 v38, v38
	v_exp_f32_e32 v39, v39
	v_exp_f32_e32 v40, v40
	v_exp_f32_e32 v41, v41
	v_exp_f32_e32 v42, v42
	v_exp_f32_e32 v43, v43
	v_exp_f32_e32 v44, v44
	v_exp_f32_e32 v45, v45
	v_exp_f32_e32 v46, v46
	v_exp_f32_e32 v47, v47
	v_cvt_pk_bf16_f32 v64, v32, v33
	v_cvt_pk_bf16_f32 v65, v34, v35
	v_cvt_pk_bf16_f32 v66, v36, v37
	v_cvt_pk_bf16_f32 v67, v38, v39
	v_cvt_pk_bf16_f32 v68, v40, v41
	v_cvt_pk_bf16_f32 v69, v42, v43
	v_cvt_pk_bf16_f32 v70, v44, v45
	v_cvt_pk_bf16_f32 v71, v46, v47
	v_pk_add_f32 v[232:233], v[232:233], v[32:33]
	v_pk_add_f32 v[232:233], v[232:233], v[34:35]
	v_pk_add_f32 v[232:233], v[232:233], v[36:37]
	v_pk_add_f32 v[232:233], v[232:233], v[38:39]
	v_pk_add_f32 v[232:233], v[232:233], v[40:41]
	v_pk_add_f32 v[232:233], v[232:233], v[42:43]
	v_pk_add_f32 v[232:233], v[232:233], v[44:45]
	v_pk_add_f32 v[232:233], v[232:233], v[46:47]
	ds_read2_b32 v[32:33], v115 offset0:40 offset1:41
	ds_read2_b32 v[34:35], v115 offset0:42 offset1:43
	ds_read2_b32 v[36:37], v115 offset0:50 offset1:51
	ds_read2_b32 v[38:39], v115 offset0:52 offset1:53
	ds_read2_b32 v[40:41], v115 offset0:60 offset1:61
	ds_read2_b32 v[42:43], v115 offset0:62 offset1:63
	ds_read2_b32 v[44:45], v115 offset0:70 offset1:71
	ds_read2_b32 v[46:47], v115 offset0:72 offset1:73
	s_waitcnt lgkmcnt(15)
	v_mfma_f32_32x32x16_bf16 v[0:15], v[64:67], v[72:75], v[0:15]
	v_mfma_f32_32x32x16_bf16 v[16:31], v[64:67], v[76:79], v[16:31]
	v_mfma_f32_32x32x16_bf16 v[0:15], v[68:71], v[220:223], v[0:15]
	v_mfma_f32_32x32x16_bf16 v[16:31], v[68:71], v[224:227], v[16:31]
	global_load_dwordx4 v[116:119], v239, s[86:87]
	global_load_dwordx4 v[120:123], v240, s[86:87]
	global_load_dwordx4 v[124:127], v241, s[86:87]
	global_load_dwordx4 v[128:131], v242, s[86:87]
	global_load_dwordx4 v[132:135], v101, s[86:87] offset:768
	global_load_dwordx4 v[136:139], v150, s[86:87] offset:768
	global_load_dwordx4 v[140:143], v101, s[86:87] offset:832
	global_load_dwordx4 v[144:147], v150, s[86:87] offset:832
	s_waitcnt lgkmcnt(0)
	v_mfma_f32_32x32x16_bf16 v[32:47], v[156:159], v[48:51], v[32:47]
	ds_read_b64_tr_b16 v[72:73], v231
	ds_read_b64_tr_b16 v[74:75], v231 offset:512
	ds_read_b64_tr_b16 v[76:77], v231 offset:2048
	ds_read_b64_tr_b16 v[78:79], v231 offset:2560
	ds_read_b64_tr_b16 v[220:221], v231 offset:1024
	ds_read_b64_tr_b16 v[222:223], v231 offset:1536
	ds_read_b64_tr_b16 v[224:225], v231 offset:3072
	ds_read_b64_tr_b16 v[226:227], v231 offset:3584
	s_waitcnt vmcnt(8)
	ds_write_b128 v247, v[188:191]
	ds_write_b128 v247, v[192:195] offset:1024
	ds_write_b128 v111, v[196:199] offset:2048
	ds_write_b128 v111, v[200:203] offset:3072
	ds_read_b128 v[188:191], v248
	ds_read_b128 v[192:195], v249
	ds_read_b128 v[196:199], v250
	ds_read_b128 v[200:203], v251
	ds_write_b128 v112, v[204:207]
	ds_write_b128 v112, v[208:211] offset:1024
	ds_write_b128 v112, v[212:215] offset:2048
	ds_write_b128 v112, v[216:219] offset:3072
	v_mfma_f32_32x32x16_bf16 v[32:47], v[160:163], v[52:55], v[32:47]
	v_mfma_f32_32x32x16_bf16 v[32:47], v[164:167], v[56:59], v[32:47]
	v_mfma_f32_32x32x16_bf16 v[32:47], v[168:171], v[60:63], v[32:47]
	s_nop 11
	v_exp_f32_e32 v32, v32
	v_exp_f32_e32 v33, v33
	v_exp_f32_e32 v34, v34
	v_exp_f32_e32 v35, v35
	v_exp_f32_e32 v36, v36
	v_exp_f32_e32 v37, v37
	v_exp_f32_e32 v38, v38
	v_exp_f32_e32 v39, v39
	v_exp_f32_e32 v40, v40
	v_exp_f32_e32 v41, v41
	v_exp_f32_e32 v42, v42
	v_exp_f32_e32 v43, v43
	v_exp_f32_e32 v44, v44
	v_exp_f32_e32 v45, v45
	v_exp_f32_e32 v46, v46
	v_exp_f32_e32 v47, v47
	v_cvt_pk_bf16_f32 v64, v32, v33
	v_cvt_pk_bf16_f32 v65, v34, v35
	v_cvt_pk_bf16_f32 v66, v36, v37
	v_cvt_pk_bf16_f32 v67, v38, v39
	v_cvt_pk_bf16_f32 v68, v40, v41
	v_cvt_pk_bf16_f32 v69, v42, v43
	v_cvt_pk_bf16_f32 v70, v44, v45
	v_cvt_pk_bf16_f32 v71, v46, v47
	v_pk_add_f32 v[232:233], v[232:233], v[32:33]
	v_pk_add_f32 v[232:233], v[232:233], v[34:35]
	v_pk_add_f32 v[232:233], v[232:233], v[36:37]
	v_pk_add_f32 v[232:233], v[232:233], v[38:39]
	v_pk_add_f32 v[232:233], v[232:233], v[40:41]
	v_pk_add_f32 v[232:233], v[232:233], v[42:43]
	v_pk_add_f32 v[232:233], v[232:233], v[44:45]
	v_pk_add_f32 v[232:233], v[232:233], v[46:47]
	ds_read2_b32 v[32:33], v115 offset0:80 offset1:81
	ds_read2_b32 v[34:35], v115 offset0:82 offset1:83
	ds_read2_b32 v[36:37], v115 offset0:90 offset1:91
	ds_read2_b32 v[38:39], v115 offset0:92 offset1:93
	ds_read2_b32 v[40:41], v115 offset0:100 offset1:101
	ds_read2_b32 v[42:43], v115 offset0:102 offset1:103
	ds_read2_b32 v[44:45], v115 offset0:110 offset1:111
	ds_read2_b32 v[46:47], v115 offset0:112 offset1:113
	s_waitcnt lgkmcnt(15)
	v_mfma_f32_32x32x16_bf16 v[0:15], v[64:67], v[72:75], v[0:15]
	v_mfma_f32_32x32x16_bf16 v[16:31], v[64:67], v[76:79], v[16:31]
	v_mfma_f32_32x32x16_bf16 v[0:15], v[68:71], v[220:223], v[0:15]
	v_mfma_f32_32x32x16_bf16 v[16:31], v[68:71], v[224:227], v[16:31]
	global_load_dwordx4 v[156:159], v243, s[88:89]
	global_load_dwordx4 v[160:163], v244, s[88:89]
	global_load_dwordx4 v[164:167], v245, s[88:89]
	global_load_dwordx4 v[168:171], v246, s[88:89]
	global_load_dwordx4 v[172:175], v148, s[88:89] offset:768
	global_load_dwordx4 v[176:179], v151, s[88:89] offset:768
	global_load_dwordx4 v[180:183], v148, s[88:89] offset:832
	global_load_dwordx4 v[184:187], v151, s[88:89] offset:832
	s_add_u32 s88, s88, 0x300000
	s_addc_u32 s89, s89, 0
	s_waitcnt lgkmcnt(0)
	v_mfma_f32_32x32x16_bf16 v[32:47], v[188:191], v[48:51], v[32:47]
	ds_read_b64_tr_b16 v[72:73], v231
	ds_read_b64_tr_b16 v[74:75], v231 offset:512
	ds_read_b64_tr_b16 v[76:77], v231 offset:2048
	ds_read_b64_tr_b16 v[78:79], v231 offset:2560
	ds_read_b64_tr_b16 v[220:221], v231 offset:1024
	ds_read_b64_tr_b16 v[222:223], v231 offset:1536
	ds_read_b64_tr_b16 v[224:225], v231 offset:3072
	ds_read_b64_tr_b16 v[226:227], v231 offset:3584
	s_waitcnt vmcnt(8)
	ds_write_b128 v247, v[116:119]
	ds_write_b128 v247, v[120:123] offset:1024
	ds_write_b128 v111, v[124:127] offset:2048
	ds_write_b128 v111, v[128:131] offset:3072
	ds_read_b128 v[116:119], v248
	ds_read_b128 v[120:123], v249
	ds_read_b128 v[124:127], v250
	ds_read_b128 v[128:131], v251
	ds_write_b128 v112, v[132:135]
	ds_write_b128 v112, v[136:139] offset:1024
	ds_write_b128 v112, v[140:143] offset:2048
	ds_write_b128 v112, v[144:147] offset:3072
	v_mfma_f32_32x32x16_bf16 v[32:47], v[192:195], v[52:55], v[32:47]
	v_mfma_f32_32x32x16_bf16 v[32:47], v[196:199], v[56:59], v[32:47]
	v_mfma_f32_32x32x16_bf16 v[32:47], v[200:203], v[60:63], v[32:47]
	s_nop 11
	v_exp_f32_e32 v32, v32
	v_exp_f32_e32 v33, v33
	v_exp_f32_e32 v34, v34
	v_exp_f32_e32 v35, v35
	v_exp_f32_e32 v36, v36
	v_exp_f32_e32 v37, v37
	v_exp_f32_e32 v38, v38
	v_exp_f32_e32 v39, v39
	v_exp_f32_e32 v40, v40
	v_exp_f32_e32 v41, v41
	v_exp_f32_e32 v42, v42
	v_exp_f32_e32 v43, v43
	v_exp_f32_e32 v44, v44
	v_exp_f32_e32 v45, v45
	v_exp_f32_e32 v46, v46
	v_exp_f32_e32 v47, v47
	v_cvt_pk_bf16_f32 v64, v32, v33
	v_cvt_pk_bf16_f32 v65, v34, v35
	v_cvt_pk_bf16_f32 v66, v36, v37
	v_cvt_pk_bf16_f32 v67, v38, v39
	v_cvt_pk_bf16_f32 v68, v40, v41
	v_cvt_pk_bf16_f32 v69, v42, v43
	v_cvt_pk_bf16_f32 v70, v44, v45
	v_cvt_pk_bf16_f32 v71, v46, v47
	v_pk_add_f32 v[232:233], v[232:233], v[32:33]
	v_pk_add_f32 v[232:233], v[232:233], v[34:35]
	v_pk_add_f32 v[232:233], v[232:233], v[36:37]
	v_pk_add_f32 v[232:233], v[232:233], v[38:39]
	v_pk_add_f32 v[232:233], v[232:233], v[40:41]
	v_pk_add_f32 v[232:233], v[232:233], v[42:43]
	v_pk_add_f32 v[232:233], v[232:233], v[44:45]
	v_pk_add_f32 v[232:233], v[232:233], v[46:47]
	ds_read2_b32 v[32:33], v115 offset0:120 offset1:121
	ds_read2_b32 v[34:35], v115 offset0:122 offset1:123
	ds_read2_b32 v[36:37], v115 offset0:130 offset1:131
	ds_read2_b32 v[38:39], v115 offset0:132 offset1:133
	ds_read2_b32 v[40:41], v115 offset0:140 offset1:141
	ds_read2_b32 v[42:43], v115 offset0:142 offset1:143
	ds_read2_b32 v[44:45], v115 offset0:150 offset1:151
	ds_read2_b32 v[46:47], v115 offset0:152 offset1:153
	s_waitcnt lgkmcnt(15)
	v_mfma_f32_32x32x16_bf16 v[0:15], v[64:67], v[72:75], v[0:15]
	v_mfma_f32_32x32x16_bf16 v[16:31], v[64:67], v[76:79], v[16:31]
	v_mfma_f32_32x32x16_bf16 v[0:15], v[68:71], v[220:223], v[0:15]
	v_mfma_f32_32x32x16_bf16 v[16:31], v[68:71], v[224:227], v[16:31]
	global_load_dwordx4 v[188:191], v243, s[88:89]
	global_load_dwordx4 v[192:195], v244, s[88:89]
	global_load_dwordx4 v[196:199], v245, s[88:89]
	global_load_dwordx4 v[200:203], v246, s[88:89]
	global_load_dwordx4 v[204:207], v148, s[88:89] offset:768
	global_load_dwordx4 v[208:211], v151, s[88:89] offset:768
	global_load_dwordx4 v[212:215], v148, s[88:89] offset:832
	global_load_dwordx4 v[216:219], v151, s[88:89] offset:832
	s_add_u32 s88, s88, 0x300000
	s_addc_u32 s89, s89, 0
	s_waitcnt lgkmcnt(0)
	v_mfma_f32_32x32x16_bf16 v[32:47], v[116:119], v[48:51], v[32:47]
	ds_read_b64_tr_b16 v[72:73], v231
	ds_read_b64_tr_b16 v[74:75], v231 offset:512
	ds_read_b64_tr_b16 v[76:77], v231 offset:2048
	ds_read_b64_tr_b16 v[78:79], v231 offset:2560
	ds_read_b64_tr_b16 v[220:221], v231 offset:1024
	ds_read_b64_tr_b16 v[222:223], v231 offset:1536
	ds_read_b64_tr_b16 v[224:225], v231 offset:3072
	ds_read_b64_tr_b16 v[226:227], v231 offset:3584
	s_waitcnt vmcnt(8)
	ds_write_b128 v247, v[156:159]
	ds_write_b128 v247, v[160:163] offset:1024
	ds_write_b128 v111, v[164:167] offset:2048
	ds_write_b128 v111, v[168:171] offset:3072
	ds_read_b128 v[156:159], v248
	ds_read_b128 v[160:163], v249
	ds_read_b128 v[164:167], v250
	ds_read_b128 v[168:171], v251
	ds_write_b128 v112, v[172:175]
	ds_write_b128 v112, v[176:179] offset:1024
	ds_write_b128 v112, v[180:183] offset:2048
	ds_write_b128 v112, v[184:187] offset:3072
	v_mfma_f32_32x32x16_bf16 v[32:47], v[120:123], v[52:55], v[32:47]
	v_mfma_f32_32x32x16_bf16 v[32:47], v[124:127], v[56:59], v[32:47]
	v_mfma_f32_32x32x16_bf16 v[32:47], v[128:131], v[60:63], v[32:47]
	s_nop 11
	v_exp_f32_e32 v32, v32
	v_exp_f32_e32 v33, v33
	v_exp_f32_e32 v34, v34
	v_exp_f32_e32 v35, v35
	v_exp_f32_e32 v36, v36
	v_exp_f32_e32 v37, v37
	v_exp_f32_e32 v38, v38
	v_exp_f32_e32 v39, v39
	v_exp_f32_e32 v40, v40
	v_exp_f32_e32 v41, v41
	v_exp_f32_e32 v42, v42
	v_exp_f32_e32 v43, v43
	v_exp_f32_e32 v44, v44
	v_exp_f32_e32 v45, v45
	v_exp_f32_e32 v46, v46
	v_exp_f32_e32 v47, v47
	v_cvt_pk_bf16_f32 v64, v32, v33
	v_cvt_pk_bf16_f32 v65, v34, v35
	v_cvt_pk_bf16_f32 v66, v36, v37
	v_cvt_pk_bf16_f32 v67, v38, v39
	v_cvt_pk_bf16_f32 v68, v40, v41
	v_cvt_pk_bf16_f32 v69, v42, v43
	v_cvt_pk_bf16_f32 v70, v44, v45
	v_cvt_pk_bf16_f32 v71, v46, v47
	v_pk_add_f32 v[232:233], v[232:233], v[32:33]
	v_pk_add_f32 v[232:233], v[232:233], v[34:35]
	v_pk_add_f32 v[232:233], v[232:233], v[36:37]
	v_pk_add_f32 v[232:233], v[232:233], v[38:39]
	v_pk_add_f32 v[232:233], v[232:233], v[40:41]
	v_pk_add_f32 v[232:233], v[232:233], v[42:43]
	v_pk_add_f32 v[232:233], v[232:233], v[44:45]
	v_pk_add_f32 v[232:233], v[232:233], v[46:47]
	v_mov_b32_e32 v115, v230
	ds_read2_b32 v[32:33], v115 offset0:0 offset1:1
	ds_read2_b32 v[34:35], v115 offset0:2 offset1:3
	ds_read2_b32 v[36:37], v115 offset0:8 offset1:9
	ds_read2_b32 v[38:39], v115 offset0:10 offset1:11
	ds_read2_b32 v[40:41], v115 offset0:16 offset1:17
	ds_read2_b32 v[42:43], v115 offset0:18 offset1:19
	ds_read2_b32 v[44:45], v115 offset0:24 offset1:25
	ds_read2_b32 v[46:47], v115 offset0:26 offset1:27
	s_waitcnt lgkmcnt(15)
	v_mfma_f32_32x32x16_bf16 v[0:15], v[64:67], v[72:75], v[0:15]
	v_mfma_f32_32x32x16_bf16 v[16:31], v[64:67], v[76:79], v[16:31]
	v_mfma_f32_32x32x16_bf16 v[0:15], v[68:71], v[220:223], v[0:15]
	v_mfma_f32_32x32x16_bf16 v[16:31], v[68:71], v[224:227], v[16:31]
	global_load_dwordx4 v[116:119], v243, s[88:89]
	global_load_dwordx4 v[120:123], v244, s[88:89]
	global_load_dwordx4 v[124:127], v245, s[88:89]
	global_load_dwordx4 v[128:131], v246, s[88:89]
	global_load_dwordx4 v[132:135], v148, s[88:89] offset:768
	global_load_dwordx4 v[136:139], v151, s[88:89] offset:768
	global_load_dwordx4 v[140:143], v148, s[88:89] offset:832
	global_load_dwordx4 v[144:147], v151, s[88:89] offset:832
	s_add_u32 s88, s88, 0x300000
	s_addc_u32 s89, s89, 0
	s_waitcnt lgkmcnt(0)
	v_mfma_f32_32x32x16_bf16 v[32:47], v[156:159], v[48:51], v[32:47]
	ds_read_b64_tr_b16 v[72:73], v231
	ds_read_b64_tr_b16 v[74:75], v231 offset:512
	ds_read_b64_tr_b16 v[76:77], v231 offset:2048
	ds_read_b64_tr_b16 v[78:79], v231 offset:2560
	ds_read_b64_tr_b16 v[220:221], v231 offset:1024
	ds_read_b64_tr_b16 v[222:223], v231 offset:1536
	ds_read_b64_tr_b16 v[224:225], v231 offset:3072
	ds_read_b64_tr_b16 v[226:227], v231 offset:3584
	s_waitcnt vmcnt(8)
	ds_write_b128 v247, v[188:191]
	ds_write_b128 v247, v[192:195] offset:1024
	ds_write_b128 v111, v[196:199] offset:2048
	ds_write_b128 v111, v[200:203] offset:3072
	ds_read_b128 v[188:191], v248
	ds_read_b128 v[192:195], v249
	ds_read_b128 v[196:199], v250
	ds_read_b128 v[200:203], v251
	ds_write_b128 v112, v[204:207]
	ds_write_b128 v112, v[208:211] offset:1024
	ds_write_b128 v112, v[212:215] offset:2048
	ds_write_b128 v112, v[216:219] offset:3072
	v_mfma_f32_32x32x16_bf16 v[32:47], v[160:163], v[52:55], v[32:47]
	v_mfma_f32_32x32x16_bf16 v[32:47], v[164:167], v[56:59], v[32:47]
	v_mfma_f32_32x32x16_bf16 v[32:47], v[168:171], v[60:63], v[32:47]
	s_nop 11
	v_exp_f32_e32 v32, v32
	v_exp_f32_e32 v33, v33
	v_exp_f32_e32 v34, v34
	v_exp_f32_e32 v35, v35
	v_exp_f32_e32 v36, v36
	v_exp_f32_e32 v37, v37
	v_exp_f32_e32 v38, v38
	v_exp_f32_e32 v39, v39
	v_exp_f32_e32 v40, v40
	v_exp_f32_e32 v41, v41
	v_exp_f32_e32 v42, v42
	v_exp_f32_e32 v43, v43
	v_exp_f32_e32 v44, v44
	v_exp_f32_e32 v45, v45
	v_exp_f32_e32 v46, v46
	v_exp_f32_e32 v47, v47
	v_cvt_pk_bf16_f32 v64, v32, v33
	v_cvt_pk_bf16_f32 v65, v34, v35
	v_cvt_pk_bf16_f32 v66, v36, v37
	v_cvt_pk_bf16_f32 v67, v38, v39
	v_cvt_pk_bf16_f32 v68, v40, v41
	v_cvt_pk_bf16_f32 v69, v42, v43
	v_cvt_pk_bf16_f32 v70, v44, v45
	v_cvt_pk_bf16_f32 v71, v46, v47
	v_pk_add_f32 v[232:233], v[232:233], v[32:33]
	v_pk_add_f32 v[232:233], v[232:233], v[34:35]
	v_pk_add_f32 v[232:233], v[232:233], v[36:37]
	v_pk_add_f32 v[232:233], v[232:233], v[38:39]
	v_pk_add_f32 v[232:233], v[232:233], v[40:41]
	v_pk_add_f32 v[232:233], v[232:233], v[42:43]
	v_pk_add_f32 v[232:233], v[232:233], v[44:45]
	v_pk_add_f32 v[232:233], v[232:233], v[46:47]
	ds_read2_b32 v[32:33], v115 offset0:32 offset1:33
	ds_read2_b32 v[34:35], v115 offset0:34 offset1:35
	ds_read2_b32 v[36:37], v115 offset0:40 offset1:41
	ds_read2_b32 v[38:39], v115 offset0:42 offset1:43
	ds_read2_b32 v[40:41], v115 offset0:48 offset1:49
	ds_read2_b32 v[42:43], v115 offset0:50 offset1:51
	ds_read2_b32 v[44:45], v115 offset0:56 offset1:57
	ds_read2_b32 v[46:47], v115 offset0:58 offset1:59
	s_waitcnt lgkmcnt(15)
	v_mfma_f32_32x32x16_bf16 v[0:15], v[64:67], v[72:75], v[0:15]
	v_mfma_f32_32x32x16_bf16 v[16:31], v[64:67], v[76:79], v[16:31]
	v_mfma_f32_32x32x16_bf16 v[0:15], v[68:71], v[220:223], v[0:15]
	v_mfma_f32_32x32x16_bf16 v[16:31], v[68:71], v[224:227], v[16:31]
	global_load_dwordx4 v[156:159], v243, s[88:89]
	global_load_dwordx4 v[160:163], v244, s[88:89]
	global_load_dwordx4 v[164:167], v245, s[88:89]
	global_load_dwordx4 v[168:171], v246, s[88:89]
	global_load_dwordx4 v[172:175], v148, s[88:89] offset:768
	global_load_dwordx4 v[176:179], v151, s[88:89] offset:768
	global_load_dwordx4 v[180:183], v148, s[88:89] offset:832
	global_load_dwordx4 v[184:187], v151, s[88:89] offset:832
	s_add_u32 s88, s88, 0x300000
	s_addc_u32 s89, s89, 0
	s_waitcnt lgkmcnt(0)
	v_mfma_f32_32x32x16_bf16 v[32:47], v[188:191], v[48:51], v[32:47]
	ds_read_b64_tr_b16 v[72:73], v231
	ds_read_b64_tr_b16 v[74:75], v231 offset:512
	ds_read_b64_tr_b16 v[76:77], v231 offset:2048
	ds_read_b64_tr_b16 v[78:79], v231 offset:2560
	ds_read_b64_tr_b16 v[220:221], v231 offset:1024
	ds_read_b64_tr_b16 v[222:223], v231 offset:1536
	ds_read_b64_tr_b16 v[224:225], v231 offset:3072
	ds_read_b64_tr_b16 v[226:227], v231 offset:3584
	s_waitcnt vmcnt(8)
	ds_write_b128 v247, v[116:119]
	ds_write_b128 v247, v[120:123] offset:1024
	ds_write_b128 v111, v[124:127] offset:2048
	ds_write_b128 v111, v[128:131] offset:3072
	ds_read_b128 v[116:119], v248
	ds_read_b128 v[120:123], v249
	ds_read_b128 v[124:127], v250
	ds_read_b128 v[128:131], v251
	ds_write_b128 v112, v[132:135]
	ds_write_b128 v112, v[136:139] offset:1024
	ds_write_b128 v112, v[140:143] offset:2048
	ds_write_b128 v112, v[144:147] offset:3072
	v_mfma_f32_32x32x16_bf16 v[32:47], v[192:195], v[52:55], v[32:47]
	v_mfma_f32_32x32x16_bf16 v[32:47], v[196:199], v[56:59], v[32:47]
	v_mfma_f32_32x32x16_bf16 v[32:47], v[200:203], v[60:63], v[32:47]
	s_nop 11
	v_exp_f32_e32 v32, v32
	v_exp_f32_e32 v33, v33
	v_exp_f32_e32 v34, v34
	v_exp_f32_e32 v35, v35
	v_exp_f32_e32 v36, v36
	v_exp_f32_e32 v37, v37
	v_exp_f32_e32 v38, v38
	v_exp_f32_e32 v39, v39
	v_exp_f32_e32 v40, v40
	v_exp_f32_e32 v41, v41
	v_exp_f32_e32 v42, v42
	v_exp_f32_e32 v43, v43
	v_exp_f32_e32 v44, v44
	v_exp_f32_e32 v45, v45
	v_exp_f32_e32 v46, v46
	v_exp_f32_e32 v47, v47
	v_cvt_pk_bf16_f32 v64, v32, v33
	v_cvt_pk_bf16_f32 v65, v34, v35
	v_cvt_pk_bf16_f32 v66, v36, v37
	v_cvt_pk_bf16_f32 v67, v38, v39
	v_cvt_pk_bf16_f32 v68, v40, v41
	v_cvt_pk_bf16_f32 v69, v42, v43
	v_cvt_pk_bf16_f32 v70, v44, v45
	v_cvt_pk_bf16_f32 v71, v46, v47
	v_pk_add_f32 v[232:233], v[232:233], v[32:33]
	v_pk_add_f32 v[232:233], v[232:233], v[34:35]
	v_pk_add_f32 v[232:233], v[232:233], v[36:37]
	v_pk_add_f32 v[232:233], v[232:233], v[38:39]
	v_pk_add_f32 v[232:233], v[232:233], v[40:41]
	v_pk_add_f32 v[232:233], v[232:233], v[42:43]
	v_pk_add_f32 v[232:233], v[232:233], v[44:45]
	v_pk_add_f32 v[232:233], v[232:233], v[46:47]
	ds_read2_b32 v[32:33], v115 offset0:64 offset1:65
	ds_read2_b32 v[34:35], v115 offset0:66 offset1:67
	ds_read2_b32 v[36:37], v115 offset0:72 offset1:73
	ds_read2_b32 v[38:39], v115 offset0:74 offset1:75
	ds_read2_b32 v[40:41], v115 offset0:80 offset1:81
	ds_read2_b32 v[42:43], v115 offset0:82 offset1:83
	ds_read2_b32 v[44:45], v115 offset0:88 offset1:89
	ds_read2_b32 v[46:47], v115 offset0:90 offset1:91
	s_waitcnt lgkmcnt(15)
	v_mfma_f32_32x32x16_bf16 v[0:15], v[64:67], v[72:75], v[0:15]
	v_mfma_f32_32x32x16_bf16 v[16:31], v[64:67], v[76:79], v[16:31]
	v_mfma_f32_32x32x16_bf16 v[0:15], v[68:71], v[220:223], v[0:15]
	v_mfma_f32_32x32x16_bf16 v[16:31], v[68:71], v[224:227], v[16:31]
	global_load_dwordx4 v[188:191], v243, s[88:89]
	global_load_dwordx4 v[192:195], v244, s[88:89]
	global_load_dwordx4 v[196:199], v245, s[88:89]
	global_load_dwordx4 v[200:203], v246, s[88:89]
	global_load_dwordx4 v[204:207], v148, s[88:89] offset:768
	global_load_dwordx4 v[208:211], v151, s[88:89] offset:768
	global_load_dwordx4 v[212:215], v148, s[88:89] offset:832
	global_load_dwordx4 v[216:219], v151, s[88:89] offset:832
	s_waitcnt lgkmcnt(0)
	v_mfma_f32_32x32x16_bf16 v[32:47], v[116:119], v[48:51], v[32:47]
	ds_read_b64_tr_b16 v[72:73], v231
	ds_read_b64_tr_b16 v[74:75], v231 offset:512
	ds_read_b64_tr_b16 v[76:77], v231 offset:2048
	ds_read_b64_tr_b16 v[78:79], v231 offset:2560
	ds_read_b64_tr_b16 v[220:221], v231 offset:1024
	ds_read_b64_tr_b16 v[222:223], v231 offset:1536
	ds_read_b64_tr_b16 v[224:225], v231 offset:3072
	ds_read_b64_tr_b16 v[226:227], v231 offset:3584
	s_waitcnt vmcnt(8)
	ds_write_b128 v247, v[156:159]
	ds_write_b128 v247, v[160:163] offset:1024
	ds_write_b128 v111, v[164:167] offset:2048
	ds_write_b128 v111, v[168:171] offset:3072
	ds_read_b128 v[156:159], v248
	ds_read_b128 v[160:163], v249
	ds_read_b128 v[164:167], v250
	ds_read_b128 v[168:171], v251
	ds_write_b128 v112, v[172:175]
	ds_write_b128 v112, v[176:179] offset:1024
	ds_write_b128 v112, v[180:183] offset:2048
	ds_write_b128 v112, v[184:187] offset:3072
	v_mfma_f32_32x32x16_bf16 v[32:47], v[120:123], v[52:55], v[32:47]
	v_mfma_f32_32x32x16_bf16 v[32:47], v[124:127], v[56:59], v[32:47]
	v_mfma_f32_32x32x16_bf16 v[32:47], v[128:131], v[60:63], v[32:47]
	s_nop 11
	v_exp_f32_e32 v32, v32
	v_exp_f32_e32 v33, v33
	v_exp_f32_e32 v34, v34
	v_exp_f32_e32 v35, v35
	v_exp_f32_e32 v36, v36
	v_exp_f32_e32 v37, v37
	v_exp_f32_e32 v38, v38
	v_exp_f32_e32 v39, v39
	v_exp_f32_e32 v40, v40
	v_exp_f32_e32 v41, v41
	v_exp_f32_e32 v42, v42
	v_exp_f32_e32 v43, v43
	v_exp_f32_e32 v44, v44
	v_exp_f32_e32 v45, v45
	v_exp_f32_e32 v46, v46
	v_exp_f32_e32 v47, v47
	v_cvt_pk_bf16_f32 v64, v32, v33
	v_cvt_pk_bf16_f32 v65, v34, v35
	v_cvt_pk_bf16_f32 v66, v36, v37
	v_cvt_pk_bf16_f32 v67, v38, v39
	v_cvt_pk_bf16_f32 v68, v40, v41
	v_cvt_pk_bf16_f32 v69, v42, v43
	v_cvt_pk_bf16_f32 v70, v44, v45
	v_cvt_pk_bf16_f32 v71, v46, v47
	v_pk_add_f32 v[232:233], v[232:233], v[32:33]
	v_pk_add_f32 v[232:233], v[232:233], v[34:35]
	v_pk_add_f32 v[232:233], v[232:233], v[36:37]
	v_pk_add_f32 v[232:233], v[232:233], v[38:39]
	v_pk_add_f32 v[232:233], v[232:233], v[40:41]
	v_pk_add_f32 v[232:233], v[232:233], v[42:43]
	v_pk_add_f32 v[232:233], v[232:233], v[44:45]
	v_pk_add_f32 v[232:233], v[232:233], v[46:47]
	ds_read2_b32 v[32:33], v115 offset0:96 offset1:97
	ds_read2_b32 v[34:35], v115 offset0:98 offset1:99
	ds_read2_b32 v[36:37], v115 offset0:104 offset1:105
	ds_read2_b32 v[38:39], v115 offset0:106 offset1:107
	ds_read2_b32 v[40:41], v115 offset0:112 offset1:113
	ds_read2_b32 v[42:43], v115 offset0:114 offset1:115
	ds_read2_b32 v[44:45], v115 offset0:120 offset1:121
	ds_read2_b32 v[46:47], v115 offset0:122 offset1:123
	s_waitcnt lgkmcnt(15)
	v_mfma_f32_32x32x16_bf16 v[0:15], v[64:67], v[72:75], v[0:15]
	v_mfma_f32_32x32x16_bf16 v[16:31], v[64:67], v[76:79], v[16:31]
	v_mfma_f32_32x32x16_bf16 v[0:15], v[68:71], v[220:223], v[0:15]
	v_mfma_f32_32x32x16_bf16 v[16:31], v[68:71], v[224:227], v[16:31]
	s_waitcnt lgkmcnt(0)
	v_mfma_f32_32x32x16_bf16 v[32:47], v[156:159], v[48:51], v[32:47]
	ds_read_b64_tr_b16 v[72:73], v231
	ds_read_b64_tr_b16 v[74:75], v231 offset:512
	ds_read_b64_tr_b16 v[76:77], v231 offset:2048
	ds_read_b64_tr_b16 v[78:79], v231 offset:2560
	ds_read_b64_tr_b16 v[220:221], v231 offset:1024
	ds_read_b64_tr_b16 v[222:223], v231 offset:1536
	ds_read_b64_tr_b16 v[224:225], v231 offset:3072
	ds_read_b64_tr_b16 v[226:227], v231 offset:3584
	s_waitcnt vmcnt(0)
	ds_write_b128 v247, v[188:191]
	ds_write_b128 v247, v[192:195] offset:1024
	ds_write_b128 v111, v[196:199] offset:2048
	ds_write_b128 v111, v[200:203] offset:3072
	ds_read_b128 v[188:191], v248
	ds_read_b128 v[192:195], v249
	ds_read_b128 v[196:199], v250
	ds_read_b128 v[200:203], v251
	ds_write_b128 v112, v[204:207]
	ds_write_b128 v112, v[208:211] offset:1024
	ds_write_b128 v112, v[212:215] offset:2048
	ds_write_b128 v112, v[216:219] offset:3072
	v_mfma_f32_32x32x16_bf16 v[32:47], v[160:163], v[52:55], v[32:47]
	v_mfma_f32_32x32x16_bf16 v[32:47], v[164:167], v[56:59], v[32:47]
	v_mfma_f32_32x32x16_bf16 v[32:47], v[168:171], v[60:63], v[32:47]
	s_nop 11
	v_exp_f32_e32 v32, v32
	v_exp_f32_e32 v33, v33
	v_exp_f32_e32 v34, v34
	v_exp_f32_e32 v35, v35
	v_exp_f32_e32 v36, v36
	v_exp_f32_e32 v37, v37
	v_exp_f32_e32 v38, v38
	v_exp_f32_e32 v39, v39
	v_exp_f32_e32 v40, v40
	v_exp_f32_e32 v41, v41
	v_exp_f32_e32 v42, v42
	v_exp_f32_e32 v43, v43
	v_exp_f32_e32 v44, v44
	v_exp_f32_e32 v45, v45
	v_exp_f32_e32 v46, v46
	v_exp_f32_e32 v47, v47
	v_cvt_pk_bf16_f32 v64, v32, v33
	v_cvt_pk_bf16_f32 v65, v34, v35
	v_cvt_pk_bf16_f32 v66, v36, v37
	v_cvt_pk_bf16_f32 v67, v38, v39
	v_cvt_pk_bf16_f32 v68, v40, v41
	v_cvt_pk_bf16_f32 v69, v42, v43
	v_cvt_pk_bf16_f32 v70, v44, v45
	v_cvt_pk_bf16_f32 v71, v46, v47
	v_pk_add_f32 v[232:233], v[232:233], v[32:33]
	v_pk_add_f32 v[232:233], v[232:233], v[34:35]
	v_pk_add_f32 v[232:233], v[232:233], v[36:37]
	v_pk_add_f32 v[232:233], v[232:233], v[38:39]
	v_pk_add_f32 v[232:233], v[232:233], v[40:41]
	v_pk_add_f32 v[232:233], v[232:233], v[42:43]
	v_pk_add_f32 v[232:233], v[232:233], v[44:45]
	v_pk_add_f32 v[232:233], v[232:233], v[46:47]
	ds_read2_b32 v[32:33], v115 offset0:128 offset1:129
	ds_read2_b32 v[34:35], v115 offset0:130 offset1:131
	ds_read2_b32 v[36:37], v115 offset0:136 offset1:137
	ds_read2_b32 v[38:39], v115 offset0:138 offset1:139
	ds_read2_b32 v[40:41], v115 offset0:144 offset1:145
	ds_read2_b32 v[42:43], v115 offset0:146 offset1:147
	ds_read2_b32 v[44:45], v115 offset0:152 offset1:153
	ds_read2_b32 v[46:47], v115 offset0:154 offset1:155
	s_waitcnt lgkmcnt(15)
; #define LAS __attribute__((address_space(3)))
; #define GAS __attribute__((address_space(1)))
; __device__ __forceinline__ int crow(int r, int hi) { return (r & 3) + 8 * (r >> 2) + 4 * hi; }
; __device__ __forceinline__ void dil_unit(LAS unsigned char* lds, bf16_t* proj, int seq, int hd, int T0, int rho) {
;     int tid_ = threadIdx.x; asm volatile("" : "+v"(tid_));
;     const int tid = tid_, lane = tid & 63, r32 = lane & 31, hi = lane >> 5, wid = __builtin_amdgcn_readfirstlane(tid >> 6);
;     bf16_t* base = proj + (size_t)seq * SEQ * NIN;
;     LAS unsigned char* wbuf = lds + wid * 4096;
;     const LAS unsigned char* vp = wbuf + ((lane >> 4) & 1) * 32 + (lane & 3) * 8 + (4 * hi + ((lane & 15) >> 2)) * 64;
;     const int P0 = T0 + rho;
;     bf16x8 qr[4];
; #pragma unroll
;     for (int ks = 0; ks < 4; ++ks) qr[ks] = *(const GAS bf16x8*)(base + (size_t)(P0 + 16 * r32) * NIN + PC_LQ + hd * 64 + 16 * ks + 8 * hi);
;     f32x16 o0 = {}, o1 = {}; float l = 0.f;
;     const bool bound = (T0 < 1024) || (T0 >= 15360);
;     ...
;     if (bound) DIL_LOOP(true); else DIL_LOOP(false);
;     ...
;     LAS bf16_t* stg = (LAS bf16_t*)wbuf;
;     l += __shfl_xor(l, 32);
; #pragma unroll
;     for (int rr = 0; rr < 16; ++rr) {
;         const int j = crow(rr, hi);
;         const float il = __builtin_amdgcn_rcpf(__shfl(l, j));
	v_mfma_f32_32x32x16_bf16 v[0:15], v[64:67], v[72:75], v[0:15]
	v_mfma_f32_32x32x16_bf16 v[16:31], v[64:67], v[76:79], v[16:31]
	v_mfma_f32_32x32x16_bf16 v[0:15], v[68:71], v[220:223], v[0:15]
	v_mfma_f32_32x32x16_bf16 v[16:31], v[68:71], v[224:227], v[16:31]
	s_waitcnt lgkmcnt(0)
	v_mfma_f32_32x32x16_bf16 v[32:47], v[188:191], v[48:51], v[32:47]
	ds_read_b64_tr_b16 v[72:73], v231
	ds_read_b64_tr_b16 v[74:75], v231 offset:512
	ds_read_b64_tr_b16 v[76:77], v231 offset:2048
	ds_read_b64_tr_b16 v[78:79], v231 offset:2560
	ds_read_b64_tr_b16 v[220:221], v231 offset:1024
	ds_read_b64_tr_b16 v[222:223], v231 offset:1536
	ds_read_b64_tr_b16 v[224:225], v231 offset:3072
	ds_read_b64_tr_b16 v[226:227], v231 offset:3584
	v_mfma_f32_32x32x16_bf16 v[32:47], v[192:195], v[52:55], v[32:47]
	v_mfma_f32_32x32x16_bf16 v[32:47], v[196:199], v[56:59], v[32:47]
	v_mfma_f32_32x32x16_bf16 v[32:47], v[200:203], v[60:63], v[32:47]
	s_nop 11
	v_exp_f32_e32 v32, v32
	v_exp_f32_e32 v33, v33
	v_exp_f32_e32 v34, v34
	v_exp_f32_e32 v35, v35
	v_exp_f32_e32 v36, v36
	v_exp_f32_e32 v37, v37
	v_exp_f32_e32 v38, v38
	v_exp_f32_e32 v39, v39
	v_exp_f32_e32 v40, v40
	v_exp_f32_e32 v41, v41
	v_exp_f32_e32 v42, v42
	v_exp_f32_e32 v43, v43
	v_exp_f32_e32 v44, v44
	v_exp_f32_e32 v45, v45
	v_exp_f32_e32 v46, v46
	v_exp_f32_e32 v47, v47
	v_cvt_pk_bf16_f32 v64, v32, v33
	v_cvt_pk_bf16_f32 v65, v34, v35
	v_cvt_pk_bf16_f32 v66, v36, v37
	v_cvt_pk_bf16_f32 v67, v38, v39
	v_cvt_pk_bf16_f32 v68, v40, v41
	v_cvt_pk_bf16_f32 v69, v42, v43
	v_cvt_pk_bf16_f32 v70, v44, v45
	v_cvt_pk_bf16_f32 v71, v46, v47
	v_pk_add_f32 v[232:233], v[232:233], v[32:33]
	v_pk_add_f32 v[232:233], v[232:233], v[34:35]
	v_pk_add_f32 v[232:233], v[232:233], v[36:37]
	v_pk_add_f32 v[232:233], v[232:233], v[38:39]
	v_pk_add_f32 v[232:233], v[232:233], v[40:41]
	v_pk_add_f32 v[232:233], v[232:233], v[42:43]
	v_pk_add_f32 v[232:233], v[232:233], v[44:45]
	v_pk_add_f32 v[232:233], v[232:233], v[46:47]
	s_waitcnt lgkmcnt(0)
	v_mfma_f32_32x32x16_bf16 v[0:15], v[64:67], v[72:75], v[0:15]
	v_mfma_f32_32x32x16_bf16 v[16:31], v[64:67], v[76:79], v[16:31]
	v_mfma_f32_32x32x16_bf16 v[0:15], v[68:71], v[220:223], v[0:15]
	v_mfma_f32_32x32x16_bf16 v[16:31], v[68:71], v[224:227], v[16:31]
	v_add_f32_e32 v113, v232, v233
	v_or_b32_e32 v114, 1, v107
	v_or_b32_e32 v97, 2, v107
	v_or_b32_e32 v96, 3, v107
	v_or_b32_e32 v95, 8, v107
	v_or_b32_e32 v94, 9, v107
	v_or_b32_e32 v93, 10, v107
	v_or_b32_e32 v92, 11, v107
	v_or_b32_e32 v91, 16, v107
	v_or_b32_e32 v90, 17, v107
	v_or_b32_e32 v89, 18, v107
	v_or_b32_e32 v88, 19, v107
	v_or_b32_e32 v87, 24, v107
	v_or_b32_e32 v86, 25, v107
	v_or_b32_e32 v85, 26, v107
	v_or_b32_e32 v84, 27, v107
	s_nop 11
	s_branch .LBB0_1265
.LBB0_1270:
	s_movk_i32 s100, 0x1800
	s_add_i32 s101, s8, 0x15c00
	s_lshl_b32 s90, s54, 1
	s_add_u32 s82, s52, s90
	s_addc_u32 s83, s53, 0
	s_add_u32 s82, s82, 0x1200
	s_addc_u32 s83, s83, 0
	s_sub_i32 s90, s67, 64
	s_mul_i32 s90, s90, 0x1800
	s_add_u32 s84, s82, s90
	s_addc_u32 s85, s83, 0
	s_sub_i32 s90, s67, 256
	s_mul_i32 s90, s90, 0x1800
	s_add_u32 s86, s82, s90
	s_addc_u32 s87, s83, 0
	s_sub_i32 s90, s67, 1024
	s_mul_i32 s90, s90, 0x1800
	s_add_u32 s88, s82, s90
	s_addc_u32 s89, s83, 0
	v_lshlrev_b32_e32 v153, 1, v98
	v_mad_u32_u24 v80, v105, s100, v82
	v_mad_u32_u24 v100, v110, s100, v153
	v_add_u32_e32 v149, 0x18000, v100
	v_lshlrev_b32_e32 v83, 2, v105
	v_mad_u32_u24 v83, v83, s100, v82
	v_lshlrev_b32_e32 v101, 2, v110
	v_mad_u32_u24 v101, v101, s100, v153
	v_add_u32_e32 v150, 0x60000, v101
	v_lshlrev_b32_e32 v99, 4, v105
	v_mad_u32_u24 v99, v99, s100, v82
	v_lshlrev_b32_e32 v148, 4, v110
	v_mad_u32_u24 v148, v148, s100, v153
	v_add_u32_e32 v151, 0x180000, v148
	v_lshrrev_b32_e32 v249, 3, v103
	v_and_b32_e32 v250, 7, v103
	v_lshlrev_b32_e32 v250, 4, v250
	v_add_u32_e32 v235, 0, v249
	v_add_u32_e32 v236, 8, v249
	v_add_u32_e32 v237, 16, v249
	v_add_u32_e32 v238, 24, v249
	v_add_u32_e32 v239, 0, v249
	v_lshlrev_b32_e32 v239, 2, v239
	v_add_u32_e32 v240, 8, v249
	v_lshlrev_b32_e32 v240, 2, v240
	v_add_u32_e32 v241, 16, v249
	v_lshlrev_b32_e32 v241, 2, v241
	v_add_u32_e32 v242, 24, v249
	v_lshlrev_b32_e32 v242, 2, v242
	v_add_u32_e32 v243, 0, v249
	v_lshlrev_b32_e32 v243, 4, v243
	v_add_u32_e32 v244, 8, v249
	v_lshlrev_b32_e32 v244, 4, v244
	v_add_u32_e32 v245, 16, v249
	v_lshlrev_b32_e32 v245, 4, v245
	v_add_u32_e32 v246, 24, v249
	v_lshlrev_b32_e32 v246, 4, v246
	v_mov_b32_e32 v252, v250
	v_mov_b32_e32 v100, v110
	v_add_u32_e32 v149, 16, v100
	v_lshlrev_b32_e32 v101, 2, v110
	v_add_u32_e32 v150, 64, v101
	v_lshlrev_b32_e32 v148, 4, v110
	v_add_u32_e32 v151, 256, v148
	s_mov_b32 s98, 0x4000
	s_mov_b32 s99, 0x3fff
	v_and_b32_e32 v247, 7, v249
	v_lshlrev_b32_e32 v247, 4, v247
	v_xor_b32_e32 v247, v247, v112
	v_xor_b32_e32 v111, 16, v247
	v_and_b32_e32 v153, 7, v105
	v_lshrrev_b32_e32 v248, 4, v105
	v_xor_b32_e32 v153, v153, v248
	v_or_b32_e32 v248, 0, v106
	v_xor_b32_e32 v248, v248, v153
	v_lshlrev_b32_e32 v248, 4, v248
	v_lshl_add_u32 v248, v105, 7, v248
	v_add_u32_e32 v248, s69, v248
	v_or_b32_e32 v249, 2, v106
	v_xor_b32_e32 v249, v249, v153
	v_lshlrev_b32_e32 v249, 4, v249
	v_lshl_add_u32 v249, v105, 7, v249
	v_add_u32_e32 v249, s69, v249
	v_or_b32_e32 v250, 4, v106
	v_xor_b32_e32 v250, v250, v153
	v_lshlrev_b32_e32 v250, 4, v250
	v_lshl_add_u32 v250, v105, 7, v250
	v_add_u32_e32 v250, s69, v250
	v_or_b32_e32 v251, 6, v106
	v_xor_b32_e32 v251, v251, v153
	v_lshlrev_b32_e32 v251, 4, v251
	v_lshl_add_u32 v251, v105, 7, v251
	v_add_u32_e32 v251, s69, v251
	v_lshlrev_b32_e32 v153, 1, v98
	v_mul_u32_u24_e32 v228, 17, v105
	v_sub_u32_e32 v228, v107, v228
	s_mul_i32 s90, s54, 153
; #define GAS __attribute__((address_space(1)))
; __device__ __forceinline__ void dil_unit(LAS unsigned char* lds, bf16_t* proj, int seq, int hd, int T0, int rho) {
;     ...
;     for (int ks = 0; ks < 4; ++ks) qr[ks] = *(const GAS bf16x8*)(base + (size_t)(P0 + 16 * r32) * NIN + PC_LQ + hd * 64 + 16 * ks + 8 * hi);
;     f32x16 o0 = {}, o1 = {}; float l = 0.f;
;     const bool bound = (T0 < 1024) || (T0 >= 15360);
	s_lshr_b32 s90, s90, 1
	s_add_i32 s90, s90, 34876
	v_lshl_add_u32 v228, v228, 2, s90
	v_mul_u32_u24_e32 v229, 5, v105
	v_sub_u32_e32 v229, v107, v229
	v_add_u32_e32 v229, v229, v106
	s_mul_i32 s90, s54, 30
	s_add_i32 s90, s90, 66156
	v_lshl_add_u32 v229, v229, 2, s90
	v_sub_u32_e32 v230, v107, v105
	s_add_i32 s90, s101, 6364
	v_lshl_add_u32 v230, v230, 2, s90
	v_add_u32_e32 v231, v109, v108
	v_mov_b64_e32 v[232:233], 0
	v_mov_b64_e32 v[0:1], 0
	v_mov_b64_e32 v[2:3], 0
	v_mov_b64_e32 v[4:5], 0
	v_mov_b64_e32 v[6:7], 0
	v_mov_b64_e32 v[8:9], 0
	v_mov_b64_e32 v[10:11], 0
	v_mov_b64_e32 v[12:13], 0
	v_mov_b64_e32 v[14:15], 0
	v_mov_b64_e32 v[16:17], 0
	v_mov_b64_e32 v[18:19], 0
	v_mov_b64_e32 v[20:21], 0
	v_mov_b64_e32 v[22:23], 0
	v_mov_b64_e32 v[24:25], 0
	v_mov_b64_e32 v[26:27], 0
	v_mov_b64_e32 v[28:29], 0
	v_mov_b64_e32 v[30:31], 0
	s_add_i32 s90, s67, -64
	v_add_u32_e32 v80, s90, v235
	v_add_u32_e32 v83, s90, v236
	v_add_u32_e32 v99, s90, v237
	v_add_u32_e32 v253, s90, v238
	v_add_u32_e32 v254, s90, v100
	v_add_u32_e32 v255, s90, v149
	v_med3_i32 v80, v80, 0, s99
	v_med3_i32 v83, v83, 0, s99
	v_med3_i32 v99, v99, 0, s99
	v_med3_i32 v253, v253, 0, s99
	v_med3_i32 v254, v254, 0, s99
	v_med3_i32 v255, v255, 0, s99
	v_mad_u32_u24 v80, v80, s100, v252
	v_mad_u32_u24 v83, v83, s100, v252
	v_mad_u32_u24 v99, v99, s100, v252
	v_mad_u32_u24 v253, v253, s100, v252
	v_mad_u32_u24 v254, v254, s100, v153
	v_mad_u32_u24 v255, v255, s100, v153
	global_load_dwordx4 v[116:119], v80, s[82:83]
	global_load_dwordx4 v[120:123], v83, s[82:83]
	global_load_dwordx4 v[124:127], v99, s[82:83]
	global_load_dwordx4 v[128:131], v253, s[82:83]
	global_load_dwordx4 v[132:135], v254, s[82:83] offset:768
	global_load_dwordx4 v[136:139], v255, s[82:83] offset:768
	global_load_dwordx4 v[140:143], v254, s[82:83] offset:832
	global_load_dwordx4 v[144:147], v255, s[82:83] offset:832
	s_add_i32 s90, s67, -32
	v_add_u32_e32 v80, s90, v235
	v_add_u32_e32 v83, s90, v236
	v_add_u32_e32 v99, s90, v237
	v_add_u32_e32 v253, s90, v238
	v_add_u32_e32 v254, s90, v100
	v_add_u32_e32 v255, s90, v149
	v_med3_i32 v80, v80, 0, s99
	v_med3_i32 v83, v83, 0, s99
	v_med3_i32 v99, v99, 0, s99
	v_med3_i32 v253, v253, 0, s99
	v_med3_i32 v254, v254, 0, s99
	v_med3_i32 v255, v255, 0, s99
	v_mad_u32_u24 v80, v80, s100, v252
	v_mad_u32_u24 v83, v83, s100, v252
	v_mad_u32_u24 v99, v99, s100, v252
	v_mad_u32_u24 v253, v253, s100, v252
	v_mad_u32_u24 v254, v254, s100, v153
	v_mad_u32_u24 v255, v255, s100, v153
	global_load_dwordx4 v[156:159], v80, s[82:83]
	global_load_dwordx4 v[160:163], v83, s[82:83]
	global_load_dwordx4 v[164:167], v99, s[82:83]
	global_load_dwordx4 v[168:171], v253, s[82:83]
	global_load_dwordx4 v[172:175], v254, s[82:83] offset:768
	global_load_dwordx4 v[176:179], v255, s[82:83] offset:768
	global_load_dwordx4 v[180:183], v254, s[82:83] offset:832
	global_load_dwordx4 v[184:187], v255, s[82:83] offset:832
	s_add_i32 s90, s67, 0
	v_add_u32_e32 v80, s90, v235
	v_add_u32_e32 v83, s90, v236
	v_add_u32_e32 v99, s90, v237
	v_add_u32_e32 v253, s90, v238
	v_add_u32_e32 v254, s90, v100
	v_add_u32_e32 v255, s90, v149
	v_med3_i32 v80, v80, 0, s99
	v_med3_i32 v83, v83, 0, s99
	v_med3_i32 v99, v99, 0, s99
	v_med3_i32 v253, v253, 0, s99
	v_med3_i32 v254, v254, 0, s99
	v_med3_i32 v255, v255, 0, s99
	v_mad_u32_u24 v80, v80, s100, v252
	v_mad_u32_u24 v83, v83, s100, v252
	v_mad_u32_u24 v99, v99, s100, v252
	v_mad_u32_u24 v253, v253, s100, v252
	v_mad_u32_u24 v254, v254, s100, v153
	v_mad_u32_u24 v255, v255, s100, v153
	global_load_dwordx4 v[188:191], v80, s[82:83]
	global_load_dwordx4 v[192:195], v83, s[82:83]
	global_load_dwordx4 v[196:199], v99, s[82:83]
	global_load_dwordx4 v[200:203], v253, s[82:83]
	global_load_dwordx4 v[204:207], v254, s[82:83] offset:768
	global_load_dwordx4 v[208:211], v255, s[82:83] offset:768
	global_load_dwordx4 v[212:215], v254, s[82:83] offset:832
	global_load_dwordx4 v[216:219], v255, s[82:83] offset:832
	s_waitcnt vmcnt(16)
	ds_write_b128 v247, v[116:119]
	ds_write_b128 v247, v[120:123] offset:1024
	ds_write_b128 v111, v[124:127] offset:2048
	ds_write_b128 v111, v[128:131] offset:3072
	ds_read_b128 v[116:119], v248
	ds_read_b128 v[120:123], v249
	ds_read_b128 v[124:127], v250
	ds_read_b128 v[128:131], v251
	ds_write_b128 v112, v[132:135]
	ds_write_b128 v112, v[136:139] offset:1024
	ds_write_b128 v112, v[140:143] offset:2048
	ds_write_b128 v112, v[144:147] offset:3072
	v_mov_b32_e32 v115, v228
	ds_read2_b32 v[32:33], v115 offset0:0 offset1:1
	ds_read2_b32 v[34:35], v115 offset0:2 offset1:3
	ds_read2_b32 v[36:37], v115 offset0:8 offset1:9
	ds_read2_b32 v[38:39], v115 offset0:10 offset1:11
	ds_read2_b32 v[40:41], v115 offset0:17 offset1:18
	ds_read2_b32 v[42:43], v115 offset0:19 offset1:20
	ds_read2_b32 v[44:45], v115 offset0:25 offset1:26
	ds_read2_b32 v[46:47], v115 offset0:27 offset1:28
	s_waitcnt lgkmcnt(0)
	v_mfma_f32_32x32x16_bf16 v[32:47], v[116:119], v[48:51], v[32:47]
	ds_read_b64_tr_b16 v[72:73], v231
	ds_read_b64_tr_b16 v[74:75], v231 offset:512
	ds_read_b64_tr_b16 v[76:77], v231 offset:2048
	ds_read_b64_tr_b16 v[78:79], v231 offset:2560
	ds_read_b64_tr_b16 v[220:221], v231 offset:1024
	ds_read_b64_tr_b16 v[222:223], v231 offset:1536
	ds_read_b64_tr_b16 v[224:225], v231 offset:3072
	ds_read_b64_tr_b16 v[226:227], v231 offset:3584
	s_waitcnt vmcnt(8)
	ds_write_b128 v247, v[156:159]
	ds_write_b128 v247, v[160:163] offset:1024
	ds_write_b128 v111, v[164:167] offset:2048
	ds_write_b128 v111, v[168:171] offset:3072
	ds_read_b128 v[156:159], v248
	ds_read_b128 v[160:163], v249
	ds_read_b128 v[164:167], v250
	ds_read_b128 v[168:171], v251
	ds_write_b128 v112, v[172:175]
	ds_write_b128 v112, v[176:179] offset:1024
	ds_write_b128 v112, v[180:183] offset:2048
	ds_write_b128 v112, v[184:187] offset:3072
	v_mfma_f32_32x32x16_bf16 v[32:47], v[120:123], v[52:55], v[32:47]
	v_mfma_f32_32x32x16_bf16 v[32:47], v[124:127], v[56:59], v[32:47]
	v_mfma_f32_32x32x16_bf16 v[32:47], v[128:131], v[60:63], v[32:47]
	s_nop 11
	v_exp_f32_e32 v32, v32
	v_exp_f32_e32 v33, v33
	v_exp_f32_e32 v34, v34
	v_exp_f32_e32 v35, v35
	v_exp_f32_e32 v36, v36
	v_exp_f32_e32 v37, v37
	v_exp_f32_e32 v38, v38
	v_exp_f32_e32 v39, v39
	v_exp_f32_e32 v40, v40
	v_exp_f32_e32 v41, v41
	v_exp_f32_e32 v42, v42
	v_exp_f32_e32 v43, v43
	v_exp_f32_e32 v44, v44
	v_exp_f32_e32 v45, v45
	v_exp_f32_e32 v46, v46
	v_exp_f32_e32 v47, v47
	s_add_i32 s90, s67, -64
	v_add_u32_e32 v84, s90, v107
	v_add_u32_e32 v85, 0, v84
	v_add_u32_e32 v86, 1, v84
	v_add_u32_e32 v87, 2, v84
	v_add_u32_e32 v88, 3, v84
	v_cmp_gt_u32_e64 s[30:31], s98, v85
	v_cmp_gt_u32_e64 s[36:37], s98, v86
	v_cmp_gt_u32_e64 s[78:79], s98, v87
	v_cmp_gt_u32_e64 s[50:51], s98, v88
	v_cndmask_b32_e64 v32, 0, v32, s[30:31]
	v_add_u32_e32 v85, 8, v84
	v_cmp_gt_u32_e64 s[30:31], s98, v85
	v_cndmask_b32_e64 v33, 0, v33, s[36:37]
	v_add_u32_e32 v86, 9, v84
	v_cmp_gt_u32_e64 s[36:37], s98, v86
	v_cndmask_b32_e64 v34, 0, v34, s[78:79]
	v_add_u32_e32 v87, 10, v84
	v_cmp_gt_u32_e64 s[78:79], s98, v87
	v_cndmask_b32_e64 v35, 0, v35, s[50:51]
	v_add_u32_e32 v88, 11, v84
	v_cmp_gt_u32_e64 s[50:51], s98, v88
	v_cndmask_b32_e64 v36, 0, v36, s[30:31]
	v_add_u32_e32 v85, 16, v84
	v_cmp_gt_u32_e64 s[30:31], s98, v85
	v_cndmask_b32_e64 v37, 0, v37, s[36:37]
	v_add_u32_e32 v86, 17, v84
	v_cmp_gt_u32_e64 s[36:37], s98, v86
	v_cndmask_b32_e64 v38, 0, v38, s[78:79]
	v_add_u32_e32 v87, 18, v84
	v_cmp_gt_u32_e64 s[78:79], s98, v87
	v_cndmask_b32_e64 v39, 0, v39, s[50:51]
	v_add_u32_e32 v88, 19, v84
	v_cmp_gt_u32_e64 s[50:51], s98, v88
	v_cndmask_b32_e64 v40, 0, v40, s[30:31]
	v_add_u32_e32 v85, 24, v84
	v_cmp_gt_u32_e64 s[30:31], s98, v85
	v_cndmask_b32_e64 v41, 0, v41, s[36:37]
	v_add_u32_e32 v86, 25, v84
	v_cmp_gt_u32_e64 s[36:37], s98, v86
	v_cndmask_b32_e64 v42, 0, v42, s[78:79]
	v_add_u32_e32 v87, 26, v84
	v_cmp_gt_u32_e64 s[78:79], s98, v87
	v_cndmask_b32_e64 v43, 0, v43, s[50:51]
	v_add_u32_e32 v88, 27, v84
	v_cmp_gt_u32_e64 s[50:51], s98, v88
	v_nop
	v_cndmask_b32_e64 v44, 0, v44, s[30:31]
	v_cndmask_b32_e64 v45, 0, v45, s[36:37]
	v_cndmask_b32_e64 v46, 0, v46, s[78:79]
	v_cndmask_b32_e64 v47, 0, v47, s[50:51]
	v_cvt_pk_bf16_f32 v64, v32, v33
	v_cvt_pk_bf16_f32 v65, v34, v35
	v_cvt_pk_bf16_f32 v66, v36, v37
	v_cvt_pk_bf16_f32 v67, v38, v39
	v_cvt_pk_bf16_f32 v68, v40, v41
	v_cvt_pk_bf16_f32 v69, v42, v43
	v_cvt_pk_bf16_f32 v70, v44, v45
	v_cvt_pk_bf16_f32 v71, v46, v47
	v_pk_add_f32 v[232:233], v[232:233], v[32:33]
	v_pk_add_f32 v[232:233], v[232:233], v[34:35]
	v_pk_add_f32 v[232:233], v[232:233], v[36:37]
	v_pk_add_f32 v[232:233], v[232:233], v[38:39]
	v_pk_add_f32 v[232:233], v[232:233], v[40:41]
	v_pk_add_f32 v[232:233], v[232:233], v[42:43]
	v_pk_add_f32 v[232:233], v[232:233], v[44:45]
	v_pk_add_f32 v[232:233], v[232:233], v[46:47]
	ds_read2_b32 v[32:33], v115 offset0:34 offset1:35
	ds_read2_b32 v[34:35], v115 offset0:36 offset1:37
	ds_read2_b32 v[36:37], v115 offset0:42 offset1:43
	ds_read2_b32 v[38:39], v115 offset0:44 offset1:45
	ds_read2_b32 v[40:41], v115 offset0:51 offset1:52
	ds_read2_b32 v[42:43], v115 offset0:53 offset1:54
	ds_read2_b32 v[44:45], v115 offset0:59 offset1:60
	ds_read2_b32 v[46:47], v115 offset0:61 offset1:62
	s_waitcnt lgkmcnt(15)
	v_mfma_f32_32x32x16_bf16 v[0:15], v[64:67], v[72:75], v[0:15]
	v_mfma_f32_32x32x16_bf16 v[16:31], v[64:67], v[76:79], v[16:31]
	v_mfma_f32_32x32x16_bf16 v[0:15], v[68:71], v[220:223], v[0:15]
	v_mfma_f32_32x32x16_bf16 v[16:31], v[68:71], v[224:227], v[16:31]
	s_add_i32 s90, s67, 32
	v_add_u32_e32 v80, s90, v235
	v_add_u32_e32 v83, s90, v236
	v_add_u32_e32 v99, s90, v237
	v_add_u32_e32 v253, s90, v238
	v_add_u32_e32 v254, s90, v100
	v_add_u32_e32 v255, s90, v149
	v_med3_i32 v80, v80, 0, s99
	v_med3_i32 v83, v83, 0, s99
	v_med3_i32 v99, v99, 0, s99
	v_med3_i32 v253, v253, 0, s99
	v_med3_i32 v254, v254, 0, s99
	v_med3_i32 v255, v255, 0, s99
	v_mad_u32_u24 v80, v80, s100, v252
	v_mad_u32_u24 v83, v83, s100, v252
	v_mad_u32_u24 v99, v99, s100, v252
	v_mad_u32_u24 v253, v253, s100, v252
	v_mad_u32_u24 v254, v254, s100, v153
	v_mad_u32_u24 v255, v255, s100, v153
	global_load_dwordx4 v[116:119], v80, s[82:83]
	global_load_dwordx4 v[120:123], v83, s[82:83]
	global_load_dwordx4 v[124:127], v99, s[82:83]
	global_load_dwordx4 v[128:131], v253, s[82:83]
	global_load_dwordx4 v[132:135], v254, s[82:83] offset:768
	global_load_dwordx4 v[136:139], v255, s[82:83] offset:768
	global_load_dwordx4 v[140:143], v254, s[82:83] offset:832
	global_load_dwordx4 v[144:147], v255, s[82:83] offset:832
	s_waitcnt lgkmcnt(0)
	v_mfma_f32_32x32x16_bf16 v[32:47], v[156:159], v[48:51], v[32:47]
	ds_read_b64_tr_b16 v[72:73], v231
	ds_read_b64_tr_b16 v[74:75], v231 offset:512
	ds_read_b64_tr_b16 v[76:77], v231 offset:2048
	ds_read_b64_tr_b16 v[78:79], v231 offset:2560
	ds_read_b64_tr_b16 v[220:221], v231 offset:1024
	ds_read_b64_tr_b16 v[222:223], v231 offset:1536
	ds_read_b64_tr_b16 v[224:225], v231 offset:3072
	ds_read_b64_tr_b16 v[226:227], v231 offset:3584
	s_waitcnt vmcnt(8)
	ds_write_b128 v247, v[188:191]
	ds_write_b128 v247, v[192:195] offset:1024
	ds_write_b128 v111, v[196:199] offset:2048
	ds_write_b128 v111, v[200:203] offset:3072
	ds_read_b128 v[188:191], v248
	ds_read_b128 v[192:195], v249
	ds_read_b128 v[196:199], v250
	ds_read_b128 v[200:203], v251
	ds_write_b128 v112, v[204:207]
	ds_write_b128 v112, v[208:211] offset:1024
	ds_write_b128 v112, v[212:215] offset:2048
	ds_write_b128 v112, v[216:219] offset:3072
	v_mfma_f32_32x32x16_bf16 v[32:47], v[160:163], v[52:55], v[32:47]
	v_mfma_f32_32x32x16_bf16 v[32:47], v[164:167], v[56:59], v[32:47]
	v_mfma_f32_32x32x16_bf16 v[32:47], v[168:171], v[60:63], v[32:47]
	s_nop 11
	v_exp_f32_e32 v32, v32
	v_exp_f32_e32 v33, v33
	v_exp_f32_e32 v34, v34
	v_exp_f32_e32 v35, v35
	v_exp_f32_e32 v36, v36
	v_exp_f32_e32 v37, v37
	v_exp_f32_e32 v38, v38
	v_exp_f32_e32 v39, v39
	v_exp_f32_e32 v40, v40
	v_exp_f32_e32 v41, v41
	v_exp_f32_e32 v42, v42
	v_exp_f32_e32 v43, v43
	v_exp_f32_e32 v44, v44
	v_exp_f32_e32 v45, v45
	v_exp_f32_e32 v46, v46
	v_exp_f32_e32 v47, v47
	s_add_i32 s90, s67, -32
	v_add_u32_e32 v84, s90, v107
	v_add_u32_e32 v85, 0, v84
	v_add_u32_e32 v86, 1, v84
	v_add_u32_e32 v87, 2, v84
	v_add_u32_e32 v88, 3, v84
	v_cmp_gt_u32_e64 s[30:31], s98, v85
	v_cmp_gt_u32_e64 s[36:37], s98, v86
	v_cmp_gt_u32_e64 s[78:79], s98, v87
	v_cmp_gt_u32_e64 s[50:51], s98, v88
	v_cndmask_b32_e64 v32, 0, v32, s[30:31]
	v_add_u32_e32 v85, 8, v84
	v_cmp_gt_u32_e64 s[30:31], s98, v85
	v_cndmask_b32_e64 v33, 0, v33, s[36:37]
	v_add_u32_e32 v86, 9, v84
	v_cmp_gt_u32_e64 s[36:37], s98, v86
	v_cndmask_b32_e64 v34, 0, v34, s[78:79]
	v_add_u32_e32 v87, 10, v84
	v_cmp_gt_u32_e64 s[78:79], s98, v87
	v_cndmask_b32_e64 v35, 0, v35, s[50:51]
	v_add_u32_e32 v88, 11, v84
	v_cmp_gt_u32_e64 s[50:51], s98, v88
	v_cndmask_b32_e64 v36, 0, v36, s[30:31]
	v_add_u32_e32 v85, 16, v84
	v_cmp_gt_u32_e64 s[30:31], s98, v85
	v_cndmask_b32_e64 v37, 0, v37, s[36:37]
	v_add_u32_e32 v86, 17, v84
	v_cmp_gt_u32_e64 s[36:37], s98, v86
	v_cndmask_b32_e64 v38, 0, v38, s[78:79]
	v_add_u32_e32 v87, 18, v84
	v_cmp_gt_u32_e64 s[78:79], s98, v87
	v_cndmask_b32_e64 v39, 0, v39, s[50:51]
	v_add_u32_e32 v88, 19, v84
	v_cmp_gt_u32_e64 s[50:51], s98, v88
	v_cndmask_b32_e64 v40, 0, v40, s[30:31]
	v_add_u32_e32 v85, 24, v84
	v_cmp_gt_u32_e64 s[30:31], s98, v85
	v_cndmask_b32_e64 v41, 0, v41, s[36:37]
	v_add_u32_e32 v86, 25, v84
	v_cmp_gt_u32_e64 s[36:37], s98, v86
	v_cndmask_b32_e64 v42, 0, v42, s[78:79]
	v_add_u32_e32 v87, 26, v84
	v_cmp_gt_u32_e64 s[78:79], s98, v87
	v_cndmask_b32_e64 v43, 0, v43, s[50:51]
	v_add_u32_e32 v88, 27, v84
	v_cmp_gt_u32_e64 s[50:51], s98, v88
	v_nop
	v_cndmask_b32_e64 v44, 0, v44, s[30:31]
	v_cndmask_b32_e64 v45, 0, v45, s[36:37]
	v_cndmask_b32_e64 v46, 0, v46, s[78:79]
	v_cndmask_b32_e64 v47, 0, v47, s[50:51]
	v_cvt_pk_bf16_f32 v64, v32, v33
	v_cvt_pk_bf16_f32 v65, v34, v35
	v_cvt_pk_bf16_f32 v66, v36, v37
	v_cvt_pk_bf16_f32 v67, v38, v39
	v_cvt_pk_bf16_f32 v68, v40, v41
	v_cvt_pk_bf16_f32 v69, v42, v43
	v_cvt_pk_bf16_f32 v70, v44, v45
	v_cvt_pk_bf16_f32 v71, v46, v47
	v_pk_add_f32 v[232:233], v[232:233], v[32:33]
	v_pk_add_f32 v[232:233], v[232:233], v[34:35]
	v_pk_add_f32 v[232:233], v[232:233], v[36:37]
	v_pk_add_f32 v[232:233], v[232:233], v[38:39]
	v_pk_add_f32 v[232:233], v[232:233], v[40:41]
	v_pk_add_f32 v[232:233], v[232:233], v[42:43]
	v_pk_add_f32 v[232:233], v[232:233], v[44:45]
	v_pk_add_f32 v[232:233], v[232:233], v[46:47]
	ds_read2_b32 v[32:33], v115 offset0:68 offset1:69
	ds_read2_b32 v[34:35], v115 offset0:70 offset1:71
	ds_read2_b32 v[36:37], v115 offset0:76 offset1:77
	ds_read2_b32 v[38:39], v115 offset0:78 offset1:79
	ds_read2_b32 v[40:41], v115 offset0:85 offset1:86
	ds_read2_b32 v[42:43], v115 offset0:87 offset1:88
	ds_read2_b32 v[44:45], v115 offset0:93 offset1:94
	ds_read2_b32 v[46:47], v115 offset0:95 offset1:96
	s_waitcnt lgkmcnt(15)
	v_mfma_f32_32x32x16_bf16 v[0:15], v[64:67], v[72:75], v[0:15]
	v_mfma_f32_32x32x16_bf16 v[16:31], v[64:67], v[76:79], v[16:31]
	v_mfma_f32_32x32x16_bf16 v[0:15], v[68:71], v[220:223], v[0:15]
	v_mfma_f32_32x32x16_bf16 v[16:31], v[68:71], v[224:227], v[16:31]
	s_add_i32 s90, s67, 64
	v_add_u32_e32 v80, s90, v235
	v_add_u32_e32 v83, s90, v236
	v_add_u32_e32 v99, s90, v237
	v_add_u32_e32 v253, s90, v238
	v_add_u32_e32 v254, s90, v100
	v_add_u32_e32 v255, s90, v149
	v_med3_i32 v80, v80, 0, s99
	v_med3_i32 v83, v83, 0, s99
	v_med3_i32 v99, v99, 0, s99
	v_med3_i32 v253, v253, 0, s99
	v_med3_i32 v254, v254, 0, s99
	v_med3_i32 v255, v255, 0, s99
	v_mad_u32_u24 v80, v80, s100, v252
	v_mad_u32_u24 v83, v83, s100, v252
	v_mad_u32_u24 v99, v99, s100, v252
	v_mad_u32_u24 v253, v253, s100, v252
	v_mad_u32_u24 v254, v254, s100, v153
	v_mad_u32_u24 v255, v255, s100, v153
	global_load_dwordx4 v[156:159], v80, s[82:83]
	global_load_dwordx4 v[160:163], v83, s[82:83]
	global_load_dwordx4 v[164:167], v99, s[82:83]
	global_load_dwordx4 v[168:171], v253, s[82:83]
	global_load_dwordx4 v[172:175], v254, s[82:83] offset:768
	global_load_dwordx4 v[176:179], v255, s[82:83] offset:768
	global_load_dwordx4 v[180:183], v254, s[82:83] offset:832
	global_load_dwordx4 v[184:187], v255, s[82:83] offset:832
	s_waitcnt lgkmcnt(0)
	v_mfma_f32_32x32x16_bf16 v[32:47], v[188:191], v[48:51], v[32:47]
	ds_read_b64_tr_b16 v[72:73], v231
	ds_read_b64_tr_b16 v[74:75], v231 offset:512
	ds_read_b64_tr_b16 v[76:77], v231 offset:2048
	ds_read_b64_tr_b16 v[78:79], v231 offset:2560
	ds_read_b64_tr_b16 v[220:221], v231 offset:1024
	ds_read_b64_tr_b16 v[222:223], v231 offset:1536
	ds_read_b64_tr_b16 v[224:225], v231 offset:3072
	ds_read_b64_tr_b16 v[226:227], v231 offset:3584
	s_waitcnt vmcnt(8)
	ds_write_b128 v247, v[116:119]
	ds_write_b128 v247, v[120:123] offset:1024
	ds_write_b128 v111, v[124:127] offset:2048
	ds_write_b128 v111, v[128:131] offset:3072
	ds_read_b128 v[116:119], v248
	ds_read_b128 v[120:123], v249
	ds_read_b128 v[124:127], v250
	ds_read_b128 v[128:131], v251
	ds_write_b128 v112, v[132:135]
	ds_write_b128 v112, v[136:139] offset:1024
	ds_write_b128 v112, v[140:143] offset:2048
	ds_write_b128 v112, v[144:147] offset:3072
	v_mfma_f32_32x32x16_bf16 v[32:47], v[192:195], v[52:55], v[32:47]
	v_mfma_f32_32x32x16_bf16 v[32:47], v[196:199], v[56:59], v[32:47]
	v_mfma_f32_32x32x16_bf16 v[32:47], v[200:203], v[60:63], v[32:47]
	s_nop 11
	v_exp_f32_e32 v32, v32
	v_exp_f32_e32 v33, v33
	v_exp_f32_e32 v34, v34
	v_exp_f32_e32 v35, v35
	v_exp_f32_e32 v36, v36
	v_exp_f32_e32 v37, v37
	v_exp_f32_e32 v38, v38
	v_exp_f32_e32 v39, v39
	v_exp_f32_e32 v40, v40
	v_exp_f32_e32 v41, v41
	v_exp_f32_e32 v42, v42
	v_exp_f32_e32 v43, v43
	v_exp_f32_e32 v44, v44
	v_exp_f32_e32 v45, v45
	v_exp_f32_e32 v46, v46
	v_exp_f32_e32 v47, v47
	s_add_i32 s90, s67, 0
	v_add_u32_e32 v84, s90, v107
	v_add_u32_e32 v85, 0, v84
	v_add_u32_e32 v86, 1, v84
	v_add_u32_e32 v87, 2, v84
	v_add_u32_e32 v88, 3, v84
	v_cmp_gt_u32_e64 s[30:31], s98, v85
	v_cmp_gt_u32_e64 s[36:37], s98, v86
	v_cmp_gt_u32_e64 s[78:79], s98, v87
	v_cmp_gt_u32_e64 s[50:51], s98, v88
	v_cndmask_b32_e64 v32, 0, v32, s[30:31]
	v_add_u32_e32 v85, 8, v84
	v_cmp_gt_u32_e64 s[30:31], s98, v85
	v_cndmask_b32_e64 v33, 0, v33, s[36:37]
	v_add_u32_e32 v86, 9, v84
	v_cmp_gt_u32_e64 s[36:37], s98, v86
	v_cndmask_b32_e64 v34, 0, v34, s[78:79]
	v_add_u32_e32 v87, 10, v84
	v_cmp_gt_u32_e64 s[78:79], s98, v87
	v_cndmask_b32_e64 v35, 0, v35, s[50:51]
	v_add_u32_e32 v88, 11, v84
	v_cmp_gt_u32_e64 s[50:51], s98, v88
	v_cndmask_b32_e64 v36, 0, v36, s[30:31]
	v_add_u32_e32 v85, 16, v84
	v_cmp_gt_u32_e64 s[30:31], s98, v85
	v_cndmask_b32_e64 v37, 0, v37, s[36:37]
	v_add_u32_e32 v86, 17, v84
	v_cmp_gt_u32_e64 s[36:37], s98, v86
	v_cndmask_b32_e64 v38, 0, v38, s[78:79]
	v_add_u32_e32 v87, 18, v84
	v_cmp_gt_u32_e64 s[78:79], s98, v87
	v_cndmask_b32_e64 v39, 0, v39, s[50:51]
	v_add_u32_e32 v88, 19, v84
	v_cmp_gt_u32_e64 s[50:51], s98, v88
	v_cndmask_b32_e64 v40, 0, v40, s[30:31]
	v_add_u32_e32 v85, 24, v84
	v_cmp_gt_u32_e64 s[30:31], s98, v85
	v_cndmask_b32_e64 v41, 0, v41, s[36:37]
	v_add_u32_e32 v86, 25, v84
	v_cmp_gt_u32_e64 s[36:37], s98, v86
	v_cndmask_b32_e64 v42, 0, v42, s[78:79]
	v_add_u32_e32 v87, 26, v84
	v_cmp_gt_u32_e64 s[78:79], s98, v87
	v_cndmask_b32_e64 v43, 0, v43, s[50:51]
	v_add_u32_e32 v88, 27, v84
	v_cmp_gt_u32_e64 s[50:51], s98, v88
	v_nop
	v_cndmask_b32_e64 v44, 0, v44, s[30:31]
	v_cndmask_b32_e64 v45, 0, v45, s[36:37]
	v_cndmask_b32_e64 v46, 0, v46, s[78:79]
	v_cndmask_b32_e64 v47, 0, v47, s[50:51]
	v_cvt_pk_bf16_f32 v64, v32, v33
	v_cvt_pk_bf16_f32 v65, v34, v35
	v_cvt_pk_bf16_f32 v66, v36, v37
	v_cvt_pk_bf16_f32 v67, v38, v39
	v_cvt_pk_bf16_f32 v68, v40, v41
	v_cvt_pk_bf16_f32 v69, v42, v43
	v_cvt_pk_bf16_f32 v70, v44, v45
	v_cvt_pk_bf16_f32 v71, v46, v47
	v_pk_add_f32 v[232:233], v[232:233], v[32:33]
	v_pk_add_f32 v[232:233], v[232:233], v[34:35]
	v_pk_add_f32 v[232:233], v[232:233], v[36:37]
	v_pk_add_f32 v[232:233], v[232:233], v[38:39]
	v_pk_add_f32 v[232:233], v[232:233], v[40:41]
	v_pk_add_f32 v[232:233], v[232:233], v[42:43]
	v_pk_add_f32 v[232:233], v[232:233], v[44:45]
	v_pk_add_f32 v[232:233], v[232:233], v[46:47]
	ds_read2_b32 v[32:33], v115 offset0:102 offset1:103
	ds_read2_b32 v[34:35], v115 offset0:104 offset1:105
	ds_read2_b32 v[36:37], v115 offset0:110 offset1:111
	ds_read2_b32 v[38:39], v115 offset0:112 offset1:113
	ds_read2_b32 v[40:41], v115 offset0:119 offset1:120
	ds_read2_b32 v[42:43], v115 offset0:121 offset1:122
	ds_read2_b32 v[44:45], v115 offset0:127 offset1:128
	ds_read2_b32 v[46:47], v115 offset0:129 offset1:130
	s_waitcnt lgkmcnt(15)
	v_mfma_f32_32x32x16_bf16 v[0:15], v[64:67], v[72:75], v[0:15]
	v_mfma_f32_32x32x16_bf16 v[16:31], v[64:67], v[76:79], v[16:31]
	v_mfma_f32_32x32x16_bf16 v[0:15], v[68:71], v[220:223], v[0:15]
	v_mfma_f32_32x32x16_bf16 v[16:31], v[68:71], v[224:227], v[16:31]
	s_add_i32 s90, s67, 96
	v_add_u32_e32 v80, s90, v235
	v_add_u32_e32 v83, s90, v236
	v_add_u32_e32 v99, s90, v237
	v_add_u32_e32 v253, s90, v238
	v_add_u32_e32 v254, s90, v100
	v_add_u32_e32 v255, s90, v149
	v_med3_i32 v80, v80, 0, s99
	v_med3_i32 v83, v83, 0, s99
	v_med3_i32 v99, v99, 0, s99
	v_med3_i32 v253, v253, 0, s99
	v_med3_i32 v254, v254, 0, s99
	v_med3_i32 v255, v255, 0, s99
	v_mad_u32_u24 v80, v80, s100, v252
	v_mad_u32_u24 v83, v83, s100, v252
	v_mad_u32_u24 v99, v99, s100, v252
	v_mad_u32_u24 v253, v253, s100, v252
	v_mad_u32_u24 v254, v254, s100, v153
	v_mad_u32_u24 v255, v255, s100, v153
	global_load_dwordx4 v[188:191], v80, s[82:83]
	global_load_dwordx4 v[192:195], v83, s[82:83]
	global_load_dwordx4 v[196:199], v99, s[82:83]
	global_load_dwordx4 v[200:203], v253, s[82:83]
	global_load_dwordx4 v[204:207], v254, s[82:83] offset:768
	global_load_dwordx4 v[208:211], v255, s[82:83] offset:768
	global_load_dwordx4 v[212:215], v254, s[82:83] offset:832
	global_load_dwordx4 v[216:219], v255, s[82:83] offset:832
	s_waitcnt lgkmcnt(0)
	v_mfma_f32_32x32x16_bf16 v[32:47], v[116:119], v[48:51], v[32:47]
	ds_read_b64_tr_b16 v[72:73], v231
	ds_read_b64_tr_b16 v[74:75], v231 offset:512
	ds_read_b64_tr_b16 v[76:77], v231 offset:2048
	ds_read_b64_tr_b16 v[78:79], v231 offset:2560
	ds_read_b64_tr_b16 v[220:221], v231 offset:1024
	ds_read_b64_tr_b16 v[222:223], v231 offset:1536
	ds_read_b64_tr_b16 v[224:225], v231 offset:3072
	ds_read_b64_tr_b16 v[226:227], v231 offset:3584
	s_waitcnt vmcnt(8)
	ds_write_b128 v247, v[156:159]
	ds_write_b128 v247, v[160:163] offset:1024
	ds_write_b128 v111, v[164:167] offset:2048
	ds_write_b128 v111, v[168:171] offset:3072
	ds_read_b128 v[156:159], v248
	ds_read_b128 v[160:163], v249
	ds_read_b128 v[164:167], v250
	ds_read_b128 v[168:171], v251
	ds_write_b128 v112, v[172:175]
	ds_write_b128 v112, v[176:179] offset:1024
	ds_write_b128 v112, v[180:183] offset:2048
	ds_write_b128 v112, v[184:187] offset:3072
	v_mfma_f32_32x32x16_bf16 v[32:47], v[120:123], v[52:55], v[32:47]
	v_mfma_f32_32x32x16_bf16 v[32:47], v[124:127], v[56:59], v[32:47]
	v_mfma_f32_32x32x16_bf16 v[32:47], v[128:131], v[60:63], v[32:47]
	s_nop 11
	v_exp_f32_e32 v32, v32
	v_exp_f32_e32 v33, v33
	v_exp_f32_e32 v34, v34
	v_exp_f32_e32 v35, v35
	v_exp_f32_e32 v36, v36
	v_exp_f32_e32 v37, v37
	v_exp_f32_e32 v38, v38
	v_exp_f32_e32 v39, v39
	v_exp_f32_e32 v40, v40
	v_exp_f32_e32 v41, v41
	v_exp_f32_e32 v42, v42
	v_exp_f32_e32 v43, v43
	v_exp_f32_e32 v44, v44
	v_exp_f32_e32 v45, v45
	v_exp_f32_e32 v46, v46
	v_exp_f32_e32 v47, v47
	s_add_i32 s90, s67, 32
	v_add_u32_e32 v84, s90, v107
	v_add_u32_e32 v85, 0, v84
	v_add_u32_e32 v86, 1, v84
	v_add_u32_e32 v87, 2, v84
	v_add_u32_e32 v88, 3, v84
	v_cmp_gt_u32_e64 s[30:31], s98, v85
	v_cmp_gt_u32_e64 s[36:37], s98, v86
	v_cmp_gt_u32_e64 s[78:79], s98, v87
	v_cmp_gt_u32_e64 s[50:51], s98, v88
	v_cndmask_b32_e64 v32, 0, v32, s[30:31]
	v_add_u32_e32 v85, 8, v84
	v_cmp_gt_u32_e64 s[30:31], s98, v85
	v_cndmask_b32_e64 v33, 0, v33, s[36:37]
	v_add_u32_e32 v86, 9, v84
	v_cmp_gt_u32_e64 s[36:37], s98, v86
	v_cndmask_b32_e64 v34, 0, v34, s[78:79]
	v_add_u32_e32 v87, 10, v84
	v_cmp_gt_u32_e64 s[78:79], s98, v87
	v_cndmask_b32_e64 v35, 0, v35, s[50:51]
	v_add_u32_e32 v88, 11, v84
	v_cmp_gt_u32_e64 s[50:51], s98, v88
	v_cndmask_b32_e64 v36, 0, v36, s[30:31]
	v_add_u32_e32 v85, 16, v84
	v_cmp_gt_u32_e64 s[30:31], s98, v85
	v_cndmask_b32_e64 v37, 0, v37, s[36:37]
	v_add_u32_e32 v86, 17, v84
	v_cmp_gt_u32_e64 s[36:37], s98, v86
	v_cndmask_b32_e64 v38, 0, v38, s[78:79]
	v_add_u32_e32 v87, 18, v84
	v_cmp_gt_u32_e64 s[78:79], s98, v87
	v_cndmask_b32_e64 v39, 0, v39, s[50:51]
	v_add_u32_e32 v88, 19, v84
	v_cmp_gt_u32_e64 s[50:51], s98, v88
	v_cndmask_b32_e64 v40, 0, v40, s[30:31]
	v_add_u32_e32 v85, 24, v84
	v_cmp_gt_u32_e64 s[30:31], s98, v85
	v_cndmask_b32_e64 v41, 0, v41, s[36:37]
	v_add_u32_e32 v86, 25, v84
	v_cmp_gt_u32_e64 s[36:37], s98, v86
	v_cndmask_b32_e64 v42, 0, v42, s[78:79]
	v_add_u32_e32 v87, 26, v84
	v_cmp_gt_u32_e64 s[78:79], s98, v87
	v_cndmask_b32_e64 v43, 0, v43, s[50:51]
	v_add_u32_e32 v88, 27, v84
	v_cmp_gt_u32_e64 s[50:51], s98, v88
	v_nop
	v_cndmask_b32_e64 v44, 0, v44, s[30:31]
	v_cndmask_b32_e64 v45, 0, v45, s[36:37]
	v_cndmask_b32_e64 v46, 0, v46, s[78:79]
	v_cndmask_b32_e64 v47, 0, v47, s[50:51]
	v_cvt_pk_bf16_f32 v64, v32, v33
	v_cvt_pk_bf16_f32 v65, v34, v35
	v_cvt_pk_bf16_f32 v66, v36, v37
	v_cvt_pk_bf16_f32 v67, v38, v39
	v_cvt_pk_bf16_f32 v68, v40, v41
	v_cvt_pk_bf16_f32 v69, v42, v43
	v_cvt_pk_bf16_f32 v70, v44, v45
	v_cvt_pk_bf16_f32 v71, v46, v47
	v_pk_add_f32 v[232:233], v[232:233], v[32:33]
	v_pk_add_f32 v[232:233], v[232:233], v[34:35]
	v_pk_add_f32 v[232:233], v[232:233], v[36:37]
	v_pk_add_f32 v[232:233], v[232:233], v[38:39]
	v_pk_add_f32 v[232:233], v[232:233], v[40:41]
	v_pk_add_f32 v[232:233], v[232:233], v[42:43]
	v_pk_add_f32 v[232:233], v[232:233], v[44:45]
	v_pk_add_f32 v[232:233], v[232:233], v[46:47]
	ds_read2_b32 v[32:33], v115 offset0:136 offset1:137
	ds_read2_b32 v[34:35], v115 offset0:138 offset1:139
	ds_read2_b32 v[36:37], v115 offset0:144 offset1:145
	ds_read2_b32 v[38:39], v115 offset0:146 offset1:147
	ds_read2_b32 v[40:41], v115 offset0:153 offset1:154
	ds_read2_b32 v[42:43], v115 offset0:155 offset1:156
	ds_read2_b32 v[44:45], v115 offset0:161 offset1:162
	ds_read2_b32 v[46:47], v115 offset0:163 offset1:164
	s_waitcnt lgkmcnt(15)
	v_mfma_f32_32x32x16_bf16 v[0:15], v[64:67], v[72:75], v[0:15]
	v_mfma_f32_32x32x16_bf16 v[16:31], v[64:67], v[76:79], v[16:31]
	v_mfma_f32_32x32x16_bf16 v[0:15], v[68:71], v[220:223], v[0:15]
	v_mfma_f32_32x32x16_bf16 v[16:31], v[68:71], v[224:227], v[16:31]
	s_add_i32 s90, s67, 128
	v_add_u32_e32 v80, s90, v235
	v_add_u32_e32 v83, s90, v236
	v_add_u32_e32 v99, s90, v237
	v_add_u32_e32 v253, s90, v238
	v_add_u32_e32 v254, s90, v100
	v_add_u32_e32 v255, s90, v149
	v_med3_i32 v80, v80, 0, s99
	v_med3_i32 v83, v83, 0, s99
	v_med3_i32 v99, v99, 0, s99
	v_med3_i32 v253, v253, 0, s99
	v_med3_i32 v254, v254, 0, s99
	v_med3_i32 v255, v255, 0, s99
	v_mad_u32_u24 v80, v80, s100, v252
	v_mad_u32_u24 v83, v83, s100, v252
	v_mad_u32_u24 v99, v99, s100, v252
	v_mad_u32_u24 v253, v253, s100, v252
	v_mad_u32_u24 v254, v254, s100, v153
	v_mad_u32_u24 v255, v255, s100, v153
	global_load_dwordx4 v[116:119], v80, s[82:83]
	global_load_dwordx4 v[120:123], v83, s[82:83]
	global_load_dwordx4 v[124:127], v99, s[82:83]
	global_load_dwordx4 v[128:131], v253, s[82:83]
	global_load_dwordx4 v[132:135], v254, s[82:83] offset:768
	global_load_dwordx4 v[136:139], v255, s[82:83] offset:768
	global_load_dwordx4 v[140:143], v254, s[82:83] offset:832
	global_load_dwordx4 v[144:147], v255, s[82:83] offset:832
	s_waitcnt lgkmcnt(0)
	v_mfma_f32_32x32x16_bf16 v[32:47], v[156:159], v[48:51], v[32:47]
	ds_read_b64_tr_b16 v[72:73], v231
	ds_read_b64_tr_b16 v[74:75], v231 offset:512
	ds_read_b64_tr_b16 v[76:77], v231 offset:2048
	ds_read_b64_tr_b16 v[78:79], v231 offset:2560
	ds_read_b64_tr_b16 v[220:221], v231 offset:1024
	ds_read_b64_tr_b16 v[222:223], v231 offset:1536
	ds_read_b64_tr_b16 v[224:225], v231 offset:3072
	ds_read_b64_tr_b16 v[226:227], v231 offset:3584
	s_waitcnt vmcnt(8)
	ds_write_b128 v247, v[188:191]
	ds_write_b128 v247, v[192:195] offset:1024
	ds_write_b128 v111, v[196:199] offset:2048
	ds_write_b128 v111, v[200:203] offset:3072
	ds_read_b128 v[188:191], v248
	ds_read_b128 v[192:195], v249
	ds_read_b128 v[196:199], v250
	ds_read_b128 v[200:203], v251
	ds_write_b128 v112, v[204:207]
	ds_write_b128 v112, v[208:211] offset:1024
	ds_write_b128 v112, v[212:215] offset:2048
	ds_write_b128 v112, v[216:219] offset:3072
	v_mfma_f32_32x32x16_bf16 v[32:47], v[160:163], v[52:55], v[32:47]
	v_mfma_f32_32x32x16_bf16 v[32:47], v[164:167], v[56:59], v[32:47]
	v_mfma_f32_32x32x16_bf16 v[32:47], v[168:171], v[60:63], v[32:47]
	s_nop 11
	v_exp_f32_e32 v32, v32
	v_exp_f32_e32 v33, v33
	v_exp_f32_e32 v34, v34
	v_exp_f32_e32 v35, v35
	v_exp_f32_e32 v36, v36
	v_exp_f32_e32 v37, v37
	v_exp_f32_e32 v38, v38
	v_exp_f32_e32 v39, v39
	v_exp_f32_e32 v40, v40
	v_exp_f32_e32 v41, v41
	v_exp_f32_e32 v42, v42
	v_exp_f32_e32 v43, v43
	v_exp_f32_e32 v44, v44
	v_exp_f32_e32 v45, v45
	v_exp_f32_e32 v46, v46
	v_exp_f32_e32 v47, v47
	s_add_i32 s90, s67, 64
	v_add_u32_e32 v84, s90, v107
	v_add_u32_e32 v85, 0, v84
	v_add_u32_e32 v86, 1, v84
	v_add_u32_e32 v87, 2, v84
	v_add_u32_e32 v88, 3, v84
	v_cmp_gt_u32_e64 s[30:31], s98, v85
	v_cmp_gt_u32_e64 s[36:37], s98, v86
	v_cmp_gt_u32_e64 s[78:79], s98, v87
	v_cmp_gt_u32_e64 s[50:51], s98, v88
	v_cndmask_b32_e64 v32, 0, v32, s[30:31]
	v_add_u32_e32 v85, 8, v84
	v_cmp_gt_u32_e64 s[30:31], s98, v85
	v_cndmask_b32_e64 v33, 0, v33, s[36:37]
	v_add_u32_e32 v86, 9, v84
	v_cmp_gt_u32_e64 s[36:37], s98, v86
	v_cndmask_b32_e64 v34, 0, v34, s[78:79]
	v_add_u32_e32 v87, 10, v84
	v_cmp_gt_u32_e64 s[78:79], s98, v87
	v_cndmask_b32_e64 v35, 0, v35, s[50:51]
	v_add_u32_e32 v88, 11, v84
	v_cmp_gt_u32_e64 s[50:51], s98, v88
	v_cndmask_b32_e64 v36, 0, v36, s[30:31]
	v_add_u32_e32 v85, 16, v84
	v_cmp_gt_u32_e64 s[30:31], s98, v85
	v_cndmask_b32_e64 v37, 0, v37, s[36:37]
	v_add_u32_e32 v86, 17, v84
	v_cmp_gt_u32_e64 s[36:37], s98, v86
	v_cndmask_b32_e64 v38, 0, v38, s[78:79]
	v_add_u32_e32 v87, 18, v84
	v_cmp_gt_u32_e64 s[78:79], s98, v87
	v_cndmask_b32_e64 v39, 0, v39, s[50:51]
	v_add_u32_e32 v88, 19, v84
	v_cmp_gt_u32_e64 s[50:51], s98, v88
	v_cndmask_b32_e64 v40, 0, v40, s[30:31]
	v_add_u32_e32 v85, 24, v84
	v_cmp_gt_u32_e64 s[30:31], s98, v85
	v_cndmask_b32_e64 v41, 0, v41, s[36:37]
	v_add_u32_e32 v86, 25, v84
	v_cmp_gt_u32_e64 s[36:37], s98, v86
	v_cndmask_b32_e64 v42, 0, v42, s[78:79]
	v_add_u32_e32 v87, 26, v84
	v_cmp_gt_u32_e64 s[78:79], s98, v87
	v_cndmask_b32_e64 v43, 0, v43, s[50:51]
	v_add_u32_e32 v88, 27, v84
	v_cmp_gt_u32_e64 s[50:51], s98, v88
	v_nop
	v_cndmask_b32_e64 v44, 0, v44, s[30:31]
	v_cndmask_b32_e64 v45, 0, v45, s[36:37]
	v_cndmask_b32_e64 v46, 0, v46, s[78:79]
	v_cndmask_b32_e64 v47, 0, v47, s[50:51]
	v_cvt_pk_bf16_f32 v64, v32, v33
	v_cvt_pk_bf16_f32 v65, v34, v35
	v_cvt_pk_bf16_f32 v66, v36, v37
	v_cvt_pk_bf16_f32 v67, v38, v39
	v_cvt_pk_bf16_f32 v68, v40, v41
	v_cvt_pk_bf16_f32 v69, v42, v43
	v_cvt_pk_bf16_f32 v70, v44, v45
	v_cvt_pk_bf16_f32 v71, v46, v47
	v_pk_add_f32 v[232:233], v[232:233], v[32:33]
	v_pk_add_f32 v[232:233], v[232:233], v[34:35]
	v_pk_add_f32 v[232:233], v[232:233], v[36:37]
	v_pk_add_f32 v[232:233], v[232:233], v[38:39]
	v_pk_add_f32 v[232:233], v[232:233], v[40:41]
	v_pk_add_f32 v[232:233], v[232:233], v[42:43]
	v_pk_add_f32 v[232:233], v[232:233], v[44:45]
	v_pk_add_f32 v[232:233], v[232:233], v[46:47]
	ds_read2_b32 v[32:33], v115 offset0:170 offset1:171
	ds_read2_b32 v[34:35], v115 offset0:172 offset1:173
	ds_read2_b32 v[36:37], v115 offset0:178 offset1:179
	ds_read2_b32 v[38:39], v115 offset0:180 offset1:181
	ds_read2_b32 v[40:41], v115 offset0:187 offset1:188
	ds_read2_b32 v[42:43], v115 offset0:189 offset1:190
	ds_read2_b32 v[44:45], v115 offset0:195 offset1:196
	ds_read2_b32 v[46:47], v115 offset0:197 offset1:198
	s_waitcnt lgkmcnt(15)
	v_mfma_f32_32x32x16_bf16 v[0:15], v[64:67], v[72:75], v[0:15]
	v_mfma_f32_32x32x16_bf16 v[16:31], v[64:67], v[76:79], v[16:31]
	v_mfma_f32_32x32x16_bf16 v[0:15], v[68:71], v[220:223], v[0:15]
	v_mfma_f32_32x32x16_bf16 v[16:31], v[68:71], v[224:227], v[16:31]
	s_add_i32 s90, s67, 160
	v_add_u32_e32 v80, s90, v235
	v_add_u32_e32 v83, s90, v236
	v_add_u32_e32 v99, s90, v237
	v_add_u32_e32 v253, s90, v238
	v_add_u32_e32 v254, s90, v100
	v_add_u32_e32 v255, s90, v149
	v_med3_i32 v80, v80, 0, s99
	v_med3_i32 v83, v83, 0, s99
	v_med3_i32 v99, v99, 0, s99
	v_med3_i32 v253, v253, 0, s99
	v_med3_i32 v254, v254, 0, s99
	v_med3_i32 v255, v255, 0, s99
	v_mad_u32_u24 v80, v80, s100, v252
	v_mad_u32_u24 v83, v83, s100, v252
	v_mad_u32_u24 v99, v99, s100, v252
	v_mad_u32_u24 v253, v253, s100, v252
	v_mad_u32_u24 v254, v254, s100, v153
	v_mad_u32_u24 v255, v255, s100, v153
	global_load_dwordx4 v[156:159], v80, s[82:83]
	global_load_dwordx4 v[160:163], v83, s[82:83]
	global_load_dwordx4 v[164:167], v99, s[82:83]
	global_load_dwordx4 v[168:171], v253, s[82:83]
	global_load_dwordx4 v[172:175], v254, s[82:83] offset:768
	global_load_dwordx4 v[176:179], v255, s[82:83] offset:768
	global_load_dwordx4 v[180:183], v254, s[82:83] offset:832
	global_load_dwordx4 v[184:187], v255, s[82:83] offset:832
	s_waitcnt lgkmcnt(0)
	v_mfma_f32_32x32x16_bf16 v[32:47], v[188:191], v[48:51], v[32:47]
	ds_read_b64_tr_b16 v[72:73], v231
	ds_read_b64_tr_b16 v[74:75], v231 offset:512
	ds_read_b64_tr_b16 v[76:77], v231 offset:2048
	ds_read_b64_tr_b16 v[78:79], v231 offset:2560
	ds_read_b64_tr_b16 v[220:221], v231 offset:1024
	ds_read_b64_tr_b16 v[222:223], v231 offset:1536
	ds_read_b64_tr_b16 v[224:225], v231 offset:3072
	ds_read_b64_tr_b16 v[226:227], v231 offset:3584
	s_waitcnt vmcnt(8)
	ds_write_b128 v247, v[116:119]
	ds_write_b128 v247, v[120:123] offset:1024
	ds_write_b128 v111, v[124:127] offset:2048
	ds_write_b128 v111, v[128:131] offset:3072
	ds_read_b128 v[116:119], v248
	ds_read_b128 v[120:123], v249
	ds_read_b128 v[124:127], v250
	ds_read_b128 v[128:131], v251
	ds_write_b128 v112, v[132:135]
	ds_write_b128 v112, v[136:139] offset:1024
	ds_write_b128 v112, v[140:143] offset:2048
	ds_write_b128 v112, v[144:147] offset:3072
	v_mfma_f32_32x32x16_bf16 v[32:47], v[192:195], v[52:55], v[32:47]
	v_mfma_f32_32x32x16_bf16 v[32:47], v[196:199], v[56:59], v[32:47]
	v_mfma_f32_32x32x16_bf16 v[32:47], v[200:203], v[60:63], v[32:47]
	s_nop 11
	v_exp_f32_e32 v32, v32
	v_exp_f32_e32 v33, v33
	v_exp_f32_e32 v34, v34
	v_exp_f32_e32 v35, v35
	v_exp_f32_e32 v36, v36
	v_exp_f32_e32 v37, v37
	v_exp_f32_e32 v38, v38
	v_exp_f32_e32 v39, v39
	v_exp_f32_e32 v40, v40
	v_exp_f32_e32 v41, v41
	v_exp_f32_e32 v42, v42
	v_exp_f32_e32 v43, v43
	v_exp_f32_e32 v44, v44
	v_exp_f32_e32 v45, v45
	v_exp_f32_e32 v46, v46
	v_exp_f32_e32 v47, v47
	s_add_i32 s90, s67, 96
	v_add_u32_e32 v84, s90, v107
	v_add_u32_e32 v85, 0, v84
	v_add_u32_e32 v86, 1, v84
	v_add_u32_e32 v87, 2, v84
	v_add_u32_e32 v88, 3, v84
	v_cmp_gt_u32_e64 s[30:31], s98, v85
	v_cmp_gt_u32_e64 s[36:37], s98, v86
	v_cmp_gt_u32_e64 s[78:79], s98, v87
	v_cmp_gt_u32_e64 s[50:51], s98, v88
	v_cndmask_b32_e64 v32, 0, v32, s[30:31]
	v_add_u32_e32 v85, 8, v84
	v_cmp_gt_u32_e64 s[30:31], s98, v85
	v_cndmask_b32_e64 v33, 0, v33, s[36:37]
	v_add_u32_e32 v86, 9, v84
	v_cmp_gt_u32_e64 s[36:37], s98, v86
	v_cndmask_b32_e64 v34, 0, v34, s[78:79]
	v_add_u32_e32 v87, 10, v84
	v_cmp_gt_u32_e64 s[78:79], s98, v87
	v_cndmask_b32_e64 v35, 0, v35, s[50:51]
	v_add_u32_e32 v88, 11, v84
	v_cmp_gt_u32_e64 s[50:51], s98, v88
	v_cndmask_b32_e64 v36, 0, v36, s[30:31]
	v_add_u32_e32 v85, 16, v84
	v_cmp_gt_u32_e64 s[30:31], s98, v85
	v_cndmask_b32_e64 v37, 0, v37, s[36:37]
	v_add_u32_e32 v86, 17, v84
	v_cmp_gt_u32_e64 s[36:37], s98, v86
	v_cndmask_b32_e64 v38, 0, v38, s[78:79]
	v_add_u32_e32 v87, 18, v84
	v_cmp_gt_u32_e64 s[78:79], s98, v87
	v_cndmask_b32_e64 v39, 0, v39, s[50:51]
	v_add_u32_e32 v88, 19, v84
	v_cmp_gt_u32_e64 s[50:51], s98, v88
	v_cndmask_b32_e64 v40, 0, v40, s[30:31]
	v_add_u32_e32 v85, 24, v84
	v_cmp_gt_u32_e64 s[30:31], s98, v85
	v_cndmask_b32_e64 v41, 0, v41, s[36:37]
	v_add_u32_e32 v86, 25, v84
	v_cmp_gt_u32_e64 s[36:37], s98, v86
	v_cndmask_b32_e64 v42, 0, v42, s[78:79]
	v_add_u32_e32 v87, 26, v84
	v_cmp_gt_u32_e64 s[78:79], s98, v87
	v_cndmask_b32_e64 v43, 0, v43, s[50:51]
	v_add_u32_e32 v88, 27, v84
	v_cmp_gt_u32_e64 s[50:51], s98, v88
	v_nop
	v_cndmask_b32_e64 v44, 0, v44, s[30:31]
	v_cndmask_b32_e64 v45, 0, v45, s[36:37]
	v_cndmask_b32_e64 v46, 0, v46, s[78:79]
	v_cndmask_b32_e64 v47, 0, v47, s[50:51]
	v_cvt_pk_bf16_f32 v64, v32, v33
	v_cvt_pk_bf16_f32 v65, v34, v35
	v_cvt_pk_bf16_f32 v66, v36, v37
	v_cvt_pk_bf16_f32 v67, v38, v39
	v_cvt_pk_bf16_f32 v68, v40, v41
	v_cvt_pk_bf16_f32 v69, v42, v43
	v_cvt_pk_bf16_f32 v70, v44, v45
	v_cvt_pk_bf16_f32 v71, v46, v47
	v_pk_add_f32 v[232:233], v[232:233], v[32:33]
	v_pk_add_f32 v[232:233], v[232:233], v[34:35]
	v_pk_add_f32 v[232:233], v[232:233], v[36:37]
	v_pk_add_f32 v[232:233], v[232:233], v[38:39]
	v_pk_add_f32 v[232:233], v[232:233], v[40:41]
	v_pk_add_f32 v[232:233], v[232:233], v[42:43]
	v_pk_add_f32 v[232:233], v[232:233], v[44:45]
	v_pk_add_f32 v[232:233], v[232:233], v[46:47]
	ds_read2_b32 v[32:33], v115 offset0:204 offset1:205
	ds_read2_b32 v[34:35], v115 offset0:206 offset1:207
	ds_read2_b32 v[36:37], v115 offset0:212 offset1:213
	ds_read2_b32 v[38:39], v115 offset0:214 offset1:215
	ds_read2_b32 v[40:41], v115 offset0:221 offset1:222
	ds_read2_b32 v[42:43], v115 offset0:223 offset1:224
	ds_read2_b32 v[44:45], v115 offset0:229 offset1:230
	ds_read2_b32 v[46:47], v115 offset0:231 offset1:232
	s_waitcnt lgkmcnt(15)
	v_mfma_f32_32x32x16_bf16 v[0:15], v[64:67], v[72:75], v[0:15]
	v_mfma_f32_32x32x16_bf16 v[16:31], v[64:67], v[76:79], v[16:31]
	v_mfma_f32_32x32x16_bf16 v[0:15], v[68:71], v[220:223], v[0:15]
	v_mfma_f32_32x32x16_bf16 v[16:31], v[68:71], v[224:227], v[16:31]
	s_add_i32 s90, s67, 192
	v_add_u32_e32 v80, s90, v235
	v_add_u32_e32 v83, s90, v236
	v_add_u32_e32 v99, s90, v237
	v_add_u32_e32 v253, s90, v238
	v_add_u32_e32 v254, s90, v100
	v_add_u32_e32 v255, s90, v149
	v_med3_i32 v80, v80, 0, s99
	v_med3_i32 v83, v83, 0, s99
	v_med3_i32 v99, v99, 0, s99
	v_med3_i32 v253, v253, 0, s99
	v_med3_i32 v254, v254, 0, s99
	v_med3_i32 v255, v255, 0, s99
	v_mad_u32_u24 v80, v80, s100, v252
	v_mad_u32_u24 v83, v83, s100, v252
	v_mad_u32_u24 v99, v99, s100, v252
	v_mad_u32_u24 v253, v253, s100, v252
	v_mad_u32_u24 v254, v254, s100, v153
	v_mad_u32_u24 v255, v255, s100, v153
	global_load_dwordx4 v[188:191], v80, s[82:83]
	global_load_dwordx4 v[192:195], v83, s[82:83]
	global_load_dwordx4 v[196:199], v99, s[82:83]
	global_load_dwordx4 v[200:203], v253, s[82:83]
	global_load_dwordx4 v[204:207], v254, s[82:83] offset:768
	global_load_dwordx4 v[208:211], v255, s[82:83] offset:768
	global_load_dwordx4 v[212:215], v254, s[82:83] offset:832
	global_load_dwordx4 v[216:219], v255, s[82:83] offset:832
	s_waitcnt lgkmcnt(0)
	v_mfma_f32_32x32x16_bf16 v[32:47], v[116:119], v[48:51], v[32:47]
	ds_read_b64_tr_b16 v[72:73], v231
	ds_read_b64_tr_b16 v[74:75], v231 offset:512
	ds_read_b64_tr_b16 v[76:77], v231 offset:2048
	ds_read_b64_tr_b16 v[78:79], v231 offset:2560
	ds_read_b64_tr_b16 v[220:221], v231 offset:1024
	ds_read_b64_tr_b16 v[222:223], v231 offset:1536
	ds_read_b64_tr_b16 v[224:225], v231 offset:3072
	ds_read_b64_tr_b16 v[226:227], v231 offset:3584
	s_waitcnt vmcnt(8)
	ds_write_b128 v247, v[156:159]
	ds_write_b128 v247, v[160:163] offset:1024
	ds_write_b128 v111, v[164:167] offset:2048
	ds_write_b128 v111, v[168:171] offset:3072
	ds_read_b128 v[156:159], v248
	ds_read_b128 v[160:163], v249
	ds_read_b128 v[164:167], v250
	ds_read_b128 v[168:171], v251
	ds_write_b128 v112, v[172:175]
	ds_write_b128 v112, v[176:179] offset:1024
	ds_write_b128 v112, v[180:183] offset:2048
	ds_write_b128 v112, v[184:187] offset:3072
	v_mfma_f32_32x32x16_bf16 v[32:47], v[120:123], v[52:55], v[32:47]
	v_mfma_f32_32x32x16_bf16 v[32:47], v[124:127], v[56:59], v[32:47]
	v_mfma_f32_32x32x16_bf16 v[32:47], v[128:131], v[60:63], v[32:47]
	s_nop 11
	v_exp_f32_e32 v32, v32
	v_exp_f32_e32 v33, v33
	v_exp_f32_e32 v34, v34
	v_exp_f32_e32 v35, v35
	v_exp_f32_e32 v36, v36
	v_exp_f32_e32 v37, v37
	v_exp_f32_e32 v38, v38
	v_exp_f32_e32 v39, v39
	v_exp_f32_e32 v40, v40
	v_exp_f32_e32 v41, v41
	v_exp_f32_e32 v42, v42
	v_exp_f32_e32 v43, v43
	v_exp_f32_e32 v44, v44
	v_exp_f32_e32 v45, v45
	v_exp_f32_e32 v46, v46
	v_exp_f32_e32 v47, v47
	s_add_i32 s90, s67, 128
	v_add_u32_e32 v84, s90, v107
	v_add_u32_e32 v85, 0, v84
	v_add_u32_e32 v86, 1, v84
	v_add_u32_e32 v87, 2, v84
	v_add_u32_e32 v88, 3, v84
	v_cmp_gt_u32_e64 s[30:31], s98, v85
	v_cmp_gt_u32_e64 s[36:37], s98, v86
	v_cmp_gt_u32_e64 s[78:79], s98, v87
	v_cmp_gt_u32_e64 s[50:51], s98, v88
	v_cndmask_b32_e64 v32, 0, v32, s[30:31]
	v_add_u32_e32 v85, 8, v84
	v_cmp_gt_u32_e64 s[30:31], s98, v85
	v_cndmask_b32_e64 v33, 0, v33, s[36:37]
	v_add_u32_e32 v86, 9, v84
	v_cmp_gt_u32_e64 s[36:37], s98, v86
	v_cndmask_b32_e64 v34, 0, v34, s[78:79]
	v_add_u32_e32 v87, 10, v84
	v_cmp_gt_u32_e64 s[78:79], s98, v87
	v_cndmask_b32_e64 v35, 0, v35, s[50:51]
	v_add_u32_e32 v88, 11, v84
	v_cmp_gt_u32_e64 s[50:51], s98, v88
	v_cndmask_b32_e64 v36, 0, v36, s[30:31]
	v_add_u32_e32 v85, 16, v84
	v_cmp_gt_u32_e64 s[30:31], s98, v85
	v_cndmask_b32_e64 v37, 0, v37, s[36:37]
	v_add_u32_e32 v86, 17, v84
	v_cmp_gt_u32_e64 s[36:37], s98, v86
	v_cndmask_b32_e64 v38, 0, v38, s[78:79]
	v_add_u32_e32 v87, 18, v84
	v_cmp_gt_u32_e64 s[78:79], s98, v87
	v_cndmask_b32_e64 v39, 0, v39, s[50:51]
	v_add_u32_e32 v88, 19, v84
	v_cmp_gt_u32_e64 s[50:51], s98, v88
	v_cndmask_b32_e64 v40, 0, v40, s[30:31]
	v_add_u32_e32 v85, 24, v84
	v_cmp_gt_u32_e64 s[30:31], s98, v85
	v_cndmask_b32_e64 v41, 0, v41, s[36:37]
	v_add_u32_e32 v86, 25, v84
	v_cmp_gt_u32_e64 s[36:37], s98, v86
	v_cndmask_b32_e64 v42, 0, v42, s[78:79]
	v_add_u32_e32 v87, 26, v84
	v_cmp_gt_u32_e64 s[78:79], s98, v87
	v_cndmask_b32_e64 v43, 0, v43, s[50:51]
	v_add_u32_e32 v88, 27, v84
	v_cmp_gt_u32_e64 s[50:51], s98, v88
	v_nop
	v_cndmask_b32_e64 v44, 0, v44, s[30:31]
	v_cndmask_b32_e64 v45, 0, v45, s[36:37]
	v_cndmask_b32_e64 v46, 0, v46, s[78:79]
	v_cndmask_b32_e64 v47, 0, v47, s[50:51]
	v_cvt_pk_bf16_f32 v64, v32, v33
	v_cvt_pk_bf16_f32 v65, v34, v35
	v_cvt_pk_bf16_f32 v66, v36, v37
	v_cvt_pk_bf16_f32 v67, v38, v39
	v_cvt_pk_bf16_f32 v68, v40, v41
	v_cvt_pk_bf16_f32 v69, v42, v43
	v_cvt_pk_bf16_f32 v70, v44, v45
	v_cvt_pk_bf16_f32 v71, v46, v47
	v_pk_add_f32 v[232:233], v[232:233], v[32:33]
	v_pk_add_f32 v[232:233], v[232:233], v[34:35]
	v_pk_add_f32 v[232:233], v[232:233], v[36:37]
	v_pk_add_f32 v[232:233], v[232:233], v[38:39]
	v_pk_add_f32 v[232:233], v[232:233], v[40:41]
	v_pk_add_f32 v[232:233], v[232:233], v[42:43]
	v_pk_add_f32 v[232:233], v[232:233], v[44:45]
	v_pk_add_f32 v[232:233], v[232:233], v[46:47]
	v_add_u32_e32 v115, 952, v115
	ds_read2_b32 v[32:33], v115 offset0:0 offset1:1
	ds_read2_b32 v[34:35], v115 offset0:2 offset1:3
	ds_read2_b32 v[36:37], v115 offset0:8 offset1:9
	ds_read2_b32 v[38:39], v115 offset0:10 offset1:11
	ds_read2_b32 v[40:41], v115 offset0:17 offset1:18
	ds_read2_b32 v[42:43], v115 offset0:19 offset1:20
	ds_read2_b32 v[44:45], v115 offset0:25 offset1:26
	ds_read2_b32 v[46:47], v115 offset0:27 offset1:28
	s_waitcnt lgkmcnt(15)
	v_mfma_f32_32x32x16_bf16 v[0:15], v[64:67], v[72:75], v[0:15]
	v_mfma_f32_32x32x16_bf16 v[16:31], v[64:67], v[76:79], v[16:31]
	v_mfma_f32_32x32x16_bf16 v[0:15], v[68:71], v[220:223], v[0:15]
	v_mfma_f32_32x32x16_bf16 v[16:31], v[68:71], v[224:227], v[16:31]
	s_add_i32 s90, s67, 224
	v_add_u32_e32 v80, s90, v235
	v_add_u32_e32 v83, s90, v236
	v_add_u32_e32 v99, s90, v237
	v_add_u32_e32 v253, s90, v238
	v_add_u32_e32 v254, s90, v100
	v_add_u32_e32 v255, s90, v149
	v_med3_i32 v80, v80, 0, s99
	v_med3_i32 v83, v83, 0, s99
	v_med3_i32 v99, v99, 0, s99
	v_med3_i32 v253, v253, 0, s99
	v_med3_i32 v254, v254, 0, s99
	v_med3_i32 v255, v255, 0, s99
	v_mad_u32_u24 v80, v80, s100, v252
	v_mad_u32_u24 v83, v83, s100, v252
	v_mad_u32_u24 v99, v99, s100, v252
	v_mad_u32_u24 v253, v253, s100, v252
	v_mad_u32_u24 v254, v254, s100, v153
	v_mad_u32_u24 v255, v255, s100, v153
	global_load_dwordx4 v[116:119], v80, s[82:83]
	global_load_dwordx4 v[120:123], v83, s[82:83]
	global_load_dwordx4 v[124:127], v99, s[82:83]
	global_load_dwordx4 v[128:131], v253, s[82:83]
	global_load_dwordx4 v[132:135], v254, s[82:83] offset:768
	global_load_dwordx4 v[136:139], v255, s[82:83] offset:768
	global_load_dwordx4 v[140:143], v254, s[82:83] offset:832
	global_load_dwordx4 v[144:147], v255, s[82:83] offset:832
	s_waitcnt lgkmcnt(0)
	v_mfma_f32_32x32x16_bf16 v[32:47], v[156:159], v[48:51], v[32:47]
	ds_read_b64_tr_b16 v[72:73], v231
	ds_read_b64_tr_b16 v[74:75], v231 offset:512
	ds_read_b64_tr_b16 v[76:77], v231 offset:2048
	ds_read_b64_tr_b16 v[78:79], v231 offset:2560
	ds_read_b64_tr_b16 v[220:221], v231 offset:1024
	ds_read_b64_tr_b16 v[222:223], v231 offset:1536
	ds_read_b64_tr_b16 v[224:225], v231 offset:3072
	ds_read_b64_tr_b16 v[226:227], v231 offset:3584
	s_waitcnt vmcnt(8)
	ds_write_b128 v247, v[188:191]
	ds_write_b128 v247, v[192:195] offset:1024
	ds_write_b128 v111, v[196:199] offset:2048
	ds_write_b128 v111, v[200:203] offset:3072
	ds_read_b128 v[188:191], v248
	ds_read_b128 v[192:195], v249
	ds_read_b128 v[196:199], v250
	ds_read_b128 v[200:203], v251
	ds_write_b128 v112, v[204:207]
	ds_write_b128 v112, v[208:211] offset:1024
	ds_write_b128 v112, v[212:215] offset:2048
	ds_write_b128 v112, v[216:219] offset:3072
	v_mfma_f32_32x32x16_bf16 v[32:47], v[160:163], v[52:55], v[32:47]
	v_mfma_f32_32x32x16_bf16 v[32:47], v[164:167], v[56:59], v[32:47]
	v_mfma_f32_32x32x16_bf16 v[32:47], v[168:171], v[60:63], v[32:47]
	s_nop 11
	v_exp_f32_e32 v32, v32
	v_exp_f32_e32 v33, v33
	v_exp_f32_e32 v34, v34
	v_exp_f32_e32 v35, v35
	v_exp_f32_e32 v36, v36
	v_exp_f32_e32 v37, v37
	v_exp_f32_e32 v38, v38
	v_exp_f32_e32 v39, v39
	v_exp_f32_e32 v40, v40
	v_exp_f32_e32 v41, v41
	v_exp_f32_e32 v42, v42
	v_exp_f32_e32 v43, v43
	v_exp_f32_e32 v44, v44
	v_exp_f32_e32 v45, v45
	v_exp_f32_e32 v46, v46
	v_exp_f32_e32 v47, v47
	s_add_i32 s90, s67, 160
	v_add_u32_e32 v84, s90, v107
	v_add_u32_e32 v85, 0, v84
	v_add_u32_e32 v86, 1, v84
	v_add_u32_e32 v87, 2, v84
	v_add_u32_e32 v88, 3, v84
	v_cmp_gt_u32_e64 s[30:31], s98, v85
	v_cmp_gt_u32_e64 s[36:37], s98, v86
	v_cmp_gt_u32_e64 s[78:79], s98, v87
	v_cmp_gt_u32_e64 s[50:51], s98, v88
	v_cndmask_b32_e64 v32, 0, v32, s[30:31]
	v_add_u32_e32 v85, 8, v84
	v_cmp_gt_u32_e64 s[30:31], s98, v85
	v_cndmask_b32_e64 v33, 0, v33, s[36:37]
	v_add_u32_e32 v86, 9, v84
	v_cmp_gt_u32_e64 s[36:37], s98, v86
	v_cndmask_b32_e64 v34, 0, v34, s[78:79]
	v_add_u32_e32 v87, 10, v84
	v_cmp_gt_u32_e64 s[78:79], s98, v87
	v_cndmask_b32_e64 v35, 0, v35, s[50:51]
	v_add_u32_e32 v88, 11, v84
	v_cmp_gt_u32_e64 s[50:51], s98, v88
	v_cndmask_b32_e64 v36, 0, v36, s[30:31]
	v_add_u32_e32 v85, 16, v84
	v_cmp_gt_u32_e64 s[30:31], s98, v85
	v_cndmask_b32_e64 v37, 0, v37, s[36:37]
	v_add_u32_e32 v86, 17, v84
	v_cmp_gt_u32_e64 s[36:37], s98, v86
	v_cndmask_b32_e64 v38, 0, v38, s[78:79]
	v_add_u32_e32 v87, 18, v84
	v_cmp_gt_u32_e64 s[78:79], s98, v87
	v_cndmask_b32_e64 v39, 0, v39, s[50:51]
	v_add_u32_e32 v88, 19, v84
	v_cmp_gt_u32_e64 s[50:51], s98, v88
	v_cndmask_b32_e64 v40, 0, v40, s[30:31]
	v_add_u32_e32 v85, 24, v84
	v_cmp_gt_u32_e64 s[30:31], s98, v85
	v_cndmask_b32_e64 v41, 0, v41, s[36:37]
	v_add_u32_e32 v86, 25, v84
	v_cmp_gt_u32_e64 s[36:37], s98, v86
	v_cndmask_b32_e64 v42, 0, v42, s[78:79]
	v_add_u32_e32 v87, 26, v84
	v_cmp_gt_u32_e64 s[78:79], s98, v87
	v_cndmask_b32_e64 v43, 0, v43, s[50:51]
	v_add_u32_e32 v88, 27, v84
	v_cmp_gt_u32_e64 s[50:51], s98, v88
	v_nop
	v_cndmask_b32_e64 v44, 0, v44, s[30:31]
	v_cndmask_b32_e64 v45, 0, v45, s[36:37]
	v_cndmask_b32_e64 v46, 0, v46, s[78:79]
	v_cndmask_b32_e64 v47, 0, v47, s[50:51]
	v_cvt_pk_bf16_f32 v64, v32, v33
	v_cvt_pk_bf16_f32 v65, v34, v35
	v_cvt_pk_bf16_f32 v66, v36, v37
	v_cvt_pk_bf16_f32 v67, v38, v39
	v_cvt_pk_bf16_f32 v68, v40, v41
	v_cvt_pk_bf16_f32 v69, v42, v43
	v_cvt_pk_bf16_f32 v70, v44, v45
	v_cvt_pk_bf16_f32 v71, v46, v47
	v_pk_add_f32 v[232:233], v[232:233], v[32:33]
	v_pk_add_f32 v[232:233], v[232:233], v[34:35]
	v_pk_add_f32 v[232:233], v[232:233], v[36:37]
	v_pk_add_f32 v[232:233], v[232:233], v[38:39]
	v_pk_add_f32 v[232:233], v[232:233], v[40:41]
	v_pk_add_f32 v[232:233], v[232:233], v[42:43]
	v_pk_add_f32 v[232:233], v[232:233], v[44:45]
	v_pk_add_f32 v[232:233], v[232:233], v[46:47]
	ds_read2_b32 v[32:33], v115 offset0:34 offset1:35
	ds_read2_b32 v[34:35], v115 offset0:36 offset1:37
	ds_read2_b32 v[36:37], v115 offset0:42 offset1:43
	ds_read2_b32 v[38:39], v115 offset0:44 offset1:45
	ds_read2_b32 v[40:41], v115 offset0:51 offset1:52
	ds_read2_b32 v[42:43], v115 offset0:53 offset1:54
	ds_read2_b32 v[44:45], v115 offset0:59 offset1:60
	ds_read2_b32 v[46:47], v115 offset0:61 offset1:62
	s_waitcnt lgkmcnt(15)
	v_mfma_f32_32x32x16_bf16 v[0:15], v[64:67], v[72:75], v[0:15]
	v_mfma_f32_32x32x16_bf16 v[16:31], v[64:67], v[76:79], v[16:31]
	v_mfma_f32_32x32x16_bf16 v[0:15], v[68:71], v[220:223], v[0:15]
	v_mfma_f32_32x32x16_bf16 v[16:31], v[68:71], v[224:227], v[16:31]
	s_add_i32 s90, s67, 256
	v_add_u32_e32 v80, s90, v235
	v_add_u32_e32 v83, s90, v236
	v_add_u32_e32 v99, s90, v237
	v_add_u32_e32 v253, s90, v238
	v_add_u32_e32 v254, s90, v100
	v_add_u32_e32 v255, s90, v149
	v_med3_i32 v80, v80, 0, s99
	v_med3_i32 v83, v83, 0, s99
	v_med3_i32 v99, v99, 0, s99
	v_med3_i32 v253, v253, 0, s99
	v_med3_i32 v254, v254, 0, s99
	v_med3_i32 v255, v255, 0, s99
	v_mad_u32_u24 v80, v80, s100, v252
	v_mad_u32_u24 v83, v83, s100, v252
	v_mad_u32_u24 v99, v99, s100, v252
	v_mad_u32_u24 v253, v253, s100, v252
	v_mad_u32_u24 v254, v254, s100, v153
	v_mad_u32_u24 v255, v255, s100, v153
	global_load_dwordx4 v[156:159], v80, s[82:83]
	global_load_dwordx4 v[160:163], v83, s[82:83]
	global_load_dwordx4 v[164:167], v99, s[82:83]
	global_load_dwordx4 v[168:171], v253, s[82:83]
	global_load_dwordx4 v[172:175], v254, s[82:83] offset:768
	global_load_dwordx4 v[176:179], v255, s[82:83] offset:768
	global_load_dwordx4 v[180:183], v254, s[82:83] offset:832
	global_load_dwordx4 v[184:187], v255, s[82:83] offset:832
	s_waitcnt lgkmcnt(0)
	v_mfma_f32_32x32x16_bf16 v[32:47], v[188:191], v[48:51], v[32:47]
	ds_read_b64_tr_b16 v[72:73], v231
	ds_read_b64_tr_b16 v[74:75], v231 offset:512
	ds_read_b64_tr_b16 v[76:77], v231 offset:2048
	ds_read_b64_tr_b16 v[78:79], v231 offset:2560
	ds_read_b64_tr_b16 v[220:221], v231 offset:1024
	ds_read_b64_tr_b16 v[222:223], v231 offset:1536
	ds_read_b64_tr_b16 v[224:225], v231 offset:3072
	ds_read_b64_tr_b16 v[226:227], v231 offset:3584
	s_waitcnt vmcnt(8)
	ds_write_b128 v247, v[116:119]
	ds_write_b128 v247, v[120:123] offset:1024
	ds_write_b128 v111, v[124:127] offset:2048
	ds_write_b128 v111, v[128:131] offset:3072
	ds_read_b128 v[116:119], v248
	ds_read_b128 v[120:123], v249
	ds_read_b128 v[124:127], v250
	ds_read_b128 v[128:131], v251
	ds_write_b128 v112, v[132:135]
	ds_write_b128 v112, v[136:139] offset:1024
	ds_write_b128 v112, v[140:143] offset:2048
	ds_write_b128 v112, v[144:147] offset:3072
	v_mfma_f32_32x32x16_bf16 v[32:47], v[192:195], v[52:55], v[32:47]
	v_mfma_f32_32x32x16_bf16 v[32:47], v[196:199], v[56:59], v[32:47]
	v_mfma_f32_32x32x16_bf16 v[32:47], v[200:203], v[60:63], v[32:47]
	s_nop 11
	v_exp_f32_e32 v32, v32
	v_exp_f32_e32 v33, v33
	v_exp_f32_e32 v34, v34
	v_exp_f32_e32 v35, v35
	v_exp_f32_e32 v36, v36
	v_exp_f32_e32 v37, v37
	v_exp_f32_e32 v38, v38
	v_exp_f32_e32 v39, v39
	v_exp_f32_e32 v40, v40
	v_exp_f32_e32 v41, v41
	v_exp_f32_e32 v42, v42
	v_exp_f32_e32 v43, v43
	v_exp_f32_e32 v44, v44
	v_exp_f32_e32 v45, v45
	v_exp_f32_e32 v46, v46
	v_exp_f32_e32 v47, v47
	s_add_i32 s90, s67, 192
	v_add_u32_e32 v84, s90, v107
	v_add_u32_e32 v85, 0, v84
	v_add_u32_e32 v86, 1, v84
	v_add_u32_e32 v87, 2, v84
	v_add_u32_e32 v88, 3, v84
	v_cmp_gt_u32_e64 s[30:31], s98, v85
	v_cmp_gt_u32_e64 s[36:37], s98, v86
	v_cmp_gt_u32_e64 s[78:79], s98, v87
	v_cmp_gt_u32_e64 s[50:51], s98, v88
	v_cndmask_b32_e64 v32, 0, v32, s[30:31]
	v_add_u32_e32 v85, 8, v84
	v_cmp_gt_u32_e64 s[30:31], s98, v85
	v_cndmask_b32_e64 v33, 0, v33, s[36:37]
	v_add_u32_e32 v86, 9, v84
	v_cmp_gt_u32_e64 s[36:37], s98, v86
	v_cndmask_b32_e64 v34, 0, v34, s[78:79]
	v_add_u32_e32 v87, 10, v84
	v_cmp_gt_u32_e64 s[78:79], s98, v87
	v_cndmask_b32_e64 v35, 0, v35, s[50:51]
	v_add_u32_e32 v88, 11, v84
	v_cmp_gt_u32_e64 s[50:51], s98, v88
	v_cndmask_b32_e64 v36, 0, v36, s[30:31]
	v_add_u32_e32 v85, 16, v84
	v_cmp_gt_u32_e64 s[30:31], s98, v85
	v_cndmask_b32_e64 v37, 0, v37, s[36:37]
	v_add_u32_e32 v86, 17, v84
	v_cmp_gt_u32_e64 s[36:37], s98, v86
	v_cndmask_b32_e64 v38, 0, v38, s[78:79]
	v_add_u32_e32 v87, 18, v84
	v_cmp_gt_u32_e64 s[78:79], s98, v87
	v_cndmask_b32_e64 v39, 0, v39, s[50:51]
	v_add_u32_e32 v88, 19, v84
	v_cmp_gt_u32_e64 s[50:51], s98, v88
	v_cndmask_b32_e64 v40, 0, v40, s[30:31]
	v_add_u32_e32 v85, 24, v84
	v_cmp_gt_u32_e64 s[30:31], s98, v85
	v_cndmask_b32_e64 v41, 0, v41, s[36:37]
	v_add_u32_e32 v86, 25, v84
	v_cmp_gt_u32_e64 s[36:37], s98, v86
	v_cndmask_b32_e64 v42, 0, v42, s[78:79]
	v_add_u32_e32 v87, 26, v84
	v_cmp_gt_u32_e64 s[78:79], s98, v87
	v_cndmask_b32_e64 v43, 0, v43, s[50:51]
	v_add_u32_e32 v88, 27, v84
	v_cmp_gt_u32_e64 s[50:51], s98, v88
	v_nop
	v_cndmask_b32_e64 v44, 0, v44, s[30:31]
	v_cndmask_b32_e64 v45, 0, v45, s[36:37]
	v_cndmask_b32_e64 v46, 0, v46, s[78:79]
	v_cndmask_b32_e64 v47, 0, v47, s[50:51]
	v_cvt_pk_bf16_f32 v64, v32, v33
	v_cvt_pk_bf16_f32 v65, v34, v35
	v_cvt_pk_bf16_f32 v66, v36, v37
	v_cvt_pk_bf16_f32 v67, v38, v39
	v_cvt_pk_bf16_f32 v68, v40, v41
	v_cvt_pk_bf16_f32 v69, v42, v43
	v_cvt_pk_bf16_f32 v70, v44, v45
	v_cvt_pk_bf16_f32 v71, v46, v47
	v_pk_add_f32 v[232:233], v[232:233], v[32:33]
	v_pk_add_f32 v[232:233], v[232:233], v[34:35]
	v_pk_add_f32 v[232:233], v[232:233], v[36:37]
	v_pk_add_f32 v[232:233], v[232:233], v[38:39]
	v_pk_add_f32 v[232:233], v[232:233], v[40:41]
	v_pk_add_f32 v[232:233], v[232:233], v[42:43]
	v_pk_add_f32 v[232:233], v[232:233], v[44:45]
	v_pk_add_f32 v[232:233], v[232:233], v[46:47]
	ds_read2_b32 v[32:33], v115 offset0:68 offset1:69
	ds_read2_b32 v[34:35], v115 offset0:70 offset1:71
	ds_read2_b32 v[36:37], v115 offset0:76 offset1:77
	ds_read2_b32 v[38:39], v115 offset0:78 offset1:79
	ds_read2_b32 v[40:41], v115 offset0:85 offset1:86
	ds_read2_b32 v[42:43], v115 offset0:87 offset1:88
	ds_read2_b32 v[44:45], v115 offset0:93 offset1:94
	ds_read2_b32 v[46:47], v115 offset0:95 offset1:96
	s_waitcnt lgkmcnt(15)
	v_mfma_f32_32x32x16_bf16 v[0:15], v[64:67], v[72:75], v[0:15]
	v_mfma_f32_32x32x16_bf16 v[16:31], v[64:67], v[76:79], v[16:31]
	v_mfma_f32_32x32x16_bf16 v[0:15], v[68:71], v[220:223], v[0:15]
	v_mfma_f32_32x32x16_bf16 v[16:31], v[68:71], v[224:227], v[16:31]
	s_add_i32 s90, s67, 288
	v_add_u32_e32 v80, s90, v235
	v_add_u32_e32 v83, s90, v236
	v_add_u32_e32 v99, s90, v237
	v_add_u32_e32 v253, s90, v238
	v_add_u32_e32 v254, s90, v100
	v_add_u32_e32 v255, s90, v149
	v_med3_i32 v80, v80, 0, s99
	v_med3_i32 v83, v83, 0, s99
	v_med3_i32 v99, v99, 0, s99
	v_med3_i32 v253, v253, 0, s99
	v_med3_i32 v254, v254, 0, s99
	v_med3_i32 v255, v255, 0, s99
	v_mad_u32_u24 v80, v80, s100, v252
	v_mad_u32_u24 v83, v83, s100, v252
	v_mad_u32_u24 v99, v99, s100, v252
	v_mad_u32_u24 v253, v253, s100, v252
	v_mad_u32_u24 v254, v254, s100, v153
	v_mad_u32_u24 v255, v255, s100, v153
	global_load_dwordx4 v[188:191], v80, s[82:83]
	global_load_dwordx4 v[192:195], v83, s[82:83]
	global_load_dwordx4 v[196:199], v99, s[82:83]
	global_load_dwordx4 v[200:203], v253, s[82:83]
	global_load_dwordx4 v[204:207], v254, s[82:83] offset:768
	global_load_dwordx4 v[208:211], v255, s[82:83] offset:768
	global_load_dwordx4 v[212:215], v254, s[82:83] offset:832
	global_load_dwordx4 v[216:219], v255, s[82:83] offset:832
	s_waitcnt lgkmcnt(0)
	v_mfma_f32_32x32x16_bf16 v[32:47], v[116:119], v[48:51], v[32:47]
	ds_read_b64_tr_b16 v[72:73], v231
	ds_read_b64_tr_b16 v[74:75], v231 offset:512
	ds_read_b64_tr_b16 v[76:77], v231 offset:2048
	ds_read_b64_tr_b16 v[78:79], v231 offset:2560
	ds_read_b64_tr_b16 v[220:221], v231 offset:1024
	ds_read_b64_tr_b16 v[222:223], v231 offset:1536
	ds_read_b64_tr_b16 v[224:225], v231 offset:3072
	ds_read_b64_tr_b16 v[226:227], v231 offset:3584
	s_waitcnt vmcnt(8)
	ds_write_b128 v247, v[156:159]
	ds_write_b128 v247, v[160:163] offset:1024
	ds_write_b128 v111, v[164:167] offset:2048
	ds_write_b128 v111, v[168:171] offset:3072
	ds_read_b128 v[156:159], v248
	ds_read_b128 v[160:163], v249
	ds_read_b128 v[164:167], v250
	ds_read_b128 v[168:171], v251
	ds_write_b128 v112, v[172:175]
	ds_write_b128 v112, v[176:179] offset:1024
	ds_write_b128 v112, v[180:183] offset:2048
	ds_write_b128 v112, v[184:187] offset:3072
	v_mfma_f32_32x32x16_bf16 v[32:47], v[120:123], v[52:55], v[32:47]
	v_mfma_f32_32x32x16_bf16 v[32:47], v[124:127], v[56:59], v[32:47]
	v_mfma_f32_32x32x16_bf16 v[32:47], v[128:131], v[60:63], v[32:47]
	s_nop 11
	v_exp_f32_e32 v32, v32
	v_exp_f32_e32 v33, v33
	v_exp_f32_e32 v34, v34
	v_exp_f32_e32 v35, v35
	v_exp_f32_e32 v36, v36
	v_exp_f32_e32 v37, v37
	v_exp_f32_e32 v38, v38
	v_exp_f32_e32 v39, v39
	v_exp_f32_e32 v40, v40
	v_exp_f32_e32 v41, v41
	v_exp_f32_e32 v42, v42
	v_exp_f32_e32 v43, v43
	v_exp_f32_e32 v44, v44
	v_exp_f32_e32 v45, v45
	v_exp_f32_e32 v46, v46
	v_exp_f32_e32 v47, v47
	s_add_i32 s90, s67, 224
	v_add_u32_e32 v84, s90, v107
	v_add_u32_e32 v85, 0, v84
	v_add_u32_e32 v86, 1, v84
	v_add_u32_e32 v87, 2, v84
	v_add_u32_e32 v88, 3, v84
	v_cmp_gt_u32_e64 s[30:31], s98, v85
	v_cmp_gt_u32_e64 s[36:37], s98, v86
	v_cmp_gt_u32_e64 s[78:79], s98, v87
	v_cmp_gt_u32_e64 s[50:51], s98, v88
	v_cndmask_b32_e64 v32, 0, v32, s[30:31]
	v_add_u32_e32 v85, 8, v84
	v_cmp_gt_u32_e64 s[30:31], s98, v85
	v_cndmask_b32_e64 v33, 0, v33, s[36:37]
	v_add_u32_e32 v86, 9, v84
	v_cmp_gt_u32_e64 s[36:37], s98, v86
	v_cndmask_b32_e64 v34, 0, v34, s[78:79]
	v_add_u32_e32 v87, 10, v84
	v_cmp_gt_u32_e64 s[78:79], s98, v87
	v_cndmask_b32_e64 v35, 0, v35, s[50:51]
	v_add_u32_e32 v88, 11, v84
	v_cmp_gt_u32_e64 s[50:51], s98, v88
	v_cndmask_b32_e64 v36, 0, v36, s[30:31]
	v_add_u32_e32 v85, 16, v84
	v_cmp_gt_u32_e64 s[30:31], s98, v85
	v_cndmask_b32_e64 v37, 0, v37, s[36:37]
	v_add_u32_e32 v86, 17, v84
	v_cmp_gt_u32_e64 s[36:37], s98, v86
	v_cndmask_b32_e64 v38, 0, v38, s[78:79]
	v_add_u32_e32 v87, 18, v84
	v_cmp_gt_u32_e64 s[78:79], s98, v87
	v_cndmask_b32_e64 v39, 0, v39, s[50:51]
	v_add_u32_e32 v88, 19, v84
	v_cmp_gt_u32_e64 s[50:51], s98, v88
	v_cndmask_b32_e64 v40, 0, v40, s[30:31]
	v_add_u32_e32 v85, 24, v84
	v_cmp_gt_u32_e64 s[30:31], s98, v85
	v_cndmask_b32_e64 v41, 0, v41, s[36:37]
	v_add_u32_e32 v86, 25, v84
	v_cmp_gt_u32_e64 s[36:37], s98, v86
	v_cndmask_b32_e64 v42, 0, v42, s[78:79]
	v_add_u32_e32 v87, 26, v84
	v_cmp_gt_u32_e64 s[78:79], s98, v87
	v_cndmask_b32_e64 v43, 0, v43, s[50:51]
	v_add_u32_e32 v88, 27, v84
	v_cmp_gt_u32_e64 s[50:51], s98, v88
	v_nop
	v_cndmask_b32_e64 v44, 0, v44, s[30:31]
	v_cndmask_b32_e64 v45, 0, v45, s[36:37]
	v_cndmask_b32_e64 v46, 0, v46, s[78:79]
	v_cndmask_b32_e64 v47, 0, v47, s[50:51]
	v_cvt_pk_bf16_f32 v64, v32, v33
	v_cvt_pk_bf16_f32 v65, v34, v35
	v_cvt_pk_bf16_f32 v66, v36, v37
	v_cvt_pk_bf16_f32 v67, v38, v39
	v_cvt_pk_bf16_f32 v68, v40, v41
	v_cvt_pk_bf16_f32 v69, v42, v43
	v_cvt_pk_bf16_f32 v70, v44, v45
	v_cvt_pk_bf16_f32 v71, v46, v47
	v_pk_add_f32 v[232:233], v[232:233], v[32:33]
	v_pk_add_f32 v[232:233], v[232:233], v[34:35]
	v_pk_add_f32 v[232:233], v[232:233], v[36:37]
	v_pk_add_f32 v[232:233], v[232:233], v[38:39]
	v_pk_add_f32 v[232:233], v[232:233], v[40:41]
	v_pk_add_f32 v[232:233], v[232:233], v[42:43]
	v_pk_add_f32 v[232:233], v[232:233], v[44:45]
	v_pk_add_f32 v[232:233], v[232:233], v[46:47]
	ds_read2_b32 v[32:33], v115 offset0:102 offset1:103
	ds_read2_b32 v[34:35], v115 offset0:104 offset1:105
	ds_read2_b32 v[36:37], v115 offset0:110 offset1:111
	ds_read2_b32 v[38:39], v115 offset0:112 offset1:113
	ds_read2_b32 v[40:41], v115 offset0:119 offset1:120
	ds_read2_b32 v[42:43], v115 offset0:121 offset1:122
	ds_read2_b32 v[44:45], v115 offset0:127 offset1:128
	ds_read2_b32 v[46:47], v115 offset0:129 offset1:130
	s_waitcnt lgkmcnt(15)
	v_mfma_f32_32x32x16_bf16 v[0:15], v[64:67], v[72:75], v[0:15]
	v_mfma_f32_32x32x16_bf16 v[16:31], v[64:67], v[76:79], v[16:31]
	v_mfma_f32_32x32x16_bf16 v[0:15], v[68:71], v[220:223], v[0:15]
	v_mfma_f32_32x32x16_bf16 v[16:31], v[68:71], v[224:227], v[16:31]
	s_add_i32 s90, s67, 320
	v_add_u32_e32 v80, s90, v235
	v_add_u32_e32 v83, s90, v236
	v_add_u32_e32 v99, s90, v237
	v_add_u32_e32 v253, s90, v238
	v_add_u32_e32 v254, s90, v100
	v_add_u32_e32 v255, s90, v149
	v_med3_i32 v80, v80, 0, s99
	v_med3_i32 v83, v83, 0, s99
	v_med3_i32 v99, v99, 0, s99
	v_med3_i32 v253, v253, 0, s99
	v_med3_i32 v254, v254, 0, s99
	v_med3_i32 v255, v255, 0, s99
	v_mad_u32_u24 v80, v80, s100, v252
	v_mad_u32_u24 v83, v83, s100, v252
	v_mad_u32_u24 v99, v99, s100, v252
	v_mad_u32_u24 v253, v253, s100, v252
	v_mad_u32_u24 v254, v254, s100, v153
	v_mad_u32_u24 v255, v255, s100, v153
	global_load_dwordx4 v[116:119], v80, s[82:83]
	global_load_dwordx4 v[120:123], v83, s[82:83]
	global_load_dwordx4 v[124:127], v99, s[82:83]
	global_load_dwordx4 v[128:131], v253, s[82:83]
	global_load_dwordx4 v[132:135], v254, s[82:83] offset:768
	global_load_dwordx4 v[136:139], v255, s[82:83] offset:768
	global_load_dwordx4 v[140:143], v254, s[82:83] offset:832
	global_load_dwordx4 v[144:147], v255, s[82:83] offset:832
	s_waitcnt lgkmcnt(0)
	v_mfma_f32_32x32x16_bf16 v[32:47], v[156:159], v[48:51], v[32:47]
	ds_read_b64_tr_b16 v[72:73], v231
	ds_read_b64_tr_b16 v[74:75], v231 offset:512
	ds_read_b64_tr_b16 v[76:77], v231 offset:2048
	ds_read_b64_tr_b16 v[78:79], v231 offset:2560
	ds_read_b64_tr_b16 v[220:221], v231 offset:1024
	ds_read_b64_tr_b16 v[222:223], v231 offset:1536
	ds_read_b64_tr_b16 v[224:225], v231 offset:3072
	ds_read_b64_tr_b16 v[226:227], v231 offset:3584
	s_waitcnt vmcnt(8)
	ds_write_b128 v247, v[188:191]
	ds_write_b128 v247, v[192:195] offset:1024
	ds_write_b128 v111, v[196:199] offset:2048
	ds_write_b128 v111, v[200:203] offset:3072
	ds_read_b128 v[188:191], v248
	ds_read_b128 v[192:195], v249
	ds_read_b128 v[196:199], v250
	ds_read_b128 v[200:203], v251
	ds_write_b128 v112, v[204:207]
	ds_write_b128 v112, v[208:211] offset:1024
	ds_write_b128 v112, v[212:215] offset:2048
	ds_write_b128 v112, v[216:219] offset:3072
	v_mfma_f32_32x32x16_bf16 v[32:47], v[160:163], v[52:55], v[32:47]
	v_mfma_f32_32x32x16_bf16 v[32:47], v[164:167], v[56:59], v[32:47]
	v_mfma_f32_32x32x16_bf16 v[32:47], v[168:171], v[60:63], v[32:47]
	s_nop 11
	v_exp_f32_e32 v32, v32
	v_exp_f32_e32 v33, v33
	v_exp_f32_e32 v34, v34
	v_exp_f32_e32 v35, v35
	v_exp_f32_e32 v36, v36
	v_exp_f32_e32 v37, v37
	v_exp_f32_e32 v38, v38
	v_exp_f32_e32 v39, v39
	v_exp_f32_e32 v40, v40
	v_exp_f32_e32 v41, v41
	v_exp_f32_e32 v42, v42
	v_exp_f32_e32 v43, v43
	v_exp_f32_e32 v44, v44
	v_exp_f32_e32 v45, v45
	v_exp_f32_e32 v46, v46
	v_exp_f32_e32 v47, v47
	s_add_i32 s90, s67, 256
	v_add_u32_e32 v84, s90, v107
	v_add_u32_e32 v85, 0, v84
	v_add_u32_e32 v86, 1, v84
	v_add_u32_e32 v87, 2, v84
	v_add_u32_e32 v88, 3, v84
	v_cmp_gt_u32_e64 s[30:31], s98, v85
	v_cmp_gt_u32_e64 s[36:37], s98, v86
	v_cmp_gt_u32_e64 s[78:79], s98, v87
	v_cmp_gt_u32_e64 s[50:51], s98, v88
	v_cndmask_b32_e64 v32, 0, v32, s[30:31]
	v_add_u32_e32 v85, 8, v84
	v_cmp_gt_u32_e64 s[30:31], s98, v85
	v_cndmask_b32_e64 v33, 0, v33, s[36:37]
	v_add_u32_e32 v86, 9, v84
	v_cmp_gt_u32_e64 s[36:37], s98, v86
	v_cndmask_b32_e64 v34, 0, v34, s[78:79]
	v_add_u32_e32 v87, 10, v84
	v_cmp_gt_u32_e64 s[78:79], s98, v87
	v_cndmask_b32_e64 v35, 0, v35, s[50:51]
	v_add_u32_e32 v88, 11, v84
	v_cmp_gt_u32_e64 s[50:51], s98, v88
	v_cndmask_b32_e64 v36, 0, v36, s[30:31]
	v_add_u32_e32 v85, 16, v84
	v_cmp_gt_u32_e64 s[30:31], s98, v85
	v_cndmask_b32_e64 v37, 0, v37, s[36:37]
	v_add_u32_e32 v86, 17, v84
	v_cmp_gt_u32_e64 s[36:37], s98, v86
	v_cndmask_b32_e64 v38, 0, v38, s[78:79]
	v_add_u32_e32 v87, 18, v84
	v_cmp_gt_u32_e64 s[78:79], s98, v87
	v_cndmask_b32_e64 v39, 0, v39, s[50:51]
	v_add_u32_e32 v88, 19, v84
	v_cmp_gt_u32_e64 s[50:51], s98, v88
	v_cndmask_b32_e64 v40, 0, v40, s[30:31]
	v_add_u32_e32 v85, 24, v84
	v_cmp_gt_u32_e64 s[30:31], s98, v85
	v_cndmask_b32_e64 v41, 0, v41, s[36:37]
	v_add_u32_e32 v86, 25, v84
	v_cmp_gt_u32_e64 s[36:37], s98, v86
	v_cndmask_b32_e64 v42, 0, v42, s[78:79]
	v_add_u32_e32 v87, 26, v84
	v_cmp_gt_u32_e64 s[78:79], s98, v87
	v_cndmask_b32_e64 v43, 0, v43, s[50:51]
	v_add_u32_e32 v88, 27, v84
	v_cmp_gt_u32_e64 s[50:51], s98, v88
	v_nop
	v_cndmask_b32_e64 v44, 0, v44, s[30:31]
	v_cndmask_b32_e64 v45, 0, v45, s[36:37]
	v_cndmask_b32_e64 v46, 0, v46, s[78:79]
	v_cndmask_b32_e64 v47, 0, v47, s[50:51]
	v_cvt_pk_bf16_f32 v64, v32, v33
	v_cvt_pk_bf16_f32 v65, v34, v35
	v_cvt_pk_bf16_f32 v66, v36, v37
	v_cvt_pk_bf16_f32 v67, v38, v39
	v_cvt_pk_bf16_f32 v68, v40, v41
	v_cvt_pk_bf16_f32 v69, v42, v43
	v_cvt_pk_bf16_f32 v70, v44, v45
	v_cvt_pk_bf16_f32 v71, v46, v47
	v_pk_add_f32 v[232:233], v[232:233], v[32:33]
	v_pk_add_f32 v[232:233], v[232:233], v[34:35]
	v_pk_add_f32 v[232:233], v[232:233], v[36:37]
	v_pk_add_f32 v[232:233], v[232:233], v[38:39]
	v_pk_add_f32 v[232:233], v[232:233], v[40:41]
	v_pk_add_f32 v[232:233], v[232:233], v[42:43]
	v_pk_add_f32 v[232:233], v[232:233], v[44:45]
	v_pk_add_f32 v[232:233], v[232:233], v[46:47]
	ds_read2_b32 v[32:33], v115 offset0:136 offset1:137
	ds_read2_b32 v[34:35], v115 offset0:138 offset1:139
	ds_read2_b32 v[36:37], v115 offset0:144 offset1:145
	ds_read2_b32 v[38:39], v115 offset0:146 offset1:147
	ds_read2_b32 v[40:41], v115 offset0:153 offset1:154
	ds_read2_b32 v[42:43], v115 offset0:155 offset1:156
	ds_read2_b32 v[44:45], v115 offset0:161 offset1:162
	ds_read2_b32 v[46:47], v115 offset0:163 offset1:164
	s_waitcnt lgkmcnt(15)
	v_mfma_f32_32x32x16_bf16 v[0:15], v[64:67], v[72:75], v[0:15]
	v_mfma_f32_32x32x16_bf16 v[16:31], v[64:67], v[76:79], v[16:31]
	v_mfma_f32_32x32x16_bf16 v[0:15], v[68:71], v[220:223], v[0:15]
	v_mfma_f32_32x32x16_bf16 v[16:31], v[68:71], v[224:227], v[16:31]
	s_add_i32 s90, s67, 352
	v_add_u32_e32 v80, s90, v235
	v_add_u32_e32 v83, s90, v236
	v_add_u32_e32 v99, s90, v237
	v_add_u32_e32 v253, s90, v238
	v_add_u32_e32 v254, s90, v100
	v_add_u32_e32 v255, s90, v149
	v_med3_i32 v80, v80, 0, s99
	v_med3_i32 v83, v83, 0, s99
	v_med3_i32 v99, v99, 0, s99
	v_med3_i32 v253, v253, 0, s99
	v_med3_i32 v254, v254, 0, s99
	v_med3_i32 v255, v255, 0, s99
	v_mad_u32_u24 v80, v80, s100, v252
	v_mad_u32_u24 v83, v83, s100, v252
	v_mad_u32_u24 v99, v99, s100, v252
	v_mad_u32_u24 v253, v253, s100, v252
	v_mad_u32_u24 v254, v254, s100, v153
	v_mad_u32_u24 v255, v255, s100, v153
	global_load_dwordx4 v[156:159], v80, s[82:83]
	global_load_dwordx4 v[160:163], v83, s[82:83]
	global_load_dwordx4 v[164:167], v99, s[82:83]
	global_load_dwordx4 v[168:171], v253, s[82:83]
	global_load_dwordx4 v[172:175], v254, s[82:83] offset:768
	global_load_dwordx4 v[176:179], v255, s[82:83] offset:768
	global_load_dwordx4 v[180:183], v254, s[82:83] offset:832
	global_load_dwordx4 v[184:187], v255, s[82:83] offset:832
	s_waitcnt lgkmcnt(0)
	v_mfma_f32_32x32x16_bf16 v[32:47], v[188:191], v[48:51], v[32:47]
	ds_read_b64_tr_b16 v[72:73], v231
	ds_read_b64_tr_b16 v[74:75], v231 offset:512
	ds_read_b64_tr_b16 v[76:77], v231 offset:2048
	ds_read_b64_tr_b16 v[78:79], v231 offset:2560
	ds_read_b64_tr_b16 v[220:221], v231 offset:1024
	ds_read_b64_tr_b16 v[222:223], v231 offset:1536
	ds_read_b64_tr_b16 v[224:225], v231 offset:3072
	ds_read_b64_tr_b16 v[226:227], v231 offset:3584
	s_waitcnt vmcnt(8)
	ds_write_b128 v247, v[116:119]
	ds_write_b128 v247, v[120:123] offset:1024
	ds_write_b128 v111, v[124:127] offset:2048
	ds_write_b128 v111, v[128:131] offset:3072
	ds_read_b128 v[116:119], v248
	ds_read_b128 v[120:123], v249
	ds_read_b128 v[124:127], v250
	ds_read_b128 v[128:131], v251
	ds_write_b128 v112, v[132:135]
	ds_write_b128 v112, v[136:139] offset:1024
	ds_write_b128 v112, v[140:143] offset:2048
	ds_write_b128 v112, v[144:147] offset:3072
	v_mfma_f32_32x32x16_bf16 v[32:47], v[192:195], v[52:55], v[32:47]
	v_mfma_f32_32x32x16_bf16 v[32:47], v[196:199], v[56:59], v[32:47]
	v_mfma_f32_32x32x16_bf16 v[32:47], v[200:203], v[60:63], v[32:47]
	s_nop 11
	v_exp_f32_e32 v32, v32
	v_exp_f32_e32 v33, v33
	v_exp_f32_e32 v34, v34
	v_exp_f32_e32 v35, v35
	v_exp_f32_e32 v36, v36
	v_exp_f32_e32 v37, v37
	v_exp_f32_e32 v38, v38
	v_exp_f32_e32 v39, v39
	v_exp_f32_e32 v40, v40
	v_exp_f32_e32 v41, v41
	v_exp_f32_e32 v42, v42
	v_exp_f32_e32 v43, v43
	v_exp_f32_e32 v44, v44
	v_exp_f32_e32 v45, v45
	v_exp_f32_e32 v46, v46
	v_exp_f32_e32 v47, v47
	s_add_i32 s90, s67, 288
	v_add_u32_e32 v84, s90, v107
	v_add_u32_e32 v85, 0, v84
	v_add_u32_e32 v86, 1, v84
	v_add_u32_e32 v87, 2, v84
	v_add_u32_e32 v88, 3, v84
	v_cmp_gt_u32_e64 s[30:31], s98, v85
	v_cmp_gt_u32_e64 s[36:37], s98, v86
	v_cmp_gt_u32_e64 s[78:79], s98, v87
	v_cmp_gt_u32_e64 s[50:51], s98, v88
	v_cndmask_b32_e64 v32, 0, v32, s[30:31]
	v_add_u32_e32 v85, 8, v84
	v_cmp_gt_u32_e64 s[30:31], s98, v85
	v_cndmask_b32_e64 v33, 0, v33, s[36:37]
	v_add_u32_e32 v86, 9, v84
	v_cmp_gt_u32_e64 s[36:37], s98, v86
	v_cndmask_b32_e64 v34, 0, v34, s[78:79]
	v_add_u32_e32 v87, 10, v84
	v_cmp_gt_u32_e64 s[78:79], s98, v87
	v_cndmask_b32_e64 v35, 0, v35, s[50:51]
	v_add_u32_e32 v88, 11, v84
	v_cmp_gt_u32_e64 s[50:51], s98, v88
	v_cndmask_b32_e64 v36, 0, v36, s[30:31]
	v_add_u32_e32 v85, 16, v84
	v_cmp_gt_u32_e64 s[30:31], s98, v85
	v_cndmask_b32_e64 v37, 0, v37, s[36:37]
	v_add_u32_e32 v86, 17, v84
	v_cmp_gt_u32_e64 s[36:37], s98, v86
	v_cndmask_b32_e64 v38, 0, v38, s[78:79]
	v_add_u32_e32 v87, 18, v84
	v_cmp_gt_u32_e64 s[78:79], s98, v87
	v_cndmask_b32_e64 v39, 0, v39, s[50:51]
	v_add_u32_e32 v88, 19, v84
	v_cmp_gt_u32_e64 s[50:51], s98, v88
	v_cndmask_b32_e64 v40, 0, v40, s[30:31]
	v_add_u32_e32 v85, 24, v84
	v_cmp_gt_u32_e64 s[30:31], s98, v85
	v_cndmask_b32_e64 v41, 0, v41, s[36:37]
	v_add_u32_e32 v86, 25, v84
	v_cmp_gt_u32_e64 s[36:37], s98, v86
	v_cndmask_b32_e64 v42, 0, v42, s[78:79]
	v_add_u32_e32 v87, 26, v84
	v_cmp_gt_u32_e64 s[78:79], s98, v87
	v_cndmask_b32_e64 v43, 0, v43, s[50:51]
	v_add_u32_e32 v88, 27, v84
	v_cmp_gt_u32_e64 s[50:51], s98, v88
	v_nop
	v_cndmask_b32_e64 v44, 0, v44, s[30:31]
	v_cndmask_b32_e64 v45, 0, v45, s[36:37]
	v_cndmask_b32_e64 v46, 0, v46, s[78:79]
	v_cndmask_b32_e64 v47, 0, v47, s[50:51]
	v_cvt_pk_bf16_f32 v64, v32, v33
	v_cvt_pk_bf16_f32 v65, v34, v35
	v_cvt_pk_bf16_f32 v66, v36, v37
	v_cvt_pk_bf16_f32 v67, v38, v39
	v_cvt_pk_bf16_f32 v68, v40, v41
	v_cvt_pk_bf16_f32 v69, v42, v43
	v_cvt_pk_bf16_f32 v70, v44, v45
	v_cvt_pk_bf16_f32 v71, v46, v47
	v_pk_add_f32 v[232:233], v[232:233], v[32:33]
	v_pk_add_f32 v[232:233], v[232:233], v[34:35]
	v_pk_add_f32 v[232:233], v[232:233], v[36:37]
	v_pk_add_f32 v[232:233], v[232:233], v[38:39]
	v_pk_add_f32 v[232:233], v[232:233], v[40:41]
	v_pk_add_f32 v[232:233], v[232:233], v[42:43]
	v_pk_add_f32 v[232:233], v[232:233], v[44:45]
	v_pk_add_f32 v[232:233], v[232:233], v[46:47]
	ds_read2_b32 v[32:33], v115 offset0:170 offset1:171
	ds_read2_b32 v[34:35], v115 offset0:172 offset1:173
	ds_read2_b32 v[36:37], v115 offset0:178 offset1:179
	ds_read2_b32 v[38:39], v115 offset0:180 offset1:181
	ds_read2_b32 v[40:41], v115 offset0:187 offset1:188
	ds_read2_b32 v[42:43], v115 offset0:189 offset1:190
	ds_read2_b32 v[44:45], v115 offset0:195 offset1:196
	ds_read2_b32 v[46:47], v115 offset0:197 offset1:198
	s_waitcnt lgkmcnt(15)
	v_mfma_f32_32x32x16_bf16 v[0:15], v[64:67], v[72:75], v[0:15]
	v_mfma_f32_32x32x16_bf16 v[16:31], v[64:67], v[76:79], v[16:31]
	v_mfma_f32_32x32x16_bf16 v[0:15], v[68:71], v[220:223], v[0:15]
	v_mfma_f32_32x32x16_bf16 v[16:31], v[68:71], v[224:227], v[16:31]
	s_add_i32 s90, s67, 384
	v_add_u32_e32 v80, s90, v235
	v_add_u32_e32 v83, s90, v236
	v_add_u32_e32 v99, s90, v237
	v_add_u32_e32 v253, s90, v238
	v_add_u32_e32 v254, s90, v100
	v_add_u32_e32 v255, s90, v149
	v_med3_i32 v80, v80, 0, s99
	v_med3_i32 v83, v83, 0, s99
	v_med3_i32 v99, v99, 0, s99
	v_med3_i32 v253, v253, 0, s99
	v_med3_i32 v254, v254, 0, s99
	v_med3_i32 v255, v255, 0, s99
	v_mad_u32_u24 v80, v80, s100, v252
	v_mad_u32_u24 v83, v83, s100, v252
	v_mad_u32_u24 v99, v99, s100, v252
	v_mad_u32_u24 v253, v253, s100, v252
	v_mad_u32_u24 v254, v254, s100, v153
	v_mad_u32_u24 v255, v255, s100, v153
	global_load_dwordx4 v[188:191], v80, s[82:83]
	global_load_dwordx4 v[192:195], v83, s[82:83]
	global_load_dwordx4 v[196:199], v99, s[82:83]
	global_load_dwordx4 v[200:203], v253, s[82:83]
	global_load_dwordx4 v[204:207], v254, s[82:83] offset:768
	global_load_dwordx4 v[208:211], v255, s[82:83] offset:768
	global_load_dwordx4 v[212:215], v254, s[82:83] offset:832
	global_load_dwordx4 v[216:219], v255, s[82:83] offset:832
	s_waitcnt lgkmcnt(0)
	v_mfma_f32_32x32x16_bf16 v[32:47], v[116:119], v[48:51], v[32:47]
	ds_read_b64_tr_b16 v[72:73], v231
	ds_read_b64_tr_b16 v[74:75], v231 offset:512
	ds_read_b64_tr_b16 v[76:77], v231 offset:2048
	ds_read_b64_tr_b16 v[78:79], v231 offset:2560
	ds_read_b64_tr_b16 v[220:221], v231 offset:1024
	ds_read_b64_tr_b16 v[222:223], v231 offset:1536
	ds_read_b64_tr_b16 v[224:225], v231 offset:3072
	ds_read_b64_tr_b16 v[226:227], v231 offset:3584
	s_waitcnt vmcnt(8)
	ds_write_b128 v247, v[156:159]
	ds_write_b128 v247, v[160:163] offset:1024
	ds_write_b128 v111, v[164:167] offset:2048
	ds_write_b128 v111, v[168:171] offset:3072
	ds_read_b128 v[156:159], v248
	ds_read_b128 v[160:163], v249
	ds_read_b128 v[164:167], v250
	ds_read_b128 v[168:171], v251
	ds_write_b128 v112, v[172:175]
	ds_write_b128 v112, v[176:179] offset:1024
	ds_write_b128 v112, v[180:183] offset:2048
	ds_write_b128 v112, v[184:187] offset:3072
	v_mfma_f32_32x32x16_bf16 v[32:47], v[120:123], v[52:55], v[32:47]
	v_mfma_f32_32x32x16_bf16 v[32:47], v[124:127], v[56:59], v[32:47]
	v_mfma_f32_32x32x16_bf16 v[32:47], v[128:131], v[60:63], v[32:47]
	s_nop 11
	v_exp_f32_e32 v32, v32
	v_exp_f32_e32 v33, v33
	v_exp_f32_e32 v34, v34
	v_exp_f32_e32 v35, v35
	v_exp_f32_e32 v36, v36
	v_exp_f32_e32 v37, v37
	v_exp_f32_e32 v38, v38
	v_exp_f32_e32 v39, v39
	v_exp_f32_e32 v40, v40
	v_exp_f32_e32 v41, v41
	v_exp_f32_e32 v42, v42
	v_exp_f32_e32 v43, v43
	v_exp_f32_e32 v44, v44
	v_exp_f32_e32 v45, v45
	v_exp_f32_e32 v46, v46
	v_exp_f32_e32 v47, v47
	s_add_i32 s90, s67, 320
	v_add_u32_e32 v84, s90, v107
	v_add_u32_e32 v85, 0, v84
	v_add_u32_e32 v86, 1, v84
	v_add_u32_e32 v87, 2, v84
	v_add_u32_e32 v88, 3, v84
	v_cmp_gt_u32_e64 s[30:31], s98, v85
	v_cmp_gt_u32_e64 s[36:37], s98, v86
	v_cmp_gt_u32_e64 s[78:79], s98, v87
	v_cmp_gt_u32_e64 s[50:51], s98, v88
	v_cndmask_b32_e64 v32, 0, v32, s[30:31]
	v_add_u32_e32 v85, 8, v84
	v_cmp_gt_u32_e64 s[30:31], s98, v85
	v_cndmask_b32_e64 v33, 0, v33, s[36:37]
	v_add_u32_e32 v86, 9, v84
	v_cmp_gt_u32_e64 s[36:37], s98, v86
	v_cndmask_b32_e64 v34, 0, v34, s[78:79]
	v_add_u32_e32 v87, 10, v84
	v_cmp_gt_u32_e64 s[78:79], s98, v87
	v_cndmask_b32_e64 v35, 0, v35, s[50:51]
	v_add_u32_e32 v88, 11, v84
	v_cmp_gt_u32_e64 s[50:51], s98, v88
	v_cndmask_b32_e64 v36, 0, v36, s[30:31]
	v_add_u32_e32 v85, 16, v84
	v_cmp_gt_u32_e64 s[30:31], s98, v85
	v_cndmask_b32_e64 v37, 0, v37, s[36:37]
	v_add_u32_e32 v86, 17, v84
	v_cmp_gt_u32_e64 s[36:37], s98, v86
	v_cndmask_b32_e64 v38, 0, v38, s[78:79]
	v_add_u32_e32 v87, 18, v84
	v_cmp_gt_u32_e64 s[78:79], s98, v87
	v_cndmask_b32_e64 v39, 0, v39, s[50:51]
	v_add_u32_e32 v88, 19, v84
	v_cmp_gt_u32_e64 s[50:51], s98, v88
	v_cndmask_b32_e64 v40, 0, v40, s[30:31]
	v_add_u32_e32 v85, 24, v84
	v_cmp_gt_u32_e64 s[30:31], s98, v85
	v_cndmask_b32_e64 v41, 0, v41, s[36:37]
	v_add_u32_e32 v86, 25, v84
	v_cmp_gt_u32_e64 s[36:37], s98, v86
	v_cndmask_b32_e64 v42, 0, v42, s[78:79]
	v_add_u32_e32 v87, 26, v84
	v_cmp_gt_u32_e64 s[78:79], s98, v87
	v_cndmask_b32_e64 v43, 0, v43, s[50:51]
	v_add_u32_e32 v88, 27, v84
	v_cmp_gt_u32_e64 s[50:51], s98, v88
	v_nop
	v_cndmask_b32_e64 v44, 0, v44, s[30:31]
	v_cndmask_b32_e64 v45, 0, v45, s[36:37]
	v_cndmask_b32_e64 v46, 0, v46, s[78:79]
	v_cndmask_b32_e64 v47, 0, v47, s[50:51]
	v_cvt_pk_bf16_f32 v64, v32, v33
	v_cvt_pk_bf16_f32 v65, v34, v35
	v_cvt_pk_bf16_f32 v66, v36, v37
	v_cvt_pk_bf16_f32 v67, v38, v39
	v_cvt_pk_bf16_f32 v68, v40, v41
	v_cvt_pk_bf16_f32 v69, v42, v43
	v_cvt_pk_bf16_f32 v70, v44, v45
	v_cvt_pk_bf16_f32 v71, v46, v47
	v_pk_add_f32 v[232:233], v[232:233], v[32:33]
	v_pk_add_f32 v[232:233], v[232:233], v[34:35]
	v_pk_add_f32 v[232:233], v[232:233], v[36:37]
	v_pk_add_f32 v[232:233], v[232:233], v[38:39]
	v_pk_add_f32 v[232:233], v[232:233], v[40:41]
	v_pk_add_f32 v[232:233], v[232:233], v[42:43]
	v_pk_add_f32 v[232:233], v[232:233], v[44:45]
	v_pk_add_f32 v[232:233], v[232:233], v[46:47]
	ds_read2_b32 v[32:33], v115 offset0:204 offset1:205
	ds_read2_b32 v[34:35], v115 offset0:206 offset1:207
	ds_read2_b32 v[36:37], v115 offset0:212 offset1:213
	ds_read2_b32 v[38:39], v115 offset0:214 offset1:215
	ds_read2_b32 v[40:41], v115 offset0:221 offset1:222
	ds_read2_b32 v[42:43], v115 offset0:223 offset1:224
	ds_read2_b32 v[44:45], v115 offset0:229 offset1:230
	ds_read2_b32 v[46:47], v115 offset0:231 offset1:232
	s_waitcnt lgkmcnt(15)
	v_mfma_f32_32x32x16_bf16 v[0:15], v[64:67], v[72:75], v[0:15]
	v_mfma_f32_32x32x16_bf16 v[16:31], v[64:67], v[76:79], v[16:31]
	v_mfma_f32_32x32x16_bf16 v[0:15], v[68:71], v[220:223], v[0:15]
	v_mfma_f32_32x32x16_bf16 v[16:31], v[68:71], v[224:227], v[16:31]
	s_add_i32 s90, s67, 416
	v_add_u32_e32 v80, s90, v235
	v_add_u32_e32 v83, s90, v236
	v_add_u32_e32 v99, s90, v237
	v_add_u32_e32 v253, s90, v238
	v_add_u32_e32 v254, s90, v100
	v_add_u32_e32 v255, s90, v149
	v_med3_i32 v80, v80, 0, s99
	v_med3_i32 v83, v83, 0, s99
	v_med3_i32 v99, v99, 0, s99
	v_med3_i32 v253, v253, 0, s99
	v_med3_i32 v254, v254, 0, s99
	v_med3_i32 v255, v255, 0, s99
	v_mad_u32_u24 v80, v80, s100, v252
	v_mad_u32_u24 v83, v83, s100, v252
	v_mad_u32_u24 v99, v99, s100, v252
	v_mad_u32_u24 v253, v253, s100, v252
	v_mad_u32_u24 v254, v254, s100, v153
	v_mad_u32_u24 v255, v255, s100, v153
	global_load_dwordx4 v[116:119], v80, s[82:83]
	global_load_dwordx4 v[120:123], v83, s[82:83]
	global_load_dwordx4 v[124:127], v99, s[82:83]
	global_load_dwordx4 v[128:131], v253, s[82:83]
	global_load_dwordx4 v[132:135], v254, s[82:83] offset:768
	global_load_dwordx4 v[136:139], v255, s[82:83] offset:768
	global_load_dwordx4 v[140:143], v254, s[82:83] offset:832
	global_load_dwordx4 v[144:147], v255, s[82:83] offset:832
	s_waitcnt lgkmcnt(0)
	v_mfma_f32_32x32x16_bf16 v[32:47], v[156:159], v[48:51], v[32:47]
	ds_read_b64_tr_b16 v[72:73], v231
	ds_read_b64_tr_b16 v[74:75], v231 offset:512
	ds_read_b64_tr_b16 v[76:77], v231 offset:2048
	ds_read_b64_tr_b16 v[78:79], v231 offset:2560
	ds_read_b64_tr_b16 v[220:221], v231 offset:1024
	ds_read_b64_tr_b16 v[222:223], v231 offset:1536
	ds_read_b64_tr_b16 v[224:225], v231 offset:3072
	ds_read_b64_tr_b16 v[226:227], v231 offset:3584
	s_waitcnt vmcnt(8)
	ds_write_b128 v247, v[188:191]
	ds_write_b128 v247, v[192:195] offset:1024
	ds_write_b128 v111, v[196:199] offset:2048
	ds_write_b128 v111, v[200:203] offset:3072
	ds_read_b128 v[188:191], v248
	ds_read_b128 v[192:195], v249
	ds_read_b128 v[196:199], v250
	ds_read_b128 v[200:203], v251
	ds_write_b128 v112, v[204:207]
	ds_write_b128 v112, v[208:211] offset:1024
	ds_write_b128 v112, v[212:215] offset:2048
	ds_write_b128 v112, v[216:219] offset:3072
	v_mfma_f32_32x32x16_bf16 v[32:47], v[160:163], v[52:55], v[32:47]
	v_mfma_f32_32x32x16_bf16 v[32:47], v[164:167], v[56:59], v[32:47]
	v_mfma_f32_32x32x16_bf16 v[32:47], v[168:171], v[60:63], v[32:47]
	s_nop 11
	v_exp_f32_e32 v32, v32
	v_exp_f32_e32 v33, v33
	v_exp_f32_e32 v34, v34
	v_exp_f32_e32 v35, v35
	v_exp_f32_e32 v36, v36
	v_exp_f32_e32 v37, v37
	v_exp_f32_e32 v38, v38
	v_exp_f32_e32 v39, v39
	v_exp_f32_e32 v40, v40
	v_exp_f32_e32 v41, v41
	v_exp_f32_e32 v42, v42
	v_exp_f32_e32 v43, v43
	v_exp_f32_e32 v44, v44
	v_exp_f32_e32 v45, v45
	v_exp_f32_e32 v46, v46
	v_exp_f32_e32 v47, v47
	s_add_i32 s90, s67, 352
	v_add_u32_e32 v84, s90, v107
	v_add_u32_e32 v85, 0, v84
	v_add_u32_e32 v86, 1, v84
	v_add_u32_e32 v87, 2, v84
	v_add_u32_e32 v88, 3, v84
	v_cmp_gt_u32_e64 s[30:31], s98, v85
	v_cmp_gt_u32_e64 s[36:37], s98, v86
	v_cmp_gt_u32_e64 s[78:79], s98, v87
	v_cmp_gt_u32_e64 s[50:51], s98, v88
	v_cndmask_b32_e64 v32, 0, v32, s[30:31]
	v_add_u32_e32 v85, 8, v84
	v_cmp_gt_u32_e64 s[30:31], s98, v85
	v_cndmask_b32_e64 v33, 0, v33, s[36:37]
	v_add_u32_e32 v86, 9, v84
	v_cmp_gt_u32_e64 s[36:37], s98, v86
	v_cndmask_b32_e64 v34, 0, v34, s[78:79]
	v_add_u32_e32 v87, 10, v84
	v_cmp_gt_u32_e64 s[78:79], s98, v87
	v_cndmask_b32_e64 v35, 0, v35, s[50:51]
	v_add_u32_e32 v88, 11, v84
	v_cmp_gt_u32_e64 s[50:51], s98, v88
	v_cndmask_b32_e64 v36, 0, v36, s[30:31]
	v_add_u32_e32 v85, 16, v84
	v_cmp_gt_u32_e64 s[30:31], s98, v85
	v_cndmask_b32_e64 v37, 0, v37, s[36:37]
	v_add_u32_e32 v86, 17, v84
	v_cmp_gt_u32_e64 s[36:37], s98, v86
	v_cndmask_b32_e64 v38, 0, v38, s[78:79]
	v_add_u32_e32 v87, 18, v84
	v_cmp_gt_u32_e64 s[78:79], s98, v87
	v_cndmask_b32_e64 v39, 0, v39, s[50:51]
	v_add_u32_e32 v88, 19, v84
	v_cmp_gt_u32_e64 s[50:51], s98, v88
	v_cndmask_b32_e64 v40, 0, v40, s[30:31]
	v_add_u32_e32 v85, 24, v84
	v_cmp_gt_u32_e64 s[30:31], s98, v85
	v_cndmask_b32_e64 v41, 0, v41, s[36:37]
	v_add_u32_e32 v86, 25, v84
	v_cmp_gt_u32_e64 s[36:37], s98, v86
	v_cndmask_b32_e64 v42, 0, v42, s[78:79]
	v_add_u32_e32 v87, 26, v84
	v_cmp_gt_u32_e64 s[78:79], s98, v87
	v_cndmask_b32_e64 v43, 0, v43, s[50:51]
	v_add_u32_e32 v88, 27, v84
	v_cmp_gt_u32_e64 s[50:51], s98, v88
	v_nop
	v_cndmask_b32_e64 v44, 0, v44, s[30:31]
	v_cndmask_b32_e64 v45, 0, v45, s[36:37]
	v_cndmask_b32_e64 v46, 0, v46, s[78:79]
	v_cndmask_b32_e64 v47, 0, v47, s[50:51]
	v_cvt_pk_bf16_f32 v64, v32, v33
	v_cvt_pk_bf16_f32 v65, v34, v35
	v_cvt_pk_bf16_f32 v66, v36, v37
	v_cvt_pk_bf16_f32 v67, v38, v39
	v_cvt_pk_bf16_f32 v68, v40, v41
	v_cvt_pk_bf16_f32 v69, v42, v43
	v_cvt_pk_bf16_f32 v70, v44, v45
	v_cvt_pk_bf16_f32 v71, v46, v47
	v_pk_add_f32 v[232:233], v[232:233], v[32:33]
	v_pk_add_f32 v[232:233], v[232:233], v[34:35]
	v_pk_add_f32 v[232:233], v[232:233], v[36:37]
	v_pk_add_f32 v[232:233], v[232:233], v[38:39]
	v_pk_add_f32 v[232:233], v[232:233], v[40:41]
	v_pk_add_f32 v[232:233], v[232:233], v[42:43]
	v_pk_add_f32 v[232:233], v[232:233], v[44:45]
	v_pk_add_f32 v[232:233], v[232:233], v[46:47]
	v_add_u32_e32 v115, 952, v115
	ds_read2_b32 v[32:33], v115 offset0:0 offset1:1
	ds_read2_b32 v[34:35], v115 offset0:2 offset1:3
	ds_read2_b32 v[36:37], v115 offset0:8 offset1:9
	ds_read2_b32 v[38:39], v115 offset0:10 offset1:11
	ds_read2_b32 v[40:41], v115 offset0:17 offset1:18
	ds_read2_b32 v[42:43], v115 offset0:19 offset1:20
	ds_read2_b32 v[44:45], v115 offset0:25 offset1:26
	ds_read2_b32 v[46:47], v115 offset0:27 offset1:28
	s_waitcnt lgkmcnt(15)
	v_mfma_f32_32x32x16_bf16 v[0:15], v[64:67], v[72:75], v[0:15]
	v_mfma_f32_32x32x16_bf16 v[16:31], v[64:67], v[76:79], v[16:31]
	v_mfma_f32_32x32x16_bf16 v[0:15], v[68:71], v[220:223], v[0:15]
	v_mfma_f32_32x32x16_bf16 v[16:31], v[68:71], v[224:227], v[16:31]
	s_add_i32 s90, s67, 448
	v_add_u32_e32 v80, s90, v235
	v_add_u32_e32 v83, s90, v236
	v_add_u32_e32 v99, s90, v237
	v_add_u32_e32 v253, s90, v238
	v_add_u32_e32 v254, s90, v100
	v_add_u32_e32 v255, s90, v149
	v_med3_i32 v80, v80, 0, s99
	v_med3_i32 v83, v83, 0, s99
	v_med3_i32 v99, v99, 0, s99
	v_med3_i32 v253, v253, 0, s99
	v_med3_i32 v254, v254, 0, s99
	v_med3_i32 v255, v255, 0, s99
	v_mad_u32_u24 v80, v80, s100, v252
	v_mad_u32_u24 v83, v83, s100, v252
	v_mad_u32_u24 v99, v99, s100, v252
	v_mad_u32_u24 v253, v253, s100, v252
	v_mad_u32_u24 v254, v254, s100, v153
	v_mad_u32_u24 v255, v255, s100, v153
	global_load_dwordx4 v[156:159], v80, s[82:83]
	global_load_dwordx4 v[160:163], v83, s[82:83]
	global_load_dwordx4 v[164:167], v99, s[82:83]
	global_load_dwordx4 v[168:171], v253, s[82:83]
	global_load_dwordx4 v[172:175], v254, s[82:83] offset:768
	global_load_dwordx4 v[176:179], v255, s[82:83] offset:768
	global_load_dwordx4 v[180:183], v254, s[82:83] offset:832
	global_load_dwordx4 v[184:187], v255, s[82:83] offset:832
	s_waitcnt lgkmcnt(0)
	v_mfma_f32_32x32x16_bf16 v[32:47], v[188:191], v[48:51], v[32:47]
	ds_read_b64_tr_b16 v[72:73], v231
	ds_read_b64_tr_b16 v[74:75], v231 offset:512
	ds_read_b64_tr_b16 v[76:77], v231 offset:2048
	ds_read_b64_tr_b16 v[78:79], v231 offset:2560
	ds_read_b64_tr_b16 v[220:221], v231 offset:1024
	ds_read_b64_tr_b16 v[222:223], v231 offset:1536
	ds_read_b64_tr_b16 v[224:225], v231 offset:3072
	ds_read_b64_tr_b16 v[226:227], v231 offset:3584
	s_waitcnt vmcnt(8)
	ds_write_b128 v247, v[116:119]
	ds_write_b128 v247, v[120:123] offset:1024
	ds_write_b128 v111, v[124:127] offset:2048
	ds_write_b128 v111, v[128:131] offset:3072
	ds_read_b128 v[116:119], v248
	ds_read_b128 v[120:123], v249
	ds_read_b128 v[124:127], v250
	ds_read_b128 v[128:131], v251
	ds_write_b128 v112, v[132:135]
	ds_write_b128 v112, v[136:139] offset:1024
	ds_write_b128 v112, v[140:143] offset:2048
	ds_write_b128 v112, v[144:147] offset:3072
	v_mfma_f32_32x32x16_bf16 v[32:47], v[192:195], v[52:55], v[32:47]
	v_mfma_f32_32x32x16_bf16 v[32:47], v[196:199], v[56:59], v[32:47]
	v_mfma_f32_32x32x16_bf16 v[32:47], v[200:203], v[60:63], v[32:47]
	s_nop 11
	v_exp_f32_e32 v32, v32
	v_exp_f32_e32 v33, v33
	v_exp_f32_e32 v34, v34
	v_exp_f32_e32 v35, v35
	v_exp_f32_e32 v36, v36
	v_exp_f32_e32 v37, v37
	v_exp_f32_e32 v38, v38
	v_exp_f32_e32 v39, v39
	v_exp_f32_e32 v40, v40
	v_exp_f32_e32 v41, v41
	v_exp_f32_e32 v42, v42
	v_exp_f32_e32 v43, v43
	v_exp_f32_e32 v44, v44
	v_exp_f32_e32 v45, v45
	v_exp_f32_e32 v46, v46
	v_exp_f32_e32 v47, v47
	s_add_i32 s90, s67, 384
	v_add_u32_e32 v84, s90, v107
	v_add_u32_e32 v85, 0, v84
	v_add_u32_e32 v86, 1, v84
	v_add_u32_e32 v87, 2, v84
	v_add_u32_e32 v88, 3, v84
	v_cmp_gt_u32_e64 s[30:31], s98, v85
	v_cmp_gt_u32_e64 s[36:37], s98, v86
	v_cmp_gt_u32_e64 s[78:79], s98, v87
	v_cmp_gt_u32_e64 s[50:51], s98, v88
	v_cndmask_b32_e64 v32, 0, v32, s[30:31]
	v_add_u32_e32 v85, 8, v84
	v_cmp_gt_u32_e64 s[30:31], s98, v85
	v_cndmask_b32_e64 v33, 0, v33, s[36:37]
	v_add_u32_e32 v86, 9, v84
	v_cmp_gt_u32_e64 s[36:37], s98, v86
	v_cndmask_b32_e64 v34, 0, v34, s[78:79]
	v_add_u32_e32 v87, 10, v84
	v_cmp_gt_u32_e64 s[78:79], s98, v87
	v_cndmask_b32_e64 v35, 0, v35, s[50:51]
	v_add_u32_e32 v88, 11, v84
	v_cmp_gt_u32_e64 s[50:51], s98, v88
	v_cndmask_b32_e64 v36, 0, v36, s[30:31]
	v_add_u32_e32 v85, 16, v84
	v_cmp_gt_u32_e64 s[30:31], s98, v85
	v_cndmask_b32_e64 v37, 0, v37, s[36:37]
	v_add_u32_e32 v86, 17, v84
	v_cmp_gt_u32_e64 s[36:37], s98, v86
	v_cndmask_b32_e64 v38, 0, v38, s[78:79]
	v_add_u32_e32 v87, 18, v84
	v_cmp_gt_u32_e64 s[78:79], s98, v87
	v_cndmask_b32_e64 v39, 0, v39, s[50:51]
	v_add_u32_e32 v88, 19, v84
	v_cmp_gt_u32_e64 s[50:51], s98, v88
	v_cndmask_b32_e64 v40, 0, v40, s[30:31]
	v_add_u32_e32 v85, 24, v84
	v_cmp_gt_u32_e64 s[30:31], s98, v85
	v_cndmask_b32_e64 v41, 0, v41, s[36:37]
	v_add_u32_e32 v86, 25, v84
	v_cmp_gt_u32_e64 s[36:37], s98, v86
	v_cndmask_b32_e64 v42, 0, v42, s[78:79]
	v_add_u32_e32 v87, 26, v84
	v_cmp_gt_u32_e64 s[78:79], s98, v87
	v_cndmask_b32_e64 v43, 0, v43, s[50:51]
	v_add_u32_e32 v88, 27, v84
	v_cmp_gt_u32_e64 s[50:51], s98, v88
	v_nop
	v_cndmask_b32_e64 v44, 0, v44, s[30:31]
	v_cndmask_b32_e64 v45, 0, v45, s[36:37]
	v_cndmask_b32_e64 v46, 0, v46, s[78:79]
	v_cndmask_b32_e64 v47, 0, v47, s[50:51]
	v_cvt_pk_bf16_f32 v64, v32, v33
	v_cvt_pk_bf16_f32 v65, v34, v35
	v_cvt_pk_bf16_f32 v66, v36, v37
	v_cvt_pk_bf16_f32 v67, v38, v39
	v_cvt_pk_bf16_f32 v68, v40, v41
	v_cvt_pk_bf16_f32 v69, v42, v43
	v_cvt_pk_bf16_f32 v70, v44, v45
	v_cvt_pk_bf16_f32 v71, v46, v47
	v_pk_add_f32 v[232:233], v[232:233], v[32:33]
	v_pk_add_f32 v[232:233], v[232:233], v[34:35]
	v_pk_add_f32 v[232:233], v[232:233], v[36:37]
	v_pk_add_f32 v[232:233], v[232:233], v[38:39]
	v_pk_add_f32 v[232:233], v[232:233], v[40:41]
	v_pk_add_f32 v[232:233], v[232:233], v[42:43]
	v_pk_add_f32 v[232:233], v[232:233], v[44:45]
	v_pk_add_f32 v[232:233], v[232:233], v[46:47]
	ds_read2_b32 v[32:33], v115 offset0:34 offset1:35
	ds_read2_b32 v[34:35], v115 offset0:36 offset1:37
	ds_read2_b32 v[36:37], v115 offset0:42 offset1:43
	ds_read2_b32 v[38:39], v115 offset0:44 offset1:45
	ds_read2_b32 v[40:41], v115 offset0:51 offset1:52
	ds_read2_b32 v[42:43], v115 offset0:53 offset1:54
	ds_read2_b32 v[44:45], v115 offset0:59 offset1:60
	ds_read2_b32 v[46:47], v115 offset0:61 offset1:62
	s_waitcnt lgkmcnt(15)
	v_mfma_f32_32x32x16_bf16 v[0:15], v[64:67], v[72:75], v[0:15]
	v_mfma_f32_32x32x16_bf16 v[16:31], v[64:67], v[76:79], v[16:31]
	v_mfma_f32_32x32x16_bf16 v[0:15], v[68:71], v[220:223], v[0:15]
	v_mfma_f32_32x32x16_bf16 v[16:31], v[68:71], v[224:227], v[16:31]
	s_add_i32 s90, s67, 480
	v_add_u32_e32 v80, s90, v235
	v_add_u32_e32 v83, s90, v236
	v_add_u32_e32 v99, s90, v237
	v_add_u32_e32 v253, s90, v238
	v_add_u32_e32 v254, s90, v100
	v_add_u32_e32 v255, s90, v149
	v_med3_i32 v80, v80, 0, s99
	v_med3_i32 v83, v83, 0, s99
	v_med3_i32 v99, v99, 0, s99
	v_med3_i32 v253, v253, 0, s99
	v_med3_i32 v254, v254, 0, s99
	v_med3_i32 v255, v255, 0, s99
	v_mad_u32_u24 v80, v80, s100, v252
	v_mad_u32_u24 v83, v83, s100, v252
	v_mad_u32_u24 v99, v99, s100, v252
	v_mad_u32_u24 v253, v253, s100, v252
	v_mad_u32_u24 v254, v254, s100, v153
	v_mad_u32_u24 v255, v255, s100, v153
	global_load_dwordx4 v[188:191], v80, s[82:83]
	global_load_dwordx4 v[192:195], v83, s[82:83]
	global_load_dwordx4 v[196:199], v99, s[82:83]
	global_load_dwordx4 v[200:203], v253, s[82:83]
	global_load_dwordx4 v[204:207], v254, s[82:83] offset:768
	global_load_dwordx4 v[208:211], v255, s[82:83] offset:768
	global_load_dwordx4 v[212:215], v254, s[82:83] offset:832
	global_load_dwordx4 v[216:219], v255, s[82:83] offset:832
	s_waitcnt lgkmcnt(0)
	v_mfma_f32_32x32x16_bf16 v[32:47], v[116:119], v[48:51], v[32:47]
	ds_read_b64_tr_b16 v[72:73], v231
	ds_read_b64_tr_b16 v[74:75], v231 offset:512
	ds_read_b64_tr_b16 v[76:77], v231 offset:2048
	ds_read_b64_tr_b16 v[78:79], v231 offset:2560
	ds_read_b64_tr_b16 v[220:221], v231 offset:1024
	ds_read_b64_tr_b16 v[222:223], v231 offset:1536
	ds_read_b64_tr_b16 v[224:225], v231 offset:3072
	ds_read_b64_tr_b16 v[226:227], v231 offset:3584
	s_waitcnt vmcnt(8)
	ds_write_b128 v247, v[156:159]
	ds_write_b128 v247, v[160:163] offset:1024
	ds_write_b128 v111, v[164:167] offset:2048
	ds_write_b128 v111, v[168:171] offset:3072
	ds_read_b128 v[156:159], v248
	ds_read_b128 v[160:163], v249
	ds_read_b128 v[164:167], v250
	ds_read_b128 v[168:171], v251
	ds_write_b128 v112, v[172:175]
	ds_write_b128 v112, v[176:179] offset:1024
	ds_write_b128 v112, v[180:183] offset:2048
	ds_write_b128 v112, v[184:187] offset:3072
	v_mfma_f32_32x32x16_bf16 v[32:47], v[120:123], v[52:55], v[32:47]
	v_mfma_f32_32x32x16_bf16 v[32:47], v[124:127], v[56:59], v[32:47]
	v_mfma_f32_32x32x16_bf16 v[32:47], v[128:131], v[60:63], v[32:47]
	s_nop 11
	v_exp_f32_e32 v32, v32
	v_exp_f32_e32 v33, v33
	v_exp_f32_e32 v34, v34
	v_exp_f32_e32 v35, v35
	v_exp_f32_e32 v36, v36
	v_exp_f32_e32 v37, v37
	v_exp_f32_e32 v38, v38
	v_exp_f32_e32 v39, v39
	v_exp_f32_e32 v40, v40
	v_exp_f32_e32 v41, v41
	v_exp_f32_e32 v42, v42
	v_exp_f32_e32 v43, v43
	v_exp_f32_e32 v44, v44
	v_exp_f32_e32 v45, v45
	v_exp_f32_e32 v46, v46
	v_exp_f32_e32 v47, v47
	s_add_i32 s90, s67, 416
	v_add_u32_e32 v84, s90, v107
	v_add_u32_e32 v85, 0, v84
	v_add_u32_e32 v86, 1, v84
	v_add_u32_e32 v87, 2, v84
	v_add_u32_e32 v88, 3, v84
	v_cmp_gt_u32_e64 s[30:31], s98, v85
	v_cmp_gt_u32_e64 s[36:37], s98, v86
	v_cmp_gt_u32_e64 s[78:79], s98, v87
	v_cmp_gt_u32_e64 s[50:51], s98, v88
	v_cndmask_b32_e64 v32, 0, v32, s[30:31]
	v_add_u32_e32 v85, 8, v84
	v_cmp_gt_u32_e64 s[30:31], s98, v85
	v_cndmask_b32_e64 v33, 0, v33, s[36:37]
	v_add_u32_e32 v86, 9, v84
	v_cmp_gt_u32_e64 s[36:37], s98, v86
	v_cndmask_b32_e64 v34, 0, v34, s[78:79]
	v_add_u32_e32 v87, 10, v84
	v_cmp_gt_u32_e64 s[78:79], s98, v87
	v_cndmask_b32_e64 v35, 0, v35, s[50:51]
	v_add_u32_e32 v88, 11, v84
	v_cmp_gt_u32_e64 s[50:51], s98, v88
	v_cndmask_b32_e64 v36, 0, v36, s[30:31]
	v_add_u32_e32 v85, 16, v84
	v_cmp_gt_u32_e64 s[30:31], s98, v85
	v_cndmask_b32_e64 v37, 0, v37, s[36:37]
	v_add_u32_e32 v86, 17, v84
	v_cmp_gt_u32_e64 s[36:37], s98, v86
	v_cndmask_b32_e64 v38, 0, v38, s[78:79]
	v_add_u32_e32 v87, 18, v84
	v_cmp_gt_u32_e64 s[78:79], s98, v87
	v_cndmask_b32_e64 v39, 0, v39, s[50:51]
	v_add_u32_e32 v88, 19, v84
	v_cmp_gt_u32_e64 s[50:51], s98, v88
	v_cndmask_b32_e64 v40, 0, v40, s[30:31]
	v_add_u32_e32 v85, 24, v84
	v_cmp_gt_u32_e64 s[30:31], s98, v85
	v_cndmask_b32_e64 v41, 0, v41, s[36:37]
	v_add_u32_e32 v86, 25, v84
	v_cmp_gt_u32_e64 s[36:37], s98, v86
	v_cndmask_b32_e64 v42, 0, v42, s[78:79]
	v_add_u32_e32 v87, 26, v84
	v_cmp_gt_u32_e64 s[78:79], s98, v87
	v_cndmask_b32_e64 v43, 0, v43, s[50:51]
	v_add_u32_e32 v88, 27, v84
	v_cmp_gt_u32_e64 s[50:51], s98, v88
	v_nop
	v_cndmask_b32_e64 v44, 0, v44, s[30:31]
	v_cndmask_b32_e64 v45, 0, v45, s[36:37]
	v_cndmask_b32_e64 v46, 0, v46, s[78:79]
	v_cndmask_b32_e64 v47, 0, v47, s[50:51]
	v_cvt_pk_bf16_f32 v64, v32, v33
	v_cvt_pk_bf16_f32 v65, v34, v35
	v_cvt_pk_bf16_f32 v66, v36, v37
	v_cvt_pk_bf16_f32 v67, v38, v39
	v_cvt_pk_bf16_f32 v68, v40, v41
	v_cvt_pk_bf16_f32 v69, v42, v43
	v_cvt_pk_bf16_f32 v70, v44, v45
	v_cvt_pk_bf16_f32 v71, v46, v47
	v_pk_add_f32 v[232:233], v[232:233], v[32:33]
	v_pk_add_f32 v[232:233], v[232:233], v[34:35]
	v_pk_add_f32 v[232:233], v[232:233], v[36:37]
	v_pk_add_f32 v[232:233], v[232:233], v[38:39]
	v_pk_add_f32 v[232:233], v[232:233], v[40:41]
	v_pk_add_f32 v[232:233], v[232:233], v[42:43]
	v_pk_add_f32 v[232:233], v[232:233], v[44:45]
	v_pk_add_f32 v[232:233], v[232:233], v[46:47]
	ds_read2_b32 v[32:33], v115 offset0:68 offset1:69
	ds_read2_b32 v[34:35], v115 offset0:70 offset1:71
	ds_read2_b32 v[36:37], v115 offset0:76 offset1:77
	ds_read2_b32 v[38:39], v115 offset0:78 offset1:79
	ds_read2_b32 v[40:41], v115 offset0:85 offset1:86
	ds_read2_b32 v[42:43], v115 offset0:87 offset1:88
	ds_read2_b32 v[44:45], v115 offset0:93 offset1:94
	ds_read2_b32 v[46:47], v115 offset0:95 offset1:96
	s_waitcnt lgkmcnt(15)
	v_mfma_f32_32x32x16_bf16 v[0:15], v[64:67], v[72:75], v[0:15]
	v_mfma_f32_32x32x16_bf16 v[16:31], v[64:67], v[76:79], v[16:31]
	v_mfma_f32_32x32x16_bf16 v[0:15], v[68:71], v[220:223], v[0:15]
	v_mfma_f32_32x32x16_bf16 v[16:31], v[68:71], v[224:227], v[16:31]
	s_add_i32 s90, s67, 512
	v_add_u32_e32 v80, s90, v235
	v_add_u32_e32 v83, s90, v236
	v_add_u32_e32 v99, s90, v237
	v_add_u32_e32 v253, s90, v238
	v_add_u32_e32 v254, s90, v100
	v_add_u32_e32 v255, s90, v149
	v_med3_i32 v80, v80, 0, s99
	v_med3_i32 v83, v83, 0, s99
	v_med3_i32 v99, v99, 0, s99
	v_med3_i32 v253, v253, 0, s99
	v_med3_i32 v254, v254, 0, s99
	v_med3_i32 v255, v255, 0, s99
	v_mad_u32_u24 v80, v80, s100, v252
	v_mad_u32_u24 v83, v83, s100, v252
	v_mad_u32_u24 v99, v99, s100, v252
	v_mad_u32_u24 v253, v253, s100, v252
	v_mad_u32_u24 v254, v254, s100, v153
	v_mad_u32_u24 v255, v255, s100, v153
	global_load_dwordx4 v[116:119], v80, s[82:83]
	global_load_dwordx4 v[120:123], v83, s[82:83]
	global_load_dwordx4 v[124:127], v99, s[82:83]
	global_load_dwordx4 v[128:131], v253, s[82:83]
	global_load_dwordx4 v[132:135], v254, s[82:83] offset:768
	global_load_dwordx4 v[136:139], v255, s[82:83] offset:768
	global_load_dwordx4 v[140:143], v254, s[82:83] offset:832
	global_load_dwordx4 v[144:147], v255, s[82:83] offset:832
	s_waitcnt lgkmcnt(0)
	v_mfma_f32_32x32x16_bf16 v[32:47], v[156:159], v[48:51], v[32:47]
	ds_read_b64_tr_b16 v[72:73], v231
	ds_read_b64_tr_b16 v[74:75], v231 offset:512
	ds_read_b64_tr_b16 v[76:77], v231 offset:2048
	ds_read_b64_tr_b16 v[78:79], v231 offset:2560
	ds_read_b64_tr_b16 v[220:221], v231 offset:1024
	ds_read_b64_tr_b16 v[222:223], v231 offset:1536
	ds_read_b64_tr_b16 v[224:225], v231 offset:3072
	ds_read_b64_tr_b16 v[226:227], v231 offset:3584
	s_waitcnt vmcnt(8)
	ds_write_b128 v247, v[188:191]
	ds_write_b128 v247, v[192:195] offset:1024
	ds_write_b128 v111, v[196:199] offset:2048
	ds_write_b128 v111, v[200:203] offset:3072
	ds_read_b128 v[188:191], v248
	ds_read_b128 v[192:195], v249
	ds_read_b128 v[196:199], v250
	ds_read_b128 v[200:203], v251
	ds_write_b128 v112, v[204:207]
	ds_write_b128 v112, v[208:211] offset:1024
	ds_write_b128 v112, v[212:215] offset:2048
	ds_write_b128 v112, v[216:219] offset:3072
	v_mfma_f32_32x32x16_bf16 v[32:47], v[160:163], v[52:55], v[32:47]
	v_mfma_f32_32x32x16_bf16 v[32:47], v[164:167], v[56:59], v[32:47]
	v_mfma_f32_32x32x16_bf16 v[32:47], v[168:171], v[60:63], v[32:47]
	s_nop 11
	v_exp_f32_e32 v32, v32
	v_exp_f32_e32 v33, v33
	v_exp_f32_e32 v34, v34
	v_exp_f32_e32 v35, v35
	v_exp_f32_e32 v36, v36
	v_exp_f32_e32 v37, v37
	v_exp_f32_e32 v38, v38
	v_exp_f32_e32 v39, v39
	v_exp_f32_e32 v40, v40
	v_exp_f32_e32 v41, v41
	v_exp_f32_e32 v42, v42
	v_exp_f32_e32 v43, v43
	v_exp_f32_e32 v44, v44
	v_exp_f32_e32 v45, v45
	v_exp_f32_e32 v46, v46
	v_exp_f32_e32 v47, v47
	s_add_i32 s90, s67, 448
	v_add_u32_e32 v84, s90, v107
	v_add_u32_e32 v85, 0, v84
	v_add_u32_e32 v86, 1, v84
	v_add_u32_e32 v87, 2, v84
	v_add_u32_e32 v88, 3, v84
	v_cmp_gt_u32_e64 s[30:31], s98, v85
	v_cmp_gt_u32_e64 s[36:37], s98, v86
	v_cmp_gt_u32_e64 s[78:79], s98, v87
	v_cmp_gt_u32_e64 s[50:51], s98, v88
	v_cndmask_b32_e64 v32, 0, v32, s[30:31]
	v_add_u32_e32 v85, 8, v84
	v_cmp_gt_u32_e64 s[30:31], s98, v85
	v_cndmask_b32_e64 v33, 0, v33, s[36:37]
	v_add_u32_e32 v86, 9, v84
	v_cmp_gt_u32_e64 s[36:37], s98, v86
	v_cndmask_b32_e64 v34, 0, v34, s[78:79]
	v_add_u32_e32 v87, 10, v84
	v_cmp_gt_u32_e64 s[78:79], s98, v87
	v_cndmask_b32_e64 v35, 0, v35, s[50:51]
	v_add_u32_e32 v88, 11, v84
	v_cmp_gt_u32_e64 s[50:51], s98, v88
	v_cndmask_b32_e64 v36, 0, v36, s[30:31]
	v_add_u32_e32 v85, 16, v84
	v_cmp_gt_u32_e64 s[30:31], s98, v85
	v_cndmask_b32_e64 v37, 0, v37, s[36:37]
	v_add_u32_e32 v86, 17, v84
	v_cmp_gt_u32_e64 s[36:37], s98, v86
	v_cndmask_b32_e64 v38, 0, v38, s[78:79]
	v_add_u32_e32 v87, 18, v84
	v_cmp_gt_u32_e64 s[78:79], s98, v87
	v_cndmask_b32_e64 v39, 0, v39, s[50:51]
	v_add_u32_e32 v88, 19, v84
	v_cmp_gt_u32_e64 s[50:51], s98, v88
	v_cndmask_b32_e64 v40, 0, v40, s[30:31]
	v_add_u32_e32 v85, 24, v84
	v_cmp_gt_u32_e64 s[30:31], s98, v85
	v_cndmask_b32_e64 v41, 0, v41, s[36:37]
	v_add_u32_e32 v86, 25, v84
	v_cmp_gt_u32_e64 s[36:37], s98, v86
	v_cndmask_b32_e64 v42, 0, v42, s[78:79]
	v_add_u32_e32 v87, 26, v84
	v_cmp_gt_u32_e64 s[78:79], s98, v87
	v_cndmask_b32_e64 v43, 0, v43, s[50:51]
	v_add_u32_e32 v88, 27, v84
	v_cmp_gt_u32_e64 s[50:51], s98, v88
	v_nop
	v_cndmask_b32_e64 v44, 0, v44, s[30:31]
	v_cndmask_b32_e64 v45, 0, v45, s[36:37]
	v_cndmask_b32_e64 v46, 0, v46, s[78:79]
	v_cndmask_b32_e64 v47, 0, v47, s[50:51]
	v_cvt_pk_bf16_f32 v64, v32, v33
	v_cvt_pk_bf16_f32 v65, v34, v35
	v_cvt_pk_bf16_f32 v66, v36, v37
	v_cvt_pk_bf16_f32 v67, v38, v39
	v_cvt_pk_bf16_f32 v68, v40, v41
	v_cvt_pk_bf16_f32 v69, v42, v43
	v_cvt_pk_bf16_f32 v70, v44, v45
	v_cvt_pk_bf16_f32 v71, v46, v47
	v_pk_add_f32 v[232:233], v[232:233], v[32:33]
	v_pk_add_f32 v[232:233], v[232:233], v[34:35]
	v_pk_add_f32 v[232:233], v[232:233], v[36:37]
	v_pk_add_f32 v[232:233], v[232:233], v[38:39]
	v_pk_add_f32 v[232:233], v[232:233], v[40:41]
	v_pk_add_f32 v[232:233], v[232:233], v[42:43]
	v_pk_add_f32 v[232:233], v[232:233], v[44:45]
	v_pk_add_f32 v[232:233], v[232:233], v[46:47]
	ds_read2_b32 v[32:33], v115 offset0:102 offset1:103
	ds_read2_b32 v[34:35], v115 offset0:104 offset1:105
	ds_read2_b32 v[36:37], v115 offset0:110 offset1:111
	ds_read2_b32 v[38:39], v115 offset0:112 offset1:113
	ds_read2_b32 v[40:41], v115 offset0:119 offset1:120
	ds_read2_b32 v[42:43], v115 offset0:121 offset1:122
	ds_read2_b32 v[44:45], v115 offset0:127 offset1:128
	ds_read2_b32 v[46:47], v115 offset0:129 offset1:130
	s_waitcnt lgkmcnt(15)
	v_mfma_f32_32x32x16_bf16 v[0:15], v[64:67], v[72:75], v[0:15]
	v_mfma_f32_32x32x16_bf16 v[16:31], v[64:67], v[76:79], v[16:31]
	v_mfma_f32_32x32x16_bf16 v[0:15], v[68:71], v[220:223], v[0:15]
	v_mfma_f32_32x32x16_bf16 v[16:31], v[68:71], v[224:227], v[16:31]
	s_add_i32 s90, s67, 544
	v_add_u32_e32 v80, s90, v235
	v_add_u32_e32 v83, s90, v236
	v_add_u32_e32 v99, s90, v237
	v_add_u32_e32 v253, s90, v238
	v_add_u32_e32 v254, s90, v100
	v_add_u32_e32 v255, s90, v149
	v_med3_i32 v80, v80, 0, s99
	v_med3_i32 v83, v83, 0, s99
	v_med3_i32 v99, v99, 0, s99
	v_med3_i32 v253, v253, 0, s99
	v_med3_i32 v254, v254, 0, s99
	v_med3_i32 v255, v255, 0, s99
	v_mad_u32_u24 v80, v80, s100, v252
	v_mad_u32_u24 v83, v83, s100, v252
	v_mad_u32_u24 v99, v99, s100, v252
	v_mad_u32_u24 v253, v253, s100, v252
	v_mad_u32_u24 v254, v254, s100, v153
	v_mad_u32_u24 v255, v255, s100, v153
	global_load_dwordx4 v[156:159], v80, s[82:83]
	global_load_dwordx4 v[160:163], v83, s[82:83]
	global_load_dwordx4 v[164:167], v99, s[82:83]
	global_load_dwordx4 v[168:171], v253, s[82:83]
	global_load_dwordx4 v[172:175], v254, s[82:83] offset:768
	global_load_dwordx4 v[176:179], v255, s[82:83] offset:768
	global_load_dwordx4 v[180:183], v254, s[82:83] offset:832
	global_load_dwordx4 v[184:187], v255, s[82:83] offset:832
	s_waitcnt lgkmcnt(0)
	v_mfma_f32_32x32x16_bf16 v[32:47], v[188:191], v[48:51], v[32:47]
	ds_read_b64_tr_b16 v[72:73], v231
	ds_read_b64_tr_b16 v[74:75], v231 offset:512
	ds_read_b64_tr_b16 v[76:77], v231 offset:2048
	ds_read_b64_tr_b16 v[78:79], v231 offset:2560
	ds_read_b64_tr_b16 v[220:221], v231 offset:1024
	ds_read_b64_tr_b16 v[222:223], v231 offset:1536
	ds_read_b64_tr_b16 v[224:225], v231 offset:3072
	ds_read_b64_tr_b16 v[226:227], v231 offset:3584
	s_waitcnt vmcnt(8)
	ds_write_b128 v247, v[116:119]
	ds_write_b128 v247, v[120:123] offset:1024
	ds_write_b128 v111, v[124:127] offset:2048
	ds_write_b128 v111, v[128:131] offset:3072
	ds_read_b128 v[116:119], v248
	ds_read_b128 v[120:123], v249
	ds_read_b128 v[124:127], v250
	ds_read_b128 v[128:131], v251
	ds_write_b128 v112, v[132:135]
	ds_write_b128 v112, v[136:139] offset:1024
	ds_write_b128 v112, v[140:143] offset:2048
	ds_write_b128 v112, v[144:147] offset:3072
	v_mfma_f32_32x32x16_bf16 v[32:47], v[192:195], v[52:55], v[32:47]
	v_mfma_f32_32x32x16_bf16 v[32:47], v[196:199], v[56:59], v[32:47]
	v_mfma_f32_32x32x16_bf16 v[32:47], v[200:203], v[60:63], v[32:47]
	s_nop 11
	v_exp_f32_e32 v32, v32
	v_exp_f32_e32 v33, v33
	v_exp_f32_e32 v34, v34
	v_exp_f32_e32 v35, v35
	v_exp_f32_e32 v36, v36
	v_exp_f32_e32 v37, v37
	v_exp_f32_e32 v38, v38
	v_exp_f32_e32 v39, v39
	v_exp_f32_e32 v40, v40
	v_exp_f32_e32 v41, v41
	v_exp_f32_e32 v42, v42
	v_exp_f32_e32 v43, v43
	v_exp_f32_e32 v44, v44
	v_exp_f32_e32 v45, v45
	v_exp_f32_e32 v46, v46
	v_exp_f32_e32 v47, v47
	s_add_i32 s90, s67, 480
	v_add_u32_e32 v84, s90, v107
	v_add_u32_e32 v85, 0, v84
	v_add_u32_e32 v86, 1, v84
	v_add_u32_e32 v87, 2, v84
	v_add_u32_e32 v88, 3, v84
	v_cmp_gt_u32_e64 s[30:31], s98, v85
	v_cmp_gt_u32_e64 s[36:37], s98, v86
	v_cmp_gt_u32_e64 s[78:79], s98, v87
	v_cmp_gt_u32_e64 s[50:51], s98, v88
	v_cndmask_b32_e64 v32, 0, v32, s[30:31]
	v_add_u32_e32 v85, 8, v84
	v_cmp_gt_u32_e64 s[30:31], s98, v85
	v_cndmask_b32_e64 v33, 0, v33, s[36:37]
	v_add_u32_e32 v86, 9, v84
	v_cmp_gt_u32_e64 s[36:37], s98, v86
	v_cndmask_b32_e64 v34, 0, v34, s[78:79]
	v_add_u32_e32 v87, 10, v84
	v_cmp_gt_u32_e64 s[78:79], s98, v87
	v_cndmask_b32_e64 v35, 0, v35, s[50:51]
	v_add_u32_e32 v88, 11, v84
	v_cmp_gt_u32_e64 s[50:51], s98, v88
	v_cndmask_b32_e64 v36, 0, v36, s[30:31]
	v_add_u32_e32 v85, 16, v84
	v_cmp_gt_u32_e64 s[30:31], s98, v85
	v_cndmask_b32_e64 v37, 0, v37, s[36:37]
	v_add_u32_e32 v86, 17, v84
	v_cmp_gt_u32_e64 s[36:37], s98, v86
	v_cndmask_b32_e64 v38, 0, v38, s[78:79]
	v_add_u32_e32 v87, 18, v84
	v_cmp_gt_u32_e64 s[78:79], s98, v87
	v_cndmask_b32_e64 v39, 0, v39, s[50:51]
	v_add_u32_e32 v88, 19, v84
	v_cmp_gt_u32_e64 s[50:51], s98, v88
	v_cndmask_b32_e64 v40, 0, v40, s[30:31]
	v_add_u32_e32 v85, 24, v84
	v_cmp_gt_u32_e64 s[30:31], s98, v85
	v_cndmask_b32_e64 v41, 0, v41, s[36:37]
	v_add_u32_e32 v86, 25, v84
	v_cmp_gt_u32_e64 s[36:37], s98, v86
	v_cndmask_b32_e64 v42, 0, v42, s[78:79]
	v_add_u32_e32 v87, 26, v84
	v_cmp_gt_u32_e64 s[78:79], s98, v87
	v_cndmask_b32_e64 v43, 0, v43, s[50:51]
	v_add_u32_e32 v88, 27, v84
	v_cmp_gt_u32_e64 s[50:51], s98, v88
	v_nop
	v_cndmask_b32_e64 v44, 0, v44, s[30:31]
	v_cndmask_b32_e64 v45, 0, v45, s[36:37]
	v_cndmask_b32_e64 v46, 0, v46, s[78:79]
	v_cndmask_b32_e64 v47, 0, v47, s[50:51]
	v_cvt_pk_bf16_f32 v64, v32, v33
	v_cvt_pk_bf16_f32 v65, v34, v35
	v_cvt_pk_bf16_f32 v66, v36, v37
	v_cvt_pk_bf16_f32 v67, v38, v39
	v_cvt_pk_bf16_f32 v68, v40, v41
	v_cvt_pk_bf16_f32 v69, v42, v43
	v_cvt_pk_bf16_f32 v70, v44, v45
	v_cvt_pk_bf16_f32 v71, v46, v47
	v_pk_add_f32 v[232:233], v[232:233], v[32:33]
	v_pk_add_f32 v[232:233], v[232:233], v[34:35]
	v_pk_add_f32 v[232:233], v[232:233], v[36:37]
	v_pk_add_f32 v[232:233], v[232:233], v[38:39]
	v_pk_add_f32 v[232:233], v[232:233], v[40:41]
	v_pk_add_f32 v[232:233], v[232:233], v[42:43]
	v_pk_add_f32 v[232:233], v[232:233], v[44:45]
	v_pk_add_f32 v[232:233], v[232:233], v[46:47]
	ds_read2_b32 v[32:33], v115 offset0:136 offset1:137
	ds_read2_b32 v[34:35], v115 offset0:138 offset1:139
	ds_read2_b32 v[36:37], v115 offset0:144 offset1:145
	ds_read2_b32 v[38:39], v115 offset0:146 offset1:147
	ds_read2_b32 v[40:41], v115 offset0:153 offset1:154
	ds_read2_b32 v[42:43], v115 offset0:155 offset1:156
	ds_read2_b32 v[44:45], v115 offset0:161 offset1:162
	ds_read2_b32 v[46:47], v115 offset0:163 offset1:164
	s_waitcnt lgkmcnt(15)
	v_mfma_f32_32x32x16_bf16 v[0:15], v[64:67], v[72:75], v[0:15]
	v_mfma_f32_32x32x16_bf16 v[16:31], v[64:67], v[76:79], v[16:31]
	v_mfma_f32_32x32x16_bf16 v[0:15], v[68:71], v[220:223], v[0:15]
	v_mfma_f32_32x32x16_bf16 v[16:31], v[68:71], v[224:227], v[16:31]
	s_add_i32 s90, s67, -256
	v_add_u32_e32 v80, s90, v239
	v_add_u32_e32 v83, s90, v240
	v_add_u32_e32 v99, s90, v241
	v_add_u32_e32 v253, s90, v242
	v_add_u32_e32 v254, s90, v101
	v_add_u32_e32 v255, s90, v150
	v_med3_i32 v80, v80, 0, s99
	v_med3_i32 v83, v83, 0, s99
	v_med3_i32 v99, v99, 0, s99
	v_med3_i32 v253, v253, 0, s99
	v_med3_i32 v254, v254, 0, s99
	v_med3_i32 v255, v255, 0, s99
	v_mad_u32_u24 v80, v80, s100, v252
	v_mad_u32_u24 v83, v83, s100, v252
	v_mad_u32_u24 v99, v99, s100, v252
	v_mad_u32_u24 v253, v253, s100, v252
	v_mad_u32_u24 v254, v254, s100, v153
	v_mad_u32_u24 v255, v255, s100, v153
	global_load_dwordx4 v[188:191], v80, s[82:83]
	global_load_dwordx4 v[192:195], v83, s[82:83]
	global_load_dwordx4 v[196:199], v99, s[82:83]
	global_load_dwordx4 v[200:203], v253, s[82:83]
	global_load_dwordx4 v[204:207], v254, s[82:83] offset:768
	global_load_dwordx4 v[208:211], v255, s[82:83] offset:768
	global_load_dwordx4 v[212:215], v254, s[82:83] offset:832
	global_load_dwordx4 v[216:219], v255, s[82:83] offset:832
	s_waitcnt lgkmcnt(0)
	v_mfma_f32_32x32x16_bf16 v[32:47], v[116:119], v[48:51], v[32:47]
	ds_read_b64_tr_b16 v[72:73], v231
	ds_read_b64_tr_b16 v[74:75], v231 offset:512
	ds_read_b64_tr_b16 v[76:77], v231 offset:2048
	ds_read_b64_tr_b16 v[78:79], v231 offset:2560
	ds_read_b64_tr_b16 v[220:221], v231 offset:1024
	ds_read_b64_tr_b16 v[222:223], v231 offset:1536
	ds_read_b64_tr_b16 v[224:225], v231 offset:3072
	ds_read_b64_tr_b16 v[226:227], v231 offset:3584
	s_waitcnt vmcnt(8)
	ds_write_b128 v247, v[156:159]
	ds_write_b128 v247, v[160:163] offset:1024
	ds_write_b128 v111, v[164:167] offset:2048
	ds_write_b128 v111, v[168:171] offset:3072
	ds_read_b128 v[156:159], v248
	ds_read_b128 v[160:163], v249
	ds_read_b128 v[164:167], v250
	ds_read_b128 v[168:171], v251
	ds_write_b128 v112, v[172:175]
	ds_write_b128 v112, v[176:179] offset:1024
	ds_write_b128 v112, v[180:183] offset:2048
	ds_write_b128 v112, v[184:187] offset:3072
	v_mfma_f32_32x32x16_bf16 v[32:47], v[120:123], v[52:55], v[32:47]
	v_mfma_f32_32x32x16_bf16 v[32:47], v[124:127], v[56:59], v[32:47]
	v_mfma_f32_32x32x16_bf16 v[32:47], v[128:131], v[60:63], v[32:47]
	s_nop 11
	v_exp_f32_e32 v32, v32
	v_exp_f32_e32 v33, v33
	v_exp_f32_e32 v34, v34
	v_exp_f32_e32 v35, v35
	v_exp_f32_e32 v36, v36
	v_exp_f32_e32 v37, v37
	v_exp_f32_e32 v38, v38
	v_exp_f32_e32 v39, v39
	v_exp_f32_e32 v40, v40
	v_exp_f32_e32 v41, v41
	v_exp_f32_e32 v42, v42
	v_exp_f32_e32 v43, v43
	v_exp_f32_e32 v44, v44
	v_exp_f32_e32 v45, v45
	v_exp_f32_e32 v46, v46
	v_exp_f32_e32 v47, v47
	s_add_i32 s90, s67, 512
	v_add_u32_e32 v84, s90, v107
	v_add_u32_e32 v85, 0, v84
	v_add_u32_e32 v86, 1, v84
	v_add_u32_e32 v87, 2, v84
	v_add_u32_e32 v88, 3, v84
	v_cmp_gt_u32_e64 s[30:31], s98, v85
	v_cmp_gt_u32_e64 s[36:37], s98, v86
	v_cmp_gt_u32_e64 s[78:79], s98, v87
	v_cmp_gt_u32_e64 s[50:51], s98, v88
	v_cndmask_b32_e64 v32, 0, v32, s[30:31]
	v_add_u32_e32 v85, 8, v84
	v_cmp_gt_u32_e64 s[30:31], s98, v85
	v_cndmask_b32_e64 v33, 0, v33, s[36:37]
	v_add_u32_e32 v86, 9, v84
	v_cmp_gt_u32_e64 s[36:37], s98, v86
	v_cndmask_b32_e64 v34, 0, v34, s[78:79]
	v_add_u32_e32 v87, 10, v84
	v_cmp_gt_u32_e64 s[78:79], s98, v87
	v_cndmask_b32_e64 v35, 0, v35, s[50:51]
	v_add_u32_e32 v88, 11, v84
	v_cmp_gt_u32_e64 s[50:51], s98, v88
	v_cndmask_b32_e64 v36, 0, v36, s[30:31]
	v_add_u32_e32 v85, 16, v84
	v_cmp_gt_u32_e64 s[30:31], s98, v85
	v_cndmask_b32_e64 v37, 0, v37, s[36:37]
	v_add_u32_e32 v86, 17, v84
	v_cmp_gt_u32_e64 s[36:37], s98, v86
	v_cndmask_b32_e64 v38, 0, v38, s[78:79]
	v_add_u32_e32 v87, 18, v84
	v_cmp_gt_u32_e64 s[78:79], s98, v87
	v_cndmask_b32_e64 v39, 0, v39, s[50:51]
	v_add_u32_e32 v88, 19, v84
	v_cmp_gt_u32_e64 s[50:51], s98, v88
	v_cndmask_b32_e64 v40, 0, v40, s[30:31]
	v_add_u32_e32 v85, 24, v84
	v_cmp_gt_u32_e64 s[30:31], s98, v85
	v_cndmask_b32_e64 v41, 0, v41, s[36:37]
	v_add_u32_e32 v86, 25, v84
	v_cmp_gt_u32_e64 s[36:37], s98, v86
	v_cndmask_b32_e64 v42, 0, v42, s[78:79]
	v_add_u32_e32 v87, 26, v84
	v_cmp_gt_u32_e64 s[78:79], s98, v87
	v_cndmask_b32_e64 v43, 0, v43, s[50:51]
	v_add_u32_e32 v88, 27, v84
	v_cmp_gt_u32_e64 s[50:51], s98, v88
	v_nop
	v_cndmask_b32_e64 v44, 0, v44, s[30:31]
	v_cndmask_b32_e64 v45, 0, v45, s[36:37]
	v_cndmask_b32_e64 v46, 0, v46, s[78:79]
	v_cndmask_b32_e64 v47, 0, v47, s[50:51]
	v_cvt_pk_bf16_f32 v64, v32, v33
	v_cvt_pk_bf16_f32 v65, v34, v35
	v_cvt_pk_bf16_f32 v66, v36, v37
	v_cvt_pk_bf16_f32 v67, v38, v39
	v_cvt_pk_bf16_f32 v68, v40, v41
	v_cvt_pk_bf16_f32 v69, v42, v43
	v_cvt_pk_bf16_f32 v70, v44, v45
	v_cvt_pk_bf16_f32 v71, v46, v47
	v_pk_add_f32 v[232:233], v[232:233], v[32:33]
	v_pk_add_f32 v[232:233], v[232:233], v[34:35]
	v_pk_add_f32 v[232:233], v[232:233], v[36:37]
	v_pk_add_f32 v[232:233], v[232:233], v[38:39]
	v_pk_add_f32 v[232:233], v[232:233], v[40:41]
	v_pk_add_f32 v[232:233], v[232:233], v[42:43]
	v_pk_add_f32 v[232:233], v[232:233], v[44:45]
	v_pk_add_f32 v[232:233], v[232:233], v[46:47]
	ds_read2_b32 v[32:33], v115 offset0:170 offset1:171
	ds_read2_b32 v[34:35], v115 offset0:172 offset1:173
	ds_read2_b32 v[36:37], v115 offset0:178 offset1:179
	ds_read2_b32 v[38:39], v115 offset0:180 offset1:181
	ds_read2_b32 v[40:41], v115 offset0:187 offset1:188
	ds_read2_b32 v[42:43], v115 offset0:189 offset1:190
	ds_read2_b32 v[44:45], v115 offset0:195 offset1:196
	ds_read2_b32 v[46:47], v115 offset0:197 offset1:198
	s_waitcnt lgkmcnt(15)
	v_mfma_f32_32x32x16_bf16 v[0:15], v[64:67], v[72:75], v[0:15]
	v_mfma_f32_32x32x16_bf16 v[16:31], v[64:67], v[76:79], v[16:31]
	v_mfma_f32_32x32x16_bf16 v[0:15], v[68:71], v[220:223], v[0:15]
	v_mfma_f32_32x32x16_bf16 v[16:31], v[68:71], v[224:227], v[16:31]
	s_add_i32 s90, s67, -128
	v_add_u32_e32 v80, s90, v239
	v_add_u32_e32 v83, s90, v240
	v_add_u32_e32 v99, s90, v241
	v_add_u32_e32 v253, s90, v242
	v_add_u32_e32 v254, s90, v101
	v_add_u32_e32 v255, s90, v150
	v_med3_i32 v80, v80, 0, s99
	v_med3_i32 v83, v83, 0, s99
	v_med3_i32 v99, v99, 0, s99
	v_med3_i32 v253, v253, 0, s99
	v_med3_i32 v254, v254, 0, s99
	v_med3_i32 v255, v255, 0, s99
	v_mad_u32_u24 v80, v80, s100, v252
	v_mad_u32_u24 v83, v83, s100, v252
	v_mad_u32_u24 v99, v99, s100, v252
	v_mad_u32_u24 v253, v253, s100, v252
	v_mad_u32_u24 v254, v254, s100, v153
	v_mad_u32_u24 v255, v255, s100, v153
	global_load_dwordx4 v[116:119], v80, s[82:83]
	global_load_dwordx4 v[120:123], v83, s[82:83]
	global_load_dwordx4 v[124:127], v99, s[82:83]
	global_load_dwordx4 v[128:131], v253, s[82:83]
	global_load_dwordx4 v[132:135], v254, s[82:83] offset:768
	global_load_dwordx4 v[136:139], v255, s[82:83] offset:768
	global_load_dwordx4 v[140:143], v254, s[82:83] offset:832
	global_load_dwordx4 v[144:147], v255, s[82:83] offset:832
	s_waitcnt lgkmcnt(0)
	v_mfma_f32_32x32x16_bf16 v[32:47], v[156:159], v[48:51], v[32:47]
	ds_read_b64_tr_b16 v[72:73], v231
	ds_read_b64_tr_b16 v[74:75], v231 offset:512
	ds_read_b64_tr_b16 v[76:77], v231 offset:2048
	ds_read_b64_tr_b16 v[78:79], v231 offset:2560
	ds_read_b64_tr_b16 v[220:221], v231 offset:1024
	ds_read_b64_tr_b16 v[222:223], v231 offset:1536
	ds_read_b64_tr_b16 v[224:225], v231 offset:3072
	ds_read_b64_tr_b16 v[226:227], v231 offset:3584
	s_waitcnt vmcnt(8)
	ds_write_b128 v247, v[188:191]
	ds_write_b128 v247, v[192:195] offset:1024
	ds_write_b128 v111, v[196:199] offset:2048
	ds_write_b128 v111, v[200:203] offset:3072
	ds_read_b128 v[188:191], v248
	ds_read_b128 v[192:195], v249
	ds_read_b128 v[196:199], v250
	ds_read_b128 v[200:203], v251
	ds_write_b128 v112, v[204:207]
	ds_write_b128 v112, v[208:211] offset:1024
	ds_write_b128 v112, v[212:215] offset:2048
	ds_write_b128 v112, v[216:219] offset:3072
	v_mfma_f32_32x32x16_bf16 v[32:47], v[160:163], v[52:55], v[32:47]
	v_mfma_f32_32x32x16_bf16 v[32:47], v[164:167], v[56:59], v[32:47]
	v_mfma_f32_32x32x16_bf16 v[32:47], v[168:171], v[60:63], v[32:47]
	s_nop 11
	v_exp_f32_e32 v32, v32
	v_exp_f32_e32 v33, v33
	v_exp_f32_e32 v34, v34
	v_exp_f32_e32 v35, v35
	v_exp_f32_e32 v36, v36
	v_exp_f32_e32 v37, v37
	v_exp_f32_e32 v38, v38
	v_exp_f32_e32 v39, v39
	v_exp_f32_e32 v40, v40
	v_exp_f32_e32 v41, v41
	v_exp_f32_e32 v42, v42
	v_exp_f32_e32 v43, v43
	v_exp_f32_e32 v44, v44
	v_exp_f32_e32 v45, v45
	v_exp_f32_e32 v46, v46
	v_exp_f32_e32 v47, v47
	s_add_i32 s90, s67, 544
	v_add_u32_e32 v84, s90, v107
	v_add_u32_e32 v85, 0, v84
	v_add_u32_e32 v86, 1, v84
	v_add_u32_e32 v87, 2, v84
	v_add_u32_e32 v88, 3, v84
	v_cmp_gt_u32_e64 s[30:31], s98, v85
	v_cmp_gt_u32_e64 s[36:37], s98, v86
	v_cmp_gt_u32_e64 s[78:79], s98, v87
	v_cmp_gt_u32_e64 s[50:51], s98, v88
	v_cndmask_b32_e64 v32, 0, v32, s[30:31]
	v_add_u32_e32 v85, 8, v84
	v_cmp_gt_u32_e64 s[30:31], s98, v85
	v_cndmask_b32_e64 v33, 0, v33, s[36:37]
	v_add_u32_e32 v86, 9, v84
	v_cmp_gt_u32_e64 s[36:37], s98, v86
	v_cndmask_b32_e64 v34, 0, v34, s[78:79]
	v_add_u32_e32 v87, 10, v84
	v_cmp_gt_u32_e64 s[78:79], s98, v87
	v_cndmask_b32_e64 v35, 0, v35, s[50:51]
	v_add_u32_e32 v88, 11, v84
	v_cmp_gt_u32_e64 s[50:51], s98, v88
	v_cndmask_b32_e64 v36, 0, v36, s[30:31]
	v_add_u32_e32 v85, 16, v84
	v_cmp_gt_u32_e64 s[30:31], s98, v85
	v_cndmask_b32_e64 v37, 0, v37, s[36:37]
	v_add_u32_e32 v86, 17, v84
	v_cmp_gt_u32_e64 s[36:37], s98, v86
	v_cndmask_b32_e64 v38, 0, v38, s[78:79]
	v_add_u32_e32 v87, 18, v84
	v_cmp_gt_u32_e64 s[78:79], s98, v87
	v_cndmask_b32_e64 v39, 0, v39, s[50:51]
	v_add_u32_e32 v88, 19, v84
	v_cmp_gt_u32_e64 s[50:51], s98, v88
	v_cndmask_b32_e64 v40, 0, v40, s[30:31]
	v_add_u32_e32 v85, 24, v84
	v_cmp_gt_u32_e64 s[30:31], s98, v85
	v_cndmask_b32_e64 v41, 0, v41, s[36:37]
	v_add_u32_e32 v86, 25, v84
	v_cmp_gt_u32_e64 s[36:37], s98, v86
	v_cndmask_b32_e64 v42, 0, v42, s[78:79]
	v_add_u32_e32 v87, 26, v84
	v_cmp_gt_u32_e64 s[78:79], s98, v87
	v_cndmask_b32_e64 v43, 0, v43, s[50:51]
	v_add_u32_e32 v88, 27, v84
	v_cmp_gt_u32_e64 s[50:51], s98, v88
	v_nop
	v_cndmask_b32_e64 v44, 0, v44, s[30:31]
	v_cndmask_b32_e64 v45, 0, v45, s[36:37]
	v_cndmask_b32_e64 v46, 0, v46, s[78:79]
	v_cndmask_b32_e64 v47, 0, v47, s[50:51]
	v_cvt_pk_bf16_f32 v64, v32, v33
	v_cvt_pk_bf16_f32 v65, v34, v35
	v_cvt_pk_bf16_f32 v66, v36, v37
	v_cvt_pk_bf16_f32 v67, v38, v39
	v_cvt_pk_bf16_f32 v68, v40, v41
	v_cvt_pk_bf16_f32 v69, v42, v43
	v_cvt_pk_bf16_f32 v70, v44, v45
	v_cvt_pk_bf16_f32 v71, v46, v47
	v_pk_add_f32 v[232:233], v[232:233], v[32:33]
	v_pk_add_f32 v[232:233], v[232:233], v[34:35]
	v_pk_add_f32 v[232:233], v[232:233], v[36:37]
	v_pk_add_f32 v[232:233], v[232:233], v[38:39]
	v_pk_add_f32 v[232:233], v[232:233], v[40:41]
	v_pk_add_f32 v[232:233], v[232:233], v[42:43]
	v_pk_add_f32 v[232:233], v[232:233], v[44:45]
	v_pk_add_f32 v[232:233], v[232:233], v[46:47]
	v_mov_b32_e32 v115, v229
	ds_read2_b32 v[32:33], v115 offset0:0 offset1:1
	ds_read2_b32 v[34:35], v115 offset0:2 offset1:3
	ds_read2_b32 v[36:37], v115 offset0:10 offset1:11
	ds_read2_b32 v[38:39], v115 offset0:12 offset1:13
	ds_read2_b32 v[40:41], v115 offset0:20 offset1:21
	ds_read2_b32 v[42:43], v115 offset0:22 offset1:23
	ds_read2_b32 v[44:45], v115 offset0:30 offset1:31
	ds_read2_b32 v[46:47], v115 offset0:32 offset1:33
	s_waitcnt lgkmcnt(15)
	v_mfma_f32_32x32x16_bf16 v[0:15], v[64:67], v[72:75], v[0:15]
	v_mfma_f32_32x32x16_bf16 v[16:31], v[64:67], v[76:79], v[16:31]
	v_mfma_f32_32x32x16_bf16 v[0:15], v[68:71], v[220:223], v[0:15]
	v_mfma_f32_32x32x16_bf16 v[16:31], v[68:71], v[224:227], v[16:31]
	s_add_i32 s90, s67, 0
	v_add_u32_e32 v80, s90, v239
	v_add_u32_e32 v83, s90, v240
	v_add_u32_e32 v99, s90, v241
	v_add_u32_e32 v253, s90, v242
	v_add_u32_e32 v254, s90, v101
	v_add_u32_e32 v255, s90, v150
	v_med3_i32 v80, v80, 0, s99
	v_med3_i32 v83, v83, 0, s99
	v_med3_i32 v99, v99, 0, s99
	v_med3_i32 v253, v253, 0, s99
	v_med3_i32 v254, v254, 0, s99
	v_med3_i32 v255, v255, 0, s99
	v_mad_u32_u24 v80, v80, s100, v252
	v_mad_u32_u24 v83, v83, s100, v252
	v_mad_u32_u24 v99, v99, s100, v252
	v_mad_u32_u24 v253, v253, s100, v252
	v_mad_u32_u24 v254, v254, s100, v153
	v_mad_u32_u24 v255, v255, s100, v153
	global_load_dwordx4 v[156:159], v80, s[82:83]
	global_load_dwordx4 v[160:163], v83, s[82:83]
	global_load_dwordx4 v[164:167], v99, s[82:83]
	global_load_dwordx4 v[168:171], v253, s[82:83]
	global_load_dwordx4 v[172:175], v254, s[82:83] offset:768
	global_load_dwordx4 v[176:179], v255, s[82:83] offset:768
	global_load_dwordx4 v[180:183], v254, s[82:83] offset:832
	global_load_dwordx4 v[184:187], v255, s[82:83] offset:832
	s_waitcnt lgkmcnt(0)
	v_mfma_f32_32x32x16_bf16 v[32:47], v[188:191], v[48:51], v[32:47]
	ds_read_b64_tr_b16 v[72:73], v231
	ds_read_b64_tr_b16 v[74:75], v231 offset:512
	ds_read_b64_tr_b16 v[76:77], v231 offset:2048
	ds_read_b64_tr_b16 v[78:79], v231 offset:2560
	ds_read_b64_tr_b16 v[220:221], v231 offset:1024
	ds_read_b64_tr_b16 v[222:223], v231 offset:1536
	ds_read_b64_tr_b16 v[224:225], v231 offset:3072
	ds_read_b64_tr_b16 v[226:227], v231 offset:3584
	s_waitcnt vmcnt(8)
	ds_write_b128 v247, v[116:119]
	ds_write_b128 v247, v[120:123] offset:1024
	ds_write_b128 v111, v[124:127] offset:2048
	ds_write_b128 v111, v[128:131] offset:3072
	ds_read_b128 v[116:119], v248
	ds_read_b128 v[120:123], v249
	ds_read_b128 v[124:127], v250
	ds_read_b128 v[128:131], v251
	ds_write_b128 v112, v[132:135]
	ds_write_b128 v112, v[136:139] offset:1024
	ds_write_b128 v112, v[140:143] offset:2048
	ds_write_b128 v112, v[144:147] offset:3072
	v_mfma_f32_32x32x16_bf16 v[32:47], v[192:195], v[52:55], v[32:47]
	v_mfma_f32_32x32x16_bf16 v[32:47], v[196:199], v[56:59], v[32:47]
	v_mfma_f32_32x32x16_bf16 v[32:47], v[200:203], v[60:63], v[32:47]
	s_nop 11
	v_exp_f32_e32 v32, v32
	v_exp_f32_e32 v33, v33
	v_exp_f32_e32 v34, v34
	v_exp_f32_e32 v35, v35
	v_exp_f32_e32 v36, v36
	v_exp_f32_e32 v37, v37
	v_exp_f32_e32 v38, v38
	v_exp_f32_e32 v39, v39
	v_exp_f32_e32 v40, v40
	v_exp_f32_e32 v41, v41
	v_exp_f32_e32 v42, v42
	v_exp_f32_e32 v43, v43
	v_exp_f32_e32 v44, v44
	v_exp_f32_e32 v45, v45
	v_exp_f32_e32 v46, v46
	v_exp_f32_e32 v47, v47
	s_add_i32 s90, s67, -256
	v_lshlrev_b32_e32 v84, 2, v107
	v_add_u32_e32 v84, s90, v84
	v_add_u32_e32 v85, 0, v84
	v_add_u32_e32 v86, 4, v84
	v_add_u32_e32 v87, 8, v84
	v_add_u32_e32 v88, 12, v84
	v_cmp_gt_u32_e64 s[30:31], s98, v85
	v_cmp_gt_u32_e64 s[36:37], s98, v86
	v_cmp_gt_u32_e64 s[78:79], s98, v87
	v_cmp_gt_u32_e64 s[50:51], s98, v88
	v_cndmask_b32_e64 v32, 0, v32, s[30:31]
	v_add_u32_e32 v85, 32, v84
	v_cmp_gt_u32_e64 s[30:31], s98, v85
	v_cndmask_b32_e64 v33, 0, v33, s[36:37]
	v_add_u32_e32 v86, 36, v84
	v_cmp_gt_u32_e64 s[36:37], s98, v86
	v_cndmask_b32_e64 v34, 0, v34, s[78:79]
	v_add_u32_e32 v87, 40, v84
	v_cmp_gt_u32_e64 s[78:79], s98, v87
	v_cndmask_b32_e64 v35, 0, v35, s[50:51]
	v_add_u32_e32 v88, 44, v84
	v_cmp_gt_u32_e64 s[50:51], s98, v88
	v_cndmask_b32_e64 v36, 0, v36, s[30:31]
	v_add_u32_e32 v85, 64, v84
	v_cmp_gt_u32_e64 s[30:31], s98, v85
	v_cndmask_b32_e64 v37, 0, v37, s[36:37]
	v_add_u32_e32 v86, 68, v84
	v_cmp_gt_u32_e64 s[36:37], s98, v86
	v_cndmask_b32_e64 v38, 0, v38, s[78:79]
	v_add_u32_e32 v87, 72, v84
	v_cmp_gt_u32_e64 s[78:79], s98, v87
	v_cndmask_b32_e64 v39, 0, v39, s[50:51]
	v_add_u32_e32 v88, 76, v84
	v_cmp_gt_u32_e64 s[50:51], s98, v88
	v_cndmask_b32_e64 v40, 0, v40, s[30:31]
	v_add_u32_e32 v85, 96, v84
	v_cmp_gt_u32_e64 s[30:31], s98, v85
	v_cndmask_b32_e64 v41, 0, v41, s[36:37]
	v_add_u32_e32 v86, 100, v84
	v_cmp_gt_u32_e64 s[36:37], s98, v86
	v_cndmask_b32_e64 v42, 0, v42, s[78:79]
	v_add_u32_e32 v87, 104, v84
	v_cmp_gt_u32_e64 s[78:79], s98, v87
	v_cndmask_b32_e64 v43, 0, v43, s[50:51]
	v_add_u32_e32 v88, 108, v84
	v_cmp_gt_u32_e64 s[50:51], s98, v88
	v_nop
	v_cndmask_b32_e64 v44, 0, v44, s[30:31]
	v_cndmask_b32_e64 v45, 0, v45, s[36:37]
	v_cndmask_b32_e64 v46, 0, v46, s[78:79]
	v_cndmask_b32_e64 v47, 0, v47, s[50:51]
	v_cvt_pk_bf16_f32 v64, v32, v33
	v_cvt_pk_bf16_f32 v65, v34, v35
	v_cvt_pk_bf16_f32 v66, v36, v37
	v_cvt_pk_bf16_f32 v67, v38, v39
	v_cvt_pk_bf16_f32 v68, v40, v41
	v_cvt_pk_bf16_f32 v69, v42, v43
	v_cvt_pk_bf16_f32 v70, v44, v45
	v_cvt_pk_bf16_f32 v71, v46, v47
	v_pk_add_f32 v[232:233], v[232:233], v[32:33]
	v_pk_add_f32 v[232:233], v[232:233], v[34:35]
	v_pk_add_f32 v[232:233], v[232:233], v[36:37]
	v_pk_add_f32 v[232:233], v[232:233], v[38:39]
	v_pk_add_f32 v[232:233], v[232:233], v[40:41]
	v_pk_add_f32 v[232:233], v[232:233], v[42:43]
	v_pk_add_f32 v[232:233], v[232:233], v[44:45]
	v_pk_add_f32 v[232:233], v[232:233], v[46:47]
	ds_read2_b32 v[32:33], v115 offset0:40 offset1:41
	ds_read2_b32 v[34:35], v115 offset0:42 offset1:43
	ds_read2_b32 v[36:37], v115 offset0:50 offset1:51
	ds_read2_b32 v[38:39], v115 offset0:52 offset1:53
	ds_read2_b32 v[40:41], v115 offset0:60 offset1:61
	ds_read2_b32 v[42:43], v115 offset0:62 offset1:63
	ds_read2_b32 v[44:45], v115 offset0:70 offset1:71
	ds_read2_b32 v[46:47], v115 offset0:72 offset1:73
	s_waitcnt lgkmcnt(15)
	v_mfma_f32_32x32x16_bf16 v[0:15], v[64:67], v[72:75], v[0:15]
	v_mfma_f32_32x32x16_bf16 v[16:31], v[64:67], v[76:79], v[16:31]
	v_mfma_f32_32x32x16_bf16 v[0:15], v[68:71], v[220:223], v[0:15]
	v_mfma_f32_32x32x16_bf16 v[16:31], v[68:71], v[224:227], v[16:31]
	s_add_i32 s90, s67, 128
	v_add_u32_e32 v80, s90, v239
	v_add_u32_e32 v83, s90, v240
	v_add_u32_e32 v99, s90, v241
	v_add_u32_e32 v253, s90, v242
	v_add_u32_e32 v254, s90, v101
	v_add_u32_e32 v255, s90, v150
	v_med3_i32 v80, v80, 0, s99
	v_med3_i32 v83, v83, 0, s99
	v_med3_i32 v99, v99, 0, s99
	v_med3_i32 v253, v253, 0, s99
	v_med3_i32 v254, v254, 0, s99
	v_med3_i32 v255, v255, 0, s99
	v_mad_u32_u24 v80, v80, s100, v252
	v_mad_u32_u24 v83, v83, s100, v252
	v_mad_u32_u24 v99, v99, s100, v252
	v_mad_u32_u24 v253, v253, s100, v252
	v_mad_u32_u24 v254, v254, s100, v153
	v_mad_u32_u24 v255, v255, s100, v153
	global_load_dwordx4 v[188:191], v80, s[82:83]
	global_load_dwordx4 v[192:195], v83, s[82:83]
	global_load_dwordx4 v[196:199], v99, s[82:83]
	global_load_dwordx4 v[200:203], v253, s[82:83]
	global_load_dwordx4 v[204:207], v254, s[82:83] offset:768
	global_load_dwordx4 v[208:211], v255, s[82:83] offset:768
	global_load_dwordx4 v[212:215], v254, s[82:83] offset:832
	global_load_dwordx4 v[216:219], v255, s[82:83] offset:832
	s_waitcnt lgkmcnt(0)
	v_mfma_f32_32x32x16_bf16 v[32:47], v[116:119], v[48:51], v[32:47]
	ds_read_b64_tr_b16 v[72:73], v231
	ds_read_b64_tr_b16 v[74:75], v231 offset:512
	ds_read_b64_tr_b16 v[76:77], v231 offset:2048
	ds_read_b64_tr_b16 v[78:79], v231 offset:2560
	ds_read_b64_tr_b16 v[220:221], v231 offset:1024
	ds_read_b64_tr_b16 v[222:223], v231 offset:1536
	ds_read_b64_tr_b16 v[224:225], v231 offset:3072
	ds_read_b64_tr_b16 v[226:227], v231 offset:3584
	s_waitcnt vmcnt(8)
	ds_write_b128 v247, v[156:159]
	ds_write_b128 v247, v[160:163] offset:1024
	ds_write_b128 v111, v[164:167] offset:2048
	ds_write_b128 v111, v[168:171] offset:3072
	ds_read_b128 v[156:159], v248
	ds_read_b128 v[160:163], v249
	ds_read_b128 v[164:167], v250
	ds_read_b128 v[168:171], v251
	ds_write_b128 v112, v[172:175]
	ds_write_b128 v112, v[176:179] offset:1024
	ds_write_b128 v112, v[180:183] offset:2048
	ds_write_b128 v112, v[184:187] offset:3072
	v_mfma_f32_32x32x16_bf16 v[32:47], v[120:123], v[52:55], v[32:47]
	v_mfma_f32_32x32x16_bf16 v[32:47], v[124:127], v[56:59], v[32:47]
	v_mfma_f32_32x32x16_bf16 v[32:47], v[128:131], v[60:63], v[32:47]
	s_nop 11
	v_exp_f32_e32 v32, v32
	v_exp_f32_e32 v33, v33
	v_exp_f32_e32 v34, v34
	v_exp_f32_e32 v35, v35
	v_exp_f32_e32 v36, v36
	v_exp_f32_e32 v37, v37
	v_exp_f32_e32 v38, v38
	v_exp_f32_e32 v39, v39
	v_exp_f32_e32 v40, v40
	v_exp_f32_e32 v41, v41
	v_exp_f32_e32 v42, v42
	v_exp_f32_e32 v43, v43
	v_exp_f32_e32 v44, v44
	v_exp_f32_e32 v45, v45
	v_exp_f32_e32 v46, v46
	v_exp_f32_e32 v47, v47
	s_add_i32 s90, s67, -128
	v_lshlrev_b32_e32 v84, 2, v107
	v_add_u32_e32 v84, s90, v84
	v_add_u32_e32 v85, 0, v84
	v_add_u32_e32 v86, 4, v84
	v_add_u32_e32 v87, 8, v84
	v_add_u32_e32 v88, 12, v84
	v_cmp_gt_u32_e64 s[30:31], s98, v85
	v_cmp_gt_u32_e64 s[36:37], s98, v86
	v_cmp_gt_u32_e64 s[78:79], s98, v87
	v_cmp_gt_u32_e64 s[50:51], s98, v88
	v_cndmask_b32_e64 v32, 0, v32, s[30:31]
	v_add_u32_e32 v85, 32, v84
	v_cmp_gt_u32_e64 s[30:31], s98, v85
	v_cndmask_b32_e64 v33, 0, v33, s[36:37]
	v_add_u32_e32 v86, 36, v84
	v_cmp_gt_u32_e64 s[36:37], s98, v86
	v_cndmask_b32_e64 v34, 0, v34, s[78:79]
	v_add_u32_e32 v87, 40, v84
	v_cmp_gt_u32_e64 s[78:79], s98, v87
	v_cndmask_b32_e64 v35, 0, v35, s[50:51]
	v_add_u32_e32 v88, 44, v84
	v_cmp_gt_u32_e64 s[50:51], s98, v88
	v_cndmask_b32_e64 v36, 0, v36, s[30:31]
	v_add_u32_e32 v85, 64, v84
	v_cmp_gt_u32_e64 s[30:31], s98, v85
	v_cndmask_b32_e64 v37, 0, v37, s[36:37]
	v_add_u32_e32 v86, 68, v84
	v_cmp_gt_u32_e64 s[36:37], s98, v86
	v_cndmask_b32_e64 v38, 0, v38, s[78:79]
	v_add_u32_e32 v87, 72, v84
	v_cmp_gt_u32_e64 s[78:79], s98, v87
	v_cndmask_b32_e64 v39, 0, v39, s[50:51]
	v_add_u32_e32 v88, 76, v84
	v_cmp_gt_u32_e64 s[50:51], s98, v88
	v_cndmask_b32_e64 v40, 0, v40, s[30:31]
	v_add_u32_e32 v85, 96, v84
	v_cmp_gt_u32_e64 s[30:31], s98, v85
	v_cndmask_b32_e64 v41, 0, v41, s[36:37]
	v_add_u32_e32 v86, 100, v84
	v_cmp_gt_u32_e64 s[36:37], s98, v86
	v_cndmask_b32_e64 v42, 0, v42, s[78:79]
	v_add_u32_e32 v87, 104, v84
	v_cmp_gt_u32_e64 s[78:79], s98, v87
	v_cndmask_b32_e64 v43, 0, v43, s[50:51]
	v_add_u32_e32 v88, 108, v84
	v_cmp_gt_u32_e64 s[50:51], s98, v88
	v_nop
	v_cndmask_b32_e64 v44, 0, v44, s[30:31]
	v_cndmask_b32_e64 v45, 0, v45, s[36:37]
	v_cndmask_b32_e64 v46, 0, v46, s[78:79]
	v_cndmask_b32_e64 v47, 0, v47, s[50:51]
	v_cvt_pk_bf16_f32 v64, v32, v33
	v_cvt_pk_bf16_f32 v65, v34, v35
	v_cvt_pk_bf16_f32 v66, v36, v37
	v_cvt_pk_bf16_f32 v67, v38, v39
	v_cvt_pk_bf16_f32 v68, v40, v41
	v_cvt_pk_bf16_f32 v69, v42, v43
	v_cvt_pk_bf16_f32 v70, v44, v45
	v_cvt_pk_bf16_f32 v71, v46, v47
	v_pk_add_f32 v[232:233], v[232:233], v[32:33]
	v_pk_add_f32 v[232:233], v[232:233], v[34:35]
	v_pk_add_f32 v[232:233], v[232:233], v[36:37]
	v_pk_add_f32 v[232:233], v[232:233], v[38:39]
	v_pk_add_f32 v[232:233], v[232:233], v[40:41]
	v_pk_add_f32 v[232:233], v[232:233], v[42:43]
	v_pk_add_f32 v[232:233], v[232:233], v[44:45]
	v_pk_add_f32 v[232:233], v[232:233], v[46:47]
	ds_read2_b32 v[32:33], v115 offset0:80 offset1:81
	ds_read2_b32 v[34:35], v115 offset0:82 offset1:83
	ds_read2_b32 v[36:37], v115 offset0:90 offset1:91
	ds_read2_b32 v[38:39], v115 offset0:92 offset1:93
	ds_read2_b32 v[40:41], v115 offset0:100 offset1:101
	ds_read2_b32 v[42:43], v115 offset0:102 offset1:103
	ds_read2_b32 v[44:45], v115 offset0:110 offset1:111
	ds_read2_b32 v[46:47], v115 offset0:112 offset1:113
	s_waitcnt lgkmcnt(15)
	v_mfma_f32_32x32x16_bf16 v[0:15], v[64:67], v[72:75], v[0:15]
	v_mfma_f32_32x32x16_bf16 v[16:31], v[64:67], v[76:79], v[16:31]
	v_mfma_f32_32x32x16_bf16 v[0:15], v[68:71], v[220:223], v[0:15]
	v_mfma_f32_32x32x16_bf16 v[16:31], v[68:71], v[224:227], v[16:31]
	s_add_i32 s90, s67, 256
	v_add_u32_e32 v80, s90, v239
	v_add_u32_e32 v83, s90, v240
	v_add_u32_e32 v99, s90, v241
	v_add_u32_e32 v253, s90, v242
	v_add_u32_e32 v254, s90, v101
	v_add_u32_e32 v255, s90, v150
	v_med3_i32 v80, v80, 0, s99
	v_med3_i32 v83, v83, 0, s99
	v_med3_i32 v99, v99, 0, s99
	v_med3_i32 v253, v253, 0, s99
	v_med3_i32 v254, v254, 0, s99
	v_med3_i32 v255, v255, 0, s99
	v_mad_u32_u24 v80, v80, s100, v252
	v_mad_u32_u24 v83, v83, s100, v252
	v_mad_u32_u24 v99, v99, s100, v252
	v_mad_u32_u24 v253, v253, s100, v252
	v_mad_u32_u24 v254, v254, s100, v153
	v_mad_u32_u24 v255, v255, s100, v153
	global_load_dwordx4 v[116:119], v80, s[82:83]
	global_load_dwordx4 v[120:123], v83, s[82:83]
	global_load_dwordx4 v[124:127], v99, s[82:83]
	global_load_dwordx4 v[128:131], v253, s[82:83]
	global_load_dwordx4 v[132:135], v254, s[82:83] offset:768
	global_load_dwordx4 v[136:139], v255, s[82:83] offset:768
	global_load_dwordx4 v[140:143], v254, s[82:83] offset:832
	global_load_dwordx4 v[144:147], v255, s[82:83] offset:832
	s_waitcnt lgkmcnt(0)
	v_mfma_f32_32x32x16_bf16 v[32:47], v[156:159], v[48:51], v[32:47]
	ds_read_b64_tr_b16 v[72:73], v231
	ds_read_b64_tr_b16 v[74:75], v231 offset:512
	ds_read_b64_tr_b16 v[76:77], v231 offset:2048
	ds_read_b64_tr_b16 v[78:79], v231 offset:2560
	ds_read_b64_tr_b16 v[220:221], v231 offset:1024
	ds_read_b64_tr_b16 v[222:223], v231 offset:1536
	ds_read_b64_tr_b16 v[224:225], v231 offset:3072
	ds_read_b64_tr_b16 v[226:227], v231 offset:3584
	s_waitcnt vmcnt(8)
	ds_write_b128 v247, v[188:191]
	ds_write_b128 v247, v[192:195] offset:1024
	ds_write_b128 v111, v[196:199] offset:2048
	ds_write_b128 v111, v[200:203] offset:3072
	ds_read_b128 v[188:191], v248
	ds_read_b128 v[192:195], v249
	ds_read_b128 v[196:199], v250
	ds_read_b128 v[200:203], v251
	ds_write_b128 v112, v[204:207]
	ds_write_b128 v112, v[208:211] offset:1024
	ds_write_b128 v112, v[212:215] offset:2048
	ds_write_b128 v112, v[216:219] offset:3072
	v_mfma_f32_32x32x16_bf16 v[32:47], v[160:163], v[52:55], v[32:47]
	v_mfma_f32_32x32x16_bf16 v[32:47], v[164:167], v[56:59], v[32:47]
	v_mfma_f32_32x32x16_bf16 v[32:47], v[168:171], v[60:63], v[32:47]
	s_nop 11
	v_exp_f32_e32 v32, v32
	v_exp_f32_e32 v33, v33
	v_exp_f32_e32 v34, v34
	v_exp_f32_e32 v35, v35
	v_exp_f32_e32 v36, v36
	v_exp_f32_e32 v37, v37
	v_exp_f32_e32 v38, v38
	v_exp_f32_e32 v39, v39
	v_exp_f32_e32 v40, v40
	v_exp_f32_e32 v41, v41
	v_exp_f32_e32 v42, v42
	v_exp_f32_e32 v43, v43
	v_exp_f32_e32 v44, v44
	v_exp_f32_e32 v45, v45
	v_exp_f32_e32 v46, v46
	v_exp_f32_e32 v47, v47
	s_add_i32 s90, s67, 0
	v_lshlrev_b32_e32 v84, 2, v107
	v_add_u32_e32 v84, s90, v84
	v_add_u32_e32 v85, 0, v84
	v_add_u32_e32 v86, 4, v84
	v_add_u32_e32 v87, 8, v84
	v_add_u32_e32 v88, 12, v84
	v_cmp_gt_u32_e64 s[30:31], s98, v85
	v_cmp_gt_u32_e64 s[36:37], s98, v86
	v_cmp_gt_u32_e64 s[78:79], s98, v87
	v_cmp_gt_u32_e64 s[50:51], s98, v88
	v_cndmask_b32_e64 v32, 0, v32, s[30:31]
	v_add_u32_e32 v85, 32, v84
	v_cmp_gt_u32_e64 s[30:31], s98, v85
	v_cndmask_b32_e64 v33, 0, v33, s[36:37]
	v_add_u32_e32 v86, 36, v84
	v_cmp_gt_u32_e64 s[36:37], s98, v86
	v_cndmask_b32_e64 v34, 0, v34, s[78:79]
	v_add_u32_e32 v87, 40, v84
	v_cmp_gt_u32_e64 s[78:79], s98, v87
	v_cndmask_b32_e64 v35, 0, v35, s[50:51]
	v_add_u32_e32 v88, 44, v84
	v_cmp_gt_u32_e64 s[50:51], s98, v88
	v_cndmask_b32_e64 v36, 0, v36, s[30:31]
	v_add_u32_e32 v85, 64, v84
	v_cmp_gt_u32_e64 s[30:31], s98, v85
	v_cndmask_b32_e64 v37, 0, v37, s[36:37]
	v_add_u32_e32 v86, 68, v84
	v_cmp_gt_u32_e64 s[36:37], s98, v86
	v_cndmask_b32_e64 v38, 0, v38, s[78:79]
	v_add_u32_e32 v87, 72, v84
	v_cmp_gt_u32_e64 s[78:79], s98, v87
	v_cndmask_b32_e64 v39, 0, v39, s[50:51]
	v_add_u32_e32 v88, 76, v84
	v_cmp_gt_u32_e64 s[50:51], s98, v88
	v_cndmask_b32_e64 v40, 0, v40, s[30:31]
	v_add_u32_e32 v85, 96, v84
	v_cmp_gt_u32_e64 s[30:31], s98, v85
	v_cndmask_b32_e64 v41, 0, v41, s[36:37]
	v_add_u32_e32 v86, 100, v84
	v_cmp_gt_u32_e64 s[36:37], s98, v86
	v_cndmask_b32_e64 v42, 0, v42, s[78:79]
	v_add_u32_e32 v87, 104, v84
	v_cmp_gt_u32_e64 s[78:79], s98, v87
	v_cndmask_b32_e64 v43, 0, v43, s[50:51]
	v_add_u32_e32 v88, 108, v84
	v_cmp_gt_u32_e64 s[50:51], s98, v88
	v_nop
	v_cndmask_b32_e64 v44, 0, v44, s[30:31]
	v_cndmask_b32_e64 v45, 0, v45, s[36:37]
	v_cndmask_b32_e64 v46, 0, v46, s[78:79]
	v_cndmask_b32_e64 v47, 0, v47, s[50:51]
	v_cvt_pk_bf16_f32 v64, v32, v33
	v_cvt_pk_bf16_f32 v65, v34, v35
	v_cvt_pk_bf16_f32 v66, v36, v37
	v_cvt_pk_bf16_f32 v67, v38, v39
	v_cvt_pk_bf16_f32 v68, v40, v41
	v_cvt_pk_bf16_f32 v69, v42, v43
	v_cvt_pk_bf16_f32 v70, v44, v45
	v_cvt_pk_bf16_f32 v71, v46, v47
	v_pk_add_f32 v[232:233], v[232:233], v[32:33]
	v_pk_add_f32 v[232:233], v[232:233], v[34:35]
	v_pk_add_f32 v[232:233], v[232:233], v[36:37]
	v_pk_add_f32 v[232:233], v[232:233], v[38:39]
	v_pk_add_f32 v[232:233], v[232:233], v[40:41]
	v_pk_add_f32 v[232:233], v[232:233], v[42:43]
	v_pk_add_f32 v[232:233], v[232:233], v[44:45]
	v_pk_add_f32 v[232:233], v[232:233], v[46:47]
	ds_read2_b32 v[32:33], v115 offset0:120 offset1:121
	ds_read2_b32 v[34:35], v115 offset0:122 offset1:123
	ds_read2_b32 v[36:37], v115 offset0:130 offset1:131
	ds_read2_b32 v[38:39], v115 offset0:132 offset1:133
	ds_read2_b32 v[40:41], v115 offset0:140 offset1:141
	ds_read2_b32 v[42:43], v115 offset0:142 offset1:143
	ds_read2_b32 v[44:45], v115 offset0:150 offset1:151
	ds_read2_b32 v[46:47], v115 offset0:152 offset1:153
	s_waitcnt lgkmcnt(15)
	v_mfma_f32_32x32x16_bf16 v[0:15], v[64:67], v[72:75], v[0:15]
	v_mfma_f32_32x32x16_bf16 v[16:31], v[64:67], v[76:79], v[16:31]
	v_mfma_f32_32x32x16_bf16 v[0:15], v[68:71], v[220:223], v[0:15]
	v_mfma_f32_32x32x16_bf16 v[16:31], v[68:71], v[224:227], v[16:31]
	s_add_i32 s90, s67, 384
	v_add_u32_e32 v80, s90, v239
	v_add_u32_e32 v83, s90, v240
	v_add_u32_e32 v99, s90, v241
	v_add_u32_e32 v253, s90, v242
	v_add_u32_e32 v254, s90, v101
	v_add_u32_e32 v255, s90, v150
	v_med3_i32 v80, v80, 0, s99
	v_med3_i32 v83, v83, 0, s99
	v_med3_i32 v99, v99, 0, s99
	v_med3_i32 v253, v253, 0, s99
	v_med3_i32 v254, v254, 0, s99
	v_med3_i32 v255, v255, 0, s99
	v_mad_u32_u24 v80, v80, s100, v252
	v_mad_u32_u24 v83, v83, s100, v252
	v_mad_u32_u24 v99, v99, s100, v252
	v_mad_u32_u24 v253, v253, s100, v252
	v_mad_u32_u24 v254, v254, s100, v153
	v_mad_u32_u24 v255, v255, s100, v153
	global_load_dwordx4 v[156:159], v80, s[82:83]
	global_load_dwordx4 v[160:163], v83, s[82:83]
	global_load_dwordx4 v[164:167], v99, s[82:83]
	global_load_dwordx4 v[168:171], v253, s[82:83]
	global_load_dwordx4 v[172:175], v254, s[82:83] offset:768
	global_load_dwordx4 v[176:179], v255, s[82:83] offset:768
	global_load_dwordx4 v[180:183], v254, s[82:83] offset:832
	global_load_dwordx4 v[184:187], v255, s[82:83] offset:832
	s_waitcnt lgkmcnt(0)
	v_mfma_f32_32x32x16_bf16 v[32:47], v[188:191], v[48:51], v[32:47]
	ds_read_b64_tr_b16 v[72:73], v231
	ds_read_b64_tr_b16 v[74:75], v231 offset:512
	ds_read_b64_tr_b16 v[76:77], v231 offset:2048
	ds_read_b64_tr_b16 v[78:79], v231 offset:2560
	ds_read_b64_tr_b16 v[220:221], v231 offset:1024
	ds_read_b64_tr_b16 v[222:223], v231 offset:1536
	ds_read_b64_tr_b16 v[224:225], v231 offset:3072
	ds_read_b64_tr_b16 v[226:227], v231 offset:3584
	s_waitcnt vmcnt(8)
	ds_write_b128 v247, v[116:119]
	ds_write_b128 v247, v[120:123] offset:1024
	ds_write_b128 v111, v[124:127] offset:2048
	ds_write_b128 v111, v[128:131] offset:3072
	ds_read_b128 v[116:119], v248
	ds_read_b128 v[120:123], v249
	ds_read_b128 v[124:127], v250
	ds_read_b128 v[128:131], v251
	ds_write_b128 v112, v[132:135]
	ds_write_b128 v112, v[136:139] offset:1024
	ds_write_b128 v112, v[140:143] offset:2048
	ds_write_b128 v112, v[144:147] offset:3072
	v_mfma_f32_32x32x16_bf16 v[32:47], v[192:195], v[52:55], v[32:47]
	v_mfma_f32_32x32x16_bf16 v[32:47], v[196:199], v[56:59], v[32:47]
	v_mfma_f32_32x32x16_bf16 v[32:47], v[200:203], v[60:63], v[32:47]
	s_nop 11
	v_exp_f32_e32 v32, v32
	v_exp_f32_e32 v33, v33
	v_exp_f32_e32 v34, v34
	v_exp_f32_e32 v35, v35
	v_exp_f32_e32 v36, v36
	v_exp_f32_e32 v37, v37
	v_exp_f32_e32 v38, v38
	v_exp_f32_e32 v39, v39
	v_exp_f32_e32 v40, v40
	v_exp_f32_e32 v41, v41
	v_exp_f32_e32 v42, v42
	v_exp_f32_e32 v43, v43
	v_exp_f32_e32 v44, v44
	v_exp_f32_e32 v45, v45
	v_exp_f32_e32 v46, v46
	v_exp_f32_e32 v47, v47
	s_add_i32 s90, s67, 128
	v_lshlrev_b32_e32 v84, 2, v107
	v_add_u32_e32 v84, s90, v84
	v_add_u32_e32 v85, 0, v84
	v_add_u32_e32 v86, 4, v84
	v_add_u32_e32 v87, 8, v84
	v_add_u32_e32 v88, 12, v84
	v_cmp_gt_u32_e64 s[30:31], s98, v85
	v_cmp_gt_u32_e64 s[36:37], s98, v86
	v_cmp_gt_u32_e64 s[78:79], s98, v87
	v_cmp_gt_u32_e64 s[50:51], s98, v88
	v_cndmask_b32_e64 v32, 0, v32, s[30:31]
	v_add_u32_e32 v85, 32, v84
	v_cmp_gt_u32_e64 s[30:31], s98, v85
	v_cndmask_b32_e64 v33, 0, v33, s[36:37]
	v_add_u32_e32 v86, 36, v84
	v_cmp_gt_u32_e64 s[36:37], s98, v86
	v_cndmask_b32_e64 v34, 0, v34, s[78:79]
	v_add_u32_e32 v87, 40, v84
	v_cmp_gt_u32_e64 s[78:79], s98, v87
	v_cndmask_b32_e64 v35, 0, v35, s[50:51]
	v_add_u32_e32 v88, 44, v84
	v_cmp_gt_u32_e64 s[50:51], s98, v88
	v_cndmask_b32_e64 v36, 0, v36, s[30:31]
	v_add_u32_e32 v85, 64, v84
	v_cmp_gt_u32_e64 s[30:31], s98, v85
	v_cndmask_b32_e64 v37, 0, v37, s[36:37]
	v_add_u32_e32 v86, 68, v84
	v_cmp_gt_u32_e64 s[36:37], s98, v86
	v_cndmask_b32_e64 v38, 0, v38, s[78:79]
	v_add_u32_e32 v87, 72, v84
	v_cmp_gt_u32_e64 s[78:79], s98, v87
	v_cndmask_b32_e64 v39, 0, v39, s[50:51]
	v_add_u32_e32 v88, 76, v84
	v_cmp_gt_u32_e64 s[50:51], s98, v88
	v_cndmask_b32_e64 v40, 0, v40, s[30:31]
	v_add_u32_e32 v85, 96, v84
	v_cmp_gt_u32_e64 s[30:31], s98, v85
	v_cndmask_b32_e64 v41, 0, v41, s[36:37]
	v_add_u32_e32 v86, 100, v84
	v_cmp_gt_u32_e64 s[36:37], s98, v86
	v_cndmask_b32_e64 v42, 0, v42, s[78:79]
	v_add_u32_e32 v87, 104, v84
	v_cmp_gt_u32_e64 s[78:79], s98, v87
	v_cndmask_b32_e64 v43, 0, v43, s[50:51]
	v_add_u32_e32 v88, 108, v84
	v_cmp_gt_u32_e64 s[50:51], s98, v88
	v_nop
	v_cndmask_b32_e64 v44, 0, v44, s[30:31]
	v_cndmask_b32_e64 v45, 0, v45, s[36:37]
	v_cndmask_b32_e64 v46, 0, v46, s[78:79]
	v_cndmask_b32_e64 v47, 0, v47, s[50:51]
	v_cvt_pk_bf16_f32 v64, v32, v33
	v_cvt_pk_bf16_f32 v65, v34, v35
	v_cvt_pk_bf16_f32 v66, v36, v37
	v_cvt_pk_bf16_f32 v67, v38, v39
	v_cvt_pk_bf16_f32 v68, v40, v41
	v_cvt_pk_bf16_f32 v69, v42, v43
	v_cvt_pk_bf16_f32 v70, v44, v45
	v_cvt_pk_bf16_f32 v71, v46, v47
	v_pk_add_f32 v[232:233], v[232:233], v[32:33]
	v_pk_add_f32 v[232:233], v[232:233], v[34:35]
	v_pk_add_f32 v[232:233], v[232:233], v[36:37]
	v_pk_add_f32 v[232:233], v[232:233], v[38:39]
	v_pk_add_f32 v[232:233], v[232:233], v[40:41]
	v_pk_add_f32 v[232:233], v[232:233], v[42:43]
	v_pk_add_f32 v[232:233], v[232:233], v[44:45]
	v_pk_add_f32 v[232:233], v[232:233], v[46:47]
	v_add_u32_e32 v115, 640, v115
	ds_read2_b32 v[32:33], v115 offset0:0 offset1:1
	ds_read2_b32 v[34:35], v115 offset0:2 offset1:3
	ds_read2_b32 v[36:37], v115 offset0:10 offset1:11
	ds_read2_b32 v[38:39], v115 offset0:12 offset1:13
	ds_read2_b32 v[40:41], v115 offset0:20 offset1:21
	ds_read2_b32 v[42:43], v115 offset0:22 offset1:23
	ds_read2_b32 v[44:45], v115 offset0:30 offset1:31
	ds_read2_b32 v[46:47], v115 offset0:32 offset1:33
	s_waitcnt lgkmcnt(15)
	v_mfma_f32_32x32x16_bf16 v[0:15], v[64:67], v[72:75], v[0:15]
	v_mfma_f32_32x32x16_bf16 v[16:31], v[64:67], v[76:79], v[16:31]
	v_mfma_f32_32x32x16_bf16 v[0:15], v[68:71], v[220:223], v[0:15]
	v_mfma_f32_32x32x16_bf16 v[16:31], v[68:71], v[224:227], v[16:31]
	s_add_i32 s90, s67, 512
	v_add_u32_e32 v80, s90, v239
	v_add_u32_e32 v83, s90, v240
	v_add_u32_e32 v99, s90, v241
	v_add_u32_e32 v253, s90, v242
	v_add_u32_e32 v254, s90, v101
	v_add_u32_e32 v255, s90, v150
	v_med3_i32 v80, v80, 0, s99
	v_med3_i32 v83, v83, 0, s99
	v_med3_i32 v99, v99, 0, s99
	v_med3_i32 v253, v253, 0, s99
	v_med3_i32 v254, v254, 0, s99
	v_med3_i32 v255, v255, 0, s99
	v_mad_u32_u24 v80, v80, s100, v252
	v_mad_u32_u24 v83, v83, s100, v252
	v_mad_u32_u24 v99, v99, s100, v252
	v_mad_u32_u24 v253, v253, s100, v252
	v_mad_u32_u24 v254, v254, s100, v153
	v_mad_u32_u24 v255, v255, s100, v153
	global_load_dwordx4 v[188:191], v80, s[82:83]
	global_load_dwordx4 v[192:195], v83, s[82:83]
	global_load_dwordx4 v[196:199], v99, s[82:83]
	global_load_dwordx4 v[200:203], v253, s[82:83]
	global_load_dwordx4 v[204:207], v254, s[82:83] offset:768
	global_load_dwordx4 v[208:211], v255, s[82:83] offset:768
	global_load_dwordx4 v[212:215], v254, s[82:83] offset:832
	global_load_dwordx4 v[216:219], v255, s[82:83] offset:832
	s_waitcnt lgkmcnt(0)
	v_mfma_f32_32x32x16_bf16 v[32:47], v[116:119], v[48:51], v[32:47]
	ds_read_b64_tr_b16 v[72:73], v231
	ds_read_b64_tr_b16 v[74:75], v231 offset:512
	ds_read_b64_tr_b16 v[76:77], v231 offset:2048
	ds_read_b64_tr_b16 v[78:79], v231 offset:2560
	ds_read_b64_tr_b16 v[220:221], v231 offset:1024
	ds_read_b64_tr_b16 v[222:223], v231 offset:1536
	ds_read_b64_tr_b16 v[224:225], v231 offset:3072
	ds_read_b64_tr_b16 v[226:227], v231 offset:3584
	s_waitcnt vmcnt(8)
	ds_write_b128 v247, v[156:159]
	ds_write_b128 v247, v[160:163] offset:1024
	ds_write_b128 v111, v[164:167] offset:2048
	ds_write_b128 v111, v[168:171] offset:3072
	ds_read_b128 v[156:159], v248
	ds_read_b128 v[160:163], v249
	ds_read_b128 v[164:167], v250
	ds_read_b128 v[168:171], v251
	ds_write_b128 v112, v[172:175]
	ds_write_b128 v112, v[176:179] offset:1024
	ds_write_b128 v112, v[180:183] offset:2048
	ds_write_b128 v112, v[184:187] offset:3072
	v_mfma_f32_32x32x16_bf16 v[32:47], v[120:123], v[52:55], v[32:47]
	v_mfma_f32_32x32x16_bf16 v[32:47], v[124:127], v[56:59], v[32:47]
	v_mfma_f32_32x32x16_bf16 v[32:47], v[128:131], v[60:63], v[32:47]
	s_nop 11
	v_exp_f32_e32 v32, v32
	v_exp_f32_e32 v33, v33
	v_exp_f32_e32 v34, v34
	v_exp_f32_e32 v35, v35
	v_exp_f32_e32 v36, v36
	v_exp_f32_e32 v37, v37
	v_exp_f32_e32 v38, v38
	v_exp_f32_e32 v39, v39
	v_exp_f32_e32 v40, v40
	v_exp_f32_e32 v41, v41
	v_exp_f32_e32 v42, v42
	v_exp_f32_e32 v43, v43
	v_exp_f32_e32 v44, v44
	v_exp_f32_e32 v45, v45
	v_exp_f32_e32 v46, v46
	v_exp_f32_e32 v47, v47
	s_add_i32 s90, s67, 256
	v_lshlrev_b32_e32 v84, 2, v107
	v_add_u32_e32 v84, s90, v84
	v_add_u32_e32 v85, 0, v84
	v_add_u32_e32 v86, 4, v84
	v_add_u32_e32 v87, 8, v84
	v_add_u32_e32 v88, 12, v84
	v_cmp_gt_u32_e64 s[30:31], s98, v85
	v_cmp_gt_u32_e64 s[36:37], s98, v86
	v_cmp_gt_u32_e64 s[78:79], s98, v87
	v_cmp_gt_u32_e64 s[50:51], s98, v88
	v_cndmask_b32_e64 v32, 0, v32, s[30:31]
	v_add_u32_e32 v85, 32, v84
	v_cmp_gt_u32_e64 s[30:31], s98, v85
	v_cndmask_b32_e64 v33, 0, v33, s[36:37]
	v_add_u32_e32 v86, 36, v84
	v_cmp_gt_u32_e64 s[36:37], s98, v86
	v_cndmask_b32_e64 v34, 0, v34, s[78:79]
	v_add_u32_e32 v87, 40, v84
	v_cmp_gt_u32_e64 s[78:79], s98, v87
	v_cndmask_b32_e64 v35, 0, v35, s[50:51]
	v_add_u32_e32 v88, 44, v84
	v_cmp_gt_u32_e64 s[50:51], s98, v88
	v_cndmask_b32_e64 v36, 0, v36, s[30:31]
	v_add_u32_e32 v85, 64, v84
	v_cmp_gt_u32_e64 s[30:31], s98, v85
	v_cndmask_b32_e64 v37, 0, v37, s[36:37]
	v_add_u32_e32 v86, 68, v84
	v_cmp_gt_u32_e64 s[36:37], s98, v86
	v_cndmask_b32_e64 v38, 0, v38, s[78:79]
	v_add_u32_e32 v87, 72, v84
	v_cmp_gt_u32_e64 s[78:79], s98, v87
	v_cndmask_b32_e64 v39, 0, v39, s[50:51]
	v_add_u32_e32 v88, 76, v84
	v_cmp_gt_u32_e64 s[50:51], s98, v88
	v_cndmask_b32_e64 v40, 0, v40, s[30:31]
	v_add_u32_e32 v85, 96, v84
	v_cmp_gt_u32_e64 s[30:31], s98, v85
	v_cndmask_b32_e64 v41, 0, v41, s[36:37]
	v_add_u32_e32 v86, 100, v84
	v_cmp_gt_u32_e64 s[36:37], s98, v86
	v_cndmask_b32_e64 v42, 0, v42, s[78:79]
	v_add_u32_e32 v87, 104, v84
	v_cmp_gt_u32_e64 s[78:79], s98, v87
	v_cndmask_b32_e64 v43, 0, v43, s[50:51]
	v_add_u32_e32 v88, 108, v84
	v_cmp_gt_u32_e64 s[50:51], s98, v88
	v_nop
	v_cndmask_b32_e64 v44, 0, v44, s[30:31]
	v_cndmask_b32_e64 v45, 0, v45, s[36:37]
	v_cndmask_b32_e64 v46, 0, v46, s[78:79]
	v_cndmask_b32_e64 v47, 0, v47, s[50:51]
	v_cvt_pk_bf16_f32 v64, v32, v33
	v_cvt_pk_bf16_f32 v65, v34, v35
	v_cvt_pk_bf16_f32 v66, v36, v37
	v_cvt_pk_bf16_f32 v67, v38, v39
	v_cvt_pk_bf16_f32 v68, v40, v41
	v_cvt_pk_bf16_f32 v69, v42, v43
	v_cvt_pk_bf16_f32 v70, v44, v45
	v_cvt_pk_bf16_f32 v71, v46, v47
	v_pk_add_f32 v[232:233], v[232:233], v[32:33]
	v_pk_add_f32 v[232:233], v[232:233], v[34:35]
	v_pk_add_f32 v[232:233], v[232:233], v[36:37]
	v_pk_add_f32 v[232:233], v[232:233], v[38:39]
	v_pk_add_f32 v[232:233], v[232:233], v[40:41]
	v_pk_add_f32 v[232:233], v[232:233], v[42:43]
	v_pk_add_f32 v[232:233], v[232:233], v[44:45]
	v_pk_add_f32 v[232:233], v[232:233], v[46:47]
	ds_read2_b32 v[32:33], v115 offset0:40 offset1:41
	ds_read2_b32 v[34:35], v115 offset0:42 offset1:43
	ds_read2_b32 v[36:37], v115 offset0:50 offset1:51
	ds_read2_b32 v[38:39], v115 offset0:52 offset1:53
	ds_read2_b32 v[40:41], v115 offset0:60 offset1:61
	ds_read2_b32 v[42:43], v115 offset0:62 offset1:63
	ds_read2_b32 v[44:45], v115 offset0:70 offset1:71
	ds_read2_b32 v[46:47], v115 offset0:72 offset1:73
	s_waitcnt lgkmcnt(15)
	v_mfma_f32_32x32x16_bf16 v[0:15], v[64:67], v[72:75], v[0:15]
	v_mfma_f32_32x32x16_bf16 v[16:31], v[64:67], v[76:79], v[16:31]
	v_mfma_f32_32x32x16_bf16 v[0:15], v[68:71], v[220:223], v[0:15]
	v_mfma_f32_32x32x16_bf16 v[16:31], v[68:71], v[224:227], v[16:31]
	s_add_i32 s90, s67, 640
	v_add_u32_e32 v80, s90, v239
	v_add_u32_e32 v83, s90, v240
	v_add_u32_e32 v99, s90, v241
	v_add_u32_e32 v253, s90, v242
	v_add_u32_e32 v254, s90, v101
	v_add_u32_e32 v255, s90, v150
	v_med3_i32 v80, v80, 0, s99
	v_med3_i32 v83, v83, 0, s99
	v_med3_i32 v99, v99, 0, s99
	v_med3_i32 v253, v253, 0, s99
	v_med3_i32 v254, v254, 0, s99
	v_med3_i32 v255, v255, 0, s99
	v_mad_u32_u24 v80, v80, s100, v252
	v_mad_u32_u24 v83, v83, s100, v252
	v_mad_u32_u24 v99, v99, s100, v252
	v_mad_u32_u24 v253, v253, s100, v252
	v_mad_u32_u24 v254, v254, s100, v153
	v_mad_u32_u24 v255, v255, s100, v153
	global_load_dwordx4 v[116:119], v80, s[82:83]
	global_load_dwordx4 v[120:123], v83, s[82:83]
	global_load_dwordx4 v[124:127], v99, s[82:83]
	global_load_dwordx4 v[128:131], v253, s[82:83]
	global_load_dwordx4 v[132:135], v254, s[82:83] offset:768
	global_load_dwordx4 v[136:139], v255, s[82:83] offset:768
	global_load_dwordx4 v[140:143], v254, s[82:83] offset:832
	global_load_dwordx4 v[144:147], v255, s[82:83] offset:832
	s_waitcnt lgkmcnt(0)
	v_mfma_f32_32x32x16_bf16 v[32:47], v[156:159], v[48:51], v[32:47]
	ds_read_b64_tr_b16 v[72:73], v231
	ds_read_b64_tr_b16 v[74:75], v231 offset:512
	ds_read_b64_tr_b16 v[76:77], v231 offset:2048
	ds_read_b64_tr_b16 v[78:79], v231 offset:2560
	ds_read_b64_tr_b16 v[220:221], v231 offset:1024
	ds_read_b64_tr_b16 v[222:223], v231 offset:1536
	ds_read_b64_tr_b16 v[224:225], v231 offset:3072
	ds_read_b64_tr_b16 v[226:227], v231 offset:3584
	s_waitcnt vmcnt(8)
	ds_write_b128 v247, v[188:191]
	ds_write_b128 v247, v[192:195] offset:1024
	ds_write_b128 v111, v[196:199] offset:2048
	ds_write_b128 v111, v[200:203] offset:3072
	ds_read_b128 v[188:191], v248
	ds_read_b128 v[192:195], v249
	ds_read_b128 v[196:199], v250
	ds_read_b128 v[200:203], v251
	ds_write_b128 v112, v[204:207]
	ds_write_b128 v112, v[208:211] offset:1024
	ds_write_b128 v112, v[212:215] offset:2048
	ds_write_b128 v112, v[216:219] offset:3072
	v_mfma_f32_32x32x16_bf16 v[32:47], v[160:163], v[52:55], v[32:47]
	v_mfma_f32_32x32x16_bf16 v[32:47], v[164:167], v[56:59], v[32:47]
	v_mfma_f32_32x32x16_bf16 v[32:47], v[168:171], v[60:63], v[32:47]
	s_nop 11
	v_exp_f32_e32 v32, v32
	v_exp_f32_e32 v33, v33
	v_exp_f32_e32 v34, v34
	v_exp_f32_e32 v35, v35
	v_exp_f32_e32 v36, v36
	v_exp_f32_e32 v37, v37
	v_exp_f32_e32 v38, v38
	v_exp_f32_e32 v39, v39
	v_exp_f32_e32 v40, v40
	v_exp_f32_e32 v41, v41
	v_exp_f32_e32 v42, v42
	v_exp_f32_e32 v43, v43
	v_exp_f32_e32 v44, v44
	v_exp_f32_e32 v45, v45
	v_exp_f32_e32 v46, v46
	v_exp_f32_e32 v47, v47
	s_add_i32 s90, s67, 384
	v_lshlrev_b32_e32 v84, 2, v107
	v_add_u32_e32 v84, s90, v84
	v_add_u32_e32 v85, 0, v84
	v_add_u32_e32 v86, 4, v84
	v_add_u32_e32 v87, 8, v84
	v_add_u32_e32 v88, 12, v84
	v_cmp_gt_u32_e64 s[30:31], s98, v85
	v_cmp_gt_u32_e64 s[36:37], s98, v86
	v_cmp_gt_u32_e64 s[78:79], s98, v87
	v_cmp_gt_u32_e64 s[50:51], s98, v88
	v_cndmask_b32_e64 v32, 0, v32, s[30:31]
	v_add_u32_e32 v85, 32, v84
	v_cmp_gt_u32_e64 s[30:31], s98, v85
	v_cndmask_b32_e64 v33, 0, v33, s[36:37]
	v_add_u32_e32 v86, 36, v84
	v_cmp_gt_u32_e64 s[36:37], s98, v86
	v_cndmask_b32_e64 v34, 0, v34, s[78:79]
	v_add_u32_e32 v87, 40, v84
	v_cmp_gt_u32_e64 s[78:79], s98, v87
	v_cndmask_b32_e64 v35, 0, v35, s[50:51]
	v_add_u32_e32 v88, 44, v84
	v_cmp_gt_u32_e64 s[50:51], s98, v88
	v_cndmask_b32_e64 v36, 0, v36, s[30:31]
	v_add_u32_e32 v85, 64, v84
	v_cmp_gt_u32_e64 s[30:31], s98, v85
	v_cndmask_b32_e64 v37, 0, v37, s[36:37]
	v_add_u32_e32 v86, 68, v84
	v_cmp_gt_u32_e64 s[36:37], s98, v86
	v_cndmask_b32_e64 v38, 0, v38, s[78:79]
	v_add_u32_e32 v87, 72, v84
	v_cmp_gt_u32_e64 s[78:79], s98, v87
	v_cndmask_b32_e64 v39, 0, v39, s[50:51]
	v_add_u32_e32 v88, 76, v84
	v_cmp_gt_u32_e64 s[50:51], s98, v88
	v_cndmask_b32_e64 v40, 0, v40, s[30:31]
	v_add_u32_e32 v85, 96, v84
	v_cmp_gt_u32_e64 s[30:31], s98, v85
	v_cndmask_b32_e64 v41, 0, v41, s[36:37]
	v_add_u32_e32 v86, 100, v84
	v_cmp_gt_u32_e64 s[36:37], s98, v86
	v_cndmask_b32_e64 v42, 0, v42, s[78:79]
	v_add_u32_e32 v87, 104, v84
	v_cmp_gt_u32_e64 s[78:79], s98, v87
	v_cndmask_b32_e64 v43, 0, v43, s[50:51]
	v_add_u32_e32 v88, 108, v84
	v_cmp_gt_u32_e64 s[50:51], s98, v88
	v_nop
	v_cndmask_b32_e64 v44, 0, v44, s[30:31]
	v_cndmask_b32_e64 v45, 0, v45, s[36:37]
	v_cndmask_b32_e64 v46, 0, v46, s[78:79]
	v_cndmask_b32_e64 v47, 0, v47, s[50:51]
	v_cvt_pk_bf16_f32 v64, v32, v33
	v_cvt_pk_bf16_f32 v65, v34, v35
	v_cvt_pk_bf16_f32 v66, v36, v37
	v_cvt_pk_bf16_f32 v67, v38, v39
	v_cvt_pk_bf16_f32 v68, v40, v41
	v_cvt_pk_bf16_f32 v69, v42, v43
	v_cvt_pk_bf16_f32 v70, v44, v45
	v_cvt_pk_bf16_f32 v71, v46, v47
	v_pk_add_f32 v[232:233], v[232:233], v[32:33]
	v_pk_add_f32 v[232:233], v[232:233], v[34:35]
	v_pk_add_f32 v[232:233], v[232:233], v[36:37]
	v_pk_add_f32 v[232:233], v[232:233], v[38:39]
	v_pk_add_f32 v[232:233], v[232:233], v[40:41]
	v_pk_add_f32 v[232:233], v[232:233], v[42:43]
	v_pk_add_f32 v[232:233], v[232:233], v[44:45]
	v_pk_add_f32 v[232:233], v[232:233], v[46:47]
	ds_read2_b32 v[32:33], v115 offset0:80 offset1:81
	ds_read2_b32 v[34:35], v115 offset0:82 offset1:83
	ds_read2_b32 v[36:37], v115 offset0:90 offset1:91
	ds_read2_b32 v[38:39], v115 offset0:92 offset1:93
	ds_read2_b32 v[40:41], v115 offset0:100 offset1:101
	ds_read2_b32 v[42:43], v115 offset0:102 offset1:103
	ds_read2_b32 v[44:45], v115 offset0:110 offset1:111
	ds_read2_b32 v[46:47], v115 offset0:112 offset1:113
	s_waitcnt lgkmcnt(15)
	v_mfma_f32_32x32x16_bf16 v[0:15], v[64:67], v[72:75], v[0:15]
	v_mfma_f32_32x32x16_bf16 v[16:31], v[64:67], v[76:79], v[16:31]
	v_mfma_f32_32x32x16_bf16 v[0:15], v[68:71], v[220:223], v[0:15]
	v_mfma_f32_32x32x16_bf16 v[16:31], v[68:71], v[224:227], v[16:31]
	s_add_i32 s90, s67, -1024
	v_add_u32_e32 v80, s90, v243
	v_add_u32_e32 v83, s90, v244
	v_add_u32_e32 v99, s90, v245
	v_add_u32_e32 v253, s90, v246
	v_add_u32_e32 v254, s90, v148
	v_add_u32_e32 v255, s90, v151
	v_med3_i32 v80, v80, 0, s99
	v_med3_i32 v83, v83, 0, s99
	v_med3_i32 v99, v99, 0, s99
	v_med3_i32 v253, v253, 0, s99
	v_med3_i32 v254, v254, 0, s99
	v_med3_i32 v255, v255, 0, s99
	v_mad_u32_u24 v80, v80, s100, v252
	v_mad_u32_u24 v83, v83, s100, v252
	v_mad_u32_u24 v99, v99, s100, v252
	v_mad_u32_u24 v253, v253, s100, v252
	v_mad_u32_u24 v254, v254, s100, v153
	v_mad_u32_u24 v255, v255, s100, v153
	global_load_dwordx4 v[156:159], v80, s[82:83]
	global_load_dwordx4 v[160:163], v83, s[82:83]
	global_load_dwordx4 v[164:167], v99, s[82:83]
	global_load_dwordx4 v[168:171], v253, s[82:83]
	global_load_dwordx4 v[172:175], v254, s[82:83] offset:768
	global_load_dwordx4 v[176:179], v255, s[82:83] offset:768
	global_load_dwordx4 v[180:183], v254, s[82:83] offset:832
	global_load_dwordx4 v[184:187], v255, s[82:83] offset:832
	s_waitcnt lgkmcnt(0)
	v_mfma_f32_32x32x16_bf16 v[32:47], v[188:191], v[48:51], v[32:47]
	ds_read_b64_tr_b16 v[72:73], v231
	ds_read_b64_tr_b16 v[74:75], v231 offset:512
	ds_read_b64_tr_b16 v[76:77], v231 offset:2048
	ds_read_b64_tr_b16 v[78:79], v231 offset:2560
	ds_read_b64_tr_b16 v[220:221], v231 offset:1024
	ds_read_b64_tr_b16 v[222:223], v231 offset:1536
	ds_read_b64_tr_b16 v[224:225], v231 offset:3072
	ds_read_b64_tr_b16 v[226:227], v231 offset:3584
	s_waitcnt vmcnt(8)
	ds_write_b128 v247, v[116:119]
	ds_write_b128 v247, v[120:123] offset:1024
	ds_write_b128 v111, v[124:127] offset:2048
	ds_write_b128 v111, v[128:131] offset:3072
	ds_read_b128 v[116:119], v248
	ds_read_b128 v[120:123], v249
	ds_read_b128 v[124:127], v250
	ds_read_b128 v[128:131], v251
	ds_write_b128 v112, v[132:135]
	ds_write_b128 v112, v[136:139] offset:1024
	ds_write_b128 v112, v[140:143] offset:2048
	ds_write_b128 v112, v[144:147] offset:3072
	v_mfma_f32_32x32x16_bf16 v[32:47], v[192:195], v[52:55], v[32:47]
	v_mfma_f32_32x32x16_bf16 v[32:47], v[196:199], v[56:59], v[32:47]
	v_mfma_f32_32x32x16_bf16 v[32:47], v[200:203], v[60:63], v[32:47]
	s_nop 11
	v_exp_f32_e32 v32, v32
	v_exp_f32_e32 v33, v33
	v_exp_f32_e32 v34, v34
	v_exp_f32_e32 v35, v35
	v_exp_f32_e32 v36, v36
	v_exp_f32_e32 v37, v37
	v_exp_f32_e32 v38, v38
	v_exp_f32_e32 v39, v39
	v_exp_f32_e32 v40, v40
	v_exp_f32_e32 v41, v41
	v_exp_f32_e32 v42, v42
	v_exp_f32_e32 v43, v43
	v_exp_f32_e32 v44, v44
	v_exp_f32_e32 v45, v45
	v_exp_f32_e32 v46, v46
	v_exp_f32_e32 v47, v47
	s_add_i32 s90, s67, 512
	v_lshlrev_b32_e32 v84, 2, v107
	v_add_u32_e32 v84, s90, v84
	v_add_u32_e32 v85, 0, v84
	v_add_u32_e32 v86, 4, v84
	v_add_u32_e32 v87, 8, v84
	v_add_u32_e32 v88, 12, v84
	v_cmp_gt_u32_e64 s[30:31], s98, v85
	v_cmp_gt_u32_e64 s[36:37], s98, v86
	v_cmp_gt_u32_e64 s[78:79], s98, v87
	v_cmp_gt_u32_e64 s[50:51], s98, v88
	v_cndmask_b32_e64 v32, 0, v32, s[30:31]
	v_add_u32_e32 v85, 32, v84
	v_cmp_gt_u32_e64 s[30:31], s98, v85
	v_cndmask_b32_e64 v33, 0, v33, s[36:37]
	v_add_u32_e32 v86, 36, v84
	v_cmp_gt_u32_e64 s[36:37], s98, v86
	v_cndmask_b32_e64 v34, 0, v34, s[78:79]
	v_add_u32_e32 v87, 40, v84
	v_cmp_gt_u32_e64 s[78:79], s98, v87
	v_cndmask_b32_e64 v35, 0, v35, s[50:51]
	v_add_u32_e32 v88, 44, v84
	v_cmp_gt_u32_e64 s[50:51], s98, v88
	v_cndmask_b32_e64 v36, 0, v36, s[30:31]
	v_add_u32_e32 v85, 64, v84
	v_cmp_gt_u32_e64 s[30:31], s98, v85
	v_cndmask_b32_e64 v37, 0, v37, s[36:37]
	v_add_u32_e32 v86, 68, v84
	v_cmp_gt_u32_e64 s[36:37], s98, v86
	v_cndmask_b32_e64 v38, 0, v38, s[78:79]
	v_add_u32_e32 v87, 72, v84
	v_cmp_gt_u32_e64 s[78:79], s98, v87
	v_cndmask_b32_e64 v39, 0, v39, s[50:51]
	v_add_u32_e32 v88, 76, v84
	v_cmp_gt_u32_e64 s[50:51], s98, v88
	v_cndmask_b32_e64 v40, 0, v40, s[30:31]
	v_add_u32_e32 v85, 96, v84
	v_cmp_gt_u32_e64 s[30:31], s98, v85
	v_cndmask_b32_e64 v41, 0, v41, s[36:37]
	v_add_u32_e32 v86, 100, v84
	v_cmp_gt_u32_e64 s[36:37], s98, v86
	v_cndmask_b32_e64 v42, 0, v42, s[78:79]
	v_add_u32_e32 v87, 104, v84
	v_cmp_gt_u32_e64 s[78:79], s98, v87
	v_cndmask_b32_e64 v43, 0, v43, s[50:51]
	v_add_u32_e32 v88, 108, v84
	v_cmp_gt_u32_e64 s[50:51], s98, v88
	v_nop
	v_cndmask_b32_e64 v44, 0, v44, s[30:31]
	v_cndmask_b32_e64 v45, 0, v45, s[36:37]
	v_cndmask_b32_e64 v46, 0, v46, s[78:79]
	v_cndmask_b32_e64 v47, 0, v47, s[50:51]
	v_cvt_pk_bf16_f32 v64, v32, v33
	v_cvt_pk_bf16_f32 v65, v34, v35
	v_cvt_pk_bf16_f32 v66, v36, v37
	v_cvt_pk_bf16_f32 v67, v38, v39
	v_cvt_pk_bf16_f32 v68, v40, v41
	v_cvt_pk_bf16_f32 v69, v42, v43
	v_cvt_pk_bf16_f32 v70, v44, v45
	v_cvt_pk_bf16_f32 v71, v46, v47
	v_pk_add_f32 v[232:233], v[232:233], v[32:33]
	v_pk_add_f32 v[232:233], v[232:233], v[34:35]
	v_pk_add_f32 v[232:233], v[232:233], v[36:37]
	v_pk_add_f32 v[232:233], v[232:233], v[38:39]
	v_pk_add_f32 v[232:233], v[232:233], v[40:41]
	v_pk_add_f32 v[232:233], v[232:233], v[42:43]
	v_pk_add_f32 v[232:233], v[232:233], v[44:45]
	v_pk_add_f32 v[232:233], v[232:233], v[46:47]
	ds_read2_b32 v[32:33], v115 offset0:120 offset1:121
	ds_read2_b32 v[34:35], v115 offset0:122 offset1:123
	ds_read2_b32 v[36:37], v115 offset0:130 offset1:131
	ds_read2_b32 v[38:39], v115 offset0:132 offset1:133
	ds_read2_b32 v[40:41], v115 offset0:140 offset1:141
	ds_read2_b32 v[42:43], v115 offset0:142 offset1:143
	ds_read2_b32 v[44:45], v115 offset0:150 offset1:151
	ds_read2_b32 v[46:47], v115 offset0:152 offset1:153
	s_waitcnt lgkmcnt(15)
	v_mfma_f32_32x32x16_bf16 v[0:15], v[64:67], v[72:75], v[0:15]
	v_mfma_f32_32x32x16_bf16 v[16:31], v[64:67], v[76:79], v[16:31]
	v_mfma_f32_32x32x16_bf16 v[0:15], v[68:71], v[220:223], v[0:15]
	v_mfma_f32_32x32x16_bf16 v[16:31], v[68:71], v[224:227], v[16:31]
	s_add_i32 s90, s67, -512
	v_add_u32_e32 v80, s90, v243
	v_add_u32_e32 v83, s90, v244
	v_add_u32_e32 v99, s90, v245
	v_add_u32_e32 v253, s90, v246
	v_add_u32_e32 v254, s90, v148
	v_add_u32_e32 v255, s90, v151
	v_med3_i32 v80, v80, 0, s99
	v_med3_i32 v83, v83, 0, s99
	v_med3_i32 v99, v99, 0, s99
	v_med3_i32 v253, v253, 0, s99
	v_med3_i32 v254, v254, 0, s99
	v_med3_i32 v255, v255, 0, s99
	v_mad_u32_u24 v80, v80, s100, v252
	v_mad_u32_u24 v83, v83, s100, v252
	v_mad_u32_u24 v99, v99, s100, v252
	v_mad_u32_u24 v253, v253, s100, v252
	v_mad_u32_u24 v254, v254, s100, v153
	v_mad_u32_u24 v255, v255, s100, v153
	global_load_dwordx4 v[188:191], v80, s[82:83]
	global_load_dwordx4 v[192:195], v83, s[82:83]
	global_load_dwordx4 v[196:199], v99, s[82:83]
	global_load_dwordx4 v[200:203], v253, s[82:83]
	global_load_dwordx4 v[204:207], v254, s[82:83] offset:768
	global_load_dwordx4 v[208:211], v255, s[82:83] offset:768
	global_load_dwordx4 v[212:215], v254, s[82:83] offset:832
	global_load_dwordx4 v[216:219], v255, s[82:83] offset:832
	s_waitcnt lgkmcnt(0)
	v_mfma_f32_32x32x16_bf16 v[32:47], v[116:119], v[48:51], v[32:47]
	ds_read_b64_tr_b16 v[72:73], v231
	ds_read_b64_tr_b16 v[74:75], v231 offset:512
	ds_read_b64_tr_b16 v[76:77], v231 offset:2048
	ds_read_b64_tr_b16 v[78:79], v231 offset:2560
	ds_read_b64_tr_b16 v[220:221], v231 offset:1024
	ds_read_b64_tr_b16 v[222:223], v231 offset:1536
	ds_read_b64_tr_b16 v[224:225], v231 offset:3072
	ds_read_b64_tr_b16 v[226:227], v231 offset:3584
	s_waitcnt vmcnt(8)
	ds_write_b128 v247, v[156:159]
	ds_write_b128 v247, v[160:163] offset:1024
	ds_write_b128 v111, v[164:167] offset:2048
	ds_write_b128 v111, v[168:171] offset:3072
	ds_read_b128 v[156:159], v248
	ds_read_b128 v[160:163], v249
	ds_read_b128 v[164:167], v250
	ds_read_b128 v[168:171], v251
	ds_write_b128 v112, v[172:175]
	ds_write_b128 v112, v[176:179] offset:1024
	ds_write_b128 v112, v[180:183] offset:2048
	ds_write_b128 v112, v[184:187] offset:3072
	v_mfma_f32_32x32x16_bf16 v[32:47], v[120:123], v[52:55], v[32:47]
	v_mfma_f32_32x32x16_bf16 v[32:47], v[124:127], v[56:59], v[32:47]
	v_mfma_f32_32x32x16_bf16 v[32:47], v[128:131], v[60:63], v[32:47]
	s_nop 11
	v_exp_f32_e32 v32, v32
	v_exp_f32_e32 v33, v33
	v_exp_f32_e32 v34, v34
	v_exp_f32_e32 v35, v35
	v_exp_f32_e32 v36, v36
	v_exp_f32_e32 v37, v37
	v_exp_f32_e32 v38, v38
	v_exp_f32_e32 v39, v39
	v_exp_f32_e32 v40, v40
	v_exp_f32_e32 v41, v41
	v_exp_f32_e32 v42, v42
	v_exp_f32_e32 v43, v43
	v_exp_f32_e32 v44, v44
	v_exp_f32_e32 v45, v45
	v_exp_f32_e32 v46, v46
	v_exp_f32_e32 v47, v47
	s_add_i32 s90, s67, 640
	v_lshlrev_b32_e32 v84, 2, v107
	v_add_u32_e32 v84, s90, v84
	v_add_u32_e32 v85, 0, v84
	v_add_u32_e32 v86, 4, v84
	v_add_u32_e32 v87, 8, v84
	v_add_u32_e32 v88, 12, v84
	v_cmp_gt_u32_e64 s[30:31], s98, v85
	v_cmp_gt_u32_e64 s[36:37], s98, v86
	v_cmp_gt_u32_e64 s[78:79], s98, v87
	v_cmp_gt_u32_e64 s[50:51], s98, v88
	v_cndmask_b32_e64 v32, 0, v32, s[30:31]
	v_add_u32_e32 v85, 32, v84
	v_cmp_gt_u32_e64 s[30:31], s98, v85
	v_cndmask_b32_e64 v33, 0, v33, s[36:37]
	v_add_u32_e32 v86, 36, v84
	v_cmp_gt_u32_e64 s[36:37], s98, v86
	v_cndmask_b32_e64 v34, 0, v34, s[78:79]
	v_add_u32_e32 v87, 40, v84
	v_cmp_gt_u32_e64 s[78:79], s98, v87
	v_cndmask_b32_e64 v35, 0, v35, s[50:51]
	v_add_u32_e32 v88, 44, v84
	v_cmp_gt_u32_e64 s[50:51], s98, v88
	v_cndmask_b32_e64 v36, 0, v36, s[30:31]
	v_add_u32_e32 v85, 64, v84
	v_cmp_gt_u32_e64 s[30:31], s98, v85
	v_cndmask_b32_e64 v37, 0, v37, s[36:37]
	v_add_u32_e32 v86, 68, v84
	v_cmp_gt_u32_e64 s[36:37], s98, v86
	v_cndmask_b32_e64 v38, 0, v38, s[78:79]
	v_add_u32_e32 v87, 72, v84
	v_cmp_gt_u32_e64 s[78:79], s98, v87
	v_cndmask_b32_e64 v39, 0, v39, s[50:51]
	v_add_u32_e32 v88, 76, v84
	v_cmp_gt_u32_e64 s[50:51], s98, v88
	v_cndmask_b32_e64 v40, 0, v40, s[30:31]
	v_add_u32_e32 v85, 96, v84
	v_cmp_gt_u32_e64 s[30:31], s98, v85
	v_cndmask_b32_e64 v41, 0, v41, s[36:37]
	v_add_u32_e32 v86, 100, v84
	v_cmp_gt_u32_e64 s[36:37], s98, v86
	v_cndmask_b32_e64 v42, 0, v42, s[78:79]
	v_add_u32_e32 v87, 104, v84
	v_cmp_gt_u32_e64 s[78:79], s98, v87
	v_cndmask_b32_e64 v43, 0, v43, s[50:51]
	v_add_u32_e32 v88, 108, v84
	v_cmp_gt_u32_e64 s[50:51], s98, v88
	v_nop
	v_cndmask_b32_e64 v44, 0, v44, s[30:31]
	v_cndmask_b32_e64 v45, 0, v45, s[36:37]
	v_cndmask_b32_e64 v46, 0, v46, s[78:79]
	v_cndmask_b32_e64 v47, 0, v47, s[50:51]
	v_cvt_pk_bf16_f32 v64, v32, v33
	v_cvt_pk_bf16_f32 v65, v34, v35
	v_cvt_pk_bf16_f32 v66, v36, v37
	v_cvt_pk_bf16_f32 v67, v38, v39
	v_cvt_pk_bf16_f32 v68, v40, v41
	v_cvt_pk_bf16_f32 v69, v42, v43
	v_cvt_pk_bf16_f32 v70, v44, v45
	v_cvt_pk_bf16_f32 v71, v46, v47
	v_pk_add_f32 v[232:233], v[232:233], v[32:33]
	v_pk_add_f32 v[232:233], v[232:233], v[34:35]
	v_pk_add_f32 v[232:233], v[232:233], v[36:37]
	v_pk_add_f32 v[232:233], v[232:233], v[38:39]
	v_pk_add_f32 v[232:233], v[232:233], v[40:41]
	v_pk_add_f32 v[232:233], v[232:233], v[42:43]
	v_pk_add_f32 v[232:233], v[232:233], v[44:45]
	v_pk_add_f32 v[232:233], v[232:233], v[46:47]
	v_mov_b32_e32 v115, v230
	ds_read2_b32 v[32:33], v115 offset0:0 offset1:1
	ds_read2_b32 v[34:35], v115 offset0:2 offset1:3
	ds_read2_b32 v[36:37], v115 offset0:8 offset1:9
	ds_read2_b32 v[38:39], v115 offset0:10 offset1:11
	ds_read2_b32 v[40:41], v115 offset0:16 offset1:17
	ds_read2_b32 v[42:43], v115 offset0:18 offset1:19
	ds_read2_b32 v[44:45], v115 offset0:24 offset1:25
	ds_read2_b32 v[46:47], v115 offset0:26 offset1:27
	s_waitcnt lgkmcnt(15)
	v_mfma_f32_32x32x16_bf16 v[0:15], v[64:67], v[72:75], v[0:15]
	v_mfma_f32_32x32x16_bf16 v[16:31], v[64:67], v[76:79], v[16:31]
	v_mfma_f32_32x32x16_bf16 v[0:15], v[68:71], v[220:223], v[0:15]
	v_mfma_f32_32x32x16_bf16 v[16:31], v[68:71], v[224:227], v[16:31]
	s_add_i32 s90, s67, 0
	v_add_u32_e32 v80, s90, v243
	v_add_u32_e32 v83, s90, v244
	v_add_u32_e32 v99, s90, v245
	v_add_u32_e32 v253, s90, v246
	v_add_u32_e32 v254, s90, v148
	v_add_u32_e32 v255, s90, v151
	v_med3_i32 v80, v80, 0, s99
	v_med3_i32 v83, v83, 0, s99
	v_med3_i32 v99, v99, 0, s99
	v_med3_i32 v253, v253, 0, s99
	v_med3_i32 v254, v254, 0, s99
	v_med3_i32 v255, v255, 0, s99
	v_mad_u32_u24 v80, v80, s100, v252
	v_mad_u32_u24 v83, v83, s100, v252
	v_mad_u32_u24 v99, v99, s100, v252
	v_mad_u32_u24 v253, v253, s100, v252
	v_mad_u32_u24 v254, v254, s100, v153
	v_mad_u32_u24 v255, v255, s100, v153
	global_load_dwordx4 v[116:119], v80, s[82:83]
	global_load_dwordx4 v[120:123], v83, s[82:83]
	global_load_dwordx4 v[124:127], v99, s[82:83]
	global_load_dwordx4 v[128:131], v253, s[82:83]
	global_load_dwordx4 v[132:135], v254, s[82:83] offset:768
	global_load_dwordx4 v[136:139], v255, s[82:83] offset:768
	global_load_dwordx4 v[140:143], v254, s[82:83] offset:832
	global_load_dwordx4 v[144:147], v255, s[82:83] offset:832
	s_waitcnt lgkmcnt(0)
	v_mfma_f32_32x32x16_bf16 v[32:47], v[156:159], v[48:51], v[32:47]
	ds_read_b64_tr_b16 v[72:73], v231
	ds_read_b64_tr_b16 v[74:75], v231 offset:512
	ds_read_b64_tr_b16 v[76:77], v231 offset:2048
	ds_read_b64_tr_b16 v[78:79], v231 offset:2560
	ds_read_b64_tr_b16 v[220:221], v231 offset:1024
	ds_read_b64_tr_b16 v[222:223], v231 offset:1536
	ds_read_b64_tr_b16 v[224:225], v231 offset:3072
	ds_read_b64_tr_b16 v[226:227], v231 offset:3584
	s_waitcnt vmcnt(8)
	ds_write_b128 v247, v[188:191]
	ds_write_b128 v247, v[192:195] offset:1024
	ds_write_b128 v111, v[196:199] offset:2048
	ds_write_b128 v111, v[200:203] offset:3072
	ds_read_b128 v[188:191], v248
	ds_read_b128 v[192:195], v249
	ds_read_b128 v[196:199], v250
	ds_read_b128 v[200:203], v251
	ds_write_b128 v112, v[204:207]
	ds_write_b128 v112, v[208:211] offset:1024
	ds_write_b128 v112, v[212:215] offset:2048
	ds_write_b128 v112, v[216:219] offset:3072
	v_mfma_f32_32x32x16_bf16 v[32:47], v[160:163], v[52:55], v[32:47]
	v_mfma_f32_32x32x16_bf16 v[32:47], v[164:167], v[56:59], v[32:47]
	v_mfma_f32_32x32x16_bf16 v[32:47], v[168:171], v[60:63], v[32:47]
	s_nop 11
	v_exp_f32_e32 v32, v32
	v_exp_f32_e32 v33, v33
	v_exp_f32_e32 v34, v34
	v_exp_f32_e32 v35, v35
	v_exp_f32_e32 v36, v36
	v_exp_f32_e32 v37, v37
	v_exp_f32_e32 v38, v38
	v_exp_f32_e32 v39, v39
	v_exp_f32_e32 v40, v40
	v_exp_f32_e32 v41, v41
	v_exp_f32_e32 v42, v42
	v_exp_f32_e32 v43, v43
	v_exp_f32_e32 v44, v44
	v_exp_f32_e32 v45, v45
	v_exp_f32_e32 v46, v46
	v_exp_f32_e32 v47, v47
	s_add_i32 s90, s67, -1024
	v_lshlrev_b32_e32 v84, 4, v107
	v_add_u32_e32 v84, s90, v84
	v_add_u32_e32 v85, 0, v84
	v_add_u32_e32 v86, 16, v84
	v_add_u32_e32 v87, 32, v84
	v_add_u32_e32 v88, 48, v84
	v_cmp_gt_u32_e64 s[30:31], s98, v85
	v_cmp_gt_u32_e64 s[36:37], s98, v86
	v_cmp_gt_u32_e64 s[78:79], s98, v87
	v_cmp_gt_u32_e64 s[50:51], s98, v88
	v_cndmask_b32_e64 v32, 0, v32, s[30:31]
	v_add_u32_e32 v85, 128, v84
	v_cmp_gt_u32_e64 s[30:31], s98, v85
	v_cndmask_b32_e64 v33, 0, v33, s[36:37]
	v_add_u32_e32 v86, 144, v84
	v_cmp_gt_u32_e64 s[36:37], s98, v86
	v_cndmask_b32_e64 v34, 0, v34, s[78:79]
	v_add_u32_e32 v87, 160, v84
	v_cmp_gt_u32_e64 s[78:79], s98, v87
	v_cndmask_b32_e64 v35, 0, v35, s[50:51]
	v_add_u32_e32 v88, 176, v84
	v_cmp_gt_u32_e64 s[50:51], s98, v88
	v_cndmask_b32_e64 v36, 0, v36, s[30:31]
	v_add_u32_e32 v85, 256, v84
	v_cmp_gt_u32_e64 s[30:31], s98, v85
	v_cndmask_b32_e64 v37, 0, v37, s[36:37]
	v_add_u32_e32 v86, 272, v84
	v_cmp_gt_u32_e64 s[36:37], s98, v86
	v_cndmask_b32_e64 v38, 0, v38, s[78:79]
	v_add_u32_e32 v87, 288, v84
	v_cmp_gt_u32_e64 s[78:79], s98, v87
	v_cndmask_b32_e64 v39, 0, v39, s[50:51]
	v_add_u32_e32 v88, 304, v84
	v_cmp_gt_u32_e64 s[50:51], s98, v88
	v_cndmask_b32_e64 v40, 0, v40, s[30:31]
	v_add_u32_e32 v85, 384, v84
	v_cmp_gt_u32_e64 s[30:31], s98, v85
	v_cndmask_b32_e64 v41, 0, v41, s[36:37]
	v_add_u32_e32 v86, 400, v84
	v_cmp_gt_u32_e64 s[36:37], s98, v86
	v_cndmask_b32_e64 v42, 0, v42, s[78:79]
	v_add_u32_e32 v87, 416, v84
	v_cmp_gt_u32_e64 s[78:79], s98, v87
	v_cndmask_b32_e64 v43, 0, v43, s[50:51]
	v_add_u32_e32 v88, 432, v84
	v_cmp_gt_u32_e64 s[50:51], s98, v88
	v_nop
	v_cndmask_b32_e64 v44, 0, v44, s[30:31]
	v_cndmask_b32_e64 v45, 0, v45, s[36:37]
	v_cndmask_b32_e64 v46, 0, v46, s[78:79]
	v_cndmask_b32_e64 v47, 0, v47, s[50:51]
	v_cvt_pk_bf16_f32 v64, v32, v33
	v_cvt_pk_bf16_f32 v65, v34, v35
	v_cvt_pk_bf16_f32 v66, v36, v37
	v_cvt_pk_bf16_f32 v67, v38, v39
	v_cvt_pk_bf16_f32 v68, v40, v41
	v_cvt_pk_bf16_f32 v69, v42, v43
	v_cvt_pk_bf16_f32 v70, v44, v45
	v_cvt_pk_bf16_f32 v71, v46, v47
	v_pk_add_f32 v[232:233], v[232:233], v[32:33]
	v_pk_add_f32 v[232:233], v[232:233], v[34:35]
	v_pk_add_f32 v[232:233], v[232:233], v[36:37]
	v_pk_add_f32 v[232:233], v[232:233], v[38:39]
	v_pk_add_f32 v[232:233], v[232:233], v[40:41]
	v_pk_add_f32 v[232:233], v[232:233], v[42:43]
	v_pk_add_f32 v[232:233], v[232:233], v[44:45]
	v_pk_add_f32 v[232:233], v[232:233], v[46:47]
	ds_read2_b32 v[32:33], v115 offset0:32 offset1:33
	ds_read2_b32 v[34:35], v115 offset0:34 offset1:35
	ds_read2_b32 v[36:37], v115 offset0:40 offset1:41
	ds_read2_b32 v[38:39], v115 offset0:42 offset1:43
	ds_read2_b32 v[40:41], v115 offset0:48 offset1:49
	ds_read2_b32 v[42:43], v115 offset0:50 offset1:51
	ds_read2_b32 v[44:45], v115 offset0:56 offset1:57
	ds_read2_b32 v[46:47], v115 offset0:58 offset1:59
	s_waitcnt lgkmcnt(15)
	v_mfma_f32_32x32x16_bf16 v[0:15], v[64:67], v[72:75], v[0:15]
	v_mfma_f32_32x32x16_bf16 v[16:31], v[64:67], v[76:79], v[16:31]
	v_mfma_f32_32x32x16_bf16 v[0:15], v[68:71], v[220:223], v[0:15]
	v_mfma_f32_32x32x16_bf16 v[16:31], v[68:71], v[224:227], v[16:31]
	s_add_i32 s90, s67, 512
	v_add_u32_e32 v80, s90, v243
	v_add_u32_e32 v83, s90, v244
	v_add_u32_e32 v99, s90, v245
	v_add_u32_e32 v253, s90, v246
	v_add_u32_e32 v254, s90, v148
	v_add_u32_e32 v255, s90, v151
	v_med3_i32 v80, v80, 0, s99
	v_med3_i32 v83, v83, 0, s99
	v_med3_i32 v99, v99, 0, s99
	v_med3_i32 v253, v253, 0, s99
	v_med3_i32 v254, v254, 0, s99
	v_med3_i32 v255, v255, 0, s99
	v_mad_u32_u24 v80, v80, s100, v252
	v_mad_u32_u24 v83, v83, s100, v252
	v_mad_u32_u24 v99, v99, s100, v252
	v_mad_u32_u24 v253, v253, s100, v252
	v_mad_u32_u24 v254, v254, s100, v153
	v_mad_u32_u24 v255, v255, s100, v153
	global_load_dwordx4 v[156:159], v80, s[82:83]
	global_load_dwordx4 v[160:163], v83, s[82:83]
	global_load_dwordx4 v[164:167], v99, s[82:83]
	global_load_dwordx4 v[168:171], v253, s[82:83]
	global_load_dwordx4 v[172:175], v254, s[82:83] offset:768
	global_load_dwordx4 v[176:179], v255, s[82:83] offset:768
	global_load_dwordx4 v[180:183], v254, s[82:83] offset:832
	global_load_dwordx4 v[184:187], v255, s[82:83] offset:832
	s_waitcnt lgkmcnt(0)
	v_mfma_f32_32x32x16_bf16 v[32:47], v[188:191], v[48:51], v[32:47]
	ds_read_b64_tr_b16 v[72:73], v231
	ds_read_b64_tr_b16 v[74:75], v231 offset:512
	ds_read_b64_tr_b16 v[76:77], v231 offset:2048
	ds_read_b64_tr_b16 v[78:79], v231 offset:2560
	ds_read_b64_tr_b16 v[220:221], v231 offset:1024
	ds_read_b64_tr_b16 v[222:223], v231 offset:1536
	ds_read_b64_tr_b16 v[224:225], v231 offset:3072
	ds_read_b64_tr_b16 v[226:227], v231 offset:3584
	s_waitcnt vmcnt(8)
	ds_write_b128 v247, v[116:119]
	ds_write_b128 v247, v[120:123] offset:1024
	ds_write_b128 v111, v[124:127] offset:2048
	ds_write_b128 v111, v[128:131] offset:3072
	ds_read_b128 v[116:119], v248
	ds_read_b128 v[120:123], v249
	ds_read_b128 v[124:127], v250
	ds_read_b128 v[128:131], v251
	ds_write_b128 v112, v[132:135]
	ds_write_b128 v112, v[136:139] offset:1024
	ds_write_b128 v112, v[140:143] offset:2048
	ds_write_b128 v112, v[144:147] offset:3072
	v_mfma_f32_32x32x16_bf16 v[32:47], v[192:195], v[52:55], v[32:47]
	v_mfma_f32_32x32x16_bf16 v[32:47], v[196:199], v[56:59], v[32:47]
	v_mfma_f32_32x32x16_bf16 v[32:47], v[200:203], v[60:63], v[32:47]
	s_nop 11
	v_exp_f32_e32 v32, v32
	v_exp_f32_e32 v33, v33
	v_exp_f32_e32 v34, v34
	v_exp_f32_e32 v35, v35
	v_exp_f32_e32 v36, v36
	v_exp_f32_e32 v37, v37
	v_exp_f32_e32 v38, v38
	v_exp_f32_e32 v39, v39
	v_exp_f32_e32 v40, v40
	v_exp_f32_e32 v41, v41
	v_exp_f32_e32 v42, v42
	v_exp_f32_e32 v43, v43
	v_exp_f32_e32 v44, v44
	v_exp_f32_e32 v45, v45
	v_exp_f32_e32 v46, v46
	v_exp_f32_e32 v47, v47
	s_add_i32 s90, s67, -512
	v_lshlrev_b32_e32 v84, 4, v107
	v_add_u32_e32 v84, s90, v84
	v_add_u32_e32 v85, 0, v84
	v_add_u32_e32 v86, 16, v84
	v_add_u32_e32 v87, 32, v84
	v_add_u32_e32 v88, 48, v84
	v_cmp_gt_u32_e64 s[30:31], s98, v85
	v_cmp_gt_u32_e64 s[36:37], s98, v86
	v_cmp_gt_u32_e64 s[78:79], s98, v87
	v_cmp_gt_u32_e64 s[50:51], s98, v88
	v_cndmask_b32_e64 v32, 0, v32, s[30:31]
	v_add_u32_e32 v85, 128, v84
	v_cmp_gt_u32_e64 s[30:31], s98, v85
	v_cndmask_b32_e64 v33, 0, v33, s[36:37]
	v_add_u32_e32 v86, 144, v84
	v_cmp_gt_u32_e64 s[36:37], s98, v86
	v_cndmask_b32_e64 v34, 0, v34, s[78:79]
	v_add_u32_e32 v87, 160, v84
	v_cmp_gt_u32_e64 s[78:79], s98, v87
	v_cndmask_b32_e64 v35, 0, v35, s[50:51]
	v_add_u32_e32 v88, 176, v84
	v_cmp_gt_u32_e64 s[50:51], s98, v88
	v_cndmask_b32_e64 v36, 0, v36, s[30:31]
	v_add_u32_e32 v85, 256, v84
	v_cmp_gt_u32_e64 s[30:31], s98, v85
	v_cndmask_b32_e64 v37, 0, v37, s[36:37]
	v_add_u32_e32 v86, 272, v84
	v_cmp_gt_u32_e64 s[36:37], s98, v86
	v_cndmask_b32_e64 v38, 0, v38, s[78:79]
	v_add_u32_e32 v87, 288, v84
	v_cmp_gt_u32_e64 s[78:79], s98, v87
	v_cndmask_b32_e64 v39, 0, v39, s[50:51]
	v_add_u32_e32 v88, 304, v84
	v_cmp_gt_u32_e64 s[50:51], s98, v88
	v_cndmask_b32_e64 v40, 0, v40, s[30:31]
	v_add_u32_e32 v85, 384, v84
	v_cmp_gt_u32_e64 s[30:31], s98, v85
	v_cndmask_b32_e64 v41, 0, v41, s[36:37]
	v_add_u32_e32 v86, 400, v84
	v_cmp_gt_u32_e64 s[36:37], s98, v86
	v_cndmask_b32_e64 v42, 0, v42, s[78:79]
	v_add_u32_e32 v87, 416, v84
	v_cmp_gt_u32_e64 s[78:79], s98, v87
	v_cndmask_b32_e64 v43, 0, v43, s[50:51]
	v_add_u32_e32 v88, 432, v84
	v_cmp_gt_u32_e64 s[50:51], s98, v88
	v_nop
	v_cndmask_b32_e64 v44, 0, v44, s[30:31]
	v_cndmask_b32_e64 v45, 0, v45, s[36:37]
	v_cndmask_b32_e64 v46, 0, v46, s[78:79]
	v_cndmask_b32_e64 v47, 0, v47, s[50:51]
	v_cvt_pk_bf16_f32 v64, v32, v33
	v_cvt_pk_bf16_f32 v65, v34, v35
	v_cvt_pk_bf16_f32 v66, v36, v37
	v_cvt_pk_bf16_f32 v67, v38, v39
	v_cvt_pk_bf16_f32 v68, v40, v41
	v_cvt_pk_bf16_f32 v69, v42, v43
	v_cvt_pk_bf16_f32 v70, v44, v45
	v_cvt_pk_bf16_f32 v71, v46, v47
	v_pk_add_f32 v[232:233], v[232:233], v[32:33]
	v_pk_add_f32 v[232:233], v[232:233], v[34:35]
	v_pk_add_f32 v[232:233], v[232:233], v[36:37]
	v_pk_add_f32 v[232:233], v[232:233], v[38:39]
	v_pk_add_f32 v[232:233], v[232:233], v[40:41]
	v_pk_add_f32 v[232:233], v[232:233], v[42:43]
	v_pk_add_f32 v[232:233], v[232:233], v[44:45]
	v_pk_add_f32 v[232:233], v[232:233], v[46:47]
	ds_read2_b32 v[32:33], v115 offset0:64 offset1:65
	ds_read2_b32 v[34:35], v115 offset0:66 offset1:67
	ds_read2_b32 v[36:37], v115 offset0:72 offset1:73
	ds_read2_b32 v[38:39], v115 offset0:74 offset1:75
	ds_read2_b32 v[40:41], v115 offset0:80 offset1:81
	ds_read2_b32 v[42:43], v115 offset0:82 offset1:83
	ds_read2_b32 v[44:45], v115 offset0:88 offset1:89
	ds_read2_b32 v[46:47], v115 offset0:90 offset1:91
	s_waitcnt lgkmcnt(15)
	v_mfma_f32_32x32x16_bf16 v[0:15], v[64:67], v[72:75], v[0:15]
	v_mfma_f32_32x32x16_bf16 v[16:31], v[64:67], v[76:79], v[16:31]
	v_mfma_f32_32x32x16_bf16 v[0:15], v[68:71], v[220:223], v[0:15]
	v_mfma_f32_32x32x16_bf16 v[16:31], v[68:71], v[224:227], v[16:31]
	s_add_i32 s90, s67, 1024
	v_add_u32_e32 v80, s90, v243
	v_add_u32_e32 v83, s90, v244
	v_add_u32_e32 v99, s90, v245
	v_add_u32_e32 v253, s90, v246
	v_add_u32_e32 v254, s90, v148
	v_add_u32_e32 v255, s90, v151
	v_med3_i32 v80, v80, 0, s99
	v_med3_i32 v83, v83, 0, s99
	v_med3_i32 v99, v99, 0, s99
	v_med3_i32 v253, v253, 0, s99
	v_med3_i32 v254, v254, 0, s99
	v_med3_i32 v255, v255, 0, s99
	v_mad_u32_u24 v80, v80, s100, v252
	v_mad_u32_u24 v83, v83, s100, v252
	v_mad_u32_u24 v99, v99, s100, v252
	v_mad_u32_u24 v253, v253, s100, v252
	v_mad_u32_u24 v254, v254, s100, v153
	v_mad_u32_u24 v255, v255, s100, v153
	global_load_dwordx4 v[188:191], v80, s[82:83]
	global_load_dwordx4 v[192:195], v83, s[82:83]
	global_load_dwordx4 v[196:199], v99, s[82:83]
	global_load_dwordx4 v[200:203], v253, s[82:83]
	global_load_dwordx4 v[204:207], v254, s[82:83] offset:768
	global_load_dwordx4 v[208:211], v255, s[82:83] offset:768
	global_load_dwordx4 v[212:215], v254, s[82:83] offset:832
	global_load_dwordx4 v[216:219], v255, s[82:83] offset:832
	s_waitcnt lgkmcnt(0)
	v_mfma_f32_32x32x16_bf16 v[32:47], v[116:119], v[48:51], v[32:47]
	ds_read_b64_tr_b16 v[72:73], v231
	ds_read_b64_tr_b16 v[74:75], v231 offset:512
	ds_read_b64_tr_b16 v[76:77], v231 offset:2048
	ds_read_b64_tr_b16 v[78:79], v231 offset:2560
	ds_read_b64_tr_b16 v[220:221], v231 offset:1024
	ds_read_b64_tr_b16 v[222:223], v231 offset:1536
	ds_read_b64_tr_b16 v[224:225], v231 offset:3072
	ds_read_b64_tr_b16 v[226:227], v231 offset:3584
	s_waitcnt vmcnt(8)
	ds_write_b128 v247, v[156:159]
	ds_write_b128 v247, v[160:163] offset:1024
	ds_write_b128 v111, v[164:167] offset:2048
	ds_write_b128 v111, v[168:171] offset:3072
	ds_read_b128 v[156:159], v248
	ds_read_b128 v[160:163], v249
	ds_read_b128 v[164:167], v250
	ds_read_b128 v[168:171], v251
	ds_write_b128 v112, v[172:175]
	ds_write_b128 v112, v[176:179] offset:1024
	ds_write_b128 v112, v[180:183] offset:2048
	ds_write_b128 v112, v[184:187] offset:3072
	v_mfma_f32_32x32x16_bf16 v[32:47], v[120:123], v[52:55], v[32:47]
	v_mfma_f32_32x32x16_bf16 v[32:47], v[124:127], v[56:59], v[32:47]
	v_mfma_f32_32x32x16_bf16 v[32:47], v[128:131], v[60:63], v[32:47]
	s_nop 11
	v_exp_f32_e32 v32, v32
	v_exp_f32_e32 v33, v33
	v_exp_f32_e32 v34, v34
	v_exp_f32_e32 v35, v35
	v_exp_f32_e32 v36, v36
	v_exp_f32_e32 v37, v37
	v_exp_f32_e32 v38, v38
	v_exp_f32_e32 v39, v39
	v_exp_f32_e32 v40, v40
	v_exp_f32_e32 v41, v41
	v_exp_f32_e32 v42, v42
	v_exp_f32_e32 v43, v43
	v_exp_f32_e32 v44, v44
	v_exp_f32_e32 v45, v45
	v_exp_f32_e32 v46, v46
	v_exp_f32_e32 v47, v47
	s_add_i32 s90, s67, 0
	v_lshlrev_b32_e32 v84, 4, v107
	v_add_u32_e32 v84, s90, v84
	v_add_u32_e32 v85, 0, v84
	v_add_u32_e32 v86, 16, v84
	v_add_u32_e32 v87, 32, v84
	v_add_u32_e32 v88, 48, v84
	v_cmp_gt_u32_e64 s[30:31], s98, v85
	v_cmp_gt_u32_e64 s[36:37], s98, v86
	v_cmp_gt_u32_e64 s[78:79], s98, v87
	v_cmp_gt_u32_e64 s[50:51], s98, v88
	v_cndmask_b32_e64 v32, 0, v32, s[30:31]
	v_add_u32_e32 v85, 128, v84
	v_cmp_gt_u32_e64 s[30:31], s98, v85
	v_cndmask_b32_e64 v33, 0, v33, s[36:37]
	v_add_u32_e32 v86, 144, v84
	v_cmp_gt_u32_e64 s[36:37], s98, v86
	v_cndmask_b32_e64 v34, 0, v34, s[78:79]
	v_add_u32_e32 v87, 160, v84
	v_cmp_gt_u32_e64 s[78:79], s98, v87
	v_cndmask_b32_e64 v35, 0, v35, s[50:51]
	v_add_u32_e32 v88, 176, v84
	v_cmp_gt_u32_e64 s[50:51], s98, v88
	v_cndmask_b32_e64 v36, 0, v36, s[30:31]
	v_add_u32_e32 v85, 256, v84
	v_cmp_gt_u32_e64 s[30:31], s98, v85
	v_cndmask_b32_e64 v37, 0, v37, s[36:37]
	v_add_u32_e32 v86, 272, v84
	v_cmp_gt_u32_e64 s[36:37], s98, v86
	v_cndmask_b32_e64 v38, 0, v38, s[78:79]
	v_add_u32_e32 v87, 288, v84
	v_cmp_gt_u32_e64 s[78:79], s98, v87
	v_cndmask_b32_e64 v39, 0, v39, s[50:51]
	v_add_u32_e32 v88, 304, v84
	v_cmp_gt_u32_e64 s[50:51], s98, v88
	v_cndmask_b32_e64 v40, 0, v40, s[30:31]
	v_add_u32_e32 v85, 384, v84
	v_cmp_gt_u32_e64 s[30:31], s98, v85
	v_cndmask_b32_e64 v41, 0, v41, s[36:37]
	v_add_u32_e32 v86, 400, v84
	v_cmp_gt_u32_e64 s[36:37], s98, v86
	v_cndmask_b32_e64 v42, 0, v42, s[78:79]
	v_add_u32_e32 v87, 416, v84
	v_cmp_gt_u32_e64 s[78:79], s98, v87
	v_cndmask_b32_e64 v43, 0, v43, s[50:51]
	v_add_u32_e32 v88, 432, v84
	v_cmp_gt_u32_e64 s[50:51], s98, v88
	v_nop
	v_cndmask_b32_e64 v44, 0, v44, s[30:31]
	v_cndmask_b32_e64 v45, 0, v45, s[36:37]
	v_cndmask_b32_e64 v46, 0, v46, s[78:79]
	v_cndmask_b32_e64 v47, 0, v47, s[50:51]
	v_cvt_pk_bf16_f32 v64, v32, v33
	v_cvt_pk_bf16_f32 v65, v34, v35
	v_cvt_pk_bf16_f32 v66, v36, v37
	v_cvt_pk_bf16_f32 v67, v38, v39
	v_cvt_pk_bf16_f32 v68, v40, v41
	v_cvt_pk_bf16_f32 v69, v42, v43
	v_cvt_pk_bf16_f32 v70, v44, v45
	v_cvt_pk_bf16_f32 v71, v46, v47
	v_pk_add_f32 v[232:233], v[232:233], v[32:33]
	v_pk_add_f32 v[232:233], v[232:233], v[34:35]
	v_pk_add_f32 v[232:233], v[232:233], v[36:37]
	v_pk_add_f32 v[232:233], v[232:233], v[38:39]
	v_pk_add_f32 v[232:233], v[232:233], v[40:41]
	v_pk_add_f32 v[232:233], v[232:233], v[42:43]
	v_pk_add_f32 v[232:233], v[232:233], v[44:45]
	v_pk_add_f32 v[232:233], v[232:233], v[46:47]
	ds_read2_b32 v[32:33], v115 offset0:96 offset1:97
	ds_read2_b32 v[34:35], v115 offset0:98 offset1:99
	ds_read2_b32 v[36:37], v115 offset0:104 offset1:105
	ds_read2_b32 v[38:39], v115 offset0:106 offset1:107
	ds_read2_b32 v[40:41], v115 offset0:112 offset1:113
	ds_read2_b32 v[42:43], v115 offset0:114 offset1:115
	ds_read2_b32 v[44:45], v115 offset0:120 offset1:121
	ds_read2_b32 v[46:47], v115 offset0:122 offset1:123
	s_waitcnt lgkmcnt(15)
	v_mfma_f32_32x32x16_bf16 v[0:15], v[64:67], v[72:75], v[0:15]
	v_mfma_f32_32x32x16_bf16 v[16:31], v[64:67], v[76:79], v[16:31]
	v_mfma_f32_32x32x16_bf16 v[0:15], v[68:71], v[220:223], v[0:15]
	v_mfma_f32_32x32x16_bf16 v[16:31], v[68:71], v[224:227], v[16:31]
	s_waitcnt lgkmcnt(0)
	v_mfma_f32_32x32x16_bf16 v[32:47], v[156:159], v[48:51], v[32:47]
	ds_read_b64_tr_b16 v[72:73], v231
	ds_read_b64_tr_b16 v[74:75], v231 offset:512
	ds_read_b64_tr_b16 v[76:77], v231 offset:2048
	ds_read_b64_tr_b16 v[78:79], v231 offset:2560
	ds_read_b64_tr_b16 v[220:221], v231 offset:1024
	ds_read_b64_tr_b16 v[222:223], v231 offset:1536
	ds_read_b64_tr_b16 v[224:225], v231 offset:3072
	ds_read_b64_tr_b16 v[226:227], v231 offset:3584
	s_waitcnt vmcnt(0)
	ds_write_b128 v247, v[188:191]
	ds_write_b128 v247, v[192:195] offset:1024
	ds_write_b128 v111, v[196:199] offset:2048
	ds_write_b128 v111, v[200:203] offset:3072
	ds_read_b128 v[188:191], v248
	ds_read_b128 v[192:195], v249
	ds_read_b128 v[196:199], v250
	ds_read_b128 v[200:203], v251
	ds_write_b128 v112, v[204:207]
	ds_write_b128 v112, v[208:211] offset:1024
	ds_write_b128 v112, v[212:215] offset:2048
	ds_write_b128 v112, v[216:219] offset:3072
	v_mfma_f32_32x32x16_bf16 v[32:47], v[160:163], v[52:55], v[32:47]
	v_mfma_f32_32x32x16_bf16 v[32:47], v[164:167], v[56:59], v[32:47]
	v_mfma_f32_32x32x16_bf16 v[32:47], v[168:171], v[60:63], v[32:47]
	s_nop 11
	v_exp_f32_e32 v32, v32
	v_exp_f32_e32 v33, v33
	v_exp_f32_e32 v34, v34
	v_exp_f32_e32 v35, v35
	v_exp_f32_e32 v36, v36
	v_exp_f32_e32 v37, v37
	v_exp_f32_e32 v38, v38
	v_exp_f32_e32 v39, v39
	v_exp_f32_e32 v40, v40
	v_exp_f32_e32 v41, v41
	v_exp_f32_e32 v42, v42
	v_exp_f32_e32 v43, v43
	v_exp_f32_e32 v44, v44
	v_exp_f32_e32 v45, v45
	v_exp_f32_e32 v46, v46
	v_exp_f32_e32 v47, v47
	s_add_i32 s90, s67, 512
	v_lshlrev_b32_e32 v84, 4, v107
	v_add_u32_e32 v84, s90, v84
	v_add_u32_e32 v85, 0, v84
	v_add_u32_e32 v86, 16, v84
	v_add_u32_e32 v87, 32, v84
	v_add_u32_e32 v88, 48, v84
	v_cmp_gt_u32_e64 s[30:31], s98, v85
	v_cmp_gt_u32_e64 s[36:37], s98, v86
	v_cmp_gt_u32_e64 s[78:79], s98, v87
	v_cmp_gt_u32_e64 s[50:51], s98, v88
	v_cndmask_b32_e64 v32, 0, v32, s[30:31]
	v_add_u32_e32 v85, 128, v84
	v_cmp_gt_u32_e64 s[30:31], s98, v85
	v_cndmask_b32_e64 v33, 0, v33, s[36:37]
	v_add_u32_e32 v86, 144, v84
	v_cmp_gt_u32_e64 s[36:37], s98, v86
	v_cndmask_b32_e64 v34, 0, v34, s[78:79]
	v_add_u32_e32 v87, 160, v84
	v_cmp_gt_u32_e64 s[78:79], s98, v87
	v_cndmask_b32_e64 v35, 0, v35, s[50:51]
	v_add_u32_e32 v88, 176, v84
	v_cmp_gt_u32_e64 s[50:51], s98, v88
	v_cndmask_b32_e64 v36, 0, v36, s[30:31]
	v_add_u32_e32 v85, 256, v84
	v_cmp_gt_u32_e64 s[30:31], s98, v85
	v_cndmask_b32_e64 v37, 0, v37, s[36:37]
	v_add_u32_e32 v86, 272, v84
	v_cmp_gt_u32_e64 s[36:37], s98, v86
	v_cndmask_b32_e64 v38, 0, v38, s[78:79]
	v_add_u32_e32 v87, 288, v84
	v_cmp_gt_u32_e64 s[78:79], s98, v87
	v_cndmask_b32_e64 v39, 0, v39, s[50:51]
	v_add_u32_e32 v88, 304, v84
	v_cmp_gt_u32_e64 s[50:51], s98, v88
	v_cndmask_b32_e64 v40, 0, v40, s[30:31]
	v_add_u32_e32 v85, 384, v84
	v_cmp_gt_u32_e64 s[30:31], s98, v85
	v_cndmask_b32_e64 v41, 0, v41, s[36:37]
	v_add_u32_e32 v86, 400, v84
	v_cmp_gt_u32_e64 s[36:37], s98, v86
	v_cndmask_b32_e64 v42, 0, v42, s[78:79]
	v_add_u32_e32 v87, 416, v84
	v_cmp_gt_u32_e64 s[78:79], s98, v87
	v_cndmask_b32_e64 v43, 0, v43, s[50:51]
	v_add_u32_e32 v88, 432, v84
	v_cmp_gt_u32_e64 s[50:51], s98, v88
	v_nop
	v_cndmask_b32_e64 v44, 0, v44, s[30:31]
	v_cndmask_b32_e64 v45, 0, v45, s[36:37]
	v_cndmask_b32_e64 v46, 0, v46, s[78:79]
	v_cndmask_b32_e64 v47, 0, v47, s[50:51]
	v_cvt_pk_bf16_f32 v64, v32, v33
	v_cvt_pk_bf16_f32 v65, v34, v35
	v_cvt_pk_bf16_f32 v66, v36, v37
	v_cvt_pk_bf16_f32 v67, v38, v39
	v_cvt_pk_bf16_f32 v68, v40, v41
	v_cvt_pk_bf16_f32 v69, v42, v43
	v_cvt_pk_bf16_f32 v70, v44, v45
	v_cvt_pk_bf16_f32 v71, v46, v47
	v_pk_add_f32 v[232:233], v[232:233], v[32:33]
	v_pk_add_f32 v[232:233], v[232:233], v[34:35]
	v_pk_add_f32 v[232:233], v[232:233], v[36:37]
	v_pk_add_f32 v[232:233], v[232:233], v[38:39]
	v_pk_add_f32 v[232:233], v[232:233], v[40:41]
	v_pk_add_f32 v[232:233], v[232:233], v[42:43]
	v_pk_add_f32 v[232:233], v[232:233], v[44:45]
	v_pk_add_f32 v[232:233], v[232:233], v[46:47]
	ds_read2_b32 v[32:33], v115 offset0:128 offset1:129
	ds_read2_b32 v[34:35], v115 offset0:130 offset1:131
	ds_read2_b32 v[36:37], v115 offset0:136 offset1:137
	ds_read2_b32 v[38:39], v115 offset0:138 offset1:139
	ds_read2_b32 v[40:41], v115 offset0:144 offset1:145
	ds_read2_b32 v[42:43], v115 offset0:146 offset1:147
	ds_read2_b32 v[44:45], v115 offset0:152 offset1:153
	ds_read2_b32 v[46:47], v115 offset0:154 offset1:155
	s_waitcnt lgkmcnt(15)
	v_mfma_f32_32x32x16_bf16 v[0:15], v[64:67], v[72:75], v[0:15]
	v_mfma_f32_32x32x16_bf16 v[16:31], v[64:67], v[76:79], v[16:31]
	v_mfma_f32_32x32x16_bf16 v[0:15], v[68:71], v[220:223], v[0:15]
	v_mfma_f32_32x32x16_bf16 v[16:31], v[68:71], v[224:227], v[16:31]
	s_waitcnt lgkmcnt(0)
; __device__ __forceinline__ int crow(int r, int hi) { return (r & 3) + 8 * (r >> 2) + 4 * hi; }
; __device__ __forceinline__ void dil_unit(LAS unsigned char* lds, bf16_t* proj, int seq, int hd, int T0, int rho) {
;     ...
;     l += __shfl_xor(l, 32);
; #pragma unroll
;     for (int rr = 0; rr < 16; ++rr) {
;         const int j = crow(rr, hi);
	v_mfma_f32_32x32x16_bf16 v[32:47], v[188:191], v[48:51], v[32:47]
	ds_read_b64_tr_b16 v[72:73], v231
	ds_read_b64_tr_b16 v[74:75], v231 offset:512
	ds_read_b64_tr_b16 v[76:77], v231 offset:2048
	ds_read_b64_tr_b16 v[78:79], v231 offset:2560
	ds_read_b64_tr_b16 v[220:221], v231 offset:1024
	ds_read_b64_tr_b16 v[222:223], v231 offset:1536
	ds_read_b64_tr_b16 v[224:225], v231 offset:3072
	ds_read_b64_tr_b16 v[226:227], v231 offset:3584
	v_mfma_f32_32x32x16_bf16 v[32:47], v[192:195], v[52:55], v[32:47]
	v_mfma_f32_32x32x16_bf16 v[32:47], v[196:199], v[56:59], v[32:47]
	v_mfma_f32_32x32x16_bf16 v[32:47], v[200:203], v[60:63], v[32:47]
	s_nop 11
	v_exp_f32_e32 v32, v32
	v_exp_f32_e32 v33, v33
	v_exp_f32_e32 v34, v34
	v_exp_f32_e32 v35, v35
	v_exp_f32_e32 v36, v36
	v_exp_f32_e32 v37, v37
	v_exp_f32_e32 v38, v38
	v_exp_f32_e32 v39, v39
	v_exp_f32_e32 v40, v40
	v_exp_f32_e32 v41, v41
	v_exp_f32_e32 v42, v42
	v_exp_f32_e32 v43, v43
	v_exp_f32_e32 v44, v44
	v_exp_f32_e32 v45, v45
	v_exp_f32_e32 v46, v46
	v_exp_f32_e32 v47, v47
	s_add_i32 s90, s67, 1024
	v_lshlrev_b32_e32 v84, 4, v107
	v_add_u32_e32 v84, s90, v84
	v_add_u32_e32 v85, 0, v84
	v_add_u32_e32 v86, 16, v84
	v_add_u32_e32 v87, 32, v84
	v_add_u32_e32 v88, 48, v84
	v_cmp_gt_u32_e64 s[30:31], s98, v85
	v_cmp_gt_u32_e64 s[36:37], s98, v86
	v_cmp_gt_u32_e64 s[78:79], s98, v87
	v_cmp_gt_u32_e64 s[50:51], s98, v88
	v_cndmask_b32_e64 v32, 0, v32, s[30:31]
	v_add_u32_e32 v85, 128, v84
	v_cmp_gt_u32_e64 s[30:31], s98, v85
	v_cndmask_b32_e64 v33, 0, v33, s[36:37]
	v_add_u32_e32 v86, 144, v84
	v_cmp_gt_u32_e64 s[36:37], s98, v86
	v_cndmask_b32_e64 v34, 0, v34, s[78:79]
	v_add_u32_e32 v87, 160, v84
	v_cmp_gt_u32_e64 s[78:79], s98, v87
	v_cndmask_b32_e64 v35, 0, v35, s[50:51]
	v_add_u32_e32 v88, 176, v84
	v_cmp_gt_u32_e64 s[50:51], s98, v88
	v_cndmask_b32_e64 v36, 0, v36, s[30:31]
	v_add_u32_e32 v85, 256, v84
	v_cmp_gt_u32_e64 s[30:31], s98, v85
	v_cndmask_b32_e64 v37, 0, v37, s[36:37]
	v_add_u32_e32 v86, 272, v84
	v_cmp_gt_u32_e64 s[36:37], s98, v86
	v_cndmask_b32_e64 v38, 0, v38, s[78:79]
	v_add_u32_e32 v87, 288, v84
	v_cmp_gt_u32_e64 s[78:79], s98, v87
	v_cndmask_b32_e64 v39, 0, v39, s[50:51]
	v_add_u32_e32 v88, 304, v84
	v_cmp_gt_u32_e64 s[50:51], s98, v88
	v_cndmask_b32_e64 v40, 0, v40, s[30:31]
	v_add_u32_e32 v85, 384, v84
	v_cmp_gt_u32_e64 s[30:31], s98, v85
	v_cndmask_b32_e64 v41, 0, v41, s[36:37]
	v_add_u32_e32 v86, 400, v84
	v_cmp_gt_u32_e64 s[36:37], s98, v86
	v_cndmask_b32_e64 v42, 0, v42, s[78:79]
	v_add_u32_e32 v87, 416, v84
	v_cmp_gt_u32_e64 s[78:79], s98, v87
	v_cndmask_b32_e64 v43, 0, v43, s[50:51]
	v_add_u32_e32 v88, 432, v84
	v_cmp_gt_u32_e64 s[50:51], s98, v88
	v_nop
	v_cndmask_b32_e64 v44, 0, v44, s[30:31]
	v_cndmask_b32_e64 v45, 0, v45, s[36:37]
	v_cndmask_b32_e64 v46, 0, v46, s[78:79]
	v_cndmask_b32_e64 v47, 0, v47, s[50:51]
	v_cvt_pk_bf16_f32 v64, v32, v33
	v_cvt_pk_bf16_f32 v65, v34, v35
	v_cvt_pk_bf16_f32 v66, v36, v37
	v_cvt_pk_bf16_f32 v67, v38, v39
	v_cvt_pk_bf16_f32 v68, v40, v41
	v_cvt_pk_bf16_f32 v69, v42, v43
	v_cvt_pk_bf16_f32 v70, v44, v45
	v_cvt_pk_bf16_f32 v71, v46, v47
	v_pk_add_f32 v[232:233], v[232:233], v[32:33]
	v_pk_add_f32 v[232:233], v[232:233], v[34:35]
	v_pk_add_f32 v[232:233], v[232:233], v[36:37]
	v_pk_add_f32 v[232:233], v[232:233], v[38:39]
	v_pk_add_f32 v[232:233], v[232:233], v[40:41]
	v_pk_add_f32 v[232:233], v[232:233], v[42:43]
	v_pk_add_f32 v[232:233], v[232:233], v[44:45]
	v_pk_add_f32 v[232:233], v[232:233], v[46:47]
	s_waitcnt lgkmcnt(0)
	v_mfma_f32_32x32x16_bf16 v[0:15], v[64:67], v[72:75], v[0:15]
	v_mfma_f32_32x32x16_bf16 v[16:31], v[64:67], v[76:79], v[16:31]
	v_mfma_f32_32x32x16_bf16 v[0:15], v[68:71], v[220:223], v[0:15]
	v_mfma_f32_32x32x16_bf16 v[16:31], v[68:71], v[224:227], v[16:31]
	v_add_f32_e32 v113, v232, v233
	v_or_b32_e32 v114, 1, v107
	v_or_b32_e32 v97, 2, v107
	v_or_b32_e32 v96, 3, v107
	v_or_b32_e32 v95, 8, v107
	v_or_b32_e32 v94, 9, v107
	v_or_b32_e32 v93, 10, v107
	v_or_b32_e32 v92, 11, v107
	v_or_b32_e32 v91, 16, v107
	v_or_b32_e32 v90, 17, v107
	v_or_b32_e32 v89, 18, v107
	v_or_b32_e32 v88, 19, v107
	v_or_b32_e32 v87, 24, v107
	v_or_b32_e32 v86, 25, v107
	v_or_b32_e32 v85, 26, v107
	v_or_b32_e32 v84, 27, v107
	s_nop 11
	s_branch .LBB0_1265
